# GEMM loops: counted vmcnt waits moved to the phase that first needs each stage (vmcnt(10) in 6 phases instead of vmcnt(6) in 2), on top of saddr DMA form, peel, in-proj fix
# speedup vs baseline: 1.0113x; 1.0060x over previous
.LBB0_234:
	s_ashr_i32 s7, s6, 31
	v_cmp_lt_i64_e32 vcc, s[8:9], v[140:141]
	s_lshl_b64 s[8:9], s[6:7], 19
	s_add_u32 s8, s96, s8
	s_addc_u32 s9, s97, s9
	s_and_b64 s[10:11], vcc, exec
	s_cselect_b32 s7, s9, s15
	s_cselect_b32 s44, s8, s14
	s_ashr_i32 s5, s4, 31
	s_lshl_b64 s[10:11], s[4:5], 19
	s_add_u32 s10, s72, s10
	s_addc_u32 s11, s73, s11
	s_and_b64 s[16:17], vcc, exec
	s_cselect_b32 s5, s11, s19
	s_cselect_b32 s45, s10, s18
	s_add_u32 s14, s14, 0x40080
	s_addc_u32 s15, s15, 0
	s_add_u32 s46, s18, 0x100
	s_addc_u32 s47, s19, 0
	s_mov_b32 s48, -2
	ds_read_b128 v[150:153], v147
	ds_read_b128 v[154:157], v147 offset:1024
	ds_read_b128 v[158:161], v147 offset:2048
	ds_read_b128 v[162:165], v147 offset:3072
	s_add_u32 s16, s14, 0xfffc0080
	s_addc_u32 s17, s15, -1
	s_cmp_eq_u32 s48, 12
	s_cselect_b32 s23, s7, s17
	s_cselect_b32 s22, s44, s16
	s_cselect_b32 s19, s5, s47
	s_cselect_b32 s18, s45, s46
	s_add_i32 m0, s13, 0xc000
	ds_read_b128 v[166:169], v148
	ds_read_b128 v[170:173], v148 offset:1024
	ds_read_b128 v[174:177], v148 offset:2048
	ds_read_b128 v[178:181], v148 offset:3072
	ds_read_b128 v[182:185], v148 offset:4096
	ds_read_b128 v[186:189], v148 offset:5120
	ds_read_b128 v[190:193], v148 offset:6144
	ds_read_b128 v[194:197], v148 offset:7168
	global_load_lds_dwordx4 v136, s[14:15]
	s_add_i32 m0, s13, 0xe000
	s_nop 0
	global_load_lds_dwordx4 v138, s[14:15]
	s_waitcnt lgkmcnt(8)
	s_waitcnt vmcnt(10)
	s_barrier
	s_waitcnt lgkmcnt(0)
	s_setprio 1
	s_waitcnt lgkmcnt(0)
	v_mfma_f32_16x16x32_bf16 v[124:127], v[150:153], v[166:169], 0
	v_mfma_f32_16x16x32_bf16 v[116:119], v[158:161], v[166:169], 0
	v_mfma_f32_16x16x32_bf16 v[108:111], v[150:153], v[174:177], 0
	v_mfma_f32_16x16x32_bf16 v[100:103], v[158:161], v[174:177], 0
	v_mfma_f32_16x16x32_bf16 v[92:95], v[150:153], v[182:185], 0
	v_mfma_f32_16x16x32_bf16 v[84:87], v[158:161], v[182:185], 0
	v_mfma_f32_16x16x32_bf16 v[76:79], v[150:153], v[190:193], 0
	v_mfma_f32_16x16x32_bf16 v[68:71], v[158:161], v[190:193], 0
	v_mfma_f32_16x16x32_bf16 v[124:127], v[154:157], v[170:173], v[124:127]
	v_mfma_f32_16x16x32_bf16 v[116:119], v[162:165], v[170:173], v[116:119]
	v_mfma_f32_16x16x32_bf16 v[108:111], v[154:157], v[178:181], v[108:111]
	v_mfma_f32_16x16x32_bf16 v[100:103], v[162:165], v[178:181], v[100:103]
	v_mfma_f32_16x16x32_bf16 v[92:95], v[154:157], v[186:189], v[92:95]
	v_mfma_f32_16x16x32_bf16 v[84:87], v[162:165], v[186:189], v[84:87]
	v_mfma_f32_16x16x32_bf16 v[76:79], v[154:157], v[194:197], v[76:79]
	v_mfma_f32_16x16x32_bf16 v[68:71], v[162:165], v[194:197], v[68:71]
	s_setprio 0
	s_barrier
	s_add_i32 s16, s40, s25
	s_mov_b32 m0, s16
	ds_read_b128 v[202:205], v149
	ds_read_b128 v[206:209], v149 offset:1024
	ds_read_b128 v[210:213], v149 offset:2048
	ds_read_b128 v[214:217], v149 offset:3072
	global_load_lds_dwordx4 v132, s[18:19]
	s_add_i32 m0, s16, 0x2000
	s_nop 0
	global_load_lds_dwordx4 v128, s[18:19]
	s_waitcnt vmcnt(10)
	s_barrier
	s_waitcnt lgkmcnt(0)
	s_setprio 1
	s_waitcnt lgkmcnt(0)
	v_mfma_f32_16x16x32_bf16 v[120:123], v[202:205], v[166:169], 0
	v_mfma_f32_16x16x32_bf16 v[112:115], v[210:213], v[166:169], 0
	v_mfma_f32_16x16x32_bf16 v[104:107], v[202:205], v[174:177], 0
	v_mfma_f32_16x16x32_bf16 v[96:99], v[210:213], v[174:177], 0
	v_mfma_f32_16x16x32_bf16 v[88:91], v[202:205], v[182:185], 0
	v_mfma_f32_16x16x32_bf16 v[80:83], v[210:213], v[182:185], 0
	v_mfma_f32_16x16x32_bf16 v[72:75], v[202:205], v[190:193], 0
	v_mfma_f32_16x16x32_bf16 v[64:67], v[210:213], v[190:193], 0
	v_mfma_f32_16x16x32_bf16 v[120:123], v[206:209], v[170:173], v[120:123]
	v_mfma_f32_16x16x32_bf16 v[112:115], v[214:217], v[170:173], v[112:115]
	v_mfma_f32_16x16x32_bf16 v[104:107], v[206:209], v[178:181], v[104:107]
	v_mfma_f32_16x16x32_bf16 v[96:99], v[214:217], v[178:181], v[96:99]
	v_mfma_f32_16x16x32_bf16 v[88:91], v[206:209], v[186:189], v[88:91]
	v_mfma_f32_16x16x32_bf16 v[80:83], v[214:217], v[186:189], v[80:83]
	v_mfma_f32_16x16x32_bf16 v[72:75], v[206:209], v[194:197], v[72:75]
	v_mfma_f32_16x16x32_bf16 v[64:67], v[214:217], v[194:197], v[64:67]
	s_setprio 0
	s_mov_b32 m0, s13
	s_barrier
	ds_read_b128 v[166:169], v148 offset:16384
	ds_read_b128 v[170:173], v148 offset:17408
	ds_read_b128 v[174:177], v148 offset:18432
	ds_read_b128 v[178:181], v148 offset:19456
	ds_read_b128 v[182:185], v148 offset:20480
	ds_read_b128 v[186:189], v148 offset:21504
	ds_read_b128 v[190:193], v148 offset:22528
	ds_read_b128 v[194:197], v148 offset:23552
	global_load_lds_dwordx4 v134, s[22:23]
	s_mov_b32 m0, s28
	s_nop 0
	global_load_lds_dwordx4 v130, s[22:23]
	s_barrier
	s_waitcnt lgkmcnt(0)
	s_setprio 1
	s_waitcnt lgkmcnt(0)
	v_mfma_f32_16x16x32_bf16 v[60:63], v[150:153], v[166:169], 0
	v_mfma_f32_16x16x32_bf16 v[56:59], v[158:161], v[166:169], 0
	v_mfma_f32_16x16x32_bf16 v[44:47], v[150:153], v[174:177], 0
	v_mfma_f32_16x16x32_bf16 v[40:43], v[158:161], v[174:177], 0
	v_mfma_f32_16x16x32_bf16 v[28:31], v[150:153], v[182:185], 0
	v_mfma_f32_16x16x32_bf16 v[24:27], v[158:161], v[182:185], 0
	v_mfma_f32_16x16x32_bf16 v[12:15], v[150:153], v[190:193], 0
	v_mfma_f32_16x16x32_bf16 v[8:11], v[158:161], v[190:193], 0
	v_mfma_f32_16x16x32_bf16 v[60:63], v[154:157], v[170:173], v[60:63]
	v_mfma_f32_16x16x32_bf16 v[56:59], v[162:165], v[170:173], v[56:59]
	v_mfma_f32_16x16x32_bf16 v[44:47], v[154:157], v[178:181], v[44:47]
	v_mfma_f32_16x16x32_bf16 v[40:43], v[162:165], v[178:181], v[40:43]
	v_mfma_f32_16x16x32_bf16 v[28:31], v[154:157], v[186:189], v[28:31]
	v_mfma_f32_16x16x32_bf16 v[24:27], v[162:165], v[186:189], v[24:27]
	v_mfma_f32_16x16x32_bf16 v[12:15], v[154:157], v[194:197], v[12:15]
	v_mfma_f32_16x16x32_bf16 v[8:11], v[162:165], v[194:197], v[8:11]
	s_setprio 0
	s_barrier
	s_add_u32 s16, s18, 0x40000
	s_addc_u32 s17, s19, 0
	s_add_i32 s20, s41, s25
	s_mov_b32 m0, s20
	s_nop 0
	global_load_lds_dwordx4 v132, s[16:17]
	s_add_i32 m0, s20, 0x2000
	s_nop 0
	global_load_lds_dwordx4 v128, s[16:17]
	s_waitcnt vmcnt(10)
	s_barrier
	s_setprio 1
	v_mfma_f32_16x16x32_bf16 v[52:55], v[202:205], v[166:169], 0
	v_mfma_f32_16x16x32_bf16 v[48:51], v[210:213], v[166:169], 0
	v_mfma_f32_16x16x32_bf16 v[36:39], v[202:205], v[174:177], 0
	v_mfma_f32_16x16x32_bf16 v[32:35], v[210:213], v[174:177], 0
	v_mfma_f32_16x16x32_bf16 v[20:23], v[202:205], v[182:185], 0
	v_mfma_f32_16x16x32_bf16 v[16:19], v[210:213], v[182:185], 0
	v_mfma_f32_16x16x32_bf16 v[4:7], v[202:205], v[190:193], 0
	v_mfma_f32_16x16x32_bf16 v[0:3], v[210:213], v[190:193], 0
	v_mfma_f32_16x16x32_bf16 v[52:55], v[206:209], v[170:173], v[52:55]
	v_mfma_f32_16x16x32_bf16 v[48:51], v[214:217], v[170:173], v[48:51]
	v_mfma_f32_16x16x32_bf16 v[36:39], v[206:209], v[178:181], v[36:39]
	v_mfma_f32_16x16x32_bf16 v[32:35], v[214:217], v[178:181], v[32:35]
	v_mfma_f32_16x16x32_bf16 v[20:23], v[206:209], v[186:189], v[20:23]
	v_mfma_f32_16x16x32_bf16 v[16:19], v[214:217], v[186:189], v[16:19]
	v_mfma_f32_16x16x32_bf16 v[4:7], v[206:209], v[194:197], v[4:7]
	v_mfma_f32_16x16x32_bf16 v[0:3], v[214:217], v[194:197], v[0:3]
	s_setprio 0
	s_add_i32 s20, 0, 0x18000
	v_add_u32_e32 v162, s20, v146
	s_barrier
	ds_read_b128 v[150:153], v162
	ds_read_b128 v[154:157], v162 offset:1024
	ds_read_b128 v[158:161], v162 offset:2048
	ds_read_b128 v[162:165], v162 offset:3072
	s_add_u32 s16, s22, 0x40000
	s_addc_u32 s17, s23, 0
	s_mov_b32 m0, s29
	ds_read_b128 v[166:169], v148 offset:32768
	ds_read_b128 v[170:173], v148 offset:33792
	ds_read_b128 v[174:177], v148 offset:34816
	ds_read_b128 v[178:181], v148 offset:35840
	ds_read_b128 v[182:185], v148 offset:36864
	ds_read_b128 v[186:189], v148 offset:37888
	ds_read_b128 v[190:193], v148 offset:38912
	ds_read_b128 v[194:197], v148 offset:39936
	global_load_lds_dwordx4 v134, s[16:17]
	s_mov_b32 m0, s33
	s_nop 0
	global_load_lds_dwordx4 v130, s[16:17]
	s_waitcnt lgkmcnt(8)
	s_waitcnt vmcnt(10)
	s_barrier
	s_waitcnt lgkmcnt(0)
	s_setprio 1
	s_waitcnt lgkmcnt(0)
	v_mfma_f32_16x16x32_bf16 v[124:127], v[150:153], v[166:169], v[124:127]
	v_mfma_f32_16x16x32_bf16 v[116:119], v[158:161], v[166:169], v[116:119]
	v_mfma_f32_16x16x32_bf16 v[108:111], v[150:153], v[174:177], v[108:111]
	v_mfma_f32_16x16x32_bf16 v[100:103], v[158:161], v[174:177], v[100:103]
	v_mfma_f32_16x16x32_bf16 v[92:95], v[150:153], v[182:185], v[92:95]
	v_mfma_f32_16x16x32_bf16 v[84:87], v[158:161], v[182:185], v[84:87]
	v_mfma_f32_16x16x32_bf16 v[76:79], v[150:153], v[190:193], v[76:79]
	v_mfma_f32_16x16x32_bf16 v[68:71], v[158:161], v[190:193], v[68:71]
	v_mfma_f32_16x16x32_bf16 v[124:127], v[154:157], v[170:173], v[124:127]
	v_mfma_f32_16x16x32_bf16 v[116:119], v[162:165], v[170:173], v[116:119]
	v_mfma_f32_16x16x32_bf16 v[108:111], v[154:157], v[178:181], v[108:111]
	v_mfma_f32_16x16x32_bf16 v[100:103], v[162:165], v[178:181], v[100:103]
	v_mfma_f32_16x16x32_bf16 v[92:95], v[154:157], v[186:189], v[92:95]
	v_mfma_f32_16x16x32_bf16 v[84:87], v[162:165], v[186:189], v[84:87]
	v_mfma_f32_16x16x32_bf16 v[76:79], v[154:157], v[194:197], v[76:79]
	v_mfma_f32_16x16x32_bf16 v[68:71], v[162:165], v[194:197], v[68:71]
	s_setprio 0
	s_barrier
	s_add_i32 s21, 0, 0x1c000
	s_add_i32 s16, s20, s25
	v_add_u32_e32 v214, s21, v146
	s_add_u32 s0, s18, 0x80
	s_addc_u32 s1, s19, 0
	s_mov_b32 m0, s16
	ds_read_b128 v[202:205], v214
	ds_read_b128 v[206:209], v214 offset:1024
	ds_read_b128 v[210:213], v214 offset:2048
	ds_read_b128 v[214:217], v214 offset:3072
	global_load_lds_dwordx4 v132, s[0:1]
	s_add_i32 m0, s16, 0x2000
	s_nop 0
	global_load_lds_dwordx4 v128, s[0:1]
	s_waitcnt vmcnt(10)
	s_barrier
	s_waitcnt lgkmcnt(0)
	s_setprio 1
	s_waitcnt lgkmcnt(0)
	v_mfma_f32_16x16x32_bf16 v[120:123], v[202:205], v[166:169], v[120:123]
	v_mfma_f32_16x16x32_bf16 v[112:115], v[210:213], v[166:169], v[112:115]
	v_mfma_f32_16x16x32_bf16 v[104:107], v[202:205], v[174:177], v[104:107]
	v_mfma_f32_16x16x32_bf16 v[96:99], v[210:213], v[174:177], v[96:99]
	v_mfma_f32_16x16x32_bf16 v[88:91], v[202:205], v[182:185], v[88:91]
	v_mfma_f32_16x16x32_bf16 v[80:83], v[210:213], v[182:185], v[80:83]
	v_mfma_f32_16x16x32_bf16 v[72:75], v[202:205], v[190:193], v[72:75]
	v_mfma_f32_16x16x32_bf16 v[64:67], v[210:213], v[190:193], v[64:67]
	v_mfma_f32_16x16x32_bf16 v[120:123], v[206:209], v[170:173], v[120:123]
	v_mfma_f32_16x16x32_bf16 v[112:115], v[214:217], v[170:173], v[112:115]
	v_mfma_f32_16x16x32_bf16 v[104:107], v[206:209], v[178:181], v[104:107]
	v_mfma_f32_16x16x32_bf16 v[96:99], v[214:217], v[178:181], v[96:99]
	v_mfma_f32_16x16x32_bf16 v[88:91], v[206:209], v[186:189], v[88:91]
	v_mfma_f32_16x16x32_bf16 v[80:83], v[214:217], v[186:189], v[80:83]
	v_mfma_f32_16x16x32_bf16 v[72:75], v[206:209], v[194:197], v[72:75]
	v_mfma_f32_16x16x32_bf16 v[64:67], v[214:217], v[194:197], v[64:67]
	s_setprio 0
	s_mov_b32 m0, s36
	s_add_u32 s0, s22, 0x80
	s_addc_u32 s1, s23, 0
	s_barrier
	ds_read_b128 v[166:169], v148 offset:49152
	ds_read_b128 v[170:173], v148 offset:50176
	ds_read_b128 v[174:177], v148 offset:51200
	ds_read_b128 v[178:181], v148 offset:52224
	ds_read_b128 v[182:185], v148 offset:53248
	ds_read_b128 v[186:189], v148 offset:54272
	ds_read_b128 v[190:193], v148 offset:55296
	ds_read_b128 v[194:197], v148 offset:56320
	global_load_lds_dwordx4 v134, s[0:1]
	s_mov_b32 m0, s37
	s_nop 0
	global_load_lds_dwordx4 v130, s[0:1]
	s_barrier
	s_waitcnt lgkmcnt(0)
	s_setprio 1
	s_waitcnt lgkmcnt(0)
	v_mfma_f32_16x16x32_bf16 v[60:63], v[150:153], v[166:169], v[60:63]
	v_mfma_f32_16x16x32_bf16 v[56:59], v[158:161], v[166:169], v[56:59]
	v_mfma_f32_16x16x32_bf16 v[44:47], v[150:153], v[174:177], v[44:47]
	v_mfma_f32_16x16x32_bf16 v[40:43], v[158:161], v[174:177], v[40:43]
	v_mfma_f32_16x16x32_bf16 v[28:31], v[150:153], v[182:185], v[28:31]
	v_mfma_f32_16x16x32_bf16 v[24:27], v[158:161], v[182:185], v[24:27]
	v_mfma_f32_16x16x32_bf16 v[12:15], v[150:153], v[190:193], v[12:15]
	v_mfma_f32_16x16x32_bf16 v[8:11], v[158:161], v[190:193], v[8:11]
	v_mfma_f32_16x16x32_bf16 v[60:63], v[154:157], v[170:173], v[60:63]
	v_mfma_f32_16x16x32_bf16 v[56:59], v[162:165], v[170:173], v[56:59]
	v_mfma_f32_16x16x32_bf16 v[44:47], v[154:157], v[178:181], v[44:47]
	v_mfma_f32_16x16x32_bf16 v[40:43], v[162:165], v[178:181], v[40:43]
	v_mfma_f32_16x16x32_bf16 v[28:31], v[154:157], v[186:189], v[28:31]
	v_mfma_f32_16x16x32_bf16 v[24:27], v[162:165], v[186:189], v[24:27]
	v_mfma_f32_16x16x32_bf16 v[12:15], v[154:157], v[194:197], v[12:15]
	v_mfma_f32_16x16x32_bf16 v[8:11], v[162:165], v[194:197], v[8:11]
	s_setprio 0
	s_barrier
	s_add_u32 s16, s18, 0x40080
	s_addc_u32 s17, s19, 0
	s_add_i32 s18, s21, s25
	s_mov_b32 m0, s18
	s_nop 0
	global_load_lds_dwordx4 v132, s[16:17]
	s_add_i32 m0, s18, 0x2000
	s_nop 0
	global_load_lds_dwordx4 v128, s[16:17]
	s_waitcnt vmcnt(10)
	s_barrier
	s_setprio 1
	v_mfma_f32_16x16x32_bf16 v[52:55], v[202:205], v[166:169], v[52:55]
	v_mfma_f32_16x16x32_bf16 v[48:51], v[210:213], v[166:169], v[48:51]
	v_mfma_f32_16x16x32_bf16 v[36:39], v[202:205], v[174:177], v[36:39]
	v_mfma_f32_16x16x32_bf16 v[32:35], v[210:213], v[174:177], v[32:35]
	v_mfma_f32_16x16x32_bf16 v[20:23], v[202:205], v[182:185], v[20:23]
	v_mfma_f32_16x16x32_bf16 v[16:19], v[210:213], v[182:185], v[16:19]
	v_mfma_f32_16x16x32_bf16 v[4:7], v[202:205], v[190:193], v[4:7]
	v_mfma_f32_16x16x32_bf16 v[0:3], v[210:213], v[190:193], v[0:3]
	v_mfma_f32_16x16x32_bf16 v[52:55], v[206:209], v[170:173], v[52:55]
	v_mfma_f32_16x16x32_bf16 v[48:51], v[214:217], v[170:173], v[48:51]
	v_mfma_f32_16x16x32_bf16 v[36:39], v[206:209], v[178:181], v[36:39]
	v_mfma_f32_16x16x32_bf16 v[32:35], v[214:217], v[178:181], v[32:35]
	v_mfma_f32_16x16x32_bf16 v[20:23], v[206:209], v[186:189], v[20:23]
	v_mfma_f32_16x16x32_bf16 v[16:19], v[214:217], v[186:189], v[16:19]
	v_mfma_f32_16x16x32_bf16 v[4:7], v[206:209], v[194:197], v[4:7]
	v_mfma_f32_16x16x32_bf16 v[0:3], v[214:217], v[194:197], v[0:3]
	s_setprio 0
	s_add_i32 s48, s48, 2
	s_add_u32 s14, s14, 0x100
	s_addc_u32 s15, s15, 0
	s_add_u32 s46, s46, 0x100
	s_addc_u32 s47, s47, 0
	s_cmp_gt_u32 s48, 13
	s_barrier
.LBB0_235:
	ds_read_b128 v[150:153], v147
	ds_read_b128 v[154:157], v147 offset:1024
	ds_read_b128 v[158:161], v147 offset:2048
	ds_read_b128 v[162:165], v147 offset:3072
	s_add_u32 s16, s14, 0xfffc0080
	s_addc_u32 s17, s15, -1
	s_cmp_eq_u32 s48, 12
	s_cselect_b32 s23, s7, s17
	s_cselect_b32 s22, s44, s16
	s_cselect_b32 s19, s5, s47
	s_cselect_b32 s18, s45, s46
	s_add_i32 m0, s13, 0xc000
	ds_read_b128 v[166:169], v148
	ds_read_b128 v[170:173], v148 offset:1024
	ds_read_b128 v[174:177], v148 offset:2048
	ds_read_b128 v[178:181], v148 offset:3072
	ds_read_b128 v[182:185], v148 offset:4096
	ds_read_b128 v[186:189], v148 offset:5120
	ds_read_b128 v[190:193], v148 offset:6144
	ds_read_b128 v[194:197], v148 offset:7168
	global_load_lds_dwordx4 v136, s[14:15]
	s_add_i32 m0, s13, 0xe000
	s_nop 0
	global_load_lds_dwordx4 v138, s[14:15]
	s_waitcnt lgkmcnt(8)
	s_waitcnt vmcnt(10)
	s_barrier
	s_waitcnt lgkmcnt(0)
	s_setprio 1
	s_waitcnt lgkmcnt(0)
	v_mfma_f32_16x16x32_bf16 v[124:127], v[150:153], v[166:169], v[124:127]
	v_mfma_f32_16x16x32_bf16 v[116:119], v[158:161], v[166:169], v[116:119]
	v_mfma_f32_16x16x32_bf16 v[108:111], v[150:153], v[174:177], v[108:111]
	v_mfma_f32_16x16x32_bf16 v[100:103], v[158:161], v[174:177], v[100:103]
	v_mfma_f32_16x16x32_bf16 v[92:95], v[150:153], v[182:185], v[92:95]
	v_mfma_f32_16x16x32_bf16 v[84:87], v[158:161], v[182:185], v[84:87]
	v_mfma_f32_16x16x32_bf16 v[76:79], v[150:153], v[190:193], v[76:79]
	v_mfma_f32_16x16x32_bf16 v[68:71], v[158:161], v[190:193], v[68:71]
	v_mfma_f32_16x16x32_bf16 v[124:127], v[154:157], v[170:173], v[124:127]
	v_mfma_f32_16x16x32_bf16 v[116:119], v[162:165], v[170:173], v[116:119]
	v_mfma_f32_16x16x32_bf16 v[108:111], v[154:157], v[178:181], v[108:111]
	v_mfma_f32_16x16x32_bf16 v[100:103], v[162:165], v[178:181], v[100:103]
	v_mfma_f32_16x16x32_bf16 v[92:95], v[154:157], v[186:189], v[92:95]
	v_mfma_f32_16x16x32_bf16 v[84:87], v[162:165], v[186:189], v[84:87]
	v_mfma_f32_16x16x32_bf16 v[76:79], v[154:157], v[194:197], v[76:79]
	v_mfma_f32_16x16x32_bf16 v[68:71], v[162:165], v[194:197], v[68:71]
	s_setprio 0
	s_barrier
	s_add_i32 s16, s40, s25
	s_mov_b32 m0, s16
	ds_read_b128 v[202:205], v149
	ds_read_b128 v[206:209], v149 offset:1024
	ds_read_b128 v[210:213], v149 offset:2048
	ds_read_b128 v[214:217], v149 offset:3072
	global_load_lds_dwordx4 v132, s[18:19]
	s_add_i32 m0, s16, 0x2000
	s_nop 0
	global_load_lds_dwordx4 v128, s[18:19]
	s_waitcnt vmcnt(10)
	s_barrier
	s_waitcnt lgkmcnt(0)
	s_setprio 1
	s_waitcnt lgkmcnt(0)
	v_mfma_f32_16x16x32_bf16 v[120:123], v[202:205], v[166:169], v[120:123]
	v_mfma_f32_16x16x32_bf16 v[112:115], v[210:213], v[166:169], v[112:115]
	v_mfma_f32_16x16x32_bf16 v[104:107], v[202:205], v[174:177], v[104:107]
	v_mfma_f32_16x16x32_bf16 v[96:99], v[210:213], v[174:177], v[96:99]
	v_mfma_f32_16x16x32_bf16 v[88:91], v[202:205], v[182:185], v[88:91]
	v_mfma_f32_16x16x32_bf16 v[80:83], v[210:213], v[182:185], v[80:83]
	v_mfma_f32_16x16x32_bf16 v[72:75], v[202:205], v[190:193], v[72:75]
	v_mfma_f32_16x16x32_bf16 v[64:67], v[210:213], v[190:193], v[64:67]
	v_mfma_f32_16x16x32_bf16 v[120:123], v[206:209], v[170:173], v[120:123]
	v_mfma_f32_16x16x32_bf16 v[112:115], v[214:217], v[170:173], v[112:115]
	v_mfma_f32_16x16x32_bf16 v[104:107], v[206:209], v[178:181], v[104:107]
	v_mfma_f32_16x16x32_bf16 v[96:99], v[214:217], v[178:181], v[96:99]
	v_mfma_f32_16x16x32_bf16 v[88:91], v[206:209], v[186:189], v[88:91]
	v_mfma_f32_16x16x32_bf16 v[80:83], v[214:217], v[186:189], v[80:83]
	v_mfma_f32_16x16x32_bf16 v[72:75], v[206:209], v[194:197], v[72:75]
	v_mfma_f32_16x16x32_bf16 v[64:67], v[214:217], v[194:197], v[64:67]
	s_setprio 0
	s_mov_b32 m0, s13
	s_barrier
	ds_read_b128 v[166:169], v148 offset:16384
	ds_read_b128 v[170:173], v148 offset:17408
	ds_read_b128 v[174:177], v148 offset:18432
	ds_read_b128 v[178:181], v148 offset:19456
	ds_read_b128 v[182:185], v148 offset:20480
	ds_read_b128 v[186:189], v148 offset:21504
	ds_read_b128 v[190:193], v148 offset:22528
	ds_read_b128 v[194:197], v148 offset:23552
	global_load_lds_dwordx4 v134, s[22:23]
	s_mov_b32 m0, s28
	s_nop 0
	global_load_lds_dwordx4 v130, s[22:23]
	s_barrier
	s_waitcnt lgkmcnt(0)
	s_setprio 1
	s_waitcnt lgkmcnt(0)
	v_mfma_f32_16x16x32_bf16 v[60:63], v[150:153], v[166:169], v[60:63]
	v_mfma_f32_16x16x32_bf16 v[56:59], v[158:161], v[166:169], v[56:59]
	v_mfma_f32_16x16x32_bf16 v[44:47], v[150:153], v[174:177], v[44:47]
	v_mfma_f32_16x16x32_bf16 v[40:43], v[158:161], v[174:177], v[40:43]
	v_mfma_f32_16x16x32_bf16 v[28:31], v[150:153], v[182:185], v[28:31]
	v_mfma_f32_16x16x32_bf16 v[24:27], v[158:161], v[182:185], v[24:27]
	v_mfma_f32_16x16x32_bf16 v[12:15], v[150:153], v[190:193], v[12:15]
	v_mfma_f32_16x16x32_bf16 v[8:11], v[158:161], v[190:193], v[8:11]
	v_mfma_f32_16x16x32_bf16 v[60:63], v[154:157], v[170:173], v[60:63]
	v_mfma_f32_16x16x32_bf16 v[56:59], v[162:165], v[170:173], v[56:59]
	v_mfma_f32_16x16x32_bf16 v[44:47], v[154:157], v[178:181], v[44:47]
	v_mfma_f32_16x16x32_bf16 v[40:43], v[162:165], v[178:181], v[40:43]
	v_mfma_f32_16x16x32_bf16 v[28:31], v[154:157], v[186:189], v[28:31]
	v_mfma_f32_16x16x32_bf16 v[24:27], v[162:165], v[186:189], v[24:27]
	v_mfma_f32_16x16x32_bf16 v[12:15], v[154:157], v[194:197], v[12:15]
	v_mfma_f32_16x16x32_bf16 v[8:11], v[162:165], v[194:197], v[8:11]
	s_setprio 0
	s_barrier
	s_add_u32 s16, s18, 0x40000
	s_addc_u32 s17, s19, 0
	s_add_i32 s20, s41, s25
	s_mov_b32 m0, s20
	s_nop 0
	global_load_lds_dwordx4 v132, s[16:17]
	s_add_i32 m0, s20, 0x2000
	s_nop 0
	global_load_lds_dwordx4 v128, s[16:17]
	s_waitcnt vmcnt(10)
	s_barrier
	s_setprio 1
	v_mfma_f32_16x16x32_bf16 v[52:55], v[202:205], v[166:169], v[52:55]
	v_mfma_f32_16x16x32_bf16 v[48:51], v[210:213], v[166:169], v[48:51]
	v_mfma_f32_16x16x32_bf16 v[36:39], v[202:205], v[174:177], v[36:39]
	v_mfma_f32_16x16x32_bf16 v[32:35], v[210:213], v[174:177], v[32:35]
	v_mfma_f32_16x16x32_bf16 v[20:23], v[202:205], v[182:185], v[20:23]
	v_mfma_f32_16x16x32_bf16 v[16:19], v[210:213], v[182:185], v[16:19]
	v_mfma_f32_16x16x32_bf16 v[4:7], v[202:205], v[190:193], v[4:7]
	v_mfma_f32_16x16x32_bf16 v[0:3], v[210:213], v[190:193], v[0:3]
	v_mfma_f32_16x16x32_bf16 v[52:55], v[206:209], v[170:173], v[52:55]
	v_mfma_f32_16x16x32_bf16 v[48:51], v[214:217], v[170:173], v[48:51]
	v_mfma_f32_16x16x32_bf16 v[36:39], v[206:209], v[178:181], v[36:39]
	v_mfma_f32_16x16x32_bf16 v[32:35], v[214:217], v[178:181], v[32:35]
	v_mfma_f32_16x16x32_bf16 v[20:23], v[206:209], v[186:189], v[20:23]
	v_mfma_f32_16x16x32_bf16 v[16:19], v[214:217], v[186:189], v[16:19]
	v_mfma_f32_16x16x32_bf16 v[4:7], v[206:209], v[194:197], v[4:7]
	v_mfma_f32_16x16x32_bf16 v[0:3], v[214:217], v[194:197], v[0:3]
	s_setprio 0
	s_add_i32 s20, 0, 0x18000
	v_add_u32_e32 v162, s20, v146
	s_barrier
	ds_read_b128 v[150:153], v162
	ds_read_b128 v[154:157], v162 offset:1024
	ds_read_b128 v[158:161], v162 offset:2048
	ds_read_b128 v[162:165], v162 offset:3072
	s_add_u32 s16, s22, 0x40000
	s_addc_u32 s17, s23, 0
	s_mov_b32 m0, s29
	ds_read_b128 v[166:169], v148 offset:32768
	ds_read_b128 v[170:173], v148 offset:33792
	ds_read_b128 v[174:177], v148 offset:34816
	ds_read_b128 v[178:181], v148 offset:35840
	ds_read_b128 v[182:185], v148 offset:36864
	ds_read_b128 v[186:189], v148 offset:37888
	ds_read_b128 v[190:193], v148 offset:38912
	ds_read_b128 v[194:197], v148 offset:39936
	global_load_lds_dwordx4 v134, s[16:17]
	s_mov_b32 m0, s33
	s_nop 0
	global_load_lds_dwordx4 v130, s[16:17]
	s_waitcnt lgkmcnt(8)
	s_waitcnt vmcnt(10)
	s_barrier
; #define PG8_STAGE(bufoff, gbase, voff) do { _Pragma("unroll") for (int _i = 0; _i < 2; ++_i) \
;         __builtin_amdgcn_global_load_lds((const unsigned*)((const char*)(gbase) + (voff)[_i]), (LAS unsigned*)(lds + (bufoff) + ldsw + _i * 8192), 16, 0, 0); } while (0)
; #define PG8_LDA(dst, b, h) do { _Pragma("unroll") for (int m = 0; m < 4; ++m) _Pragma("unroll") for (int k = 0; k < 2; ++k) dst[m][k] = *(const LAS bf16x8*)(lds + PG8_SA(b, h) + aoff + m * 2048 + k * 1024); } while (0)
; #define PG8_LDB(dst, b, h) do { _Pragma("unroll") for (int n = 0; n < 2; ++n) _Pragma("unroll") for (int k = 0; k < 2; ++k) dst[n][k] = *(const LAS bf16x8*)(lds + PG8_SB(b, h) + boff + n * 2048 + k * 1024); } while (0)
; #define PG8_MMA(ai, bj, At, Bt) do { __builtin_amdgcn_s_setprio(1); _Pragma("unroll") for (int m = 0; m < 4; ++m) _Pragma("unroll") for (int n = 0; n < 2; ++n) _Pragma("unroll") for (int k = 0; k < 2; ++k) \
;         acc[ai][bj][m][n] = __builtin_amdgcn_mfma_f32_16x16x32_bf16(Bt[n][k], At[m][k], acc[ai][bj][m][n], 0, 0, 0); __builtin_amdgcn_s_setprio(0); } while (0)
; #define PG8_WAIT_V(n) asm volatile("s_waitcnt vmcnt(" #n ")" ::: "memory")
; #define PG8_WAIT_L(n) asm volatile("s_waitcnt lgkmcnt(" #n ")" ::: "memory")
; #define PG8_BAR __builtin_amdgcn_s_barrier()
; #define PG8_SCHED __builtin_amdgcn_sched_barrier(0)
; template <class Epi, class Sched>
; __device__ __forceinline__ void gemm_phase(LAS unsigned char* lds, const Gemm g, const Sched& S, const Epi& E) {
;     ...
;             PG8_WAIT_L(8); PG8_BAR; PG8_WAIT_L(0); PG8_MMA(0, 0, At, B0); PG8_BAR; PG8_SCHED;
;             PG8_LDB(B1, 1, 1); PG8_STAGE(PG8_SB(1, 0), b3, voffB);
;             PG8_BAR; PG8_WAIT_L(0); PG8_MMA(0, 1, At, B1); PG8_BAR;
;             PG8_LDA(At, 1, 1); PG8_STAGE(PG8_SA(1, 0), a3, voffA);
;             PG8_BAR; PG8_WAIT_L(0); PG8_MMA(1, 0, At, B0); PG8_BAR; PG8_SCHED;
;             PG8_STAGE(PG8_SB(1, 1), b3 + hstep, voffB);
;             PG8_WAIT_V(6); PG8_BAR; PG8_MMA(1, 1, At, B1); PG8_BAR;
	s_waitcnt lgkmcnt(0)
	s_setprio 1
	s_waitcnt lgkmcnt(0)
	v_mfma_f32_16x16x32_bf16 v[124:127], v[150:153], v[166:169], v[124:127]
	v_mfma_f32_16x16x32_bf16 v[116:119], v[158:161], v[166:169], v[116:119]
	v_mfma_f32_16x16x32_bf16 v[108:111], v[150:153], v[174:177], v[108:111]
	v_mfma_f32_16x16x32_bf16 v[100:103], v[158:161], v[174:177], v[100:103]
	v_mfma_f32_16x16x32_bf16 v[92:95], v[150:153], v[182:185], v[92:95]
	v_mfma_f32_16x16x32_bf16 v[84:87], v[158:161], v[182:185], v[84:87]
	v_mfma_f32_16x16x32_bf16 v[76:79], v[150:153], v[190:193], v[76:79]
	v_mfma_f32_16x16x32_bf16 v[68:71], v[158:161], v[190:193], v[68:71]
	v_mfma_f32_16x16x32_bf16 v[124:127], v[154:157], v[170:173], v[124:127]
	v_mfma_f32_16x16x32_bf16 v[116:119], v[162:165], v[170:173], v[116:119]
	v_mfma_f32_16x16x32_bf16 v[108:111], v[154:157], v[178:181], v[108:111]
	v_mfma_f32_16x16x32_bf16 v[100:103], v[162:165], v[178:181], v[100:103]
	v_mfma_f32_16x16x32_bf16 v[92:95], v[154:157], v[186:189], v[92:95]
	v_mfma_f32_16x16x32_bf16 v[84:87], v[162:165], v[186:189], v[84:87]
	v_mfma_f32_16x16x32_bf16 v[76:79], v[154:157], v[194:197], v[76:79]
	v_mfma_f32_16x16x32_bf16 v[68:71], v[162:165], v[194:197], v[68:71]
	s_setprio 0
	s_barrier
	s_add_i32 s21, 0, 0x1c000
	s_add_i32 s16, s20, s25
	v_add_u32_e32 v214, s21, v146
	s_add_u32 s0, s18, 0x80
	s_addc_u32 s1, s19, 0
	s_mov_b32 m0, s16
	ds_read_b128 v[202:205], v214
	ds_read_b128 v[206:209], v214 offset:1024
	ds_read_b128 v[210:213], v214 offset:2048
	ds_read_b128 v[214:217], v214 offset:3072
	global_load_lds_dwordx4 v132, s[0:1]
	s_add_i32 m0, s16, 0x2000
	s_nop 0
	global_load_lds_dwordx4 v128, s[0:1]
	s_waitcnt vmcnt(10)
	s_barrier
	s_waitcnt lgkmcnt(0)
	s_setprio 1
	s_waitcnt lgkmcnt(0)
	v_mfma_f32_16x16x32_bf16 v[120:123], v[202:205], v[166:169], v[120:123]
	v_mfma_f32_16x16x32_bf16 v[112:115], v[210:213], v[166:169], v[112:115]
	v_mfma_f32_16x16x32_bf16 v[104:107], v[202:205], v[174:177], v[104:107]
	v_mfma_f32_16x16x32_bf16 v[96:99], v[210:213], v[174:177], v[96:99]
	v_mfma_f32_16x16x32_bf16 v[88:91], v[202:205], v[182:185], v[88:91]
	v_mfma_f32_16x16x32_bf16 v[80:83], v[210:213], v[182:185], v[80:83]
	v_mfma_f32_16x16x32_bf16 v[72:75], v[202:205], v[190:193], v[72:75]
	v_mfma_f32_16x16x32_bf16 v[64:67], v[210:213], v[190:193], v[64:67]
	v_mfma_f32_16x16x32_bf16 v[120:123], v[206:209], v[170:173], v[120:123]
	v_mfma_f32_16x16x32_bf16 v[112:115], v[214:217], v[170:173], v[112:115]
	v_mfma_f32_16x16x32_bf16 v[104:107], v[206:209], v[178:181], v[104:107]
	v_mfma_f32_16x16x32_bf16 v[96:99], v[214:217], v[178:181], v[96:99]
	v_mfma_f32_16x16x32_bf16 v[88:91], v[206:209], v[186:189], v[88:91]
	v_mfma_f32_16x16x32_bf16 v[80:83], v[214:217], v[186:189], v[80:83]
	v_mfma_f32_16x16x32_bf16 v[72:75], v[206:209], v[194:197], v[72:75]
	v_mfma_f32_16x16x32_bf16 v[64:67], v[214:217], v[194:197], v[64:67]
	s_setprio 0
	s_mov_b32 m0, s36
	s_add_u32 s0, s22, 0x80
	s_addc_u32 s1, s23, 0
	s_barrier
	ds_read_b128 v[166:169], v148 offset:49152
	ds_read_b128 v[170:173], v148 offset:50176
	ds_read_b128 v[174:177], v148 offset:51200
	ds_read_b128 v[178:181], v148 offset:52224
	ds_read_b128 v[182:185], v148 offset:53248
	ds_read_b128 v[186:189], v148 offset:54272
	ds_read_b128 v[190:193], v148 offset:55296
	ds_read_b128 v[194:197], v148 offset:56320
	global_load_lds_dwordx4 v134, s[0:1]
	s_mov_b32 m0, s37
	s_nop 0
	global_load_lds_dwordx4 v130, s[0:1]
	s_barrier
	s_waitcnt lgkmcnt(0)
	s_setprio 1
	s_waitcnt lgkmcnt(0)
	v_mfma_f32_16x16x32_bf16 v[60:63], v[150:153], v[166:169], v[60:63]
	v_mfma_f32_16x16x32_bf16 v[56:59], v[158:161], v[166:169], v[56:59]
	v_mfma_f32_16x16x32_bf16 v[44:47], v[150:153], v[174:177], v[44:47]
	v_mfma_f32_16x16x32_bf16 v[40:43], v[158:161], v[174:177], v[40:43]
	v_mfma_f32_16x16x32_bf16 v[28:31], v[150:153], v[182:185], v[28:31]
	v_mfma_f32_16x16x32_bf16 v[24:27], v[158:161], v[182:185], v[24:27]
	v_mfma_f32_16x16x32_bf16 v[12:15], v[150:153], v[190:193], v[12:15]
	v_mfma_f32_16x16x32_bf16 v[8:11], v[158:161], v[190:193], v[8:11]
	v_mfma_f32_16x16x32_bf16 v[60:63], v[154:157], v[170:173], v[60:63]
	v_mfma_f32_16x16x32_bf16 v[56:59], v[162:165], v[170:173], v[56:59]
	v_mfma_f32_16x16x32_bf16 v[44:47], v[154:157], v[178:181], v[44:47]
	v_mfma_f32_16x16x32_bf16 v[40:43], v[162:165], v[178:181], v[40:43]
	v_mfma_f32_16x16x32_bf16 v[28:31], v[154:157], v[186:189], v[28:31]
	v_mfma_f32_16x16x32_bf16 v[24:27], v[162:165], v[186:189], v[24:27]
	v_mfma_f32_16x16x32_bf16 v[12:15], v[154:157], v[194:197], v[12:15]
	v_mfma_f32_16x16x32_bf16 v[8:11], v[162:165], v[194:197], v[8:11]
	s_setprio 0
	s_barrier
	s_add_u32 s16, s18, 0x40080
	s_addc_u32 s17, s19, 0
	s_add_i32 s18, s21, s25
	s_mov_b32 m0, s18
	s_nop 0
	global_load_lds_dwordx4 v132, s[16:17]
	s_add_i32 m0, s18, 0x2000
	s_nop 0
	global_load_lds_dwordx4 v128, s[16:17]
	s_waitcnt vmcnt(10)
	s_barrier
	s_setprio 1
	v_mfma_f32_16x16x32_bf16 v[52:55], v[202:205], v[166:169], v[52:55]
	v_mfma_f32_16x16x32_bf16 v[48:51], v[210:213], v[166:169], v[48:51]
	v_mfma_f32_16x16x32_bf16 v[36:39], v[202:205], v[174:177], v[36:39]
	v_mfma_f32_16x16x32_bf16 v[32:35], v[210:213], v[174:177], v[32:35]
	v_mfma_f32_16x16x32_bf16 v[20:23], v[202:205], v[182:185], v[20:23]
	v_mfma_f32_16x16x32_bf16 v[16:19], v[210:213], v[182:185], v[16:19]
	v_mfma_f32_16x16x32_bf16 v[4:7], v[202:205], v[190:193], v[4:7]
	v_mfma_f32_16x16x32_bf16 v[0:3], v[210:213], v[190:193], v[0:3]
	v_mfma_f32_16x16x32_bf16 v[52:55], v[206:209], v[170:173], v[52:55]
	v_mfma_f32_16x16x32_bf16 v[48:51], v[214:217], v[170:173], v[48:51]
	v_mfma_f32_16x16x32_bf16 v[36:39], v[206:209], v[178:181], v[36:39]
	v_mfma_f32_16x16x32_bf16 v[32:35], v[214:217], v[178:181], v[32:35]
	v_mfma_f32_16x16x32_bf16 v[20:23], v[206:209], v[186:189], v[20:23]
	v_mfma_f32_16x16x32_bf16 v[16:19], v[214:217], v[186:189], v[16:19]
	v_mfma_f32_16x16x32_bf16 v[4:7], v[206:209], v[194:197], v[4:7]
	v_mfma_f32_16x16x32_bf16 v[0:3], v[214:217], v[194:197], v[0:3]
	s_setprio 0
	s_add_i32 s48, s48, 2
	s_add_u32 s14, s14, 0x100
	s_addc_u32 s15, s15, 0
	s_add_u32 s46, s46, 0x100
	s_addc_u32 s47, s47, 0
	s_cmp_gt_u32 s48, 13
	s_barrier
; __device__ __forceinline__ unsigned cvt_pk_bf16(float lo, float hi) { unsigned r; asm volatile("v_cvt_pk_bf16_f32 %0, %1, %2" : "=v"(r) : "v"(lo), "v"(hi)); return r; }
; __device__ __forceinline__ float silu_f(float a) { return a * __builtin_amdgcn_rcpf(1.0f + __expf(-a)); }
; template <class Epi, class Sched>
; __device__ __forceinline__ void gemm_phase(LAS unsigned char* lds, const Gemm g, const Sched& S, const Epi& E) {
;     ...
;         const bool has_next = S.next(ui + 1, nxt);
;         const char* nA = has_next ? (const char*)g.A + (size_t)nxt.pm * tstep : cA; const char* nB = has_next ? (const char*)g.Bt + (size_t)nxt.pn * tstep : cB;
;     __device__ __forceinline__ void operator()(const AccT& acc, const Unit& u, int wr, int wc, int fr, int fq) const {
;     ...
;         const int row0 = u.pm * 256 + wr * 64 + fr, hc0 = u.pn * 128 + wc * 32 + 8 * fq;
; #pragma unroll
;         for (int ai = 0; ai < 2; ++ai)
; #pragma unroll
;             for (int m = 0; m < 4; ++m) {
;                 const f32x4 a0 = acc[ai][0][m][0], a1 = acc[ai][0][m][1], b0 = acc[ai][1][m][0], b1 = acc[ai][1][m][1];
;                 u32x4 w;
;                 w.x = cvt_pk_bf16(silu_f(a0[0]) * b0[0], silu_f(a0[1]) * b0[1]); w.y = cvt_pk_bf16(silu_f(a0[2]) * b0[2], silu_f(a0[3]) * b0[3]);
;                 w.z = cvt_pk_bf16(silu_f(a1[0]) * b1[0], silu_f(a1[1]) * b1[1]); w.w = cvt_pk_bf16(silu_f(a1[2]) * b1[2], silu_f(a1[3]) * b1[3]);
;                 *(u32x4*)(H + (size_t)(row0 + ai * 128 + m * 16) * DFF + hc0) = w;
;             }
	s_cbranch_scc0 .LBB0_235
	v_mul_f32_e32 v152, 0xbfb8aa3b, v124
	v_mov_b32_e32 v151, v145
	v_mov_b32_e32 v150, v144
	s_lshl_b32 s5, s12, 8
	v_exp_f32_e32 v153, v152
	v_mul_f32_e32 v152, 0xbfb8aa3b, v125
	s_add_i32 s5, s5, s34
	v_exp_f32_e32 v154, v152
	v_add_u32_e32 v150, s5, v150
	s_lshl_b32 s5, s43, 7
	s_or_b32 s5, s5, s35
	v_lshl_add_u32 v152, v151, 3, s5
	v_add_f32_e32 v151, 1.0, v153
	v_rcp_f32_e32 v151, v151
	v_add_f32_e32 v153, 1.0, v154
	v_rcp_f32_e32 v154, v153
	v_ashrrev_i32_e32 v153, 31, v152
	v_mul_f32_e32 v124, v124, v151
	v_mul_f32_e32 v120, v124, v120
	v_mul_f32_e32 v124, v125, v154
	v_mul_f32_e32 v125, 0xbfb8aa3b, v126
	v_exp_f32_e32 v125, v125
	v_mul_f32_e32 v151, 0xbfb8aa3b, v127
	v_exp_f32_e32 v151, v151
	v_mul_f32_e32 v121, v124, v121
	v_add_f32_e32 v124, 1.0, v125
	v_rcp_f32_e32 v124, v124
	v_add_f32_e32 v125, 1.0, v151
	v_rcp_f32_e32 v125, v125
	v_cvt_pk_bf16_f32 v120, v120, v121
	v_mul_f32_e32 v121, v126, v124
	v_mul_f32_e32 v124, 0xbfb8aa3b, v116
	v_mul_f32_e32 v121, v121, v122
	v_mul_f32_e32 v122, v127, v125
	v_exp_f32_e32 v124, v124
	v_mul_f32_e32 v125, 0xbfb8aa3b, v117
	v_exp_f32_e32 v125, v125
	v_mul_f32_e32 v122, v122, v123
	v_add_f32_e32 v123, 1.0, v124
	v_rcp_f32_e32 v123, v123
	v_add_f32_e32 v124, 1.0, v125
	v_rcp_f32_e32 v124, v124
	v_cvt_pk_bf16_f32 v121, v121, v122
	v_mul_f32_e32 v116, v116, v123
	v_mul_f32_e32 v112, v116, v112
	v_mul_f32_e32 v116, v117, v124
	v_mul_f32_e32 v117, 0xbfb8aa3b, v118
	v_exp_f32_e32 v117, v117
	v_mul_f32_e32 v122, 0xbfb8aa3b, v119
	v_exp_f32_e32 v122, v122
	v_mul_f32_e32 v113, v116, v113
	v_add_f32_e32 v116, 1.0, v117
	v_rcp_f32_e32 v116, v116
	v_add_f32_e32 v117, 1.0, v122
	v_rcp_f32_e32 v117, v117
	v_cvt_pk_bf16_f32 v122, v112, v113
	v_mul_f32_e32 v112, v118, v116
	v_mul_f32_e32 v118, 0xbfb8aa3b, v108
	v_mul_f32_e32 v113, v119, v117
	v_exp_f32_e32 v118, v118
	v_mul_f32_e32 v119, 0xbfb8aa3b, v109
	v_exp_f32_e32 v119, v119
	v_mul_f32_e32 v112, v112, v114
	v_add_f32_e32 v118, 1.0, v118
	v_rcp_f32_e32 v118, v118
	v_add_f32_e32 v119, 1.0, v119
	v_rcp_f32_e32 v119, v119
	v_mul_f32_e32 v113, v113, v115
	v_cvt_pk_bf16_f32 v123, v112, v113
	v_mov_b64_e32 v[112:113], s[82:83]
	v_mad_i64_i32 v[116:117], s[14:15], v150, s42, v[112:113]
	v_lshlrev_b64 v[114:115], 1, v[152:153]
	v_mul_f32_e32 v108, v108, v118
	v_lshl_add_u64 v[116:117], v[116:117], 0, v[114:115]
	v_mul_f32_e32 v104, v108, v104
	v_mul_f32_e32 v108, v109, v119
	v_mul_f32_e32 v109, 0xbfb8aa3b, v110
	global_store_dwordx4 v[116:117], v[120:123], off
	v_exp_f32_e32 v109, v109
	v_mul_f32_e32 v116, 0xbfb8aa3b, v111
	v_exp_f32_e32 v116, v116
	v_mul_f32_e32 v105, v108, v105
	v_add_f32_e32 v108, 1.0, v109
	v_rcp_f32_e32 v108, v108
	v_add_f32_e32 v109, 1.0, v116
	v_rcp_f32_e32 v109, v109
	v_cvt_pk_bf16_f32 v104, v104, v105
	v_mul_f32_e32 v105, v110, v108
	v_mul_f32_e32 v108, 0xbfb8aa3b, v100
	v_mul_f32_e32 v105, v105, v106
	v_mul_f32_e32 v106, v111, v109
	v_exp_f32_e32 v108, v108
	v_mul_f32_e32 v109, 0xbfb8aa3b, v101
	v_exp_f32_e32 v109, v109
	v_mul_f32_e32 v106, v106, v107
	v_add_f32_e32 v107, 1.0, v108
	v_rcp_f32_e32 v107, v107
	v_add_f32_e32 v108, 1.0, v109
	v_rcp_f32_e32 v108, v108
	v_cvt_pk_bf16_f32 v105, v105, v106
	v_mul_f32_e32 v100, v100, v107
	v_mul_f32_e32 v96, v100, v96
	v_mul_f32_e32 v100, v101, v108
	v_mul_f32_e32 v101, 0xbfb8aa3b, v102
	v_exp_f32_e32 v101, v101
	v_mul_f32_e32 v106, 0xbfb8aa3b, v103
	v_exp_f32_e32 v106, v106
	v_mul_f32_e32 v97, v100, v97
	v_add_f32_e32 v100, 1.0, v101
	v_rcp_f32_e32 v100, v100
	v_add_f32_e32 v101, 1.0, v106
	v_rcp_f32_e32 v101, v101
	v_cvt_pk_bf16_f32 v106, v96, v97
	v_mul_f32_e32 v96, v102, v100
	v_mul_f32_e32 v96, v96, v98
	v_mul_f32_e32 v97, v103, v101
	v_mul_f32_e32 v98, 0xbfb8aa3b, v92
	v_mul_f32_e32 v97, v97, v99
	v_exp_f32_e32 v98, v98
	v_mul_f32_e32 v99, 0xbfb8aa3b, v93
	v_exp_f32_e32 v99, v99
	v_cvt_pk_bf16_f32 v107, v96, v97
	v_add_f32_e32 v98, 1.0, v98
	v_rcp_f32_e32 v98, v98
	v_add_f32_e32 v99, 1.0, v99
	v_rcp_f32_e32 v99, v99
	v_add_u32_e32 v96, 16, v150
	v_mad_i64_i32 v[96:97], s[14:15], v96, s42, v[112:113]
	v_mul_f32_e32 v92, v92, v98
	v_lshl_add_u64 v[96:97], v[96:97], 0, v[114:115]
	v_mul_f32_e32 v88, v92, v88
	v_mul_f32_e32 v92, v93, v99
	v_mul_f32_e32 v93, 0xbfb8aa3b, v94
	global_store_dwordx4 v[96:97], v[104:107], off
	v_exp_f32_e32 v93, v93
	v_mul_f32_e32 v96, 0xbfb8aa3b, v95
	v_exp_f32_e32 v96, v96
	v_mul_f32_e32 v89, v92, v89
	v_add_f32_e32 v92, 1.0, v93
	v_rcp_f32_e32 v92, v92
	v_add_f32_e32 v93, 1.0, v96
	v_rcp_f32_e32 v93, v93
	v_cvt_pk_bf16_f32 v88, v88, v89
	v_mul_f32_e32 v89, v94, v92
	v_mul_f32_e32 v92, 0xbfb8aa3b, v84
	v_mul_f32_e32 v89, v89, v90
	v_mul_f32_e32 v90, v95, v93
	v_exp_f32_e32 v92, v92
	v_mul_f32_e32 v93, 0xbfb8aa3b, v85
	v_exp_f32_e32 v93, v93
	v_mul_f32_e32 v90, v90, v91
	v_add_f32_e32 v91, 1.0, v92
	v_rcp_f32_e32 v91, v91
	v_add_f32_e32 v92, 1.0, v93
	v_rcp_f32_e32 v92, v92
	v_cvt_pk_bf16_f32 v89, v89, v90
	v_mul_f32_e32 v84, v84, v91
	v_mul_f32_e32 v80, v84, v80
	v_mul_f32_e32 v84, v85, v92
	v_mul_f32_e32 v85, 0xbfb8aa3b, v86
	v_exp_f32_e32 v85, v85
	v_mul_f32_e32 v90, 0xbfb8aa3b, v87
	v_exp_f32_e32 v90, v90
	v_mul_f32_e32 v81, v84, v81
	v_add_f32_e32 v84, 1.0, v85
	v_rcp_f32_e32 v84, v84
	v_add_f32_e32 v85, 1.0, v90
	v_rcp_f32_e32 v85, v85
	v_cvt_pk_bf16_f32 v90, v80, v81
	v_mul_f32_e32 v80, v86, v84
	v_mul_f32_e32 v80, v80, v82
	v_mul_f32_e32 v81, v87, v85
	v_mul_f32_e32 v82, 0xbfb8aa3b, v76
	v_mul_f32_e32 v81, v81, v83
	v_exp_f32_e32 v82, v82
	v_mul_f32_e32 v83, 0xbfb8aa3b, v77
	v_exp_f32_e32 v83, v83
	v_cvt_pk_bf16_f32 v91, v80, v81
	v_add_f32_e32 v82, 1.0, v82
	v_rcp_f32_e32 v82, v82
	v_add_f32_e32 v83, 1.0, v83
	v_rcp_f32_e32 v83, v83
; __device__ __forceinline__ unsigned cvt_pk_bf16(float lo, float hi) { unsigned r; asm volatile("v_cvt_pk_bf16_f32 %0, %1, %2" : "=v"(r) : "v"(lo), "v"(hi)); return r; }
; __device__ __forceinline__ float silu_f(float a) { return a * __builtin_amdgcn_rcpf(1.0f + __expf(-a)); }
;     __device__ __forceinline__ void operator()(const AccT& acc, const Unit& u, int wr, int wc, int fr, int fq) const {
;     ...
;         const int row0 = u.pm * 256 + wr * 64 + fr, hc0 = u.pn * 128 + wc * 32 + 8 * fq;
; #pragma unroll
;         for (int ai = 0; ai < 2; ++ai)
; #pragma unroll
;             for (int m = 0; m < 4; ++m) {
;                 const f32x4 a0 = acc[ai][0][m][0], a1 = acc[ai][0][m][1], b0 = acc[ai][1][m][0], b1 = acc[ai][1][m][1];
;                 u32x4 w;
;                 w.x = cvt_pk_bf16(silu_f(a0[0]) * b0[0], silu_f(a0[1]) * b0[1]); w.y = cvt_pk_bf16(silu_f(a0[2]) * b0[2], silu_f(a0[3]) * b0[3]);
;                 w.z = cvt_pk_bf16(silu_f(a1[0]) * b1[0], silu_f(a1[1]) * b1[1]); w.w = cvt_pk_bf16(silu_f(a1[2]) * b1[2], silu_f(a1[3]) * b1[3]);
;                 *(u32x4*)(H + (size_t)(row0 + ai * 128 + m * 16) * DFF + hc0) = w;
;             }
	v_add_u32_e32 v80, 32, v150
	v_mad_i64_i32 v[80:81], s[14:15], v80, s42, v[112:113]
	v_mul_f32_e32 v76, v76, v82
	v_lshl_add_u64 v[80:81], v[80:81], 0, v[114:115]
	v_mul_f32_e32 v72, v76, v72
	v_mul_f32_e32 v76, v77, v83
	v_mul_f32_e32 v77, 0xbfb8aa3b, v78
	global_store_dwordx4 v[80:81], v[88:91], off
	v_exp_f32_e32 v77, v77
	v_mul_f32_e32 v80, 0xbfb8aa3b, v79
	v_exp_f32_e32 v80, v80
	v_mul_f32_e32 v73, v76, v73
	v_add_f32_e32 v76, 1.0, v77
	v_rcp_f32_e32 v76, v76
	v_add_f32_e32 v77, 1.0, v80
	v_rcp_f32_e32 v77, v77
	v_cvt_pk_bf16_f32 v72, v72, v73
	v_mul_f32_e32 v73, v78, v76
	v_mul_f32_e32 v76, 0xbfb8aa3b, v68
	v_mul_f32_e32 v73, v73, v74
	v_mul_f32_e32 v74, v79, v77
	v_exp_f32_e32 v76, v76
	v_mul_f32_e32 v77, 0xbfb8aa3b, v69
	v_exp_f32_e32 v77, v77
	v_mul_f32_e32 v74, v74, v75
	v_add_f32_e32 v75, 1.0, v76
	v_rcp_f32_e32 v75, v75
	v_add_f32_e32 v76, 1.0, v77
	v_rcp_f32_e32 v76, v76
	v_cvt_pk_bf16_f32 v73, v73, v74
	v_mul_f32_e32 v68, v68, v75
	v_mul_f32_e32 v64, v68, v64
	v_mul_f32_e32 v68, v69, v76
	v_mul_f32_e32 v69, 0xbfb8aa3b, v70
	v_exp_f32_e32 v69, v69
	v_mul_f32_e32 v74, 0xbfb8aa3b, v71
	v_exp_f32_e32 v74, v74
	v_mul_f32_e32 v65, v68, v65
	v_add_f32_e32 v68, 1.0, v69
	v_rcp_f32_e32 v68, v68
	v_add_f32_e32 v69, 1.0, v74
	v_rcp_f32_e32 v69, v69
	v_cvt_pk_bf16_f32 v74, v64, v65
	v_mul_f32_e32 v64, v70, v68
	v_mul_f32_e32 v64, v64, v66
	v_mul_f32_e32 v65, v71, v69
	v_mul_f32_e32 v66, 0xbfb8aa3b, v60
	v_mul_f32_e32 v65, v65, v67
	v_exp_f32_e32 v66, v66
	v_mul_f32_e32 v67, 0xbfb8aa3b, v61
	v_cvt_pk_bf16_f32 v75, v64, v65
	v_add_u32_e32 v64, 48, v150
	v_exp_f32_e32 v67, v67
	v_mad_i64_i32 v[64:65], s[14:15], v64, s42, v[112:113]
	v_lshl_add_u64 v[64:65], v[64:65], 0, v[114:115]
	global_store_dwordx4 v[64:65], v[72:75], off
	v_add_f32_e32 v64, 1.0, v66
	v_rcp_f32_e32 v64, v64
	v_add_f32_e32 v65, 1.0, v67
	v_rcp_f32_e32 v65, v65
	v_add_u32_e32 v66, 0x80, v150
	v_mul_f32_e32 v60, v60, v64
	v_mul_f32_e32 v52, v60, v52
	v_mul_f32_e32 v60, v61, v65
	v_mul_f32_e32 v61, 0xbfb8aa3b, v62
	v_exp_f32_e32 v61, v61
	v_mul_f32_e32 v64, 0xbfb8aa3b, v63
	v_exp_f32_e32 v64, v64
	v_mul_f32_e32 v53, v60, v53
	v_add_f32_e32 v60, 1.0, v61
	v_rcp_f32_e32 v60, v60
	v_add_f32_e32 v61, 1.0, v64
	v_rcp_f32_e32 v61, v61
	v_cvt_pk_bf16_f32 v52, v52, v53
	v_mul_f32_e32 v53, v62, v60
	v_mul_f32_e32 v60, 0xbfb8aa3b, v56
	v_exp_f32_e32 v60, v60
	v_mul_f32_e32 v53, v53, v54
	v_mul_f32_e32 v54, v63, v61
	v_mul_f32_e32 v61, 0xbfb8aa3b, v57
	v_exp_f32_e32 v61, v61
	v_mul_f32_e32 v54, v54, v55
	v_add_f32_e32 v55, 1.0, v60
	v_rcp_f32_e32 v55, v55
	v_add_f32_e32 v60, 1.0, v61
	v_rcp_f32_e32 v60, v60
	v_cvt_pk_bf16_f32 v53, v53, v54
	v_mul_f32_e32 v54, v56, v55
	v_mul_f32_e32 v55, 0xbfb8aa3b, v58
	v_exp_f32_e32 v55, v55
	v_mul_f32_e32 v56, 0xbfb8aa3b, v59
	v_exp_f32_e32 v56, v56
	v_mul_f32_e32 v48, v54, v48
	v_mul_f32_e32 v54, v57, v60
	v_mul_f32_e32 v49, v54, v49
	v_add_f32_e32 v54, 1.0, v55
	v_rcp_f32_e32 v55, v54
	v_add_f32_e32 v54, 1.0, v56
	v_rcp_f32_e32 v56, v54
	v_cvt_pk_bf16_f32 v54, v48, v49
	v_mul_f32_e32 v48, v58, v55
	v_mul_f32_e32 v48, v48, v50
	v_mul_f32_e32 v49, v59, v56
	v_mul_f32_e32 v50, 0xbfb8aa3b, v44
	v_mul_f32_e32 v49, v49, v51
	v_exp_f32_e32 v50, v50
	v_mul_f32_e32 v51, 0xbfb8aa3b, v45
	v_exp_f32_e32 v51, v51
	v_cvt_pk_bf16_f32 v55, v48, v49
	v_add_f32_e32 v50, 1.0, v50
	v_rcp_f32_e32 v50, v50
	v_add_f32_e32 v51, 1.0, v51
	v_rcp_f32_e32 v51, v51
	v_mad_i64_i32 v[48:49], s[14:15], v66, s42, v[112:113]
	v_mul_f32_e32 v44, v44, v50
	v_mul_f32_e32 v36, v44, v36
	v_mul_f32_e32 v44, v45, v51
	v_mul_f32_e32 v45, 0xbfb8aa3b, v46
	v_exp_f32_e32 v45, v45
	v_lshl_add_u64 v[48:49], v[48:49], 0, v[114:115]
	global_store_dwordx4 v[48:49], v[52:55], off
	v_mul_f32_e32 v48, 0xbfb8aa3b, v47
	v_exp_f32_e32 v48, v48
	v_mul_f32_e32 v37, v44, v37
	v_add_f32_e32 v44, 1.0, v45
	v_rcp_f32_e32 v44, v44
	v_add_f32_e32 v45, 1.0, v48
	v_rcp_f32_e32 v45, v45
	v_cvt_pk_bf16_f32 v36, v36, v37
	v_mul_f32_e32 v37, v46, v44
	v_mul_f32_e32 v44, 0xbfb8aa3b, v40
	v_exp_f32_e32 v44, v44
	v_mul_f32_e32 v37, v37, v38
	v_mul_f32_e32 v38, v47, v45
	v_mul_f32_e32 v45, 0xbfb8aa3b, v41
	v_exp_f32_e32 v45, v45
	v_mul_f32_e32 v38, v38, v39
	v_add_f32_e32 v39, 1.0, v44
	v_rcp_f32_e32 v39, v39
	v_add_f32_e32 v44, 1.0, v45
	v_rcp_f32_e32 v44, v44
; __device__ __forceinline__ unsigned cvt_pk_bf16(float lo, float hi) { unsigned r; asm volatile("v_cvt_pk_bf16_f32 %0, %1, %2" : "=v"(r) : "v"(lo), "v"(hi)); return r; }
; __device__ __forceinline__ float silu_f(float a) { return a * __builtin_amdgcn_rcpf(1.0f + __expf(-a)); }
; #define PG8_WAIT_V(n) asm volatile("s_waitcnt vmcnt(" #n ")" ::: "memory")
; #define PG8_BAR __builtin_amdgcn_s_barrier()
; template <class Epi, class Sched>
; __device__ __forceinline__ void gemm_phase(LAS unsigned char* lds, const Gemm g, const Sched& S, const Epi& E) {
;     ...
;         if (!has_next) break;
; #pragma unroll
;         for (int a = 0; a < 2; ++a)
; #pragma unroll
;             for (int b = 0; b < 2; ++b)
; #pragma unroll
;                 for (int m = 0; m < 4; ++m)
; #pragma unroll
;                     for (int n = 0; n < 2; ++n) acc[a][b][m][n] = (f32x4){0.f, 0.f, 0.f, 0.f};
;         cur = nxt; cA = nA; cB = nB; ++ui;
;     }
;     PG8_WAIT_V(0);
;     if (wr == 0) PG8_BAR;
;     PG8_BAR;
;     __device__ __forceinline__ void operator()(const AccT& acc, const Unit& u, int wr, int wc, int fr, int fq) const {
;     ...
;         const int row0 = u.pm * 256 + wr * 64 + fr, hc0 = u.pn * 128 + wc * 32 + 8 * fq;
; #pragma unroll
;         for (int ai = 0; ai < 2; ++ai)
; #pragma unroll
;             for (int m = 0; m < 4; ++m) {
;                 const f32x4 a0 = acc[ai][0][m][0], a1 = acc[ai][0][m][1], b0 = acc[ai][1][m][0], b1 = acc[ai][1][m][1];
;                 u32x4 w;
;                 w.x = cvt_pk_bf16(silu_f(a0[0]) * b0[0], silu_f(a0[1]) * b0[1]); w.y = cvt_pk_bf16(silu_f(a0[2]) * b0[2], silu_f(a0[3]) * b0[3]);
;                 w.z = cvt_pk_bf16(silu_f(a1[0]) * b1[0], silu_f(a1[1]) * b1[1]); w.w = cvt_pk_bf16(silu_f(a1[2]) * b1[2], silu_f(a1[3]) * b1[3]);
;                 *(u32x4*)(H + (size_t)(row0 + ai * 128 + m * 16) * DFF + hc0) = w;
;             }
	v_cvt_pk_bf16_f32 v37, v37, v38
	v_mul_f32_e32 v38, v40, v39
	v_mul_f32_e32 v39, 0xbfb8aa3b, v42
	v_exp_f32_e32 v39, v39
	v_mul_f32_e32 v40, 0xbfb8aa3b, v43
	v_exp_f32_e32 v40, v40
	v_mul_f32_e32 v32, v38, v32
	v_mul_f32_e32 v38, v41, v44
	v_mul_f32_e32 v33, v38, v33
	v_add_f32_e32 v38, 1.0, v39
	v_rcp_f32_e32 v39, v38
	v_add_f32_e32 v38, 1.0, v40
	v_rcp_f32_e32 v40, v38
	v_cvt_pk_bf16_f32 v38, v32, v33
	v_mul_f32_e32 v32, v42, v39
	v_mul_f32_e32 v32, v32, v34
	v_mul_f32_e32 v33, v43, v40
	v_mul_f32_e32 v34, 0xbfb8aa3b, v28
	v_mul_f32_e32 v33, v33, v35
	v_exp_f32_e32 v34, v34
	v_mul_f32_e32 v35, 0xbfb8aa3b, v29
	v_exp_f32_e32 v35, v35
	v_cvt_pk_bf16_f32 v39, v32, v33
	v_add_f32_e32 v34, 1.0, v34
	v_rcp_f32_e32 v34, v34
	v_add_f32_e32 v35, 1.0, v35
	v_rcp_f32_e32 v35, v35
	v_add_u32_e32 v32, 0x90, v150
	v_mul_f32_e32 v28, v28, v34
	v_mul_f32_e32 v20, v28, v20
	v_mul_f32_e32 v28, v29, v35
	v_mul_f32_e32 v29, 0xbfb8aa3b, v30
	v_exp_f32_e32 v29, v29
	v_mad_i64_i32 v[32:33], s[14:15], v32, s42, v[112:113]
	v_lshl_add_u64 v[32:33], v[32:33], 0, v[114:115]
	global_store_dwordx4 v[32:33], v[36:39], off
	v_mul_f32_e32 v32, 0xbfb8aa3b, v31
	v_exp_f32_e32 v32, v32
	v_mul_f32_e32 v21, v28, v21
	v_add_f32_e32 v28, 1.0, v29
	v_rcp_f32_e32 v28, v28
	v_add_f32_e32 v29, 1.0, v32
	v_rcp_f32_e32 v29, v29
	v_cvt_pk_bf16_f32 v20, v20, v21
	v_mul_f32_e32 v21, v30, v28
	v_mul_f32_e32 v28, 0xbfb8aa3b, v24
	v_exp_f32_e32 v28, v28
	v_mul_f32_e32 v21, v21, v22
	v_mul_f32_e32 v22, v31, v29
	v_mul_f32_e32 v29, 0xbfb8aa3b, v25
	v_exp_f32_e32 v29, v29
	v_mul_f32_e32 v22, v22, v23
	v_add_f32_e32 v23, 1.0, v28
	v_rcp_f32_e32 v23, v23
	v_add_f32_e32 v28, 1.0, v29
	v_rcp_f32_e32 v28, v28
	v_cvt_pk_bf16_f32 v21, v21, v22
	v_mul_f32_e32 v22, v24, v23
	v_mul_f32_e32 v23, 0xbfb8aa3b, v26
	v_exp_f32_e32 v23, v23
	v_mul_f32_e32 v24, 0xbfb8aa3b, v27
	v_exp_f32_e32 v24, v24
	v_mul_f32_e32 v16, v22, v16
	v_mul_f32_e32 v22, v25, v28
	v_mul_f32_e32 v17, v22, v17
	v_add_f32_e32 v22, 1.0, v23
	v_rcp_f32_e32 v23, v22
	v_add_f32_e32 v22, 1.0, v24
	v_rcp_f32_e32 v24, v22
	v_cvt_pk_bf16_f32 v22, v16, v17
	v_mul_f32_e32 v16, v26, v23
	v_mul_f32_e32 v16, v16, v18
	v_mul_f32_e32 v17, v27, v24
	v_mul_f32_e32 v18, 0xbfb8aa3b, v12
	v_mul_f32_e32 v17, v17, v19
	v_exp_f32_e32 v18, v18
	v_mul_f32_e32 v19, 0xbfb8aa3b, v13
	v_exp_f32_e32 v19, v19
	v_cvt_pk_bf16_f32 v23, v16, v17
	v_add_f32_e32 v18, 1.0, v18
	v_rcp_f32_e32 v18, v18
	v_add_f32_e32 v19, 1.0, v19
	v_rcp_f32_e32 v19, v19
	v_add_u32_e32 v16, 0xa0, v150
	v_mul_f32_e32 v12, v12, v18
	v_mul_f32_e32 v4, v12, v4
	v_mul_f32_e32 v12, v13, v19
	v_mul_f32_e32 v13, 0xbfb8aa3b, v14
	v_exp_f32_e32 v13, v13
	v_mad_i64_i32 v[16:17], s[14:15], v16, s42, v[112:113]
	v_lshl_add_u64 v[16:17], v[16:17], 0, v[114:115]
	global_store_dwordx4 v[16:17], v[20:23], off
	v_mul_f32_e32 v16, 0xbfb8aa3b, v15
	v_exp_f32_e32 v16, v16
	v_mul_f32_e32 v5, v12, v5
	v_add_f32_e32 v12, 1.0, v13
	v_rcp_f32_e32 v12, v12
	v_add_f32_e32 v13, 1.0, v16
	v_rcp_f32_e32 v13, v13
	v_cvt_pk_bf16_f32 v4, v4, v5
	v_mul_f32_e32 v5, v14, v12
	v_mul_f32_e32 v12, 0xbfb8aa3b, v8
	v_exp_f32_e32 v12, v12
	v_mul_f32_e32 v5, v5, v6
	v_mul_f32_e32 v6, v15, v13
	v_mul_f32_e32 v13, 0xbfb8aa3b, v9
	v_exp_f32_e32 v13, v13
	v_mul_f32_e32 v6, v6, v7
	v_add_f32_e32 v7, 1.0, v12
	v_rcp_f32_e32 v7, v7
	v_add_f32_e32 v12, 1.0, v13
	v_rcp_f32_e32 v12, v12
	v_cvt_pk_bf16_f32 v5, v5, v6
	v_mul_f32_e32 v6, v8, v7
	v_mul_f32_e32 v7, 0xbfb8aa3b, v10
	v_exp_f32_e32 v7, v7
	v_mul_f32_e32 v8, 0xbfb8aa3b, v11
	v_exp_f32_e32 v8, v8
	v_mul_f32_e32 v0, v6, v0
	v_mul_f32_e32 v6, v9, v12
	v_mul_f32_e32 v1, v6, v1
	v_add_f32_e32 v6, 1.0, v7
	v_rcp_f32_e32 v7, v6
	v_add_f32_e32 v6, 1.0, v8
	v_rcp_f32_e32 v8, v6
	v_cvt_pk_bf16_f32 v6, v0, v1
	v_mul_f32_e32 v0, v10, v7
	v_mul_f32_e32 v0, v0, v2
	v_mul_f32_e32 v1, v11, v8
	v_mul_f32_e32 v1, v1, v3
	v_cvt_pk_bf16_f32 v7, v0, v1
	v_add_u32_e32 v0, 0xb0, v150
	v_mad_i64_i32 v[0:1], s[14:15], v0, s42, v[112:113]
	v_lshl_add_u64 v[0:1], v[0:1], 0, v[114:115]
	s_and_b64 vcc, exec, s[2:3]
	s_mov_b32 s43, s4
	s_mov_b32 s12, s6
	s_mov_b64 s[18:19], s[10:11]
	s_mov_b64 s[14:15], s[8:9]
	global_store_dwordx4 v[0:1], v[4:7], off
	s_cbranch_vccz .LBB0_232
	s_waitcnt vmcnt(0)
	s_cmpk_gt_u32 s24, 0xff
	s_cbranch_scc1 .LBB0_239
	s_barrier

; #define PG8_STAGE(bufoff, gbase, voff) do { _Pragma("unroll") for (int _i = 0; _i < 2; ++_i) \
;         __builtin_amdgcn_global_load_lds((const unsigned*)((const char*)(gbase) + (voff)[_i]), (LAS unsigned*)(lds + (bufoff) + ldsw + _i * 8192), 16, 0, 0); } while (0)
; #define PG8_LDA(dst, b, h) do { _Pragma("unroll") for (int m = 0; m < 4; ++m) _Pragma("unroll") for (int k = 0; k < 2; ++k) dst[m][k] = *(const LAS bf16x8*)(lds + PG8_SA(b, h) + aoff + m * 2048 + k * 1024); } while (0)
; #define PG8_WAIT_V(n) asm volatile("s_waitcnt vmcnt(" #n ")" ::: "memory")
; #define PG8_WAIT_L(n) asm volatile("s_waitcnt lgkmcnt(" #n ")" ::: "memory")
; template <class Epi, class Sched>
; __device__ __forceinline__ void gemm_phase(LAS unsigned char* lds, const Gemm g, const Sched& S, const Epi& E) {
;     ...
;         for (int t = 0; t < nt; t += 2) {
;             const bool last = (t == nt - 2);
;             const char* a1 = cA + (size_t)(t + 1) * kstep;
;             const char* a2 = last ? nA : cA + (size_t)(t + 2) * kstep; const char* b2 = last ? nB : cB + (size_t)(t + 2) * kstep;
;             const char* a3 = a2 + kstep; const char* b3 = b2 + kstep;
;             PG8_LDB(B0, 0, 0); PG8_SCHED; PG8_LDA(At, 0, 0); PG8_STAGE(PG8_SA(1, 1), a1 + hstep, voffA);
;             PG8_WAIT_L(8); PG8_BAR; PG8_WAIT_L(0); PG8_MMA(0, 0, At, B0); PG8_BAR; PG8_SCHED;
;             PG8_LDB(B1, 0, 1); PG8_STAGE(PG8_SB(0, 0), b2, voffB);
;             PG8_BAR; PG8_WAIT_L(0); PG8_MMA(0, 1, At, B1); PG8_BAR;
;             PG8_LDA(At, 0, 1); PG8_STAGE(PG8_SA(0, 0), a2, voffA);
;             PG8_BAR; PG8_WAIT_L(0); PG8_MMA(1, 0, At, B0); PG8_BAR; PG8_SCHED;
;             PG8_STAGE(PG8_SB(0, 1), b2 + hstep, voffB);
;             PG8_WAIT_V(6); PG8_BAR; PG8_MMA(1, 1, At, B1); PG8_BAR;
;             PG8_LDB(B0, 1, 0); PG8_SCHED; PG8_LDA(At, 1, 0); PG8_STAGE(PG8_SA(0, 1), a2 + hstep, voffA);
;             PG8_WAIT_L(8); PG8_BAR; PG8_WAIT_L(0); PG8_MMA(0, 0, At, B0); PG8_BAR; PG8_SCHED;
;             PG8_LDB(B1, 1, 1); PG8_STAGE(PG8_SB(1, 0), b3, voffB);
;             PG8_BAR; PG8_WAIT_L(0); PG8_MMA(0, 1, At, B1); PG8_BAR;
;             PG8_LDA(At, 1, 1); PG8_STAGE(PG8_SA(1, 0), a3, voffA);
;             PG8_BAR; PG8_WAIT_L(0); PG8_MMA(1, 0, At, B0); PG8_BAR; PG8_SCHED;
;             PG8_STAGE(PG8_SB(1, 1), b3 + hstep, voffB);
;             PG8_WAIT_V(6); PG8_BAR; PG8_MMA(1, 1, At, B1); PG8_BAR;
.LBB0_304:
	s_add_u32 s0, s28, 0x100
	s_addc_u32 s67, s29, 0
	s_mov_b32 s68, -2
	ds_read_b128 v[144:147], v165
	ds_read_b128 v[148:151], v165 offset:1024
	ds_read_b128 v[152:155], v165 offset:2048
	ds_read_b128 v[156:159], v165 offset:3072
	s_add_u32 s28, s26, 0x100
	s_addc_u32 s29, s27, 0
	s_cmp_eq_u32 s68, 40
	s_cselect_b32 s37, s5, s29
	s_cselect_b32 s36, s4, s28
	s_cselect_b32 s35, s7, s67
	s_cselect_b32 s34, s6, s0
	v_lshl_add_u64 v[160:161], s[26:27], 0, v[136:137]
	s_add_i32 m0, s42, 0xc000
	ds_read_b128 v[168:171], v166
	ds_read_b128 v[172:175], v166 offset:1024
	ds_read_b128 v[176:179], v166 offset:2048
	ds_read_b128 v[180:183], v166 offset:3072
	ds_read_b128 v[184:187], v166 offset:4096
	ds_read_b128 v[188:191], v166 offset:5120
	ds_read_b128 v[192:195], v166 offset:6144
	ds_read_b128 v[196:199], v166 offset:7168
	global_load_lds_dwordx4 v[160:161], off
	v_lshl_add_u64 v[160:161], s[26:27], 0, v[138:139]
	s_add_i32 m0, s42, 0xe000
	s_nop 0
	global_load_lds_dwordx4 v[160:161], off
	s_waitcnt lgkmcnt(8)
	s_waitcnt vmcnt(10)
	s_barrier
	s_waitcnt lgkmcnt(0)
	s_setprio 1
	s_waitcnt lgkmcnt(0)
	v_mfma_f32_16x16x32_bf16 v[124:127], v[144:147], v[168:171], 0
	v_mfma_f32_16x16x32_bf16 v[120:123], v[152:155], v[168:171], 0
	v_mfma_f32_16x16x32_bf16 v[116:119], v[144:147], v[176:179], 0
	v_mfma_f32_16x16x32_bf16 v[104:107], v[152:155], v[176:179], 0
	v_mfma_f32_16x16x32_bf16 v[96:99], v[144:147], v[184:187], 0
	v_mfma_f32_16x16x32_bf16 v[88:91], v[152:155], v[184:187], 0
	v_mfma_f32_16x16x32_bf16 v[80:83], v[144:147], v[192:195], 0
	v_mfma_f32_16x16x32_bf16 v[72:75], v[152:155], v[192:195], 0
	v_mfma_f32_16x16x32_bf16 v[124:127], v[148:151], v[172:175], v[124:127]
	v_mfma_f32_16x16x32_bf16 v[120:123], v[156:159], v[172:175], v[120:123]
	v_mfma_f32_16x16x32_bf16 v[116:119], v[148:151], v[180:183], v[116:119]
	v_mfma_f32_16x16x32_bf16 v[104:107], v[156:159], v[180:183], v[104:107]
	v_mfma_f32_16x16x32_bf16 v[96:99], v[148:151], v[188:191], v[96:99]
	v_mfma_f32_16x16x32_bf16 v[88:91], v[156:159], v[188:191], v[88:91]
	v_mfma_f32_16x16x32_bf16 v[80:83], v[148:151], v[196:199], v[80:83]
	v_mfma_f32_16x16x32_bf16 v[72:75], v[156:159], v[196:199], v[72:75]
	s_setprio 0
	s_barrier
	s_add_i32 s16, s58, s40
	s_mov_b32 m0, s16
	ds_read_b128 v[202:205], v167
	ds_read_b128 v[206:209], v167 offset:1024
	ds_read_b128 v[210:213], v167 offset:2048
	ds_read_b128 v[214:217], v167 offset:3072
	global_load_lds_dwordx4 v132, s[34:35]
	s_add_i32 m0, s16, 0x2000
	s_nop 0
	global_load_lds_dwordx4 v128, s[34:35]
	s_waitcnt vmcnt(10)
	s_barrier
	s_waitcnt lgkmcnt(0)
	s_setprio 1
	s_waitcnt lgkmcnt(0)
	v_mfma_f32_16x16x32_bf16 v[112:115], v[202:205], v[168:171], 0
	v_mfma_f32_16x16x32_bf16 v[108:111], v[210:213], v[168:171], 0
	v_mfma_f32_16x16x32_bf16 v[100:103], v[202:205], v[176:179], 0
	v_mfma_f32_16x16x32_bf16 v[92:95], v[210:213], v[176:179], 0
	v_mfma_f32_16x16x32_bf16 v[84:87], v[202:205], v[184:187], 0
	v_mfma_f32_16x16x32_bf16 v[76:79], v[210:213], v[184:187], 0
	v_mfma_f32_16x16x32_bf16 v[68:71], v[202:205], v[192:195], 0
	v_mfma_f32_16x16x32_bf16 v[64:67], v[210:213], v[192:195], 0
	v_mfma_f32_16x16x32_bf16 v[112:115], v[206:209], v[172:175], v[112:115]
	v_mfma_f32_16x16x32_bf16 v[108:111], v[214:217], v[172:175], v[108:111]
	v_mfma_f32_16x16x32_bf16 v[100:103], v[206:209], v[180:183], v[100:103]
	v_mfma_f32_16x16x32_bf16 v[92:95], v[214:217], v[180:183], v[92:95]
	v_mfma_f32_16x16x32_bf16 v[84:87], v[206:209], v[188:191], v[84:87]
	v_mfma_f32_16x16x32_bf16 v[76:79], v[214:217], v[188:191], v[76:79]
	v_mfma_f32_16x16x32_bf16 v[68:71], v[206:209], v[196:199], v[68:71]
	v_mfma_f32_16x16x32_bf16 v[64:67], v[214:217], v[196:199], v[64:67]
	s_setprio 0
	s_mov_b32 m0, s42
	s_barrier
	ds_read_b128 v[168:171], v166 offset:16384
	ds_read_b128 v[172:175], v166 offset:17408
	ds_read_b128 v[176:179], v166 offset:18432
	ds_read_b128 v[180:183], v166 offset:19456
	ds_read_b128 v[184:187], v166 offset:20480
	ds_read_b128 v[188:191], v166 offset:21504
	ds_read_b128 v[192:195], v166 offset:22528
	ds_read_b128 v[196:199], v166 offset:23552
	global_load_lds_dwordx4 v134, s[36:37]
	s_mov_b32 m0, s43
	s_nop 0
	global_load_lds_dwordx4 v130, s[36:37]
	s_barrier
	s_waitcnt lgkmcnt(0)
	s_setprio 1
	s_waitcnt lgkmcnt(0)
	v_mfma_f32_16x16x32_bf16 v[60:63], v[144:147], v[168:171], 0
	v_mfma_f32_16x16x32_bf16 v[56:59], v[152:155], v[168:171], 0
	v_mfma_f32_16x16x32_bf16 v[48:51], v[144:147], v[176:179], 0
	v_mfma_f32_16x16x32_bf16 v[40:43], v[152:155], v[176:179], 0
	v_mfma_f32_16x16x32_bf16 v[32:35], v[144:147], v[184:187], 0
	v_mfma_f32_16x16x32_bf16 v[24:27], v[152:155], v[184:187], 0
	v_mfma_f32_16x16x32_bf16 v[16:19], v[144:147], v[192:195], 0
	v_mfma_f32_16x16x32_bf16 v[8:11], v[152:155], v[192:195], 0
	v_mfma_f32_16x16x32_bf16 v[60:63], v[148:151], v[172:175], v[60:63]
	v_mfma_f32_16x16x32_bf16 v[56:59], v[156:159], v[172:175], v[56:59]
	v_mfma_f32_16x16x32_bf16 v[48:51], v[148:151], v[180:183], v[48:51]
	v_mfma_f32_16x16x32_bf16 v[40:43], v[156:159], v[180:183], v[40:43]
	v_mfma_f32_16x16x32_bf16 v[32:35], v[148:151], v[188:191], v[32:35]
	v_mfma_f32_16x16x32_bf16 v[24:27], v[156:159], v[188:191], v[24:27]
	v_mfma_f32_16x16x32_bf16 v[16:19], v[148:151], v[196:199], v[16:19]
	v_mfma_f32_16x16x32_bf16 v[8:11], v[156:159], v[196:199], v[8:11]
	s_setprio 0
	s_barrier
	s_add_u32 s16, s34, 0xb0000
	s_addc_u32 s17, s35, 0
	s_add_i32 s20, s59, s40
	s_mov_b32 m0, s20
	s_nop 0
	global_load_lds_dwordx4 v132, s[16:17]
	s_add_i32 m0, s20, 0x2000
	s_nop 0
	global_load_lds_dwordx4 v128, s[16:17]
	s_waitcnt vmcnt(10)
	s_barrier
; #define PG8_STAGE(bufoff, gbase, voff) do { _Pragma("unroll") for (int _i = 0; _i < 2; ++_i) \
;         __builtin_amdgcn_global_load_lds((const unsigned*)((const char*)(gbase) + (voff)[_i]), (LAS unsigned*)(lds + (bufoff) + ldsw + _i * 8192), 16, 0, 0); } while (0)
; #define PG8_LDA(dst, b, h) do { _Pragma("unroll") for (int m = 0; m < 4; ++m) _Pragma("unroll") for (int k = 0; k < 2; ++k) dst[m][k] = *(const LAS bf16x8*)(lds + PG8_SA(b, h) + aoff + m * 2048 + k * 1024); } while (0)
; #define PG8_LDB(dst, b, h) do { _Pragma("unroll") for (int n = 0; n < 2; ++n) _Pragma("unroll") for (int k = 0; k < 2; ++k) dst[n][k] = *(const LAS bf16x8*)(lds + PG8_SB(b, h) + boff + n * 2048 + k * 1024); } while (0)
; #define PG8_WAIT_V(n) asm volatile("s_waitcnt vmcnt(" #n ")" ::: "memory")
; #define PG8_WAIT_L(n) asm volatile("s_waitcnt lgkmcnt(" #n ")" ::: "memory")
; #define PG8_BAR __builtin_amdgcn_s_barrier()
; #define PG8_SCHED __builtin_amdgcn_sched_barrier(0)
; template <class Epi, class Sched>
; __device__ __forceinline__ void gemm_phase(LAS unsigned char* lds, const Gemm g, const Sched& S, const Epi& E) {
;     ...
;             PG8_LDB(B0, 0, 0); PG8_SCHED; PG8_LDA(At, 0, 0); PG8_STAGE(PG8_SA(1, 1), a1 + hstep, voffA);
;             PG8_WAIT_L(8); PG8_BAR; PG8_WAIT_L(0); PG8_MMA(0, 0, At, B0); PG8_BAR; PG8_SCHED;
;             PG8_LDB(B1, 0, 1); PG8_STAGE(PG8_SB(0, 0), b2, voffB);
;             PG8_BAR; PG8_WAIT_L(0); PG8_MMA(0, 1, At, B1); PG8_BAR;
;             PG8_LDA(At, 0, 1); PG8_STAGE(PG8_SA(0, 0), a2, voffA);
;             PG8_BAR; PG8_WAIT_L(0); PG8_MMA(1, 0, At, B0); PG8_BAR; PG8_SCHED;
;             PG8_STAGE(PG8_SB(0, 1), b2 + hstep, voffB);
;             PG8_WAIT_V(6); PG8_BAR; PG8_MMA(1, 1, At, B1); PG8_BAR;
;             PG8_LDB(B0, 1, 0); PG8_SCHED; PG8_LDA(At, 1, 0); PG8_STAGE(PG8_SA(0, 1), a2 + hstep, voffA);
;             PG8_WAIT_L(8); PG8_BAR; PG8_WAIT_L(0); PG8_MMA(0, 0, At, B0); PG8_BAR; PG8_SCHED;
;             PG8_LDB(B1, 1, 1); PG8_STAGE(PG8_SB(1, 0), b3, voffB);
;             PG8_BAR; PG8_WAIT_L(0); PG8_MMA(0, 1, At, B1); PG8_BAR;
;             PG8_LDA(At, 1, 1); PG8_STAGE(PG8_SA(1, 0), a3, voffA);
;             PG8_BAR; PG8_WAIT_L(0); PG8_MMA(1, 0, At, B0); PG8_BAR; PG8_SCHED;
;             PG8_STAGE(PG8_SB(1, 1), b3 + hstep, voffB);
;             PG8_WAIT_V(6); PG8_BAR; PG8_MMA(1, 1, At, B1); PG8_BAR;
	s_setprio 1
	v_mfma_f32_16x16x32_bf16 v[52:55], v[202:205], v[168:171], 0
	v_mfma_f32_16x16x32_bf16 v[44:47], v[210:213], v[168:171], 0
	v_mfma_f32_16x16x32_bf16 v[36:39], v[202:205], v[176:179], 0
	v_mfma_f32_16x16x32_bf16 v[28:31], v[210:213], v[176:179], 0
	v_mfma_f32_16x16x32_bf16 v[20:23], v[202:205], v[184:187], 0
	v_mfma_f32_16x16x32_bf16 v[12:15], v[210:213], v[184:187], 0
	v_mfma_f32_16x16x32_bf16 v[4:7], v[202:205], v[192:195], 0
	v_mfma_f32_16x16x32_bf16 v[0:3], v[210:213], v[192:195], 0
	v_mfma_f32_16x16x32_bf16 v[52:55], v[206:209], v[172:175], v[52:55]
	v_mfma_f32_16x16x32_bf16 v[44:47], v[214:217], v[172:175], v[44:47]
	v_mfma_f32_16x16x32_bf16 v[36:39], v[206:209], v[180:183], v[36:39]
	v_mfma_f32_16x16x32_bf16 v[28:31], v[214:217], v[180:183], v[28:31]
	v_mfma_f32_16x16x32_bf16 v[20:23], v[206:209], v[188:191], v[20:23]
	v_mfma_f32_16x16x32_bf16 v[12:15], v[214:217], v[188:191], v[12:15]
	v_mfma_f32_16x16x32_bf16 v[4:7], v[206:209], v[196:199], v[4:7]
	v_mfma_f32_16x16x32_bf16 v[0:3], v[214:217], v[196:199], v[0:3]
	s_setprio 0
	s_add_i32 s20, 0, 0x18000
	v_add_u32_e32 v156, s20, v164
	s_barrier
	ds_read_b128 v[144:147], v156
	ds_read_b128 v[148:151], v156 offset:1024
	ds_read_b128 v[152:155], v156 offset:2048
	ds_read_b128 v[156:159], v156 offset:3072
	s_add_u32 s16, s36, 0xb0000
	s_addc_u32 s17, s37, 0
	s_mov_b32 m0, s44
	ds_read_b128 v[168:171], v166 offset:32768
	ds_read_b128 v[172:175], v166 offset:33792
	ds_read_b128 v[176:179], v166 offset:34816
	ds_read_b128 v[180:183], v166 offset:35840
	ds_read_b128 v[184:187], v166 offset:36864
	ds_read_b128 v[188:191], v166 offset:37888
	ds_read_b128 v[192:195], v166 offset:38912
	ds_read_b128 v[196:199], v166 offset:39936
	global_load_lds_dwordx4 v134, s[16:17]
	s_mov_b32 m0, s45
	s_nop 0
	global_load_lds_dwordx4 v130, s[16:17]
	s_waitcnt lgkmcnt(8)
	s_waitcnt vmcnt(10)
	s_barrier
	s_waitcnt lgkmcnt(0)
	s_setprio 1
	s_waitcnt lgkmcnt(0)
	v_mfma_f32_16x16x32_bf16 v[124:127], v[144:147], v[168:171], v[124:127]
	v_mfma_f32_16x16x32_bf16 v[120:123], v[152:155], v[168:171], v[120:123]
	v_mfma_f32_16x16x32_bf16 v[116:119], v[144:147], v[176:179], v[116:119]
	v_mfma_f32_16x16x32_bf16 v[104:107], v[152:155], v[176:179], v[104:107]
	v_mfma_f32_16x16x32_bf16 v[96:99], v[144:147], v[184:187], v[96:99]
	v_mfma_f32_16x16x32_bf16 v[88:91], v[152:155], v[184:187], v[88:91]
	v_mfma_f32_16x16x32_bf16 v[80:83], v[144:147], v[192:195], v[80:83]
	v_mfma_f32_16x16x32_bf16 v[72:75], v[152:155], v[192:195], v[72:75]
	v_mfma_f32_16x16x32_bf16 v[124:127], v[148:151], v[172:175], v[124:127]
	v_mfma_f32_16x16x32_bf16 v[120:123], v[156:159], v[172:175], v[120:123]
	v_mfma_f32_16x16x32_bf16 v[116:119], v[148:151], v[180:183], v[116:119]
	v_mfma_f32_16x16x32_bf16 v[104:107], v[156:159], v[180:183], v[104:107]
	v_mfma_f32_16x16x32_bf16 v[96:99], v[148:151], v[188:191], v[96:99]
	v_mfma_f32_16x16x32_bf16 v[88:91], v[156:159], v[188:191], v[88:91]
	v_mfma_f32_16x16x32_bf16 v[80:83], v[148:151], v[196:199], v[80:83]
	v_mfma_f32_16x16x32_bf16 v[72:75], v[156:159], v[196:199], v[72:75]
	s_setprio 0
	s_barrier
	s_add_i32 s21, 0, 0x1c000
	s_add_i32 s16, s20, s40
	v_add_u32_e32 v214, s21, v164
	s_add_u32 s8, s34, 0x80
	s_addc_u32 s9, s35, 0
	s_mov_b32 m0, s16
	ds_read_b128 v[202:205], v214
	ds_read_b128 v[206:209], v214 offset:1024
	ds_read_b128 v[210:213], v214 offset:2048
	ds_read_b128 v[214:217], v214 offset:3072
	global_load_lds_dwordx4 v132, s[8:9]
	s_add_i32 m0, s16, 0x2000
	s_nop 0
	global_load_lds_dwordx4 v128, s[8:9]
	s_waitcnt vmcnt(10)
	s_barrier
	s_waitcnt lgkmcnt(0)
	s_setprio 1
	s_waitcnt lgkmcnt(0)
	v_mfma_f32_16x16x32_bf16 v[112:115], v[202:205], v[168:171], v[112:115]
	v_mfma_f32_16x16x32_bf16 v[108:111], v[210:213], v[168:171], v[108:111]
	v_mfma_f32_16x16x32_bf16 v[100:103], v[202:205], v[176:179], v[100:103]
	v_mfma_f32_16x16x32_bf16 v[92:95], v[210:213], v[176:179], v[92:95]
	v_mfma_f32_16x16x32_bf16 v[84:87], v[202:205], v[184:187], v[84:87]
	v_mfma_f32_16x16x32_bf16 v[76:79], v[210:213], v[184:187], v[76:79]
	v_mfma_f32_16x16x32_bf16 v[68:71], v[202:205], v[192:195], v[68:71]
	v_mfma_f32_16x16x32_bf16 v[64:67], v[210:213], v[192:195], v[64:67]
	v_mfma_f32_16x16x32_bf16 v[112:115], v[206:209], v[172:175], v[112:115]
	v_mfma_f32_16x16x32_bf16 v[108:111], v[214:217], v[172:175], v[108:111]
	v_mfma_f32_16x16x32_bf16 v[100:103], v[206:209], v[180:183], v[100:103]
	v_mfma_f32_16x16x32_bf16 v[92:95], v[214:217], v[180:183], v[92:95]
	v_mfma_f32_16x16x32_bf16 v[84:87], v[206:209], v[188:191], v[84:87]
	v_mfma_f32_16x16x32_bf16 v[76:79], v[214:217], v[188:191], v[76:79]
	v_mfma_f32_16x16x32_bf16 v[68:71], v[206:209], v[196:199], v[68:71]
	v_mfma_f32_16x16x32_bf16 v[64:67], v[214:217], v[196:199], v[64:67]
	s_setprio 0
	s_mov_b32 m0, s52
	s_add_u32 s8, s36, 0x80
	s_addc_u32 s9, s37, 0
	s_barrier
	ds_read_b128 v[168:171], v166 offset:49152
	ds_read_b128 v[172:175], v166 offset:50176
	ds_read_b128 v[176:179], v166 offset:51200
	ds_read_b128 v[180:183], v166 offset:52224
	ds_read_b128 v[184:187], v166 offset:53248
	ds_read_b128 v[188:191], v166 offset:54272
	ds_read_b128 v[192:195], v166 offset:55296
	ds_read_b128 v[196:199], v166 offset:56320
	global_load_lds_dwordx4 v134, s[8:9]
	s_mov_b32 m0, s53
	s_nop 0
	global_load_lds_dwordx4 v130, s[8:9]
	s_barrier
; #define PG8_STAGE(bufoff, gbase, voff) do { _Pragma("unroll") for (int _i = 0; _i < 2; ++_i) \
;         __builtin_amdgcn_global_load_lds((const unsigned*)((const char*)(gbase) + (voff)[_i]), (LAS unsigned*)(lds + (bufoff) + ldsw + _i * 8192), 16, 0, 0); } while (0)
; #define PG8_LDA(dst, b, h) do { _Pragma("unroll") for (int m = 0; m < 4; ++m) _Pragma("unroll") for (int k = 0; k < 2; ++k) dst[m][k] = *(const LAS bf16x8*)(lds + PG8_SA(b, h) + aoff + m * 2048 + k * 1024); } while (0)
; #define PG8_LDB(dst, b, h) do { _Pragma("unroll") for (int n = 0; n < 2; ++n) _Pragma("unroll") for (int k = 0; k < 2; ++k) dst[n][k] = *(const LAS bf16x8*)(lds + PG8_SB(b, h) + boff + n * 2048 + k * 1024); } while (0)
; #define PG8_WAIT_V(n) asm volatile("s_waitcnt vmcnt(" #n ")" ::: "memory")
; #define PG8_WAIT_L(n) asm volatile("s_waitcnt lgkmcnt(" #n ")" ::: "memory")
; #define PG8_BAR __builtin_amdgcn_s_barrier()
; #define PG8_SCHED __builtin_amdgcn_sched_barrier(0)
; template <class Epi, class Sched>
; __device__ __forceinline__ void gemm_phase(LAS unsigned char* lds, const Gemm g, const Sched& S, const Epi& E) {
;     ...
;             PG8_LDB(B0, 0, 0); PG8_SCHED; PG8_LDA(At, 0, 0); PG8_STAGE(PG8_SA(1, 1), a1 + hstep, voffA);
;             PG8_WAIT_L(8); PG8_BAR; PG8_WAIT_L(0); PG8_MMA(0, 0, At, B0); PG8_BAR; PG8_SCHED;
;             PG8_LDB(B1, 0, 1); PG8_STAGE(PG8_SB(0, 0), b2, voffB);
;             PG8_BAR; PG8_WAIT_L(0); PG8_MMA(0, 1, At, B1); PG8_BAR;
;             PG8_LDA(At, 0, 1); PG8_STAGE(PG8_SA(0, 0), a2, voffA);
;             PG8_BAR; PG8_WAIT_L(0); PG8_MMA(1, 0, At, B0); PG8_BAR; PG8_SCHED;
;             PG8_STAGE(PG8_SB(0, 1), b2 + hstep, voffB);
;             PG8_WAIT_V(6); PG8_BAR; PG8_MMA(1, 1, At, B1); PG8_BAR;
;             PG8_LDB(B0, 1, 0); PG8_SCHED; PG8_LDA(At, 1, 0); PG8_STAGE(PG8_SA(0, 1), a2 + hstep, voffA);
;             PG8_WAIT_L(8); PG8_BAR; PG8_WAIT_L(0); PG8_MMA(0, 0, At, B0); PG8_BAR; PG8_SCHED;
;             PG8_LDB(B1, 1, 1); PG8_STAGE(PG8_SB(1, 0), b3, voffB);
;             PG8_BAR; PG8_WAIT_L(0); PG8_MMA(0, 1, At, B1); PG8_BAR;
;             PG8_LDA(At, 1, 1); PG8_STAGE(PG8_SA(1, 0), a3, voffA);
;             PG8_BAR; PG8_WAIT_L(0); PG8_MMA(1, 0, At, B0); PG8_BAR; PG8_SCHED;
;             PG8_STAGE(PG8_SB(1, 1), b3 + hstep, voffB);
;             PG8_WAIT_V(6); PG8_BAR; PG8_MMA(1, 1, At, B1); PG8_BAR;
	s_waitcnt lgkmcnt(0)
	s_setprio 1
	s_waitcnt lgkmcnt(0)
	v_mfma_f32_16x16x32_bf16 v[60:63], v[144:147], v[168:171], v[60:63]
	v_mfma_f32_16x16x32_bf16 v[56:59], v[152:155], v[168:171], v[56:59]
	v_mfma_f32_16x16x32_bf16 v[48:51], v[144:147], v[176:179], v[48:51]
	v_mfma_f32_16x16x32_bf16 v[40:43], v[152:155], v[176:179], v[40:43]
	v_mfma_f32_16x16x32_bf16 v[32:35], v[144:147], v[184:187], v[32:35]
	v_mfma_f32_16x16x32_bf16 v[24:27], v[152:155], v[184:187], v[24:27]
	v_mfma_f32_16x16x32_bf16 v[16:19], v[144:147], v[192:195], v[16:19]
	v_mfma_f32_16x16x32_bf16 v[8:11], v[152:155], v[192:195], v[8:11]
	v_mfma_f32_16x16x32_bf16 v[60:63], v[148:151], v[172:175], v[60:63]
	v_mfma_f32_16x16x32_bf16 v[56:59], v[156:159], v[172:175], v[56:59]
	v_mfma_f32_16x16x32_bf16 v[48:51], v[148:151], v[180:183], v[48:51]
	v_mfma_f32_16x16x32_bf16 v[40:43], v[156:159], v[180:183], v[40:43]
	v_mfma_f32_16x16x32_bf16 v[32:35], v[148:151], v[188:191], v[32:35]
	v_mfma_f32_16x16x32_bf16 v[24:27], v[156:159], v[188:191], v[24:27]
	v_mfma_f32_16x16x32_bf16 v[16:19], v[148:151], v[196:199], v[16:19]
	v_mfma_f32_16x16x32_bf16 v[8:11], v[156:159], v[196:199], v[8:11]
	s_setprio 0
	s_barrier
	s_add_u32 s16, s34, 0xb0080
	s_addc_u32 s17, s35, 0
	s_add_i32 s20, s21, s40
	s_mov_b32 m0, s20
	s_nop 0
	global_load_lds_dwordx4 v132, s[16:17]
	s_add_i32 m0, s20, 0x2000
	s_nop 0
	global_load_lds_dwordx4 v128, s[16:17]
	s_waitcnt vmcnt(10)
	s_barrier
	s_setprio 1
	v_mfma_f32_16x16x32_bf16 v[52:55], v[202:205], v[168:171], v[52:55]
	v_mfma_f32_16x16x32_bf16 v[44:47], v[210:213], v[168:171], v[44:47]
	v_mfma_f32_16x16x32_bf16 v[36:39], v[202:205], v[176:179], v[36:39]
	v_mfma_f32_16x16x32_bf16 v[28:31], v[210:213], v[176:179], v[28:31]
	v_mfma_f32_16x16x32_bf16 v[20:23], v[202:205], v[184:187], v[20:23]
	v_mfma_f32_16x16x32_bf16 v[12:15], v[210:213], v[184:187], v[12:15]
	v_mfma_f32_16x16x32_bf16 v[4:7], v[202:205], v[192:195], v[4:7]
	v_mfma_f32_16x16x32_bf16 v[0:3], v[210:213], v[192:195], v[0:3]
	v_mfma_f32_16x16x32_bf16 v[52:55], v[206:209], v[172:175], v[52:55]
	v_mfma_f32_16x16x32_bf16 v[44:47], v[214:217], v[172:175], v[44:47]
	v_mfma_f32_16x16x32_bf16 v[36:39], v[206:209], v[180:183], v[36:39]
	v_mfma_f32_16x16x32_bf16 v[28:31], v[214:217], v[180:183], v[28:31]
	v_mfma_f32_16x16x32_bf16 v[20:23], v[206:209], v[188:191], v[20:23]
	v_mfma_f32_16x16x32_bf16 v[12:15], v[214:217], v[188:191], v[12:15]
	v_mfma_f32_16x16x32_bf16 v[4:7], v[206:209], v[196:199], v[4:7]
	v_mfma_f32_16x16x32_bf16 v[0:3], v[214:217], v[196:199], v[0:3]
	s_setprio 0
	s_add_i32 s68, s68, 2
	s_add_u32 s0, s0, 0x100
	s_addc_u32 s67, s67, 0
	s_cmp_gt_u32 s68, 41
	s_mov_b64 s[26:27], s[28:29]
	s_barrier
.LBB0_305:
	ds_read_b128 v[144:147], v165
	ds_read_b128 v[148:151], v165 offset:1024
	ds_read_b128 v[152:155], v165 offset:2048
	ds_read_b128 v[156:159], v165 offset:3072
	s_add_u32 s28, s26, 0x100
	s_addc_u32 s29, s27, 0
	s_cmp_eq_u32 s68, 40
	s_cselect_b32 s37, s5, s29
	s_cselect_b32 s36, s4, s28
	s_cselect_b32 s35, s7, s67
	s_cselect_b32 s34, s6, s0
	v_lshl_add_u64 v[160:161], s[26:27], 0, v[136:137]
	s_add_i32 m0, s42, 0xc000
	ds_read_b128 v[168:171], v166
	ds_read_b128 v[172:175], v166 offset:1024
	ds_read_b128 v[176:179], v166 offset:2048
	ds_read_b128 v[180:183], v166 offset:3072
	ds_read_b128 v[184:187], v166 offset:4096
	ds_read_b128 v[188:191], v166 offset:5120
	ds_read_b128 v[192:195], v166 offset:6144
	ds_read_b128 v[196:199], v166 offset:7168
	global_load_lds_dwordx4 v[160:161], off
	v_lshl_add_u64 v[160:161], s[26:27], 0, v[138:139]
	s_add_i32 m0, s42, 0xe000
	s_nop 0
	global_load_lds_dwordx4 v[160:161], off
	s_waitcnt lgkmcnt(8)
	s_waitcnt vmcnt(10)
	s_barrier
	s_waitcnt lgkmcnt(0)
	s_setprio 1
	s_waitcnt lgkmcnt(0)
	v_mfma_f32_16x16x32_bf16 v[124:127], v[144:147], v[168:171], v[124:127]
	v_mfma_f32_16x16x32_bf16 v[120:123], v[152:155], v[168:171], v[120:123]
	v_mfma_f32_16x16x32_bf16 v[116:119], v[144:147], v[176:179], v[116:119]
	v_mfma_f32_16x16x32_bf16 v[104:107], v[152:155], v[176:179], v[104:107]
	v_mfma_f32_16x16x32_bf16 v[96:99], v[144:147], v[184:187], v[96:99]
	v_mfma_f32_16x16x32_bf16 v[88:91], v[152:155], v[184:187], v[88:91]
	v_mfma_f32_16x16x32_bf16 v[80:83], v[144:147], v[192:195], v[80:83]
	v_mfma_f32_16x16x32_bf16 v[72:75], v[152:155], v[192:195], v[72:75]
	v_mfma_f32_16x16x32_bf16 v[124:127], v[148:151], v[172:175], v[124:127]
	v_mfma_f32_16x16x32_bf16 v[120:123], v[156:159], v[172:175], v[120:123]
	v_mfma_f32_16x16x32_bf16 v[116:119], v[148:151], v[180:183], v[116:119]
	v_mfma_f32_16x16x32_bf16 v[104:107], v[156:159], v[180:183], v[104:107]
	v_mfma_f32_16x16x32_bf16 v[96:99], v[148:151], v[188:191], v[96:99]
	v_mfma_f32_16x16x32_bf16 v[88:91], v[156:159], v[188:191], v[88:91]
	v_mfma_f32_16x16x32_bf16 v[80:83], v[148:151], v[196:199], v[80:83]
	v_mfma_f32_16x16x32_bf16 v[72:75], v[156:159], v[196:199], v[72:75]
	s_setprio 0
	s_barrier
	s_add_i32 s16, s58, s40
	s_mov_b32 m0, s16
	ds_read_b128 v[202:205], v167
	ds_read_b128 v[206:209], v167 offset:1024
	ds_read_b128 v[210:213], v167 offset:2048
	ds_read_b128 v[214:217], v167 offset:3072
	global_load_lds_dwordx4 v132, s[34:35]
	s_add_i32 m0, s16, 0x2000
	s_nop 0
	global_load_lds_dwordx4 v128, s[34:35]
	s_waitcnt vmcnt(10)
	s_barrier
; #define PG8_STAGE(bufoff, gbase, voff) do { _Pragma("unroll") for (int _i = 0; _i < 2; ++_i) \
;         __builtin_amdgcn_global_load_lds((const unsigned*)((const char*)(gbase) + (voff)[_i]), (LAS unsigned*)(lds + (bufoff) + ldsw + _i * 8192), 16, 0, 0); } while (0)
; #define PG8_LDA(dst, b, h) do { _Pragma("unroll") for (int m = 0; m < 4; ++m) _Pragma("unroll") for (int k = 0; k < 2; ++k) dst[m][k] = *(const LAS bf16x8*)(lds + PG8_SA(b, h) + aoff + m * 2048 + k * 1024); } while (0)
; #define PG8_LDB(dst, b, h) do { _Pragma("unroll") for (int n = 0; n < 2; ++n) _Pragma("unroll") for (int k = 0; k < 2; ++k) dst[n][k] = *(const LAS bf16x8*)(lds + PG8_SB(b, h) + boff + n * 2048 + k * 1024); } while (0)
; #define PG8_WAIT_V(n) asm volatile("s_waitcnt vmcnt(" #n ")" ::: "memory")
; #define PG8_WAIT_L(n) asm volatile("s_waitcnt lgkmcnt(" #n ")" ::: "memory")
; #define PG8_BAR __builtin_amdgcn_s_barrier()
; #define PG8_SCHED __builtin_amdgcn_sched_barrier(0)
; template <class Epi, class Sched>
; __device__ __forceinline__ void gemm_phase(LAS unsigned char* lds, const Gemm g, const Sched& S, const Epi& E) {
;     ...
;             PG8_LDB(B0, 0, 0); PG8_SCHED; PG8_LDA(At, 0, 0); PG8_STAGE(PG8_SA(1, 1), a1 + hstep, voffA);
;             PG8_WAIT_L(8); PG8_BAR; PG8_WAIT_L(0); PG8_MMA(0, 0, At, B0); PG8_BAR; PG8_SCHED;
;             PG8_LDB(B1, 0, 1); PG8_STAGE(PG8_SB(0, 0), b2, voffB);
;             PG8_BAR; PG8_WAIT_L(0); PG8_MMA(0, 1, At, B1); PG8_BAR;
;             PG8_LDA(At, 0, 1); PG8_STAGE(PG8_SA(0, 0), a2, voffA);
;             PG8_BAR; PG8_WAIT_L(0); PG8_MMA(1, 0, At, B0); PG8_BAR; PG8_SCHED;
;             PG8_STAGE(PG8_SB(0, 1), b2 + hstep, voffB);
;             PG8_WAIT_V(6); PG8_BAR; PG8_MMA(1, 1, At, B1); PG8_BAR;
;             PG8_LDB(B0, 1, 0); PG8_SCHED; PG8_LDA(At, 1, 0); PG8_STAGE(PG8_SA(0, 1), a2 + hstep, voffA);
;             PG8_WAIT_L(8); PG8_BAR; PG8_WAIT_L(0); PG8_MMA(0, 0, At, B0); PG8_BAR; PG8_SCHED;
;             PG8_LDB(B1, 1, 1); PG8_STAGE(PG8_SB(1, 0), b3, voffB);
;             PG8_BAR; PG8_WAIT_L(0); PG8_MMA(0, 1, At, B1); PG8_BAR;
;             PG8_LDA(At, 1, 1); PG8_STAGE(PG8_SA(1, 0), a3, voffA);
;             PG8_BAR; PG8_WAIT_L(0); PG8_MMA(1, 0, At, B0); PG8_BAR; PG8_SCHED;
;             PG8_STAGE(PG8_SB(1, 1), b3 + hstep, voffB);
;             PG8_WAIT_V(6); PG8_BAR; PG8_MMA(1, 1, At, B1); PG8_BAR;
	s_waitcnt lgkmcnt(0)
	s_setprio 1
	s_waitcnt lgkmcnt(0)
	v_mfma_f32_16x16x32_bf16 v[112:115], v[202:205], v[168:171], v[112:115]
	v_mfma_f32_16x16x32_bf16 v[108:111], v[210:213], v[168:171], v[108:111]
	v_mfma_f32_16x16x32_bf16 v[100:103], v[202:205], v[176:179], v[100:103]
	v_mfma_f32_16x16x32_bf16 v[92:95], v[210:213], v[176:179], v[92:95]
	v_mfma_f32_16x16x32_bf16 v[84:87], v[202:205], v[184:187], v[84:87]
	v_mfma_f32_16x16x32_bf16 v[76:79], v[210:213], v[184:187], v[76:79]
	v_mfma_f32_16x16x32_bf16 v[68:71], v[202:205], v[192:195], v[68:71]
	v_mfma_f32_16x16x32_bf16 v[64:67], v[210:213], v[192:195], v[64:67]
	v_mfma_f32_16x16x32_bf16 v[112:115], v[206:209], v[172:175], v[112:115]
	v_mfma_f32_16x16x32_bf16 v[108:111], v[214:217], v[172:175], v[108:111]
	v_mfma_f32_16x16x32_bf16 v[100:103], v[206:209], v[180:183], v[100:103]
	v_mfma_f32_16x16x32_bf16 v[92:95], v[214:217], v[180:183], v[92:95]
	v_mfma_f32_16x16x32_bf16 v[84:87], v[206:209], v[188:191], v[84:87]
	v_mfma_f32_16x16x32_bf16 v[76:79], v[214:217], v[188:191], v[76:79]
	v_mfma_f32_16x16x32_bf16 v[68:71], v[206:209], v[196:199], v[68:71]
	v_mfma_f32_16x16x32_bf16 v[64:67], v[214:217], v[196:199], v[64:67]
	s_setprio 0
	s_mov_b32 m0, s42
	s_barrier
	ds_read_b128 v[168:171], v166 offset:16384
	ds_read_b128 v[172:175], v166 offset:17408
	ds_read_b128 v[176:179], v166 offset:18432
	ds_read_b128 v[180:183], v166 offset:19456
	ds_read_b128 v[184:187], v166 offset:20480
	ds_read_b128 v[188:191], v166 offset:21504
	ds_read_b128 v[192:195], v166 offset:22528
	ds_read_b128 v[196:199], v166 offset:23552
	global_load_lds_dwordx4 v134, s[36:37]
	s_mov_b32 m0, s43
	s_nop 0
	global_load_lds_dwordx4 v130, s[36:37]
	s_barrier
	s_waitcnt lgkmcnt(0)
	s_setprio 1
	s_waitcnt lgkmcnt(0)
	v_mfma_f32_16x16x32_bf16 v[60:63], v[144:147], v[168:171], v[60:63]
	v_mfma_f32_16x16x32_bf16 v[56:59], v[152:155], v[168:171], v[56:59]
	v_mfma_f32_16x16x32_bf16 v[48:51], v[144:147], v[176:179], v[48:51]
	v_mfma_f32_16x16x32_bf16 v[40:43], v[152:155], v[176:179], v[40:43]
	v_mfma_f32_16x16x32_bf16 v[32:35], v[144:147], v[184:187], v[32:35]
	v_mfma_f32_16x16x32_bf16 v[24:27], v[152:155], v[184:187], v[24:27]
	v_mfma_f32_16x16x32_bf16 v[16:19], v[144:147], v[192:195], v[16:19]
	v_mfma_f32_16x16x32_bf16 v[8:11], v[152:155], v[192:195], v[8:11]
	v_mfma_f32_16x16x32_bf16 v[60:63], v[148:151], v[172:175], v[60:63]
	v_mfma_f32_16x16x32_bf16 v[56:59], v[156:159], v[172:175], v[56:59]
	v_mfma_f32_16x16x32_bf16 v[48:51], v[148:151], v[180:183], v[48:51]
	v_mfma_f32_16x16x32_bf16 v[40:43], v[156:159], v[180:183], v[40:43]
	v_mfma_f32_16x16x32_bf16 v[32:35], v[148:151], v[188:191], v[32:35]
	v_mfma_f32_16x16x32_bf16 v[24:27], v[156:159], v[188:191], v[24:27]
	v_mfma_f32_16x16x32_bf16 v[16:19], v[148:151], v[196:199], v[16:19]
	v_mfma_f32_16x16x32_bf16 v[8:11], v[156:159], v[196:199], v[8:11]
	s_setprio 0
	s_barrier
	s_add_u32 s16, s34, 0xb0000
	s_addc_u32 s17, s35, 0
	s_add_i32 s20, s59, s40
	s_mov_b32 m0, s20
	s_nop 0
	global_load_lds_dwordx4 v132, s[16:17]
	s_add_i32 m0, s20, 0x2000
	s_nop 0
	global_load_lds_dwordx4 v128, s[16:17]
	s_waitcnt vmcnt(10)
	s_barrier
	s_setprio 1
	v_mfma_f32_16x16x32_bf16 v[52:55], v[202:205], v[168:171], v[52:55]
	v_mfma_f32_16x16x32_bf16 v[44:47], v[210:213], v[168:171], v[44:47]
	v_mfma_f32_16x16x32_bf16 v[36:39], v[202:205], v[176:179], v[36:39]
	v_mfma_f32_16x16x32_bf16 v[28:31], v[210:213], v[176:179], v[28:31]
	v_mfma_f32_16x16x32_bf16 v[20:23], v[202:205], v[184:187], v[20:23]
	v_mfma_f32_16x16x32_bf16 v[12:15], v[210:213], v[184:187], v[12:15]
	v_mfma_f32_16x16x32_bf16 v[4:7], v[202:205], v[192:195], v[4:7]
	v_mfma_f32_16x16x32_bf16 v[0:3], v[210:213], v[192:195], v[0:3]
	v_mfma_f32_16x16x32_bf16 v[52:55], v[206:209], v[172:175], v[52:55]
	v_mfma_f32_16x16x32_bf16 v[44:47], v[214:217], v[172:175], v[44:47]
	v_mfma_f32_16x16x32_bf16 v[36:39], v[206:209], v[180:183], v[36:39]
	v_mfma_f32_16x16x32_bf16 v[28:31], v[214:217], v[180:183], v[28:31]
	v_mfma_f32_16x16x32_bf16 v[20:23], v[206:209], v[188:191], v[20:23]
	v_mfma_f32_16x16x32_bf16 v[12:15], v[214:217], v[188:191], v[12:15]
	v_mfma_f32_16x16x32_bf16 v[4:7], v[206:209], v[196:199], v[4:7]
	v_mfma_f32_16x16x32_bf16 v[0:3], v[214:217], v[196:199], v[0:3]
	s_setprio 0
	s_add_i32 s20, 0, 0x18000
	v_add_u32_e32 v156, s20, v164
	s_barrier
	ds_read_b128 v[144:147], v156
	ds_read_b128 v[148:151], v156 offset:1024
	ds_read_b128 v[152:155], v156 offset:2048
	ds_read_b128 v[156:159], v156 offset:3072
	s_add_u32 s16, s36, 0xb0000
	s_addc_u32 s17, s37, 0
	s_mov_b32 m0, s44
	ds_read_b128 v[168:171], v166 offset:32768
	ds_read_b128 v[172:175], v166 offset:33792
	ds_read_b128 v[176:179], v166 offset:34816
	ds_read_b128 v[180:183], v166 offset:35840
	ds_read_b128 v[184:187], v166 offset:36864
	ds_read_b128 v[188:191], v166 offset:37888
	ds_read_b128 v[192:195], v166 offset:38912
	ds_read_b128 v[196:199], v166 offset:39936
	global_load_lds_dwordx4 v134, s[16:17]
	s_mov_b32 m0, s45
	s_nop 0
	global_load_lds_dwordx4 v130, s[16:17]
	s_waitcnt lgkmcnt(8)
	s_waitcnt vmcnt(10)
	s_barrier
; #define PG8_STAGE(bufoff, gbase, voff) do { _Pragma("unroll") for (int _i = 0; _i < 2; ++_i) \
;         __builtin_amdgcn_global_load_lds((const unsigned*)((const char*)(gbase) + (voff)[_i]), (LAS unsigned*)(lds + (bufoff) + ldsw + _i * 8192), 16, 0, 0); } while (0)
; #define PG8_LDA(dst, b, h) do { _Pragma("unroll") for (int m = 0; m < 4; ++m) _Pragma("unroll") for (int k = 0; k < 2; ++k) dst[m][k] = *(const LAS bf16x8*)(lds + PG8_SA(b, h) + aoff + m * 2048 + k * 1024); } while (0)
; #define PG8_LDB(dst, b, h) do { _Pragma("unroll") for (int n = 0; n < 2; ++n) _Pragma("unroll") for (int k = 0; k < 2; ++k) dst[n][k] = *(const LAS bf16x8*)(lds + PG8_SB(b, h) + boff + n * 2048 + k * 1024); } while (0)
; #define PG8_MMA(ai, bj, At, Bt) do { __builtin_amdgcn_s_setprio(1); _Pragma("unroll") for (int m = 0; m < 4; ++m) _Pragma("unroll") for (int n = 0; n < 2; ++n) _Pragma("unroll") for (int k = 0; k < 2; ++k) \
;         acc[ai][bj][m][n] = __builtin_amdgcn_mfma_f32_16x16x32_bf16(Bt[n][k], At[m][k], acc[ai][bj][m][n], 0, 0, 0); __builtin_amdgcn_s_setprio(0); } while (0)
; #define PG8_WAIT_V(n) asm volatile("s_waitcnt vmcnt(" #n ")" ::: "memory")
; #define PG8_WAIT_L(n) asm volatile("s_waitcnt lgkmcnt(" #n ")" ::: "memory")
; #define PG8_BAR __builtin_amdgcn_s_barrier()
; #define PG8_SCHED __builtin_amdgcn_sched_barrier(0)
; template <class Epi, class Sched>
; __device__ __forceinline__ void gemm_phase(LAS unsigned char* lds, const Gemm g, const Sched& S, const Epi& E) {
;     ...
;         const bool has_next = S.next(ui + 1, nxt);
;         const char* nA = has_next ? (const char*)g.A + (size_t)nxt.pm * tstep : cA; const char* nB = has_next ? (const char*)g.Bt + (size_t)nxt.pn * tstep : cB;
;     ...
;             PG8_WAIT_L(8); PG8_BAR; PG8_WAIT_L(0); PG8_MMA(0, 0, At, B0); PG8_BAR; PG8_SCHED;
;             PG8_LDB(B1, 1, 1); PG8_STAGE(PG8_SB(1, 0), b3, voffB);
;             PG8_BAR; PG8_WAIT_L(0); PG8_MMA(0, 1, At, B1); PG8_BAR;
;             PG8_LDA(At, 1, 1); PG8_STAGE(PG8_SA(1, 0), a3, voffA);
;             PG8_BAR; PG8_WAIT_L(0); PG8_MMA(1, 0, At, B0); PG8_BAR; PG8_SCHED;
;             PG8_STAGE(PG8_SB(1, 1), b3 + hstep, voffB);
;             PG8_WAIT_V(6); PG8_BAR; PG8_MMA(1, 1, At, B1); PG8_BAR;
	s_waitcnt lgkmcnt(0)
	s_setprio 1
	s_waitcnt lgkmcnt(0)
	v_mfma_f32_16x16x32_bf16 v[124:127], v[144:147], v[168:171], v[124:127]
	v_mfma_f32_16x16x32_bf16 v[120:123], v[152:155], v[168:171], v[120:123]
	v_mfma_f32_16x16x32_bf16 v[116:119], v[144:147], v[176:179], v[116:119]
	v_mfma_f32_16x16x32_bf16 v[104:107], v[152:155], v[176:179], v[104:107]
	v_mfma_f32_16x16x32_bf16 v[96:99], v[144:147], v[184:187], v[96:99]
	v_mfma_f32_16x16x32_bf16 v[88:91], v[152:155], v[184:187], v[88:91]
	v_mfma_f32_16x16x32_bf16 v[80:83], v[144:147], v[192:195], v[80:83]
	v_mfma_f32_16x16x32_bf16 v[72:75], v[152:155], v[192:195], v[72:75]
	v_mfma_f32_16x16x32_bf16 v[124:127], v[148:151], v[172:175], v[124:127]
	v_mfma_f32_16x16x32_bf16 v[120:123], v[156:159], v[172:175], v[120:123]
	v_mfma_f32_16x16x32_bf16 v[116:119], v[148:151], v[180:183], v[116:119]
	v_mfma_f32_16x16x32_bf16 v[104:107], v[156:159], v[180:183], v[104:107]
	v_mfma_f32_16x16x32_bf16 v[96:99], v[148:151], v[188:191], v[96:99]
	v_mfma_f32_16x16x32_bf16 v[88:91], v[156:159], v[188:191], v[88:91]
	v_mfma_f32_16x16x32_bf16 v[80:83], v[148:151], v[196:199], v[80:83]
	v_mfma_f32_16x16x32_bf16 v[72:75], v[156:159], v[196:199], v[72:75]
	s_setprio 0
	s_barrier
	s_add_i32 s21, 0, 0x1c000
	s_add_i32 s16, s20, s40
	v_add_u32_e32 v214, s21, v164
	s_add_u32 s8, s34, 0x80
	s_addc_u32 s9, s35, 0
	s_mov_b32 m0, s16
	ds_read_b128 v[202:205], v214
	ds_read_b128 v[206:209], v214 offset:1024
	ds_read_b128 v[210:213], v214 offset:2048
	ds_read_b128 v[214:217], v214 offset:3072
	global_load_lds_dwordx4 v132, s[8:9]
	s_add_i32 m0, s16, 0x2000
	s_nop 0
	global_load_lds_dwordx4 v128, s[8:9]
	s_waitcnt vmcnt(10)
	s_barrier
	s_waitcnt lgkmcnt(0)
	s_setprio 1
	s_waitcnt lgkmcnt(0)
	v_mfma_f32_16x16x32_bf16 v[112:115], v[202:205], v[168:171], v[112:115]
	v_mfma_f32_16x16x32_bf16 v[108:111], v[210:213], v[168:171], v[108:111]
	v_mfma_f32_16x16x32_bf16 v[100:103], v[202:205], v[176:179], v[100:103]
	v_mfma_f32_16x16x32_bf16 v[92:95], v[210:213], v[176:179], v[92:95]
	v_mfma_f32_16x16x32_bf16 v[84:87], v[202:205], v[184:187], v[84:87]
	v_mfma_f32_16x16x32_bf16 v[76:79], v[210:213], v[184:187], v[76:79]
	v_mfma_f32_16x16x32_bf16 v[68:71], v[202:205], v[192:195], v[68:71]
	v_mfma_f32_16x16x32_bf16 v[64:67], v[210:213], v[192:195], v[64:67]
	v_mfma_f32_16x16x32_bf16 v[112:115], v[206:209], v[172:175], v[112:115]
	v_mfma_f32_16x16x32_bf16 v[108:111], v[214:217], v[172:175], v[108:111]
	v_mfma_f32_16x16x32_bf16 v[100:103], v[206:209], v[180:183], v[100:103]
	v_mfma_f32_16x16x32_bf16 v[92:95], v[214:217], v[180:183], v[92:95]
	v_mfma_f32_16x16x32_bf16 v[84:87], v[206:209], v[188:191], v[84:87]
	v_mfma_f32_16x16x32_bf16 v[76:79], v[214:217], v[188:191], v[76:79]
	v_mfma_f32_16x16x32_bf16 v[68:71], v[206:209], v[196:199], v[68:71]
	v_mfma_f32_16x16x32_bf16 v[64:67], v[214:217], v[196:199], v[64:67]
	s_setprio 0
	s_mov_b32 m0, s52
	s_add_u32 s8, s36, 0x80
	s_addc_u32 s9, s37, 0
	s_barrier
	ds_read_b128 v[168:171], v166 offset:49152
	ds_read_b128 v[172:175], v166 offset:50176
	ds_read_b128 v[176:179], v166 offset:51200
	ds_read_b128 v[180:183], v166 offset:52224
	ds_read_b128 v[184:187], v166 offset:53248
	ds_read_b128 v[188:191], v166 offset:54272
	ds_read_b128 v[192:195], v166 offset:55296
	ds_read_b128 v[196:199], v166 offset:56320
	global_load_lds_dwordx4 v134, s[8:9]
	s_mov_b32 m0, s53
	s_nop 0
	global_load_lds_dwordx4 v130, s[8:9]
	s_barrier
	s_waitcnt lgkmcnt(0)
	s_setprio 1
	s_waitcnt lgkmcnt(0)
	v_mfma_f32_16x16x32_bf16 v[60:63], v[144:147], v[168:171], v[60:63]
	v_mfma_f32_16x16x32_bf16 v[56:59], v[152:155], v[168:171], v[56:59]
	v_mfma_f32_16x16x32_bf16 v[48:51], v[144:147], v[176:179], v[48:51]
	v_mfma_f32_16x16x32_bf16 v[40:43], v[152:155], v[176:179], v[40:43]
	v_mfma_f32_16x16x32_bf16 v[32:35], v[144:147], v[184:187], v[32:35]
	v_mfma_f32_16x16x32_bf16 v[24:27], v[152:155], v[184:187], v[24:27]
	v_mfma_f32_16x16x32_bf16 v[16:19], v[144:147], v[192:195], v[16:19]
	v_mfma_f32_16x16x32_bf16 v[8:11], v[152:155], v[192:195], v[8:11]
	v_mfma_f32_16x16x32_bf16 v[60:63], v[148:151], v[172:175], v[60:63]
	v_mfma_f32_16x16x32_bf16 v[56:59], v[156:159], v[172:175], v[56:59]
	v_mfma_f32_16x16x32_bf16 v[48:51], v[148:151], v[180:183], v[48:51]
	v_mfma_f32_16x16x32_bf16 v[40:43], v[156:159], v[180:183], v[40:43]
	v_mfma_f32_16x16x32_bf16 v[32:35], v[148:151], v[188:191], v[32:35]
	v_mfma_f32_16x16x32_bf16 v[24:27], v[156:159], v[188:191], v[24:27]
	v_mfma_f32_16x16x32_bf16 v[16:19], v[148:151], v[196:199], v[16:19]
	v_mfma_f32_16x16x32_bf16 v[8:11], v[156:159], v[196:199], v[8:11]
	s_setprio 0
	s_barrier
	s_add_u32 s16, s34, 0xb0080
	s_addc_u32 s17, s35, 0
	s_add_i32 s20, s21, s40
	s_mov_b32 m0, s20
	s_nop 0
	global_load_lds_dwordx4 v132, s[16:17]
	s_add_i32 m0, s20, 0x2000
	s_nop 0
	global_load_lds_dwordx4 v128, s[16:17]
	s_waitcnt vmcnt(10)
	s_barrier
	s_setprio 1
	v_mfma_f32_16x16x32_bf16 v[52:55], v[202:205], v[168:171], v[52:55]
	v_mfma_f32_16x16x32_bf16 v[44:47], v[210:213], v[168:171], v[44:47]
	v_mfma_f32_16x16x32_bf16 v[36:39], v[202:205], v[176:179], v[36:39]
	v_mfma_f32_16x16x32_bf16 v[28:31], v[210:213], v[176:179], v[28:31]
	v_mfma_f32_16x16x32_bf16 v[20:23], v[202:205], v[184:187], v[20:23]
	v_mfma_f32_16x16x32_bf16 v[12:15], v[210:213], v[184:187], v[12:15]
	v_mfma_f32_16x16x32_bf16 v[4:7], v[202:205], v[192:195], v[4:7]
	v_mfma_f32_16x16x32_bf16 v[0:3], v[210:213], v[192:195], v[0:3]
	v_mfma_f32_16x16x32_bf16 v[52:55], v[206:209], v[172:175], v[52:55]
	v_mfma_f32_16x16x32_bf16 v[44:47], v[214:217], v[172:175], v[44:47]
	v_mfma_f32_16x16x32_bf16 v[36:39], v[206:209], v[180:183], v[36:39]
	v_mfma_f32_16x16x32_bf16 v[28:31], v[214:217], v[180:183], v[28:31]
	v_mfma_f32_16x16x32_bf16 v[20:23], v[206:209], v[188:191], v[20:23]
	v_mfma_f32_16x16x32_bf16 v[12:15], v[214:217], v[188:191], v[12:15]
	v_mfma_f32_16x16x32_bf16 v[4:7], v[206:209], v[196:199], v[4:7]
	v_mfma_f32_16x16x32_bf16 v[0:3], v[214:217], v[196:199], v[0:3]
	s_setprio 0
	s_add_i32 s68, s68, 2
	s_add_u32 s0, s0, 0x100
	s_addc_u32 s67, s67, 0
	s_cmp_gt_u32 s68, 41
	s_mov_b64 s[26:27], s[28:29]
	s_barrier
	s_cbranch_scc0 .LBB0_305
	s_lshl_b32 s0, s66, 8
	v_mov_b32_e32 v145, v163
	v_mov_b32_e32 v144, v162
	s_cmpk_lt_i32 s66, 0x100
	s_cbranch_scc0 .LBB0_308
	s_ashr_i32 s29, s0, 31
	s_mov_b32 s28, s0
	s_lshl_b64 s[16:17], s[28:29], 12
	v_readlane_b32 s80, v254, 23
	v_readlane_b32 s81, v254, 24
	s_add_u32 s26, s80, s16
	v_readlane_b32 s82, v254, 25
	v_readlane_b32 s83, v254, 26
	v_readlane_b32 s84, v254, 27
	v_readlane_b32 s85, v254, 28
	v_readlane_b32 s86, v254, 29
	v_readlane_b32 s87, v254, 30
	v_readlane_b32 s88, v254, 31
	v_readlane_b32 s89, v254, 32
	v_readlane_b32 s90, v254, 33
	v_readlane_b32 s91, v254, 34
	v_readlane_b32 s92, v254, 35
	v_readlane_b32 s93, v254, 36
	v_readlane_b32 s94, v254, 37
	v_readlane_b32 s95, v254, 38
	s_addc_u32 s27, s81, s17
	s_cbranch_execnz .LBB0_297
	s_branch .LBB0_296

; #define PG8_STAGE(bufoff, gbase, voff) do { _Pragma("unroll") for (int _i = 0; _i < 2; ++_i) \
;         __builtin_amdgcn_global_load_lds((const unsigned*)((const char*)(gbase) + (voff)[_i]), (LAS unsigned*)(lds + (bufoff) + ldsw + _i * 8192), 16, 0, 0); } while (0)
; #define PG8_LDA(dst, b, h) do { _Pragma("unroll") for (int m = 0; m < 4; ++m) _Pragma("unroll") for (int k = 0; k < 2; ++k) dst[m][k] = *(const LAS bf16x8*)(lds + PG8_SA(b, h) + aoff + m * 2048 + k * 1024); } while (0)
; #define PG8_LDB(dst, b, h) do { _Pragma("unroll") for (int n = 0; n < 2; ++n) _Pragma("unroll") for (int k = 0; k < 2; ++k) dst[n][k] = *(const LAS bf16x8*)(lds + PG8_SB(b, h) + boff + n * 2048 + k * 1024); } while (0)
; #define PG8_WAIT_V(n) asm volatile("s_waitcnt vmcnt(" #n ")" ::: "memory")
; #define PG8_WAIT_L(n) asm volatile("s_waitcnt lgkmcnt(" #n ")" ::: "memory")
; #define PG8_BAR __builtin_amdgcn_s_barrier()
; #define PG8_SCHED __builtin_amdgcn_sched_barrier(0)
; template <class Epi, class Sched>
; __device__ __forceinline__ void gemm_phase(LAS unsigned char* lds, const Gemm g, const Sched& S, const Epi& E) {
;     ...
;         const bool has_next = S.next(ui + 1, nxt);
;         const char* nA = has_next ? (const char*)g.A + (size_t)nxt.pm * tstep : cA; const char* nB = has_next ? (const char*)g.Bt + (size_t)nxt.pn * tstep : cB;
;         for (int t = 0; t < nt; t += 2) {
;             const bool last = (t == nt - 2);
;             const char* a1 = cA + (size_t)(t + 1) * kstep;
;             const char* a2 = last ? nA : cA + (size_t)(t + 2) * kstep; const char* b2 = last ? nB : cB + (size_t)(t + 2) * kstep;
;             const char* a3 = a2 + kstep; const char* b3 = b2 + kstep;
;             PG8_LDB(B0, 0, 0); PG8_SCHED; PG8_LDA(At, 0, 0); PG8_STAGE(PG8_SA(1, 1), a1 + hstep, voffA);
;             PG8_WAIT_L(8); PG8_BAR; PG8_WAIT_L(0); PG8_MMA(0, 0, At, B0); PG8_BAR; PG8_SCHED;
;             PG8_LDB(B1, 0, 1); PG8_STAGE(PG8_SB(0, 0), b2, voffB);
;             PG8_BAR; PG8_WAIT_L(0); PG8_MMA(0, 1, At, B1); PG8_BAR;
;             PG8_LDA(At, 0, 1); PG8_STAGE(PG8_SA(0, 0), a2, voffA);
;             PG8_BAR; PG8_WAIT_L(0); PG8_MMA(1, 0, At, B0); PG8_BAR; PG8_SCHED;
;             PG8_STAGE(PG8_SB(0, 1), b2 + hstep, voffB);
;             PG8_WAIT_V(6); PG8_BAR; PG8_MMA(1, 1, At, B1); PG8_BAR;
.LBB0_577:
	s_ashr_i32 s21, s20, 31
	v_cmp_lt_i64_e32 vcc, s[22:23], v[156:157]
	s_lshl_b64 s[22:23], s[20:21], 19
	s_add_u32 s22, s96, s22
	s_addc_u32 s23, s97, s23
	s_and_b64 s[24:25], vcc, exec
	s_cselect_b32 s5, s23, s7
	s_cselect_b32 s21, s22, s6
	s_ashr_i32 s19, s18, 31
	s_lshl_b64 s[24:25], s[18:19], 19
	s_add_u32 s24, s31, s24
	s_addc_u32 s25, s33, s25
	s_and_b64 s[28:29], vcc, exec
	s_cselect_b32 s19, s25, s27
	s_cselect_b32 s53, s24, s26
	s_add_u32 s6, s6, 0x40080
	s_addc_u32 s7, s7, 0
	s_add_u32 s54, s26, 0x100
	s_addc_u32 s55, s27, 0
	s_mov_b32 s56, -2
	s_waitcnt lgkmcnt(0)
	ds_read_b128 v[128:131], v167
	ds_read_b128 v[132:135], v167 offset:1024
	ds_read_b128 v[136:139], v167 offset:2048
	ds_read_b128 v[160:163], v167 offset:3072
	s_add_u32 s26, s6, 0xfffc0080
	s_addc_u32 s27, s7, -1
	s_cmp_eq_u32 s56, 12
	s_cselect_b32 s29, s5, s27
	s_cselect_b32 s28, s21, s26
	s_cselect_b32 s27, s19, s55
	s_cselect_b32 s26, s53, s54
	s_add_i32 m0, s37, 0xc000
	ds_read_b128 v[170:173], v168
	ds_read_b128 v[174:177], v168 offset:1024
	ds_read_b128 v[178:181], v168 offset:2048
	ds_read_b128 v[182:185], v168 offset:3072
	ds_read_b128 v[186:189], v168 offset:4096
	ds_read_b128 v[190:193], v168 offset:5120
	ds_read_b128 v[194:197], v168 offset:6144
	ds_read_b128 v[202:205], v168 offset:7168
	global_load_lds_dwordx4 v152, s[6:7]
	s_add_i32 m0, s37, 0xe000
	s_nop 0
	global_load_lds_dwordx4 v154, s[6:7]
	s_waitcnt lgkmcnt(8)
	s_waitcnt vmcnt(10)
	s_barrier
	s_waitcnt lgkmcnt(0)
	s_setprio 1
	s_waitcnt lgkmcnt(0)
	v_mfma_f32_16x16x32_bf16 v[124:127], v[128:131], v[170:173], 0
	v_mfma_f32_16x16x32_bf16 v[120:123], v[136:139], v[170:173], 0
	v_mfma_f32_16x16x32_bf16 v[108:111], v[128:131], v[178:181], 0
	v_mfma_f32_16x16x32_bf16 v[104:107], v[136:139], v[178:181], 0
	v_mfma_f32_16x16x32_bf16 v[92:95], v[128:131], v[186:189], 0
	v_mfma_f32_16x16x32_bf16 v[88:91], v[136:139], v[186:189], 0
	v_mfma_f32_16x16x32_bf16 v[76:79], v[128:131], v[194:197], 0
	v_mfma_f32_16x16x32_bf16 v[72:75], v[136:139], v[194:197], 0
	v_mfma_f32_16x16x32_bf16 v[124:127], v[132:135], v[174:177], v[124:127]
	v_mfma_f32_16x16x32_bf16 v[120:123], v[160:163], v[174:177], v[120:123]
	v_mfma_f32_16x16x32_bf16 v[108:111], v[132:135], v[182:185], v[108:111]
	v_mfma_f32_16x16x32_bf16 v[104:107], v[160:163], v[182:185], v[104:107]
	v_mfma_f32_16x16x32_bf16 v[92:95], v[132:135], v[190:193], v[92:95]
	v_mfma_f32_16x16x32_bf16 v[88:91], v[160:163], v[190:193], v[88:91]
	v_mfma_f32_16x16x32_bf16 v[76:79], v[132:135], v[202:205], v[76:79]
	v_mfma_f32_16x16x32_bf16 v[72:75], v[160:163], v[202:205], v[72:75]
	s_setprio 0
	s_barrier
	s_add_i32 s57, s48, s34
	s_mov_b32 m0, s57
	ds_read_b128 v[206:209], v169
	ds_read_b128 v[210:213], v169 offset:1024
	ds_read_b128 v[214:217], v169 offset:2048
	ds_read_b128 v[218:221], v169 offset:3072
	global_load_lds_dwordx4 v146, s[26:27]
	s_add_i32 m0, s57, 0x2000
	s_nop 0
	global_load_lds_dwordx4 v142, s[26:27]
	s_waitcnt vmcnt(10)
	s_barrier
	s_waitcnt lgkmcnt(0)
	s_setprio 1
	s_waitcnt lgkmcnt(0)
	v_mfma_f32_16x16x32_bf16 v[116:119], v[206:209], v[170:173], 0
	v_mfma_f32_16x16x32_bf16 v[112:115], v[214:217], v[170:173], 0
	v_mfma_f32_16x16x32_bf16 v[100:103], v[206:209], v[178:181], 0
	v_mfma_f32_16x16x32_bf16 v[96:99], v[214:217], v[178:181], 0
	v_mfma_f32_16x16x32_bf16 v[84:87], v[206:209], v[186:189], 0
	v_mfma_f32_16x16x32_bf16 v[80:83], v[214:217], v[186:189], 0
	v_mfma_f32_16x16x32_bf16 v[68:71], v[206:209], v[194:197], 0
	v_mfma_f32_16x16x32_bf16 v[64:67], v[214:217], v[194:197], 0
	v_mfma_f32_16x16x32_bf16 v[116:119], v[210:213], v[174:177], v[116:119]
	v_mfma_f32_16x16x32_bf16 v[112:115], v[218:221], v[174:177], v[112:115]
	v_mfma_f32_16x16x32_bf16 v[100:103], v[210:213], v[182:185], v[100:103]
	v_mfma_f32_16x16x32_bf16 v[96:99], v[218:221], v[182:185], v[96:99]
	v_mfma_f32_16x16x32_bf16 v[84:87], v[210:213], v[190:193], v[84:87]
	v_mfma_f32_16x16x32_bf16 v[80:83], v[218:221], v[190:193], v[80:83]
	v_mfma_f32_16x16x32_bf16 v[68:71], v[210:213], v[202:205], v[68:71]
	v_mfma_f32_16x16x32_bf16 v[64:67], v[218:221], v[202:205], v[64:67]
	s_setprio 0
	s_mov_b32 m0, s37
	v_lshl_add_u64 v[222:223], s[28:29], 0, v[148:149]
	s_barrier
	ds_read_b128 v[170:173], v168 offset:16384
	ds_read_b128 v[174:177], v168 offset:17408
	ds_read_b128 v[178:181], v168 offset:18432
	ds_read_b128 v[182:185], v168 offset:19456
	ds_read_b128 v[186:189], v168 offset:20480
	ds_read_b128 v[190:193], v168 offset:21504
	ds_read_b128 v[194:197], v168 offset:22528
	ds_read_b128 v[202:205], v168 offset:23552
	global_load_lds_dwordx4 v148, s[28:29]
	v_lshl_add_u64 v[224:225], s[28:29], 0, v[144:145]
	s_mov_b32 m0, s38
	s_nop 0
	global_load_lds_dwordx4 v144, s[28:29]
	s_barrier
	s_waitcnt lgkmcnt(0)
	s_setprio 1
	s_waitcnt lgkmcnt(0)
	v_mfma_f32_16x16x32_bf16 v[60:63], v[128:131], v[170:173], 0
	v_mfma_f32_16x16x32_bf16 v[56:59], v[136:139], v[170:173], 0
	v_mfma_f32_16x16x32_bf16 v[44:47], v[128:131], v[178:181], 0
	v_mfma_f32_16x16x32_bf16 v[40:43], v[136:139], v[178:181], 0
	v_mfma_f32_16x16x32_bf16 v[28:31], v[128:131], v[186:189], 0
	v_mfma_f32_16x16x32_bf16 v[24:27], v[136:139], v[186:189], 0
	v_mfma_f32_16x16x32_bf16 v[12:15], v[128:131], v[194:197], 0
	v_mfma_f32_16x16x32_bf16 v[8:11], v[136:139], v[194:197], 0
	v_mfma_f32_16x16x32_bf16 v[60:63], v[132:135], v[174:177], v[60:63]
	v_mfma_f32_16x16x32_bf16 v[56:59], v[160:163], v[174:177], v[56:59]
	v_mfma_f32_16x16x32_bf16 v[44:47], v[132:135], v[182:185], v[44:47]
	v_mfma_f32_16x16x32_bf16 v[40:43], v[160:163], v[182:185], v[40:43]
	v_mfma_f32_16x16x32_bf16 v[28:31], v[132:135], v[190:193], v[28:31]
	v_mfma_f32_16x16x32_bf16 v[24:27], v[160:163], v[190:193], v[24:27]
	v_mfma_f32_16x16x32_bf16 v[12:15], v[132:135], v[202:205], v[12:15]
	v_mfma_f32_16x16x32_bf16 v[8:11], v[160:163], v[202:205], v[8:11]
	s_setprio 0
	s_barrier
; #define PG8_STAGE(bufoff, gbase, voff) do { _Pragma("unroll") for (int _i = 0; _i < 2; ++_i) \
;         __builtin_amdgcn_global_load_lds((const unsigned*)((const char*)(gbase) + (voff)[_i]), (LAS unsigned*)(lds + (bufoff) + ldsw + _i * 8192), 16, 0, 0); } while (0)
; #define PG8_LDA(dst, b, h) do { _Pragma("unroll") for (int m = 0; m < 4; ++m) _Pragma("unroll") for (int k = 0; k < 2; ++k) dst[m][k] = *(const LAS bf16x8*)(lds + PG8_SA(b, h) + aoff + m * 2048 + k * 1024); } while (0)
; #define PG8_LDB(dst, b, h) do { _Pragma("unroll") for (int n = 0; n < 2; ++n) _Pragma("unroll") for (int k = 0; k < 2; ++k) dst[n][k] = *(const LAS bf16x8*)(lds + PG8_SB(b, h) + boff + n * 2048 + k * 1024); } while (0)
; #define PG8_MMA(ai, bj, At, Bt) do { __builtin_amdgcn_s_setprio(1); _Pragma("unroll") for (int m = 0; m < 4; ++m) _Pragma("unroll") for (int n = 0; n < 2; ++n) _Pragma("unroll") for (int k = 0; k < 2; ++k) \
;         acc[ai][bj][m][n] = __builtin_amdgcn_mfma_f32_16x16x32_bf16(Bt[n][k], At[m][k], acc[ai][bj][m][n], 0, 0, 0); __builtin_amdgcn_s_setprio(0); } while (0)
; #define PG8_WAIT_V(n) asm volatile("s_waitcnt vmcnt(" #n ")" ::: "memory")
; #define PG8_WAIT_L(n) asm volatile("s_waitcnt lgkmcnt(" #n ")" ::: "memory")
; #define PG8_BAR __builtin_amdgcn_s_barrier()
; #define PG8_SCHED __builtin_amdgcn_sched_barrier(0)
; template <class Epi, class Sched>
; __device__ __forceinline__ void gemm_phase(LAS unsigned char* lds, const Gemm g, const Sched& S, const Epi& E) {
;     ...
;             PG8_STAGE(PG8_SB(0, 1), b2 + hstep, voffB);
;             PG8_WAIT_V(6); PG8_BAR; PG8_MMA(1, 1, At, B1); PG8_BAR;
;             PG8_LDB(B0, 1, 0); PG8_SCHED; PG8_LDA(At, 1, 0); PG8_STAGE(PG8_SA(0, 1), a2 + hstep, voffA);
;             PG8_WAIT_L(8); PG8_BAR; PG8_WAIT_L(0); PG8_MMA(0, 0, At, B0); PG8_BAR; PG8_SCHED;
;             PG8_LDB(B1, 1, 1); PG8_STAGE(PG8_SB(1, 0), b3, voffB);
;             PG8_BAR; PG8_WAIT_L(0); PG8_MMA(0, 1, At, B1); PG8_BAR;
;             PG8_LDA(At, 1, 1); PG8_STAGE(PG8_SA(1, 0), a3, voffA);
;             PG8_BAR; PG8_WAIT_L(0); PG8_MMA(1, 0, At, B0); PG8_BAR; PG8_SCHED;
;             PG8_STAGE(PG8_SB(1, 1), b3 + hstep, voffB);
;             PG8_WAIT_V(6); PG8_BAR; PG8_MMA(1, 1, At, B1); PG8_BAR;
	s_add_u32 s58, s26, 0x40000
	s_addc_u32 s59, s27, 0
	s_add_i32 s57, s49, s34
	s_mov_b32 m0, s57
	s_nop 0
	global_load_lds_dwordx4 v146, s[58:59]
	s_add_i32 m0, s57, 0x2000
	s_nop 0
	global_load_lds_dwordx4 v142, s[58:59]
	s_waitcnt vmcnt(10)
	s_barrier
	s_setprio 1
	v_mfma_f32_16x16x32_bf16 v[52:55], v[206:209], v[170:173], 0
	v_mfma_f32_16x16x32_bf16 v[48:51], v[214:217], v[170:173], 0
	v_mfma_f32_16x16x32_bf16 v[36:39], v[206:209], v[178:181], 0
	v_mfma_f32_16x16x32_bf16 v[32:35], v[214:217], v[178:181], 0
	v_mfma_f32_16x16x32_bf16 v[20:23], v[206:209], v[186:189], 0
	v_mfma_f32_16x16x32_bf16 v[16:19], v[214:217], v[186:189], 0
	v_mfma_f32_16x16x32_bf16 v[4:7], v[206:209], v[194:197], 0
	v_mfma_f32_16x16x32_bf16 v[0:3], v[214:217], v[194:197], 0
	v_mfma_f32_16x16x32_bf16 v[52:55], v[210:213], v[174:177], v[52:55]
	v_mfma_f32_16x16x32_bf16 v[48:51], v[218:221], v[174:177], v[48:51]
	v_mfma_f32_16x16x32_bf16 v[36:39], v[210:213], v[182:185], v[36:39]
	v_mfma_f32_16x16x32_bf16 v[32:35], v[218:221], v[182:185], v[32:35]
	v_mfma_f32_16x16x32_bf16 v[20:23], v[210:213], v[190:193], v[20:23]
	v_mfma_f32_16x16x32_bf16 v[16:19], v[218:221], v[190:193], v[16:19]
	v_mfma_f32_16x16x32_bf16 v[4:7], v[210:213], v[202:205], v[4:7]
	v_mfma_f32_16x16x32_bf16 v[0:3], v[218:221], v[202:205], v[0:3]
	s_setprio 0
	s_add_i32 s57, 0, 0x18000
	v_add_u32_e32 v150, s57, v166
	s_barrier
	ds_read_b128 v[128:131], v150
	ds_read_b128 v[132:135], v150 offset:1024
	ds_read_b128 v[136:139], v150 offset:2048
	ds_read_b128 v[160:163], v150 offset:3072
	s_add_u32 s28, s28, 0x40000
	s_addc_u32 s29, s29, 0
	s_mov_b32 m0, s39
	ds_read_b128 v[170:173], v168 offset:32768
	ds_read_b128 v[174:177], v168 offset:33792
	ds_read_b128 v[178:181], v168 offset:34816
	ds_read_b128 v[182:185], v168 offset:35840
	ds_read_b128 v[186:189], v168 offset:36864
	ds_read_b128 v[190:193], v168 offset:37888
	ds_read_b128 v[194:197], v168 offset:38912
	ds_read_b128 v[202:205], v168 offset:39936
	global_load_lds_dwordx4 v148, s[28:29]
	s_mov_b32 m0, s40
	s_nop 0
	global_load_lds_dwordx4 v144, s[28:29]
	s_waitcnt lgkmcnt(8)
	s_waitcnt vmcnt(10)
	s_barrier
	s_waitcnt lgkmcnt(0)
	s_setprio 1
	s_waitcnt lgkmcnt(0)
	v_mfma_f32_16x16x32_bf16 v[124:127], v[128:131], v[170:173], v[124:127]
	v_mfma_f32_16x16x32_bf16 v[120:123], v[136:139], v[170:173], v[120:123]
	v_mfma_f32_16x16x32_bf16 v[108:111], v[128:131], v[178:181], v[108:111]
	v_mfma_f32_16x16x32_bf16 v[104:107], v[136:139], v[178:181], v[104:107]
	v_mfma_f32_16x16x32_bf16 v[92:95], v[128:131], v[186:189], v[92:95]
	v_mfma_f32_16x16x32_bf16 v[88:91], v[136:139], v[186:189], v[88:91]
	v_mfma_f32_16x16x32_bf16 v[76:79], v[128:131], v[194:197], v[76:79]
	v_mfma_f32_16x16x32_bf16 v[72:75], v[136:139], v[194:197], v[72:75]
	v_mfma_f32_16x16x32_bf16 v[124:127], v[132:135], v[174:177], v[124:127]
	v_mfma_f32_16x16x32_bf16 v[120:123], v[160:163], v[174:177], v[120:123]
	v_mfma_f32_16x16x32_bf16 v[108:111], v[132:135], v[182:185], v[108:111]
	v_mfma_f32_16x16x32_bf16 v[104:107], v[160:163], v[182:185], v[104:107]
	v_mfma_f32_16x16x32_bf16 v[92:95], v[132:135], v[190:193], v[92:95]
	v_mfma_f32_16x16x32_bf16 v[88:91], v[160:163], v[190:193], v[88:91]
	v_mfma_f32_16x16x32_bf16 v[76:79], v[132:135], v[202:205], v[76:79]
	v_mfma_f32_16x16x32_bf16 v[72:75], v[160:163], v[202:205], v[72:75]
	s_setprio 0
	s_barrier
	s_add_i32 s28, 0, 0x1c000
	s_add_i32 s29, s57, s34
	v_add_u32_e32 v150, s28, v166
	s_add_u32 s0, s26, 0x80
	s_addc_u32 s1, s27, 0
	s_mov_b32 m0, s29
	ds_read_b128 v[206:209], v150
	ds_read_b128 v[210:213], v150 offset:1024
	ds_read_b128 v[214:217], v150 offset:2048
	ds_read_b128 v[218:221], v150 offset:3072
	global_load_lds_dwordx4 v146, s[0:1]
	s_add_i32 m0, s29, 0x2000
	s_nop 0
	global_load_lds_dwordx4 v142, s[0:1]
	s_waitcnt vmcnt(10)
	s_barrier
	s_waitcnt lgkmcnt(0)
	s_setprio 1
	s_waitcnt lgkmcnt(0)
	v_mfma_f32_16x16x32_bf16 v[116:119], v[206:209], v[170:173], v[116:119]
	v_mfma_f32_16x16x32_bf16 v[112:115], v[214:217], v[170:173], v[112:115]
	v_mfma_f32_16x16x32_bf16 v[100:103], v[206:209], v[178:181], v[100:103]
	v_mfma_f32_16x16x32_bf16 v[96:99], v[214:217], v[178:181], v[96:99]
	v_mfma_f32_16x16x32_bf16 v[84:87], v[206:209], v[186:189], v[84:87]
	v_mfma_f32_16x16x32_bf16 v[80:83], v[214:217], v[186:189], v[80:83]
	v_mfma_f32_16x16x32_bf16 v[68:71], v[206:209], v[194:197], v[68:71]
	v_mfma_f32_16x16x32_bf16 v[64:67], v[214:217], v[194:197], v[64:67]
	v_mfma_f32_16x16x32_bf16 v[116:119], v[210:213], v[174:177], v[116:119]
	v_mfma_f32_16x16x32_bf16 v[112:115], v[218:221], v[174:177], v[112:115]
	v_mfma_f32_16x16x32_bf16 v[100:103], v[210:213], v[182:185], v[100:103]
	v_mfma_f32_16x16x32_bf16 v[96:99], v[218:221], v[182:185], v[96:99]
	v_mfma_f32_16x16x32_bf16 v[84:87], v[210:213], v[190:193], v[84:87]
	v_mfma_f32_16x16x32_bf16 v[80:83], v[218:221], v[190:193], v[80:83]
	v_mfma_f32_16x16x32_bf16 v[68:71], v[210:213], v[202:205], v[68:71]
	v_mfma_f32_16x16x32_bf16 v[64:67], v[218:221], v[202:205], v[64:67]
	s_setprio 0
	s_mov_b32 m0, s44
	s_mov_b64 s[0:1], 0x80
	v_lshl_add_u64 v[140:141], v[222:223], 0, s[0:1]
	s_barrier
	ds_read_b128 v[170:173], v168 offset:49152
	ds_read_b128 v[174:177], v168 offset:50176
	ds_read_b128 v[178:181], v168 offset:51200
	ds_read_b128 v[182:185], v168 offset:52224
	ds_read_b128 v[186:189], v168 offset:53248
	ds_read_b128 v[190:193], v168 offset:54272
	ds_read_b128 v[194:197], v168 offset:55296
	ds_read_b128 v[202:205], v168 offset:56320
	global_load_lds_dwordx4 v[140:141], off
	v_lshl_add_u64 v[140:141], v[224:225], 0, s[0:1]
	s_mov_b32 m0, s45
	s_nop 0
	global_load_lds_dwordx4 v[140:141], off
	s_barrier
; #define PG8_STAGE(bufoff, gbase, voff) do { _Pragma("unroll") for (int _i = 0; _i < 2; ++_i) \
;         __builtin_amdgcn_global_load_lds((const unsigned*)((const char*)(gbase) + (voff)[_i]), (LAS unsigned*)(lds + (bufoff) + ldsw + _i * 8192), 16, 0, 0); } while (0)
; #define PG8_LDA(dst, b, h) do { _Pragma("unroll") for (int m = 0; m < 4; ++m) _Pragma("unroll") for (int k = 0; k < 2; ++k) dst[m][k] = *(const LAS bf16x8*)(lds + PG8_SA(b, h) + aoff + m * 2048 + k * 1024); } while (0)
; #define PG8_LDB(dst, b, h) do { _Pragma("unroll") for (int n = 0; n < 2; ++n) _Pragma("unroll") for (int k = 0; k < 2; ++k) dst[n][k] = *(const LAS bf16x8*)(lds + PG8_SB(b, h) + boff + n * 2048 + k * 1024); } while (0)
; #define PG8_WAIT_V(n) asm volatile("s_waitcnt vmcnt(" #n ")" ::: "memory")
; #define PG8_WAIT_L(n) asm volatile("s_waitcnt lgkmcnt(" #n ")" ::: "memory")
; #define PG8_BAR __builtin_amdgcn_s_barrier()
; #define PG8_SCHED __builtin_amdgcn_sched_barrier(0)
; template <class Epi, class Sched>
; __device__ __forceinline__ void gemm_phase(LAS unsigned char* lds, const Gemm g, const Sched& S, const Epi& E) {
;     ...
;             PG8_LDB(B0, 0, 0); PG8_SCHED; PG8_LDA(At, 0, 0); PG8_STAGE(PG8_SA(1, 1), a1 + hstep, voffA);
;             PG8_WAIT_L(8); PG8_BAR; PG8_WAIT_L(0); PG8_MMA(0, 0, At, B0); PG8_BAR; PG8_SCHED;
;             PG8_LDB(B1, 0, 1); PG8_STAGE(PG8_SB(0, 0), b2, voffB);
;             PG8_BAR; PG8_WAIT_L(0); PG8_MMA(0, 1, At, B1); PG8_BAR;
;             PG8_LDA(At, 0, 1); PG8_STAGE(PG8_SA(0, 0), a2, voffA);
;             PG8_BAR; PG8_WAIT_L(0); PG8_MMA(1, 0, At, B0); PG8_BAR; PG8_SCHED;
;             PG8_STAGE(PG8_SB(0, 1), b2 + hstep, voffB);
;             PG8_WAIT_V(6); PG8_BAR; PG8_MMA(1, 1, At, B1); PG8_BAR;
;             PG8_LDB(B0, 1, 0); PG8_SCHED; PG8_LDA(At, 1, 0); PG8_STAGE(PG8_SA(0, 1), a2 + hstep, voffA);
;             PG8_WAIT_L(8); PG8_BAR; PG8_WAIT_L(0); PG8_MMA(0, 0, At, B0); PG8_BAR; PG8_SCHED;
;             PG8_LDB(B1, 1, 1); PG8_STAGE(PG8_SB(1, 0), b3, voffB);
;             PG8_BAR; PG8_WAIT_L(0); PG8_MMA(0, 1, At, B1); PG8_BAR;
;             PG8_LDA(At, 1, 1); PG8_STAGE(PG8_SA(1, 0), a3, voffA);
;             PG8_BAR; PG8_WAIT_L(0); PG8_MMA(1, 0, At, B0); PG8_BAR; PG8_SCHED;
;             PG8_STAGE(PG8_SB(1, 1), b3 + hstep, voffB);
;             PG8_WAIT_V(6); PG8_BAR; PG8_MMA(1, 1, At, B1); PG8_BAR;
	s_waitcnt lgkmcnt(0)
	s_setprio 1
	s_waitcnt lgkmcnt(0)
	v_mfma_f32_16x16x32_bf16 v[60:63], v[128:131], v[170:173], v[60:63]
	v_mfma_f32_16x16x32_bf16 v[56:59], v[136:139], v[170:173], v[56:59]
	v_mfma_f32_16x16x32_bf16 v[44:47], v[128:131], v[178:181], v[44:47]
	v_mfma_f32_16x16x32_bf16 v[40:43], v[136:139], v[178:181], v[40:43]
	v_mfma_f32_16x16x32_bf16 v[28:31], v[128:131], v[186:189], v[28:31]
	v_mfma_f32_16x16x32_bf16 v[24:27], v[136:139], v[186:189], v[24:27]
	v_mfma_f32_16x16x32_bf16 v[12:15], v[128:131], v[194:197], v[12:15]
	v_mfma_f32_16x16x32_bf16 v[8:11], v[136:139], v[194:197], v[8:11]
	v_mfma_f32_16x16x32_bf16 v[60:63], v[132:135], v[174:177], v[60:63]
	v_mfma_f32_16x16x32_bf16 v[56:59], v[160:163], v[174:177], v[56:59]
	v_mfma_f32_16x16x32_bf16 v[44:47], v[132:135], v[182:185], v[44:47]
	v_mfma_f32_16x16x32_bf16 v[40:43], v[160:163], v[182:185], v[40:43]
	v_mfma_f32_16x16x32_bf16 v[28:31], v[132:135], v[190:193], v[28:31]
	v_mfma_f32_16x16x32_bf16 v[24:27], v[160:163], v[190:193], v[24:27]
	v_mfma_f32_16x16x32_bf16 v[12:15], v[132:135], v[202:205], v[12:15]
	v_mfma_f32_16x16x32_bf16 v[8:11], v[160:163], v[202:205], v[8:11]
	s_setprio 0
	s_barrier
	s_add_u32 s26, s26, 0x40080
	s_addc_u32 s27, s27, 0
	s_add_i32 s28, s28, s34
	s_mov_b32 m0, s28
	s_nop 0
	global_load_lds_dwordx4 v146, s[26:27]
	s_add_i32 m0, s28, 0x2000
	s_nop 0
	global_load_lds_dwordx4 v142, s[26:27]
	s_waitcnt vmcnt(10)
	s_barrier
	s_setprio 1
	v_mfma_f32_16x16x32_bf16 v[52:55], v[206:209], v[170:173], v[52:55]
	v_mfma_f32_16x16x32_bf16 v[48:51], v[214:217], v[170:173], v[48:51]
	v_mfma_f32_16x16x32_bf16 v[36:39], v[206:209], v[178:181], v[36:39]
	v_mfma_f32_16x16x32_bf16 v[32:35], v[214:217], v[178:181], v[32:35]
	v_mfma_f32_16x16x32_bf16 v[20:23], v[206:209], v[186:189], v[20:23]
	v_mfma_f32_16x16x32_bf16 v[16:19], v[214:217], v[186:189], v[16:19]
	v_mfma_f32_16x16x32_bf16 v[4:7], v[206:209], v[194:197], v[4:7]
	v_mfma_f32_16x16x32_bf16 v[0:3], v[214:217], v[194:197], v[0:3]
	v_mfma_f32_16x16x32_bf16 v[52:55], v[210:213], v[174:177], v[52:55]
	v_mfma_f32_16x16x32_bf16 v[48:51], v[218:221], v[174:177], v[48:51]
	v_mfma_f32_16x16x32_bf16 v[36:39], v[210:213], v[182:185], v[36:39]
	v_mfma_f32_16x16x32_bf16 v[32:35], v[218:221], v[182:185], v[32:35]
	v_mfma_f32_16x16x32_bf16 v[20:23], v[210:213], v[190:193], v[20:23]
	v_mfma_f32_16x16x32_bf16 v[16:19], v[218:221], v[190:193], v[16:19]
	v_mfma_f32_16x16x32_bf16 v[4:7], v[210:213], v[202:205], v[4:7]
	v_mfma_f32_16x16x32_bf16 v[0:3], v[218:221], v[202:205], v[0:3]
	s_setprio 0
	s_add_i32 s56, s56, 2
	s_add_u32 s6, s6, 0x100
	s_addc_u32 s7, s7, 0
	s_add_u32 s54, s54, 0x100
	s_addc_u32 s55, s55, 0
	s_cmp_gt_u32 s56, 13
	s_barrier
.LBB0_578:
	ds_read_b128 v[128:131], v167
	ds_read_b128 v[132:135], v167 offset:1024
	ds_read_b128 v[136:139], v167 offset:2048
	ds_read_b128 v[160:163], v167 offset:3072
	s_add_u32 s26, s6, 0xfffc0080
	s_addc_u32 s27, s7, -1
	s_cmp_eq_u32 s56, 12
	s_cselect_b32 s29, s5, s27
	s_cselect_b32 s28, s21, s26
	s_cselect_b32 s27, s19, s55
	s_cselect_b32 s26, s53, s54
	s_add_i32 m0, s37, 0xc000
	ds_read_b128 v[170:173], v168
	ds_read_b128 v[174:177], v168 offset:1024
	ds_read_b128 v[178:181], v168 offset:2048
	ds_read_b128 v[182:185], v168 offset:3072
	ds_read_b128 v[186:189], v168 offset:4096
	ds_read_b128 v[190:193], v168 offset:5120
	ds_read_b128 v[194:197], v168 offset:6144
	ds_read_b128 v[202:205], v168 offset:7168
	global_load_lds_dwordx4 v152, s[6:7]
	s_add_i32 m0, s37, 0xe000
	s_nop 0
	global_load_lds_dwordx4 v154, s[6:7]
	s_waitcnt lgkmcnt(8)
	s_waitcnt vmcnt(10)
	s_barrier
	s_waitcnt lgkmcnt(0)
	s_setprio 1
	s_waitcnt lgkmcnt(0)
	v_mfma_f32_16x16x32_bf16 v[124:127], v[128:131], v[170:173], v[124:127]
	v_mfma_f32_16x16x32_bf16 v[120:123], v[136:139], v[170:173], v[120:123]
	v_mfma_f32_16x16x32_bf16 v[108:111], v[128:131], v[178:181], v[108:111]
	v_mfma_f32_16x16x32_bf16 v[104:107], v[136:139], v[178:181], v[104:107]
	v_mfma_f32_16x16x32_bf16 v[92:95], v[128:131], v[186:189], v[92:95]
	v_mfma_f32_16x16x32_bf16 v[88:91], v[136:139], v[186:189], v[88:91]
	v_mfma_f32_16x16x32_bf16 v[76:79], v[128:131], v[194:197], v[76:79]
	v_mfma_f32_16x16x32_bf16 v[72:75], v[136:139], v[194:197], v[72:75]
	v_mfma_f32_16x16x32_bf16 v[124:127], v[132:135], v[174:177], v[124:127]
	v_mfma_f32_16x16x32_bf16 v[120:123], v[160:163], v[174:177], v[120:123]
	v_mfma_f32_16x16x32_bf16 v[108:111], v[132:135], v[182:185], v[108:111]
	v_mfma_f32_16x16x32_bf16 v[104:107], v[160:163], v[182:185], v[104:107]
	v_mfma_f32_16x16x32_bf16 v[92:95], v[132:135], v[190:193], v[92:95]
	v_mfma_f32_16x16x32_bf16 v[88:91], v[160:163], v[190:193], v[88:91]
	v_mfma_f32_16x16x32_bf16 v[76:79], v[132:135], v[202:205], v[76:79]
	v_mfma_f32_16x16x32_bf16 v[72:75], v[160:163], v[202:205], v[72:75]
	s_setprio 0
	s_barrier
	s_add_i32 s57, s48, s34
	s_mov_b32 m0, s57
	ds_read_b128 v[206:209], v169
	ds_read_b128 v[210:213], v169 offset:1024
	ds_read_b128 v[214:217], v169 offset:2048
	ds_read_b128 v[218:221], v169 offset:3072
	global_load_lds_dwordx4 v146, s[26:27]
	s_add_i32 m0, s57, 0x2000
	s_nop 0
	global_load_lds_dwordx4 v142, s[26:27]
	s_waitcnt vmcnt(10)
	s_barrier
; #define PG8_STAGE(bufoff, gbase, voff) do { _Pragma("unroll") for (int _i = 0; _i < 2; ++_i) \
;         __builtin_amdgcn_global_load_lds((const unsigned*)((const char*)(gbase) + (voff)[_i]), (LAS unsigned*)(lds + (bufoff) + ldsw + _i * 8192), 16, 0, 0); } while (0)
; #define PG8_LDA(dst, b, h) do { _Pragma("unroll") for (int m = 0; m < 4; ++m) _Pragma("unroll") for (int k = 0; k < 2; ++k) dst[m][k] = *(const LAS bf16x8*)(lds + PG8_SA(b, h) + aoff + m * 2048 + k * 1024); } while (0)
; #define PG8_LDB(dst, b, h) do { _Pragma("unroll") for (int n = 0; n < 2; ++n) _Pragma("unroll") for (int k = 0; k < 2; ++k) dst[n][k] = *(const LAS bf16x8*)(lds + PG8_SB(b, h) + boff + n * 2048 + k * 1024); } while (0)
; #define PG8_MMA(ai, bj, At, Bt) do { __builtin_amdgcn_s_setprio(1); _Pragma("unroll") for (int m = 0; m < 4; ++m) _Pragma("unroll") for (int n = 0; n < 2; ++n) _Pragma("unroll") for (int k = 0; k < 2; ++k) \
;         acc[ai][bj][m][n] = __builtin_amdgcn_mfma_f32_16x16x32_bf16(Bt[n][k], At[m][k], acc[ai][bj][m][n], 0, 0, 0); __builtin_amdgcn_s_setprio(0); } while (0)
; #define PG8_WAIT_V(n) asm volatile("s_waitcnt vmcnt(" #n ")" ::: "memory")
; #define PG8_WAIT_L(n) asm volatile("s_waitcnt lgkmcnt(" #n ")" ::: "memory")
; #define PG8_BAR __builtin_amdgcn_s_barrier()
; #define PG8_SCHED __builtin_amdgcn_sched_barrier(0)
; template <class Epi, class Sched>
; __device__ __forceinline__ void gemm_phase(LAS unsigned char* lds, const Gemm g, const Sched& S, const Epi& E) {
;     ...
;             PG8_LDB(B1, 0, 1); PG8_STAGE(PG8_SB(0, 0), b2, voffB);
;             PG8_BAR; PG8_WAIT_L(0); PG8_MMA(0, 1, At, B1); PG8_BAR;
;             PG8_LDA(At, 0, 1); PG8_STAGE(PG8_SA(0, 0), a2, voffA);
;             PG8_BAR; PG8_WAIT_L(0); PG8_MMA(1, 0, At, B0); PG8_BAR; PG8_SCHED;
;             PG8_STAGE(PG8_SB(0, 1), b2 + hstep, voffB);
;             PG8_WAIT_V(6); PG8_BAR; PG8_MMA(1, 1, At, B1); PG8_BAR;
;             PG8_LDB(B0, 1, 0); PG8_SCHED; PG8_LDA(At, 1, 0); PG8_STAGE(PG8_SA(0, 1), a2 + hstep, voffA);
;             PG8_WAIT_L(8); PG8_BAR; PG8_WAIT_L(0); PG8_MMA(0, 0, At, B0); PG8_BAR; PG8_SCHED;
	s_waitcnt lgkmcnt(0)
	s_setprio 1
	s_waitcnt lgkmcnt(0)
	v_mfma_f32_16x16x32_bf16 v[116:119], v[206:209], v[170:173], v[116:119]
	v_mfma_f32_16x16x32_bf16 v[112:115], v[214:217], v[170:173], v[112:115]
	v_mfma_f32_16x16x32_bf16 v[100:103], v[206:209], v[178:181], v[100:103]
	v_mfma_f32_16x16x32_bf16 v[96:99], v[214:217], v[178:181], v[96:99]
	v_mfma_f32_16x16x32_bf16 v[84:87], v[206:209], v[186:189], v[84:87]
	v_mfma_f32_16x16x32_bf16 v[80:83], v[214:217], v[186:189], v[80:83]
	v_mfma_f32_16x16x32_bf16 v[68:71], v[206:209], v[194:197], v[68:71]
	v_mfma_f32_16x16x32_bf16 v[64:67], v[214:217], v[194:197], v[64:67]
	v_mfma_f32_16x16x32_bf16 v[116:119], v[210:213], v[174:177], v[116:119]
	v_mfma_f32_16x16x32_bf16 v[112:115], v[218:221], v[174:177], v[112:115]
	v_mfma_f32_16x16x32_bf16 v[100:103], v[210:213], v[182:185], v[100:103]
	v_mfma_f32_16x16x32_bf16 v[96:99], v[218:221], v[182:185], v[96:99]
	v_mfma_f32_16x16x32_bf16 v[84:87], v[210:213], v[190:193], v[84:87]
	v_mfma_f32_16x16x32_bf16 v[80:83], v[218:221], v[190:193], v[80:83]
	v_mfma_f32_16x16x32_bf16 v[68:71], v[210:213], v[202:205], v[68:71]
	v_mfma_f32_16x16x32_bf16 v[64:67], v[218:221], v[202:205], v[64:67]
	s_setprio 0
	s_mov_b32 m0, s37
	v_lshl_add_u64 v[222:223], s[28:29], 0, v[148:149]
	s_barrier
	ds_read_b128 v[170:173], v168 offset:16384
	ds_read_b128 v[174:177], v168 offset:17408
	ds_read_b128 v[178:181], v168 offset:18432
	ds_read_b128 v[182:185], v168 offset:19456
	ds_read_b128 v[186:189], v168 offset:20480
	ds_read_b128 v[190:193], v168 offset:21504
	ds_read_b128 v[194:197], v168 offset:22528
	ds_read_b128 v[202:205], v168 offset:23552
	global_load_lds_dwordx4 v148, s[28:29]
	v_lshl_add_u64 v[224:225], s[28:29], 0, v[144:145]
	s_mov_b32 m0, s38
	s_nop 0
	global_load_lds_dwordx4 v144, s[28:29]
	s_barrier
	s_waitcnt lgkmcnt(0)
	s_setprio 1
	s_waitcnt lgkmcnt(0)
	v_mfma_f32_16x16x32_bf16 v[60:63], v[128:131], v[170:173], v[60:63]
	v_mfma_f32_16x16x32_bf16 v[56:59], v[136:139], v[170:173], v[56:59]
	v_mfma_f32_16x16x32_bf16 v[44:47], v[128:131], v[178:181], v[44:47]
	v_mfma_f32_16x16x32_bf16 v[40:43], v[136:139], v[178:181], v[40:43]
	v_mfma_f32_16x16x32_bf16 v[28:31], v[128:131], v[186:189], v[28:31]
	v_mfma_f32_16x16x32_bf16 v[24:27], v[136:139], v[186:189], v[24:27]
	v_mfma_f32_16x16x32_bf16 v[12:15], v[128:131], v[194:197], v[12:15]
	v_mfma_f32_16x16x32_bf16 v[8:11], v[136:139], v[194:197], v[8:11]
	v_mfma_f32_16x16x32_bf16 v[60:63], v[132:135], v[174:177], v[60:63]
	v_mfma_f32_16x16x32_bf16 v[56:59], v[160:163], v[174:177], v[56:59]
	v_mfma_f32_16x16x32_bf16 v[44:47], v[132:135], v[182:185], v[44:47]
	v_mfma_f32_16x16x32_bf16 v[40:43], v[160:163], v[182:185], v[40:43]
	v_mfma_f32_16x16x32_bf16 v[28:31], v[132:135], v[190:193], v[28:31]
	v_mfma_f32_16x16x32_bf16 v[24:27], v[160:163], v[190:193], v[24:27]
	v_mfma_f32_16x16x32_bf16 v[12:15], v[132:135], v[202:205], v[12:15]
	v_mfma_f32_16x16x32_bf16 v[8:11], v[160:163], v[202:205], v[8:11]
	s_setprio 0
	s_barrier
	s_add_u32 s58, s26, 0x40000
	s_addc_u32 s59, s27, 0
	s_add_i32 s57, s49, s34
	s_mov_b32 m0, s57
	s_nop 0
	global_load_lds_dwordx4 v146, s[58:59]
	s_add_i32 m0, s57, 0x2000
	s_nop 0
	global_load_lds_dwordx4 v142, s[58:59]
	s_waitcnt vmcnt(10)
	s_barrier
	s_setprio 1
	v_mfma_f32_16x16x32_bf16 v[52:55], v[206:209], v[170:173], v[52:55]
	v_mfma_f32_16x16x32_bf16 v[48:51], v[214:217], v[170:173], v[48:51]
	v_mfma_f32_16x16x32_bf16 v[36:39], v[206:209], v[178:181], v[36:39]
	v_mfma_f32_16x16x32_bf16 v[32:35], v[214:217], v[178:181], v[32:35]
	v_mfma_f32_16x16x32_bf16 v[20:23], v[206:209], v[186:189], v[20:23]
	v_mfma_f32_16x16x32_bf16 v[16:19], v[214:217], v[186:189], v[16:19]
	v_mfma_f32_16x16x32_bf16 v[4:7], v[206:209], v[194:197], v[4:7]
	v_mfma_f32_16x16x32_bf16 v[0:3], v[214:217], v[194:197], v[0:3]
	v_mfma_f32_16x16x32_bf16 v[52:55], v[210:213], v[174:177], v[52:55]
	v_mfma_f32_16x16x32_bf16 v[48:51], v[218:221], v[174:177], v[48:51]
	v_mfma_f32_16x16x32_bf16 v[36:39], v[210:213], v[182:185], v[36:39]
	v_mfma_f32_16x16x32_bf16 v[32:35], v[218:221], v[182:185], v[32:35]
	v_mfma_f32_16x16x32_bf16 v[20:23], v[210:213], v[190:193], v[20:23]
	v_mfma_f32_16x16x32_bf16 v[16:19], v[218:221], v[190:193], v[16:19]
	v_mfma_f32_16x16x32_bf16 v[4:7], v[210:213], v[202:205], v[4:7]
	v_mfma_f32_16x16x32_bf16 v[0:3], v[218:221], v[202:205], v[0:3]
	s_setprio 0
	s_add_i32 s57, 0, 0x18000
	v_add_u32_e32 v150, s57, v166
	s_barrier
	ds_read_b128 v[128:131], v150
	ds_read_b128 v[132:135], v150 offset:1024
	ds_read_b128 v[136:139], v150 offset:2048
	ds_read_b128 v[160:163], v150 offset:3072
	s_add_u32 s28, s28, 0x40000
	s_addc_u32 s29, s29, 0
	s_mov_b32 m0, s39
	ds_read_b128 v[170:173], v168 offset:32768
	ds_read_b128 v[174:177], v168 offset:33792
	ds_read_b128 v[178:181], v168 offset:34816
	ds_read_b128 v[182:185], v168 offset:35840
	ds_read_b128 v[186:189], v168 offset:36864
	ds_read_b128 v[190:193], v168 offset:37888
	ds_read_b128 v[194:197], v168 offset:38912
	ds_read_b128 v[202:205], v168 offset:39936
	global_load_lds_dwordx4 v148, s[28:29]
	s_mov_b32 m0, s40
	s_nop 0
	global_load_lds_dwordx4 v144, s[28:29]
	s_waitcnt lgkmcnt(8)
	s_waitcnt vmcnt(10)
	s_barrier
; #define PG8_STAGE(bufoff, gbase, voff) do { _Pragma("unroll") for (int _i = 0; _i < 2; ++_i) \
;         __builtin_amdgcn_global_load_lds((const unsigned*)((const char*)(gbase) + (voff)[_i]), (LAS unsigned*)(lds + (bufoff) + ldsw + _i * 8192), 16, 0, 0); } while (0)
; #define PG8_LDA(dst, b, h) do { _Pragma("unroll") for (int m = 0; m < 4; ++m) _Pragma("unroll") for (int k = 0; k < 2; ++k) dst[m][k] = *(const LAS bf16x8*)(lds + PG8_SA(b, h) + aoff + m * 2048 + k * 1024); } while (0)
; #define PG8_LDB(dst, b, h) do { _Pragma("unroll") for (int n = 0; n < 2; ++n) _Pragma("unroll") for (int k = 0; k < 2; ++k) dst[n][k] = *(const LAS bf16x8*)(lds + PG8_SB(b, h) + boff + n * 2048 + k * 1024); } while (0)
; #define PG8_MMA(ai, bj, At, Bt) do { __builtin_amdgcn_s_setprio(1); _Pragma("unroll") for (int m = 0; m < 4; ++m) _Pragma("unroll") for (int n = 0; n < 2; ++n) _Pragma("unroll") for (int k = 0; k < 2; ++k) \
;         acc[ai][bj][m][n] = __builtin_amdgcn_mfma_f32_16x16x32_bf16(Bt[n][k], At[m][k], acc[ai][bj][m][n], 0, 0, 0); __builtin_amdgcn_s_setprio(0); } while (0)
; #define PG8_WAIT_L(n) asm volatile("s_waitcnt lgkmcnt(" #n ")" ::: "memory")
; #define PG8_BAR __builtin_amdgcn_s_barrier()
; #define PG8_SCHED __builtin_amdgcn_sched_barrier(0)
; template <class Epi, class Sched>
; __device__ __forceinline__ void gemm_phase(LAS unsigned char* lds, const Gemm g, const Sched& S, const Epi& E) {
;     ...
;             PG8_WAIT_L(8); PG8_BAR; PG8_WAIT_L(0); PG8_MMA(0, 0, At, B0); PG8_BAR; PG8_SCHED;
;             PG8_LDB(B1, 1, 1); PG8_STAGE(PG8_SB(1, 0), b3, voffB);
;             PG8_BAR; PG8_WAIT_L(0); PG8_MMA(0, 1, At, B1); PG8_BAR;
;             PG8_LDA(At, 1, 1); PG8_STAGE(PG8_SA(1, 0), a3, voffA);
	s_waitcnt lgkmcnt(0)
	s_setprio 1
	s_waitcnt lgkmcnt(0)
	v_mfma_f32_16x16x32_bf16 v[124:127], v[128:131], v[170:173], v[124:127]
	v_mfma_f32_16x16x32_bf16 v[120:123], v[136:139], v[170:173], v[120:123]
	v_mfma_f32_16x16x32_bf16 v[108:111], v[128:131], v[178:181], v[108:111]
	v_mfma_f32_16x16x32_bf16 v[104:107], v[136:139], v[178:181], v[104:107]
	v_mfma_f32_16x16x32_bf16 v[92:95], v[128:131], v[186:189], v[92:95]
	v_mfma_f32_16x16x32_bf16 v[88:91], v[136:139], v[186:189], v[88:91]
	v_mfma_f32_16x16x32_bf16 v[76:79], v[128:131], v[194:197], v[76:79]
	v_mfma_f32_16x16x32_bf16 v[72:75], v[136:139], v[194:197], v[72:75]
	v_mfma_f32_16x16x32_bf16 v[124:127], v[132:135], v[174:177], v[124:127]
	v_mfma_f32_16x16x32_bf16 v[120:123], v[160:163], v[174:177], v[120:123]
	v_mfma_f32_16x16x32_bf16 v[108:111], v[132:135], v[182:185], v[108:111]
	v_mfma_f32_16x16x32_bf16 v[104:107], v[160:163], v[182:185], v[104:107]
	v_mfma_f32_16x16x32_bf16 v[92:95], v[132:135], v[190:193], v[92:95]
	v_mfma_f32_16x16x32_bf16 v[88:91], v[160:163], v[190:193], v[88:91]
	v_mfma_f32_16x16x32_bf16 v[76:79], v[132:135], v[202:205], v[76:79]
	v_mfma_f32_16x16x32_bf16 v[72:75], v[160:163], v[202:205], v[72:75]
	s_setprio 0
	s_barrier
	s_add_i32 s28, 0, 0x1c000
	s_add_i32 s29, s57, s34
	v_add_u32_e32 v150, s28, v166
	s_add_u32 s0, s26, 0x80
	s_addc_u32 s1, s27, 0
	s_mov_b32 m0, s29
	ds_read_b128 v[206:209], v150
	ds_read_b128 v[210:213], v150 offset:1024
	ds_read_b128 v[214:217], v150 offset:2048
	ds_read_b128 v[218:221], v150 offset:3072
	global_load_lds_dwordx4 v146, s[0:1]
	s_add_i32 m0, s29, 0x2000
	s_nop 0
	global_load_lds_dwordx4 v142, s[0:1]
	s_waitcnt vmcnt(10)
	s_barrier
	s_waitcnt lgkmcnt(0)
	s_setprio 1
	s_waitcnt lgkmcnt(0)
	v_mfma_f32_16x16x32_bf16 v[116:119], v[206:209], v[170:173], v[116:119]
	v_mfma_f32_16x16x32_bf16 v[112:115], v[214:217], v[170:173], v[112:115]
	v_mfma_f32_16x16x32_bf16 v[100:103], v[206:209], v[178:181], v[100:103]
	v_mfma_f32_16x16x32_bf16 v[96:99], v[214:217], v[178:181], v[96:99]
	v_mfma_f32_16x16x32_bf16 v[84:87], v[206:209], v[186:189], v[84:87]
	v_mfma_f32_16x16x32_bf16 v[80:83], v[214:217], v[186:189], v[80:83]
	v_mfma_f32_16x16x32_bf16 v[68:71], v[206:209], v[194:197], v[68:71]
	v_mfma_f32_16x16x32_bf16 v[64:67], v[214:217], v[194:197], v[64:67]
	v_mfma_f32_16x16x32_bf16 v[116:119], v[210:213], v[174:177], v[116:119]
	v_mfma_f32_16x16x32_bf16 v[112:115], v[218:221], v[174:177], v[112:115]
	v_mfma_f32_16x16x32_bf16 v[100:103], v[210:213], v[182:185], v[100:103]
	v_mfma_f32_16x16x32_bf16 v[96:99], v[218:221], v[182:185], v[96:99]
	v_mfma_f32_16x16x32_bf16 v[84:87], v[210:213], v[190:193], v[84:87]
	v_mfma_f32_16x16x32_bf16 v[80:83], v[218:221], v[190:193], v[80:83]
	v_mfma_f32_16x16x32_bf16 v[68:71], v[210:213], v[202:205], v[68:71]
	v_mfma_f32_16x16x32_bf16 v[64:67], v[218:221], v[202:205], v[64:67]
	s_setprio 0
	s_mov_b32 m0, s44
	s_mov_b64 s[0:1], 0x80
	v_lshl_add_u64 v[140:141], v[222:223], 0, s[0:1]
	s_barrier
	ds_read_b128 v[170:173], v168 offset:49152
	ds_read_b128 v[174:177], v168 offset:50176
	ds_read_b128 v[178:181], v168 offset:51200
	ds_read_b128 v[182:185], v168 offset:52224
	ds_read_b128 v[186:189], v168 offset:53248
	ds_read_b128 v[190:193], v168 offset:54272
	ds_read_b128 v[194:197], v168 offset:55296
	ds_read_b128 v[202:205], v168 offset:56320
	global_load_lds_dwordx4 v[140:141], off
	v_lshl_add_u64 v[140:141], v[224:225], 0, s[0:1]
	s_mov_b32 m0, s45
	s_nop 0
	global_load_lds_dwordx4 v[140:141], off
	s_barrier
; #define PG8_STAGE(bufoff, gbase, voff) do { _Pragma("unroll") for (int _i = 0; _i < 2; ++_i) \
;         __builtin_amdgcn_global_load_lds((const unsigned*)((const char*)(gbase) + (voff)[_i]), (LAS unsigned*)(lds + (bufoff) + ldsw + _i * 8192), 16, 0, 0); } while (0)
; #define PG8_MMA(ai, bj, At, Bt) do { __builtin_amdgcn_s_setprio(1); _Pragma("unroll") for (int m = 0; m < 4; ++m) _Pragma("unroll") for (int n = 0; n < 2; ++n) _Pragma("unroll") for (int k = 0; k < 2; ++k) \
;         acc[ai][bj][m][n] = __builtin_amdgcn_mfma_f32_16x16x32_bf16(Bt[n][k], At[m][k], acc[ai][bj][m][n], 0, 0, 0); __builtin_amdgcn_s_setprio(0); } while (0)
; #define PG8_WAIT_V(n) asm volatile("s_waitcnt vmcnt(" #n ")" ::: "memory")
; #define PG8_WAIT_L(n) asm volatile("s_waitcnt lgkmcnt(" #n ")" ::: "memory")
; #define PG8_BAR __builtin_amdgcn_s_barrier()
; #define PG8_SCHED __builtin_amdgcn_sched_barrier(0)
; template <class Epi, class Sched>
; __device__ __forceinline__ void gemm_phase(LAS unsigned char* lds, const Gemm g, const Sched& S, const Epi& E) {
;     ...
;             PG8_BAR; PG8_WAIT_L(0); PG8_MMA(1, 0, At, B0); PG8_BAR; PG8_SCHED;
;             PG8_STAGE(PG8_SB(1, 1), b3 + hstep, voffB);
;             PG8_WAIT_V(6); PG8_BAR; PG8_MMA(1, 1, At, B1); PG8_BAR;
;     __device__ __forceinline__ void operator()(const AccT& acc, const Unit& u, int wr, int wc, int fr, int fq) const {
;     ...
;         const int row0 = u.pm * 256 + wr * 64 + fr, col0 = u.pn * 256 + wc * 32 + 8 * fq;
;         const bool rope = u.pn < 2;
;         const int i = 4 * (wc & 1) + fq;
; #pragma unroll
;         for (int ai = 0; ai < 2; ++ai)
; #pragma unroll
;             for (int m = 0; m < 4; ++m) {
;                 const int row = row0 + ai * 128 + m * 16;
;                 f32x4 cs = {1.f, 1.f, 1.f, 1.f}, sn = {0.f, 0.f, 0.f, 0.f};
;                 if (rope) { const int t = row & 2047; const int pos = (i < 4) ? (t >> 6) : (t & 63);
;                     cs = *(const f32x4*)(ropeA + pos * 16 + ((4 * i) & 15)); sn = *(const f32x4*)(ropeA + 1024 + pos * 16 + ((4 * i) & 15)); }
	s_waitcnt lgkmcnt(0)
	s_setprio 1
	s_waitcnt lgkmcnt(0)
	v_mfma_f32_16x16x32_bf16 v[60:63], v[128:131], v[170:173], v[60:63]
	v_mfma_f32_16x16x32_bf16 v[56:59], v[136:139], v[170:173], v[56:59]
	v_mfma_f32_16x16x32_bf16 v[44:47], v[128:131], v[178:181], v[44:47]
	v_mfma_f32_16x16x32_bf16 v[40:43], v[136:139], v[178:181], v[40:43]
	v_mfma_f32_16x16x32_bf16 v[28:31], v[128:131], v[186:189], v[28:31]
	v_mfma_f32_16x16x32_bf16 v[24:27], v[136:139], v[186:189], v[24:27]
	v_mfma_f32_16x16x32_bf16 v[12:15], v[128:131], v[194:197], v[12:15]
	v_mfma_f32_16x16x32_bf16 v[8:11], v[136:139], v[194:197], v[8:11]
	v_mfma_f32_16x16x32_bf16 v[60:63], v[132:135], v[174:177], v[60:63]
	v_mfma_f32_16x16x32_bf16 v[56:59], v[160:163], v[174:177], v[56:59]
	v_mfma_f32_16x16x32_bf16 v[44:47], v[132:135], v[182:185], v[44:47]
	v_mfma_f32_16x16x32_bf16 v[40:43], v[160:163], v[182:185], v[40:43]
	v_mfma_f32_16x16x32_bf16 v[28:31], v[132:135], v[190:193], v[28:31]
	v_mfma_f32_16x16x32_bf16 v[24:27], v[160:163], v[190:193], v[24:27]
	v_mfma_f32_16x16x32_bf16 v[12:15], v[132:135], v[202:205], v[12:15]
	v_mfma_f32_16x16x32_bf16 v[8:11], v[160:163], v[202:205], v[8:11]
	s_setprio 0
	s_barrier
	s_add_u32 s26, s26, 0x40080
	s_addc_u32 s27, s27, 0
	s_add_i32 s28, s28, s34
	s_mov_b32 m0, s28
	s_nop 0
	global_load_lds_dwordx4 v146, s[26:27]
	s_add_i32 m0, s28, 0x2000
	s_nop 0
	global_load_lds_dwordx4 v142, s[26:27]
	s_waitcnt vmcnt(10)
	s_barrier
	s_setprio 1
	v_mfma_f32_16x16x32_bf16 v[52:55], v[206:209], v[170:173], v[52:55]
	v_mfma_f32_16x16x32_bf16 v[48:51], v[214:217], v[170:173], v[48:51]
	v_mfma_f32_16x16x32_bf16 v[36:39], v[206:209], v[178:181], v[36:39]
	v_mfma_f32_16x16x32_bf16 v[32:35], v[214:217], v[178:181], v[32:35]
	v_mfma_f32_16x16x32_bf16 v[20:23], v[206:209], v[186:189], v[20:23]
	v_mfma_f32_16x16x32_bf16 v[16:19], v[214:217], v[186:189], v[16:19]
	v_mfma_f32_16x16x32_bf16 v[4:7], v[206:209], v[194:197], v[4:7]
	v_mfma_f32_16x16x32_bf16 v[0:3], v[214:217], v[194:197], v[0:3]
	v_mfma_f32_16x16x32_bf16 v[52:55], v[210:213], v[174:177], v[52:55]
	v_mfma_f32_16x16x32_bf16 v[48:51], v[218:221], v[174:177], v[48:51]
	v_mfma_f32_16x16x32_bf16 v[36:39], v[210:213], v[182:185], v[36:39]
	v_mfma_f32_16x16x32_bf16 v[32:35], v[218:221], v[182:185], v[32:35]
	v_mfma_f32_16x16x32_bf16 v[20:23], v[210:213], v[190:193], v[20:23]
	v_mfma_f32_16x16x32_bf16 v[16:19], v[218:221], v[190:193], v[16:19]
	v_mfma_f32_16x16x32_bf16 v[4:7], v[210:213], v[202:205], v[4:7]
	v_mfma_f32_16x16x32_bf16 v[0:3], v[218:221], v[202:205], v[0:3]
	s_setprio 0
	s_add_i32 s56, s56, 2
	s_add_u32 s6, s6, 0x100
	s_addc_u32 s7, s7, 0
	s_add_u32 s54, s54, 0x100
	s_addc_u32 s55, s55, 0
	s_cmp_gt_u32 s56, 13
	s_barrier
	s_cbranch_scc0 .LBB0_578
	v_mov_b32_e32 v129, v165
	v_mov_b32_e32 v173, v164
	s_lshl_b32 s4, s4, 8
	s_add_i32 s4, s4, s42
	v_add_u32_e32 v128, s46, v129
	v_add_u32_e32 v170, s4, v173
	v_cmp_gt_i32_e64 s[4:5], 4, v128
	v_lshlrev_b32_e32 v128, 2, v128
	s_cmp_lt_i32 s52, 2
	v_and_b32_e32 v130, 12, v128
	s_cselect_b64 s[26:27], -1, 0
	s_cmp_gt_i32 s52, 1
	v_and_b32_e32 v172, 63, v173
	v_mov_b32_e32 v128, 1.0
	v_mov_b32_e32 v132, 0
	v_lshlrev_b32_e32 v162, 2, v130
	v_mov_b32_e32 v134, 0
	v_mov_b32_e32 v135, 0
	v_mov_b32_e32 v136, 0
	v_mov_b32_e32 v137, 0
	v_mov_b32_e32 v138, 1.0
	v_mov_b32_e32 v139, 1.0
	v_mov_b32_e32 v140, 1.0
	v_mov_b32_e32 v141, 1.0
	s_cbranch_scc1 .LBB0_581
	v_bfe_u32 v130, v170, 6, 5
	v_cndmask_b32_e64 v130, v172, v130, s[4:5]
	v_lshlrev_b32_e32 v150, 6, v130
	v_lshl_add_u64 v[130:131], s[16:17], 0, v[150:151]
	v_mov_b32_e32 v163, v151
	v_lshl_add_u64 v[134:135], s[8:9], 0, v[150:151]
	v_lshl_add_u64 v[130:131], v[130:131], 0, v[162:163]
	v_lshl_add_u64 v[134:135], v[134:135], 0, v[162:163]
	global_load_dwordx4 v[138:141], v[130:131], off
	s_nop 0
	global_load_dwordx4 v[134:137], v[134:135], off
	s_waitcnt vmcnt(0)

; #define PG8_STAGE(bufoff, gbase, voff) do { _Pragma("unroll") for (int _i = 0; _i < 2; ++_i) \
;         __builtin_amdgcn_global_load_lds((const unsigned*)((const char*)(gbase) + (voff)[_i]), (LAS unsigned*)(lds + (bufoff) + ldsw + _i * 8192), 16, 0, 0); } while (0)
; #define PG8_LDA(dst, b, h) do { _Pragma("unroll") for (int m = 0; m < 4; ++m) _Pragma("unroll") for (int k = 0; k < 2; ++k) dst[m][k] = *(const LAS bf16x8*)(lds + PG8_SA(b, h) + aoff + m * 2048 + k * 1024); } while (0)
; #define PG8_LDB(dst, b, h) do { _Pragma("unroll") for (int n = 0; n < 2; ++n) _Pragma("unroll") for (int k = 0; k < 2; ++k) dst[n][k] = *(const LAS bf16x8*)(lds + PG8_SB(b, h) + boff + n * 2048 + k * 1024); } while (0)
; #define PG8_WAIT_V(n) asm volatile("s_waitcnt vmcnt(" #n ")" ::: "memory")
; #define PG8_WAIT_L(n) asm volatile("s_waitcnt lgkmcnt(" #n ")" ::: "memory")
; #define PG8_BAR __builtin_amdgcn_s_barrier()
; #define PG8_SCHED __builtin_amdgcn_sched_barrier(0)
; template <class Epi, class Sched>
; __device__ __forceinline__ void gemm_phase(LAS unsigned char* lds, const Gemm g, const Sched& S, const Epi& E) {
;     ...
;         const bool has_next = S.next(ui + 1, nxt);
;         const char* nA = has_next ? (const char*)g.A + (size_t)nxt.pm * tstep : cA; const char* nB = has_next ? (const char*)g.Bt + (size_t)nxt.pn * tstep : cB;
;         for (int t = 0; t < nt; t += 2) {
;             const bool last = (t == nt - 2);
;             const char* a1 = cA + (size_t)(t + 1) * kstep;
;             const char* a2 = last ? nA : cA + (size_t)(t + 2) * kstep; const char* b2 = last ? nB : cB + (size_t)(t + 2) * kstep;
;             const char* a3 = a2 + kstep; const char* b3 = b2 + kstep;
;             PG8_LDB(B0, 0, 0); PG8_SCHED; PG8_LDA(At, 0, 0); PG8_STAGE(PG8_SA(1, 1), a1 + hstep, voffA);
;             PG8_WAIT_L(8); PG8_BAR; PG8_WAIT_L(0); PG8_MMA(0, 0, At, B0); PG8_BAR; PG8_SCHED;
;             PG8_LDB(B1, 0, 1); PG8_STAGE(PG8_SB(0, 0), b2, voffB);
;             PG8_BAR; PG8_WAIT_L(0); PG8_MMA(0, 1, At, B1); PG8_BAR;
;             PG8_LDA(At, 0, 1); PG8_STAGE(PG8_SA(0, 0), a2, voffA);
;             PG8_BAR; PG8_WAIT_L(0); PG8_MMA(1, 0, At, B0); PG8_BAR; PG8_SCHED;
;             PG8_STAGE(PG8_SB(0, 1), b2 + hstep, voffB);
;             PG8_WAIT_V(6); PG8_BAR; PG8_MMA(1, 1, At, B1); PG8_BAR;
.LBB0_612:
	s_ashr_i32 s35, s34, 31
	v_cmp_lt_i64_e32 vcc, s[6:7], v[142:143]
	s_lshl_b64 s[6:7], s[34:35], 19
	s_add_u32 s36, s40, s6
	s_addc_u32 s37, s41, s7
	s_and_b64 s[6:7], vcc, exec
	s_cselect_b32 s8, s37, s1
	s_cselect_b32 s9, s36, s0
	s_ashr_i32 s31, s30, 31
	s_lshl_b64 s[6:7], s[30:31], 19
	s_add_u32 s38, s96, s6
	s_addc_u32 s39, s97, s7
	s_and_b64 s[6:7], vcc, exec
	s_cselect_b32 s31, s39, s5
	s_cselect_b32 s35, s38, s4
	s_add_u32 s0, s0, 0x40080
	s_addc_u32 s1, s1, 0
	s_add_u32 s65, s4, 0x100
	s_addc_u32 s66, s5, 0
	s_mov_b32 s67, -2
	s_waitcnt lgkmcnt(0)
	ds_read_b128 v[146:149], v171
	ds_read_b128 v[150:153], v171 offset:1024
	ds_read_b128 v[154:157], v171 offset:2048
	ds_read_b128 v[158:161], v171 offset:3072
	s_add_u32 s4, s0, 0xfffc0080
	s_addc_u32 s5, s1, -1
	s_cmp_eq_u32 s67, 12
	s_cselect_b32 s7, s8, s5
	s_cselect_b32 s6, s9, s4
	s_cselect_b32 s5, s31, s66
	s_cselect_b32 s4, s35, s65
	s_add_i32 m0, s45, 0xc000
	ds_read_b128 v[162:165], v172
	ds_read_b128 v[178:181], v172 offset:1024
	ds_read_b128 v[182:185], v172 offset:2048
	ds_read_b128 v[186:189], v172 offset:3072
	ds_read_b128 v[190:193], v172 offset:4096
	ds_read_b128 v[194:197], v172 offset:5120
	ds_read_b128 v[202:205], v172 offset:6144
	ds_read_b128 v[206:209], v172 offset:7168
	global_load_lds_dwordx4 v138, s[0:1]
	s_add_i32 m0, s45, 0xe000
	s_nop 0
	global_load_lds_dwordx4 v140, s[0:1]
	s_waitcnt lgkmcnt(8)
	s_waitcnt vmcnt(10)
	s_barrier
	s_waitcnt lgkmcnt(0)
	s_setprio 1
	s_waitcnt lgkmcnt(0)
	v_mfma_f32_16x16x32_bf16 v[124:127], v[146:149], v[162:165], 0
	v_mfma_f32_16x16x32_bf16 v[120:123], v[154:157], v[162:165], 0
	v_mfma_f32_16x16x32_bf16 v[108:111], v[146:149], v[182:185], 0
	v_mfma_f32_16x16x32_bf16 v[104:107], v[154:157], v[182:185], 0
	v_mfma_f32_16x16x32_bf16 v[92:95], v[146:149], v[190:193], 0
	v_mfma_f32_16x16x32_bf16 v[88:91], v[154:157], v[190:193], 0
	v_mfma_f32_16x16x32_bf16 v[76:79], v[146:149], v[202:205], 0
	v_mfma_f32_16x16x32_bf16 v[72:75], v[154:157], v[202:205], 0
	v_mfma_f32_16x16x32_bf16 v[124:127], v[150:153], v[178:181], v[124:127]
	v_mfma_f32_16x16x32_bf16 v[120:123], v[158:161], v[178:181], v[120:123]
	v_mfma_f32_16x16x32_bf16 v[108:111], v[150:153], v[186:189], v[108:111]
	v_mfma_f32_16x16x32_bf16 v[104:107], v[158:161], v[186:189], v[104:107]
	v_mfma_f32_16x16x32_bf16 v[92:95], v[150:153], v[194:197], v[92:95]
	v_mfma_f32_16x16x32_bf16 v[88:91], v[158:161], v[194:197], v[88:91]
	v_mfma_f32_16x16x32_bf16 v[76:79], v[150:153], v[206:209], v[76:79]
	v_mfma_f32_16x16x32_bf16 v[72:75], v[158:161], v[206:209], v[72:75]
	s_setprio 0
	s_barrier
	s_add_i32 s68, s57, s44
	s_mov_b32 m0, s68
	ds_read_b128 v[210:213], v173
	ds_read_b128 v[214:217], v173 offset:1024
	ds_read_b128 v[218:221], v173 offset:2048
	ds_read_b128 v[222:225], v173 offset:3072
	global_load_lds_dwordx4 v130, s[4:5]
	s_add_i32 m0, s68, 0x2000
	s_nop 0
	global_load_lds_dwordx4 v134, s[4:5]
	s_waitcnt vmcnt(10)
	s_barrier
	s_waitcnt lgkmcnt(0)
	s_setprio 1
	s_waitcnt lgkmcnt(0)
	v_mfma_f32_16x16x32_bf16 v[116:119], v[210:213], v[162:165], 0
	v_mfma_f32_16x16x32_bf16 v[112:115], v[218:221], v[162:165], 0
	v_mfma_f32_16x16x32_bf16 v[100:103], v[210:213], v[182:185], 0
	v_mfma_f32_16x16x32_bf16 v[96:99], v[218:221], v[182:185], 0
	v_mfma_f32_16x16x32_bf16 v[84:87], v[210:213], v[190:193], 0
	v_mfma_f32_16x16x32_bf16 v[80:83], v[218:221], v[190:193], 0
	v_mfma_f32_16x16x32_bf16 v[68:71], v[210:213], v[202:205], 0
	v_mfma_f32_16x16x32_bf16 v[64:67], v[218:221], v[202:205], 0
	v_mfma_f32_16x16x32_bf16 v[116:119], v[214:217], v[178:181], v[116:119]
	v_mfma_f32_16x16x32_bf16 v[112:115], v[222:225], v[178:181], v[112:115]
	v_mfma_f32_16x16x32_bf16 v[100:103], v[214:217], v[186:189], v[100:103]
	v_mfma_f32_16x16x32_bf16 v[96:99], v[222:225], v[186:189], v[96:99]
	v_mfma_f32_16x16x32_bf16 v[84:87], v[214:217], v[194:197], v[84:87]
	v_mfma_f32_16x16x32_bf16 v[80:83], v[222:225], v[194:197], v[80:83]
	v_mfma_f32_16x16x32_bf16 v[68:71], v[214:217], v[206:209], v[68:71]
	v_mfma_f32_16x16x32_bf16 v[64:67], v[222:225], v[206:209], v[64:67]
	s_setprio 0
	s_mov_b32 m0, s45
	v_lshl_add_u64 v[226:227], s[6:7], 0, v[128:129]
	s_barrier
	ds_read_b128 v[162:165], v172 offset:16384
	ds_read_b128 v[178:181], v172 offset:17408
	ds_read_b128 v[182:185], v172 offset:18432
	ds_read_b128 v[186:189], v172 offset:19456
	ds_read_b128 v[190:193], v172 offset:20480
	ds_read_b128 v[194:197], v172 offset:21504
	ds_read_b128 v[202:205], v172 offset:22528
	ds_read_b128 v[206:209], v172 offset:23552
	global_load_lds_dwordx4 v128, s[6:7]
	v_lshl_add_u64 v[228:229], s[6:7], 0, v[132:133]
	s_mov_b32 m0, s46
	s_nop 0
	global_load_lds_dwordx4 v132, s[6:7]
	s_barrier
	s_waitcnt lgkmcnt(0)
	s_setprio 1
	s_waitcnt lgkmcnt(0)
	v_mfma_f32_16x16x32_bf16 v[60:63], v[146:149], v[162:165], 0
	v_mfma_f32_16x16x32_bf16 v[56:59], v[154:157], v[162:165], 0
	v_mfma_f32_16x16x32_bf16 v[44:47], v[146:149], v[182:185], 0
	v_mfma_f32_16x16x32_bf16 v[40:43], v[154:157], v[182:185], 0
	v_mfma_f32_16x16x32_bf16 v[28:31], v[146:149], v[190:193], 0
	v_mfma_f32_16x16x32_bf16 v[24:27], v[154:157], v[190:193], 0
	v_mfma_f32_16x16x32_bf16 v[12:15], v[146:149], v[202:205], 0
	v_mfma_f32_16x16x32_bf16 v[8:11], v[154:157], v[202:205], 0
	v_mfma_f32_16x16x32_bf16 v[60:63], v[150:153], v[178:181], v[60:63]
	v_mfma_f32_16x16x32_bf16 v[56:59], v[158:161], v[178:181], v[56:59]
	v_mfma_f32_16x16x32_bf16 v[44:47], v[150:153], v[186:189], v[44:47]
	v_mfma_f32_16x16x32_bf16 v[40:43], v[158:161], v[186:189], v[40:43]
	v_mfma_f32_16x16x32_bf16 v[28:31], v[150:153], v[194:197], v[28:31]
	v_mfma_f32_16x16x32_bf16 v[24:27], v[158:161], v[194:197], v[24:27]
	v_mfma_f32_16x16x32_bf16 v[12:15], v[150:153], v[206:209], v[12:15]
	v_mfma_f32_16x16x32_bf16 v[8:11], v[158:161], v[206:209], v[8:11]
	s_setprio 0
	s_barrier
; #define PG8_STAGE(bufoff, gbase, voff) do { _Pragma("unroll") for (int _i = 0; _i < 2; ++_i) \
;         __builtin_amdgcn_global_load_lds((const unsigned*)((const char*)(gbase) + (voff)[_i]), (LAS unsigned*)(lds + (bufoff) + ldsw + _i * 8192), 16, 0, 0); } while (0)
; #define PG8_LDA(dst, b, h) do { _Pragma("unroll") for (int m = 0; m < 4; ++m) _Pragma("unroll") for (int k = 0; k < 2; ++k) dst[m][k] = *(const LAS bf16x8*)(lds + PG8_SA(b, h) + aoff + m * 2048 + k * 1024); } while (0)
; #define PG8_LDB(dst, b, h) do { _Pragma("unroll") for (int n = 0; n < 2; ++n) _Pragma("unroll") for (int k = 0; k < 2; ++k) dst[n][k] = *(const LAS bf16x8*)(lds + PG8_SB(b, h) + boff + n * 2048 + k * 1024); } while (0)
; #define PG8_MMA(ai, bj, At, Bt) do { __builtin_amdgcn_s_setprio(1); _Pragma("unroll") for (int m = 0; m < 4; ++m) _Pragma("unroll") for (int n = 0; n < 2; ++n) _Pragma("unroll") for (int k = 0; k < 2; ++k) \
;         acc[ai][bj][m][n] = __builtin_amdgcn_mfma_f32_16x16x32_bf16(Bt[n][k], At[m][k], acc[ai][bj][m][n], 0, 0, 0); __builtin_amdgcn_s_setprio(0); } while (0)
; #define PG8_WAIT_V(n) asm volatile("s_waitcnt vmcnt(" #n ")" ::: "memory")
; #define PG8_WAIT_L(n) asm volatile("s_waitcnt lgkmcnt(" #n ")" ::: "memory")
; #define PG8_BAR __builtin_amdgcn_s_barrier()
; #define PG8_SCHED __builtin_amdgcn_sched_barrier(0)
; template <class Epi, class Sched>
; __device__ __forceinline__ void gemm_phase(LAS unsigned char* lds, const Gemm g, const Sched& S, const Epi& E) {
;     ...
;             PG8_STAGE(PG8_SB(0, 1), b2 + hstep, voffB);
;             PG8_WAIT_V(6); PG8_BAR; PG8_MMA(1, 1, At, B1); PG8_BAR;
;             PG8_LDB(B0, 1, 0); PG8_SCHED; PG8_LDA(At, 1, 0); PG8_STAGE(PG8_SA(0, 1), a2 + hstep, voffA);
;             PG8_WAIT_L(8); PG8_BAR; PG8_WAIT_L(0); PG8_MMA(0, 0, At, B0); PG8_BAR; PG8_SCHED;
;             PG8_LDB(B1, 1, 1); PG8_STAGE(PG8_SB(1, 0), b3, voffB);
;             PG8_BAR; PG8_WAIT_L(0); PG8_MMA(0, 1, At, B1); PG8_BAR;
;             PG8_LDA(At, 1, 1); PG8_STAGE(PG8_SA(1, 0), a3, voffA);
;             PG8_BAR; PG8_WAIT_L(0); PG8_MMA(1, 0, At, B0); PG8_BAR; PG8_SCHED;
;             PG8_STAGE(PG8_SB(1, 1), b3 + hstep, voffB);
;             PG8_WAIT_V(6); PG8_BAR; PG8_MMA(1, 1, At, B1); PG8_BAR;
	s_add_u32 s68, s4, 0x40000
	s_addc_u32 s69, s5, 0
	s_add_i32 s70, s58, s44
	s_mov_b32 m0, s70
	s_nop 0
	global_load_lds_dwordx4 v130, s[68:69]
	s_add_i32 m0, s70, 0x2000
	s_nop 0
	global_load_lds_dwordx4 v134, s[68:69]
	s_waitcnt vmcnt(10)
	s_barrier
	s_setprio 1
	v_mfma_f32_16x16x32_bf16 v[52:55], v[210:213], v[162:165], 0
	v_mfma_f32_16x16x32_bf16 v[48:51], v[218:221], v[162:165], 0
	v_mfma_f32_16x16x32_bf16 v[36:39], v[210:213], v[182:185], 0
	v_mfma_f32_16x16x32_bf16 v[32:35], v[218:221], v[182:185], 0
	v_mfma_f32_16x16x32_bf16 v[20:23], v[210:213], v[190:193], 0
	v_mfma_f32_16x16x32_bf16 v[16:19], v[218:221], v[190:193], 0
	v_mfma_f32_16x16x32_bf16 v[4:7], v[210:213], v[202:205], 0
	v_mfma_f32_16x16x32_bf16 v[0:3], v[218:221], v[202:205], 0
	v_mfma_f32_16x16x32_bf16 v[52:55], v[214:217], v[178:181], v[52:55]
	v_mfma_f32_16x16x32_bf16 v[48:51], v[222:225], v[178:181], v[48:51]
	v_mfma_f32_16x16x32_bf16 v[36:39], v[214:217], v[186:189], v[36:39]
	v_mfma_f32_16x16x32_bf16 v[32:35], v[222:225], v[186:189], v[32:35]
	v_mfma_f32_16x16x32_bf16 v[20:23], v[214:217], v[194:197], v[20:23]
	v_mfma_f32_16x16x32_bf16 v[16:19], v[222:225], v[194:197], v[16:19]
	v_mfma_f32_16x16x32_bf16 v[4:7], v[214:217], v[206:209], v[4:7]
	v_mfma_f32_16x16x32_bf16 v[0:3], v[222:225], v[206:209], v[0:3]
	s_setprio 0
	s_add_i32 s68, 0, 0x18000
	v_add_u32_e32 v136, s68, v170
	s_barrier
	ds_read_b128 v[146:149], v136
	ds_read_b128 v[150:153], v136 offset:1024
	ds_read_b128 v[154:157], v136 offset:2048
	ds_read_b128 v[158:161], v136 offset:3072
	s_add_u32 s6, s6, 0x40000
	s_addc_u32 s7, s7, 0
	s_mov_b32 m0, s47
	ds_read_b128 v[162:165], v172 offset:32768
	ds_read_b128 v[178:181], v172 offset:33792
	ds_read_b128 v[182:185], v172 offset:34816
	ds_read_b128 v[186:189], v172 offset:35840
	ds_read_b128 v[190:193], v172 offset:36864
	ds_read_b128 v[194:197], v172 offset:37888
	ds_read_b128 v[202:205], v172 offset:38912
	ds_read_b128 v[206:209], v172 offset:39936
	global_load_lds_dwordx4 v128, s[6:7]
	s_mov_b32 m0, s48
	s_nop 0
	global_load_lds_dwordx4 v132, s[6:7]
	s_waitcnt lgkmcnt(8)
	s_waitcnt vmcnt(10)
	s_barrier
	s_waitcnt lgkmcnt(0)
	s_setprio 1
	s_waitcnt lgkmcnt(0)
	v_mfma_f32_16x16x32_bf16 v[124:127], v[146:149], v[162:165], v[124:127]
	v_mfma_f32_16x16x32_bf16 v[120:123], v[154:157], v[162:165], v[120:123]
	v_mfma_f32_16x16x32_bf16 v[108:111], v[146:149], v[182:185], v[108:111]
	v_mfma_f32_16x16x32_bf16 v[104:107], v[154:157], v[182:185], v[104:107]
	v_mfma_f32_16x16x32_bf16 v[92:95], v[146:149], v[190:193], v[92:95]
	v_mfma_f32_16x16x32_bf16 v[88:91], v[154:157], v[190:193], v[88:91]
	v_mfma_f32_16x16x32_bf16 v[76:79], v[146:149], v[202:205], v[76:79]
	v_mfma_f32_16x16x32_bf16 v[72:75], v[154:157], v[202:205], v[72:75]
	v_mfma_f32_16x16x32_bf16 v[124:127], v[150:153], v[178:181], v[124:127]
	v_mfma_f32_16x16x32_bf16 v[120:123], v[158:161], v[178:181], v[120:123]
	v_mfma_f32_16x16x32_bf16 v[108:111], v[150:153], v[186:189], v[108:111]
	v_mfma_f32_16x16x32_bf16 v[104:107], v[158:161], v[186:189], v[104:107]
	v_mfma_f32_16x16x32_bf16 v[92:95], v[150:153], v[194:197], v[92:95]
	v_mfma_f32_16x16x32_bf16 v[88:91], v[158:161], v[194:197], v[88:91]
	v_mfma_f32_16x16x32_bf16 v[76:79], v[150:153], v[206:209], v[76:79]
	v_mfma_f32_16x16x32_bf16 v[72:75], v[158:161], v[206:209], v[72:75]
	s_setprio 0
	s_barrier
	s_add_i32 s6, 0, 0x1c000
	s_add_i32 s7, s68, s44
	v_add_u32_e32 v136, s6, v170
	s_add_u32 s20, s4, 0x80
	s_addc_u32 s21, s5, 0
	s_mov_b32 m0, s7
	ds_read_b128 v[210:213], v136
	ds_read_b128 v[214:217], v136 offset:1024
	ds_read_b128 v[218:221], v136 offset:2048
	ds_read_b128 v[222:225], v136 offset:3072
	global_load_lds_dwordx4 v130, s[20:21]
	s_add_i32 m0, s7, 0x2000
	s_nop 0
	global_load_lds_dwordx4 v134, s[20:21]
	s_waitcnt vmcnt(10)
	s_barrier
	s_waitcnt lgkmcnt(0)
	s_setprio 1
	s_waitcnt lgkmcnt(0)
	v_mfma_f32_16x16x32_bf16 v[116:119], v[210:213], v[162:165], v[116:119]
	v_mfma_f32_16x16x32_bf16 v[112:115], v[218:221], v[162:165], v[112:115]
	v_mfma_f32_16x16x32_bf16 v[100:103], v[210:213], v[182:185], v[100:103]
	v_mfma_f32_16x16x32_bf16 v[96:99], v[218:221], v[182:185], v[96:99]
	v_mfma_f32_16x16x32_bf16 v[84:87], v[210:213], v[190:193], v[84:87]
	v_mfma_f32_16x16x32_bf16 v[80:83], v[218:221], v[190:193], v[80:83]
	v_mfma_f32_16x16x32_bf16 v[68:71], v[210:213], v[202:205], v[68:71]
	v_mfma_f32_16x16x32_bf16 v[64:67], v[218:221], v[202:205], v[64:67]
	v_mfma_f32_16x16x32_bf16 v[116:119], v[214:217], v[178:181], v[116:119]
	v_mfma_f32_16x16x32_bf16 v[112:115], v[222:225], v[178:181], v[112:115]
	v_mfma_f32_16x16x32_bf16 v[100:103], v[214:217], v[186:189], v[100:103]
	v_mfma_f32_16x16x32_bf16 v[96:99], v[222:225], v[186:189], v[96:99]
	v_mfma_f32_16x16x32_bf16 v[84:87], v[214:217], v[194:197], v[84:87]
	v_mfma_f32_16x16x32_bf16 v[80:83], v[222:225], v[194:197], v[80:83]
	v_mfma_f32_16x16x32_bf16 v[68:71], v[214:217], v[206:209], v[68:71]
	v_mfma_f32_16x16x32_bf16 v[64:67], v[222:225], v[206:209], v[64:67]
	s_setprio 0
	s_mov_b32 m0, s54
	s_mov_b64 s[20:21], 0x80
	v_lshl_add_u64 v[166:167], v[226:227], 0, s[20:21]
	s_barrier
	ds_read_b128 v[162:165], v172 offset:49152
	ds_read_b128 v[178:181], v172 offset:50176
	ds_read_b128 v[182:185], v172 offset:51200
	ds_read_b128 v[186:189], v172 offset:52224
	ds_read_b128 v[190:193], v172 offset:53248
	ds_read_b128 v[194:197], v172 offset:54272
	ds_read_b128 v[202:205], v172 offset:55296
	ds_read_b128 v[206:209], v172 offset:56320
	global_load_lds_dwordx4 v[166:167], off
	v_lshl_add_u64 v[166:167], v[228:229], 0, s[20:21]
	s_mov_b32 m0, s55
	s_nop 0
	global_load_lds_dwordx4 v[166:167], off
	s_barrier
; #define PG8_STAGE(bufoff, gbase, voff) do { _Pragma("unroll") for (int _i = 0; _i < 2; ++_i) \
;         __builtin_amdgcn_global_load_lds((const unsigned*)((const char*)(gbase) + (voff)[_i]), (LAS unsigned*)(lds + (bufoff) + ldsw + _i * 8192), 16, 0, 0); } while (0)
; #define PG8_LDA(dst, b, h) do { _Pragma("unroll") for (int m = 0; m < 4; ++m) _Pragma("unroll") for (int k = 0; k < 2; ++k) dst[m][k] = *(const LAS bf16x8*)(lds + PG8_SA(b, h) + aoff + m * 2048 + k * 1024); } while (0)
; #define PG8_LDB(dst, b, h) do { _Pragma("unroll") for (int n = 0; n < 2; ++n) _Pragma("unroll") for (int k = 0; k < 2; ++k) dst[n][k] = *(const LAS bf16x8*)(lds + PG8_SB(b, h) + boff + n * 2048 + k * 1024); } while (0)
; #define PG8_WAIT_V(n) asm volatile("s_waitcnt vmcnt(" #n ")" ::: "memory")
; #define PG8_WAIT_L(n) asm volatile("s_waitcnt lgkmcnt(" #n ")" ::: "memory")
; #define PG8_BAR __builtin_amdgcn_s_barrier()
; #define PG8_SCHED __builtin_amdgcn_sched_barrier(0)
; template <class Epi, class Sched>
; __device__ __forceinline__ void gemm_phase(LAS unsigned char* lds, const Gemm g, const Sched& S, const Epi& E) {
;     ...
;             PG8_LDB(B0, 0, 0); PG8_SCHED; PG8_LDA(At, 0, 0); PG8_STAGE(PG8_SA(1, 1), a1 + hstep, voffA);
;             PG8_WAIT_L(8); PG8_BAR; PG8_WAIT_L(0); PG8_MMA(0, 0, At, B0); PG8_BAR; PG8_SCHED;
;             PG8_LDB(B1, 0, 1); PG8_STAGE(PG8_SB(0, 0), b2, voffB);
;             PG8_BAR; PG8_WAIT_L(0); PG8_MMA(0, 1, At, B1); PG8_BAR;
;             PG8_LDA(At, 0, 1); PG8_STAGE(PG8_SA(0, 0), a2, voffA);
;             PG8_BAR; PG8_WAIT_L(0); PG8_MMA(1, 0, At, B0); PG8_BAR; PG8_SCHED;
;             PG8_STAGE(PG8_SB(0, 1), b2 + hstep, voffB);
;             PG8_WAIT_V(6); PG8_BAR; PG8_MMA(1, 1, At, B1); PG8_BAR;
;             PG8_LDB(B0, 1, 0); PG8_SCHED; PG8_LDA(At, 1, 0); PG8_STAGE(PG8_SA(0, 1), a2 + hstep, voffA);
;             PG8_WAIT_L(8); PG8_BAR; PG8_WAIT_L(0); PG8_MMA(0, 0, At, B0); PG8_BAR; PG8_SCHED;
;             PG8_LDB(B1, 1, 1); PG8_STAGE(PG8_SB(1, 0), b3, voffB);
;             PG8_BAR; PG8_WAIT_L(0); PG8_MMA(0, 1, At, B1); PG8_BAR;
;             PG8_LDA(At, 1, 1); PG8_STAGE(PG8_SA(1, 0), a3, voffA);
;             PG8_BAR; PG8_WAIT_L(0); PG8_MMA(1, 0, At, B0); PG8_BAR; PG8_SCHED;
;             PG8_STAGE(PG8_SB(1, 1), b3 + hstep, voffB);
;             PG8_WAIT_V(6); PG8_BAR; PG8_MMA(1, 1, At, B1); PG8_BAR;
	s_waitcnt lgkmcnt(0)
	s_setprio 1
	s_waitcnt lgkmcnt(0)
	v_mfma_f32_16x16x32_bf16 v[60:63], v[146:149], v[162:165], v[60:63]
	v_mfma_f32_16x16x32_bf16 v[56:59], v[154:157], v[162:165], v[56:59]
	v_mfma_f32_16x16x32_bf16 v[44:47], v[146:149], v[182:185], v[44:47]
	v_mfma_f32_16x16x32_bf16 v[40:43], v[154:157], v[182:185], v[40:43]
	v_mfma_f32_16x16x32_bf16 v[28:31], v[146:149], v[190:193], v[28:31]
	v_mfma_f32_16x16x32_bf16 v[24:27], v[154:157], v[190:193], v[24:27]
	v_mfma_f32_16x16x32_bf16 v[12:15], v[146:149], v[202:205], v[12:15]
	v_mfma_f32_16x16x32_bf16 v[8:11], v[154:157], v[202:205], v[8:11]
	v_mfma_f32_16x16x32_bf16 v[60:63], v[150:153], v[178:181], v[60:63]
	v_mfma_f32_16x16x32_bf16 v[56:59], v[158:161], v[178:181], v[56:59]
	v_mfma_f32_16x16x32_bf16 v[44:47], v[150:153], v[186:189], v[44:47]
	v_mfma_f32_16x16x32_bf16 v[40:43], v[158:161], v[186:189], v[40:43]
	v_mfma_f32_16x16x32_bf16 v[28:31], v[150:153], v[194:197], v[28:31]
	v_mfma_f32_16x16x32_bf16 v[24:27], v[158:161], v[194:197], v[24:27]
	v_mfma_f32_16x16x32_bf16 v[12:15], v[150:153], v[206:209], v[12:15]
	v_mfma_f32_16x16x32_bf16 v[8:11], v[158:161], v[206:209], v[8:11]
	s_setprio 0
	s_barrier
	s_add_u32 s4, s4, 0x40080
	s_addc_u32 s5, s5, 0
	s_add_i32 s6, s6, s44
	s_mov_b32 m0, s6
	s_nop 0
	global_load_lds_dwordx4 v130, s[4:5]
	s_add_i32 m0, s6, 0x2000
	s_nop 0
	global_load_lds_dwordx4 v134, s[4:5]
	s_waitcnt vmcnt(10)
	s_barrier
	s_setprio 1
	v_mfma_f32_16x16x32_bf16 v[52:55], v[210:213], v[162:165], v[52:55]
	v_mfma_f32_16x16x32_bf16 v[48:51], v[218:221], v[162:165], v[48:51]
	v_mfma_f32_16x16x32_bf16 v[36:39], v[210:213], v[182:185], v[36:39]
	v_mfma_f32_16x16x32_bf16 v[32:35], v[218:221], v[182:185], v[32:35]
	v_mfma_f32_16x16x32_bf16 v[20:23], v[210:213], v[190:193], v[20:23]
	v_mfma_f32_16x16x32_bf16 v[16:19], v[218:221], v[190:193], v[16:19]
	v_mfma_f32_16x16x32_bf16 v[4:7], v[210:213], v[202:205], v[4:7]
	v_mfma_f32_16x16x32_bf16 v[0:3], v[218:221], v[202:205], v[0:3]
	v_mfma_f32_16x16x32_bf16 v[52:55], v[214:217], v[178:181], v[52:55]
	v_mfma_f32_16x16x32_bf16 v[48:51], v[222:225], v[178:181], v[48:51]
	v_mfma_f32_16x16x32_bf16 v[36:39], v[214:217], v[186:189], v[36:39]
	v_mfma_f32_16x16x32_bf16 v[32:35], v[222:225], v[186:189], v[32:35]
	v_mfma_f32_16x16x32_bf16 v[20:23], v[214:217], v[194:197], v[20:23]
	v_mfma_f32_16x16x32_bf16 v[16:19], v[222:225], v[194:197], v[16:19]
	v_mfma_f32_16x16x32_bf16 v[4:7], v[214:217], v[206:209], v[4:7]
	v_mfma_f32_16x16x32_bf16 v[0:3], v[222:225], v[206:209], v[0:3]
	s_setprio 0
	s_add_i32 s67, s67, 2
	s_add_u32 s0, s0, 0x100
	s_addc_u32 s1, s1, 0
	s_add_u32 s65, s65, 0x100
	s_addc_u32 s66, s66, 0
	s_cmp_gt_u32 s67, 13
	s_barrier
.LBB0_613:
	ds_read_b128 v[146:149], v171
	ds_read_b128 v[150:153], v171 offset:1024
	ds_read_b128 v[154:157], v171 offset:2048
	ds_read_b128 v[158:161], v171 offset:3072
	s_add_u32 s4, s0, 0xfffc0080
	s_addc_u32 s5, s1, -1
	s_cmp_eq_u32 s67, 12
	s_cselect_b32 s7, s8, s5
	s_cselect_b32 s6, s9, s4
	s_cselect_b32 s5, s31, s66
	s_cselect_b32 s4, s35, s65
	s_add_i32 m0, s45, 0xc000
	ds_read_b128 v[162:165], v172
	ds_read_b128 v[178:181], v172 offset:1024
	ds_read_b128 v[182:185], v172 offset:2048
	ds_read_b128 v[186:189], v172 offset:3072
	ds_read_b128 v[190:193], v172 offset:4096
	ds_read_b128 v[194:197], v172 offset:5120
	ds_read_b128 v[202:205], v172 offset:6144
	ds_read_b128 v[206:209], v172 offset:7168
	global_load_lds_dwordx4 v138, s[0:1]
	s_add_i32 m0, s45, 0xe000
	s_nop 0
	global_load_lds_dwordx4 v140, s[0:1]
	s_waitcnt lgkmcnt(8)
	s_waitcnt vmcnt(10)
	s_barrier
	s_waitcnt lgkmcnt(0)
	s_setprio 1
	s_waitcnt lgkmcnt(0)
	v_mfma_f32_16x16x32_bf16 v[124:127], v[146:149], v[162:165], v[124:127]
	v_mfma_f32_16x16x32_bf16 v[120:123], v[154:157], v[162:165], v[120:123]
	v_mfma_f32_16x16x32_bf16 v[108:111], v[146:149], v[182:185], v[108:111]
	v_mfma_f32_16x16x32_bf16 v[104:107], v[154:157], v[182:185], v[104:107]
	v_mfma_f32_16x16x32_bf16 v[92:95], v[146:149], v[190:193], v[92:95]
	v_mfma_f32_16x16x32_bf16 v[88:91], v[154:157], v[190:193], v[88:91]
	v_mfma_f32_16x16x32_bf16 v[76:79], v[146:149], v[202:205], v[76:79]
	v_mfma_f32_16x16x32_bf16 v[72:75], v[154:157], v[202:205], v[72:75]
	v_mfma_f32_16x16x32_bf16 v[124:127], v[150:153], v[178:181], v[124:127]
	v_mfma_f32_16x16x32_bf16 v[120:123], v[158:161], v[178:181], v[120:123]
	v_mfma_f32_16x16x32_bf16 v[108:111], v[150:153], v[186:189], v[108:111]
	v_mfma_f32_16x16x32_bf16 v[104:107], v[158:161], v[186:189], v[104:107]
	v_mfma_f32_16x16x32_bf16 v[92:95], v[150:153], v[194:197], v[92:95]
	v_mfma_f32_16x16x32_bf16 v[88:91], v[158:161], v[194:197], v[88:91]
	v_mfma_f32_16x16x32_bf16 v[76:79], v[150:153], v[206:209], v[76:79]
	v_mfma_f32_16x16x32_bf16 v[72:75], v[158:161], v[206:209], v[72:75]
	s_setprio 0
	s_barrier
	s_add_i32 s68, s57, s44
	s_mov_b32 m0, s68
	ds_read_b128 v[210:213], v173
	ds_read_b128 v[214:217], v173 offset:1024
	ds_read_b128 v[218:221], v173 offset:2048
	ds_read_b128 v[222:225], v173 offset:3072
	global_load_lds_dwordx4 v130, s[4:5]
	s_add_i32 m0, s68, 0x2000
	s_nop 0
	global_load_lds_dwordx4 v134, s[4:5]
	s_waitcnt vmcnt(10)
	s_barrier
; #define PG8_STAGE(bufoff, gbase, voff) do { _Pragma("unroll") for (int _i = 0; _i < 2; ++_i) \
;         __builtin_amdgcn_global_load_lds((const unsigned*)((const char*)(gbase) + (voff)[_i]), (LAS unsigned*)(lds + (bufoff) + ldsw + _i * 8192), 16, 0, 0); } while (0)
; #define PG8_LDA(dst, b, h) do { _Pragma("unroll") for (int m = 0; m < 4; ++m) _Pragma("unroll") for (int k = 0; k < 2; ++k) dst[m][k] = *(const LAS bf16x8*)(lds + PG8_SA(b, h) + aoff + m * 2048 + k * 1024); } while (0)
; #define PG8_LDB(dst, b, h) do { _Pragma("unroll") for (int n = 0; n < 2; ++n) _Pragma("unroll") for (int k = 0; k < 2; ++k) dst[n][k] = *(const LAS bf16x8*)(lds + PG8_SB(b, h) + boff + n * 2048 + k * 1024); } while (0)
; #define PG8_MMA(ai, bj, At, Bt) do { __builtin_amdgcn_s_setprio(1); _Pragma("unroll") for (int m = 0; m < 4; ++m) _Pragma("unroll") for (int n = 0; n < 2; ++n) _Pragma("unroll") for (int k = 0; k < 2; ++k) \
;         acc[ai][bj][m][n] = __builtin_amdgcn_mfma_f32_16x16x32_bf16(Bt[n][k], At[m][k], acc[ai][bj][m][n], 0, 0, 0); __builtin_amdgcn_s_setprio(0); } while (0)
; #define PG8_WAIT_V(n) asm volatile("s_waitcnt vmcnt(" #n ")" ::: "memory")
; #define PG8_WAIT_L(n) asm volatile("s_waitcnt lgkmcnt(" #n ")" ::: "memory")
; #define PG8_BAR __builtin_amdgcn_s_barrier()
; #define PG8_SCHED __builtin_amdgcn_sched_barrier(0)
; template <class Epi, class Sched>
; __device__ __forceinline__ void gemm_phase(LAS unsigned char* lds, const Gemm g, const Sched& S, const Epi& E) {
;     ...
;             PG8_LDB(B1, 0, 1); PG8_STAGE(PG8_SB(0, 0), b2, voffB);
;             PG8_BAR; PG8_WAIT_L(0); PG8_MMA(0, 1, At, B1); PG8_BAR;
;             PG8_LDA(At, 0, 1); PG8_STAGE(PG8_SA(0, 0), a2, voffA);
;             PG8_BAR; PG8_WAIT_L(0); PG8_MMA(1, 0, At, B0); PG8_BAR; PG8_SCHED;
;             PG8_STAGE(PG8_SB(0, 1), b2 + hstep, voffB);
;             PG8_WAIT_V(6); PG8_BAR; PG8_MMA(1, 1, At, B1); PG8_BAR;
;             PG8_LDB(B0, 1, 0); PG8_SCHED; PG8_LDA(At, 1, 0); PG8_STAGE(PG8_SA(0, 1), a2 + hstep, voffA);
;             PG8_WAIT_L(8); PG8_BAR; PG8_WAIT_L(0); PG8_MMA(0, 0, At, B0); PG8_BAR; PG8_SCHED;
	s_waitcnt lgkmcnt(0)
	s_setprio 1
	s_waitcnt lgkmcnt(0)
	v_mfma_f32_16x16x32_bf16 v[116:119], v[210:213], v[162:165], v[116:119]
	v_mfma_f32_16x16x32_bf16 v[112:115], v[218:221], v[162:165], v[112:115]
	v_mfma_f32_16x16x32_bf16 v[100:103], v[210:213], v[182:185], v[100:103]
	v_mfma_f32_16x16x32_bf16 v[96:99], v[218:221], v[182:185], v[96:99]
	v_mfma_f32_16x16x32_bf16 v[84:87], v[210:213], v[190:193], v[84:87]
	v_mfma_f32_16x16x32_bf16 v[80:83], v[218:221], v[190:193], v[80:83]
	v_mfma_f32_16x16x32_bf16 v[68:71], v[210:213], v[202:205], v[68:71]
	v_mfma_f32_16x16x32_bf16 v[64:67], v[218:221], v[202:205], v[64:67]
	v_mfma_f32_16x16x32_bf16 v[116:119], v[214:217], v[178:181], v[116:119]
	v_mfma_f32_16x16x32_bf16 v[112:115], v[222:225], v[178:181], v[112:115]
	v_mfma_f32_16x16x32_bf16 v[100:103], v[214:217], v[186:189], v[100:103]
	v_mfma_f32_16x16x32_bf16 v[96:99], v[222:225], v[186:189], v[96:99]
	v_mfma_f32_16x16x32_bf16 v[84:87], v[214:217], v[194:197], v[84:87]
	v_mfma_f32_16x16x32_bf16 v[80:83], v[222:225], v[194:197], v[80:83]
	v_mfma_f32_16x16x32_bf16 v[68:71], v[214:217], v[206:209], v[68:71]
	v_mfma_f32_16x16x32_bf16 v[64:67], v[222:225], v[206:209], v[64:67]
	s_setprio 0
	s_mov_b32 m0, s45
	v_lshl_add_u64 v[226:227], s[6:7], 0, v[128:129]
	s_barrier
	ds_read_b128 v[162:165], v172 offset:16384
	ds_read_b128 v[178:181], v172 offset:17408
	ds_read_b128 v[182:185], v172 offset:18432
	ds_read_b128 v[186:189], v172 offset:19456
	ds_read_b128 v[190:193], v172 offset:20480
	ds_read_b128 v[194:197], v172 offset:21504
	ds_read_b128 v[202:205], v172 offset:22528
	ds_read_b128 v[206:209], v172 offset:23552
	global_load_lds_dwordx4 v128, s[6:7]
	v_lshl_add_u64 v[228:229], s[6:7], 0, v[132:133]
	s_mov_b32 m0, s46
	s_nop 0
	global_load_lds_dwordx4 v132, s[6:7]
	s_barrier
	s_waitcnt lgkmcnt(0)
	s_setprio 1
	s_waitcnt lgkmcnt(0)
	v_mfma_f32_16x16x32_bf16 v[60:63], v[146:149], v[162:165], v[60:63]
	v_mfma_f32_16x16x32_bf16 v[56:59], v[154:157], v[162:165], v[56:59]
	v_mfma_f32_16x16x32_bf16 v[44:47], v[146:149], v[182:185], v[44:47]
	v_mfma_f32_16x16x32_bf16 v[40:43], v[154:157], v[182:185], v[40:43]
	v_mfma_f32_16x16x32_bf16 v[28:31], v[146:149], v[190:193], v[28:31]
	v_mfma_f32_16x16x32_bf16 v[24:27], v[154:157], v[190:193], v[24:27]
	v_mfma_f32_16x16x32_bf16 v[12:15], v[146:149], v[202:205], v[12:15]
	v_mfma_f32_16x16x32_bf16 v[8:11], v[154:157], v[202:205], v[8:11]
	v_mfma_f32_16x16x32_bf16 v[60:63], v[150:153], v[178:181], v[60:63]
	v_mfma_f32_16x16x32_bf16 v[56:59], v[158:161], v[178:181], v[56:59]
	v_mfma_f32_16x16x32_bf16 v[44:47], v[150:153], v[186:189], v[44:47]
	v_mfma_f32_16x16x32_bf16 v[40:43], v[158:161], v[186:189], v[40:43]
	v_mfma_f32_16x16x32_bf16 v[28:31], v[150:153], v[194:197], v[28:31]
	v_mfma_f32_16x16x32_bf16 v[24:27], v[158:161], v[194:197], v[24:27]
	v_mfma_f32_16x16x32_bf16 v[12:15], v[150:153], v[206:209], v[12:15]
	v_mfma_f32_16x16x32_bf16 v[8:11], v[158:161], v[206:209], v[8:11]
	s_setprio 0
	s_barrier
	s_add_u32 s68, s4, 0x40000
	s_addc_u32 s69, s5, 0
	s_add_i32 s70, s58, s44
	s_mov_b32 m0, s70
	s_nop 0
	global_load_lds_dwordx4 v130, s[68:69]
	s_add_i32 m0, s70, 0x2000
	s_nop 0
	global_load_lds_dwordx4 v134, s[68:69]
	s_waitcnt vmcnt(10)
	s_barrier
	s_setprio 1
	v_mfma_f32_16x16x32_bf16 v[52:55], v[210:213], v[162:165], v[52:55]
	v_mfma_f32_16x16x32_bf16 v[48:51], v[218:221], v[162:165], v[48:51]
	v_mfma_f32_16x16x32_bf16 v[36:39], v[210:213], v[182:185], v[36:39]
	v_mfma_f32_16x16x32_bf16 v[32:35], v[218:221], v[182:185], v[32:35]
	v_mfma_f32_16x16x32_bf16 v[20:23], v[210:213], v[190:193], v[20:23]
	v_mfma_f32_16x16x32_bf16 v[16:19], v[218:221], v[190:193], v[16:19]
	v_mfma_f32_16x16x32_bf16 v[4:7], v[210:213], v[202:205], v[4:7]
	v_mfma_f32_16x16x32_bf16 v[0:3], v[218:221], v[202:205], v[0:3]
	v_mfma_f32_16x16x32_bf16 v[52:55], v[214:217], v[178:181], v[52:55]
	v_mfma_f32_16x16x32_bf16 v[48:51], v[222:225], v[178:181], v[48:51]
	v_mfma_f32_16x16x32_bf16 v[36:39], v[214:217], v[186:189], v[36:39]
	v_mfma_f32_16x16x32_bf16 v[32:35], v[222:225], v[186:189], v[32:35]
	v_mfma_f32_16x16x32_bf16 v[20:23], v[214:217], v[194:197], v[20:23]
	v_mfma_f32_16x16x32_bf16 v[16:19], v[222:225], v[194:197], v[16:19]
	v_mfma_f32_16x16x32_bf16 v[4:7], v[214:217], v[206:209], v[4:7]
	v_mfma_f32_16x16x32_bf16 v[0:3], v[222:225], v[206:209], v[0:3]
	s_setprio 0
	s_add_i32 s68, 0, 0x18000
	v_add_u32_e32 v136, s68, v170
	s_barrier
	ds_read_b128 v[146:149], v136
	ds_read_b128 v[150:153], v136 offset:1024
	ds_read_b128 v[154:157], v136 offset:2048
	ds_read_b128 v[158:161], v136 offset:3072
	s_add_u32 s6, s6, 0x40000
	s_addc_u32 s7, s7, 0
	s_mov_b32 m0, s47
	ds_read_b128 v[162:165], v172 offset:32768
	ds_read_b128 v[178:181], v172 offset:33792
	ds_read_b128 v[182:185], v172 offset:34816
	ds_read_b128 v[186:189], v172 offset:35840
	ds_read_b128 v[190:193], v172 offset:36864
	ds_read_b128 v[194:197], v172 offset:37888
	ds_read_b128 v[202:205], v172 offset:38912
	ds_read_b128 v[206:209], v172 offset:39936
	global_load_lds_dwordx4 v128, s[6:7]
	s_mov_b32 m0, s48
	s_nop 0
	global_load_lds_dwordx4 v132, s[6:7]
	s_waitcnt lgkmcnt(8)
	s_waitcnt vmcnt(10)
	s_barrier
; #define PG8_STAGE(bufoff, gbase, voff) do { _Pragma("unroll") for (int _i = 0; _i < 2; ++_i) \
;         __builtin_amdgcn_global_load_lds((const unsigned*)((const char*)(gbase) + (voff)[_i]), (LAS unsigned*)(lds + (bufoff) + ldsw + _i * 8192), 16, 0, 0); } while (0)
; #define PG8_LDA(dst, b, h) do { _Pragma("unroll") for (int m = 0; m < 4; ++m) _Pragma("unroll") for (int k = 0; k < 2; ++k) dst[m][k] = *(const LAS bf16x8*)(lds + PG8_SA(b, h) + aoff + m * 2048 + k * 1024); } while (0)
; #define PG8_LDB(dst, b, h) do { _Pragma("unroll") for (int n = 0; n < 2; ++n) _Pragma("unroll") for (int k = 0; k < 2; ++k) dst[n][k] = *(const LAS bf16x8*)(lds + PG8_SB(b, h) + boff + n * 2048 + k * 1024); } while (0)
; #define PG8_MMA(ai, bj, At, Bt) do { __builtin_amdgcn_s_setprio(1); _Pragma("unroll") for (int m = 0; m < 4; ++m) _Pragma("unroll") for (int n = 0; n < 2; ++n) _Pragma("unroll") for (int k = 0; k < 2; ++k) \
;         acc[ai][bj][m][n] = __builtin_amdgcn_mfma_f32_16x16x32_bf16(Bt[n][k], At[m][k], acc[ai][bj][m][n], 0, 0, 0); __builtin_amdgcn_s_setprio(0); } while (0)
; #define PG8_WAIT_V(n) asm volatile("s_waitcnt vmcnt(" #n ")" ::: "memory")
; #define PG8_WAIT_L(n) asm volatile("s_waitcnt lgkmcnt(" #n ")" ::: "memory")
; #define PG8_BAR __builtin_amdgcn_s_barrier()
; #define PG8_SCHED __builtin_amdgcn_sched_barrier(0)
; template <class Epi, class Sched>
; __device__ __forceinline__ void gemm_phase(LAS unsigned char* lds, const Gemm g, const Sched& S, const Epi& E) {
;     ...
;             PG8_WAIT_L(8); PG8_BAR; PG8_WAIT_L(0); PG8_MMA(0, 0, At, B0); PG8_BAR; PG8_SCHED;
;             PG8_LDB(B1, 1, 1); PG8_STAGE(PG8_SB(1, 0), b3, voffB);
;             PG8_BAR; PG8_WAIT_L(0); PG8_MMA(0, 1, At, B1); PG8_BAR;
;             PG8_LDA(At, 1, 1); PG8_STAGE(PG8_SA(1, 0), a3, voffA);
;             PG8_BAR; PG8_WAIT_L(0); PG8_MMA(1, 0, At, B0); PG8_BAR; PG8_SCHED;
;             PG8_STAGE(PG8_SB(1, 1), b3 + hstep, voffB);
;             PG8_WAIT_V(6); PG8_BAR; PG8_MMA(1, 1, At, B1); PG8_BAR;
	s_waitcnt lgkmcnt(0)
	s_setprio 1
	s_waitcnt lgkmcnt(0)
	v_mfma_f32_16x16x32_bf16 v[124:127], v[146:149], v[162:165], v[124:127]
	v_mfma_f32_16x16x32_bf16 v[120:123], v[154:157], v[162:165], v[120:123]
	v_mfma_f32_16x16x32_bf16 v[108:111], v[146:149], v[182:185], v[108:111]
	v_mfma_f32_16x16x32_bf16 v[104:107], v[154:157], v[182:185], v[104:107]
	v_mfma_f32_16x16x32_bf16 v[92:95], v[146:149], v[190:193], v[92:95]
	v_mfma_f32_16x16x32_bf16 v[88:91], v[154:157], v[190:193], v[88:91]
	v_mfma_f32_16x16x32_bf16 v[76:79], v[146:149], v[202:205], v[76:79]
	v_mfma_f32_16x16x32_bf16 v[72:75], v[154:157], v[202:205], v[72:75]
	v_mfma_f32_16x16x32_bf16 v[124:127], v[150:153], v[178:181], v[124:127]
	v_mfma_f32_16x16x32_bf16 v[120:123], v[158:161], v[178:181], v[120:123]
	v_mfma_f32_16x16x32_bf16 v[108:111], v[150:153], v[186:189], v[108:111]
	v_mfma_f32_16x16x32_bf16 v[104:107], v[158:161], v[186:189], v[104:107]
	v_mfma_f32_16x16x32_bf16 v[92:95], v[150:153], v[194:197], v[92:95]
	v_mfma_f32_16x16x32_bf16 v[88:91], v[158:161], v[194:197], v[88:91]
	v_mfma_f32_16x16x32_bf16 v[76:79], v[150:153], v[206:209], v[76:79]
	v_mfma_f32_16x16x32_bf16 v[72:75], v[158:161], v[206:209], v[72:75]
	s_setprio 0
	s_barrier
	s_add_i32 s6, 0, 0x1c000
	s_add_i32 s7, s68, s44
	v_add_u32_e32 v136, s6, v170
	s_add_u32 s20, s4, 0x80
	s_addc_u32 s21, s5, 0
	s_mov_b32 m0, s7
	ds_read_b128 v[210:213], v136
	ds_read_b128 v[214:217], v136 offset:1024
	ds_read_b128 v[218:221], v136 offset:2048
	ds_read_b128 v[222:225], v136 offset:3072
	global_load_lds_dwordx4 v130, s[20:21]
	s_add_i32 m0, s7, 0x2000
	s_nop 0
	global_load_lds_dwordx4 v134, s[20:21]
	s_waitcnt vmcnt(10)
	s_barrier
	s_waitcnt lgkmcnt(0)
	s_setprio 1
	s_waitcnt lgkmcnt(0)
	v_mfma_f32_16x16x32_bf16 v[116:119], v[210:213], v[162:165], v[116:119]
	v_mfma_f32_16x16x32_bf16 v[112:115], v[218:221], v[162:165], v[112:115]
	v_mfma_f32_16x16x32_bf16 v[100:103], v[210:213], v[182:185], v[100:103]
	v_mfma_f32_16x16x32_bf16 v[96:99], v[218:221], v[182:185], v[96:99]
	v_mfma_f32_16x16x32_bf16 v[84:87], v[210:213], v[190:193], v[84:87]
	v_mfma_f32_16x16x32_bf16 v[80:83], v[218:221], v[190:193], v[80:83]
	v_mfma_f32_16x16x32_bf16 v[68:71], v[210:213], v[202:205], v[68:71]
	v_mfma_f32_16x16x32_bf16 v[64:67], v[218:221], v[202:205], v[64:67]
	v_mfma_f32_16x16x32_bf16 v[116:119], v[214:217], v[178:181], v[116:119]
	v_mfma_f32_16x16x32_bf16 v[112:115], v[222:225], v[178:181], v[112:115]
	v_mfma_f32_16x16x32_bf16 v[100:103], v[214:217], v[186:189], v[100:103]
	v_mfma_f32_16x16x32_bf16 v[96:99], v[222:225], v[186:189], v[96:99]
	v_mfma_f32_16x16x32_bf16 v[84:87], v[214:217], v[194:197], v[84:87]
	v_mfma_f32_16x16x32_bf16 v[80:83], v[222:225], v[194:197], v[80:83]
	v_mfma_f32_16x16x32_bf16 v[68:71], v[214:217], v[206:209], v[68:71]
	v_mfma_f32_16x16x32_bf16 v[64:67], v[222:225], v[206:209], v[64:67]
	s_setprio 0
	s_mov_b32 m0, s54
	s_mov_b64 s[20:21], 0x80
	v_lshl_add_u64 v[166:167], v[226:227], 0, s[20:21]
	s_barrier
	ds_read_b128 v[162:165], v172 offset:49152
	ds_read_b128 v[178:181], v172 offset:50176
	ds_read_b128 v[182:185], v172 offset:51200
	ds_read_b128 v[186:189], v172 offset:52224
	ds_read_b128 v[190:193], v172 offset:53248
	ds_read_b128 v[194:197], v172 offset:54272
	ds_read_b128 v[202:205], v172 offset:55296
	ds_read_b128 v[206:209], v172 offset:56320
	global_load_lds_dwordx4 v[166:167], off
	v_lshl_add_u64 v[166:167], v[228:229], 0, s[20:21]
	s_mov_b32 m0, s55
	s_nop 0
	global_load_lds_dwordx4 v[166:167], off
	s_barrier
	s_waitcnt lgkmcnt(0)
	s_setprio 1
	s_waitcnt lgkmcnt(0)
	v_mfma_f32_16x16x32_bf16 v[60:63], v[146:149], v[162:165], v[60:63]
	v_mfma_f32_16x16x32_bf16 v[56:59], v[154:157], v[162:165], v[56:59]
	v_mfma_f32_16x16x32_bf16 v[44:47], v[146:149], v[182:185], v[44:47]
	v_mfma_f32_16x16x32_bf16 v[40:43], v[154:157], v[182:185], v[40:43]
	v_mfma_f32_16x16x32_bf16 v[28:31], v[146:149], v[190:193], v[28:31]
	v_mfma_f32_16x16x32_bf16 v[24:27], v[154:157], v[190:193], v[24:27]
	v_mfma_f32_16x16x32_bf16 v[12:15], v[146:149], v[202:205], v[12:15]
	v_mfma_f32_16x16x32_bf16 v[8:11], v[154:157], v[202:205], v[8:11]
	v_mfma_f32_16x16x32_bf16 v[60:63], v[150:153], v[178:181], v[60:63]
	v_mfma_f32_16x16x32_bf16 v[56:59], v[158:161], v[178:181], v[56:59]
	v_mfma_f32_16x16x32_bf16 v[44:47], v[150:153], v[186:189], v[44:47]
	v_mfma_f32_16x16x32_bf16 v[40:43], v[158:161], v[186:189], v[40:43]
	v_mfma_f32_16x16x32_bf16 v[28:31], v[150:153], v[194:197], v[28:31]
	v_mfma_f32_16x16x32_bf16 v[24:27], v[158:161], v[194:197], v[24:27]
	v_mfma_f32_16x16x32_bf16 v[12:15], v[150:153], v[206:209], v[12:15]
	v_mfma_f32_16x16x32_bf16 v[8:11], v[158:161], v[206:209], v[8:11]
	s_setprio 0
	s_barrier
	s_add_u32 s4, s4, 0x40080
	s_addc_u32 s5, s5, 0
	s_add_i32 s6, s6, s44
	s_mov_b32 m0, s6
	s_nop 0
	global_load_lds_dwordx4 v130, s[4:5]
	s_add_i32 m0, s6, 0x2000
	s_nop 0
	global_load_lds_dwordx4 v134, s[4:5]
	s_waitcnt vmcnt(10)
	s_barrier
	s_setprio 1
	v_mfma_f32_16x16x32_bf16 v[52:55], v[210:213], v[162:165], v[52:55]
	v_mfma_f32_16x16x32_bf16 v[48:51], v[218:221], v[162:165], v[48:51]
	v_mfma_f32_16x16x32_bf16 v[36:39], v[210:213], v[182:185], v[36:39]
	v_mfma_f32_16x16x32_bf16 v[32:35], v[218:221], v[182:185], v[32:35]
	v_mfma_f32_16x16x32_bf16 v[20:23], v[210:213], v[190:193], v[20:23]
	v_mfma_f32_16x16x32_bf16 v[16:19], v[218:221], v[190:193], v[16:19]
	v_mfma_f32_16x16x32_bf16 v[4:7], v[210:213], v[202:205], v[4:7]
	v_mfma_f32_16x16x32_bf16 v[0:3], v[218:221], v[202:205], v[0:3]
	v_mfma_f32_16x16x32_bf16 v[52:55], v[214:217], v[178:181], v[52:55]
	v_mfma_f32_16x16x32_bf16 v[48:51], v[222:225], v[178:181], v[48:51]
	v_mfma_f32_16x16x32_bf16 v[36:39], v[214:217], v[186:189], v[36:39]
	v_mfma_f32_16x16x32_bf16 v[32:35], v[222:225], v[186:189], v[32:35]
	v_mfma_f32_16x16x32_bf16 v[20:23], v[214:217], v[194:197], v[20:23]
	v_mfma_f32_16x16x32_bf16 v[16:19], v[222:225], v[194:197], v[16:19]
	v_mfma_f32_16x16x32_bf16 v[4:7], v[214:217], v[206:209], v[4:7]
	v_mfma_f32_16x16x32_bf16 v[0:3], v[222:225], v[206:209], v[0:3]
	s_setprio 0
	s_add_i32 s67, s67, 2
	s_add_u32 s0, s0, 0x100
	s_addc_u32 s1, s1, 0
	s_add_u32 s65, s65, 0x100
	s_addc_u32 s66, s66, 0
	s_cmp_gt_u32 s67, 13
	s_barrier
;     __device__ __forceinline__ void operator()(const AccT& acc, const Unit& u, int wr, int wc, int fr, int fq) const {
;     ...
;         const int rbase = wr * 64 + fr;
;         const int tb = u.pn * 256 + wc * 32 + 8 * fq;
;         const int o0 = wc * 32 + 8 * fq;
;         const int j = fr & 3; const float sgn = ((fr >> 2) & 1) ? 1.0f : -1.0f;
; #pragma unroll
;         for (int ai = 0; ai < 2; ++ai) {
;             const int hh = 2 * ai + wr;
;             const float l2f = lgd[hh] * 1.4426950408889634f, l2b = lgd[4 + hh] * 1.4426950408889634f;
;             const float zf0 = exp2f((float)(127 - o0) * l2f), zfs = exp2f(-l2f), zb0 = exp2f((float)o0 * l2b), zbs = exp2f(l2b);
; #pragma unroll
;             for (int m = 0; m < 4; ++m) {
;                 const int r = rbase + ai * 128 + m * 16;
;                 const int d = 4 * (2 * m + (fr >> 3)) + j;
; #pragma unroll
;                 for (int bj = 0; bj < 2; ++bj) {
;                     const int t0 = tb + bj * 128;
;                     float v[8];
; #pragma unroll
;                     for (int jj = 0; jj < 4; ++jj) { v[jj] = acc[ai][bj][m][0][jj]; v[4 + jj] = acc[ai][bj][m][1][jj]; }
;                     if constexpr (ROPE) {
;                         const int t = t0 & 2047;
; #pragma unroll
;                         for (int hf = 0; hf < 2; ++hf) {
;                             f32x4 cs, sn;
;                             if (m < 2) { const float c1 = ropeA[(t >> 6) * 16 + d], s1 = ropeA[1024 + (t >> 6) * 16 + d]; cs = (f32x4){c1, c1, c1, c1}; sn = (f32x4){s1, s1, s1, s1}; }
;                             else { const float* cb = ropeA + 2048 + (d - 16) * 64 + (t & 63) + 4 * hf; cs = *(const f32x4*)(cb); sn = *(const f32x4*)(cb + 1024); }
; #pragma unroll
;                             for (int jj = 0; jj < 4; ++jj) { const float pr = __shfl_xor(v[4 * hf + jj], 4); v[4 * hf + jj] = v[4 * hf + jj] * cs[jj] + sgn * pr * sn[jj]; }
;                             __builtin_amdgcn_sched_barrier(0);
;                         }
;                     }
;                     float zf[8], zb[8]; zf[0] = zf0; zb[0] = zb0;
; #pragma unroll
;                     for (int jj = 1; jj < 8; ++jj) { zf[jj] = zf[jj - 1] * zfs; zb[jj] = zb[jj - 1] * zbs; }
;                     u32x4 wf, wb;
	s_cbranch_scc0 .LBB0_613
	v_mov_b32_e32 v136, v169
	v_mov_b32_e32 v150, v168
	s_lshl_b32 s0, s33, 8
	global_load_dword v154, v137, s[22:23]
	global_load_dword v155, v137, s[22:23] offset:16
	s_or_b32 s0, s0, s53
	v_lshlrev_b32_e32 v151, 3, v136
	v_ashrrev_i32_e32 v136, 1, v150
	v_add_u32_e32 v162, s0, v151
	v_bfi_b32 v136, -4, v136, v150
	v_lshrrev_b32_e32 v146, 2, v162
	v_add_u32_e32 v192, 0x400, v136
	v_and_b32_e32 v187, 0x1f0, v146
	v_add_u32_e32 v146, v192, v187
	v_add_u32_e32 v148, v187, v136
	v_ashrrev_i32_e32 v147, 31, v146
	v_ashrrev_i32_e32 v149, 31, v148
	v_lshl_add_u64 v[146:147], v[146:147], 2, s[16:17]
	v_lshl_add_u64 v[148:149], v[148:149], 2, s[16:17]
	global_load_dword v153, v[146:147], off
	global_load_dword v166, v[148:149], off
	v_and_b32_e32 v157, 64, v174
	v_xor_b32_e32 v156, 4, v174
	v_add_u32_e32 v157, 64, v157
	v_cmp_lt_i32_e32 vcc, v156, v157
	v_mov_b32_e32 v152, v124
	v_add_u32_e32 v151, s53, v151
	v_cndmask_b32_e32 v156, v174, v156, vcc
	v_lshlrev_b32_e32 v177, 2, v156
	ds_bpermute_b32 v124, v177, v124
	v_sub_u32_e32 v156, 0x7f, v151
	v_add_u32_e32 v164, s52, v150
	v_and_b32_e32 v150, 4, v150
	v_cvt_f32_i32_e32 v179, v156
	v_cvt_f32_i32_e32 v178, v151
	v_cmp_eq_u32_e32 vcc, 0, v150
	ds_bpermute_b32 v157, v177, v125
	ds_bpermute_b32 v158, v177, v127
	s_waitcnt lgkmcnt(0)
	v_cndmask_b32_e64 v167, v124, -v124, vcc
	ds_bpermute_b32 v151, v177, v126
	v_ashrrev_i32_e32 v165, 31, v164
	v_and_b32_e32 v186, 56, v162
	s_waitcnt lgkmcnt(0)
	v_cndmask_b32_e64 v151, v151, -v151, vcc
	s_waitcnt vmcnt(0)
	v_mul_f32_e32 v124, 0x3fb8aa3b, v154
	v_mul_f32_e32 v150, 0x3fb8aa3b, v155
	v_cmp_lt_f32_e64 s[4:5], s60, v124
	v_mul_f32_e32 v156, v124, v179
	v_cmp_gt_f32_e64 s[6:7], s59, v150
	v_cndmask_b32_e64 v159, 0, v176, s[4:5]
	v_mul_f32_e32 v160, v150, v178
	v_cndmask_b32_e64 v161, 0, v176, s[6:7]
	v_cmp_gt_f32_e64 s[8:9], s59, v156
	v_fmac_f32_e32 v159, 0xbfb8aa3b, v154
	s_and_b64 s[0:1], s[4:5], exec
	v_cmp_gt_f32_e64 s[4:5], s59, v160
	v_fmac_f32_e32 v161, 0x3fb8aa3b, v155
	v_cndmask_b32_e64 v154, 0, v176, s[8:9]
	v_exp_f32_e32 v155, v159
	v_cndmask_b32_e64 v159, 0, v176, s[4:5]
	v_fmac_f32_e32 v154, v124, v179
	v_fmac_f32_e32 v159, v150, v178
	v_exp_f32_e32 v150, v154
	v_cndmask_b32_e64 v156, 0, v175, s[8:9]
	s_cselect_b32 s8, 0xffffffc0, 0
	v_exp_f32_e32 v161, v161
	v_exp_f32_e32 v159, v159
	v_ldexp_f32 v163, v155, s8
	v_pk_mul_f32 v[154:155], v[152:153], v[166:167]
	v_cndmask_b32_e64 v167, v157, -v157, vcc
	v_mov_b32_e32 v152, v125
	s_and_b64 s[0:1], s[6:7], exec
	v_add_f32_e32 v190, v154, v155
	v_pk_mul_f32 v[154:155], v[152:153], v[166:167]
	v_cndmask_b32_e64 v167, v158, -v158, vcc
	v_mov_b32_e32 v152, v127
	v_cndmask_b32_e64 v160, 0, v175, s[4:5]
	s_cselect_b32 s0, 0xffffffc0, 0
	v_ldexp_f32 v180, v150, v156
	v_add_f32_e32 v191, v154, v155
	v_pk_mul_f32 v[154:155], v[152:153], v[166:167]
	v_ldexp_f32 v124, v161, s0
	v_mul_f32_e32 v161, v126, v166
	v_ldexp_f32 v150, v159, v160
	v_mul_f32_e32 v181, v163, v180
	v_add_f32_e32 v193, v154, v155
	global_load_dword v188, v[148:149], off
	global_load_dword v157, v[146:147], off
	ds_bpermute_b32 v127, v177, v121
	v_mov_b32_e32 v156, v121
	ds_bpermute_b32 v121, v177, v123
	ds_bpermute_b32 v125, v177, v120
	ds_bpermute_b32 v152, v177, v122
	s_waitcnt lgkmcnt(3)
	v_cndmask_b32_e64 v189, v127, -v127, vcc
	s_waitcnt lgkmcnt(1)
	v_cndmask_b32_e64 v158, v125, -v125, vcc
	s_waitcnt lgkmcnt(0)
	v_cndmask_b32_e64 v127, v152, -v152, vcc
	s_waitcnt vmcnt(1)
	v_mul_f32_e32 v159, v120, v188
	s_waitcnt vmcnt(0)
	v_pk_mul_f32 v[154:155], v[156:157], v[188:189]
	v_cndmask_b32_e64 v189, v121, -v121, vcc
	v_mov_b32_e32 v156, v123
	v_add_f32_e32 v121, v154, v155
	v_pk_mul_f32 v[154:155], v[156:157], v[188:189]
	s_nop 0
	v_add_f32_e32 v123, v154, v155
	v_mov_b32_e32 v125, v153
	v_pk_mul_f32 v[152:153], v[124:125], v[150:151]
	v_mov_b32_e32 v125, v161
	v_pk_mul_f32 v[154:155], v[124:125], v[152:153]
	v_mov_b32_e32 v125, v157
	v_mov_b32_e32 v155, v158
	v_pk_mul_f32 v[156:157], v[124:125], v[154:155]
	v_mov_b32_e32 v158, v124
	v_pk_mul_f32 v[158:159], v[158:159], v[156:157]
	v_mul_f32_e32 v167, v163, v181
	v_mov_b32_e32 v159, v127
	v_mul_f32_e32 v183, v163, v167
	v_pk_mul_f32 v[160:161], v[124:125], v[158:159]
	v_mul_f32_e32 v182, v163, v183
	v_mul_f32_e32 v151, v124, v160
	v_mul_f32_e32 v185, v163, v182
	v_mul_f32_e32 v155, v124, v151
	v_mul_f32_e32 v124, v180, v190
	v_mul_f32_e32 v125, v181, v191
	v_fma_f32 v153, v126, v166, v153
	v_mul_f32_e32 v184, v163, v185
	v_cvt_pk_bf16_f32 v124, v124, v125
	v_mul_f32_e32 v125, v167, v153
	v_mul_f32_e32 v126, v183, v193
	v_fma_f32 v120, v120, v188, v157
	v_mul_f32_e32 v159, v163, v184
	v_cvt_pk_bf16_f32 v125, v125, v126
	v_mul_f32_e32 v126, v182, v120
	v_mul_f32_e32 v127, v185, v121
	v_fma_f32 v122, v122, v188, v161
	v_cvt_pk_bf16_f32 v126, v126, v127
	v_mul_f32_e32 v127, v184, v122
	v_mul_f32_e32 v157, v159, v123
	v_cvt_pk_bf16_f32 v127, v127, v157
	v_mul_f32_e32 v157, v150, v190
	v_mul_f32_e32 v120, v158, v120
	v_mul_f32_e32 v121, v160, v121
	v_mul_f32_e32 v161, v152, v191
	v_cvt_pk_bf16_f32 v188, v157, v161
	v_mul_f32_e32 v153, v154, v153
	v_mul_f32_e32 v157, v156, v193
	v_cvt_pk_bf16_f32 v189, v153, v157
	v_cvt_pk_bf16_f32 v190, v120, v121
	v_mul_f32_e32 v120, v151, v122
	v_mul_f32_e32 v121, v155, v123
	v_cvt_pk_bf16_f32 v191, v120, v121
	v_lshlrev_b64 v[120:121], 17, v[164:165]
	v_lshl_add_u64 v[120:121], s[80:81], 0, v[120:121]
	v_ashrrev_i32_e32 v163, 31, v162
	v_lshl_add_u64 v[120:121], v[162:163], 1, v[120:121]
	s_mov_b64 s[0:1], 0x2000000
	global_store_dwordx4 v[120:121], v[124:127], off
	s_nop 1
	v_lshl_add_u64 v[126:127], v[120:121], 0, s[0:1]
	s_brev_b32 s0, 64
	v_add_co_u32_e64 v122, s[4:5], s0, v120
	s_nop 1
	v_addc_co_u32_e64 v123, s[4:5], 0, v121, s[4:5]
	global_store_dwordx4 v[122:123], v[188:191], off
	v_add_u32_e32 v122, 0x80, v162
	v_lshrrev_b32_e32 v122, 2, v122
	v_and_b32_e32 v153, 0x1f0, v122
	v_add_u32_e32 v122, v153, v192
	v_add_u32_e32 v124, v153, v136
	v_ashrrev_i32_e32 v123, 31, v122
	v_ashrrev_i32_e32 v125, 31, v124
	v_lshl_add_u64 v[122:123], v[122:123], 2, s[16:17]
	v_lshl_add_u64 v[124:125], v[124:125], 2, s[16:17]
	global_load_dword v163, v[122:123], off
	global_load_dword v164, v[124:125], off
	ds_bpermute_b32 v157, v177, v116
	v_mov_b32_e32 v162, v116
	ds_bpermute_b32 v116, v177, v117
	ds_bpermute_b32 v161, v177, v118
	ds_bpermute_b32 v166, v177, v119
	s_waitcnt lgkmcnt(3)
; __device__ __forceinline__ unsigned cvt_pk_bf16(float lo, float hi) { unsigned r; asm volatile("v_cvt_pk_bf16_f32 %0, %1, %2" : "=v"(r) : "v"(lo), "v"(hi)); return r; }
;     __device__ __forceinline__ void operator()(const AccT& acc, const Unit& u, int wr, int wc, int fr, int fq) const {
;     ...
;                     for (int jj = 0; jj < 4; ++jj) { v[jj] = acc[ai][bj][m][0][jj]; v[4 + jj] = acc[ai][bj][m][1][jj]; }
;                     if constexpr (ROPE) {
;                         const int t = t0 & 2047;
; #pragma unroll
;                         for (int hf = 0; hf < 2; ++hf) {
;                             f32x4 cs, sn;
;                             if (m < 2) { const float c1 = ropeA[(t >> 6) * 16 + d], s1 = ropeA[1024 + (t >> 6) * 16 + d]; cs = (f32x4){c1, c1, c1, c1}; sn = (f32x4){s1, s1, s1, s1}; }
;                             else { const float* cb = ropeA + 2048 + (d - 16) * 64 + (t & 63) + 4 * hf; cs = *(const f32x4*)(cb); sn = *(const f32x4*)(cb + 1024); }
; #pragma unroll
;                             for (int jj = 0; jj < 4; ++jj) { const float pr = __shfl_xor(v[4 * hf + jj], 4); v[4 * hf + jj] = v[4 * hf + jj] * cs[jj] + sgn * pr * sn[jj]; }
;                             __builtin_amdgcn_sched_barrier(0);
;                         }
;                     }
;                     float zf[8], zb[8]; zf[0] = zf0; zb[0] = zb0;
; #pragma unroll
;                     for (int jj = 1; jj < 8; ++jj) { zf[jj] = zf[jj - 1] * zfs; zb[jj] = zb[jj - 1] * zbs; }
;                     u32x4 wf, wb;
;                     wf.x = cvt_pk_bf16(v[0] * zf[0], v[1] * zf[1]); wf.y = cvt_pk_bf16(v[2] * zf[2], v[3] * zf[3]); wf.z = cvt_pk_bf16(v[4] * zf[4], v[5] * zf[5]); wf.w = cvt_pk_bf16(v[6] * zf[6], v[7] * zf[7]);
;                     wb.x = cvt_pk_bf16(v[0] * zb[0], v[1] * zb[1]); wb.y = cvt_pk_bf16(v[2] * zb[2], v[3] * zb[3]); wb.z = cvt_pk_bf16(v[4] * zb[4], v[5] * zb[5]); wb.w = cvt_pk_bf16(v[6] * zb[6], v[7] * zb[7]);
;                     *(u32x4*)(KTZ + (size_t)r * NT + t0) = wf;
;                     *(u32x4*)(KTZ + (size_t)(256 + r) * NT + t0) = wb;
	v_cndmask_b32_e64 v165, v157, -v157, vcc
	s_waitcnt vmcnt(0)
	v_pk_mul_f32 v[188:189], v[162:163], v[164:165]
	s_waitcnt lgkmcnt(2)
	v_cndmask_b32_e64 v165, v116, -v116, vcc
	v_mov_b32_e32 v162, v117
	v_pk_mul_f32 v[116:117], v[162:163], v[164:165]
	s_waitcnt lgkmcnt(1)
	v_cndmask_b32_e64 v165, v161, -v161, vcc
	v_mov_b32_e32 v162, v118
	v_add_f32_e32 v161, v116, v117
	v_pk_mul_f32 v[116:117], v[162:163], v[164:165]
	s_waitcnt lgkmcnt(0)
	v_cndmask_b32_e64 v165, v166, -v166, vcc
	v_mov_b32_e32 v162, v119
	v_add_f32_e32 v166, v116, v117
	v_pk_mul_f32 v[116:117], v[162:163], v[164:165]
	v_add_f32_e32 v157, v188, v189
	v_add_f32_e32 v164, v116, v117
	global_load_dword v117, v[122:123], off
	global_load_dword v118, v[124:125], off
	ds_bpermute_b32 v119, v177, v112
	v_mov_b32_e32 v116, v112
	ds_bpermute_b32 v112, v177, v113
	ds_bpermute_b32 v165, v177, v114
	ds_bpermute_b32 v188, v177, v115
	s_waitcnt lgkmcnt(3)
	v_cndmask_b32_e64 v119, v119, -v119, vcc
	s_waitcnt vmcnt(0)
	v_pk_mul_f32 v[162:163], v[116:117], v[118:119]
	s_waitcnt lgkmcnt(2)
	v_cndmask_b32_e64 v119, v112, -v112, vcc
	v_mov_b32_e32 v116, v113
	v_pk_mul_f32 v[112:113], v[116:117], v[118:119]
	s_waitcnt lgkmcnt(1)
	v_cndmask_b32_e64 v119, v165, -v165, vcc
	v_mov_b32_e32 v116, v114
	v_add_f32_e32 v162, v162, v163
	v_add_f32_e32 v163, v112, v113
	v_pk_mul_f32 v[112:113], v[116:117], v[118:119]
	s_waitcnt lgkmcnt(0)
	v_cndmask_b32_e64 v119, v188, -v188, vcc
	v_mov_b32_e32 v116, v115
	v_add_f32_e32 v165, v112, v113
	v_pk_mul_f32 v[112:113], v[116:117], v[118:119]
	s_nop 0
	v_add_f32_e32 v119, v112, v113
	v_mul_f32_e32 v112, v180, v157
	v_mul_f32_e32 v113, v181, v161
	v_cvt_pk_bf16_f32 v112, v112, v113
	v_mul_f32_e32 v113, v167, v166
	v_mul_f32_e32 v114, v183, v164
	v_cvt_pk_bf16_f32 v113, v113, v114
	v_mul_f32_e32 v114, v182, v162
	v_mul_f32_e32 v115, v185, v163
	v_cvt_pk_bf16_f32 v114, v114, v115
	v_mul_f32_e32 v115, v184, v165
	v_mul_f32_e32 v116, v159, v119
	v_cvt_pk_bf16_f32 v115, v115, v116
	v_mul_f32_e32 v116, v150, v157
	v_mul_f32_e32 v117, v152, v161
	v_cvt_pk_bf16_f32 v116, v116, v117
	v_mul_f32_e32 v117, v154, v166
	v_mul_f32_e32 v118, v156, v164
	v_cvt_pk_bf16_f32 v117, v117, v118
	v_mul_f32_e32 v118, v158, v162
	v_mul_f32_e32 v157, v160, v163
	v_mul_f32_e32 v119, v155, v119
	v_cvt_pk_bf16_f32 v118, v118, v157
	v_mul_f32_e32 v157, v151, v165
	v_cvt_pk_bf16_f32 v119, v157, v119
	global_store_dwordx4 v[120:121], v[112:115], off offset:256
	global_store_dwordx4 v[126:127], v[116:119], off offset:256
	v_add_u32_e32 v161, 0x408, v136
	v_add_u32_e32 v157, 8, v136
	v_add_u32_e32 v112, v161, v187
	v_add_u32_e32 v114, v187, v157
	v_ashrrev_i32_e32 v113, 31, v112
	v_ashrrev_i32_e32 v115, 31, v114
	v_lshl_add_u64 v[112:113], v[112:113], 2, s[16:17]
	v_lshl_add_u64 v[114:115], v[114:115], 2, s[16:17]
	global_load_dword v117, v[112:113], off
	global_load_dword v118, v[114:115], off
	ds_bpermute_b32 v119, v177, v108
	v_mov_b32_e32 v116, v108
	ds_bpermute_b32 v108, v177, v109
	ds_bpermute_b32 v162, v177, v110
	ds_bpermute_b32 v163, v177, v111
	s_waitcnt lgkmcnt(3)
	v_cndmask_b32_e64 v119, v119, -v119, vcc
	s_waitcnt vmcnt(0)
	v_pk_mul_f32 v[126:127], v[116:117], v[118:119]
	s_waitcnt lgkmcnt(2)
	v_cndmask_b32_e64 v119, v108, -v108, vcc
	v_mov_b32_e32 v116, v109
	v_pk_mul_f32 v[108:109], v[116:117], v[118:119]
	s_waitcnt lgkmcnt(1)
	v_cndmask_b32_e64 v119, v162, -v162, vcc
	v_mov_b32_e32 v116, v110
	v_add_f32_e32 v126, v126, v127
	v_add_f32_e32 v127, v108, v109
	v_pk_mul_f32 v[108:109], v[116:117], v[118:119]
	s_waitcnt lgkmcnt(0)
	v_cndmask_b32_e64 v119, v163, -v163, vcc
	v_mov_b32_e32 v116, v111
	v_add_f32_e32 v162, v108, v109
	v_pk_mul_f32 v[108:109], v[116:117], v[118:119]
	s_nop 0
	v_add_f32_e32 v118, v108, v109
	global_load_dword v109, v[112:113], off
	global_load_dword v110, v[114:115], off
	ds_bpermute_b32 v111, v177, v104
	v_mov_b32_e32 v108, v104
	ds_bpermute_b32 v104, v177, v105
	ds_bpermute_b32 v119, v177, v106
	ds_bpermute_b32 v163, v177, v107
	s_waitcnt lgkmcnt(3)
	v_cndmask_b32_e64 v111, v111, -v111, vcc
	s_waitcnt vmcnt(0)
	v_pk_mul_f32 v[116:117], v[108:109], v[110:111]
	s_waitcnt lgkmcnt(2)
	v_cndmask_b32_e64 v111, v104, -v104, vcc
	v_mov_b32_e32 v108, v105
	v_pk_mul_f32 v[104:105], v[108:109], v[110:111]
	s_waitcnt lgkmcnt(1)
	v_cndmask_b32_e64 v111, v119, -v119, vcc
	v_mov_b32_e32 v108, v106
	v_add_f32_e32 v119, v104, v105
	v_pk_mul_f32 v[104:105], v[108:109], v[110:111]
	s_waitcnt lgkmcnt(0)
	v_cndmask_b32_e64 v111, v163, -v163, vcc
	v_mov_b32_e32 v108, v107
	v_add_f32_e32 v163, v104, v105
	v_pk_mul_f32 v[104:105], v[108:109], v[110:111]
	v_add_f32_e32 v164, v116, v117
	v_add_f32_e32 v108, v104, v105
	v_mul_f32_e32 v104, v180, v126
	v_mul_f32_e32 v105, v181, v127
	v_cvt_pk_bf16_f32 v104, v104, v105
	v_mul_f32_e32 v105, v167, v162
	v_mul_f32_e32 v106, v183, v118
	v_cvt_pk_bf16_f32 v105, v105, v106
	v_mul_f32_e32 v106, v182, v164
	v_mul_f32_e32 v107, v185, v119
	v_cvt_pk_bf16_f32 v106, v106, v107
	v_mul_f32_e32 v107, v184, v163
	v_mul_f32_e32 v109, v159, v108
	v_cvt_pk_bf16_f32 v107, v107, v109
	v_mul_f32_e32 v109, v150, v126
	v_mul_f32_e32 v110, v152, v127
	v_cvt_pk_bf16_f32 v116, v109, v110
	v_mul_f32_e32 v109, v154, v162
	v_mul_f32_e32 v110, v156, v118
	v_cvt_pk_bf16_f32 v117, v109, v110
	v_mul_f32_e32 v109, v158, v164
	v_mul_f32_e32 v110, v160, v119
	v_cvt_pk_bf16_f32 v118, v109, v110
	v_mul_f32_e32 v109, v151, v163
	v_mul_f32_e32 v108, v155, v108
	s_mov_b64 s[0:1], 0x200000
	v_cvt_pk_bf16_f32 v119, v109, v108
	v_lshl_add_u64 v[108:109], v[120:121], 0, s[0:1]
	s_mov_b32 s0, 0x200000
	v_add_co_u32_e64 v110, s[4:5], s0, v120
	s_mov_b64 s[0:1], 0x2200000
	s_nop 0
	v_addc_co_u32_e64 v111, s[4:5], 0, v121, s[4:5]
	global_store_dwordx4 v[110:111], v[104:107], off
	v_lshl_add_u64 v[110:111], v[120:121], 0, s[0:1]
	s_mov_b32 s0, 0x2200000
	v_add_co_u32_e64 v104, s[4:5], s0, v120
	s_nop 1
	v_addc_co_u32_e64 v105, s[4:5], 0, v121, s[4:5]
	global_store_dwordx4 v[104:105], v[116:119], off
	v_add_u32_e32 v104, v153, v161
	v_add_u32_e32 v106, v153, v157
	v_ashrrev_i32_e32 v105, 31, v104
	v_ashrrev_i32_e32 v107, 31, v106
	v_lshl_add_u64 v[104:105], v[104:105], 2, s[16:17]
	v_lshl_add_u64 v[106:107], v[106:107], 2, s[16:17]
	global_load_dword v117, v[104:105], off
	global_load_dword v118, v[106:107], off
	ds_bpermute_b32 v119, v177, v100
	v_mov_b32_e32 v116, v100
	ds_bpermute_b32 v100, v177, v101
	ds_bpermute_b32 v153, v177, v102
	ds_bpermute_b32 v157, v177, v103
	s_waitcnt lgkmcnt(3)
; __device__ __forceinline__ unsigned cvt_pk_bf16(float lo, float hi) { unsigned r; asm volatile("v_cvt_pk_bf16_f32 %0, %1, %2" : "=v"(r) : "v"(lo), "v"(hi)); return r; }
;     __device__ __forceinline__ void operator()(const AccT& acc, const Unit& u, int wr, int wc, int fr, int fq) const {
;     ...
;                         const int t = t0 & 2047;
; #pragma unroll
;                         for (int hf = 0; hf < 2; ++hf) {
;                             f32x4 cs, sn;
;                             if (m < 2) { const float c1 = ropeA[(t >> 6) * 16 + d], s1 = ropeA[1024 + (t >> 6) * 16 + d]; cs = (f32x4){c1, c1, c1, c1}; sn = (f32x4){s1, s1, s1, s1}; }
;                             else { const float* cb = ropeA + 2048 + (d - 16) * 64 + (t & 63) + 4 * hf; cs = *(const f32x4*)(cb); sn = *(const f32x4*)(cb + 1024); }
; #pragma unroll
;                             for (int jj = 0; jj < 4; ++jj) { const float pr = __shfl_xor(v[4 * hf + jj], 4); v[4 * hf + jj] = v[4 * hf + jj] * cs[jj] + sgn * pr * sn[jj]; }
;                             __builtin_amdgcn_sched_barrier(0);
;                         }
;                     }
;                     float zf[8], zb[8]; zf[0] = zf0; zb[0] = zb0;
; #pragma unroll
;                     for (int jj = 1; jj < 8; ++jj) { zf[jj] = zf[jj - 1] * zfs; zb[jj] = zb[jj - 1] * zbs; }
;                     u32x4 wf, wb;
;                     wf.x = cvt_pk_bf16(v[0] * zf[0], v[1] * zf[1]); wf.y = cvt_pk_bf16(v[2] * zf[2], v[3] * zf[3]); wf.z = cvt_pk_bf16(v[4] * zf[4], v[5] * zf[5]); wf.w = cvt_pk_bf16(v[6] * zf[6], v[7] * zf[7]);
;                     wb.x = cvt_pk_bf16(v[0] * zb[0], v[1] * zb[1]); wb.y = cvt_pk_bf16(v[2] * zb[2], v[3] * zb[3]); wb.z = cvt_pk_bf16(v[4] * zb[4], v[5] * zb[5]); wb.w = cvt_pk_bf16(v[6] * zb[6], v[7] * zb[7]);
;                     *(u32x4*)(KTZ + (size_t)r * NT + t0) = wf;
;                     *(u32x4*)(KTZ + (size_t)(256 + r) * NT + t0) = wb;
	v_cndmask_b32_e64 v119, v119, -v119, vcc
	s_waitcnt vmcnt(0)
	v_pk_mul_f32 v[126:127], v[116:117], v[118:119]
	s_waitcnt lgkmcnt(2)
	v_cndmask_b32_e64 v119, v100, -v100, vcc
	v_mov_b32_e32 v116, v101
	v_pk_mul_f32 v[100:101], v[116:117], v[118:119]
	s_waitcnt lgkmcnt(1)
	v_cndmask_b32_e64 v119, v153, -v153, vcc
	v_mov_b32_e32 v116, v102
	v_add_f32_e32 v126, v126, v127
	v_add_f32_e32 v127, v100, v101
	v_pk_mul_f32 v[100:101], v[116:117], v[118:119]
	s_waitcnt lgkmcnt(0)
	v_cndmask_b32_e64 v119, v157, -v157, vcc
	v_mov_b32_e32 v116, v103
	v_add_f32_e32 v153, v100, v101
	v_pk_mul_f32 v[100:101], v[116:117], v[118:119]
	s_nop 0
	v_add_f32_e32 v118, v100, v101
	global_load_dword v101, v[104:105], off
	global_load_dword v102, v[106:107], off
	ds_bpermute_b32 v103, v177, v96
	v_mov_b32_e32 v100, v96
	ds_bpermute_b32 v96, v177, v97
	ds_bpermute_b32 v119, v177, v98
	ds_bpermute_b32 v157, v177, v99
	s_waitcnt lgkmcnt(3)
	v_cndmask_b32_e64 v103, v103, -v103, vcc
	s_waitcnt vmcnt(0)
	v_pk_mul_f32 v[116:117], v[100:101], v[102:103]
	s_waitcnt lgkmcnt(2)
	v_cndmask_b32_e64 v103, v96, -v96, vcc
	v_mov_b32_e32 v100, v97
	v_pk_mul_f32 v[96:97], v[100:101], v[102:103]
	s_waitcnt lgkmcnt(1)
	v_cndmask_b32_e64 v103, v119, -v119, vcc
	v_mov_b32_e32 v100, v98
	v_add_f32_e32 v116, v116, v117
	v_add_f32_e32 v117, v96, v97
	v_pk_mul_f32 v[96:97], v[100:101], v[102:103]
	s_waitcnt lgkmcnt(0)
	v_cndmask_b32_e64 v103, v157, -v157, vcc
	v_mov_b32_e32 v100, v99
	v_add_f32_e32 v119, v96, v97
	v_pk_mul_f32 v[96:97], v[100:101], v[102:103]
	s_nop 0
	v_add_f32_e32 v103, v96, v97
	v_mul_f32_e32 v96, v180, v126
	v_mul_f32_e32 v97, v181, v127
	v_cvt_pk_bf16_f32 v96, v96, v97
	v_mul_f32_e32 v97, v167, v153
	v_mul_f32_e32 v98, v183, v118
	v_cvt_pk_bf16_f32 v97, v97, v98
	v_mul_f32_e32 v98, v182, v116
	v_mul_f32_e32 v99, v185, v117
	v_cvt_pk_bf16_f32 v98, v98, v99
	v_mul_f32_e32 v99, v184, v119
	v_mul_f32_e32 v100, v159, v103
	v_cvt_pk_bf16_f32 v99, v99, v100
	v_mul_f32_e32 v100, v150, v126
	v_mul_f32_e32 v101, v152, v127
	v_cvt_pk_bf16_f32 v100, v100, v101
	v_mul_f32_e32 v101, v154, v153
	v_mul_f32_e32 v102, v156, v118
	v_cvt_pk_bf16_f32 v101, v101, v102
	v_mul_f32_e32 v102, v158, v116
	v_mul_f32_e32 v116, v160, v117
	v_mul_f32_e32 v103, v155, v103
	v_cvt_pk_bf16_f32 v102, v102, v116
	v_mul_f32_e32 v116, v151, v119
	v_cvt_pk_bf16_f32 v103, v116, v103
	global_store_dwordx4 v[108:109], v[96:99], off offset:256
	global_store_dwordx4 v[110:111], v[100:103], off offset:256
	s_nop 1
	v_lshlrev_b32_e32 v100, 6, v136
	v_ashrrev_i32_e32 v101, 31, v100
	v_lshlrev_b64 v[102:103], 2, v[100:101]
	v_lshl_add_u64 v[96:97], s[24:25], 0, v[102:103]
	v_lshlrev_b32_e32 v136, 2, v186
	v_lshl_add_u64 v[96:97], v[96:97], 0, v[136:137]
	v_add_co_u32_e64 v98, s[4:5], s61, v96
	ds_bpermute_b32 v101, v177, v92
	s_nop 0
	v_addc_co_u32_e64 v99, s[4:5], 0, v97, s[4:5]
	global_load_dwordx4 v[108:111], v[98:99], off
	global_load_dwordx4 v[116:119], v[96:97], off
	ds_bpermute_b32 v127, v177, v93
	ds_bpermute_b32 v153, v177, v94
	ds_bpermute_b32 v157, v177, v95
	v_mov_b32_e32 v126, v92
	v_mov_b32_e32 v92, v94
	s_waitcnt lgkmcnt(3)
	v_cndmask_b32_e64 v163, v101, -v101, vcc
	s_waitcnt lgkmcnt(2)
	v_cndmask_b32_e64 v165, v127, -v127, vcc
	s_waitcnt lgkmcnt(1)
	v_cndmask_b32_e64 v187, v153, -v153, vcc
	s_waitcnt lgkmcnt(0)
	v_cndmask_b32_e64 v189, v157, -v157, vcc
	s_waitcnt vmcnt(1)
	v_mov_b32_e32 v127, v108
	s_waitcnt vmcnt(0)
	v_mov_b32_e32 v162, v116
	v_mov_b32_e32 v108, v93
	v_mov_b32_e32 v164, v117
	v_mov_b32_e32 v93, v110
	v_mov_b32_e32 v186, v118
	v_mov_b32_e32 v110, v95
	v_mov_b32_e32 v188, v119
	v_pk_mul_f32 v[94:95], v[126:127], v[162:163]
	v_pk_mul_f32 v[108:109], v[108:109], v[164:165]
	v_pk_mul_f32 v[92:93], v[92:93], v[186:187]
	v_pk_mul_f32 v[110:111], v[110:111], v[188:189]
	v_add_f32_e32 v101, v94, v95
	v_add_f32_e32 v153, v108, v109
	v_add_f32_e32 v157, v92, v93
	v_add_f32_e32 v161, v110, v111
	v_lshl_add_u64 v[92:93], s[16:17], 0, v[102:103]
	v_lshl_add_u64 v[94:95], v[92:93], 0, v[136:137]
	v_add_co_u32_e64 v92, s[4:5], s62, v94
	ds_bpermute_b32 v103, v177, v88
	s_nop 0
	v_addc_co_u32_e64 v93, s[4:5], 0, v95, s[4:5]
	v_add_co_u32_e64 v94, s[4:5], s49, v94
	ds_bpermute_b32 v126, v177, v89
	s_nop 0
	v_addc_co_u32_e64 v95, s[4:5], 0, v95, s[4:5]
	global_load_dwordx4 v[108:111], v[92:93], off offset:16
	global_load_dwordx4 v[116:119], v[94:95], off offset:16
	ds_bpermute_b32 v162, v177, v90
	ds_bpermute_b32 v164, v177, v91
	v_mov_b32_e32 v102, v88
	v_mov_b32_e32 v88, v90
	s_waitcnt lgkmcnt(3)
	v_cndmask_b32_e64 v127, v103, -v103, vcc
	s_waitcnt lgkmcnt(2)
	v_cndmask_b32_e64 v163, v126, -v126, vcc
	s_waitcnt lgkmcnt(1)
	v_cndmask_b32_e64 v165, v162, -v162, vcc
	s_waitcnt lgkmcnt(0)
	v_cndmask_b32_e64 v187, v164, -v164, vcc
	s_waitcnt vmcnt(1)
	v_mov_b32_e32 v103, v108
	s_waitcnt vmcnt(0)
;     __device__ __forceinline__ void operator()(const AccT& acc, const Unit& u, int wr, int wc, int fr, int fq) const {
;     ...
;                 const int r = rbase + ai * 128 + m * 16;
;                 const int d = 4 * (2 * m + (fr >> 3)) + j;
; #pragma unroll
;                 for (int bj = 0; bj < 2; ++bj) {
;                     const int t0 = tb + bj * 128;
;                     float v[8];
; #pragma unroll
;                     for (int jj = 0; jj < 4; ++jj) { v[jj] = acc[ai][bj][m][0][jj]; v[4 + jj] = acc[ai][bj][m][1][jj]; }
;                     if constexpr (ROPE) {
;                         const int t = t0 & 2047;
; #pragma unroll
;                         for (int hf = 0; hf < 2; ++hf) {
;                             f32x4 cs, sn;
;                             if (m < 2) { const float c1 = ropeA[(t >> 6) * 16 + d], s1 = ropeA[1024 + (t >> 6) * 16 + d]; cs = (f32x4){c1, c1, c1, c1}; sn = (f32x4){s1, s1, s1, s1}; }
;                             else { const float* cb = ropeA + 2048 + (d - 16) * 64 + (t & 63) + 4 * hf; cs = *(const f32x4*)(cb); sn = *(const f32x4*)(cb + 1024); }
; #pragma unroll
;                             for (int jj = 0; jj < 4; ++jj) { const float pr = __shfl_xor(v[4 * hf + jj], 4); v[4 * hf + jj] = v[4 * hf + jj] * cs[jj] + sgn * pr * sn[jj]; }
;                             __builtin_amdgcn_sched_barrier(0);
;                         }
;                     }
;                     float zf[8], zb[8]; zf[0] = zf0; zb[0] = zb0;
; #pragma unroll
;                     for (int jj = 1; jj < 8; ++jj) { zf[jj] = zf[jj - 1] * zfs; zb[jj] = zb[jj - 1] * zbs; }
;                     u32x4 wf, wb;
;                     wf.x = cvt_pk_bf16(v[0] * zf[0], v[1] * zf[1]); wf.y = cvt_pk_bf16(v[2] * zf[2], v[3] * zf[3]); wf.z = cvt_pk_bf16(v[4] * zf[4], v[5] * zf[5]); wf.w = cvt_pk_bf16(v[6] * zf[6], v[7] * zf[7]);
;                     wb.x = cvt_pk_bf16(v[0] * zb[0], v[1] * zb[1]); wb.y = cvt_pk_bf16(v[2] * zb[2], v[3] * zb[3]); wb.z = cvt_pk_bf16(v[4] * zb[4], v[5] * zb[5]); wb.w = cvt_pk_bf16(v[6] * zb[6], v[7] * zb[7]);
;                     *(u32x4*)(KTZ + (size_t)r * NT + t0) = wf;
;                     *(u32x4*)(KTZ + (size_t)(256 + r) * NT + t0) = wb;
;                     __builtin_amdgcn_sched_barrier(0);
	v_mov_b32_e32 v126, v116
	v_mov_b32_e32 v108, v89
	v_mov_b32_e32 v162, v117
	v_mov_b32_e32 v89, v110
	v_mov_b32_e32 v164, v118
	v_mov_b32_e32 v110, v91
	v_mov_b32_e32 v186, v119
	v_pk_mul_f32 v[90:91], v[102:103], v[126:127]
	v_pk_mul_f32 v[102:103], v[108:109], v[162:163]
	v_pk_mul_f32 v[88:89], v[88:89], v[164:165]
	v_pk_mul_f32 v[108:109], v[110:111], v[186:187]
	v_add_f32_e32 v90, v90, v91
	v_add_f32_e32 v91, v102, v103
	v_add_f32_e32 v88, v88, v89
	v_add_f32_e32 v89, v108, v109
	v_mul_f32_e32 v102, v180, v101
	v_mul_f32_e32 v103, v181, v153
	v_cvt_pk_bf16_f32 v108, v102, v103
	v_mul_f32_e32 v102, v167, v157
	v_mul_f32_e32 v103, v183, v161
	v_cvt_pk_bf16_f32 v109, v102, v103
	v_mul_f32_e32 v102, v182, v90
	v_mul_f32_e32 v103, v185, v91
	v_cvt_pk_bf16_f32 v110, v102, v103
	v_mul_f32_e32 v102, v184, v88
	v_mul_f32_e32 v103, v159, v89
	v_cvt_pk_bf16_f32 v111, v102, v103
	v_mul_f32_e32 v101, v150, v101
	v_mul_f32_e32 v102, v152, v153
	v_mul_f32_e32 v88, v151, v88
	v_mul_f32_e32 v89, v155, v89
	s_mov_b64 s[0:1], 0x400000
	v_cvt_pk_bf16_f32 v116, v101, v102
	v_mul_f32_e32 v101, v154, v157
	v_mul_f32_e32 v102, v156, v161
	v_cvt_pk_bf16_f32 v117, v101, v102
	v_mul_f32_e32 v90, v158, v90
	v_mul_f32_e32 v91, v160, v91
	v_cvt_pk_bf16_f32 v118, v90, v91
	v_cvt_pk_bf16_f32 v119, v88, v89
	v_lshl_add_u64 v[88:89], v[120:121], 0, s[0:1]
	s_mov_b32 s0, 0x400000
	v_add_co_u32_e64 v90, s[4:5], s0, v120
	s_mov_b64 s[0:1], 0x2400000
	s_nop 0
	v_addc_co_u32_e64 v91, s[4:5], 0, v121, s[4:5]
	global_store_dwordx4 v[90:91], v[108:111], off
	v_lshl_add_u64 v[90:91], v[120:121], 0, s[0:1]
	s_mov_b32 s0, 0x2400000
	v_add_co_u32_e64 v102, s[4:5], s0, v120
	s_nop 1
	v_addc_co_u32_e64 v103, s[4:5], 0, v121, s[4:5]
	global_store_dwordx4 v[102:103], v[116:119], off
	global_load_dwordx4 v[108:111], v[98:99], off
	s_nop 0
	global_load_dwordx4 v[116:119], v[96:97], off
	ds_bpermute_b32 v101, v177, v84
	ds_bpermute_b32 v103, v177, v85
	ds_bpermute_b32 v126, v177, v86
	ds_bpermute_b32 v153, v177, v87
	v_mov_b32_e32 v102, v84
	v_mov_b32_e32 v84, v86
	s_waitcnt lgkmcnt(3)
	v_cndmask_b32_e64 v127, v101, -v101, vcc
	s_waitcnt lgkmcnt(2)
	v_cndmask_b32_e64 v163, v103, -v103, vcc
	s_waitcnt lgkmcnt(1)
	v_cndmask_b32_e64 v165, v126, -v126, vcc
	s_waitcnt lgkmcnt(0)
	v_cndmask_b32_e64 v187, v153, -v153, vcc
	s_waitcnt vmcnt(1)
	v_mov_b32_e32 v103, v108
	s_waitcnt vmcnt(0)
	v_mov_b32_e32 v126, v116
	v_mov_b32_e32 v108, v85
	v_mov_b32_e32 v162, v117
	v_mov_b32_e32 v85, v110
	v_mov_b32_e32 v164, v118
	v_mov_b32_e32 v110, v87
	v_mov_b32_e32 v186, v119
	v_pk_mul_f32 v[86:87], v[102:103], v[126:127]
	v_pk_mul_f32 v[102:103], v[108:109], v[162:163]
	v_pk_mul_f32 v[84:85], v[84:85], v[164:165]
	v_pk_mul_f32 v[108:109], v[110:111], v[186:187]
	v_add_f32_e32 v101, v86, v87
	v_add_f32_e32 v153, v102, v103
	v_add_f32_e32 v157, v84, v85
	v_add_f32_e32 v161, v108, v109
	global_load_dwordx4 v[84:87], v[92:93], off offset:16
	global_load_dwordx4 v[108:111], v[94:95], off offset:16
	ds_bpermute_b32 v103, v177, v80
	ds_bpermute_b32 v116, v177, v81
	ds_bpermute_b32 v118, v177, v82
	ds_bpermute_b32 v126, v177, v83
	v_mov_b32_e32 v102, v80
	v_mov_b32_e32 v80, v82
	s_waitcnt lgkmcnt(3)
	v_cndmask_b32_e64 v117, v103, -v103, vcc
	s_waitcnt lgkmcnt(2)
	v_cndmask_b32_e64 v119, v116, -v116, vcc
	s_waitcnt lgkmcnt(1)
	v_cndmask_b32_e64 v127, v118, -v118, vcc
	s_waitcnt lgkmcnt(0)
	v_cndmask_b32_e64 v163, v126, -v126, vcc
	s_waitcnt vmcnt(1)
	v_mov_b32_e32 v103, v84
	s_waitcnt vmcnt(0)
	v_mov_b32_e32 v116, v108
	v_mov_b32_e32 v84, v81
	v_mov_b32_e32 v118, v109
	v_mov_b32_e32 v81, v86
	v_mov_b32_e32 v126, v110
	v_mov_b32_e32 v86, v83
	v_mov_b32_e32 v162, v111
	v_pk_mul_f32 v[82:83], v[102:103], v[116:117]
	v_pk_mul_f32 v[84:85], v[84:85], v[118:119]
	v_pk_mul_f32 v[80:81], v[80:81], v[126:127]
	v_pk_mul_f32 v[86:87], v[86:87], v[162:163]
	v_add_f32_e32 v102, v82, v83
	v_add_f32_e32 v103, v84, v85
	v_add_f32_e32 v108, v80, v81
	v_add_f32_e32 v87, v86, v87
	v_mul_f32_e32 v80, v180, v101
	v_mul_f32_e32 v81, v181, v153
	v_cvt_pk_bf16_f32 v80, v80, v81
	v_mul_f32_e32 v81, v167, v157
	v_mul_f32_e32 v82, v183, v161
	v_cvt_pk_bf16_f32 v81, v81, v82
	v_mul_f32_e32 v82, v182, v102
	v_mul_f32_e32 v83, v185, v103
	v_cvt_pk_bf16_f32 v82, v82, v83
	v_mul_f32_e32 v83, v184, v108
	v_mul_f32_e32 v84, v159, v87
	v_cvt_pk_bf16_f32 v83, v83, v84
	v_mul_f32_e32 v84, v150, v101
	v_mul_f32_e32 v85, v152, v153
	v_cvt_pk_bf16_f32 v84, v84, v85
	v_mul_f32_e32 v85, v154, v157
	v_mul_f32_e32 v86, v156, v161
	v_cvt_pk_bf16_f32 v85, v85, v86
	v_mul_f32_e32 v86, v158, v102
	v_mul_f32_e32 v101, v160, v103
	v_mul_f32_e32 v87, v155, v87
	v_cvt_pk_bf16_f32 v86, v86, v101
	v_mul_f32_e32 v101, v151, v108
	v_cvt_pk_bf16_f32 v87, v101, v87
	global_store_dwordx4 v[88:89], v[80:83], off offset:256
	global_store_dwordx4 v[90:91], v[84:87], off offset:256
	s_nop 0
	v_add_u32_e32 v80, 0x200, v100
	v_ashrrev_i32_e32 v81, 31, v80
	v_lshl_add_u64 v[82:83], s[24:25], 0, v[136:137]
	v_lshlrev_b64 v[100:101], 2, v[80:81]
	v_lshl_add_u64 v[80:81], v[82:83], 0, v[100:101]
	v_add_co_u32_e64 v82, s[4:5], s61, v80
	ds_bpermute_b32 v103, v177, v76
	s_nop 0
	v_addc_co_u32_e64 v83, s[4:5], 0, v81, s[4:5]
	global_load_dwordx4 v[84:87], v[82:83], off
	global_load_dwordx4 v[88:91], v[80:81], off
	ds_bpermute_b32 v108, v177, v77
	ds_bpermute_b32 v110, v177, v78
	ds_bpermute_b32 v116, v177, v79
	v_mov_b32_e32 v102, v76
	v_mov_b32_e32 v76, v78
	s_waitcnt lgkmcnt(3)
	v_cndmask_b32_e64 v109, v103, -v103, vcc
	s_waitcnt lgkmcnt(2)
	v_cndmask_b32_e64 v111, v108, -v108, vcc
	s_waitcnt lgkmcnt(1)
	v_cndmask_b32_e64 v117, v110, -v110, vcc
	s_waitcnt lgkmcnt(0)
;     __device__ __forceinline__ void operator()(const AccT& acc, const Unit& u, int wr, int wc, int fr, int fq) const {
;     ...
;                 const int r = rbase + ai * 128 + m * 16;
;                 const int d = 4 * (2 * m + (fr >> 3)) + j;
; #pragma unroll
;                 for (int bj = 0; bj < 2; ++bj) {
;                     const int t0 = tb + bj * 128;
;                     float v[8];
; #pragma unroll
;                     for (int jj = 0; jj < 4; ++jj) { v[jj] = acc[ai][bj][m][0][jj]; v[4 + jj] = acc[ai][bj][m][1][jj]; }
;                     if constexpr (ROPE) {
;                         const int t = t0 & 2047;
; #pragma unroll
;                         for (int hf = 0; hf < 2; ++hf) {
;                             f32x4 cs, sn;
;                             if (m < 2) { const float c1 = ropeA[(t >> 6) * 16 + d], s1 = ropeA[1024 + (t >> 6) * 16 + d]; cs = (f32x4){c1, c1, c1, c1}; sn = (f32x4){s1, s1, s1, s1}; }
;                             else { const float* cb = ropeA + 2048 + (d - 16) * 64 + (t & 63) + 4 * hf; cs = *(const f32x4*)(cb); sn = *(const f32x4*)(cb + 1024); }
; #pragma unroll
;                             for (int jj = 0; jj < 4; ++jj) { const float pr = __shfl_xor(v[4 * hf + jj], 4); v[4 * hf + jj] = v[4 * hf + jj] * cs[jj] + sgn * pr * sn[jj]; }
;                             __builtin_amdgcn_sched_barrier(0);
;                         }
;                     }
;                     float zf[8], zb[8]; zf[0] = zf0; zb[0] = zb0;
; #pragma unroll
;                     for (int jj = 1; jj < 8; ++jj) { zf[jj] = zf[jj - 1] * zfs; zb[jj] = zb[jj - 1] * zbs; }
;                     u32x4 wf, wb;
;                     wf.x = cvt_pk_bf16(v[0] * zf[0], v[1] * zf[1]); wf.y = cvt_pk_bf16(v[2] * zf[2], v[3] * zf[3]); wf.z = cvt_pk_bf16(v[4] * zf[4], v[5] * zf[5]); wf.w = cvt_pk_bf16(v[6] * zf[6], v[7] * zf[7]);
;                     wb.x = cvt_pk_bf16(v[0] * zb[0], v[1] * zb[1]); wb.y = cvt_pk_bf16(v[2] * zb[2], v[3] * zb[3]); wb.z = cvt_pk_bf16(v[4] * zb[4], v[5] * zb[5]); wb.w = cvt_pk_bf16(v[6] * zb[6], v[7] * zb[7]);
;                     *(u32x4*)(KTZ + (size_t)r * NT + t0) = wf;
;                     *(u32x4*)(KTZ + (size_t)(256 + r) * NT + t0) = wb;
;                     __builtin_amdgcn_sched_barrier(0);
	v_cndmask_b32_e64 v119, v116, -v116, vcc
	s_waitcnt vmcnt(1)
	v_mov_b32_e32 v103, v84
	s_waitcnt vmcnt(0)
	v_mov_b32_e32 v108, v88
	v_mov_b32_e32 v84, v77
	v_mov_b32_e32 v110, v89
	v_mov_b32_e32 v77, v86
	v_mov_b32_e32 v116, v90
	v_mov_b32_e32 v86, v79
	v_mov_b32_e32 v118, v91
	v_pk_mul_f32 v[78:79], v[102:103], v[108:109]
	v_pk_mul_f32 v[84:85], v[84:85], v[110:111]
	v_pk_mul_f32 v[76:77], v[76:77], v[116:117]
	v_pk_mul_f32 v[86:87], v[86:87], v[118:119]
	v_add_f32_e32 v118, v78, v79
	v_add_f32_e32 v119, v84, v85
	v_add_f32_e32 v126, v76, v77
	v_add_f32_e32 v127, v86, v87
	v_lshl_add_u64 v[76:77], s[16:17], 0, v[100:101]
	v_lshl_add_u64 v[78:79], v[76:77], 0, v[136:137]
	v_add_co_u32_e64 v76, s[4:5], s62, v78
	ds_bpermute_b32 v101, v177, v72
	s_nop 0
	v_addc_co_u32_e64 v77, s[4:5], 0, v79, s[4:5]
	v_add_co_u32_e64 v78, s[4:5], s49, v78
	ds_bpermute_b32 v102, v177, v73
	s_nop 0
	v_addc_co_u32_e64 v79, s[4:5], 0, v79, s[4:5]
	global_load_dwordx4 v[84:87], v[76:77], off offset:16
	global_load_dwordx4 v[88:91], v[78:79], off offset:16
	ds_bpermute_b32 v108, v177, v74
	ds_bpermute_b32 v110, v177, v75
	v_mov_b32_e32 v100, v72
	v_mov_b32_e32 v72, v74
	s_waitcnt lgkmcnt(3)
	v_cndmask_b32_e64 v103, v101, -v101, vcc
	s_waitcnt lgkmcnt(2)
	v_cndmask_b32_e64 v109, v102, -v102, vcc
	s_waitcnt lgkmcnt(1)
	v_cndmask_b32_e64 v111, v108, -v108, vcc
	s_waitcnt lgkmcnt(0)
	v_cndmask_b32_e64 v117, v110, -v110, vcc
	s_waitcnt vmcnt(1)
	v_mov_b32_e32 v101, v84
	s_waitcnt vmcnt(0)
	v_mov_b32_e32 v102, v88
	v_mov_b32_e32 v84, v73
	v_mov_b32_e32 v108, v89
	v_mov_b32_e32 v73, v86
	v_mov_b32_e32 v110, v90
	v_mov_b32_e32 v86, v75
	v_mov_b32_e32 v116, v91
	v_pk_mul_f32 v[74:75], v[100:101], v[102:103]
	v_pk_mul_f32 v[84:85], v[84:85], v[108:109]
	v_pk_mul_f32 v[72:73], v[72:73], v[110:111]
	v_pk_mul_f32 v[86:87], v[86:87], v[116:117]
	v_add_f32_e32 v74, v74, v75
	v_add_f32_e32 v75, v84, v85
	v_add_f32_e32 v72, v72, v73
	v_add_f32_e32 v73, v86, v87
	v_mul_f32_e32 v84, v180, v118
	v_mul_f32_e32 v85, v181, v119
	v_cvt_pk_bf16_f32 v84, v84, v85
	v_mul_f32_e32 v85, v167, v126
	v_mul_f32_e32 v86, v183, v127
	v_cvt_pk_bf16_f32 v85, v85, v86
	v_mul_f32_e32 v86, v182, v74
	v_mul_f32_e32 v87, v185, v75
	v_cvt_pk_bf16_f32 v86, v86, v87
	v_mul_f32_e32 v87, v184, v72
	v_mul_f32_e32 v88, v159, v73
	v_cvt_pk_bf16_f32 v87, v87, v88
	v_mul_f32_e32 v88, v150, v118
	v_mul_f32_e32 v89, v152, v119
	v_cvt_pk_bf16_f32 v88, v88, v89
	v_mul_f32_e32 v89, v154, v126
	v_mul_f32_e32 v90, v156, v127
	v_mul_f32_e32 v72, v151, v72
	v_mul_f32_e32 v73, v155, v73
	s_mov_b64 s[0:1], 0x600000
	v_cvt_pk_bf16_f32 v89, v89, v90
	v_mul_f32_e32 v74, v158, v74
	v_mul_f32_e32 v75, v160, v75
	v_cvt_pk_bf16_f32 v90, v74, v75
	v_cvt_pk_bf16_f32 v91, v72, v73
	v_lshl_add_u64 v[72:73], v[120:121], 0, s[0:1]
	s_mov_b32 s0, 0x600000
	v_add_co_u32_e64 v74, s[4:5], s0, v120
	s_mov_b64 s[0:1], 0x2600000
	s_nop 0
	v_addc_co_u32_e64 v75, s[4:5], 0, v121, s[4:5]
	global_store_dwordx4 v[74:75], v[84:87], off
	v_lshl_add_u64 v[74:75], v[120:121], 0, s[0:1]
	s_mov_b32 s0, 0x2600000
	v_add_co_u32_e64 v84, s[4:5], s0, v120
	s_nop 1
	v_addc_co_u32_e64 v85, s[4:5], 0, v121, s[4:5]
	global_store_dwordx4 v[84:85], v[88:91], off
	global_load_dwordx4 v[84:87], v[82:83], off
	s_nop 0
	global_load_dwordx4 v[88:91], v[80:81], off
	ds_bpermute_b32 v101, v177, v68
	ds_bpermute_b32 v102, v177, v69
	ds_bpermute_b32 v108, v177, v70
	ds_bpermute_b32 v110, v177, v71
	v_mov_b32_e32 v100, v68
	v_mov_b32_e32 v68, v70
	s_waitcnt lgkmcnt(3)
	v_cndmask_b32_e64 v103, v101, -v101, vcc
	s_waitcnt lgkmcnt(2)
	v_cndmask_b32_e64 v109, v102, -v102, vcc
	s_waitcnt lgkmcnt(1)
	v_cndmask_b32_e64 v111, v108, -v108, vcc
	s_waitcnt lgkmcnt(0)
	v_cndmask_b32_e64 v117, v110, -v110, vcc
	s_waitcnt vmcnt(1)
	v_mov_b32_e32 v101, v84
	s_waitcnt vmcnt(0)
	v_mov_b32_e32 v102, v88
	v_mov_b32_e32 v84, v69
	v_mov_b32_e32 v108, v89
	v_mov_b32_e32 v69, v86
	v_mov_b32_e32 v110, v90
	v_mov_b32_e32 v86, v71
	v_mov_b32_e32 v116, v91
	v_pk_mul_f32 v[70:71], v[100:101], v[102:103]
	v_pk_mul_f32 v[84:85], v[84:85], v[108:109]
	v_pk_mul_f32 v[68:69], v[68:69], v[110:111]
	v_pk_mul_f32 v[86:87], v[86:87], v[116:117]
	v_add_f32_e32 v110, v70, v71
	v_add_f32_e32 v111, v84, v85
	v_add_f32_e32 v116, v68, v69
	v_add_f32_e32 v117, v86, v87
	global_load_dwordx4 v[68:71], v[76:77], off offset:16
	global_load_dwordx4 v[84:87], v[78:79], off offset:16
	ds_bpermute_b32 v89, v177, v64
	ds_bpermute_b32 v90, v177, v65
	ds_bpermute_b32 v100, v177, v66
	ds_bpermute_b32 v102, v177, v67
	v_mov_b32_e32 v88, v64
	v_mov_b32_e32 v64, v66
	s_waitcnt lgkmcnt(3)
	v_cndmask_b32_e64 v91, v89, -v89, vcc
	s_waitcnt lgkmcnt(2)
	v_cndmask_b32_e64 v101, v90, -v90, vcc
	s_waitcnt lgkmcnt(1)
	v_cndmask_b32_e64 v103, v100, -v100, vcc
	s_waitcnt lgkmcnt(0)
	v_cndmask_b32_e64 v109, v102, -v102, vcc
	s_waitcnt vmcnt(1)
	v_mov_b32_e32 v89, v68
	s_waitcnt vmcnt(0)
;     __device__ __forceinline__ void operator()(const AccT& acc, const Unit& u, int wr, int wc, int fr, int fq) const {
;     ...
;         for (int ai = 0; ai < 2; ++ai) {
;             const int hh = 2 * ai + wr;
;             const float l2f = lgd[hh] * 1.4426950408889634f, l2b = lgd[4 + hh] * 1.4426950408889634f;
;             const float zf0 = exp2f((float)(127 - o0) * l2f), zfs = exp2f(-l2f), zb0 = exp2f((float)o0 * l2b), zbs = exp2f(l2b);
; #pragma unroll
;             for (int m = 0; m < 4; ++m) {
;                 const int r = rbase + ai * 128 + m * 16;
;                 const int d = 4 * (2 * m + (fr >> 3)) + j;
; #pragma unroll
;                 for (int bj = 0; bj < 2; ++bj) {
;                     const int t0 = tb + bj * 128;
;                     float v[8];
; #pragma unroll
;                     for (int jj = 0; jj < 4; ++jj) { v[jj] = acc[ai][bj][m][0][jj]; v[4 + jj] = acc[ai][bj][m][1][jj]; }
;                     if constexpr (ROPE) {
;                         const int t = t0 & 2047;
; #pragma unroll
;                         for (int hf = 0; hf < 2; ++hf) {
;                             f32x4 cs, sn;
;                             if (m < 2) { const float c1 = ropeA[(t >> 6) * 16 + d], s1 = ropeA[1024 + (t >> 6) * 16 + d]; cs = (f32x4){c1, c1, c1, c1}; sn = (f32x4){s1, s1, s1, s1}; }
;                             else { const float* cb = ropeA + 2048 + (d - 16) * 64 + (t & 63) + 4 * hf; cs = *(const f32x4*)(cb); sn = *(const f32x4*)(cb + 1024); }
; #pragma unroll
;                             for (int jj = 0; jj < 4; ++jj) { const float pr = __shfl_xor(v[4 * hf + jj], 4); v[4 * hf + jj] = v[4 * hf + jj] * cs[jj] + sgn * pr * sn[jj]; }
;                             __builtin_amdgcn_sched_barrier(0);
;                         }
;                     }
;                     float zf[8], zb[8]; zf[0] = zf0; zb[0] = zb0;
; #pragma unroll
;                     for (int jj = 1; jj < 8; ++jj) { zf[jj] = zf[jj - 1] * zfs; zb[jj] = zb[jj - 1] * zbs; }
;                     u32x4 wf, wb;
;                     wf.x = cvt_pk_bf16(v[0] * zf[0], v[1] * zf[1]); wf.y = cvt_pk_bf16(v[2] * zf[2], v[3] * zf[3]); wf.z = cvt_pk_bf16(v[4] * zf[4], v[5] * zf[5]); wf.w = cvt_pk_bf16(v[6] * zf[6], v[7] * zf[7]);
	v_mov_b32_e32 v90, v84
	v_mov_b32_e32 v68, v65
	v_mov_b32_e32 v100, v85
	v_mov_b32_e32 v65, v70
	v_mov_b32_e32 v102, v86
	v_mov_b32_e32 v70, v67
	v_mov_b32_e32 v108, v87
	v_pk_mul_f32 v[66:67], v[88:89], v[90:91]
	v_pk_mul_f32 v[68:69], v[68:69], v[100:101]
	v_pk_mul_f32 v[64:65], v[64:65], v[102:103]
	v_pk_mul_f32 v[70:71], v[70:71], v[108:109]
	v_add_f32_e32 v84, v66, v67
	v_add_f32_e32 v85, v68, v69
	v_add_f32_e32 v86, v64, v65
	v_add_f32_e32 v71, v70, v71
	v_mul_f32_e32 v64, v180, v110
	v_mul_f32_e32 v65, v181, v111
	v_cvt_pk_bf16_f32 v64, v64, v65
	v_mul_f32_e32 v65, v167, v116
	v_mul_f32_e32 v66, v183, v117
	v_cvt_pk_bf16_f32 v65, v65, v66
	v_mul_f32_e32 v66, v182, v84
	v_mul_f32_e32 v67, v185, v85
	v_cvt_pk_bf16_f32 v66, v66, v67
	v_mul_f32_e32 v67, v184, v86
	v_mul_f32_e32 v68, v159, v71
	v_cvt_pk_bf16_f32 v67, v67, v68
	v_mul_f32_e32 v68, v150, v110
	v_mul_f32_e32 v69, v152, v111
	v_cvt_pk_bf16_f32 v68, v68, v69
	v_mul_f32_e32 v69, v154, v116
	v_mul_f32_e32 v70, v156, v117
	v_cvt_pk_bf16_f32 v69, v69, v70
	v_mul_f32_e32 v70, v158, v84
	v_mul_f32_e32 v84, v160, v85
	v_mul_f32_e32 v71, v155, v71
	v_cvt_pk_bf16_f32 v70, v70, v84
	v_mul_f32_e32 v84, v151, v86
	v_cvt_pk_bf16_f32 v71, v84, v71
	global_store_dwordx4 v[72:73], v[64:67], off offset:256
	global_store_dwordx4 v[74:75], v[68:71], off offset:256
	global_load_dword v64, v137, s[22:23] offset:8
	s_nop 0
	global_load_dword v70, v137, s[22:23] offset:24
	global_load_dword v67, v[146:147], off
	global_load_dword v74, v[148:149], off
	ds_bpermute_b32 v65, v177, v60
	ds_bpermute_b32 v68, v177, v62
	v_mov_b32_e32 v66, v60
	ds_bpermute_b32 v60, v177, v61
	ds_bpermute_b32 v71, v177, v63
	s_waitcnt lgkmcnt(3)
	v_cndmask_b32_e64 v75, v65, -v65, vcc
	s_waitcnt lgkmcnt(2)
	v_cndmask_b32_e64 v65, v68, -v68, vcc
	s_waitcnt vmcnt(3)
	v_mul_f32_e32 v72, 0x3fb8aa3b, v64
	s_waitcnt vmcnt(2)
	v_mul_f32_e32 v73, 0x3fb8aa3b, v70
	v_mul_f32_e32 v84, v72, v179
	s_waitcnt vmcnt(0)
	v_pk_mul_f32 v[68:69], v[66:67], v[74:75]
	s_waitcnt lgkmcnt(1)
	v_cndmask_b32_e64 v75, v60, -v60, vcc
	v_mov_b32_e32 v66, v61
	v_cmp_lt_f32_e64 s[4:5], s60, v72
	v_mul_f32_e32 v87, v73, v178
	v_pk_mul_f32 v[60:61], v[66:67], v[74:75]
	s_waitcnt lgkmcnt(0)
	v_cndmask_b32_e64 v75, v71, -v71, vcc
	v_mov_b32_e32 v66, v63
	v_cmp_gt_f32_e64 s[8:9], s59, v84
	v_cndmask_b32_e64 v86, 0, v176, s[4:5]
	v_cmp_gt_f32_e64 s[6:7], s59, v73
	s_and_b64 s[0:1], s[4:5], exec
	v_cmp_gt_f32_e64 s[4:5], s59, v87
	v_add_f32_e32 v110, v60, v61
	v_pk_mul_f32 v[60:61], v[66:67], v[74:75]
	v_cndmask_b32_e64 v66, 0, v176, s[8:9]
	v_cndmask_b32_e64 v88, 0, v176, s[6:7]
	v_add_f32_e32 v89, v68, v69
	v_fmac_f32_e32 v86, 0xbfb8aa3b, v64
	v_cndmask_b32_e64 v69, 0, v176, s[4:5]
	v_fmac_f32_e32 v66, v72, v179
	v_fmac_f32_e32 v88, 0x3fb8aa3b, v70
	v_exp_f32_e32 v68, v86
	v_fmac_f32_e32 v69, v73, v178
	v_exp_f32_e32 v66, v66
	v_exp_f32_e32 v70, v88
	v_exp_f32_e32 v69, v69
	v_cndmask_b32_e64 v63, 0, v175, s[8:9]
	s_cselect_b32 s8, 0xffffffc0, 0
	s_and_b64 s[0:1], s[6:7], exec
	v_cndmask_b32_e64 v64, 0, v175, s[4:5]
	s_cselect_b32 s0, 0xffffffc0, 0
	v_ldexp_f32 v100, v68, s8
	v_ldexp_f32 v63, v66, v63
	v_mul_f32_e32 v85, v62, v74
	v_ldexp_f32 v90, v70, s0
	v_ldexp_f32 v64, v69, v64
	v_mul_f32_e32 v75, v100, v63
	v_add_f32_e32 v111, v60, v61
	global_load_dword v108, v[148:149], off
	global_load_dword v69, v[146:147], off
	ds_bpermute_b32 v61, v177, v57
	ds_bpermute_b32 v60, v177, v56
	v_mov_b32_e32 v68, v57
	ds_bpermute_b32 v57, v177, v59
	ds_bpermute_b32 v66, v177, v58
	s_waitcnt lgkmcnt(3)
	v_cndmask_b32_e64 v109, v61, -v61, vcc
	s_waitcnt lgkmcnt(2)
	v_cndmask_b32_e64 v70, v60, -v60, vcc
	s_waitcnt lgkmcnt(0)
	v_cndmask_b32_e64 v72, v66, -v66, vcc
	s_waitcnt vmcnt(1)
	v_mul_f32_e32 v71, v56, v108
	s_waitcnt vmcnt(0)
	v_pk_mul_f32 v[60:61], v[68:69], v[108:109]
	v_cndmask_b32_e64 v109, v57, -v57, vcc
	v_mov_b32_e32 v68, v59
	v_add_f32_e32 v57, v60, v61
	v_pk_mul_f32 v[60:61], v[68:69], v[108:109]
	s_nop 0
	v_add_f32_e32 v59, v60, v61
	v_mov_b32_e32 v91, v67
	v_pk_mul_f32 v[60:61], v[90:91], v[64:65]
	v_mov_b32_e32 v91, v85
	v_pk_mul_f32 v[66:67], v[90:91], v[60:61]
	v_mov_b32_e32 v91, v69
	v_mov_b32_e32 v67, v70
	v_mul_f32_e32 v84, v100, v75
	v_pk_mul_f32 v[68:69], v[90:91], v[66:67]
	v_mov_b32_e32 v70, v90
	v_mul_f32_e32 v86, v100, v84
	v_pk_mul_f32 v[70:71], v[70:71], v[68:69]
	v_mul_f32_e32 v85, v100, v86
	v_mov_b32_e32 v71, v72
	v_mul_f32_e32 v88, v100, v85
	v_pk_mul_f32 v[72:73], v[90:91], v[70:71]
	v_fma_f32 v61, v62, v74, v61
	v_mul_f32_e32 v87, v100, v88
	v_mul_f32_e32 v65, v90, v72
	v_mul_f32_e32 v62, v84, v61
	v_fma_f32 v56, v56, v108, v69
	v_mul_f32_e32 v71, v100, v87
	v_mul_f32_e32 v67, v90, v65
	v_mul_f32_e32 v90, v63, v89
	v_mul_f32_e32 v91, v75, v110
	v_cvt_pk_bf16_f32 v100, v90, v91
	v_mul_f32_e32 v74, v86, v111
	v_cvt_pk_bf16_f32 v101, v62, v74
	v_mul_f32_e32 v62, v85, v56
	v_fma_f32 v58, v58, v108, v73
	v_mul_f32_e32 v69, v88, v57
	v_cvt_pk_bf16_f32 v102, v62, v69
	v_mul_f32_e32 v62, v87, v58
	v_mul_f32_e32 v69, v71, v59
	v_cvt_pk_bf16_f32 v103, v62, v69
	v_mul_f32_e32 v62, v64, v89
	v_mul_f32_e32 v56, v70, v56
	v_mul_f32_e32 v57, v72, v57
	v_mul_f32_e32 v69, v60, v110
	v_cvt_pk_bf16_f32 v108, v62, v69
	v_mul_f32_e32 v61, v66, v61
	v_mul_f32_e32 v62, v68, v111
	v_cvt_pk_bf16_f32 v109, v61, v62
	v_cvt_pk_bf16_f32 v110, v56, v57
	v_mul_f32_e32 v56, v65, v58
	v_mul_f32_e32 v57, v67, v59
	s_mov_b64 s[0:1], 0x1000000
	v_cvt_pk_bf16_f32 v111, v56, v57
	v_lshl_add_u64 v[56:57], v[120:121], 0, s[0:1]
	s_mov_b32 s0, 0x1000000
	v_add_co_u32_e64 v58, s[4:5], s0, v120
	s_mov_b64 s[0:1], 0x3000000
	s_nop 0
	v_addc_co_u32_e64 v59, s[4:5], 0, v121, s[4:5]
	global_store_dwordx4 v[58:59], v[100:103], off
	v_lshl_add_u64 v[58:59], v[120:121], 0, s[0:1]
	s_mov_b32 s0, 0x3000000
	v_add_co_u32_e64 v90, s[4:5], s0, v120
	s_nop 1
	v_addc_co_u32_e64 v91, s[4:5], 0, v121, s[4:5]
	global_store_dwordx4 v[90:91], v[108:111], off
	global_load_dword v91, v[122:123], off
	s_nop 0
	global_load_dword v100, v[124:125], off
	ds_bpermute_b32 v61, v177, v52
	v_mov_b32_e32 v90, v52
	ds_bpermute_b32 v52, v177, v53
	ds_bpermute_b32 v62, v177, v54
	ds_bpermute_b32 v69, v177, v55
	s_waitcnt lgkmcnt(3)
; __device__ __forceinline__ unsigned cvt_pk_bf16(float lo, float hi) { unsigned r; asm volatile("v_cvt_pk_bf16_f32 %0, %1, %2" : "=v"(r) : "v"(lo), "v"(hi)); return r; }
;     __device__ __forceinline__ void operator()(const AccT& acc, const Unit& u, int wr, int wc, int fr, int fq) const {
;     ...
;                     if constexpr (ROPE) {
;                         const int t = t0 & 2047;
; #pragma unroll
;                         for (int hf = 0; hf < 2; ++hf) {
;                             f32x4 cs, sn;
;                             if (m < 2) { const float c1 = ropeA[(t >> 6) * 16 + d], s1 = ropeA[1024 + (t >> 6) * 16 + d]; cs = (f32x4){c1, c1, c1, c1}; sn = (f32x4){s1, s1, s1, s1}; }
;                             else { const float* cb = ropeA + 2048 + (d - 16) * 64 + (t & 63) + 4 * hf; cs = *(const f32x4*)(cb); sn = *(const f32x4*)(cb + 1024); }
; #pragma unroll
;                             for (int jj = 0; jj < 4; ++jj) { const float pr = __shfl_xor(v[4 * hf + jj], 4); v[4 * hf + jj] = v[4 * hf + jj] * cs[jj] + sgn * pr * sn[jj]; }
;                             __builtin_amdgcn_sched_barrier(0);
;                         }
;                     }
;                     float zf[8], zb[8]; zf[0] = zf0; zb[0] = zb0;
; #pragma unroll
;                     for (int jj = 1; jj < 8; ++jj) { zf[jj] = zf[jj - 1] * zfs; zb[jj] = zb[jj - 1] * zbs; }
;                     u32x4 wf, wb;
;                     wf.x = cvt_pk_bf16(v[0] * zf[0], v[1] * zf[1]); wf.y = cvt_pk_bf16(v[2] * zf[2], v[3] * zf[3]); wf.z = cvt_pk_bf16(v[4] * zf[4], v[5] * zf[5]); wf.w = cvt_pk_bf16(v[6] * zf[6], v[7] * zf[7]);
;                     wb.x = cvt_pk_bf16(v[0] * zb[0], v[1] * zb[1]); wb.y = cvt_pk_bf16(v[2] * zb[2], v[3] * zb[3]); wb.z = cvt_pk_bf16(v[4] * zb[4], v[5] * zb[5]); wb.w = cvt_pk_bf16(v[6] * zb[6], v[7] * zb[7]);
;                     *(u32x4*)(KTZ + (size_t)r * NT + t0) = wf;
;                     *(u32x4*)(KTZ + (size_t)(256 + r) * NT + t0) = wb;
;                     __builtin_amdgcn_sched_barrier(0);
	v_cndmask_b32_e64 v101, v61, -v61, vcc
	s_waitcnt vmcnt(0)
	v_pk_mul_f32 v[102:103], v[90:91], v[100:101]
	s_waitcnt lgkmcnt(2)
	v_cndmask_b32_e64 v101, v52, -v52, vcc
	v_mov_b32_e32 v90, v53
	v_pk_mul_f32 v[52:53], v[90:91], v[100:101]
	s_waitcnt lgkmcnt(1)
	v_cndmask_b32_e64 v101, v62, -v62, vcc
	v_mov_b32_e32 v90, v54
	v_add_f32_e32 v62, v52, v53
	v_pk_mul_f32 v[52:53], v[90:91], v[100:101]
	s_waitcnt lgkmcnt(0)
	v_cndmask_b32_e64 v101, v69, -v69, vcc
	v_mov_b32_e32 v90, v55
	v_add_f32_e32 v69, v52, v53
	v_pk_mul_f32 v[52:53], v[90:91], v[100:101]
	v_add_f32_e32 v61, v102, v103
	v_add_f32_e32 v73, v52, v53
	global_load_dword v53, v[122:123], off
	global_load_dword v54, v[124:125], off
	ds_bpermute_b32 v55, v177, v48
	v_mov_b32_e32 v52, v48
	ds_bpermute_b32 v48, v177, v49
	ds_bpermute_b32 v74, v177, v50
	ds_bpermute_b32 v89, v177, v51
	s_waitcnt lgkmcnt(3)
	v_cndmask_b32_e64 v55, v55, -v55, vcc
	s_waitcnt vmcnt(0)
	v_pk_mul_f32 v[90:91], v[52:53], v[54:55]
	s_waitcnt lgkmcnt(2)
	v_cndmask_b32_e64 v55, v48, -v48, vcc
	v_mov_b32_e32 v52, v49
	v_pk_mul_f32 v[48:49], v[52:53], v[54:55]
	s_waitcnt lgkmcnt(1)
	v_cndmask_b32_e64 v55, v74, -v74, vcc
	v_mov_b32_e32 v52, v50
	v_add_f32_e32 v74, v48, v49
	v_pk_mul_f32 v[48:49], v[52:53], v[54:55]
	s_waitcnt lgkmcnt(0)
	v_cndmask_b32_e64 v55, v89, -v89, vcc
	v_mov_b32_e32 v52, v51
	v_add_f32_e32 v89, v48, v49
	v_pk_mul_f32 v[48:49], v[52:53], v[54:55]
	v_add_f32_e32 v90, v90, v91
	v_add_f32_e32 v55, v48, v49
	v_mul_f32_e32 v48, v63, v61
	v_mul_f32_e32 v49, v75, v62
	v_cvt_pk_bf16_f32 v48, v48, v49
	v_mul_f32_e32 v49, v84, v69
	v_mul_f32_e32 v50, v86, v73
	v_cvt_pk_bf16_f32 v49, v49, v50
	v_mul_f32_e32 v50, v85, v90
	v_mul_f32_e32 v51, v88, v74
	v_cvt_pk_bf16_f32 v50, v50, v51
	v_mul_f32_e32 v51, v87, v89
	v_mul_f32_e32 v52, v71, v55
	v_cvt_pk_bf16_f32 v51, v51, v52
	v_mul_f32_e32 v52, v64, v61
	v_mul_f32_e32 v53, v60, v62
	v_cvt_pk_bf16_f32 v52, v52, v53
	v_mul_f32_e32 v53, v66, v69
	v_mul_f32_e32 v54, v68, v73
	v_cvt_pk_bf16_f32 v53, v53, v54
	v_mul_f32_e32 v54, v70, v90
	v_mul_f32_e32 v61, v72, v74
	v_mul_f32_e32 v55, v67, v55
	v_cvt_pk_bf16_f32 v54, v54, v61
	v_mul_f32_e32 v61, v65, v89
	v_cvt_pk_bf16_f32 v55, v61, v55
	global_store_dwordx4 v[56:57], v[48:51], off offset:256
	global_store_dwordx4 v[58:59], v[52:55], off offset:256
	global_load_dword v49, v[112:113], off
	s_nop 0
	global_load_dword v50, v[114:115], off
	ds_bpermute_b32 v51, v177, v44
	v_mov_b32_e32 v48, v44
	ds_bpermute_b32 v44, v177, v45
	ds_bpermute_b32 v54, v177, v46
	ds_bpermute_b32 v55, v177, v47
	s_waitcnt lgkmcnt(3)
	v_cndmask_b32_e64 v51, v51, -v51, vcc
	s_waitcnt vmcnt(0)
	v_pk_mul_f32 v[52:53], v[48:49], v[50:51]
	s_waitcnt lgkmcnt(2)
	v_cndmask_b32_e64 v51, v44, -v44, vcc
	v_mov_b32_e32 v48, v45
	v_pk_mul_f32 v[44:45], v[48:49], v[50:51]
	s_waitcnt lgkmcnt(1)
	v_cndmask_b32_e64 v51, v54, -v54, vcc
	v_mov_b32_e32 v48, v46
	v_add_f32_e32 v52, v52, v53
	v_add_f32_e32 v53, v44, v45
	v_pk_mul_f32 v[44:45], v[48:49], v[50:51]
	s_waitcnt lgkmcnt(0)
	v_cndmask_b32_e64 v51, v55, -v55, vcc
	v_mov_b32_e32 v48, v47
	v_add_f32_e32 v54, v44, v45
	v_pk_mul_f32 v[44:45], v[48:49], v[50:51]
	s_nop 0
	v_add_f32_e32 v50, v44, v45
	global_load_dword v45, v[112:113], off
	global_load_dword v46, v[114:115], off
	ds_bpermute_b32 v47, v177, v40
	v_mov_b32_e32 v44, v40
	ds_bpermute_b32 v40, v177, v41
	ds_bpermute_b32 v51, v177, v42
	ds_bpermute_b32 v55, v177, v43
	s_waitcnt lgkmcnt(3)
	v_cndmask_b32_e64 v47, v47, -v47, vcc
	s_waitcnt vmcnt(0)
	v_pk_mul_f32 v[48:49], v[44:45], v[46:47]
	s_waitcnt lgkmcnt(2)
	v_cndmask_b32_e64 v47, v40, -v40, vcc
	v_mov_b32_e32 v44, v41
	v_pk_mul_f32 v[40:41], v[44:45], v[46:47]
	s_waitcnt lgkmcnt(1)
	v_cndmask_b32_e64 v47, v51, -v51, vcc
	v_mov_b32_e32 v44, v42
	v_add_f32_e32 v48, v48, v49
	v_add_f32_e32 v49, v40, v41
	v_pk_mul_f32 v[40:41], v[44:45], v[46:47]
	s_waitcnt lgkmcnt(0)
	v_cndmask_b32_e64 v47, v55, -v55, vcc
	v_mov_b32_e32 v44, v43
	v_add_f32_e32 v51, v40, v41
	v_pk_mul_f32 v[40:41], v[44:45], v[46:47]
	s_nop 0
	v_add_f32_e32 v40, v40, v41
	v_mul_f32_e32 v41, v63, v52
	v_mul_f32_e32 v42, v75, v53
	v_cvt_pk_bf16_f32 v42, v41, v42
	v_mul_f32_e32 v41, v84, v54
	v_mul_f32_e32 v43, v86, v50
	v_cvt_pk_bf16_f32 v43, v41, v43
	v_mul_f32_e32 v41, v85, v48
	v_mul_f32_e32 v44, v88, v49
	v_cvt_pk_bf16_f32 v44, v41, v44
	v_mul_f32_e32 v41, v87, v51
	v_mul_f32_e32 v45, v71, v40
	v_cvt_pk_bf16_f32 v45, v41, v45
	v_mul_f32_e32 v41, v64, v52
	v_mul_f32_e32 v46, v60, v53
	v_cvt_pk_bf16_f32 v46, v41, v46
	v_mul_f32_e32 v41, v66, v54
	v_mul_f32_e32 v47, v68, v50
	v_cvt_pk_bf16_f32 v47, v41, v47
	v_mul_f32_e32 v41, v70, v48
	v_mul_f32_e32 v48, v72, v49
	v_cvt_pk_bf16_f32 v48, v41, v48
	v_mul_f32_e32 v41, v65, v51
	v_mul_f32_e32 v40, v67, v40
	s_mov_b64 s[0:1], 0x1200000
	v_cvt_pk_bf16_f32 v49, v41, v40
	v_lshl_add_u64 v[40:41], v[120:121], 0, s[0:1]
	s_mov_b32 s0, 0x1200000
	v_add_co_u32_e64 v50, s[4:5], s0, v120
	s_mov_b64 s[0:1], 0x3200000
	s_nop 0
	v_addc_co_u32_e64 v51, s[4:5], 0, v121, s[4:5]
	global_store_dwordx4 v[50:51], v[42:45], off
	s_nop 1
	v_lshl_add_u64 v[42:43], v[120:121], 0, s[0:1]
	s_mov_b32 s0, 0x3200000
	v_add_co_u32_e64 v44, s[4:5], s0, v120
	s_nop 1
	v_addc_co_u32_e64 v45, s[4:5], 0, v121, s[4:5]
	global_store_dwordx4 v[44:45], v[46:49], off
	global_load_dword v45, v[104:105], off
	s_nop 0
	global_load_dword v46, v[106:107], off
	ds_bpermute_b32 v47, v177, v36
	v_mov_b32_e32 v44, v36
	ds_bpermute_b32 v36, v177, v37
	ds_bpermute_b32 v50, v177, v38
	ds_bpermute_b32 v51, v177, v39
	s_waitcnt lgkmcnt(3)
	v_cndmask_b32_e64 v47, v47, -v47, vcc
	s_waitcnt vmcnt(0)
	v_pk_mul_f32 v[48:49], v[44:45], v[46:47]
	s_waitcnt lgkmcnt(2)
; __device__ __forceinline__ unsigned cvt_pk_bf16(float lo, float hi) { unsigned r; asm volatile("v_cvt_pk_bf16_f32 %0, %1, %2" : "=v"(r) : "v"(lo), "v"(hi)); return r; }
;     __device__ __forceinline__ void operator()(const AccT& acc, const Unit& u, int wr, int wc, int fr, int fq) const {
;     ...
;                     if constexpr (ROPE) {
;                         const int t = t0 & 2047;
; #pragma unroll
;                         for (int hf = 0; hf < 2; ++hf) {
;                             f32x4 cs, sn;
;                             if (m < 2) { const float c1 = ropeA[(t >> 6) * 16 + d], s1 = ropeA[1024 + (t >> 6) * 16 + d]; cs = (f32x4){c1, c1, c1, c1}; sn = (f32x4){s1, s1, s1, s1}; }
;                             else { const float* cb = ropeA + 2048 + (d - 16) * 64 + (t & 63) + 4 * hf; cs = *(const f32x4*)(cb); sn = *(const f32x4*)(cb + 1024); }
; #pragma unroll
;                             for (int jj = 0; jj < 4; ++jj) { const float pr = __shfl_xor(v[4 * hf + jj], 4); v[4 * hf + jj] = v[4 * hf + jj] * cs[jj] + sgn * pr * sn[jj]; }
;                             __builtin_amdgcn_sched_barrier(0);
;                         }
;                     }
;                     float zf[8], zb[8]; zf[0] = zf0; zb[0] = zb0;
; #pragma unroll
;                     for (int jj = 1; jj < 8; ++jj) { zf[jj] = zf[jj - 1] * zfs; zb[jj] = zb[jj - 1] * zbs; }
;                     u32x4 wf, wb;
;                     wf.x = cvt_pk_bf16(v[0] * zf[0], v[1] * zf[1]); wf.y = cvt_pk_bf16(v[2] * zf[2], v[3] * zf[3]); wf.z = cvt_pk_bf16(v[4] * zf[4], v[5] * zf[5]); wf.w = cvt_pk_bf16(v[6] * zf[6], v[7] * zf[7]);
;                     wb.x = cvt_pk_bf16(v[0] * zb[0], v[1] * zb[1]); wb.y = cvt_pk_bf16(v[2] * zb[2], v[3] * zb[3]); wb.z = cvt_pk_bf16(v[4] * zb[4], v[5] * zb[5]); wb.w = cvt_pk_bf16(v[6] * zb[6], v[7] * zb[7]);
;                     *(u32x4*)(KTZ + (size_t)r * NT + t0) = wf;
;                     *(u32x4*)(KTZ + (size_t)(256 + r) * NT + t0) = wb;
;                     __builtin_amdgcn_sched_barrier(0);
	v_cndmask_b32_e64 v47, v36, -v36, vcc
	v_mov_b32_e32 v44, v37
	v_pk_mul_f32 v[36:37], v[44:45], v[46:47]
	s_waitcnt lgkmcnt(1)
	v_cndmask_b32_e64 v47, v50, -v50, vcc
	v_mov_b32_e32 v44, v38
	v_add_f32_e32 v48, v48, v49
	v_add_f32_e32 v49, v36, v37
	v_pk_mul_f32 v[36:37], v[44:45], v[46:47]
	s_waitcnt lgkmcnt(0)
	v_cndmask_b32_e64 v47, v51, -v51, vcc
	v_mov_b32_e32 v44, v39
	v_add_f32_e32 v50, v36, v37
	v_pk_mul_f32 v[36:37], v[44:45], v[46:47]
	s_nop 0
	v_add_f32_e32 v46, v36, v37
	global_load_dword v37, v[104:105], off
	global_load_dword v38, v[106:107], off
	ds_bpermute_b32 v39, v177, v32
	v_mov_b32_e32 v36, v32
	ds_bpermute_b32 v32, v177, v33
	ds_bpermute_b32 v47, v177, v34
	ds_bpermute_b32 v51, v177, v35
	s_waitcnt lgkmcnt(3)
	v_cndmask_b32_e64 v39, v39, -v39, vcc
	s_waitcnt vmcnt(0)
	v_pk_mul_f32 v[44:45], v[36:37], v[38:39]
	s_waitcnt lgkmcnt(2)
	v_cndmask_b32_e64 v39, v32, -v32, vcc
	v_mov_b32_e32 v36, v33
	v_pk_mul_f32 v[32:33], v[36:37], v[38:39]
	s_waitcnt lgkmcnt(1)
	v_cndmask_b32_e64 v39, v47, -v47, vcc
	v_mov_b32_e32 v36, v34
	v_add_f32_e32 v44, v44, v45
	v_add_f32_e32 v45, v32, v33
	v_pk_mul_f32 v[32:33], v[36:37], v[38:39]
	s_waitcnt lgkmcnt(0)
	v_cndmask_b32_e64 v39, v51, -v51, vcc
	v_mov_b32_e32 v36, v35
	v_add_f32_e32 v47, v32, v33
	v_pk_mul_f32 v[32:33], v[36:37], v[38:39]
	s_nop 0
	v_add_f32_e32 v39, v32, v33
	v_mul_f32_e32 v32, v63, v48
	v_mul_f32_e32 v33, v75, v49
	v_cvt_pk_bf16_f32 v32, v32, v33
	v_mul_f32_e32 v33, v84, v50
	v_mul_f32_e32 v34, v86, v46
	v_cvt_pk_bf16_f32 v33, v33, v34
	v_mul_f32_e32 v34, v85, v44
	v_mul_f32_e32 v35, v88, v45
	v_cvt_pk_bf16_f32 v34, v34, v35
	v_mul_f32_e32 v35, v87, v47
	v_mul_f32_e32 v36, v71, v39
	v_cvt_pk_bf16_f32 v35, v35, v36
	v_mul_f32_e32 v36, v64, v48
	v_mul_f32_e32 v37, v60, v49
	v_cvt_pk_bf16_f32 v36, v36, v37
	v_mul_f32_e32 v37, v66, v50
	v_mul_f32_e32 v38, v68, v46
	v_cvt_pk_bf16_f32 v37, v37, v38
	v_mul_f32_e32 v38, v70, v44
	v_mul_f32_e32 v44, v72, v45
	v_mul_f32_e32 v39, v67, v39
	v_cvt_pk_bf16_f32 v38, v38, v44
	v_mul_f32_e32 v44, v65, v47
	v_cvt_pk_bf16_f32 v39, v44, v39
	global_store_dwordx4 v[40:41], v[32:35], off offset:256
	global_store_dwordx4 v[42:43], v[36:39], off offset:256
	global_load_dwordx4 v[32:35], v[98:99], off
	s_nop 0
	global_load_dwordx4 v[36:39], v[96:97], off
	ds_bpermute_b32 v41, v177, v28
	ds_bpermute_b32 v42, v177, v29
	ds_bpermute_b32 v44, v177, v30
	ds_bpermute_b32 v46, v177, v31
	v_mov_b32_e32 v40, v28
	v_mov_b32_e32 v28, v30
	s_waitcnt lgkmcnt(3)
	v_cndmask_b32_e64 v43, v41, -v41, vcc
	s_waitcnt lgkmcnt(2)
	v_cndmask_b32_e64 v45, v42, -v42, vcc
	s_waitcnt lgkmcnt(1)
	v_cndmask_b32_e64 v47, v44, -v44, vcc
	s_waitcnt lgkmcnt(0)
	v_cndmask_b32_e64 v49, v46, -v46, vcc
	s_waitcnt vmcnt(1)
	v_mov_b32_e32 v41, v32
	s_waitcnt vmcnt(0)
	v_mov_b32_e32 v42, v36
	v_mov_b32_e32 v32, v29
	v_mov_b32_e32 v44, v37
	v_mov_b32_e32 v29, v34
	v_mov_b32_e32 v46, v38
	v_mov_b32_e32 v34, v31
	v_mov_b32_e32 v48, v39
	v_pk_mul_f32 v[30:31], v[40:41], v[42:43]
	v_pk_mul_f32 v[32:33], v[32:33], v[44:45]
	v_pk_mul_f32 v[28:29], v[28:29], v[46:47]
	v_pk_mul_f32 v[34:35], v[34:35], v[48:49]
	v_add_f32_e32 v46, v30, v31
	v_add_f32_e32 v47, v32, v33
	v_add_f32_e32 v48, v28, v29
	v_add_f32_e32 v49, v34, v35
	global_load_dwordx4 v[28:31], v[92:93], off offset:16
	global_load_dwordx4 v[32:35], v[94:95], off offset:16
	ds_bpermute_b32 v37, v177, v24
	ds_bpermute_b32 v38, v177, v25
	ds_bpermute_b32 v40, v177, v26
	ds_bpermute_b32 v42, v177, v27
	v_mov_b32_e32 v36, v24
	v_mov_b32_e32 v24, v26
	s_waitcnt lgkmcnt(3)
	v_cndmask_b32_e64 v39, v37, -v37, vcc
	s_waitcnt lgkmcnt(2)
	v_cndmask_b32_e64 v41, v38, -v38, vcc
	s_waitcnt lgkmcnt(1)
	v_cndmask_b32_e64 v43, v40, -v40, vcc
	s_waitcnt lgkmcnt(0)
	v_cndmask_b32_e64 v45, v42, -v42, vcc
	s_waitcnt vmcnt(1)
	v_mov_b32_e32 v37, v28
	s_waitcnt vmcnt(0)
	v_mov_b32_e32 v38, v32
	v_mov_b32_e32 v28, v25
	v_mov_b32_e32 v40, v33
	v_mov_b32_e32 v25, v30
	v_mov_b32_e32 v42, v34
	v_mov_b32_e32 v30, v27
	v_mov_b32_e32 v44, v35
	v_pk_mul_f32 v[26:27], v[36:37], v[38:39]
	v_pk_mul_f32 v[28:29], v[28:29], v[40:41]
	v_pk_mul_f32 v[24:25], v[24:25], v[42:43]
	v_pk_mul_f32 v[30:31], v[30:31], v[44:45]
	v_add_f32_e32 v32, v26, v27
	v_add_f32_e32 v33, v28, v29
	v_add_f32_e32 v24, v24, v25
	v_add_f32_e32 v25, v30, v31
	v_mul_f32_e32 v26, v63, v46
	v_mul_f32_e32 v27, v75, v47
	v_cvt_pk_bf16_f32 v26, v26, v27
	v_mul_f32_e32 v27, v84, v48
	v_mul_f32_e32 v28, v86, v49
	v_cvt_pk_bf16_f32 v27, v27, v28
	v_mul_f32_e32 v28, v85, v32
	v_mul_f32_e32 v29, v88, v33
	v_cvt_pk_bf16_f32 v28, v28, v29
	v_mul_f32_e32 v29, v87, v24
	v_mul_f32_e32 v30, v71, v25
	v_cvt_pk_bf16_f32 v29, v29, v30
	v_mul_f32_e32 v30, v64, v46
	v_mul_f32_e32 v31, v60, v47
	v_cvt_pk_bf16_f32 v30, v30, v31
	v_mul_f32_e32 v31, v66, v48
	v_mul_f32_e32 v32, v70, v32
	v_mul_f32_e32 v33, v72, v33
	v_mul_f32_e32 v24, v65, v24
	v_mul_f32_e32 v25, v67, v25
	s_mov_b64 s[0:1], 0x1400000
	v_mul_f32_e32 v34, v68, v49
	v_cvt_pk_bf16_f32 v31, v31, v34
	v_cvt_pk_bf16_f32 v32, v32, v33
	v_cvt_pk_bf16_f32 v33, v24, v25
	v_lshl_add_u64 v[24:25], v[120:121], 0, s[0:1]
	s_mov_b32 s0, 0x1400000
	v_add_co_u32_e64 v34, s[4:5], s0, v120
	s_mov_b64 s[0:1], 0x3400000
	s_nop 0
	v_addc_co_u32_e64 v35, s[4:5], 0, v121, s[4:5]
	global_store_dwordx4 v[34:35], v[26:29], off
	s_nop 1
	v_lshl_add_u64 v[26:27], v[120:121], 0, s[0:1]
	s_mov_b32 s0, 0x3400000
	v_add_co_u32_e64 v28, s[4:5], s0, v120
	s_nop 1
	v_addc_co_u32_e64 v29, s[4:5], 0, v121, s[4:5]
	global_store_dwordx4 v[28:29], v[30:33], off
	global_load_dwordx4 v[28:31], v[98:99], off
	s_nop 0
	global_load_dwordx4 v[32:35], v[96:97], off
	ds_bpermute_b32 v37, v177, v20
	ds_bpermute_b32 v38, v177, v21
	ds_bpermute_b32 v40, v177, v22
	ds_bpermute_b32 v42, v177, v23
	v_mov_b32_e32 v36, v20
	v_mov_b32_e32 v20, v22
	s_waitcnt lgkmcnt(3)
; __device__ __forceinline__ unsigned cvt_pk_bf16(float lo, float hi) { unsigned r; asm volatile("v_cvt_pk_bf16_f32 %0, %1, %2" : "=v"(r) : "v"(lo), "v"(hi)); return r; }
;     __device__ __forceinline__ void operator()(const AccT& acc, const Unit& u, int wr, int wc, int fr, int fq) const {
;     ...
;                     if constexpr (ROPE) {
;                         const int t = t0 & 2047;
; #pragma unroll
;                         for (int hf = 0; hf < 2; ++hf) {
;                             f32x4 cs, sn;
;                             if (m < 2) { const float c1 = ropeA[(t >> 6) * 16 + d], s1 = ropeA[1024 + (t >> 6) * 16 + d]; cs = (f32x4){c1, c1, c1, c1}; sn = (f32x4){s1, s1, s1, s1}; }
;                             else { const float* cb = ropeA + 2048 + (d - 16) * 64 + (t & 63) + 4 * hf; cs = *(const f32x4*)(cb); sn = *(const f32x4*)(cb + 1024); }
; #pragma unroll
;                             for (int jj = 0; jj < 4; ++jj) { const float pr = __shfl_xor(v[4 * hf + jj], 4); v[4 * hf + jj] = v[4 * hf + jj] * cs[jj] + sgn * pr * sn[jj]; }
;                             __builtin_amdgcn_sched_barrier(0);
;                         }
;                     }
;                     float zf[8], zb[8]; zf[0] = zf0; zb[0] = zb0;
; #pragma unroll
;                     for (int jj = 1; jj < 8; ++jj) { zf[jj] = zf[jj - 1] * zfs; zb[jj] = zb[jj - 1] * zbs; }
;                     u32x4 wf, wb;
;                     wf.x = cvt_pk_bf16(v[0] * zf[0], v[1] * zf[1]); wf.y = cvt_pk_bf16(v[2] * zf[2], v[3] * zf[3]); wf.z = cvt_pk_bf16(v[4] * zf[4], v[5] * zf[5]); wf.w = cvt_pk_bf16(v[6] * zf[6], v[7] * zf[7]);
;                     wb.x = cvt_pk_bf16(v[0] * zb[0], v[1] * zb[1]); wb.y = cvt_pk_bf16(v[2] * zb[2], v[3] * zb[3]); wb.z = cvt_pk_bf16(v[4] * zb[4], v[5] * zb[5]); wb.w = cvt_pk_bf16(v[6] * zb[6], v[7] * zb[7]);
;                     *(u32x4*)(KTZ + (size_t)r * NT + t0) = wf;
;                     *(u32x4*)(KTZ + (size_t)(256 + r) * NT + t0) = wb;
;                     __builtin_amdgcn_sched_barrier(0);
	v_cndmask_b32_e64 v39, v37, -v37, vcc
	s_waitcnt lgkmcnt(2)
	v_cndmask_b32_e64 v41, v38, -v38, vcc
	s_waitcnt lgkmcnt(1)
	v_cndmask_b32_e64 v43, v40, -v40, vcc
	s_waitcnt lgkmcnt(0)
	v_cndmask_b32_e64 v45, v42, -v42, vcc
	s_waitcnt vmcnt(1)
	v_mov_b32_e32 v37, v28
	s_waitcnt vmcnt(0)
	v_mov_b32_e32 v38, v32
	v_mov_b32_e32 v28, v21
	v_mov_b32_e32 v40, v33
	v_mov_b32_e32 v21, v30
	v_mov_b32_e32 v42, v34
	v_mov_b32_e32 v30, v23
	v_mov_b32_e32 v44, v35
	v_pk_mul_f32 v[22:23], v[36:37], v[38:39]
	v_pk_mul_f32 v[28:29], v[28:29], v[40:41]
	v_pk_mul_f32 v[20:21], v[20:21], v[42:43]
	v_pk_mul_f32 v[30:31], v[30:31], v[44:45]
	v_add_f32_e32 v42, v22, v23
	v_add_f32_e32 v43, v28, v29
	v_add_f32_e32 v44, v20, v21
	v_add_f32_e32 v45, v30, v31
	global_load_dwordx4 v[20:23], v[92:93], off offset:16
	global_load_dwordx4 v[28:31], v[94:95], off offset:16
	ds_bpermute_b32 v33, v177, v16
	ds_bpermute_b32 v34, v177, v17
	ds_bpermute_b32 v36, v177, v18
	ds_bpermute_b32 v38, v177, v19
	v_mov_b32_e32 v32, v16
	v_mov_b32_e32 v16, v18
	s_waitcnt lgkmcnt(3)
	v_cndmask_b32_e64 v35, v33, -v33, vcc
	s_waitcnt lgkmcnt(2)
	v_cndmask_b32_e64 v37, v34, -v34, vcc
	s_waitcnt lgkmcnt(1)
	v_cndmask_b32_e64 v39, v36, -v36, vcc
	s_waitcnt lgkmcnt(0)
	v_cndmask_b32_e64 v41, v38, -v38, vcc
	s_waitcnt vmcnt(1)
	v_mov_b32_e32 v33, v20
	s_waitcnt vmcnt(0)
	v_mov_b32_e32 v34, v28
	v_mov_b32_e32 v20, v17
	v_mov_b32_e32 v36, v29
	v_mov_b32_e32 v17, v22
	v_mov_b32_e32 v38, v30
	v_mov_b32_e32 v22, v19
	v_mov_b32_e32 v40, v31
	v_pk_mul_f32 v[18:19], v[32:33], v[34:35]
	v_pk_mul_f32 v[20:21], v[20:21], v[36:37]
	v_pk_mul_f32 v[16:17], v[16:17], v[38:39]
	v_pk_mul_f32 v[22:23], v[22:23], v[40:41]
	v_add_f32_e32 v28, v18, v19
	v_add_f32_e32 v29, v20, v21
	v_add_f32_e32 v30, v16, v17
	v_add_f32_e32 v23, v22, v23
	v_mul_f32_e32 v16, v63, v42
	v_mul_f32_e32 v17, v75, v43
	v_cvt_pk_bf16_f32 v16, v16, v17
	v_mul_f32_e32 v17, v84, v44
	v_mul_f32_e32 v18, v86, v45
	v_cvt_pk_bf16_f32 v17, v17, v18
	v_mul_f32_e32 v18, v85, v28
	v_mul_f32_e32 v19, v88, v29
	v_cvt_pk_bf16_f32 v18, v18, v19
	v_mul_f32_e32 v19, v87, v30
	v_mul_f32_e32 v20, v71, v23
	v_cvt_pk_bf16_f32 v19, v19, v20
	v_mul_f32_e32 v20, v64, v42
	v_mul_f32_e32 v21, v60, v43
	v_cvt_pk_bf16_f32 v20, v20, v21
	v_mul_f32_e32 v21, v66, v44
	v_mul_f32_e32 v22, v68, v45
	v_cvt_pk_bf16_f32 v21, v21, v22
	v_mul_f32_e32 v22, v70, v28
	v_mul_f32_e32 v28, v72, v29
	v_mul_f32_e32 v23, v67, v23
	v_cvt_pk_bf16_f32 v22, v22, v28
	v_mul_f32_e32 v28, v65, v30
	v_cvt_pk_bf16_f32 v23, v28, v23
	global_store_dwordx4 v[24:25], v[16:19], off offset:256
	global_store_dwordx4 v[26:27], v[20:23], off offset:256
	global_load_dwordx4 v[16:19], v[82:83], off
	s_nop 0
	global_load_dwordx4 v[20:23], v[80:81], off
	ds_bpermute_b32 v25, v177, v12
	ds_bpermute_b32 v26, v177, v13
	ds_bpermute_b32 v28, v177, v14
	ds_bpermute_b32 v30, v177, v15
	v_mov_b32_e32 v24, v12
	v_mov_b32_e32 v12, v14
	s_waitcnt lgkmcnt(3)
	v_cndmask_b32_e64 v27, v25, -v25, vcc
	s_waitcnt lgkmcnt(2)
	v_cndmask_b32_e64 v29, v26, -v26, vcc
	s_waitcnt lgkmcnt(1)
	v_cndmask_b32_e64 v31, v28, -v28, vcc
	s_waitcnt lgkmcnt(0)
	v_cndmask_b32_e64 v33, v30, -v30, vcc
	s_waitcnt vmcnt(1)
	v_mov_b32_e32 v25, v16
	s_waitcnt vmcnt(0)
	v_mov_b32_e32 v26, v20
	v_mov_b32_e32 v16, v13
	v_mov_b32_e32 v28, v21
	v_mov_b32_e32 v13, v18
	v_mov_b32_e32 v30, v22
	v_mov_b32_e32 v18, v15
	v_mov_b32_e32 v32, v23
	v_pk_mul_f32 v[14:15], v[24:25], v[26:27]
	v_pk_mul_f32 v[16:17], v[16:17], v[28:29]
	v_pk_mul_f32 v[12:13], v[12:13], v[30:31]
	v_pk_mul_f32 v[18:19], v[18:19], v[32:33]
	v_add_f32_e32 v30, v14, v15
	v_add_f32_e32 v31, v16, v17
	v_add_f32_e32 v32, v12, v13
	v_add_f32_e32 v33, v18, v19
	global_load_dwordx4 v[12:15], v[76:77], off offset:16
	global_load_dwordx4 v[16:19], v[78:79], off offset:16
	ds_bpermute_b32 v21, v177, v8
	ds_bpermute_b32 v22, v177, v9
	ds_bpermute_b32 v24, v177, v10
	ds_bpermute_b32 v26, v177, v11
	v_mov_b32_e32 v20, v8
	v_mov_b32_e32 v8, v10
	s_waitcnt lgkmcnt(3)
	v_cndmask_b32_e64 v23, v21, -v21, vcc
	s_waitcnt lgkmcnt(2)
	v_cndmask_b32_e64 v25, v22, -v22, vcc
	s_waitcnt lgkmcnt(1)
	v_cndmask_b32_e64 v27, v24, -v24, vcc
	s_waitcnt lgkmcnt(0)
	v_cndmask_b32_e64 v29, v26, -v26, vcc
	s_waitcnt vmcnt(1)
	v_mov_b32_e32 v21, v12
	s_waitcnt vmcnt(0)
; template <class Epi, class Sched>
; __device__ __forceinline__ void gemm_phase(LAS unsigned char* lds, const Gemm g, const Sched& S, const Epi& E) {
;     ...
;         if (!has_next) break;
; #pragma unroll
;         for (int a = 0; a < 2; ++a)
; #pragma unroll
;             for (int b = 0; b < 2; ++b)
; #pragma unroll
;                 for (int m = 0; m < 4; ++m)
; #pragma unroll
;                     for (int n = 0; n < 2; ++n) acc[a][b][m][n] = (f32x4){0.f, 0.f, 0.f, 0.f};
;         cur = nxt; cA = nA; cB = nB; ++ui;
;     }
;     PG8_WAIT_V(0);
;     __device__ __forceinline__ void operator()(const AccT& acc, const Unit& u, int wr, int wc, int fr, int fq) const {
;     ...
;                     if constexpr (ROPE) {
;                         const int t = t0 & 2047;
; #pragma unroll
;                         for (int hf = 0; hf < 2; ++hf) {
;                             f32x4 cs, sn;
;                             if (m < 2) { const float c1 = ropeA[(t >> 6) * 16 + d], s1 = ropeA[1024 + (t >> 6) * 16 + d]; cs = (f32x4){c1, c1, c1, c1}; sn = (f32x4){s1, s1, s1, s1}; }
;                             else { const float* cb = ropeA + 2048 + (d - 16) * 64 + (t & 63) + 4 * hf; cs = *(const f32x4*)(cb); sn = *(const f32x4*)(cb + 1024); }
; #pragma unroll
;                             for (int jj = 0; jj < 4; ++jj) { const float pr = __shfl_xor(v[4 * hf + jj], 4); v[4 * hf + jj] = v[4 * hf + jj] * cs[jj] + sgn * pr * sn[jj]; }
;                             __builtin_amdgcn_sched_barrier(0);
;                         }
;                     }
;                     float zf[8], zb[8]; zf[0] = zf0; zb[0] = zb0;
; #pragma unroll
;                     for (int jj = 1; jj < 8; ++jj) { zf[jj] = zf[jj - 1] * zfs; zb[jj] = zb[jj - 1] * zbs; }
;                     u32x4 wf, wb;
;                     wf.x = cvt_pk_bf16(v[0] * zf[0], v[1] * zf[1]); wf.y = cvt_pk_bf16(v[2] * zf[2], v[3] * zf[3]); wf.z = cvt_pk_bf16(v[4] * zf[4], v[5] * zf[5]); wf.w = cvt_pk_bf16(v[6] * zf[6], v[7] * zf[7]);
;                     wb.x = cvt_pk_bf16(v[0] * zb[0], v[1] * zb[1]); wb.y = cvt_pk_bf16(v[2] * zb[2], v[3] * zb[3]); wb.z = cvt_pk_bf16(v[4] * zb[4], v[5] * zb[5]); wb.w = cvt_pk_bf16(v[6] * zb[6], v[7] * zb[7]);
;                     *(u32x4*)(KTZ + (size_t)r * NT + t0) = wf;
;                     *(u32x4*)(KTZ + (size_t)(256 + r) * NT + t0) = wb;
;                     __builtin_amdgcn_sched_barrier(0);
	v_mov_b32_e32 v22, v16
	v_mov_b32_e32 v12, v9
	v_mov_b32_e32 v24, v17
	v_mov_b32_e32 v9, v14
	v_mov_b32_e32 v26, v18
	v_mov_b32_e32 v14, v11
	v_mov_b32_e32 v28, v19
	v_pk_mul_f32 v[10:11], v[20:21], v[22:23]
	v_pk_mul_f32 v[12:13], v[12:13], v[24:25]
	v_pk_mul_f32 v[8:9], v[8:9], v[26:27]
	v_pk_mul_f32 v[14:15], v[14:15], v[28:29]
	v_add_f32_e32 v16, v10, v11
	v_add_f32_e32 v17, v12, v13
	v_add_f32_e32 v8, v8, v9
	v_add_f32_e32 v9, v14, v15
	v_mul_f32_e32 v10, v63, v30
	v_mul_f32_e32 v11, v75, v31
	v_cvt_pk_bf16_f32 v10, v10, v11
	v_mul_f32_e32 v11, v84, v32
	v_mul_f32_e32 v12, v86, v33
	v_cvt_pk_bf16_f32 v11, v11, v12
	v_mul_f32_e32 v12, v85, v16
	v_mul_f32_e32 v13, v88, v17
	v_cvt_pk_bf16_f32 v12, v12, v13
	v_mul_f32_e32 v13, v87, v8
	v_mul_f32_e32 v14, v71, v9
	v_cvt_pk_bf16_f32 v13, v13, v14
	v_mul_f32_e32 v14, v64, v30
	v_mul_f32_e32 v15, v60, v31
	v_cvt_pk_bf16_f32 v14, v14, v15
	v_mul_f32_e32 v15, v66, v32
	v_mul_f32_e32 v18, v68, v33
	v_cvt_pk_bf16_f32 v15, v15, v18
	v_add_co_u32_e64 v18, s[4:5], s63, v120
	v_mul_f32_e32 v16, v70, v16
	v_mul_f32_e32 v17, v72, v17
	v_addc_co_u32_e64 v19, s[4:5], 0, v121, s[4:5]
	v_cvt_pk_bf16_f32 v16, v16, v17
	v_mul_f32_e32 v8, v65, v8
	v_mul_f32_e32 v9, v67, v9
	v_cvt_pk_bf16_f32 v17, v8, v9
	global_store_dwordx4 v[18:19], v[10:13], off
	v_lshl_add_u64 v[8:9], v[120:121], 0, s[26:27]
	s_nop 0
	v_add_co_u32_e64 v12, s[4:5], s64, v120
	v_lshl_add_u64 v[10:11], v[120:121], 0, s[28:29]
	s_nop 0
	v_addc_co_u32_e64 v13, s[4:5], 0, v121, s[4:5]
	global_store_dwordx4 v[12:13], v[14:17], off
	global_load_dwordx4 v[12:15], v[82:83], off
	s_nop 0
	global_load_dwordx4 v[16:19], v[80:81], off
	ds_bpermute_b32 v34, v177, v4
	ds_bpermute_b32 v32, v177, v5
	ds_bpermute_b32 v33, v177, v6
	ds_bpermute_b32 v28, v177, v7
	global_load_dwordx4 v[20:23], v[76:77], off offset:16
	global_load_dwordx4 v[24:27], v[78:79], off offset:16
	s_waitcnt lgkmcnt(0)
	v_cndmask_b32_e64 v29, v28, -v28, vcc
	v_mov_b32_e32 v30, v7
	s_waitcnt vmcnt(3)
	v_mov_b32_e32 v31, v15
	s_waitcnt vmcnt(2)
	v_mov_b32_e32 v28, v19
	v_cndmask_b32_e64 v19, v33, -v33, vcc
	v_mov_b32_e32 v7, v14
	v_cndmask_b32_e64 v15, v32, -v32, vcc
	v_mov_b32_e32 v32, v5
	v_mov_b32_e32 v33, v13
	v_mov_b32_e32 v14, v17
	v_cndmask_b32_e64 v17, v34, -v34, vcc
	v_mov_b32_e32 v5, v12
	ds_bpermute_b32 v13, v177, v0
	v_mov_b32_e32 v12, v0
	ds_bpermute_b32 v34, v177, v1
	ds_bpermute_b32 v35, v177, v2
	v_mov_b32_e32 v0, v2
	ds_bpermute_b32 v2, v177, v3
	v_pk_mul_f32 v[28:29], v[30:31], v[28:29]
	v_pk_mul_f32 v[6:7], v[6:7], v[18:19]
	v_pk_mul_f32 v[14:15], v[32:33], v[14:15]
	v_pk_mul_f32 v[4:5], v[4:5], v[16:17]
	v_add_f32_e32 v18, v28, v29
	v_add_f32_e32 v19, v6, v7
	v_add_f32_e32 v28, v14, v15
	v_add_f32_e32 v29, v4, v5
	s_waitcnt lgkmcnt(3)
	v_cndmask_b32_e64 v5, v13, -v13, vcc
	s_waitcnt lgkmcnt(2)
	v_cndmask_b32_e64 v7, v34, -v34, vcc
	s_waitcnt lgkmcnt(1)
	v_cndmask_b32_e64 v15, v35, -v35, vcc
	s_waitcnt lgkmcnt(0)
	v_cndmask_b32_e64 v17, v2, -v2, vcc
	s_waitcnt vmcnt(1)
	v_mov_b32_e32 v13, v20
	s_waitcnt vmcnt(0)
	v_mov_b32_e32 v4, v24
	v_mov_b32_e32 v20, v1
	v_mov_b32_e32 v6, v25
	v_mov_b32_e32 v1, v22
	v_mov_b32_e32 v14, v26
	v_mov_b32_e32 v22, v3
	v_mov_b32_e32 v16, v27
	v_pk_mul_f32 v[2:3], v[12:13], v[4:5]
	v_pk_mul_f32 v[4:5], v[20:21], v[6:7]
	v_pk_mul_f32 v[0:1], v[0:1], v[14:15]
	v_pk_mul_f32 v[6:7], v[22:23], v[16:17]
	v_add_f32_e32 v12, v2, v3
	v_add_f32_e32 v13, v4, v5
	v_add_f32_e32 v14, v0, v1
	v_add_f32_e32 v7, v6, v7
	v_mul_f32_e32 v0, v63, v29
	v_mul_f32_e32 v1, v75, v28
	v_cvt_pk_bf16_f32 v0, v0, v1
	v_mul_f32_e32 v1, v84, v19
	v_mul_f32_e32 v2, v86, v18
	v_cvt_pk_bf16_f32 v1, v1, v2
	v_mul_f32_e32 v2, v85, v12
	v_mul_f32_e32 v3, v88, v13
	v_cvt_pk_bf16_f32 v2, v2, v3
	v_mul_f32_e32 v3, v87, v14
	v_mul_f32_e32 v4, v71, v7
	v_cvt_pk_bf16_f32 v3, v3, v4
	v_mul_f32_e32 v4, v64, v29
	v_mul_f32_e32 v5, v60, v28
	v_cvt_pk_bf16_f32 v4, v4, v5
	v_mul_f32_e32 v5, v66, v19
	v_mul_f32_e32 v6, v68, v18
	v_cvt_pk_bf16_f32 v5, v5, v6
	v_mul_f32_e32 v6, v70, v12
	v_mul_f32_e32 v12, v72, v13
	v_mul_f32_e32 v7, v67, v7
	v_cvt_pk_bf16_f32 v6, v6, v12
	v_mul_f32_e32 v12, v65, v14
	v_cvt_pk_bf16_f32 v7, v12, v7
	global_store_dwordx4 v[8:9], v[0:3], off offset:256
	global_store_dwordx4 v[10:11], v[4:7], off offset:256
	s_and_b64 vcc, exec, s[2:3]
	s_mov_b32 s33, s30
	s_mov_b64 s[4:5], s[38:39]
	s_mov_b64 s[0:1], s[36:37]
	s_cbranch_vccz .LBB0_606
	s_waitcnt vmcnt(0)
	s_cmpk_gt_u32 s42, 0xff
	s_cbranch_scc1 .LBB0_617
	s_barrier

; #define PG8_STAGE(bufoff, gbase, voff) do { _Pragma("unroll") for (int _i = 0; _i < 2; ++_i) \
;         __builtin_amdgcn_global_load_lds((const unsigned*)((const char*)(gbase) + (voff)[_i]), (LAS unsigned*)(lds + (bufoff) + ldsw + _i * 8192), 16, 0, 0); } while (0)
; #define PG8_LDA(dst, b, h) do { _Pragma("unroll") for (int m = 0; m < 4; ++m) _Pragma("unroll") for (int k = 0; k < 2; ++k) dst[m][k] = *(const LAS bf16x8*)(lds + PG8_SA(b, h) + aoff + m * 2048 + k * 1024); } while (0)
; #define PG8_LDB(dst, b, h) do { _Pragma("unroll") for (int n = 0; n < 2; ++n) _Pragma("unroll") for (int k = 0; k < 2; ++k) dst[n][k] = *(const LAS bf16x8*)(lds + PG8_SB(b, h) + boff + n * 2048 + k * 1024); } while (0)
; #define PG8_WAIT_V(n) asm volatile("s_waitcnt vmcnt(" #n ")" ::: "memory")
; #define PG8_WAIT_L(n) asm volatile("s_waitcnt lgkmcnt(" #n ")" ::: "memory")
; #define PG8_BAR __builtin_amdgcn_s_barrier()
; #define PG8_SCHED __builtin_amdgcn_sched_barrier(0)
; template <class Epi, class Sched>
; __device__ __forceinline__ void gemm_phase(LAS unsigned char* lds, const Gemm g, const Sched& S, const Epi& E) {
;     ...
;         const bool has_next = S.next(ui + 1, nxt);
;         const char* nA = has_next ? (const char*)g.A + (size_t)nxt.pm * tstep : cA; const char* nB = has_next ? (const char*)g.Bt + (size_t)nxt.pn * tstep : cB;
;         for (int t = 0; t < nt; t += 2) {
;             const bool last = (t == nt - 2);
;             const char* a1 = cA + (size_t)(t + 1) * kstep;
;             const char* a2 = last ? nA : cA + (size_t)(t + 2) * kstep; const char* b2 = last ? nB : cB + (size_t)(t + 2) * kstep;
;             const char* a3 = a2 + kstep; const char* b3 = b2 + kstep;
;             PG8_LDB(B0, 0, 0); PG8_SCHED; PG8_LDA(At, 0, 0); PG8_STAGE(PG8_SA(1, 1), a1 + hstep, voffA);
;             PG8_WAIT_L(8); PG8_BAR; PG8_WAIT_L(0); PG8_MMA(0, 0, At, B0); PG8_BAR; PG8_SCHED;
;             PG8_LDB(B1, 0, 1); PG8_STAGE(PG8_SB(0, 0), b2, voffB);
;             PG8_BAR; PG8_WAIT_L(0); PG8_MMA(0, 1, At, B1); PG8_BAR;
;             PG8_LDA(At, 0, 1); PG8_STAGE(PG8_SA(0, 0), a2, voffA);
;             PG8_BAR; PG8_WAIT_L(0); PG8_MMA(1, 0, At, B0); PG8_BAR; PG8_SCHED;
;             PG8_STAGE(PG8_SB(0, 1), b2 + hstep, voffB);
;             PG8_WAIT_V(6); PG8_BAR; PG8_MMA(1, 1, At, B1); PG8_BAR;
.LBB0_632:
	s_ashr_i32 s23, s22, 31
	v_cmp_lt_i64_e32 vcc, s[24:25], v[140:141]
	s_lshl_b64 s[24:25], s[22:23], 19
	s_add_u32 s24, s38, s24
	s_addc_u32 s25, s39, s25
	s_and_b64 s[26:27], vcc, exec
	s_cselect_b32 s23, s25, s31
	s_cselect_b32 s61, s24, s30
	s_ashr_i32 s21, s20, 31
	s_lshl_b64 s[26:27], s[20:21], 19
	s_add_u32 s26, s96, s26
	s_addc_u32 s27, s97, s27
	s_and_b64 s[36:37], vcc, exec
	s_cselect_b32 s21, s27, s35
	s_cselect_b32 s62, s26, s34
	s_add_u32 s30, s30, 0x40080
	s_addc_u32 s31, s31, 0
	s_add_u32 s63, s34, 0x100
	s_addc_u32 s64, s35, 0
	s_mov_b32 s65, -2
	s_waitcnt lgkmcnt(0)
	ds_read_b128 v[150:153], v147
	ds_read_b128 v[154:157], v147 offset:1024
	ds_read_b128 v[158:161], v147 offset:2048
	ds_read_b128 v[162:165], v147 offset:3072
	s_add_u32 s34, s30, 0xfffc0080
	s_addc_u32 s35, s31, -1
	s_cmp_eq_u32 s65, 12
	s_cselect_b32 s37, s23, s35
	s_cselect_b32 s36, s61, s34
	s_cselect_b32 s35, s21, s64
	s_cselect_b32 s34, s62, s63
	s_add_i32 m0, s29, 0xc000
	ds_read_b128 v[166:169], v148
	ds_read_b128 v[170:173], v148 offset:1024
	ds_read_b128 v[174:177], v148 offset:2048
	ds_read_b128 v[178:181], v148 offset:3072
	ds_read_b128 v[182:185], v148 offset:4096
	ds_read_b128 v[186:189], v148 offset:5120
	ds_read_b128 v[190:193], v148 offset:6144
	ds_read_b128 v[194:197], v148 offset:7168
	global_load_lds_dwordx4 v136, s[30:31]
	s_add_i32 m0, s29, 0xe000
	s_nop 0
	global_load_lds_dwordx4 v138, s[30:31]
	s_waitcnt lgkmcnt(8)
	s_waitcnt vmcnt(10)
	s_barrier
	s_waitcnt lgkmcnt(0)
	s_setprio 1
	s_waitcnt lgkmcnt(0)
	v_mfma_f32_16x16x32_bf16 v[124:127], v[150:153], v[166:169], 0
	v_mfma_f32_16x16x32_bf16 v[120:123], v[158:161], v[166:169], 0
	v_mfma_f32_16x16x32_bf16 v[116:119], v[150:153], v[174:177], 0
	v_mfma_f32_16x16x32_bf16 v[108:111], v[158:161], v[174:177], 0
	v_mfma_f32_16x16x32_bf16 v[100:103], v[150:153], v[182:185], 0
	v_mfma_f32_16x16x32_bf16 v[92:95], v[158:161], v[182:185], 0
	v_mfma_f32_16x16x32_bf16 v[84:87], v[150:153], v[190:193], 0
	v_mfma_f32_16x16x32_bf16 v[76:79], v[158:161], v[190:193], 0
	v_mfma_f32_16x16x32_bf16 v[124:127], v[154:157], v[170:173], v[124:127]
	v_mfma_f32_16x16x32_bf16 v[120:123], v[162:165], v[170:173], v[120:123]
	v_mfma_f32_16x16x32_bf16 v[116:119], v[154:157], v[178:181], v[116:119]
	v_mfma_f32_16x16x32_bf16 v[108:111], v[162:165], v[178:181], v[108:111]
	v_mfma_f32_16x16x32_bf16 v[100:103], v[154:157], v[186:189], v[100:103]
	v_mfma_f32_16x16x32_bf16 v[92:95], v[162:165], v[186:189], v[92:95]
	v_mfma_f32_16x16x32_bf16 v[84:87], v[154:157], v[194:197], v[84:87]
	v_mfma_f32_16x16x32_bf16 v[76:79], v[162:165], v[194:197], v[76:79]
	s_setprio 0
	s_barrier
	s_add_i32 s66, s54, s43
	s_mov_b32 m0, s66
	ds_read_b128 v[202:205], v149
	ds_read_b128 v[206:209], v149 offset:1024
	ds_read_b128 v[210:213], v149 offset:2048
	ds_read_b128 v[214:217], v149 offset:3072
	global_load_lds_dwordx4 v130, s[34:35]
	s_add_i32 m0, s66, 0x2000
	s_nop 0
	global_load_lds_dwordx4 v134, s[34:35]
	s_waitcnt vmcnt(10)
	s_barrier
	s_waitcnt lgkmcnt(0)
	s_setprio 1
	s_waitcnt lgkmcnt(0)
	v_mfma_f32_16x16x32_bf16 v[112:115], v[202:205], v[166:169], 0
	v_mfma_f32_16x16x32_bf16 v[104:107], v[210:213], v[166:169], 0
	v_mfma_f32_16x16x32_bf16 v[96:99], v[202:205], v[174:177], 0
	v_mfma_f32_16x16x32_bf16 v[88:91], v[210:213], v[174:177], 0
	v_mfma_f32_16x16x32_bf16 v[80:83], v[202:205], v[182:185], 0
	v_mfma_f32_16x16x32_bf16 v[72:75], v[210:213], v[182:185], 0
	v_mfma_f32_16x16x32_bf16 v[68:71], v[202:205], v[190:193], 0
	v_mfma_f32_16x16x32_bf16 v[64:67], v[210:213], v[190:193], 0
	v_mfma_f32_16x16x32_bf16 v[112:115], v[206:209], v[170:173], v[112:115]
	v_mfma_f32_16x16x32_bf16 v[104:107], v[214:217], v[170:173], v[104:107]
	v_mfma_f32_16x16x32_bf16 v[96:99], v[206:209], v[178:181], v[96:99]
	v_mfma_f32_16x16x32_bf16 v[88:91], v[214:217], v[178:181], v[88:91]
	v_mfma_f32_16x16x32_bf16 v[80:83], v[206:209], v[186:189], v[80:83]
	v_mfma_f32_16x16x32_bf16 v[72:75], v[214:217], v[186:189], v[72:75]
	v_mfma_f32_16x16x32_bf16 v[68:71], v[206:209], v[194:197], v[68:71]
	v_mfma_f32_16x16x32_bf16 v[64:67], v[214:217], v[194:197], v[64:67]
	s_setprio 0
	s_mov_b32 m0, s29
	v_lshl_add_u64 v[220:221], s[36:37], 0, v[128:129]
	s_barrier
	ds_read_b128 v[166:169], v148 offset:16384
	ds_read_b128 v[170:173], v148 offset:17408
	ds_read_b128 v[174:177], v148 offset:18432
	ds_read_b128 v[178:181], v148 offset:19456
	ds_read_b128 v[182:185], v148 offset:20480
	ds_read_b128 v[186:189], v148 offset:21504
	ds_read_b128 v[190:193], v148 offset:22528
	ds_read_b128 v[194:197], v148 offset:23552
	global_load_lds_dwordx4 v128, s[36:37]
	v_lshl_add_u64 v[222:223], s[36:37], 0, v[132:133]
	s_mov_b32 m0, s44
	s_nop 0
	global_load_lds_dwordx4 v132, s[36:37]
	s_barrier
	s_waitcnt lgkmcnt(0)
	s_setprio 1
	s_waitcnt lgkmcnt(0)
	v_mfma_f32_16x16x32_bf16 v[60:63], v[150:153], v[166:169], 0
	v_mfma_f32_16x16x32_bf16 v[56:59], v[158:161], v[166:169], 0
	v_mfma_f32_16x16x32_bf16 v[52:55], v[150:153], v[174:177], 0
	v_mfma_f32_16x16x32_bf16 v[44:47], v[158:161], v[174:177], 0
	v_mfma_f32_16x16x32_bf16 v[36:39], v[150:153], v[182:185], 0
	v_mfma_f32_16x16x32_bf16 v[28:31], v[158:161], v[182:185], 0
	v_mfma_f32_16x16x32_bf16 v[20:23], v[150:153], v[190:193], 0
	v_mfma_f32_16x16x32_bf16 v[12:15], v[158:161], v[190:193], 0
	v_mfma_f32_16x16x32_bf16 v[60:63], v[154:157], v[170:173], v[60:63]
	v_mfma_f32_16x16x32_bf16 v[56:59], v[162:165], v[170:173], v[56:59]
	v_mfma_f32_16x16x32_bf16 v[52:55], v[154:157], v[178:181], v[52:55]
	v_mfma_f32_16x16x32_bf16 v[44:47], v[162:165], v[178:181], v[44:47]
	v_mfma_f32_16x16x32_bf16 v[36:39], v[154:157], v[186:189], v[36:39]
	v_mfma_f32_16x16x32_bf16 v[28:31], v[162:165], v[186:189], v[28:31]
	v_mfma_f32_16x16x32_bf16 v[20:23], v[154:157], v[194:197], v[20:23]
	v_mfma_f32_16x16x32_bf16 v[12:15], v[162:165], v[194:197], v[12:15]
	s_setprio 0
	s_barrier
; #define PG8_STAGE(bufoff, gbase, voff) do { _Pragma("unroll") for (int _i = 0; _i < 2; ++_i) \
;         __builtin_amdgcn_global_load_lds((const unsigned*)((const char*)(gbase) + (voff)[_i]), (LAS unsigned*)(lds + (bufoff) + ldsw + _i * 8192), 16, 0, 0); } while (0)
; #define PG8_LDA(dst, b, h) do { _Pragma("unroll") for (int m = 0; m < 4; ++m) _Pragma("unroll") for (int k = 0; k < 2; ++k) dst[m][k] = *(const LAS bf16x8*)(lds + PG8_SA(b, h) + aoff + m * 2048 + k * 1024); } while (0)
; #define PG8_LDB(dst, b, h) do { _Pragma("unroll") for (int n = 0; n < 2; ++n) _Pragma("unroll") for (int k = 0; k < 2; ++k) dst[n][k] = *(const LAS bf16x8*)(lds + PG8_SB(b, h) + boff + n * 2048 + k * 1024); } while (0)
; #define PG8_MMA(ai, bj, At, Bt) do { __builtin_amdgcn_s_setprio(1); _Pragma("unroll") for (int m = 0; m < 4; ++m) _Pragma("unroll") for (int n = 0; n < 2; ++n) _Pragma("unroll") for (int k = 0; k < 2; ++k) \
;         acc[ai][bj][m][n] = __builtin_amdgcn_mfma_f32_16x16x32_bf16(Bt[n][k], At[m][k], acc[ai][bj][m][n], 0, 0, 0); __builtin_amdgcn_s_setprio(0); } while (0)
; #define PG8_WAIT_V(n) asm volatile("s_waitcnt vmcnt(" #n ")" ::: "memory")
; #define PG8_WAIT_L(n) asm volatile("s_waitcnt lgkmcnt(" #n ")" ::: "memory")
; #define PG8_BAR __builtin_amdgcn_s_barrier()
; #define PG8_SCHED __builtin_amdgcn_sched_barrier(0)
; template <class Epi, class Sched>
; __device__ __forceinline__ void gemm_phase(LAS unsigned char* lds, const Gemm g, const Sched& S, const Epi& E) {
;     ...
;             PG8_WAIT_V(6); PG8_BAR; PG8_MMA(1, 1, At, B1); PG8_BAR;
;             PG8_LDB(B0, 1, 0); PG8_SCHED; PG8_LDA(At, 1, 0); PG8_STAGE(PG8_SA(0, 1), a2 + hstep, voffA);
;             PG8_WAIT_L(8); PG8_BAR; PG8_WAIT_L(0); PG8_MMA(0, 0, At, B0); PG8_BAR; PG8_SCHED;
;             PG8_LDB(B1, 1, 1); PG8_STAGE(PG8_SB(1, 0), b3, voffB);
;             PG8_BAR; PG8_WAIT_L(0); PG8_MMA(0, 1, At, B1); PG8_BAR;
;             PG8_LDA(At, 1, 1); PG8_STAGE(PG8_SA(1, 0), a3, voffA);
;             PG8_BAR; PG8_WAIT_L(0); PG8_MMA(1, 0, At, B0); PG8_BAR; PG8_SCHED;
	s_add_u32 s66, s34, 0x40000
	s_addc_u32 s67, s35, 0
	s_add_i32 s68, s55, s43
	s_mov_b32 m0, s68
	s_nop 0
	global_load_lds_dwordx4 v130, s[66:67]
	s_add_i32 m0, s68, 0x2000
	s_nop 0
	global_load_lds_dwordx4 v134, s[66:67]
	s_waitcnt vmcnt(10)
	s_barrier
	s_setprio 1
	v_mfma_f32_16x16x32_bf16 v[48:51], v[202:205], v[166:169], 0
	v_mfma_f32_16x16x32_bf16 v[40:43], v[210:213], v[166:169], 0
	v_mfma_f32_16x16x32_bf16 v[32:35], v[202:205], v[174:177], 0
	v_mfma_f32_16x16x32_bf16 v[24:27], v[210:213], v[174:177], 0
	v_mfma_f32_16x16x32_bf16 v[16:19], v[202:205], v[182:185], 0
	v_mfma_f32_16x16x32_bf16 v[8:11], v[210:213], v[182:185], 0
	v_mfma_f32_16x16x32_bf16 v[4:7], v[202:205], v[190:193], 0
	v_mfma_f32_16x16x32_bf16 v[0:3], v[210:213], v[190:193], 0
	v_mfma_f32_16x16x32_bf16 v[48:51], v[206:209], v[170:173], v[48:51]
	v_mfma_f32_16x16x32_bf16 v[40:43], v[214:217], v[170:173], v[40:43]
	v_mfma_f32_16x16x32_bf16 v[32:35], v[206:209], v[178:181], v[32:35]
	v_mfma_f32_16x16x32_bf16 v[24:27], v[214:217], v[178:181], v[24:27]
	v_mfma_f32_16x16x32_bf16 v[16:19], v[206:209], v[186:189], v[16:19]
	v_mfma_f32_16x16x32_bf16 v[8:11], v[214:217], v[186:189], v[8:11]
	v_mfma_f32_16x16x32_bf16 v[4:7], v[206:209], v[194:197], v[4:7]
	v_mfma_f32_16x16x32_bf16 v[0:3], v[214:217], v[194:197], v[0:3]
	s_setprio 0
	s_add_i32 s66, 0, 0x18000
	v_add_u32_e32 v162, s66, v146
	s_barrier
	ds_read_b128 v[150:153], v162
	ds_read_b128 v[154:157], v162 offset:1024
	ds_read_b128 v[158:161], v162 offset:2048
	ds_read_b128 v[162:165], v162 offset:3072
	s_add_u32 s36, s36, 0x40000
	s_addc_u32 s37, s37, 0
	s_mov_b32 m0, s45
	ds_read_b128 v[166:169], v148 offset:32768
	ds_read_b128 v[170:173], v148 offset:33792
	ds_read_b128 v[174:177], v148 offset:34816
	ds_read_b128 v[178:181], v148 offset:35840
	ds_read_b128 v[182:185], v148 offset:36864
	ds_read_b128 v[186:189], v148 offset:37888
	ds_read_b128 v[190:193], v148 offset:38912
	ds_read_b128 v[194:197], v148 offset:39936
	global_load_lds_dwordx4 v128, s[36:37]
	s_mov_b32 m0, s46
	s_nop 0
	global_load_lds_dwordx4 v132, s[36:37]
	s_waitcnt lgkmcnt(8)
	s_waitcnt vmcnt(10)
	s_barrier
	s_waitcnt lgkmcnt(0)
	s_setprio 1
	s_waitcnt lgkmcnt(0)
	v_mfma_f32_16x16x32_bf16 v[124:127], v[150:153], v[166:169], v[124:127]
	v_mfma_f32_16x16x32_bf16 v[120:123], v[158:161], v[166:169], v[120:123]
	v_mfma_f32_16x16x32_bf16 v[116:119], v[150:153], v[174:177], v[116:119]
	v_mfma_f32_16x16x32_bf16 v[108:111], v[158:161], v[174:177], v[108:111]
	v_mfma_f32_16x16x32_bf16 v[100:103], v[150:153], v[182:185], v[100:103]
	v_mfma_f32_16x16x32_bf16 v[92:95], v[158:161], v[182:185], v[92:95]
	v_mfma_f32_16x16x32_bf16 v[84:87], v[150:153], v[190:193], v[84:87]
	v_mfma_f32_16x16x32_bf16 v[76:79], v[158:161], v[190:193], v[76:79]
	v_mfma_f32_16x16x32_bf16 v[124:127], v[154:157], v[170:173], v[124:127]
	v_mfma_f32_16x16x32_bf16 v[120:123], v[162:165], v[170:173], v[120:123]
	v_mfma_f32_16x16x32_bf16 v[116:119], v[154:157], v[178:181], v[116:119]
	v_mfma_f32_16x16x32_bf16 v[108:111], v[162:165], v[178:181], v[108:111]
	v_mfma_f32_16x16x32_bf16 v[100:103], v[154:157], v[186:189], v[100:103]
	v_mfma_f32_16x16x32_bf16 v[92:95], v[162:165], v[186:189], v[92:95]
	v_mfma_f32_16x16x32_bf16 v[84:87], v[154:157], v[194:197], v[84:87]
	v_mfma_f32_16x16x32_bf16 v[76:79], v[162:165], v[194:197], v[76:79]
	s_setprio 0
	s_barrier
	s_add_i32 s36, 0, 0x1c000
	s_add_i32 s37, s66, s43
	v_add_u32_e32 v214, s36, v146
	s_add_u32 s4, s34, 0x80
	s_addc_u32 s5, s35, 0
	s_mov_b32 m0, s37
	ds_read_b128 v[202:205], v214
	ds_read_b128 v[206:209], v214 offset:1024
	ds_read_b128 v[210:213], v214 offset:2048
	ds_read_b128 v[214:217], v214 offset:3072
	global_load_lds_dwordx4 v130, s[4:5]
	s_add_i32 m0, s37, 0x2000
	s_nop 0
	global_load_lds_dwordx4 v134, s[4:5]
	s_waitcnt vmcnt(10)
	s_barrier
	s_waitcnt lgkmcnt(0)
	s_setprio 1
	s_waitcnt lgkmcnt(0)
	v_mfma_f32_16x16x32_bf16 v[112:115], v[202:205], v[166:169], v[112:115]
	v_mfma_f32_16x16x32_bf16 v[104:107], v[210:213], v[166:169], v[104:107]
	v_mfma_f32_16x16x32_bf16 v[96:99], v[202:205], v[174:177], v[96:99]
	v_mfma_f32_16x16x32_bf16 v[88:91], v[210:213], v[174:177], v[88:91]
	v_mfma_f32_16x16x32_bf16 v[80:83], v[202:205], v[182:185], v[80:83]
	v_mfma_f32_16x16x32_bf16 v[72:75], v[210:213], v[182:185], v[72:75]
	v_mfma_f32_16x16x32_bf16 v[68:71], v[202:205], v[190:193], v[68:71]
	v_mfma_f32_16x16x32_bf16 v[64:67], v[210:213], v[190:193], v[64:67]
	v_mfma_f32_16x16x32_bf16 v[112:115], v[206:209], v[170:173], v[112:115]
	v_mfma_f32_16x16x32_bf16 v[104:107], v[214:217], v[170:173], v[104:107]
	v_mfma_f32_16x16x32_bf16 v[96:99], v[206:209], v[178:181], v[96:99]
	v_mfma_f32_16x16x32_bf16 v[88:91], v[214:217], v[178:181], v[88:91]
	v_mfma_f32_16x16x32_bf16 v[80:83], v[206:209], v[186:189], v[80:83]
	v_mfma_f32_16x16x32_bf16 v[72:75], v[214:217], v[186:189], v[72:75]
	v_mfma_f32_16x16x32_bf16 v[68:71], v[206:209], v[194:197], v[68:71]
	v_mfma_f32_16x16x32_bf16 v[64:67], v[214:217], v[194:197], v[64:67]
	s_setprio 0
	s_mov_b32 m0, s51
	s_mov_b64 s[4:5], 0x80
	v_lshl_add_u64 v[198:199], v[220:221], 0, s[4:5]
	s_barrier
	ds_read_b128 v[166:169], v148 offset:49152
	ds_read_b128 v[170:173], v148 offset:50176
	ds_read_b128 v[174:177], v148 offset:51200
	ds_read_b128 v[178:181], v148 offset:52224
	ds_read_b128 v[182:185], v148 offset:53248
	ds_read_b128 v[186:189], v148 offset:54272
	ds_read_b128 v[190:193], v148 offset:55296
	ds_read_b128 v[194:197], v148 offset:56320
	global_load_lds_dwordx4 v[198:199], off
	v_lshl_add_u64 v[198:199], v[222:223], 0, s[4:5]
	s_mov_b32 m0, s52
	s_nop 0
	global_load_lds_dwordx4 v[198:199], off
	s_barrier
; #define PG8_STAGE(bufoff, gbase, voff) do { _Pragma("unroll") for (int _i = 0; _i < 2; ++_i) \
;         __builtin_amdgcn_global_load_lds((const unsigned*)((const char*)(gbase) + (voff)[_i]), (LAS unsigned*)(lds + (bufoff) + ldsw + _i * 8192), 16, 0, 0); } while (0)
; #define PG8_LDA(dst, b, h) do { _Pragma("unroll") for (int m = 0; m < 4; ++m) _Pragma("unroll") for (int k = 0; k < 2; ++k) dst[m][k] = *(const LAS bf16x8*)(lds + PG8_SA(b, h) + aoff + m * 2048 + k * 1024); } while (0)
; #define PG8_LDB(dst, b, h) do { _Pragma("unroll") for (int n = 0; n < 2; ++n) _Pragma("unroll") for (int k = 0; k < 2; ++k) dst[n][k] = *(const LAS bf16x8*)(lds + PG8_SB(b, h) + boff + n * 2048 + k * 1024); } while (0)
; #define PG8_WAIT_V(n) asm volatile("s_waitcnt vmcnt(" #n ")" ::: "memory")
; #define PG8_WAIT_L(n) asm volatile("s_waitcnt lgkmcnt(" #n ")" ::: "memory")
; #define PG8_BAR __builtin_amdgcn_s_barrier()
; #define PG8_SCHED __builtin_amdgcn_sched_barrier(0)
; template <class Epi, class Sched>
; __device__ __forceinline__ void gemm_phase(LAS unsigned char* lds, const Gemm g, const Sched& S, const Epi& E) {
;     ...
;             PG8_LDB(B0, 0, 0); PG8_SCHED; PG8_LDA(At, 0, 0); PG8_STAGE(PG8_SA(1, 1), a1 + hstep, voffA);
;             PG8_WAIT_L(8); PG8_BAR; PG8_WAIT_L(0); PG8_MMA(0, 0, At, B0); PG8_BAR; PG8_SCHED;
;             PG8_LDB(B1, 0, 1); PG8_STAGE(PG8_SB(0, 0), b2, voffB);
;             PG8_BAR; PG8_WAIT_L(0); PG8_MMA(0, 1, At, B1); PG8_BAR;
;             PG8_LDA(At, 0, 1); PG8_STAGE(PG8_SA(0, 0), a2, voffA);
;             PG8_BAR; PG8_WAIT_L(0); PG8_MMA(1, 0, At, B0); PG8_BAR; PG8_SCHED;
;             PG8_STAGE(PG8_SB(0, 1), b2 + hstep, voffB);
;             PG8_WAIT_V(6); PG8_BAR; PG8_MMA(1, 1, At, B1); PG8_BAR;
;             PG8_LDB(B0, 1, 0); PG8_SCHED; PG8_LDA(At, 1, 0); PG8_STAGE(PG8_SA(0, 1), a2 + hstep, voffA);
;             PG8_WAIT_L(8); PG8_BAR; PG8_WAIT_L(0); PG8_MMA(0, 0, At, B0); PG8_BAR; PG8_SCHED;
;             PG8_LDB(B1, 1, 1); PG8_STAGE(PG8_SB(1, 0), b3, voffB);
;             PG8_BAR; PG8_WAIT_L(0); PG8_MMA(0, 1, At, B1); PG8_BAR;
;             PG8_LDA(At, 1, 1); PG8_STAGE(PG8_SA(1, 0), a3, voffA);
;             PG8_BAR; PG8_WAIT_L(0); PG8_MMA(1, 0, At, B0); PG8_BAR; PG8_SCHED;
;             PG8_STAGE(PG8_SB(1, 1), b3 + hstep, voffB);
;             PG8_WAIT_V(6); PG8_BAR; PG8_MMA(1, 1, At, B1); PG8_BAR;
	s_waitcnt lgkmcnt(0)
	s_setprio 1
	s_waitcnt lgkmcnt(0)
	v_mfma_f32_16x16x32_bf16 v[60:63], v[150:153], v[166:169], v[60:63]
	v_mfma_f32_16x16x32_bf16 v[56:59], v[158:161], v[166:169], v[56:59]
	v_mfma_f32_16x16x32_bf16 v[52:55], v[150:153], v[174:177], v[52:55]
	v_mfma_f32_16x16x32_bf16 v[44:47], v[158:161], v[174:177], v[44:47]
	v_mfma_f32_16x16x32_bf16 v[36:39], v[150:153], v[182:185], v[36:39]
	v_mfma_f32_16x16x32_bf16 v[28:31], v[158:161], v[182:185], v[28:31]
	v_mfma_f32_16x16x32_bf16 v[20:23], v[150:153], v[190:193], v[20:23]
	v_mfma_f32_16x16x32_bf16 v[12:15], v[158:161], v[190:193], v[12:15]
	v_mfma_f32_16x16x32_bf16 v[60:63], v[154:157], v[170:173], v[60:63]
	v_mfma_f32_16x16x32_bf16 v[56:59], v[162:165], v[170:173], v[56:59]
	v_mfma_f32_16x16x32_bf16 v[52:55], v[154:157], v[178:181], v[52:55]
	v_mfma_f32_16x16x32_bf16 v[44:47], v[162:165], v[178:181], v[44:47]
	v_mfma_f32_16x16x32_bf16 v[36:39], v[154:157], v[186:189], v[36:39]
	v_mfma_f32_16x16x32_bf16 v[28:31], v[162:165], v[186:189], v[28:31]
	v_mfma_f32_16x16x32_bf16 v[20:23], v[154:157], v[194:197], v[20:23]
	v_mfma_f32_16x16x32_bf16 v[12:15], v[162:165], v[194:197], v[12:15]
	s_setprio 0
	s_barrier
	s_add_u32 s34, s34, 0x40080
	s_addc_u32 s35, s35, 0
	s_add_i32 s36, s36, s43
	s_mov_b32 m0, s36
	s_nop 0
	global_load_lds_dwordx4 v130, s[34:35]
	s_add_i32 m0, s36, 0x2000
	s_nop 0
	global_load_lds_dwordx4 v134, s[34:35]
	s_waitcnt vmcnt(10)
	s_barrier
	s_setprio 1
	v_mfma_f32_16x16x32_bf16 v[48:51], v[202:205], v[166:169], v[48:51]
	v_mfma_f32_16x16x32_bf16 v[40:43], v[210:213], v[166:169], v[40:43]
	v_mfma_f32_16x16x32_bf16 v[32:35], v[202:205], v[174:177], v[32:35]
	v_mfma_f32_16x16x32_bf16 v[24:27], v[210:213], v[174:177], v[24:27]
	v_mfma_f32_16x16x32_bf16 v[16:19], v[202:205], v[182:185], v[16:19]
	v_mfma_f32_16x16x32_bf16 v[8:11], v[210:213], v[182:185], v[8:11]
	v_mfma_f32_16x16x32_bf16 v[4:7], v[202:205], v[190:193], v[4:7]
	v_mfma_f32_16x16x32_bf16 v[0:3], v[210:213], v[190:193], v[0:3]
	v_mfma_f32_16x16x32_bf16 v[48:51], v[206:209], v[170:173], v[48:51]
	v_mfma_f32_16x16x32_bf16 v[40:43], v[214:217], v[170:173], v[40:43]
	v_mfma_f32_16x16x32_bf16 v[32:35], v[206:209], v[178:181], v[32:35]
	v_mfma_f32_16x16x32_bf16 v[24:27], v[214:217], v[178:181], v[24:27]
	v_mfma_f32_16x16x32_bf16 v[16:19], v[206:209], v[186:189], v[16:19]
	v_mfma_f32_16x16x32_bf16 v[8:11], v[214:217], v[186:189], v[8:11]
	v_mfma_f32_16x16x32_bf16 v[4:7], v[206:209], v[194:197], v[4:7]
	v_mfma_f32_16x16x32_bf16 v[0:3], v[214:217], v[194:197], v[0:3]
	s_setprio 0
	s_add_i32 s65, s65, 2
	s_add_u32 s30, s30, 0x100
	s_addc_u32 s31, s31, 0
	s_add_u32 s63, s63, 0x100
	s_addc_u32 s64, s64, 0
	s_cmp_gt_u32 s65, 13
	s_barrier
.LBB0_633:
	ds_read_b128 v[150:153], v147
	ds_read_b128 v[154:157], v147 offset:1024
	ds_read_b128 v[158:161], v147 offset:2048
	ds_read_b128 v[162:165], v147 offset:3072
	s_add_u32 s34, s30, 0xfffc0080
	s_addc_u32 s35, s31, -1
	s_cmp_eq_u32 s65, 12
	s_cselect_b32 s37, s23, s35
	s_cselect_b32 s36, s61, s34
	s_cselect_b32 s35, s21, s64
	s_cselect_b32 s34, s62, s63
	s_add_i32 m0, s29, 0xc000
	ds_read_b128 v[166:169], v148
	ds_read_b128 v[170:173], v148 offset:1024
	ds_read_b128 v[174:177], v148 offset:2048
	ds_read_b128 v[178:181], v148 offset:3072
	ds_read_b128 v[182:185], v148 offset:4096
	ds_read_b128 v[186:189], v148 offset:5120
	ds_read_b128 v[190:193], v148 offset:6144
	ds_read_b128 v[194:197], v148 offset:7168
	global_load_lds_dwordx4 v136, s[30:31]
	s_add_i32 m0, s29, 0xe000
	s_nop 0
	global_load_lds_dwordx4 v138, s[30:31]
	s_waitcnt lgkmcnt(8)
	s_waitcnt vmcnt(10)
	s_barrier
	s_waitcnt lgkmcnt(0)
	s_setprio 1
	s_waitcnt lgkmcnt(0)
	v_mfma_f32_16x16x32_bf16 v[124:127], v[150:153], v[166:169], v[124:127]
	v_mfma_f32_16x16x32_bf16 v[120:123], v[158:161], v[166:169], v[120:123]
	v_mfma_f32_16x16x32_bf16 v[116:119], v[150:153], v[174:177], v[116:119]
	v_mfma_f32_16x16x32_bf16 v[108:111], v[158:161], v[174:177], v[108:111]
	v_mfma_f32_16x16x32_bf16 v[100:103], v[150:153], v[182:185], v[100:103]
	v_mfma_f32_16x16x32_bf16 v[92:95], v[158:161], v[182:185], v[92:95]
	v_mfma_f32_16x16x32_bf16 v[84:87], v[150:153], v[190:193], v[84:87]
	v_mfma_f32_16x16x32_bf16 v[76:79], v[158:161], v[190:193], v[76:79]
	v_mfma_f32_16x16x32_bf16 v[124:127], v[154:157], v[170:173], v[124:127]
	v_mfma_f32_16x16x32_bf16 v[120:123], v[162:165], v[170:173], v[120:123]
	v_mfma_f32_16x16x32_bf16 v[116:119], v[154:157], v[178:181], v[116:119]
	v_mfma_f32_16x16x32_bf16 v[108:111], v[162:165], v[178:181], v[108:111]
	v_mfma_f32_16x16x32_bf16 v[100:103], v[154:157], v[186:189], v[100:103]
	v_mfma_f32_16x16x32_bf16 v[92:95], v[162:165], v[186:189], v[92:95]
	v_mfma_f32_16x16x32_bf16 v[84:87], v[154:157], v[194:197], v[84:87]
	v_mfma_f32_16x16x32_bf16 v[76:79], v[162:165], v[194:197], v[76:79]
	s_setprio 0
	s_barrier
	s_add_i32 s66, s54, s43
	s_mov_b32 m0, s66
	ds_read_b128 v[202:205], v149
	ds_read_b128 v[206:209], v149 offset:1024
	ds_read_b128 v[210:213], v149 offset:2048
	ds_read_b128 v[214:217], v149 offset:3072
	global_load_lds_dwordx4 v130, s[34:35]
	s_add_i32 m0, s66, 0x2000
	s_nop 0
	global_load_lds_dwordx4 v134, s[34:35]
	s_waitcnt vmcnt(10)
	s_barrier
; #define PG8_STAGE(bufoff, gbase, voff) do { _Pragma("unroll") for (int _i = 0; _i < 2; ++_i) \
;         __builtin_amdgcn_global_load_lds((const unsigned*)((const char*)(gbase) + (voff)[_i]), (LAS unsigned*)(lds + (bufoff) + ldsw + _i * 8192), 16, 0, 0); } while (0)
; #define PG8_LDA(dst, b, h) do { _Pragma("unroll") for (int m = 0; m < 4; ++m) _Pragma("unroll") for (int k = 0; k < 2; ++k) dst[m][k] = *(const LAS bf16x8*)(lds + PG8_SA(b, h) + aoff + m * 2048 + k * 1024); } while (0)
; #define PG8_LDB(dst, b, h) do { _Pragma("unroll") for (int n = 0; n < 2; ++n) _Pragma("unroll") for (int k = 0; k < 2; ++k) dst[n][k] = *(const LAS bf16x8*)(lds + PG8_SB(b, h) + boff + n * 2048 + k * 1024); } while (0)
; #define PG8_MMA(ai, bj, At, Bt) do { __builtin_amdgcn_s_setprio(1); _Pragma("unroll") for (int m = 0; m < 4; ++m) _Pragma("unroll") for (int n = 0; n < 2; ++n) _Pragma("unroll") for (int k = 0; k < 2; ++k) \
;         acc[ai][bj][m][n] = __builtin_amdgcn_mfma_f32_16x16x32_bf16(Bt[n][k], At[m][k], acc[ai][bj][m][n], 0, 0, 0); __builtin_amdgcn_s_setprio(0); } while (0)
; #define PG8_WAIT_V(n) asm volatile("s_waitcnt vmcnt(" #n ")" ::: "memory")
; #define PG8_WAIT_L(n) asm volatile("s_waitcnt lgkmcnt(" #n ")" ::: "memory")
; #define PG8_BAR __builtin_amdgcn_s_barrier()
; #define PG8_SCHED __builtin_amdgcn_sched_barrier(0)
; template <class Epi, class Sched>
; __device__ __forceinline__ void gemm_phase(LAS unsigned char* lds, const Gemm g, const Sched& S, const Epi& E) {
;     ...
;             PG8_BAR; PG8_WAIT_L(0); PG8_MMA(0, 1, At, B1); PG8_BAR;
;             PG8_LDA(At, 0, 1); PG8_STAGE(PG8_SA(0, 0), a2, voffA);
;             PG8_BAR; PG8_WAIT_L(0); PG8_MMA(1, 0, At, B0); PG8_BAR; PG8_SCHED;
;             PG8_STAGE(PG8_SB(0, 1), b2 + hstep, voffB);
;             PG8_WAIT_V(6); PG8_BAR; PG8_MMA(1, 1, At, B1); PG8_BAR;
;             PG8_LDB(B0, 1, 0); PG8_SCHED; PG8_LDA(At, 1, 0); PG8_STAGE(PG8_SA(0, 1), a2 + hstep, voffA);
	s_waitcnt lgkmcnt(0)
	s_setprio 1
	s_waitcnt lgkmcnt(0)
	v_mfma_f32_16x16x32_bf16 v[112:115], v[202:205], v[166:169], v[112:115]
	v_mfma_f32_16x16x32_bf16 v[104:107], v[210:213], v[166:169], v[104:107]
	v_mfma_f32_16x16x32_bf16 v[96:99], v[202:205], v[174:177], v[96:99]
	v_mfma_f32_16x16x32_bf16 v[88:91], v[210:213], v[174:177], v[88:91]
	v_mfma_f32_16x16x32_bf16 v[80:83], v[202:205], v[182:185], v[80:83]
	v_mfma_f32_16x16x32_bf16 v[72:75], v[210:213], v[182:185], v[72:75]
	v_mfma_f32_16x16x32_bf16 v[68:71], v[202:205], v[190:193], v[68:71]
	v_mfma_f32_16x16x32_bf16 v[64:67], v[210:213], v[190:193], v[64:67]
	v_mfma_f32_16x16x32_bf16 v[112:115], v[206:209], v[170:173], v[112:115]
	v_mfma_f32_16x16x32_bf16 v[104:107], v[214:217], v[170:173], v[104:107]
	v_mfma_f32_16x16x32_bf16 v[96:99], v[206:209], v[178:181], v[96:99]
	v_mfma_f32_16x16x32_bf16 v[88:91], v[214:217], v[178:181], v[88:91]
	v_mfma_f32_16x16x32_bf16 v[80:83], v[206:209], v[186:189], v[80:83]
	v_mfma_f32_16x16x32_bf16 v[72:75], v[214:217], v[186:189], v[72:75]
	v_mfma_f32_16x16x32_bf16 v[68:71], v[206:209], v[194:197], v[68:71]
	v_mfma_f32_16x16x32_bf16 v[64:67], v[214:217], v[194:197], v[64:67]
	s_setprio 0
	s_mov_b32 m0, s29
	v_lshl_add_u64 v[220:221], s[36:37], 0, v[128:129]
	s_barrier
	ds_read_b128 v[166:169], v148 offset:16384
	ds_read_b128 v[170:173], v148 offset:17408
	ds_read_b128 v[174:177], v148 offset:18432
	ds_read_b128 v[178:181], v148 offset:19456
	ds_read_b128 v[182:185], v148 offset:20480
	ds_read_b128 v[186:189], v148 offset:21504
	ds_read_b128 v[190:193], v148 offset:22528
	ds_read_b128 v[194:197], v148 offset:23552
	global_load_lds_dwordx4 v128, s[36:37]
	v_lshl_add_u64 v[222:223], s[36:37], 0, v[132:133]
	s_mov_b32 m0, s44
	s_nop 0
	global_load_lds_dwordx4 v132, s[36:37]
	s_barrier
	s_waitcnt lgkmcnt(0)
	s_setprio 1
	s_waitcnt lgkmcnt(0)
	v_mfma_f32_16x16x32_bf16 v[60:63], v[150:153], v[166:169], v[60:63]
	v_mfma_f32_16x16x32_bf16 v[56:59], v[158:161], v[166:169], v[56:59]
	v_mfma_f32_16x16x32_bf16 v[52:55], v[150:153], v[174:177], v[52:55]
	v_mfma_f32_16x16x32_bf16 v[44:47], v[158:161], v[174:177], v[44:47]
	v_mfma_f32_16x16x32_bf16 v[36:39], v[150:153], v[182:185], v[36:39]
	v_mfma_f32_16x16x32_bf16 v[28:31], v[158:161], v[182:185], v[28:31]
	v_mfma_f32_16x16x32_bf16 v[20:23], v[150:153], v[190:193], v[20:23]
	v_mfma_f32_16x16x32_bf16 v[12:15], v[158:161], v[190:193], v[12:15]
	v_mfma_f32_16x16x32_bf16 v[60:63], v[154:157], v[170:173], v[60:63]
	v_mfma_f32_16x16x32_bf16 v[56:59], v[162:165], v[170:173], v[56:59]
	v_mfma_f32_16x16x32_bf16 v[52:55], v[154:157], v[178:181], v[52:55]
	v_mfma_f32_16x16x32_bf16 v[44:47], v[162:165], v[178:181], v[44:47]
	v_mfma_f32_16x16x32_bf16 v[36:39], v[154:157], v[186:189], v[36:39]
	v_mfma_f32_16x16x32_bf16 v[28:31], v[162:165], v[186:189], v[28:31]
	v_mfma_f32_16x16x32_bf16 v[20:23], v[154:157], v[194:197], v[20:23]
	v_mfma_f32_16x16x32_bf16 v[12:15], v[162:165], v[194:197], v[12:15]
	s_setprio 0
	s_barrier
	s_add_u32 s66, s34, 0x40000
	s_addc_u32 s67, s35, 0
	s_add_i32 s68, s55, s43
	s_mov_b32 m0, s68
	s_nop 0
	global_load_lds_dwordx4 v130, s[66:67]
	s_add_i32 m0, s68, 0x2000
	s_nop 0
	global_load_lds_dwordx4 v134, s[66:67]
	s_waitcnt vmcnt(10)
	s_barrier
	s_setprio 1
	v_mfma_f32_16x16x32_bf16 v[48:51], v[202:205], v[166:169], v[48:51]
	v_mfma_f32_16x16x32_bf16 v[40:43], v[210:213], v[166:169], v[40:43]
	v_mfma_f32_16x16x32_bf16 v[32:35], v[202:205], v[174:177], v[32:35]
	v_mfma_f32_16x16x32_bf16 v[24:27], v[210:213], v[174:177], v[24:27]
	v_mfma_f32_16x16x32_bf16 v[16:19], v[202:205], v[182:185], v[16:19]
	v_mfma_f32_16x16x32_bf16 v[8:11], v[210:213], v[182:185], v[8:11]
	v_mfma_f32_16x16x32_bf16 v[4:7], v[202:205], v[190:193], v[4:7]
	v_mfma_f32_16x16x32_bf16 v[0:3], v[210:213], v[190:193], v[0:3]
	v_mfma_f32_16x16x32_bf16 v[48:51], v[206:209], v[170:173], v[48:51]
	v_mfma_f32_16x16x32_bf16 v[40:43], v[214:217], v[170:173], v[40:43]
	v_mfma_f32_16x16x32_bf16 v[32:35], v[206:209], v[178:181], v[32:35]
	v_mfma_f32_16x16x32_bf16 v[24:27], v[214:217], v[178:181], v[24:27]
	v_mfma_f32_16x16x32_bf16 v[16:19], v[206:209], v[186:189], v[16:19]
	v_mfma_f32_16x16x32_bf16 v[8:11], v[214:217], v[186:189], v[8:11]
	v_mfma_f32_16x16x32_bf16 v[4:7], v[206:209], v[194:197], v[4:7]
	v_mfma_f32_16x16x32_bf16 v[0:3], v[214:217], v[194:197], v[0:3]
	s_setprio 0
	s_add_i32 s66, 0, 0x18000
	v_add_u32_e32 v162, s66, v146
	s_barrier
	ds_read_b128 v[150:153], v162
	ds_read_b128 v[154:157], v162 offset:1024
	ds_read_b128 v[158:161], v162 offset:2048
	ds_read_b128 v[162:165], v162 offset:3072
	s_add_u32 s36, s36, 0x40000
	s_addc_u32 s37, s37, 0
	s_mov_b32 m0, s45
	ds_read_b128 v[166:169], v148 offset:32768
	ds_read_b128 v[170:173], v148 offset:33792
	ds_read_b128 v[174:177], v148 offset:34816
	ds_read_b128 v[178:181], v148 offset:35840
	ds_read_b128 v[182:185], v148 offset:36864
	ds_read_b128 v[186:189], v148 offset:37888
	ds_read_b128 v[190:193], v148 offset:38912
	ds_read_b128 v[194:197], v148 offset:39936
	global_load_lds_dwordx4 v128, s[36:37]
	s_mov_b32 m0, s46
	s_nop 0
	global_load_lds_dwordx4 v132, s[36:37]
	s_waitcnt lgkmcnt(8)
	s_waitcnt vmcnt(10)
	s_barrier
; #define PG8_STAGE(bufoff, gbase, voff) do { _Pragma("unroll") for (int _i = 0; _i < 2; ++_i) \
;         __builtin_amdgcn_global_load_lds((const unsigned*)((const char*)(gbase) + (voff)[_i]), (LAS unsigned*)(lds + (bufoff) + ldsw + _i * 8192), 16, 0, 0); } while (0)
; #define PG8_LDA(dst, b, h) do { _Pragma("unroll") for (int m = 0; m < 4; ++m) _Pragma("unroll") for (int k = 0; k < 2; ++k) dst[m][k] = *(const LAS bf16x8*)(lds + PG8_SA(b, h) + aoff + m * 2048 + k * 1024); } while (0)
; #define PG8_LDB(dst, b, h) do { _Pragma("unroll") for (int n = 0; n < 2; ++n) _Pragma("unroll") for (int k = 0; k < 2; ++k) dst[n][k] = *(const LAS bf16x8*)(lds + PG8_SB(b, h) + boff + n * 2048 + k * 1024); } while (0)
; #define PG8_MMA(ai, bj, At, Bt) do { __builtin_amdgcn_s_setprio(1); _Pragma("unroll") for (int m = 0; m < 4; ++m) _Pragma("unroll") for (int n = 0; n < 2; ++n) _Pragma("unroll") for (int k = 0; k < 2; ++k) \
;         acc[ai][bj][m][n] = __builtin_amdgcn_mfma_f32_16x16x32_bf16(Bt[n][k], At[m][k], acc[ai][bj][m][n], 0, 0, 0); __builtin_amdgcn_s_setprio(0); } while (0)
; #define PG8_WAIT_V(n) asm volatile("s_waitcnt vmcnt(" #n ")" ::: "memory")
; #define PG8_WAIT_L(n) asm volatile("s_waitcnt lgkmcnt(" #n ")" ::: "memory")
; #define PG8_BAR __builtin_amdgcn_s_barrier()
; #define PG8_SCHED __builtin_amdgcn_sched_barrier(0)
; template <class Epi, class Sched>
; __device__ __forceinline__ void gemm_phase(LAS unsigned char* lds, const Gemm g, const Sched& S, const Epi& E) {
;     ...
;             PG8_WAIT_L(8); PG8_BAR; PG8_WAIT_L(0); PG8_MMA(0, 0, At, B0); PG8_BAR; PG8_SCHED;
;             PG8_LDB(B1, 1, 1); PG8_STAGE(PG8_SB(1, 0), b3, voffB);
;             PG8_BAR; PG8_WAIT_L(0); PG8_MMA(0, 1, At, B1); PG8_BAR;
;             PG8_LDA(At, 1, 1); PG8_STAGE(PG8_SA(1, 0), a3, voffA);
;             PG8_BAR; PG8_WAIT_L(0); PG8_MMA(1, 0, At, B0); PG8_BAR; PG8_SCHED;
;             PG8_STAGE(PG8_SB(1, 1), b3 + hstep, voffB);
;             PG8_WAIT_V(6); PG8_BAR; PG8_MMA(1, 1, At, B1); PG8_BAR;
	s_waitcnt lgkmcnt(0)
	s_setprio 1
	s_waitcnt lgkmcnt(0)
	v_mfma_f32_16x16x32_bf16 v[124:127], v[150:153], v[166:169], v[124:127]
	v_mfma_f32_16x16x32_bf16 v[120:123], v[158:161], v[166:169], v[120:123]
	v_mfma_f32_16x16x32_bf16 v[116:119], v[150:153], v[174:177], v[116:119]
	v_mfma_f32_16x16x32_bf16 v[108:111], v[158:161], v[174:177], v[108:111]
	v_mfma_f32_16x16x32_bf16 v[100:103], v[150:153], v[182:185], v[100:103]
	v_mfma_f32_16x16x32_bf16 v[92:95], v[158:161], v[182:185], v[92:95]
	v_mfma_f32_16x16x32_bf16 v[84:87], v[150:153], v[190:193], v[84:87]
	v_mfma_f32_16x16x32_bf16 v[76:79], v[158:161], v[190:193], v[76:79]
	v_mfma_f32_16x16x32_bf16 v[124:127], v[154:157], v[170:173], v[124:127]
	v_mfma_f32_16x16x32_bf16 v[120:123], v[162:165], v[170:173], v[120:123]
	v_mfma_f32_16x16x32_bf16 v[116:119], v[154:157], v[178:181], v[116:119]
	v_mfma_f32_16x16x32_bf16 v[108:111], v[162:165], v[178:181], v[108:111]
	v_mfma_f32_16x16x32_bf16 v[100:103], v[154:157], v[186:189], v[100:103]
	v_mfma_f32_16x16x32_bf16 v[92:95], v[162:165], v[186:189], v[92:95]
	v_mfma_f32_16x16x32_bf16 v[84:87], v[154:157], v[194:197], v[84:87]
	v_mfma_f32_16x16x32_bf16 v[76:79], v[162:165], v[194:197], v[76:79]
	s_setprio 0
	s_barrier
	s_add_i32 s36, 0, 0x1c000
	s_add_i32 s37, s66, s43
	v_add_u32_e32 v214, s36, v146
	s_add_u32 s4, s34, 0x80
	s_addc_u32 s5, s35, 0
	s_mov_b32 m0, s37
	ds_read_b128 v[202:205], v214
	ds_read_b128 v[206:209], v214 offset:1024
	ds_read_b128 v[210:213], v214 offset:2048
	ds_read_b128 v[214:217], v214 offset:3072
	global_load_lds_dwordx4 v130, s[4:5]
	s_add_i32 m0, s37, 0x2000
	s_nop 0
	global_load_lds_dwordx4 v134, s[4:5]
	s_waitcnt vmcnt(10)
	s_barrier
	s_waitcnt lgkmcnt(0)
	s_setprio 1
	s_waitcnt lgkmcnt(0)
	v_mfma_f32_16x16x32_bf16 v[112:115], v[202:205], v[166:169], v[112:115]
	v_mfma_f32_16x16x32_bf16 v[104:107], v[210:213], v[166:169], v[104:107]
	v_mfma_f32_16x16x32_bf16 v[96:99], v[202:205], v[174:177], v[96:99]
	v_mfma_f32_16x16x32_bf16 v[88:91], v[210:213], v[174:177], v[88:91]
	v_mfma_f32_16x16x32_bf16 v[80:83], v[202:205], v[182:185], v[80:83]
	v_mfma_f32_16x16x32_bf16 v[72:75], v[210:213], v[182:185], v[72:75]
	v_mfma_f32_16x16x32_bf16 v[68:71], v[202:205], v[190:193], v[68:71]
	v_mfma_f32_16x16x32_bf16 v[64:67], v[210:213], v[190:193], v[64:67]
	v_mfma_f32_16x16x32_bf16 v[112:115], v[206:209], v[170:173], v[112:115]
	v_mfma_f32_16x16x32_bf16 v[104:107], v[214:217], v[170:173], v[104:107]
	v_mfma_f32_16x16x32_bf16 v[96:99], v[206:209], v[178:181], v[96:99]
	v_mfma_f32_16x16x32_bf16 v[88:91], v[214:217], v[178:181], v[88:91]
	v_mfma_f32_16x16x32_bf16 v[80:83], v[206:209], v[186:189], v[80:83]
	v_mfma_f32_16x16x32_bf16 v[72:75], v[214:217], v[186:189], v[72:75]
	v_mfma_f32_16x16x32_bf16 v[68:71], v[206:209], v[194:197], v[68:71]
	v_mfma_f32_16x16x32_bf16 v[64:67], v[214:217], v[194:197], v[64:67]
	s_setprio 0
	s_mov_b32 m0, s51
	s_mov_b64 s[4:5], 0x80
	v_lshl_add_u64 v[198:199], v[220:221], 0, s[4:5]
	s_barrier
	ds_read_b128 v[166:169], v148 offset:49152
	ds_read_b128 v[170:173], v148 offset:50176
	ds_read_b128 v[174:177], v148 offset:51200
	ds_read_b128 v[178:181], v148 offset:52224
	ds_read_b128 v[182:185], v148 offset:53248
	ds_read_b128 v[186:189], v148 offset:54272
	ds_read_b128 v[190:193], v148 offset:55296
	ds_read_b128 v[194:197], v148 offset:56320
	global_load_lds_dwordx4 v[198:199], off
	v_lshl_add_u64 v[198:199], v[222:223], 0, s[4:5]
	s_mov_b32 m0, s52
	s_nop 0
	global_load_lds_dwordx4 v[198:199], off
	s_barrier
	s_waitcnt lgkmcnt(0)
	s_setprio 1
	s_waitcnt lgkmcnt(0)
	v_mfma_f32_16x16x32_bf16 v[60:63], v[150:153], v[166:169], v[60:63]
	v_mfma_f32_16x16x32_bf16 v[56:59], v[158:161], v[166:169], v[56:59]
	v_mfma_f32_16x16x32_bf16 v[52:55], v[150:153], v[174:177], v[52:55]
	v_mfma_f32_16x16x32_bf16 v[44:47], v[158:161], v[174:177], v[44:47]
	v_mfma_f32_16x16x32_bf16 v[36:39], v[150:153], v[182:185], v[36:39]
	v_mfma_f32_16x16x32_bf16 v[28:31], v[158:161], v[182:185], v[28:31]
	v_mfma_f32_16x16x32_bf16 v[20:23], v[150:153], v[190:193], v[20:23]
	v_mfma_f32_16x16x32_bf16 v[12:15], v[158:161], v[190:193], v[12:15]
	v_mfma_f32_16x16x32_bf16 v[60:63], v[154:157], v[170:173], v[60:63]
	v_mfma_f32_16x16x32_bf16 v[56:59], v[162:165], v[170:173], v[56:59]
	v_mfma_f32_16x16x32_bf16 v[52:55], v[154:157], v[178:181], v[52:55]
	v_mfma_f32_16x16x32_bf16 v[44:47], v[162:165], v[178:181], v[44:47]
	v_mfma_f32_16x16x32_bf16 v[36:39], v[154:157], v[186:189], v[36:39]
	v_mfma_f32_16x16x32_bf16 v[28:31], v[162:165], v[186:189], v[28:31]
	v_mfma_f32_16x16x32_bf16 v[20:23], v[154:157], v[194:197], v[20:23]
	v_mfma_f32_16x16x32_bf16 v[12:15], v[162:165], v[194:197], v[12:15]
	s_setprio 0
	s_barrier
	s_add_u32 s34, s34, 0x40080
	s_addc_u32 s35, s35, 0
	s_add_i32 s36, s36, s43
	s_mov_b32 m0, s36
	s_nop 0
	global_load_lds_dwordx4 v130, s[34:35]
	s_add_i32 m0, s36, 0x2000
	s_nop 0
	global_load_lds_dwordx4 v134, s[34:35]
	s_waitcnt vmcnt(10)
	s_barrier
; __device__ __forceinline__ unsigned cvt_pk_bf16(float lo, float hi) { unsigned r; asm volatile("v_cvt_pk_bf16_f32 %0, %1, %2" : "=v"(r) : "v"(lo), "v"(hi)); return r; }
; #define PG8_STAGE(bufoff, gbase, voff) do { _Pragma("unroll") for (int _i = 0; _i < 2; ++_i) \
;         __builtin_amdgcn_global_load_lds((const unsigned*)((const char*)(gbase) + (voff)[_i]), (LAS unsigned*)(lds + (bufoff) + ldsw + _i * 8192), 16, 0, 0); } while (0)
; #define PG8_MMA(ai, bj, At, Bt) do { __builtin_amdgcn_s_setprio(1); _Pragma("unroll") for (int m = 0; m < 4; ++m) _Pragma("unroll") for (int n = 0; n < 2; ++n) _Pragma("unroll") for (int k = 0; k < 2; ++k) \
;         acc[ai][bj][m][n] = __builtin_amdgcn_mfma_f32_16x16x32_bf16(Bt[n][k], At[m][k], acc[ai][bj][m][n], 0, 0, 0); __builtin_amdgcn_s_setprio(0); } while (0)
; #define PG8_WAIT_V(n) asm volatile("s_waitcnt vmcnt(" #n ")" ::: "memory")
; #define PG8_BAR __builtin_amdgcn_s_barrier()
; template <class Epi, class Sched>
; __device__ __forceinline__ void gemm_phase(LAS unsigned char* lds, const Gemm g, const Sched& S, const Epi& E) {
;     ...
;             PG8_STAGE(PG8_SB(1, 1), b3 + hstep, voffB);
;             PG8_WAIT_V(6); PG8_BAR; PG8_MMA(1, 1, At, B1); PG8_BAR;
;     __device__ __forceinline__ void operator()(const AccT& acc, const Unit& u, int wr, int wc, int fr, int fq) const {
;         asm volatile("" : "+v"(fr), "+v"(fq));
;         const int rbase = u.pm * 256 + wr * 64 + fr;
;         const int tb = u.pn * 256 + wc * 32 + 8 * fq;
; #pragma unroll
;         for (int ai = 0; ai < 2; ++ai)
; #pragma unroll
;             for (int m = 0; m < 4; ++m) {
;                 const int r = rbase + ai * 128 + m * 16;
; #pragma unroll
;                 for (int bj = 0; bj < 2; ++bj) {
;                     const int t0 = tb + bj * 128;
;                     const f32x4 v0 = acc[ai][bj][m][0], v1 = acc[ai][bj][m][1];
;                     u32x4 w; w.x = cvt_pk_bf16(v0[0], v0[1]); w.y = cvt_pk_bf16(v0[2], v0[3]); w.z = cvt_pk_bf16(v1[0], v1[1]); w.w = cvt_pk_bf16(v1[2], v1[3]);
;                     *(u32x4*)(VT + (size_t)r * NT + t0) = w;
;                 }
;             }
;     }
	s_setprio 1
	v_mfma_f32_16x16x32_bf16 v[48:51], v[202:205], v[166:169], v[48:51]
	v_mfma_f32_16x16x32_bf16 v[40:43], v[210:213], v[166:169], v[40:43]
	v_mfma_f32_16x16x32_bf16 v[32:35], v[202:205], v[174:177], v[32:35]
	v_mfma_f32_16x16x32_bf16 v[24:27], v[210:213], v[174:177], v[24:27]
	v_mfma_f32_16x16x32_bf16 v[16:19], v[202:205], v[182:185], v[16:19]
	v_mfma_f32_16x16x32_bf16 v[8:11], v[210:213], v[182:185], v[8:11]
	v_mfma_f32_16x16x32_bf16 v[4:7], v[202:205], v[190:193], v[4:7]
	v_mfma_f32_16x16x32_bf16 v[0:3], v[210:213], v[190:193], v[0:3]
	v_mfma_f32_16x16x32_bf16 v[48:51], v[206:209], v[170:173], v[48:51]
	v_mfma_f32_16x16x32_bf16 v[40:43], v[214:217], v[170:173], v[40:43]
	v_mfma_f32_16x16x32_bf16 v[32:35], v[206:209], v[178:181], v[32:35]
	v_mfma_f32_16x16x32_bf16 v[24:27], v[214:217], v[178:181], v[24:27]
	v_mfma_f32_16x16x32_bf16 v[16:19], v[206:209], v[186:189], v[16:19]
	v_mfma_f32_16x16x32_bf16 v[8:11], v[214:217], v[186:189], v[8:11]
	v_mfma_f32_16x16x32_bf16 v[4:7], v[206:209], v[194:197], v[4:7]
	v_mfma_f32_16x16x32_bf16 v[0:3], v[214:217], v[194:197], v[0:3]
	s_setprio 0
	s_add_i32 s65, s65, 2
	s_add_u32 s30, s30, 0x100
	s_addc_u32 s31, s31, 0
	s_add_u32 s63, s63, 0x100
	s_addc_u32 s64, s64, 0
	s_cmp_gt_u32 s65, 13
	s_barrier
	s_cbranch_scc0 .LBB0_633
	v_mov_b32_e32 v150, v144
	v_mov_b32_e32 v151, v145
	s_lshl_b32 s21, s28, 8
	s_add_i32 s21, s21, s48
	v_add_u32_e32 v150, s21, v150
	s_lshl_b32 s21, s60, 8
	s_or_b32 s21, s21, s49
	v_lshl_add_u32 v152, v151, 3, s21
	v_ashrrev_i32_e32 v151, 31, v150
	v_cvt_pk_bf16_f32 v124, v124, v125
	v_cvt_pk_bf16_f32 v125, v126, v127
	v_cvt_pk_bf16_f32 v126, v120, v121
	v_lshlrev_b64 v[120:121], 17, v[150:151]
	v_lshl_add_u64 v[120:121], s[0:1], 0, v[120:121]
	v_ashrrev_i32_e32 v153, 31, v152
	v_lshl_add_u64 v[120:121], v[152:153], 1, v[120:121]
	s_mov_b32 s21, 0x200000
	v_cvt_pk_bf16_f32 v127, v122, v123
	global_store_dwordx4 v[120:121], v[124:127], off
	v_cvt_pk_bf16_f32 v112, v112, v113
	v_cvt_pk_bf16_f32 v113, v114, v115
	v_cvt_pk_bf16_f32 v114, v104, v105
	v_cvt_pk_bf16_f32 v115, v106, v107
	global_store_dwordx4 v[120:121], v[112:115], off offset:256
	v_cvt_pk_bf16_f32 v104, v116, v117
	v_cvt_pk_bf16_f32 v105, v118, v119
	v_cvt_pk_bf16_f32 v106, v108, v109
	v_cvt_pk_bf16_f32 v107, v110, v111
	s_mov_b64 s[30:31], 0x200000
	v_add_co_u32_e32 v110, vcc, s21, v120
	v_lshl_add_u64 v[108:109], v[120:121], 0, s[30:31]
	s_nop 0
	v_addc_co_u32_e32 v111, vcc, 0, v121, vcc
	s_mov_b32 s21, 0x400000
	global_store_dwordx4 v[110:111], v[104:107], off
	v_cvt_pk_bf16_f32 v96, v96, v97
	v_cvt_pk_bf16_f32 v97, v98, v99
	v_cvt_pk_bf16_f32 v98, v88, v89
	v_cvt_pk_bf16_f32 v99, v90, v91
	global_store_dwordx4 v[108:109], v[96:99], off offset:256
	v_cvt_pk_bf16_f32 v88, v100, v101
	v_cvt_pk_bf16_f32 v89, v102, v103
	v_cvt_pk_bf16_f32 v90, v92, v93
	v_cvt_pk_bf16_f32 v91, v94, v95
	s_mov_b64 s[30:31], 0x400000
	v_add_co_u32_e32 v94, vcc, s21, v120
	v_lshl_add_u64 v[92:93], v[120:121], 0, s[30:31]
	s_nop 0
	v_addc_co_u32_e32 v95, vcc, 0, v121, vcc
	s_mov_b32 s21, 0x600000
	global_store_dwordx4 v[94:95], v[88:91], off
	v_cvt_pk_bf16_f32 v80, v80, v81
	v_cvt_pk_bf16_f32 v81, v82, v83
	v_cvt_pk_bf16_f32 v82, v72, v73
	v_cvt_pk_bf16_f32 v83, v74, v75
	global_store_dwordx4 v[92:93], v[80:83], off offset:256
	v_cvt_pk_bf16_f32 v72, v84, v85
	v_cvt_pk_bf16_f32 v73, v86, v87
	v_cvt_pk_bf16_f32 v74, v76, v77
	v_cvt_pk_bf16_f32 v75, v78, v79
	s_mov_b64 s[30:31], 0x600000
	v_add_co_u32_e32 v78, vcc, s21, v120
	v_lshl_add_u64 v[76:77], v[120:121], 0, s[30:31]
	s_nop 0
	v_addc_co_u32_e32 v79, vcc, 0, v121, vcc
	global_store_dwordx4 v[78:79], v[72:75], off
	v_cvt_pk_bf16_f32 v68, v68, v69
	v_cvt_pk_bf16_f32 v69, v70, v71
	v_cvt_pk_bf16_f32 v70, v64, v65
	v_cvt_pk_bf16_f32 v71, v66, v67
	global_store_dwordx4 v[76:77], v[68:71], off offset:256
	v_cvt_pk_bf16_f32 v60, v60, v61
	v_cvt_pk_bf16_f32 v61, v62, v63
	v_cvt_pk_bf16_f32 v62, v56, v57
	v_cvt_pk_bf16_f32 v63, v58, v59
	s_mov_b64 s[30:31], 0x1000000
	v_add_co_u32_e32 v58, vcc, s56, v120
	v_lshl_add_u64 v[56:57], v[120:121], 0, s[30:31]
	s_nop 0
	v_addc_co_u32_e32 v59, vcc, 0, v121, vcc
	global_store_dwordx4 v[58:59], v[60:63], off
	v_cvt_pk_bf16_f32 v48, v48, v49
	v_cvt_pk_bf16_f32 v49, v50, v51
	v_cvt_pk_bf16_f32 v50, v40, v41
	v_cvt_pk_bf16_f32 v51, v42, v43
	global_store_dwordx4 v[56:57], v[48:51], off offset:256
	v_cvt_pk_bf16_f32 v40, v52, v53
	v_cvt_pk_bf16_f32 v41, v54, v55
	v_cvt_pk_bf16_f32 v42, v44, v45
	v_cvt_pk_bf16_f32 v43, v46, v47
	v_add_co_u32_e32 v46, vcc, s57, v120
	v_lshl_add_u64 v[44:45], v[120:121], 0, s[6:7]
	s_nop 0
	v_addc_co_u32_e32 v47, vcc, 0, v121, vcc
	global_store_dwordx4 v[46:47], v[40:43], off
	v_cvt_pk_bf16_f32 v32, v32, v33
	v_cvt_pk_bf16_f32 v33, v34, v35
	v_cvt_pk_bf16_f32 v34, v24, v25
	v_cvt_pk_bf16_f32 v35, v26, v27
	global_store_dwordx4 v[44:45], v[32:35], off offset:256
	v_cvt_pk_bf16_f32 v24, v36, v37
	v_cvt_pk_bf16_f32 v25, v38, v39
	v_cvt_pk_bf16_f32 v26, v28, v29
	v_cvt_pk_bf16_f32 v27, v30, v31
	v_add_co_u32_e32 v30, vcc, s58, v120
	v_lshl_add_u64 v[28:29], v[120:121], 0, s[8:9]
	s_nop 0
	v_addc_co_u32_e32 v31, vcc, 0, v121, vcc
	global_store_dwordx4 v[30:31], v[24:27], off
	v_cvt_pk_bf16_f32 v16, v16, v17
	v_cvt_pk_bf16_f32 v17, v18, v19
	v_cvt_pk_bf16_f32 v18, v8, v9
	v_cvt_pk_bf16_f32 v19, v10, v11
	global_store_dwordx4 v[28:29], v[16:19], off offset:256
	v_cvt_pk_bf16_f32 v8, v20, v21
	v_cvt_pk_bf16_f32 v9, v22, v23
	v_cvt_pk_bf16_f32 v10, v12, v13
	v_cvt_pk_bf16_f32 v11, v14, v15
	v_add_co_u32_e32 v14, vcc, s59, v120
	v_lshl_add_u64 v[12:13], v[120:121], 0, s[16:17]
	s_nop 0
	v_addc_co_u32_e32 v15, vcc, 0, v121, vcc
	s_and_b64 vcc, exec, s[2:3]
	s_mov_b32 s60, s20
	s_mov_b32 s28, s22
	s_mov_b64 s[34:35], s[26:27]
	s_mov_b64 s[30:31], s[24:25]
	global_store_dwordx4 v[14:15], v[8:11], off
	v_cvt_pk_bf16_f32 v4, v4, v5
	v_cvt_pk_bf16_f32 v5, v6, v7
	v_cvt_pk_bf16_f32 v6, v0, v1
	v_cvt_pk_bf16_f32 v7, v2, v3
	global_store_dwordx4 v[12:13], v[4:7], off offset:256
	s_cbranch_vccz .LBB0_626
	s_waitcnt vmcnt(0)
	s_cmpk_gt_u32 s33, 0xff
	s_cbranch_scc1 .LBB0_637
	s_barrier

; #define PG8_STAGE(bufoff, gbase, voff) do { _Pragma("unroll") for (int _i = 0; _i < 2; ++_i) \
;         __builtin_amdgcn_global_load_lds((const unsigned*)((const char*)(gbase) + (voff)[_i]), (LAS unsigned*)(lds + (bufoff) + ldsw + _i * 8192), 16, 0, 0); } while (0)
; #define PG8_LDA(dst, b, h) do { _Pragma("unroll") for (int m = 0; m < 4; ++m) _Pragma("unroll") for (int k = 0; k < 2; ++k) dst[m][k] = *(const LAS bf16x8*)(lds + PG8_SA(b, h) + aoff + m * 2048 + k * 1024); } while (0)
; #define PG8_LDB(dst, b, h) do { _Pragma("unroll") for (int n = 0; n < 2; ++n) _Pragma("unroll") for (int k = 0; k < 2; ++k) dst[n][k] = *(const LAS bf16x8*)(lds + PG8_SB(b, h) + boff + n * 2048 + k * 1024); } while (0)
; #define PG8_WAIT_V(n) asm volatile("s_waitcnt vmcnt(" #n ")" ::: "memory")
; #define PG8_WAIT_L(n) asm volatile("s_waitcnt lgkmcnt(" #n ")" ::: "memory")
; #define PG8_BAR __builtin_amdgcn_s_barrier()
; #define PG8_SCHED __builtin_amdgcn_sched_barrier(0)
; template <class Epi, class Sched>
; __device__ __forceinline__ void gemm_phase(LAS unsigned char* lds, const Gemm g, const Sched& S, const Epi& E) {
;     ...
;         const bool has_next = S.next(ui + 1, nxt);
;         const char* nA = has_next ? (const char*)g.A + (size_t)nxt.pm * tstep : cA; const char* nB = has_next ? (const char*)g.Bt + (size_t)nxt.pn * tstep : cB;
;         for (int t = 0; t < nt; t += 2) {
;             const bool last = (t == nt - 2);
;             const char* a1 = cA + (size_t)(t + 1) * kstep;
;             const char* a2 = last ? nA : cA + (size_t)(t + 2) * kstep; const char* b2 = last ? nB : cB + (size_t)(t + 2) * kstep;
;             const char* a3 = a2 + kstep; const char* b3 = b2 + kstep;
;             PG8_LDB(B0, 0, 0); PG8_SCHED; PG8_LDA(At, 0, 0); PG8_STAGE(PG8_SA(1, 1), a1 + hstep, voffA);
;             PG8_WAIT_L(8); PG8_BAR; PG8_WAIT_L(0); PG8_MMA(0, 0, At, B0); PG8_BAR; PG8_SCHED;
;             PG8_LDB(B1, 0, 1); PG8_STAGE(PG8_SB(0, 0), b2, voffB);
;             PG8_BAR; PG8_WAIT_L(0); PG8_MMA(0, 1, At, B1); PG8_BAR;
;             PG8_LDA(At, 0, 1); PG8_STAGE(PG8_SA(0, 0), a2, voffA);
;             PG8_BAR; PG8_WAIT_L(0); PG8_MMA(1, 0, At, B0); PG8_BAR; PG8_SCHED;
;             PG8_STAGE(PG8_SB(0, 1), b2 + hstep, voffB);
;             PG8_WAIT_V(6); PG8_BAR; PG8_MMA(1, 1, At, B1); PG8_BAR;
.LBB0_652:
	s_ashr_i32 s9, s8, 31
	v_cmp_lt_i64_e32 vcc, s[16:17], v[142:143]
	s_lshl_b64 s[16:17], s[8:9], 19
	s_add_u32 s16, s14, s16
	s_addc_u32 s17, s15, s17
	s_and_b64 s[18:19], vcc, exec
	s_cselect_b32 s9, s17, s23
	s_cselect_b32 s48, s16, s22
	s_ashr_i32 s7, s6, 31
	s_lshl_b64 s[18:19], s[6:7], 19
	s_add_u32 s18, s12, s18
	s_addc_u32 s19, s13, s19
	s_and_b64 s[26:27], vcc, exec
	s_cselect_b32 s7, s19, s25
	s_cselect_b32 s49, s18, s24
	s_add_u32 s22, s22, 0x40080
	s_addc_u32 s23, s23, 0
	s_add_u32 s51, s24, 0x100
	s_addc_u32 s52, s25, 0
	s_mov_b32 s53, -2
	s_waitcnt lgkmcnt(0)
	ds_read_b128 v[152:155], v149
	ds_read_b128 v[156:159], v149 offset:1024
	ds_read_b128 v[160:163], v149 offset:2048
	ds_read_b128 v[164:167], v149 offset:3072
	s_add_u32 s24, s22, 0xfffc0080
	s_addc_u32 s25, s23, -1
	s_cmp_eq_u32 s53, 12
	s_cselect_b32 s27, s9, s25
	s_cselect_b32 s26, s48, s24
	s_cselect_b32 s25, s7, s52
	s_cselect_b32 s24, s49, s51
	s_add_i32 m0, s21, 0xc000
	ds_read_b128 v[168:171], v150
	ds_read_b128 v[172:175], v150 offset:1024
	ds_read_b128 v[176:179], v150 offset:2048
	ds_read_b128 v[180:183], v150 offset:3072
	ds_read_b128 v[184:187], v150 offset:4096
	ds_read_b128 v[188:191], v150 offset:5120
	ds_read_b128 v[192:195], v150 offset:6144
	ds_read_b128 v[196:199], v150 offset:7168
	global_load_lds_dwordx4 v138, s[22:23]
	s_add_i32 m0, s21, 0xe000
	s_nop 0
	global_load_lds_dwordx4 v140, s[22:23]
	s_waitcnt lgkmcnt(8)
	s_waitcnt vmcnt(10)
	s_barrier
	s_waitcnt lgkmcnt(0)
	s_setprio 1
	s_waitcnt lgkmcnt(0)
	v_mfma_f32_16x16x32_bf16 v[124:127], v[152:155], v[168:171], 0
	v_mfma_f32_16x16x32_bf16 v[120:123], v[160:163], v[168:171], 0
	v_mfma_f32_16x16x32_bf16 v[112:115], v[152:155], v[176:179], 0
	v_mfma_f32_16x16x32_bf16 v[104:107], v[160:163], v[176:179], 0
	v_mfma_f32_16x16x32_bf16 v[96:99], v[152:155], v[184:187], 0
	v_mfma_f32_16x16x32_bf16 v[88:91], v[160:163], v[184:187], 0
	v_mfma_f32_16x16x32_bf16 v[80:83], v[152:155], v[192:195], 0
	v_mfma_f32_16x16x32_bf16 v[72:75], v[160:163], v[192:195], 0
	v_mfma_f32_16x16x32_bf16 v[124:127], v[156:159], v[172:175], v[124:127]
	v_mfma_f32_16x16x32_bf16 v[120:123], v[164:167], v[172:175], v[120:123]
	v_mfma_f32_16x16x32_bf16 v[112:115], v[156:159], v[180:183], v[112:115]
	v_mfma_f32_16x16x32_bf16 v[104:107], v[164:167], v[180:183], v[104:107]
	v_mfma_f32_16x16x32_bf16 v[96:99], v[156:159], v[188:191], v[96:99]
	v_mfma_f32_16x16x32_bf16 v[88:91], v[164:167], v[188:191], v[88:91]
	v_mfma_f32_16x16x32_bf16 v[80:83], v[156:159], v[196:199], v[80:83]
	v_mfma_f32_16x16x32_bf16 v[72:75], v[164:167], v[196:199], v[72:75]
	s_setprio 0
	s_barrier
	s_add_i32 s54, s45, s30
	s_mov_b32 m0, s54
	ds_read_b128 v[202:205], v151
	ds_read_b128 v[206:209], v151 offset:1024
	ds_read_b128 v[210:213], v151 offset:2048
	ds_read_b128 v[214:217], v151 offset:3072
	global_load_lds_dwordx4 v130, s[24:25]
	s_add_i32 m0, s54, 0x2000
	s_nop 0
	global_load_lds_dwordx4 v134, s[24:25]
	s_waitcnt vmcnt(10)
	s_barrier
	s_waitcnt lgkmcnt(0)
	s_setprio 1
	s_waitcnt lgkmcnt(0)
	v_mfma_f32_16x16x32_bf16 v[116:119], v[202:205], v[168:171], 0
	v_mfma_f32_16x16x32_bf16 v[108:111], v[210:213], v[168:171], 0
	v_mfma_f32_16x16x32_bf16 v[100:103], v[202:205], v[176:179], 0
	v_mfma_f32_16x16x32_bf16 v[92:95], v[210:213], v[176:179], 0
	v_mfma_f32_16x16x32_bf16 v[84:87], v[202:205], v[184:187], 0
	v_mfma_f32_16x16x32_bf16 v[76:79], v[210:213], v[184:187], 0
	v_mfma_f32_16x16x32_bf16 v[68:71], v[202:205], v[192:195], 0
	v_mfma_f32_16x16x32_bf16 v[64:67], v[210:213], v[192:195], 0
	v_mfma_f32_16x16x32_bf16 v[116:119], v[206:209], v[172:175], v[116:119]
	v_mfma_f32_16x16x32_bf16 v[108:111], v[214:217], v[172:175], v[108:111]
	v_mfma_f32_16x16x32_bf16 v[100:103], v[206:209], v[180:183], v[100:103]
	v_mfma_f32_16x16x32_bf16 v[92:95], v[214:217], v[180:183], v[92:95]
	v_mfma_f32_16x16x32_bf16 v[84:87], v[206:209], v[188:191], v[84:87]
	v_mfma_f32_16x16x32_bf16 v[76:79], v[214:217], v[188:191], v[76:79]
	v_mfma_f32_16x16x32_bf16 v[68:71], v[206:209], v[196:199], v[68:71]
	v_mfma_f32_16x16x32_bf16 v[64:67], v[214:217], v[196:199], v[64:67]
	s_setprio 0
	s_mov_b32 m0, s21
	v_lshl_add_u64 v[222:223], s[26:27], 0, v[128:129]
	s_barrier
	ds_read_b128 v[168:171], v150 offset:16384
	ds_read_b128 v[172:175], v150 offset:17408
	ds_read_b128 v[176:179], v150 offset:18432
	ds_read_b128 v[180:183], v150 offset:19456
	ds_read_b128 v[184:187], v150 offset:20480
	ds_read_b128 v[188:191], v150 offset:21504
	ds_read_b128 v[192:195], v150 offset:22528
	ds_read_b128 v[196:199], v150 offset:23552
	global_load_lds_dwordx4 v128, s[26:27]
	v_lshl_add_u64 v[224:225], s[26:27], 0, v[132:133]
	s_mov_b32 m0, s31
	s_nop 0
	global_load_lds_dwordx4 v132, s[26:27]
	s_barrier
	s_waitcnt lgkmcnt(0)
	s_setprio 1
	s_waitcnt lgkmcnt(0)
	v_mfma_f32_16x16x32_bf16 v[60:63], v[152:155], v[168:171], 0
	v_mfma_f32_16x16x32_bf16 v[56:59], v[160:163], v[168:171], 0
	v_mfma_f32_16x16x32_bf16 v[48:51], v[152:155], v[176:179], 0
	v_mfma_f32_16x16x32_bf16 v[40:43], v[160:163], v[176:179], 0
	v_mfma_f32_16x16x32_bf16 v[32:35], v[152:155], v[184:187], 0
	v_mfma_f32_16x16x32_bf16 v[24:27], v[160:163], v[184:187], 0
	v_mfma_f32_16x16x32_bf16 v[16:19], v[152:155], v[192:195], 0
	v_mfma_f32_16x16x32_bf16 v[8:11], v[160:163], v[192:195], 0
	v_mfma_f32_16x16x32_bf16 v[60:63], v[156:159], v[172:175], v[60:63]
	v_mfma_f32_16x16x32_bf16 v[56:59], v[164:167], v[172:175], v[56:59]
	v_mfma_f32_16x16x32_bf16 v[48:51], v[156:159], v[180:183], v[48:51]
	v_mfma_f32_16x16x32_bf16 v[40:43], v[164:167], v[180:183], v[40:43]
	v_mfma_f32_16x16x32_bf16 v[32:35], v[156:159], v[188:191], v[32:35]
	v_mfma_f32_16x16x32_bf16 v[24:27], v[164:167], v[188:191], v[24:27]
	v_mfma_f32_16x16x32_bf16 v[16:19], v[156:159], v[196:199], v[16:19]
	v_mfma_f32_16x16x32_bf16 v[8:11], v[164:167], v[196:199], v[8:11]
	s_setprio 0
	s_barrier
; #define PG8_STAGE(bufoff, gbase, voff) do { _Pragma("unroll") for (int _i = 0; _i < 2; ++_i) \
;         __builtin_amdgcn_global_load_lds((const unsigned*)((const char*)(gbase) + (voff)[_i]), (LAS unsigned*)(lds + (bufoff) + ldsw + _i * 8192), 16, 0, 0); } while (0)
; #define PG8_LDA(dst, b, h) do { _Pragma("unroll") for (int m = 0; m < 4; ++m) _Pragma("unroll") for (int k = 0; k < 2; ++k) dst[m][k] = *(const LAS bf16x8*)(lds + PG8_SA(b, h) + aoff + m * 2048 + k * 1024); } while (0)
; #define PG8_LDB(dst, b, h) do { _Pragma("unroll") for (int n = 0; n < 2; ++n) _Pragma("unroll") for (int k = 0; k < 2; ++k) dst[n][k] = *(const LAS bf16x8*)(lds + PG8_SB(b, h) + boff + n * 2048 + k * 1024); } while (0)
; #define PG8_MMA(ai, bj, At, Bt) do { __builtin_amdgcn_s_setprio(1); _Pragma("unroll") for (int m = 0; m < 4; ++m) _Pragma("unroll") for (int n = 0; n < 2; ++n) _Pragma("unroll") for (int k = 0; k < 2; ++k) \
;         acc[ai][bj][m][n] = __builtin_amdgcn_mfma_f32_16x16x32_bf16(Bt[n][k], At[m][k], acc[ai][bj][m][n], 0, 0, 0); __builtin_amdgcn_s_setprio(0); } while (0)
; #define PG8_WAIT_V(n) asm volatile("s_waitcnt vmcnt(" #n ")" ::: "memory")
; #define PG8_WAIT_L(n) asm volatile("s_waitcnt lgkmcnt(" #n ")" ::: "memory")
; #define PG8_BAR __builtin_amdgcn_s_barrier()
; #define PG8_SCHED __builtin_amdgcn_sched_barrier(0)
; template <class Epi, class Sched>
; __device__ __forceinline__ void gemm_phase(LAS unsigned char* lds, const Gemm g, const Sched& S, const Epi& E) {
;     ...
;             PG8_WAIT_V(6); PG8_BAR; PG8_MMA(1, 1, At, B1); PG8_BAR;
;             PG8_LDB(B0, 1, 0); PG8_SCHED; PG8_LDA(At, 1, 0); PG8_STAGE(PG8_SA(0, 1), a2 + hstep, voffA);
;             PG8_WAIT_L(8); PG8_BAR; PG8_WAIT_L(0); PG8_MMA(0, 0, At, B0); PG8_BAR; PG8_SCHED;
;             PG8_LDB(B1, 1, 1); PG8_STAGE(PG8_SB(1, 0), b3, voffB);
;             PG8_BAR; PG8_WAIT_L(0); PG8_MMA(0, 1, At, B1); PG8_BAR;
;             PG8_LDA(At, 1, 1); PG8_STAGE(PG8_SA(1, 0), a3, voffA);
;             PG8_BAR; PG8_WAIT_L(0); PG8_MMA(1, 0, At, B0); PG8_BAR; PG8_SCHED;
	s_add_u32 s54, s24, 0x40000
	s_addc_u32 s55, s25, 0
	s_add_i32 s56, s46, s30
	s_mov_b32 m0, s56
	s_nop 0
	global_load_lds_dwordx4 v130, s[54:55]
	s_add_i32 m0, s56, 0x2000
	s_nop 0
	global_load_lds_dwordx4 v134, s[54:55]
	s_waitcnt vmcnt(10)
	s_barrier
	s_setprio 1
	v_mfma_f32_16x16x32_bf16 v[52:55], v[202:205], v[168:171], 0
	v_mfma_f32_16x16x32_bf16 v[44:47], v[210:213], v[168:171], 0
	v_mfma_f32_16x16x32_bf16 v[36:39], v[202:205], v[176:179], 0
	v_mfma_f32_16x16x32_bf16 v[28:31], v[210:213], v[176:179], 0
	v_mfma_f32_16x16x32_bf16 v[20:23], v[202:205], v[184:187], 0
	v_mfma_f32_16x16x32_bf16 v[12:15], v[210:213], v[184:187], 0
	v_mfma_f32_16x16x32_bf16 v[4:7], v[202:205], v[192:195], 0
	v_mfma_f32_16x16x32_bf16 v[0:3], v[210:213], v[192:195], 0
	v_mfma_f32_16x16x32_bf16 v[52:55], v[206:209], v[172:175], v[52:55]
	v_mfma_f32_16x16x32_bf16 v[44:47], v[214:217], v[172:175], v[44:47]
	v_mfma_f32_16x16x32_bf16 v[36:39], v[206:209], v[180:183], v[36:39]
	v_mfma_f32_16x16x32_bf16 v[28:31], v[214:217], v[180:183], v[28:31]
	v_mfma_f32_16x16x32_bf16 v[20:23], v[206:209], v[188:191], v[20:23]
	v_mfma_f32_16x16x32_bf16 v[12:15], v[214:217], v[188:191], v[12:15]
	v_mfma_f32_16x16x32_bf16 v[4:7], v[206:209], v[196:199], v[4:7]
	v_mfma_f32_16x16x32_bf16 v[0:3], v[214:217], v[196:199], v[0:3]
	s_setprio 0
	s_add_i32 s54, 0, 0x18000
	v_add_u32_e32 v136, s54, v148
	s_barrier
	ds_read_b128 v[152:155], v136
	ds_read_b128 v[156:159], v136 offset:1024
	ds_read_b128 v[160:163], v136 offset:2048
	ds_read_b128 v[164:167], v136 offset:3072
	s_add_u32 s26, s26, 0x40000
	s_addc_u32 s27, s27, 0
	s_mov_b32 m0, s33
	ds_read_b128 v[168:171], v150 offset:32768
	ds_read_b128 v[172:175], v150 offset:33792
	ds_read_b128 v[176:179], v150 offset:34816
	ds_read_b128 v[180:183], v150 offset:35840
	ds_read_b128 v[184:187], v150 offset:36864
	ds_read_b128 v[188:191], v150 offset:37888
	ds_read_b128 v[192:195], v150 offset:38912
	ds_read_b128 v[196:199], v150 offset:39936
	global_load_lds_dwordx4 v128, s[26:27]
	s_mov_b32 m0, s34
	s_nop 0
	global_load_lds_dwordx4 v132, s[26:27]
	s_waitcnt lgkmcnt(8)
	s_waitcnt vmcnt(10)
	s_barrier
	s_waitcnt lgkmcnt(0)
	s_setprio 1
	s_waitcnt lgkmcnt(0)
	v_mfma_f32_16x16x32_bf16 v[124:127], v[152:155], v[168:171], v[124:127]
	v_mfma_f32_16x16x32_bf16 v[120:123], v[160:163], v[168:171], v[120:123]
	v_mfma_f32_16x16x32_bf16 v[112:115], v[152:155], v[176:179], v[112:115]
	v_mfma_f32_16x16x32_bf16 v[104:107], v[160:163], v[176:179], v[104:107]
	v_mfma_f32_16x16x32_bf16 v[96:99], v[152:155], v[184:187], v[96:99]
	v_mfma_f32_16x16x32_bf16 v[88:91], v[160:163], v[184:187], v[88:91]
	v_mfma_f32_16x16x32_bf16 v[80:83], v[152:155], v[192:195], v[80:83]
	v_mfma_f32_16x16x32_bf16 v[72:75], v[160:163], v[192:195], v[72:75]
	v_mfma_f32_16x16x32_bf16 v[124:127], v[156:159], v[172:175], v[124:127]
	v_mfma_f32_16x16x32_bf16 v[120:123], v[164:167], v[172:175], v[120:123]
	v_mfma_f32_16x16x32_bf16 v[112:115], v[156:159], v[180:183], v[112:115]
	v_mfma_f32_16x16x32_bf16 v[104:107], v[164:167], v[180:183], v[104:107]
	v_mfma_f32_16x16x32_bf16 v[96:99], v[156:159], v[188:191], v[96:99]
	v_mfma_f32_16x16x32_bf16 v[88:91], v[164:167], v[188:191], v[88:91]
	v_mfma_f32_16x16x32_bf16 v[80:83], v[156:159], v[196:199], v[80:83]
	v_mfma_f32_16x16x32_bf16 v[72:75], v[164:167], v[196:199], v[72:75]
	s_setprio 0
	s_barrier
	s_add_i32 s26, 0, 0x1c000
	s_add_i32 s27, s54, s30
	v_add_u32_e32 v136, s26, v148
	s_add_u32 s0, s24, 0x80
	s_addc_u32 s1, s25, 0
	s_mov_b32 m0, s27
	ds_read_b128 v[202:205], v136
	ds_read_b128 v[206:209], v136 offset:1024
	ds_read_b128 v[210:213], v136 offset:2048
	ds_read_b128 v[214:217], v136 offset:3072
	global_load_lds_dwordx4 v130, s[0:1]
	s_add_i32 m0, s27, 0x2000
	s_nop 0
	global_load_lds_dwordx4 v134, s[0:1]
	s_waitcnt vmcnt(10)
	s_barrier
	s_waitcnt lgkmcnt(0)
	s_setprio 1
	s_waitcnt lgkmcnt(0)
	v_mfma_f32_16x16x32_bf16 v[116:119], v[202:205], v[168:171], v[116:119]
	v_mfma_f32_16x16x32_bf16 v[108:111], v[210:213], v[168:171], v[108:111]
	v_mfma_f32_16x16x32_bf16 v[100:103], v[202:205], v[176:179], v[100:103]
	v_mfma_f32_16x16x32_bf16 v[92:95], v[210:213], v[176:179], v[92:95]
	v_mfma_f32_16x16x32_bf16 v[84:87], v[202:205], v[184:187], v[84:87]
	v_mfma_f32_16x16x32_bf16 v[76:79], v[210:213], v[184:187], v[76:79]
	v_mfma_f32_16x16x32_bf16 v[68:71], v[202:205], v[192:195], v[68:71]
	v_mfma_f32_16x16x32_bf16 v[64:67], v[210:213], v[192:195], v[64:67]
	v_mfma_f32_16x16x32_bf16 v[116:119], v[206:209], v[172:175], v[116:119]
	v_mfma_f32_16x16x32_bf16 v[108:111], v[214:217], v[172:175], v[108:111]
	v_mfma_f32_16x16x32_bf16 v[100:103], v[206:209], v[180:183], v[100:103]
	v_mfma_f32_16x16x32_bf16 v[92:95], v[214:217], v[180:183], v[92:95]
	v_mfma_f32_16x16x32_bf16 v[84:87], v[206:209], v[188:191], v[84:87]
	v_mfma_f32_16x16x32_bf16 v[76:79], v[214:217], v[188:191], v[76:79]
	v_mfma_f32_16x16x32_bf16 v[68:71], v[206:209], v[196:199], v[68:71]
	v_mfma_f32_16x16x32_bf16 v[64:67], v[214:217], v[196:199], v[64:67]
	s_setprio 0
	s_mov_b32 m0, s42
	s_mov_b64 s[0:1], 0x80
	v_lshl_add_u64 v[218:219], v[222:223], 0, s[0:1]
	s_barrier
	ds_read_b128 v[168:171], v150 offset:49152
	ds_read_b128 v[172:175], v150 offset:50176
	ds_read_b128 v[176:179], v150 offset:51200
	ds_read_b128 v[180:183], v150 offset:52224
	ds_read_b128 v[184:187], v150 offset:53248
	ds_read_b128 v[188:191], v150 offset:54272
	ds_read_b128 v[192:195], v150 offset:55296
	ds_read_b128 v[196:199], v150 offset:56320
	global_load_lds_dwordx4 v[218:219], off
	v_lshl_add_u64 v[218:219], v[224:225], 0, s[0:1]
	s_mov_b32 m0, s43
	s_nop 0
	global_load_lds_dwordx4 v[218:219], off
	s_barrier
; #define PG8_STAGE(bufoff, gbase, voff) do { _Pragma("unroll") for (int _i = 0; _i < 2; ++_i) \
;         __builtin_amdgcn_global_load_lds((const unsigned*)((const char*)(gbase) + (voff)[_i]), (LAS unsigned*)(lds + (bufoff) + ldsw + _i * 8192), 16, 0, 0); } while (0)
; #define PG8_LDA(dst, b, h) do { _Pragma("unroll") for (int m = 0; m < 4; ++m) _Pragma("unroll") for (int k = 0; k < 2; ++k) dst[m][k] = *(const LAS bf16x8*)(lds + PG8_SA(b, h) + aoff + m * 2048 + k * 1024); } while (0)
; #define PG8_LDB(dst, b, h) do { _Pragma("unroll") for (int n = 0; n < 2; ++n) _Pragma("unroll") for (int k = 0; k < 2; ++k) dst[n][k] = *(const LAS bf16x8*)(lds + PG8_SB(b, h) + boff + n * 2048 + k * 1024); } while (0)
; #define PG8_WAIT_V(n) asm volatile("s_waitcnt vmcnt(" #n ")" ::: "memory")
; #define PG8_WAIT_L(n) asm volatile("s_waitcnt lgkmcnt(" #n ")" ::: "memory")
; #define PG8_BAR __builtin_amdgcn_s_barrier()
; #define PG8_SCHED __builtin_amdgcn_sched_barrier(0)
; template <class Epi, class Sched>
; __device__ __forceinline__ void gemm_phase(LAS unsigned char* lds, const Gemm g, const Sched& S, const Epi& E) {
;     ...
;             PG8_LDB(B0, 0, 0); PG8_SCHED; PG8_LDA(At, 0, 0); PG8_STAGE(PG8_SA(1, 1), a1 + hstep, voffA);
;             PG8_WAIT_L(8); PG8_BAR; PG8_WAIT_L(0); PG8_MMA(0, 0, At, B0); PG8_BAR; PG8_SCHED;
;             PG8_LDB(B1, 0, 1); PG8_STAGE(PG8_SB(0, 0), b2, voffB);
;             PG8_BAR; PG8_WAIT_L(0); PG8_MMA(0, 1, At, B1); PG8_BAR;
;             PG8_LDA(At, 0, 1); PG8_STAGE(PG8_SA(0, 0), a2, voffA);
;             PG8_BAR; PG8_WAIT_L(0); PG8_MMA(1, 0, At, B0); PG8_BAR; PG8_SCHED;
;             PG8_STAGE(PG8_SB(0, 1), b2 + hstep, voffB);
;             PG8_WAIT_V(6); PG8_BAR; PG8_MMA(1, 1, At, B1); PG8_BAR;
;             PG8_LDB(B0, 1, 0); PG8_SCHED; PG8_LDA(At, 1, 0); PG8_STAGE(PG8_SA(0, 1), a2 + hstep, voffA);
;             PG8_WAIT_L(8); PG8_BAR; PG8_WAIT_L(0); PG8_MMA(0, 0, At, B0); PG8_BAR; PG8_SCHED;
;             PG8_LDB(B1, 1, 1); PG8_STAGE(PG8_SB(1, 0), b3, voffB);
;             PG8_BAR; PG8_WAIT_L(0); PG8_MMA(0, 1, At, B1); PG8_BAR;
;             PG8_LDA(At, 1, 1); PG8_STAGE(PG8_SA(1, 0), a3, voffA);
;             PG8_BAR; PG8_WAIT_L(0); PG8_MMA(1, 0, At, B0); PG8_BAR; PG8_SCHED;
;             PG8_STAGE(PG8_SB(1, 1), b3 + hstep, voffB);
;             PG8_WAIT_V(6); PG8_BAR; PG8_MMA(1, 1, At, B1); PG8_BAR;
	s_waitcnt lgkmcnt(0)
	s_setprio 1
	s_waitcnt lgkmcnt(0)
	v_mfma_f32_16x16x32_bf16 v[60:63], v[152:155], v[168:171], v[60:63]
	v_mfma_f32_16x16x32_bf16 v[56:59], v[160:163], v[168:171], v[56:59]
	v_mfma_f32_16x16x32_bf16 v[48:51], v[152:155], v[176:179], v[48:51]
	v_mfma_f32_16x16x32_bf16 v[40:43], v[160:163], v[176:179], v[40:43]
	v_mfma_f32_16x16x32_bf16 v[32:35], v[152:155], v[184:187], v[32:35]
	v_mfma_f32_16x16x32_bf16 v[24:27], v[160:163], v[184:187], v[24:27]
	v_mfma_f32_16x16x32_bf16 v[16:19], v[152:155], v[192:195], v[16:19]
	v_mfma_f32_16x16x32_bf16 v[8:11], v[160:163], v[192:195], v[8:11]
	v_mfma_f32_16x16x32_bf16 v[60:63], v[156:159], v[172:175], v[60:63]
	v_mfma_f32_16x16x32_bf16 v[56:59], v[164:167], v[172:175], v[56:59]
	v_mfma_f32_16x16x32_bf16 v[48:51], v[156:159], v[180:183], v[48:51]
	v_mfma_f32_16x16x32_bf16 v[40:43], v[164:167], v[180:183], v[40:43]
	v_mfma_f32_16x16x32_bf16 v[32:35], v[156:159], v[188:191], v[32:35]
	v_mfma_f32_16x16x32_bf16 v[24:27], v[164:167], v[188:191], v[24:27]
	v_mfma_f32_16x16x32_bf16 v[16:19], v[156:159], v[196:199], v[16:19]
	v_mfma_f32_16x16x32_bf16 v[8:11], v[164:167], v[196:199], v[8:11]
	s_setprio 0
	s_barrier
	s_add_u32 s24, s24, 0x40080
	s_addc_u32 s25, s25, 0
	s_add_i32 s26, s26, s30
	s_mov_b32 m0, s26
	s_nop 0
	global_load_lds_dwordx4 v130, s[24:25]
	s_add_i32 m0, s26, 0x2000
	s_nop 0
	global_load_lds_dwordx4 v134, s[24:25]
	s_waitcnt vmcnt(10)
	s_barrier
	s_setprio 1
	v_mfma_f32_16x16x32_bf16 v[52:55], v[202:205], v[168:171], v[52:55]
	v_mfma_f32_16x16x32_bf16 v[44:47], v[210:213], v[168:171], v[44:47]
	v_mfma_f32_16x16x32_bf16 v[36:39], v[202:205], v[176:179], v[36:39]
	v_mfma_f32_16x16x32_bf16 v[28:31], v[210:213], v[176:179], v[28:31]
	v_mfma_f32_16x16x32_bf16 v[20:23], v[202:205], v[184:187], v[20:23]
	v_mfma_f32_16x16x32_bf16 v[12:15], v[210:213], v[184:187], v[12:15]
	v_mfma_f32_16x16x32_bf16 v[4:7], v[202:205], v[192:195], v[4:7]
	v_mfma_f32_16x16x32_bf16 v[0:3], v[210:213], v[192:195], v[0:3]
	v_mfma_f32_16x16x32_bf16 v[52:55], v[206:209], v[172:175], v[52:55]
	v_mfma_f32_16x16x32_bf16 v[44:47], v[214:217], v[172:175], v[44:47]
	v_mfma_f32_16x16x32_bf16 v[36:39], v[206:209], v[180:183], v[36:39]
	v_mfma_f32_16x16x32_bf16 v[28:31], v[214:217], v[180:183], v[28:31]
	v_mfma_f32_16x16x32_bf16 v[20:23], v[206:209], v[188:191], v[20:23]
	v_mfma_f32_16x16x32_bf16 v[12:15], v[214:217], v[188:191], v[12:15]
	v_mfma_f32_16x16x32_bf16 v[4:7], v[206:209], v[196:199], v[4:7]
	v_mfma_f32_16x16x32_bf16 v[0:3], v[214:217], v[196:199], v[0:3]
	s_setprio 0
	s_add_i32 s53, s53, 2
	s_add_u32 s22, s22, 0x100
	s_addc_u32 s23, s23, 0
	s_add_u32 s51, s51, 0x100
	s_addc_u32 s52, s52, 0
	s_cmp_gt_u32 s53, 13
	s_barrier
.LBB0_653:
	ds_read_b128 v[152:155], v149
	ds_read_b128 v[156:159], v149 offset:1024
	ds_read_b128 v[160:163], v149 offset:2048
	ds_read_b128 v[164:167], v149 offset:3072
	s_add_u32 s24, s22, 0xfffc0080
	s_addc_u32 s25, s23, -1
	s_cmp_eq_u32 s53, 12
	s_cselect_b32 s27, s9, s25
	s_cselect_b32 s26, s48, s24
	s_cselect_b32 s25, s7, s52
	s_cselect_b32 s24, s49, s51
	s_add_i32 m0, s21, 0xc000
	ds_read_b128 v[168:171], v150
	ds_read_b128 v[172:175], v150 offset:1024
	ds_read_b128 v[176:179], v150 offset:2048
	ds_read_b128 v[180:183], v150 offset:3072
	ds_read_b128 v[184:187], v150 offset:4096
	ds_read_b128 v[188:191], v150 offset:5120
	ds_read_b128 v[192:195], v150 offset:6144
	ds_read_b128 v[196:199], v150 offset:7168
	global_load_lds_dwordx4 v138, s[22:23]
	s_add_i32 m0, s21, 0xe000
	s_nop 0
	global_load_lds_dwordx4 v140, s[22:23]
	s_waitcnt lgkmcnt(8)
	s_waitcnt vmcnt(10)
	s_barrier
	s_waitcnt lgkmcnt(0)
	s_setprio 1
	s_waitcnt lgkmcnt(0)
	v_mfma_f32_16x16x32_bf16 v[124:127], v[152:155], v[168:171], v[124:127]
	v_mfma_f32_16x16x32_bf16 v[120:123], v[160:163], v[168:171], v[120:123]
	v_mfma_f32_16x16x32_bf16 v[112:115], v[152:155], v[176:179], v[112:115]
	v_mfma_f32_16x16x32_bf16 v[104:107], v[160:163], v[176:179], v[104:107]
	v_mfma_f32_16x16x32_bf16 v[96:99], v[152:155], v[184:187], v[96:99]
	v_mfma_f32_16x16x32_bf16 v[88:91], v[160:163], v[184:187], v[88:91]
	v_mfma_f32_16x16x32_bf16 v[80:83], v[152:155], v[192:195], v[80:83]
	v_mfma_f32_16x16x32_bf16 v[72:75], v[160:163], v[192:195], v[72:75]
	v_mfma_f32_16x16x32_bf16 v[124:127], v[156:159], v[172:175], v[124:127]
	v_mfma_f32_16x16x32_bf16 v[120:123], v[164:167], v[172:175], v[120:123]
	v_mfma_f32_16x16x32_bf16 v[112:115], v[156:159], v[180:183], v[112:115]
	v_mfma_f32_16x16x32_bf16 v[104:107], v[164:167], v[180:183], v[104:107]
	v_mfma_f32_16x16x32_bf16 v[96:99], v[156:159], v[188:191], v[96:99]
	v_mfma_f32_16x16x32_bf16 v[88:91], v[164:167], v[188:191], v[88:91]
	v_mfma_f32_16x16x32_bf16 v[80:83], v[156:159], v[196:199], v[80:83]
	v_mfma_f32_16x16x32_bf16 v[72:75], v[164:167], v[196:199], v[72:75]
	s_setprio 0
	s_barrier
	s_add_i32 s54, s45, s30
	s_mov_b32 m0, s54
	ds_read_b128 v[202:205], v151
	ds_read_b128 v[206:209], v151 offset:1024
	ds_read_b128 v[210:213], v151 offset:2048
	ds_read_b128 v[214:217], v151 offset:3072
	global_load_lds_dwordx4 v130, s[24:25]
	s_add_i32 m0, s54, 0x2000
	s_nop 0
	global_load_lds_dwordx4 v134, s[24:25]
	s_waitcnt vmcnt(10)
	s_barrier
; #define PG8_STAGE(bufoff, gbase, voff) do { _Pragma("unroll") for (int _i = 0; _i < 2; ++_i) \
;         __builtin_amdgcn_global_load_lds((const unsigned*)((const char*)(gbase) + (voff)[_i]), (LAS unsigned*)(lds + (bufoff) + ldsw + _i * 8192), 16, 0, 0); } while (0)
; #define PG8_LDA(dst, b, h) do { _Pragma("unroll") for (int m = 0; m < 4; ++m) _Pragma("unroll") for (int k = 0; k < 2; ++k) dst[m][k] = *(const LAS bf16x8*)(lds + PG8_SA(b, h) + aoff + m * 2048 + k * 1024); } while (0)
; #define PG8_LDB(dst, b, h) do { _Pragma("unroll") for (int n = 0; n < 2; ++n) _Pragma("unroll") for (int k = 0; k < 2; ++k) dst[n][k] = *(const LAS bf16x8*)(lds + PG8_SB(b, h) + boff + n * 2048 + k * 1024); } while (0)
; #define PG8_MMA(ai, bj, At, Bt) do { __builtin_amdgcn_s_setprio(1); _Pragma("unroll") for (int m = 0; m < 4; ++m) _Pragma("unroll") for (int n = 0; n < 2; ++n) _Pragma("unroll") for (int k = 0; k < 2; ++k) \
;         acc[ai][bj][m][n] = __builtin_amdgcn_mfma_f32_16x16x32_bf16(Bt[n][k], At[m][k], acc[ai][bj][m][n], 0, 0, 0); __builtin_amdgcn_s_setprio(0); } while (0)
; #define PG8_WAIT_V(n) asm volatile("s_waitcnt vmcnt(" #n ")" ::: "memory")
; #define PG8_WAIT_L(n) asm volatile("s_waitcnt lgkmcnt(" #n ")" ::: "memory")
; #define PG8_BAR __builtin_amdgcn_s_barrier()
; #define PG8_SCHED __builtin_amdgcn_sched_barrier(0)
; template <class Epi, class Sched>
; __device__ __forceinline__ void gemm_phase(LAS unsigned char* lds, const Gemm g, const Sched& S, const Epi& E) {
;     ...
;             PG8_BAR; PG8_WAIT_L(0); PG8_MMA(1, 0, At, B0); PG8_BAR; PG8_SCHED;
;             PG8_STAGE(PG8_SB(0, 1), b2 + hstep, voffB);
;             PG8_WAIT_V(6); PG8_BAR; PG8_MMA(1, 1, At, B1); PG8_BAR;
;             PG8_LDB(B0, 1, 0); PG8_SCHED; PG8_LDA(At, 1, 0); PG8_STAGE(PG8_SA(0, 1), a2 + hstep, voffA);
;             PG8_WAIT_L(8); PG8_BAR; PG8_WAIT_L(0); PG8_MMA(0, 0, At, B0); PG8_BAR; PG8_SCHED;
;             PG8_LDB(B1, 1, 1); PG8_STAGE(PG8_SB(1, 0), b3, voffB);
;             PG8_BAR; PG8_WAIT_L(0); PG8_MMA(0, 1, At, B1); PG8_BAR;
	s_waitcnt lgkmcnt(0)
	s_setprio 1
	s_waitcnt lgkmcnt(0)
	v_mfma_f32_16x16x32_bf16 v[116:119], v[202:205], v[168:171], v[116:119]
	v_mfma_f32_16x16x32_bf16 v[108:111], v[210:213], v[168:171], v[108:111]
	v_mfma_f32_16x16x32_bf16 v[100:103], v[202:205], v[176:179], v[100:103]
	v_mfma_f32_16x16x32_bf16 v[92:95], v[210:213], v[176:179], v[92:95]
	v_mfma_f32_16x16x32_bf16 v[84:87], v[202:205], v[184:187], v[84:87]
	v_mfma_f32_16x16x32_bf16 v[76:79], v[210:213], v[184:187], v[76:79]
	v_mfma_f32_16x16x32_bf16 v[68:71], v[202:205], v[192:195], v[68:71]
	v_mfma_f32_16x16x32_bf16 v[64:67], v[210:213], v[192:195], v[64:67]
	v_mfma_f32_16x16x32_bf16 v[116:119], v[206:209], v[172:175], v[116:119]
	v_mfma_f32_16x16x32_bf16 v[108:111], v[214:217], v[172:175], v[108:111]
	v_mfma_f32_16x16x32_bf16 v[100:103], v[206:209], v[180:183], v[100:103]
	v_mfma_f32_16x16x32_bf16 v[92:95], v[214:217], v[180:183], v[92:95]
	v_mfma_f32_16x16x32_bf16 v[84:87], v[206:209], v[188:191], v[84:87]
	v_mfma_f32_16x16x32_bf16 v[76:79], v[214:217], v[188:191], v[76:79]
	v_mfma_f32_16x16x32_bf16 v[68:71], v[206:209], v[196:199], v[68:71]
	v_mfma_f32_16x16x32_bf16 v[64:67], v[214:217], v[196:199], v[64:67]
	s_setprio 0
	s_mov_b32 m0, s21
	v_lshl_add_u64 v[222:223], s[26:27], 0, v[128:129]
	s_barrier
	ds_read_b128 v[168:171], v150 offset:16384
	ds_read_b128 v[172:175], v150 offset:17408
	ds_read_b128 v[176:179], v150 offset:18432
	ds_read_b128 v[180:183], v150 offset:19456
	ds_read_b128 v[184:187], v150 offset:20480
	ds_read_b128 v[188:191], v150 offset:21504
	ds_read_b128 v[192:195], v150 offset:22528
	ds_read_b128 v[196:199], v150 offset:23552
	global_load_lds_dwordx4 v128, s[26:27]
	v_lshl_add_u64 v[224:225], s[26:27], 0, v[132:133]
	s_mov_b32 m0, s31
	s_nop 0
	global_load_lds_dwordx4 v132, s[26:27]
	s_barrier
	s_waitcnt lgkmcnt(0)
	s_setprio 1
	s_waitcnt lgkmcnt(0)
	v_mfma_f32_16x16x32_bf16 v[60:63], v[152:155], v[168:171], v[60:63]
	v_mfma_f32_16x16x32_bf16 v[56:59], v[160:163], v[168:171], v[56:59]
	v_mfma_f32_16x16x32_bf16 v[48:51], v[152:155], v[176:179], v[48:51]
	v_mfma_f32_16x16x32_bf16 v[40:43], v[160:163], v[176:179], v[40:43]
	v_mfma_f32_16x16x32_bf16 v[32:35], v[152:155], v[184:187], v[32:35]
	v_mfma_f32_16x16x32_bf16 v[24:27], v[160:163], v[184:187], v[24:27]
	v_mfma_f32_16x16x32_bf16 v[16:19], v[152:155], v[192:195], v[16:19]
	v_mfma_f32_16x16x32_bf16 v[8:11], v[160:163], v[192:195], v[8:11]
	v_mfma_f32_16x16x32_bf16 v[60:63], v[156:159], v[172:175], v[60:63]
	v_mfma_f32_16x16x32_bf16 v[56:59], v[164:167], v[172:175], v[56:59]
	v_mfma_f32_16x16x32_bf16 v[48:51], v[156:159], v[180:183], v[48:51]
	v_mfma_f32_16x16x32_bf16 v[40:43], v[164:167], v[180:183], v[40:43]
	v_mfma_f32_16x16x32_bf16 v[32:35], v[156:159], v[188:191], v[32:35]
	v_mfma_f32_16x16x32_bf16 v[24:27], v[164:167], v[188:191], v[24:27]
	v_mfma_f32_16x16x32_bf16 v[16:19], v[156:159], v[196:199], v[16:19]
	v_mfma_f32_16x16x32_bf16 v[8:11], v[164:167], v[196:199], v[8:11]
	s_setprio 0
	s_barrier
	s_add_u32 s54, s24, 0x40000
	s_addc_u32 s55, s25, 0
	s_add_i32 s56, s46, s30
	s_mov_b32 m0, s56
	s_nop 0
	global_load_lds_dwordx4 v130, s[54:55]
	s_add_i32 m0, s56, 0x2000
	s_nop 0
	global_load_lds_dwordx4 v134, s[54:55]
	s_waitcnt vmcnt(10)
	s_barrier
	s_setprio 1
	v_mfma_f32_16x16x32_bf16 v[52:55], v[202:205], v[168:171], v[52:55]
	v_mfma_f32_16x16x32_bf16 v[44:47], v[210:213], v[168:171], v[44:47]
	v_mfma_f32_16x16x32_bf16 v[36:39], v[202:205], v[176:179], v[36:39]
	v_mfma_f32_16x16x32_bf16 v[28:31], v[210:213], v[176:179], v[28:31]
	v_mfma_f32_16x16x32_bf16 v[20:23], v[202:205], v[184:187], v[20:23]
	v_mfma_f32_16x16x32_bf16 v[12:15], v[210:213], v[184:187], v[12:15]
	v_mfma_f32_16x16x32_bf16 v[4:7], v[202:205], v[192:195], v[4:7]
	v_mfma_f32_16x16x32_bf16 v[0:3], v[210:213], v[192:195], v[0:3]
	v_mfma_f32_16x16x32_bf16 v[52:55], v[206:209], v[172:175], v[52:55]
	v_mfma_f32_16x16x32_bf16 v[44:47], v[214:217], v[172:175], v[44:47]
	v_mfma_f32_16x16x32_bf16 v[36:39], v[206:209], v[180:183], v[36:39]
	v_mfma_f32_16x16x32_bf16 v[28:31], v[214:217], v[180:183], v[28:31]
	v_mfma_f32_16x16x32_bf16 v[20:23], v[206:209], v[188:191], v[20:23]
	v_mfma_f32_16x16x32_bf16 v[12:15], v[214:217], v[188:191], v[12:15]
	v_mfma_f32_16x16x32_bf16 v[4:7], v[206:209], v[196:199], v[4:7]
	v_mfma_f32_16x16x32_bf16 v[0:3], v[214:217], v[196:199], v[0:3]
	s_setprio 0
	s_add_i32 s54, 0, 0x18000
	v_add_u32_e32 v136, s54, v148
	s_barrier
	ds_read_b128 v[152:155], v136
	ds_read_b128 v[156:159], v136 offset:1024
	ds_read_b128 v[160:163], v136 offset:2048
	ds_read_b128 v[164:167], v136 offset:3072
	s_add_u32 s26, s26, 0x40000
	s_addc_u32 s27, s27, 0
	s_mov_b32 m0, s33
	ds_read_b128 v[168:171], v150 offset:32768
	ds_read_b128 v[172:175], v150 offset:33792
	ds_read_b128 v[176:179], v150 offset:34816
	ds_read_b128 v[180:183], v150 offset:35840
	ds_read_b128 v[184:187], v150 offset:36864
	ds_read_b128 v[188:191], v150 offset:37888
	ds_read_b128 v[192:195], v150 offset:38912
	ds_read_b128 v[196:199], v150 offset:39936
	global_load_lds_dwordx4 v128, s[26:27]
	s_mov_b32 m0, s34
	s_nop 0
	global_load_lds_dwordx4 v132, s[26:27]
	s_waitcnt lgkmcnt(8)
	s_waitcnt vmcnt(10)
	s_barrier
; #define PG8_STAGE(bufoff, gbase, voff) do { _Pragma("unroll") for (int _i = 0; _i < 2; ++_i) \
;         __builtin_amdgcn_global_load_lds((const unsigned*)((const char*)(gbase) + (voff)[_i]), (LAS unsigned*)(lds + (bufoff) + ldsw + _i * 8192), 16, 0, 0); } while (0)
; #define PG8_LDA(dst, b, h) do { _Pragma("unroll") for (int m = 0; m < 4; ++m) _Pragma("unroll") for (int k = 0; k < 2; ++k) dst[m][k] = *(const LAS bf16x8*)(lds + PG8_SA(b, h) + aoff + m * 2048 + k * 1024); } while (0)
; #define PG8_MMA(ai, bj, At, Bt) do { __builtin_amdgcn_s_setprio(1); _Pragma("unroll") for (int m = 0; m < 4; ++m) _Pragma("unroll") for (int n = 0; n < 2; ++n) _Pragma("unroll") for (int k = 0; k < 2; ++k) \
;         acc[ai][bj][m][n] = __builtin_amdgcn_mfma_f32_16x16x32_bf16(Bt[n][k], At[m][k], acc[ai][bj][m][n], 0, 0, 0); __builtin_amdgcn_s_setprio(0); } while (0)
; #define PG8_WAIT_V(n) asm volatile("s_waitcnt vmcnt(" #n ")" ::: "memory")
; #define PG8_WAIT_L(n) asm volatile("s_waitcnt lgkmcnt(" #n ")" ::: "memory")
; #define PG8_BAR __builtin_amdgcn_s_barrier()
; #define PG8_SCHED __builtin_amdgcn_sched_barrier(0)
; template <class Epi, class Sched>
; __device__ __forceinline__ void gemm_phase(LAS unsigned char* lds, const Gemm g, const Sched& S, const Epi& E) {
;     ...
;             PG8_BAR; PG8_WAIT_L(0); PG8_MMA(0, 1, At, B1); PG8_BAR;
;             PG8_LDA(At, 1, 1); PG8_STAGE(PG8_SA(1, 0), a3, voffA);
;             PG8_BAR; PG8_WAIT_L(0); PG8_MMA(1, 0, At, B0); PG8_BAR; PG8_SCHED;
;             PG8_STAGE(PG8_SB(1, 1), b3 + hstep, voffB);
;             PG8_WAIT_V(6); PG8_BAR; PG8_MMA(1, 1, At, B1); PG8_BAR;
	s_waitcnt lgkmcnt(0)
	s_setprio 1
	s_waitcnt lgkmcnt(0)
	v_mfma_f32_16x16x32_bf16 v[124:127], v[152:155], v[168:171], v[124:127]
	v_mfma_f32_16x16x32_bf16 v[120:123], v[160:163], v[168:171], v[120:123]
	v_mfma_f32_16x16x32_bf16 v[112:115], v[152:155], v[176:179], v[112:115]
	v_mfma_f32_16x16x32_bf16 v[104:107], v[160:163], v[176:179], v[104:107]
	v_mfma_f32_16x16x32_bf16 v[96:99], v[152:155], v[184:187], v[96:99]
	v_mfma_f32_16x16x32_bf16 v[88:91], v[160:163], v[184:187], v[88:91]
	v_mfma_f32_16x16x32_bf16 v[80:83], v[152:155], v[192:195], v[80:83]
	v_mfma_f32_16x16x32_bf16 v[72:75], v[160:163], v[192:195], v[72:75]
	v_mfma_f32_16x16x32_bf16 v[124:127], v[156:159], v[172:175], v[124:127]
	v_mfma_f32_16x16x32_bf16 v[120:123], v[164:167], v[172:175], v[120:123]
	v_mfma_f32_16x16x32_bf16 v[112:115], v[156:159], v[180:183], v[112:115]
	v_mfma_f32_16x16x32_bf16 v[104:107], v[164:167], v[180:183], v[104:107]
	v_mfma_f32_16x16x32_bf16 v[96:99], v[156:159], v[188:191], v[96:99]
	v_mfma_f32_16x16x32_bf16 v[88:91], v[164:167], v[188:191], v[88:91]
	v_mfma_f32_16x16x32_bf16 v[80:83], v[156:159], v[196:199], v[80:83]
	v_mfma_f32_16x16x32_bf16 v[72:75], v[164:167], v[196:199], v[72:75]
	s_setprio 0
	s_barrier
	s_add_i32 s26, 0, 0x1c000
	s_add_i32 s27, s54, s30
	v_add_u32_e32 v136, s26, v148
	s_add_u32 s0, s24, 0x80
	s_addc_u32 s1, s25, 0
	s_mov_b32 m0, s27
	ds_read_b128 v[202:205], v136
	ds_read_b128 v[206:209], v136 offset:1024
	ds_read_b128 v[210:213], v136 offset:2048
	ds_read_b128 v[214:217], v136 offset:3072
	global_load_lds_dwordx4 v130, s[0:1]
	s_add_i32 m0, s27, 0x2000
	s_nop 0
	global_load_lds_dwordx4 v134, s[0:1]
	s_waitcnt vmcnt(10)
	s_barrier
	s_waitcnt lgkmcnt(0)
	s_setprio 1
	s_waitcnt lgkmcnt(0)
	v_mfma_f32_16x16x32_bf16 v[116:119], v[202:205], v[168:171], v[116:119]
	v_mfma_f32_16x16x32_bf16 v[108:111], v[210:213], v[168:171], v[108:111]
	v_mfma_f32_16x16x32_bf16 v[100:103], v[202:205], v[176:179], v[100:103]
	v_mfma_f32_16x16x32_bf16 v[92:95], v[210:213], v[176:179], v[92:95]
	v_mfma_f32_16x16x32_bf16 v[84:87], v[202:205], v[184:187], v[84:87]
	v_mfma_f32_16x16x32_bf16 v[76:79], v[210:213], v[184:187], v[76:79]
	v_mfma_f32_16x16x32_bf16 v[68:71], v[202:205], v[192:195], v[68:71]
	v_mfma_f32_16x16x32_bf16 v[64:67], v[210:213], v[192:195], v[64:67]
	v_mfma_f32_16x16x32_bf16 v[116:119], v[206:209], v[172:175], v[116:119]
	v_mfma_f32_16x16x32_bf16 v[108:111], v[214:217], v[172:175], v[108:111]
	v_mfma_f32_16x16x32_bf16 v[100:103], v[206:209], v[180:183], v[100:103]
	v_mfma_f32_16x16x32_bf16 v[92:95], v[214:217], v[180:183], v[92:95]
	v_mfma_f32_16x16x32_bf16 v[84:87], v[206:209], v[188:191], v[84:87]
	v_mfma_f32_16x16x32_bf16 v[76:79], v[214:217], v[188:191], v[76:79]
	v_mfma_f32_16x16x32_bf16 v[68:71], v[206:209], v[196:199], v[68:71]
	v_mfma_f32_16x16x32_bf16 v[64:67], v[214:217], v[196:199], v[64:67]
	s_setprio 0
	s_mov_b32 m0, s42
	s_mov_b64 s[0:1], 0x80
	v_lshl_add_u64 v[218:219], v[222:223], 0, s[0:1]
	s_barrier
	ds_read_b128 v[168:171], v150 offset:49152
	ds_read_b128 v[172:175], v150 offset:50176
	ds_read_b128 v[176:179], v150 offset:51200
	ds_read_b128 v[180:183], v150 offset:52224
	ds_read_b128 v[184:187], v150 offset:53248
	ds_read_b128 v[188:191], v150 offset:54272
	ds_read_b128 v[192:195], v150 offset:55296
	ds_read_b128 v[196:199], v150 offset:56320
	global_load_lds_dwordx4 v[218:219], off
	v_lshl_add_u64 v[218:219], v[224:225], 0, s[0:1]
	s_mov_b32 m0, s43
	s_nop 0
	global_load_lds_dwordx4 v[218:219], off
	s_barrier
	s_waitcnt lgkmcnt(0)
	s_setprio 1
	s_waitcnt lgkmcnt(0)
	v_mfma_f32_16x16x32_bf16 v[60:63], v[152:155], v[168:171], v[60:63]
	v_mfma_f32_16x16x32_bf16 v[56:59], v[160:163], v[168:171], v[56:59]
	v_mfma_f32_16x16x32_bf16 v[48:51], v[152:155], v[176:179], v[48:51]
	v_mfma_f32_16x16x32_bf16 v[40:43], v[160:163], v[176:179], v[40:43]
	v_mfma_f32_16x16x32_bf16 v[32:35], v[152:155], v[184:187], v[32:35]
	v_mfma_f32_16x16x32_bf16 v[24:27], v[160:163], v[184:187], v[24:27]
	v_mfma_f32_16x16x32_bf16 v[16:19], v[152:155], v[192:195], v[16:19]
	v_mfma_f32_16x16x32_bf16 v[8:11], v[160:163], v[192:195], v[8:11]
	v_mfma_f32_16x16x32_bf16 v[60:63], v[156:159], v[172:175], v[60:63]
	v_mfma_f32_16x16x32_bf16 v[56:59], v[164:167], v[172:175], v[56:59]
	v_mfma_f32_16x16x32_bf16 v[48:51], v[156:159], v[180:183], v[48:51]
	v_mfma_f32_16x16x32_bf16 v[40:43], v[164:167], v[180:183], v[40:43]
	v_mfma_f32_16x16x32_bf16 v[32:35], v[156:159], v[188:191], v[32:35]
	v_mfma_f32_16x16x32_bf16 v[24:27], v[164:167], v[188:191], v[24:27]
	v_mfma_f32_16x16x32_bf16 v[16:19], v[156:159], v[196:199], v[16:19]
	v_mfma_f32_16x16x32_bf16 v[8:11], v[164:167], v[196:199], v[8:11]
	s_setprio 0
	s_barrier
	s_add_u32 s24, s24, 0x40080
	s_addc_u32 s25, s25, 0
	s_add_i32 s26, s26, s30
	s_mov_b32 m0, s26
	s_nop 0
	global_load_lds_dwordx4 v130, s[24:25]
	s_add_i32 m0, s26, 0x2000
	s_nop 0
	global_load_lds_dwordx4 v134, s[24:25]
	s_waitcnt vmcnt(10)
	s_barrier
	s_setprio 1
	v_mfma_f32_16x16x32_bf16 v[52:55], v[202:205], v[168:171], v[52:55]
	v_mfma_f32_16x16x32_bf16 v[44:47], v[210:213], v[168:171], v[44:47]
	v_mfma_f32_16x16x32_bf16 v[36:39], v[202:205], v[176:179], v[36:39]
	v_mfma_f32_16x16x32_bf16 v[28:31], v[210:213], v[176:179], v[28:31]
	v_mfma_f32_16x16x32_bf16 v[20:23], v[202:205], v[184:187], v[20:23]
	v_mfma_f32_16x16x32_bf16 v[12:15], v[210:213], v[184:187], v[12:15]
	v_mfma_f32_16x16x32_bf16 v[4:7], v[202:205], v[192:195], v[4:7]
	v_mfma_f32_16x16x32_bf16 v[0:3], v[210:213], v[192:195], v[0:3]
	v_mfma_f32_16x16x32_bf16 v[52:55], v[206:209], v[172:175], v[52:55]
	v_mfma_f32_16x16x32_bf16 v[44:47], v[214:217], v[172:175], v[44:47]
	v_mfma_f32_16x16x32_bf16 v[36:39], v[206:209], v[180:183], v[36:39]
	v_mfma_f32_16x16x32_bf16 v[28:31], v[214:217], v[180:183], v[28:31]
	v_mfma_f32_16x16x32_bf16 v[20:23], v[206:209], v[188:191], v[20:23]
	v_mfma_f32_16x16x32_bf16 v[12:15], v[214:217], v[188:191], v[12:15]
	v_mfma_f32_16x16x32_bf16 v[4:7], v[206:209], v[196:199], v[4:7]
	v_mfma_f32_16x16x32_bf16 v[0:3], v[214:217], v[196:199], v[0:3]
	s_setprio 0
	s_add_i32 s53, s53, 2
	s_add_u32 s22, s22, 0x100
	s_addc_u32 s23, s23, 0
	s_add_u32 s51, s51, 0x100
	s_addc_u32 s52, s52, 0
	s_cmp_gt_u32 s53, 13
	s_barrier
; __device__ __forceinline__ unsigned cvt_pk_bf16(float lo, float hi) { unsigned r; asm volatile("v_cvt_pk_bf16_f32 %0, %1, %2" : "=v"(r) : "v"(lo), "v"(hi)); return r; }
;     __device__ __forceinline__ void operator()(const AccT& acc, const Unit& u, int wr, int wc, int fr, int fq) const {
;         asm volatile("" : "+v"(fr), "+v"(fq));
;         const int rbase = u.pm * 256 + wr * 64 + fr;
;         const int tb = u.pn * 256 + wc * 32 + 8 * fq;
; #pragma unroll
;         for (int ai = 0; ai < 2; ++ai)
; #pragma unroll
;             for (int m = 0; m < 4; ++m) {
;                 const int gm = rbase + ai * 128 + m * 16;
; #pragma unroll
;                 for (int bj = 0; bj < 2; ++bj) {
;                     const int t0 = tb + bj * 128;
;                     const f32x4 v0 = acc[ai][bj][m][0], v1 = acc[ai][bj][m][1];
;                     u32x4 w; w.x = cvt_pk_bf16(v0[0], v0[1]); w.y = cvt_pk_bf16(v0[2], v0[3]); w.z = cvt_pk_bf16(v1[0], v1[1]); w.w = cvt_pk_bf16(v1[2], v1[3]);
;                     *(u32x4*)(YT + ((size_t)((t0 >> 10) * 512 + gm)) * 2048 + part * 1024 + (t0 & 1023)) = w;
;                 }
;             }
	s_cbranch_scc0 .LBB0_653
	v_mov_b32_e32 v136, v147
	v_mov_b32_e32 v152, v146
	s_lshl_b32 s7, s20, 8
	s_add_i32 s7, s7, s36
	v_add_u32_e32 v152, s7, v152
	s_lshl_b32 s7, s47, 8
	s_or_b32 s7, s7, s37
	v_lshl_add_u32 v153, v136, 3, s7
	v_cvt_pk_bf16_f32 v124, v124, v125
	v_cvt_pk_bf16_f32 v125, v126, v127
	v_cvt_pk_bf16_f32 v126, v120, v121
	v_ashrrev_i32_e32 v120, 1, v153
	v_cvt_pk_bf16_f32 v127, v122, v123
	v_and_b32_e32 v122, 0xfffffe00, v120
	v_add_u32_e32 v120, v122, v152
	v_ashrrev_i32_e32 v121, 31, v120
	v_lshlrev_b64 v[120:121], 12, v[120:121]
	v_and_b32_e32 v123, 0x3f8, v153
	v_lshl_add_u64 v[120:121], s[68:69], 0, v[120:121]
	v_lshlrev_b32_e32 v136, 1, v123
	v_lshl_add_u64 v[120:121], v[120:121], 0, v[136:137]
	global_store_dwordx4 v[120:121], v[124:127], off
	v_add_u32_e32 v120, 0x80, v153
	v_cvt_pk_bf16_f32 v116, v116, v117
	v_cvt_pk_bf16_f32 v117, v118, v119
	v_cvt_pk_bf16_f32 v118, v108, v109
	v_ashrrev_i32_e32 v108, 1, v120
	v_and_b32_e32 v121, 0xfffffe00, v108
	v_add_u32_e32 v108, v121, v152
	v_ashrrev_i32_e32 v109, 31, v108
	v_lshlrev_b64 v[108:109], 12, v[108:109]
	v_cvt_pk_bf16_f32 v119, v110, v111
	v_lshl_add_u64 v[110:111], s[68:69], 0, v[108:109]
	v_and_b32_e32 v108, 0x3f8, v120
	v_lshlrev_b32_e32 v108, 1, v108
	v_mov_b32_e32 v109, v137
	v_lshl_add_u64 v[110:111], v[110:111], 0, v[108:109]
	global_store_dwordx4 v[110:111], v[116:119], off
	v_cvt_pk_bf16_f32 v110, v112, v113
	v_cvt_pk_bf16_f32 v111, v114, v115
	v_cvt_pk_bf16_f32 v112, v104, v105
	v_cvt_pk_bf16_f32 v113, v106, v107
	s_and_b64 vcc, exec, s[4:5]
	s_nop 0
	v_add_u32_e32 v116, 16, v152
	v_add_u32_e32 v104, v122, v116
	v_ashrrev_i32_e32 v105, 31, v104
	v_lshlrev_b64 v[104:105], 12, v[104:105]
	v_lshl_add_u64 v[104:105], s[68:69], 0, v[104:105]
	v_lshl_add_u64 v[104:105], v[104:105], 0, v[136:137]
	global_store_dwordx4 v[104:105], v[110:113], off
	v_cvt_pk_bf16_f32 v100, v100, v101
	v_cvt_pk_bf16_f32 v101, v102, v103
	v_cvt_pk_bf16_f32 v102, v92, v93
	v_add_u32_e32 v92, v121, v116
	v_ashrrev_i32_e32 v93, 31, v92
	v_lshlrev_b64 v[92:93], 12, v[92:93]
	v_lshl_add_u64 v[92:93], s[68:69], 0, v[92:93]
	v_lshl_add_u64 v[92:93], v[92:93], 0, v[108:109]
	v_cvt_pk_bf16_f32 v103, v94, v95
	global_store_dwordx4 v[92:93], v[100:103], off
	v_cvt_pk_bf16_f32 v92, v96, v97
	v_cvt_pk_bf16_f32 v93, v98, v99
	v_cvt_pk_bf16_f32 v94, v88, v89
	v_cvt_pk_bf16_f32 v95, v90, v91
	s_mov_b32 s47, s6
	s_nop 0
	v_add_u32_e32 v100, 32, v152
	v_add_u32_e32 v88, v122, v100
	v_ashrrev_i32_e32 v89, 31, v88
	v_lshlrev_b64 v[88:89], 12, v[88:89]
	v_lshl_add_u64 v[88:89], s[68:69], 0, v[88:89]
	v_lshl_add_u64 v[88:89], v[88:89], 0, v[136:137]
	global_store_dwordx4 v[88:89], v[92:95], off
	v_cvt_pk_bf16_f32 v84, v84, v85
	v_cvt_pk_bf16_f32 v85, v86, v87
	v_cvt_pk_bf16_f32 v86, v76, v77
	v_add_u32_e32 v76, v121, v100
	v_ashrrev_i32_e32 v77, 31, v76
	v_lshlrev_b64 v[76:77], 12, v[76:77]
	v_lshl_add_u64 v[76:77], s[68:69], 0, v[76:77]
	v_lshl_add_u64 v[76:77], v[76:77], 0, v[108:109]
	v_cvt_pk_bf16_f32 v87, v78, v79
	global_store_dwordx4 v[76:77], v[84:87], off
	v_cvt_pk_bf16_f32 v76, v80, v81
	v_cvt_pk_bf16_f32 v77, v82, v83
	v_cvt_pk_bf16_f32 v78, v72, v73
	v_cvt_pk_bf16_f32 v79, v74, v75
	s_mov_b32 s20, s8
	s_nop 0
	v_add_u32_e32 v84, 48, v152
	v_add_u32_e32 v72, v122, v84
	v_ashrrev_i32_e32 v73, 31, v72
	v_lshlrev_b64 v[72:73], 12, v[72:73]
	v_lshl_add_u64 v[72:73], s[68:69], 0, v[72:73]
	v_lshl_add_u64 v[72:73], v[72:73], 0, v[136:137]
	global_store_dwordx4 v[72:73], v[76:79], off
	v_cvt_pk_bf16_f32 v68, v68, v69
	v_cvt_pk_bf16_f32 v69, v70, v71
; __device__ __forceinline__ unsigned cvt_pk_bf16(float lo, float hi) { unsigned r; asm volatile("v_cvt_pk_bf16_f32 %0, %1, %2" : "=v"(r) : "v"(lo), "v"(hi)); return r; }
; #define PG8_WAIT_V(n) asm volatile("s_waitcnt vmcnt(" #n ")" ::: "memory")
; #define PG8_BAR __builtin_amdgcn_s_barrier()
; template <class Epi, class Sched>
; __device__ __forceinline__ void gemm_phase(LAS unsigned char* lds, const Gemm g, const Sched& S, const Epi& E) {
;     ...
;     PG8_WAIT_V(0);
;     if (wr == 0) PG8_BAR;
;     PG8_BAR;
;     __device__ __forceinline__ void operator()(const AccT& acc, const Unit& u, int wr, int wc, int fr, int fq) const {
;         asm volatile("" : "+v"(fr), "+v"(fq));
;         const int rbase = u.pm * 256 + wr * 64 + fr;
;         const int tb = u.pn * 256 + wc * 32 + 8 * fq;
; #pragma unroll
;         for (int ai = 0; ai < 2; ++ai)
; #pragma unroll
;             for (int m = 0; m < 4; ++m) {
;                 const int gm = rbase + ai * 128 + m * 16;
; #pragma unroll
;                 for (int bj = 0; bj < 2; ++bj) {
;                     const int t0 = tb + bj * 128;
;                     const f32x4 v0 = acc[ai][bj][m][0], v1 = acc[ai][bj][m][1];
;                     u32x4 w; w.x = cvt_pk_bf16(v0[0], v0[1]); w.y = cvt_pk_bf16(v0[2], v0[3]); w.z = cvt_pk_bf16(v1[0], v1[1]); w.w = cvt_pk_bf16(v1[2], v1[3]);
;                     *(u32x4*)(YT + ((size_t)((t0 >> 10) * 512 + gm)) * 2048 + part * 1024 + (t0 & 1023)) = w;
;                 }
;             }
	v_cvt_pk_bf16_f32 v70, v64, v65
	v_add_u32_e32 v64, v121, v84
	v_ashrrev_i32_e32 v65, 31, v64
	v_lshlrev_b64 v[64:65], 12, v[64:65]
	v_lshl_add_u64 v[64:65], s[68:69], 0, v[64:65]
	v_lshl_add_u64 v[64:65], v[64:65], 0, v[108:109]
	v_cvt_pk_bf16_f32 v71, v66, v67
	global_store_dwordx4 v[64:65], v[68:71], off
	v_add_u32_e32 v64, 0x80, v152
	v_cvt_pk_bf16_f32 v60, v60, v61
	v_cvt_pk_bf16_f32 v61, v62, v63
	v_cvt_pk_bf16_f32 v62, v56, v57
	v_add_u32_e32 v56, v122, v64
	v_ashrrev_i32_e32 v57, 31, v56
	v_lshlrev_b64 v[56:57], 12, v[56:57]
	v_lshl_add_u64 v[56:57], s[68:69], 0, v[56:57]
	v_lshl_add_u64 v[56:57], v[56:57], 0, v[136:137]
	v_cvt_pk_bf16_f32 v63, v58, v59
	global_store_dwordx4 v[56:57], v[60:63], off
	v_cvt_pk_bf16_f32 v52, v52, v53
	v_cvt_pk_bf16_f32 v53, v54, v55
	v_cvt_pk_bf16_f32 v54, v44, v45
	v_add_u32_e32 v44, v121, v64
	v_ashrrev_i32_e32 v45, 31, v44
	v_lshlrev_b64 v[44:45], 12, v[44:45]
	v_lshl_add_u64 v[44:45], s[68:69], 0, v[44:45]
	v_lshl_add_u64 v[44:45], v[44:45], 0, v[108:109]
	v_cvt_pk_bf16_f32 v55, v46, v47
	global_store_dwordx4 v[44:45], v[52:55], off
	v_cvt_pk_bf16_f32 v44, v48, v49
	v_cvt_pk_bf16_f32 v45, v50, v51
	v_cvt_pk_bf16_f32 v46, v40, v41
	v_cvt_pk_bf16_f32 v47, v42, v43
	s_mov_b64 s[24:25], s[18:19]
	s_nop 0
	v_add_u32_e32 v52, 0x90, v152
	v_add_u32_e32 v40, v122, v52
	v_ashrrev_i32_e32 v41, 31, v40
	v_lshlrev_b64 v[40:41], 12, v[40:41]
	v_lshl_add_u64 v[40:41], s[68:69], 0, v[40:41]
	v_lshl_add_u64 v[40:41], v[40:41], 0, v[136:137]
	global_store_dwordx4 v[40:41], v[44:47], off
	v_cvt_pk_bf16_f32 v36, v36, v37
	v_cvt_pk_bf16_f32 v37, v38, v39
	v_cvt_pk_bf16_f32 v38, v28, v29
	v_add_u32_e32 v28, v121, v52
	v_ashrrev_i32_e32 v29, 31, v28
	v_lshlrev_b64 v[28:29], 12, v[28:29]
	v_lshl_add_u64 v[28:29], s[68:69], 0, v[28:29]
	v_lshl_add_u64 v[28:29], v[28:29], 0, v[108:109]
	v_cvt_pk_bf16_f32 v39, v30, v31
	global_store_dwordx4 v[28:29], v[36:39], off
	v_cvt_pk_bf16_f32 v28, v32, v33
	v_cvt_pk_bf16_f32 v29, v34, v35
	v_cvt_pk_bf16_f32 v30, v24, v25
	v_cvt_pk_bf16_f32 v31, v26, v27
	s_mov_b64 s[22:23], s[16:17]
	s_nop 0
	v_add_u32_e32 v36, 0xa0, v152
	v_add_u32_e32 v24, v122, v36
	v_ashrrev_i32_e32 v25, 31, v24
	v_lshlrev_b64 v[24:25], 12, v[24:25]
	v_lshl_add_u64 v[24:25], s[68:69], 0, v[24:25]
	v_lshl_add_u64 v[24:25], v[24:25], 0, v[136:137]
	global_store_dwordx4 v[24:25], v[28:31], off
	v_cvt_pk_bf16_f32 v20, v20, v21
	v_cvt_pk_bf16_f32 v21, v22, v23
	v_cvt_pk_bf16_f32 v22, v12, v13
	v_add_u32_e32 v12, v121, v36
	v_ashrrev_i32_e32 v13, 31, v12
	v_lshlrev_b64 v[12:13], 12, v[12:13]
	v_lshl_add_u64 v[12:13], s[68:69], 0, v[12:13]
	v_lshl_add_u64 v[12:13], v[12:13], 0, v[108:109]
	v_cvt_pk_bf16_f32 v23, v14, v15
	global_store_dwordx4 v[12:13], v[20:23], off
	v_cvt_pk_bf16_f32 v12, v16, v17
	v_cvt_pk_bf16_f32 v13, v18, v19
	v_cvt_pk_bf16_f32 v14, v8, v9
	v_cvt_pk_bf16_f32 v15, v10, v11
	s_nop 1
	v_add_u32_e32 v20, 0xb0, v152
	v_add_u32_e32 v8, v122, v20
	v_ashrrev_i32_e32 v9, 31, v8
	v_lshlrev_b64 v[8:9], 12, v[8:9]
	v_lshl_add_u64 v[8:9], s[68:69], 0, v[8:9]
	v_lshl_add_u64 v[8:9], v[8:9], 0, v[136:137]
	global_store_dwordx4 v[8:9], v[12:15], off
	v_cvt_pk_bf16_f32 v4, v4, v5
	v_cvt_pk_bf16_f32 v5, v6, v7
	v_cvt_pk_bf16_f32 v6, v0, v1
	v_add_u32_e32 v0, v121, v20
	v_ashrrev_i32_e32 v1, 31, v0
	v_lshlrev_b64 v[0:1], 12, v[0:1]
	v_lshl_add_u64 v[0:1], s[68:69], 0, v[0:1]
	v_lshl_add_u64 v[0:1], v[0:1], 0, v[108:109]
	v_cvt_pk_bf16_f32 v7, v2, v3
	global_store_dwordx4 v[0:1], v[4:7], off
	s_cbranch_vccz .LBB0_646
	s_waitcnt vmcnt(0)
	s_cmpk_gt_u32 s28, 0xff
	s_cbranch_scc1 .LBB0_657
	s_barrier

; #define PG8_STAGE(bufoff, gbase, voff) do { _Pragma("unroll") for (int _i = 0; _i < 2; ++_i) \
;         __builtin_amdgcn_global_load_lds((const unsigned*)((const char*)(gbase) + (voff)[_i]), (LAS unsigned*)(lds + (bufoff) + ldsw + _i * 8192), 16, 0, 0); } while (0)
; #define PG8_LDA(dst, b, h) do { _Pragma("unroll") for (int m = 0; m < 4; ++m) _Pragma("unroll") for (int k = 0; k < 2; ++k) dst[m][k] = *(const LAS bf16x8*)(lds + PG8_SA(b, h) + aoff + m * 2048 + k * 1024); } while (0)
; #define PG8_LDB(dst, b, h) do { _Pragma("unroll") for (int n = 0; n < 2; ++n) _Pragma("unroll") for (int k = 0; k < 2; ++k) dst[n][k] = *(const LAS bf16x8*)(lds + PG8_SB(b, h) + boff + n * 2048 + k * 1024); } while (0)
; #define PG8_WAIT_V(n) asm volatile("s_waitcnt vmcnt(" #n ")" ::: "memory")
; #define PG8_WAIT_L(n) asm volatile("s_waitcnt lgkmcnt(" #n ")" ::: "memory")
; #define PG8_BAR __builtin_amdgcn_s_barrier()
; #define PG8_SCHED __builtin_amdgcn_sched_barrier(0)
; template <class Epi, class Sched>
; __device__ __forceinline__ void gemm_phase(LAS unsigned char* lds, const Gemm g, const Sched& S, const Epi& E) {
;     ...
;         const bool has_next = S.next(ui + 1, nxt);
;         const char* nA = has_next ? (const char*)g.A + (size_t)nxt.pm * tstep : cA; const char* nB = has_next ? (const char*)g.Bt + (size_t)nxt.pn * tstep : cB;
;         for (int t = 0; t < nt; t += 2) {
;             const bool last = (t == nt - 2);
;             const char* a1 = cA + (size_t)(t + 1) * kstep;
;             const char* a2 = last ? nA : cA + (size_t)(t + 2) * kstep; const char* b2 = last ? nB : cB + (size_t)(t + 2) * kstep;
;             const char* a3 = a2 + kstep; const char* b3 = b2 + kstep;
;             PG8_LDB(B0, 0, 0); PG8_SCHED; PG8_LDA(At, 0, 0); PG8_STAGE(PG8_SA(1, 1), a1 + hstep, voffA);
;             PG8_WAIT_L(8); PG8_BAR; PG8_WAIT_L(0); PG8_MMA(0, 0, At, B0); PG8_BAR; PG8_SCHED;
;             PG8_LDB(B1, 0, 1); PG8_STAGE(PG8_SB(0, 0), b2, voffB);
;             PG8_BAR; PG8_WAIT_L(0); PG8_MMA(0, 1, At, B1); PG8_BAR;
;             PG8_LDA(At, 0, 1); PG8_STAGE(PG8_SA(0, 0), a2, voffA);
;             PG8_BAR; PG8_WAIT_L(0); PG8_MMA(1, 0, At, B0); PG8_BAR; PG8_SCHED;
;             PG8_STAGE(PG8_SB(0, 1), b2 + hstep, voffB);
;             PG8_WAIT_V(6); PG8_BAR; PG8_MMA(1, 1, At, B1); PG8_BAR;
.LBB0_672:
	s_ashr_i32 s9, s8, 31
	v_cmp_lt_i64_e32 vcc, s[12:13], v[142:143]
	s_lshl_b64 s[12:13], s[8:9], 19
	s_add_u32 s12, s26, s12
	s_addc_u32 s13, s27, s13
	s_and_b64 s[14:15], vcc, exec
	s_cselect_b32 s9, s13, s19
	s_cselect_b32 s46, s12, s18
	s_ashr_i32 s7, s6, 31
	s_lshl_b64 s[14:15], s[6:7], 19
	s_add_u32 s14, s10, s14
	s_addc_u32 s15, s11, s15
	s_and_b64 s[22:23], vcc, exec
	s_cselect_b32 s7, s15, s21
	s_cselect_b32 s47, s14, s20
	s_add_u32 s18, s18, 0x40080
	s_addc_u32 s19, s19, 0
	s_add_u32 s48, s20, 0x100
	s_addc_u32 s49, s21, 0
	s_mov_b32 s51, -2
	s_waitcnt lgkmcnt(0)
	ds_read_b128 v[152:155], v149
	ds_read_b128 v[156:159], v149 offset:1024
	ds_read_b128 v[160:163], v149 offset:2048
	ds_read_b128 v[164:167], v149 offset:3072
	s_add_u32 s20, s18, 0xfffc0080
	s_addc_u32 s21, s19, -1
	s_cmp_eq_u32 s51, 12
	s_cselect_b32 s23, s9, s21
	s_cselect_b32 s22, s46, s20
	s_cselect_b32 s21, s7, s49
	s_cselect_b32 s20, s47, s48
	s_add_i32 m0, s17, 0xc000
	ds_read_b128 v[168:171], v150
	ds_read_b128 v[172:175], v150 offset:1024
	ds_read_b128 v[176:179], v150 offset:2048
	ds_read_b128 v[180:183], v150 offset:3072
	ds_read_b128 v[184:187], v150 offset:4096
	ds_read_b128 v[188:191], v150 offset:5120
	ds_read_b128 v[192:195], v150 offset:6144
	ds_read_b128 v[196:199], v150 offset:7168
	global_load_lds_dwordx4 v138, s[18:19]
	s_add_i32 m0, s17, 0xe000
	s_nop 0
	global_load_lds_dwordx4 v140, s[18:19]
	s_waitcnt lgkmcnt(8)
	s_waitcnt vmcnt(10)
	s_barrier
	s_waitcnt lgkmcnt(0)
	s_setprio 1
	s_waitcnt lgkmcnt(0)
	v_mfma_f32_16x16x32_bf16 v[124:127], v[152:155], v[168:171], 0
	v_mfma_f32_16x16x32_bf16 v[120:123], v[160:163], v[168:171], 0
	v_mfma_f32_16x16x32_bf16 v[112:115], v[152:155], v[176:179], 0
	v_mfma_f32_16x16x32_bf16 v[104:107], v[160:163], v[176:179], 0
	v_mfma_f32_16x16x32_bf16 v[96:99], v[152:155], v[184:187], 0
	v_mfma_f32_16x16x32_bf16 v[88:91], v[160:163], v[184:187], 0
	v_mfma_f32_16x16x32_bf16 v[80:83], v[152:155], v[192:195], 0
	v_mfma_f32_16x16x32_bf16 v[72:75], v[160:163], v[192:195], 0
	v_mfma_f32_16x16x32_bf16 v[124:127], v[156:159], v[172:175], v[124:127]
	v_mfma_f32_16x16x32_bf16 v[120:123], v[164:167], v[172:175], v[120:123]
	v_mfma_f32_16x16x32_bf16 v[112:115], v[156:159], v[180:183], v[112:115]
	v_mfma_f32_16x16x32_bf16 v[104:107], v[164:167], v[180:183], v[104:107]
	v_mfma_f32_16x16x32_bf16 v[96:99], v[156:159], v[188:191], v[96:99]
	v_mfma_f32_16x16x32_bf16 v[88:91], v[164:167], v[188:191], v[88:91]
	v_mfma_f32_16x16x32_bf16 v[80:83], v[156:159], v[196:199], v[80:83]
	v_mfma_f32_16x16x32_bf16 v[72:75], v[164:167], v[196:199], v[72:75]
	s_setprio 0
	s_barrier
	s_add_i32 s52, s43, s28
	s_mov_b32 m0, s52
	ds_read_b128 v[202:205], v151
	ds_read_b128 v[206:209], v151 offset:1024
	ds_read_b128 v[210:213], v151 offset:2048
	ds_read_b128 v[214:217], v151 offset:3072
	global_load_lds_dwordx4 v130, s[20:21]
	s_add_i32 m0, s52, 0x2000
	s_nop 0
	global_load_lds_dwordx4 v134, s[20:21]
	s_waitcnt vmcnt(10)
	s_barrier
	s_waitcnt lgkmcnt(0)
	s_setprio 1
	s_waitcnt lgkmcnt(0)
	v_mfma_f32_16x16x32_bf16 v[116:119], v[202:205], v[168:171], 0
	v_mfma_f32_16x16x32_bf16 v[108:111], v[210:213], v[168:171], 0
	v_mfma_f32_16x16x32_bf16 v[100:103], v[202:205], v[176:179], 0
	v_mfma_f32_16x16x32_bf16 v[92:95], v[210:213], v[176:179], 0
	v_mfma_f32_16x16x32_bf16 v[84:87], v[202:205], v[184:187], 0
	v_mfma_f32_16x16x32_bf16 v[76:79], v[210:213], v[184:187], 0
	v_mfma_f32_16x16x32_bf16 v[68:71], v[202:205], v[192:195], 0
	v_mfma_f32_16x16x32_bf16 v[64:67], v[210:213], v[192:195], 0
	v_mfma_f32_16x16x32_bf16 v[116:119], v[206:209], v[172:175], v[116:119]
	v_mfma_f32_16x16x32_bf16 v[108:111], v[214:217], v[172:175], v[108:111]
	v_mfma_f32_16x16x32_bf16 v[100:103], v[206:209], v[180:183], v[100:103]
	v_mfma_f32_16x16x32_bf16 v[92:95], v[214:217], v[180:183], v[92:95]
	v_mfma_f32_16x16x32_bf16 v[84:87], v[206:209], v[188:191], v[84:87]
	v_mfma_f32_16x16x32_bf16 v[76:79], v[214:217], v[188:191], v[76:79]
	v_mfma_f32_16x16x32_bf16 v[68:71], v[206:209], v[196:199], v[68:71]
	v_mfma_f32_16x16x32_bf16 v[64:67], v[214:217], v[196:199], v[64:67]
	s_setprio 0
	s_mov_b32 m0, s17
	v_lshl_add_u64 v[222:223], s[22:23], 0, v[128:129]
	s_barrier
	ds_read_b128 v[168:171], v150 offset:16384
	ds_read_b128 v[172:175], v150 offset:17408
	ds_read_b128 v[176:179], v150 offset:18432
	ds_read_b128 v[180:183], v150 offset:19456
	ds_read_b128 v[184:187], v150 offset:20480
	ds_read_b128 v[188:191], v150 offset:21504
	ds_read_b128 v[192:195], v150 offset:22528
	ds_read_b128 v[196:199], v150 offset:23552
	global_load_lds_dwordx4 v128, s[22:23]
	v_lshl_add_u64 v[224:225], s[22:23], 0, v[132:133]
	s_mov_b32 m0, s29
	s_nop 0
	global_load_lds_dwordx4 v132, s[22:23]
	s_barrier
	s_waitcnt lgkmcnt(0)
	s_setprio 1
	s_waitcnt lgkmcnt(0)
	v_mfma_f32_16x16x32_bf16 v[60:63], v[152:155], v[168:171], 0
	v_mfma_f32_16x16x32_bf16 v[56:59], v[160:163], v[168:171], 0
	v_mfma_f32_16x16x32_bf16 v[48:51], v[152:155], v[176:179], 0
	v_mfma_f32_16x16x32_bf16 v[40:43], v[160:163], v[176:179], 0
	v_mfma_f32_16x16x32_bf16 v[32:35], v[152:155], v[184:187], 0
	v_mfma_f32_16x16x32_bf16 v[24:27], v[160:163], v[184:187], 0
	v_mfma_f32_16x16x32_bf16 v[16:19], v[152:155], v[192:195], 0
	v_mfma_f32_16x16x32_bf16 v[8:11], v[160:163], v[192:195], 0
	v_mfma_f32_16x16x32_bf16 v[60:63], v[156:159], v[172:175], v[60:63]
	v_mfma_f32_16x16x32_bf16 v[56:59], v[164:167], v[172:175], v[56:59]
	v_mfma_f32_16x16x32_bf16 v[48:51], v[156:159], v[180:183], v[48:51]
	v_mfma_f32_16x16x32_bf16 v[40:43], v[164:167], v[180:183], v[40:43]
	v_mfma_f32_16x16x32_bf16 v[32:35], v[156:159], v[188:191], v[32:35]
	v_mfma_f32_16x16x32_bf16 v[24:27], v[164:167], v[188:191], v[24:27]
	v_mfma_f32_16x16x32_bf16 v[16:19], v[156:159], v[196:199], v[16:19]
	v_mfma_f32_16x16x32_bf16 v[8:11], v[164:167], v[196:199], v[8:11]
	s_setprio 0
	s_barrier
; #define PG8_STAGE(bufoff, gbase, voff) do { _Pragma("unroll") for (int _i = 0; _i < 2; ++_i) \
;         __builtin_amdgcn_global_load_lds((const unsigned*)((const char*)(gbase) + (voff)[_i]), (LAS unsigned*)(lds + (bufoff) + ldsw + _i * 8192), 16, 0, 0); } while (0)
; #define PG8_LDA(dst, b, h) do { _Pragma("unroll") for (int m = 0; m < 4; ++m) _Pragma("unroll") for (int k = 0; k < 2; ++k) dst[m][k] = *(const LAS bf16x8*)(lds + PG8_SA(b, h) + aoff + m * 2048 + k * 1024); } while (0)
; #define PG8_LDB(dst, b, h) do { _Pragma("unroll") for (int n = 0; n < 2; ++n) _Pragma("unroll") for (int k = 0; k < 2; ++k) dst[n][k] = *(const LAS bf16x8*)(lds + PG8_SB(b, h) + boff + n * 2048 + k * 1024); } while (0)
; #define PG8_MMA(ai, bj, At, Bt) do { __builtin_amdgcn_s_setprio(1); _Pragma("unroll") for (int m = 0; m < 4; ++m) _Pragma("unroll") for (int n = 0; n < 2; ++n) _Pragma("unroll") for (int k = 0; k < 2; ++k) \
;         acc[ai][bj][m][n] = __builtin_amdgcn_mfma_f32_16x16x32_bf16(Bt[n][k], At[m][k], acc[ai][bj][m][n], 0, 0, 0); __builtin_amdgcn_s_setprio(0); } while (0)
; #define PG8_WAIT_V(n) asm volatile("s_waitcnt vmcnt(" #n ")" ::: "memory")
; #define PG8_WAIT_L(n) asm volatile("s_waitcnt lgkmcnt(" #n ")" ::: "memory")
; #define PG8_BAR __builtin_amdgcn_s_barrier()
; #define PG8_SCHED __builtin_amdgcn_sched_barrier(0)
; template <class Epi, class Sched>
; __device__ __forceinline__ void gemm_phase(LAS unsigned char* lds, const Gemm g, const Sched& S, const Epi& E) {
;     ...
;             PG8_WAIT_V(6); PG8_BAR; PG8_MMA(1, 1, At, B1); PG8_BAR;
;             PG8_LDB(B0, 1, 0); PG8_SCHED; PG8_LDA(At, 1, 0); PG8_STAGE(PG8_SA(0, 1), a2 + hstep, voffA);
;             PG8_WAIT_L(8); PG8_BAR; PG8_WAIT_L(0); PG8_MMA(0, 0, At, B0); PG8_BAR; PG8_SCHED;
;             PG8_LDB(B1, 1, 1); PG8_STAGE(PG8_SB(1, 0), b3, voffB);
;             PG8_BAR; PG8_WAIT_L(0); PG8_MMA(0, 1, At, B1); PG8_BAR;
;             PG8_LDA(At, 1, 1); PG8_STAGE(PG8_SA(1, 0), a3, voffA);
;             PG8_BAR; PG8_WAIT_L(0); PG8_MMA(1, 0, At, B0); PG8_BAR; PG8_SCHED;
	s_add_u32 s52, s20, 0x40000
	s_addc_u32 s53, s21, 0
	s_add_i32 s54, s44, s28
	s_mov_b32 m0, s54
	s_nop 0
	global_load_lds_dwordx4 v130, s[52:53]
	s_add_i32 m0, s54, 0x2000
	s_nop 0
	global_load_lds_dwordx4 v134, s[52:53]
	s_waitcnt vmcnt(10)
	s_barrier
	s_setprio 1
	v_mfma_f32_16x16x32_bf16 v[52:55], v[202:205], v[168:171], 0
	v_mfma_f32_16x16x32_bf16 v[44:47], v[210:213], v[168:171], 0
	v_mfma_f32_16x16x32_bf16 v[36:39], v[202:205], v[176:179], 0
	v_mfma_f32_16x16x32_bf16 v[28:31], v[210:213], v[176:179], 0
	v_mfma_f32_16x16x32_bf16 v[20:23], v[202:205], v[184:187], 0
	v_mfma_f32_16x16x32_bf16 v[12:15], v[210:213], v[184:187], 0
	v_mfma_f32_16x16x32_bf16 v[4:7], v[202:205], v[192:195], 0
	v_mfma_f32_16x16x32_bf16 v[0:3], v[210:213], v[192:195], 0
	v_mfma_f32_16x16x32_bf16 v[52:55], v[206:209], v[172:175], v[52:55]
	v_mfma_f32_16x16x32_bf16 v[44:47], v[214:217], v[172:175], v[44:47]
	v_mfma_f32_16x16x32_bf16 v[36:39], v[206:209], v[180:183], v[36:39]
	v_mfma_f32_16x16x32_bf16 v[28:31], v[214:217], v[180:183], v[28:31]
	v_mfma_f32_16x16x32_bf16 v[20:23], v[206:209], v[188:191], v[20:23]
	v_mfma_f32_16x16x32_bf16 v[12:15], v[214:217], v[188:191], v[12:15]
	v_mfma_f32_16x16x32_bf16 v[4:7], v[206:209], v[196:199], v[4:7]
	v_mfma_f32_16x16x32_bf16 v[0:3], v[214:217], v[196:199], v[0:3]
	s_setprio 0
	s_add_i32 s52, 0, 0x18000
	v_add_u32_e32 v136, s52, v148
	s_barrier
	ds_read_b128 v[152:155], v136
	ds_read_b128 v[156:159], v136 offset:1024
	ds_read_b128 v[160:163], v136 offset:2048
	ds_read_b128 v[164:167], v136 offset:3072
	s_add_u32 s22, s22, 0x40000
	s_addc_u32 s23, s23, 0
	s_mov_b32 m0, s30
	ds_read_b128 v[168:171], v150 offset:32768
	ds_read_b128 v[172:175], v150 offset:33792
	ds_read_b128 v[176:179], v150 offset:34816
	ds_read_b128 v[180:183], v150 offset:35840
	ds_read_b128 v[184:187], v150 offset:36864
	ds_read_b128 v[188:191], v150 offset:37888
	ds_read_b128 v[192:195], v150 offset:38912
	ds_read_b128 v[196:199], v150 offset:39936
	global_load_lds_dwordx4 v128, s[22:23]
	s_mov_b32 m0, s31
	s_nop 0
	global_load_lds_dwordx4 v132, s[22:23]
	s_waitcnt lgkmcnt(8)
	s_waitcnt vmcnt(10)
	s_barrier
	s_waitcnt lgkmcnt(0)
	s_setprio 1
	s_waitcnt lgkmcnt(0)
	v_mfma_f32_16x16x32_bf16 v[124:127], v[152:155], v[168:171], v[124:127]
	v_mfma_f32_16x16x32_bf16 v[120:123], v[160:163], v[168:171], v[120:123]
	v_mfma_f32_16x16x32_bf16 v[112:115], v[152:155], v[176:179], v[112:115]
	v_mfma_f32_16x16x32_bf16 v[104:107], v[160:163], v[176:179], v[104:107]
	v_mfma_f32_16x16x32_bf16 v[96:99], v[152:155], v[184:187], v[96:99]
	v_mfma_f32_16x16x32_bf16 v[88:91], v[160:163], v[184:187], v[88:91]
	v_mfma_f32_16x16x32_bf16 v[80:83], v[152:155], v[192:195], v[80:83]
	v_mfma_f32_16x16x32_bf16 v[72:75], v[160:163], v[192:195], v[72:75]
	v_mfma_f32_16x16x32_bf16 v[124:127], v[156:159], v[172:175], v[124:127]
	v_mfma_f32_16x16x32_bf16 v[120:123], v[164:167], v[172:175], v[120:123]
	v_mfma_f32_16x16x32_bf16 v[112:115], v[156:159], v[180:183], v[112:115]
	v_mfma_f32_16x16x32_bf16 v[104:107], v[164:167], v[180:183], v[104:107]
	v_mfma_f32_16x16x32_bf16 v[96:99], v[156:159], v[188:191], v[96:99]
	v_mfma_f32_16x16x32_bf16 v[88:91], v[164:167], v[188:191], v[88:91]
	v_mfma_f32_16x16x32_bf16 v[80:83], v[156:159], v[196:199], v[80:83]
	v_mfma_f32_16x16x32_bf16 v[72:75], v[164:167], v[196:199], v[72:75]
	s_setprio 0
	s_barrier
	s_add_i32 s22, 0, 0x1c000
	s_add_i32 s23, s52, s28
	v_add_u32_e32 v136, s22, v148
	s_add_u32 s0, s20, 0x80
	s_addc_u32 s1, s21, 0
	s_mov_b32 m0, s23
	ds_read_b128 v[202:205], v136
	ds_read_b128 v[206:209], v136 offset:1024
	ds_read_b128 v[210:213], v136 offset:2048
	ds_read_b128 v[214:217], v136 offset:3072
	global_load_lds_dwordx4 v130, s[0:1]
	s_add_i32 m0, s23, 0x2000
	s_nop 0
	global_load_lds_dwordx4 v134, s[0:1]
	s_waitcnt vmcnt(10)
	s_barrier
	s_waitcnt lgkmcnt(0)
	s_setprio 1
	s_waitcnt lgkmcnt(0)
	v_mfma_f32_16x16x32_bf16 v[116:119], v[202:205], v[168:171], v[116:119]
	v_mfma_f32_16x16x32_bf16 v[108:111], v[210:213], v[168:171], v[108:111]
	v_mfma_f32_16x16x32_bf16 v[100:103], v[202:205], v[176:179], v[100:103]
	v_mfma_f32_16x16x32_bf16 v[92:95], v[210:213], v[176:179], v[92:95]
	v_mfma_f32_16x16x32_bf16 v[84:87], v[202:205], v[184:187], v[84:87]
	v_mfma_f32_16x16x32_bf16 v[76:79], v[210:213], v[184:187], v[76:79]
	v_mfma_f32_16x16x32_bf16 v[68:71], v[202:205], v[192:195], v[68:71]
	v_mfma_f32_16x16x32_bf16 v[64:67], v[210:213], v[192:195], v[64:67]
	v_mfma_f32_16x16x32_bf16 v[116:119], v[206:209], v[172:175], v[116:119]
	v_mfma_f32_16x16x32_bf16 v[108:111], v[214:217], v[172:175], v[108:111]
	v_mfma_f32_16x16x32_bf16 v[100:103], v[206:209], v[180:183], v[100:103]
	v_mfma_f32_16x16x32_bf16 v[92:95], v[214:217], v[180:183], v[92:95]
	v_mfma_f32_16x16x32_bf16 v[84:87], v[206:209], v[188:191], v[84:87]
	v_mfma_f32_16x16x32_bf16 v[76:79], v[214:217], v[188:191], v[76:79]
	v_mfma_f32_16x16x32_bf16 v[68:71], v[206:209], v[196:199], v[68:71]
	v_mfma_f32_16x16x32_bf16 v[64:67], v[214:217], v[196:199], v[64:67]
	s_setprio 0
	s_mov_b32 m0, s36
	s_mov_b64 s[0:1], 0x80
	v_lshl_add_u64 v[218:219], v[222:223], 0, s[0:1]
	s_barrier
	ds_read_b128 v[168:171], v150 offset:49152
	ds_read_b128 v[172:175], v150 offset:50176
	ds_read_b128 v[176:179], v150 offset:51200
	ds_read_b128 v[180:183], v150 offset:52224
	ds_read_b128 v[184:187], v150 offset:53248
	ds_read_b128 v[188:191], v150 offset:54272
	ds_read_b128 v[192:195], v150 offset:55296
	ds_read_b128 v[196:199], v150 offset:56320
	global_load_lds_dwordx4 v[218:219], off
	v_lshl_add_u64 v[218:219], v[224:225], 0, s[0:1]
	s_mov_b32 m0, s37
	s_nop 0
	global_load_lds_dwordx4 v[218:219], off
	s_barrier
; #define PG8_STAGE(bufoff, gbase, voff) do { _Pragma("unroll") for (int _i = 0; _i < 2; ++_i) \
;         __builtin_amdgcn_global_load_lds((const unsigned*)((const char*)(gbase) + (voff)[_i]), (LAS unsigned*)(lds + (bufoff) + ldsw + _i * 8192), 16, 0, 0); } while (0)
; #define PG8_LDA(dst, b, h) do { _Pragma("unroll") for (int m = 0; m < 4; ++m) _Pragma("unroll") for (int k = 0; k < 2; ++k) dst[m][k] = *(const LAS bf16x8*)(lds + PG8_SA(b, h) + aoff + m * 2048 + k * 1024); } while (0)
; #define PG8_LDB(dst, b, h) do { _Pragma("unroll") for (int n = 0; n < 2; ++n) _Pragma("unroll") for (int k = 0; k < 2; ++k) dst[n][k] = *(const LAS bf16x8*)(lds + PG8_SB(b, h) + boff + n * 2048 + k * 1024); } while (0)
; #define PG8_WAIT_V(n) asm volatile("s_waitcnt vmcnt(" #n ")" ::: "memory")
; #define PG8_WAIT_L(n) asm volatile("s_waitcnt lgkmcnt(" #n ")" ::: "memory")
; #define PG8_BAR __builtin_amdgcn_s_barrier()
; #define PG8_SCHED __builtin_amdgcn_sched_barrier(0)
; template <class Epi, class Sched>
; __device__ __forceinline__ void gemm_phase(LAS unsigned char* lds, const Gemm g, const Sched& S, const Epi& E) {
;     ...
;             PG8_LDB(B0, 0, 0); PG8_SCHED; PG8_LDA(At, 0, 0); PG8_STAGE(PG8_SA(1, 1), a1 + hstep, voffA);
;             PG8_WAIT_L(8); PG8_BAR; PG8_WAIT_L(0); PG8_MMA(0, 0, At, B0); PG8_BAR; PG8_SCHED;
;             PG8_LDB(B1, 0, 1); PG8_STAGE(PG8_SB(0, 0), b2, voffB);
;             PG8_BAR; PG8_WAIT_L(0); PG8_MMA(0, 1, At, B1); PG8_BAR;
;             PG8_LDA(At, 0, 1); PG8_STAGE(PG8_SA(0, 0), a2, voffA);
;             PG8_BAR; PG8_WAIT_L(0); PG8_MMA(1, 0, At, B0); PG8_BAR; PG8_SCHED;
;             PG8_STAGE(PG8_SB(0, 1), b2 + hstep, voffB);
;             PG8_WAIT_V(6); PG8_BAR; PG8_MMA(1, 1, At, B1); PG8_BAR;
;             PG8_LDB(B0, 1, 0); PG8_SCHED; PG8_LDA(At, 1, 0); PG8_STAGE(PG8_SA(0, 1), a2 + hstep, voffA);
;             PG8_WAIT_L(8); PG8_BAR; PG8_WAIT_L(0); PG8_MMA(0, 0, At, B0); PG8_BAR; PG8_SCHED;
;             PG8_LDB(B1, 1, 1); PG8_STAGE(PG8_SB(1, 0), b3, voffB);
;             PG8_BAR; PG8_WAIT_L(0); PG8_MMA(0, 1, At, B1); PG8_BAR;
;             PG8_LDA(At, 1, 1); PG8_STAGE(PG8_SA(1, 0), a3, voffA);
;             PG8_BAR; PG8_WAIT_L(0); PG8_MMA(1, 0, At, B0); PG8_BAR; PG8_SCHED;
;             PG8_STAGE(PG8_SB(1, 1), b3 + hstep, voffB);
;             PG8_WAIT_V(6); PG8_BAR; PG8_MMA(1, 1, At, B1); PG8_BAR;
	s_waitcnt lgkmcnt(0)
	s_setprio 1
	s_waitcnt lgkmcnt(0)
	v_mfma_f32_16x16x32_bf16 v[60:63], v[152:155], v[168:171], v[60:63]
	v_mfma_f32_16x16x32_bf16 v[56:59], v[160:163], v[168:171], v[56:59]
	v_mfma_f32_16x16x32_bf16 v[48:51], v[152:155], v[176:179], v[48:51]
	v_mfma_f32_16x16x32_bf16 v[40:43], v[160:163], v[176:179], v[40:43]
	v_mfma_f32_16x16x32_bf16 v[32:35], v[152:155], v[184:187], v[32:35]
	v_mfma_f32_16x16x32_bf16 v[24:27], v[160:163], v[184:187], v[24:27]
	v_mfma_f32_16x16x32_bf16 v[16:19], v[152:155], v[192:195], v[16:19]
	v_mfma_f32_16x16x32_bf16 v[8:11], v[160:163], v[192:195], v[8:11]
	v_mfma_f32_16x16x32_bf16 v[60:63], v[156:159], v[172:175], v[60:63]
	v_mfma_f32_16x16x32_bf16 v[56:59], v[164:167], v[172:175], v[56:59]
	v_mfma_f32_16x16x32_bf16 v[48:51], v[156:159], v[180:183], v[48:51]
	v_mfma_f32_16x16x32_bf16 v[40:43], v[164:167], v[180:183], v[40:43]
	v_mfma_f32_16x16x32_bf16 v[32:35], v[156:159], v[188:191], v[32:35]
	v_mfma_f32_16x16x32_bf16 v[24:27], v[164:167], v[188:191], v[24:27]
	v_mfma_f32_16x16x32_bf16 v[16:19], v[156:159], v[196:199], v[16:19]
	v_mfma_f32_16x16x32_bf16 v[8:11], v[164:167], v[196:199], v[8:11]
	s_setprio 0
	s_barrier
	s_add_u32 s20, s20, 0x40080
	s_addc_u32 s21, s21, 0
	s_add_i32 s22, s22, s28
	s_mov_b32 m0, s22
	s_nop 0
	global_load_lds_dwordx4 v130, s[20:21]
	s_add_i32 m0, s22, 0x2000
	s_nop 0
	global_load_lds_dwordx4 v134, s[20:21]
	s_waitcnt vmcnt(10)
	s_barrier
	s_setprio 1
	v_mfma_f32_16x16x32_bf16 v[52:55], v[202:205], v[168:171], v[52:55]
	v_mfma_f32_16x16x32_bf16 v[44:47], v[210:213], v[168:171], v[44:47]
	v_mfma_f32_16x16x32_bf16 v[36:39], v[202:205], v[176:179], v[36:39]
	v_mfma_f32_16x16x32_bf16 v[28:31], v[210:213], v[176:179], v[28:31]
	v_mfma_f32_16x16x32_bf16 v[20:23], v[202:205], v[184:187], v[20:23]
	v_mfma_f32_16x16x32_bf16 v[12:15], v[210:213], v[184:187], v[12:15]
	v_mfma_f32_16x16x32_bf16 v[4:7], v[202:205], v[192:195], v[4:7]
	v_mfma_f32_16x16x32_bf16 v[0:3], v[210:213], v[192:195], v[0:3]
	v_mfma_f32_16x16x32_bf16 v[52:55], v[206:209], v[172:175], v[52:55]
	v_mfma_f32_16x16x32_bf16 v[44:47], v[214:217], v[172:175], v[44:47]
	v_mfma_f32_16x16x32_bf16 v[36:39], v[206:209], v[180:183], v[36:39]
	v_mfma_f32_16x16x32_bf16 v[28:31], v[214:217], v[180:183], v[28:31]
	v_mfma_f32_16x16x32_bf16 v[20:23], v[206:209], v[188:191], v[20:23]
	v_mfma_f32_16x16x32_bf16 v[12:15], v[214:217], v[188:191], v[12:15]
	v_mfma_f32_16x16x32_bf16 v[4:7], v[206:209], v[196:199], v[4:7]
	v_mfma_f32_16x16x32_bf16 v[0:3], v[214:217], v[196:199], v[0:3]
	s_setprio 0
	s_add_i32 s51, s51, 2
	s_add_u32 s18, s18, 0x100
	s_addc_u32 s19, s19, 0
	s_add_u32 s48, s48, 0x100
	s_addc_u32 s49, s49, 0
	s_cmp_gt_u32 s51, 13
	s_barrier
.LBB0_673:
	ds_read_b128 v[152:155], v149
	ds_read_b128 v[156:159], v149 offset:1024
	ds_read_b128 v[160:163], v149 offset:2048
	ds_read_b128 v[164:167], v149 offset:3072
	s_add_u32 s20, s18, 0xfffc0080
	s_addc_u32 s21, s19, -1
	s_cmp_eq_u32 s51, 12
	s_cselect_b32 s23, s9, s21
	s_cselect_b32 s22, s46, s20
	s_cselect_b32 s21, s7, s49
	s_cselect_b32 s20, s47, s48
	s_add_i32 m0, s17, 0xc000
	ds_read_b128 v[168:171], v150
	ds_read_b128 v[172:175], v150 offset:1024
	ds_read_b128 v[176:179], v150 offset:2048
	ds_read_b128 v[180:183], v150 offset:3072
	ds_read_b128 v[184:187], v150 offset:4096
	ds_read_b128 v[188:191], v150 offset:5120
	ds_read_b128 v[192:195], v150 offset:6144
	ds_read_b128 v[196:199], v150 offset:7168
	global_load_lds_dwordx4 v138, s[18:19]
	s_add_i32 m0, s17, 0xe000
	s_nop 0
	global_load_lds_dwordx4 v140, s[18:19]
	s_waitcnt lgkmcnt(8)
	s_waitcnt vmcnt(10)
	s_barrier
	s_waitcnt lgkmcnt(0)
	s_setprio 1
	s_waitcnt lgkmcnt(0)
	v_mfma_f32_16x16x32_bf16 v[124:127], v[152:155], v[168:171], v[124:127]
	v_mfma_f32_16x16x32_bf16 v[120:123], v[160:163], v[168:171], v[120:123]
	v_mfma_f32_16x16x32_bf16 v[112:115], v[152:155], v[176:179], v[112:115]
	v_mfma_f32_16x16x32_bf16 v[104:107], v[160:163], v[176:179], v[104:107]
	v_mfma_f32_16x16x32_bf16 v[96:99], v[152:155], v[184:187], v[96:99]
	v_mfma_f32_16x16x32_bf16 v[88:91], v[160:163], v[184:187], v[88:91]
	v_mfma_f32_16x16x32_bf16 v[80:83], v[152:155], v[192:195], v[80:83]
	v_mfma_f32_16x16x32_bf16 v[72:75], v[160:163], v[192:195], v[72:75]
	v_mfma_f32_16x16x32_bf16 v[124:127], v[156:159], v[172:175], v[124:127]
	v_mfma_f32_16x16x32_bf16 v[120:123], v[164:167], v[172:175], v[120:123]
	v_mfma_f32_16x16x32_bf16 v[112:115], v[156:159], v[180:183], v[112:115]
	v_mfma_f32_16x16x32_bf16 v[104:107], v[164:167], v[180:183], v[104:107]
	v_mfma_f32_16x16x32_bf16 v[96:99], v[156:159], v[188:191], v[96:99]
	v_mfma_f32_16x16x32_bf16 v[88:91], v[164:167], v[188:191], v[88:91]
	v_mfma_f32_16x16x32_bf16 v[80:83], v[156:159], v[196:199], v[80:83]
	v_mfma_f32_16x16x32_bf16 v[72:75], v[164:167], v[196:199], v[72:75]
	s_setprio 0
	s_barrier
	s_add_i32 s52, s43, s28
	s_mov_b32 m0, s52
	ds_read_b128 v[202:205], v151
	ds_read_b128 v[206:209], v151 offset:1024
	ds_read_b128 v[210:213], v151 offset:2048
	ds_read_b128 v[214:217], v151 offset:3072
	global_load_lds_dwordx4 v130, s[20:21]
	s_add_i32 m0, s52, 0x2000
	s_nop 0
	global_load_lds_dwordx4 v134, s[20:21]
	s_waitcnt vmcnt(10)
	s_barrier
; #define PG8_STAGE(bufoff, gbase, voff) do { _Pragma("unroll") for (int _i = 0; _i < 2; ++_i) \
;         __builtin_amdgcn_global_load_lds((const unsigned*)((const char*)(gbase) + (voff)[_i]), (LAS unsigned*)(lds + (bufoff) + ldsw + _i * 8192), 16, 0, 0); } while (0)
; #define PG8_LDA(dst, b, h) do { _Pragma("unroll") for (int m = 0; m < 4; ++m) _Pragma("unroll") for (int k = 0; k < 2; ++k) dst[m][k] = *(const LAS bf16x8*)(lds + PG8_SA(b, h) + aoff + m * 2048 + k * 1024); } while (0)
; #define PG8_LDB(dst, b, h) do { _Pragma("unroll") for (int n = 0; n < 2; ++n) _Pragma("unroll") for (int k = 0; k < 2; ++k) dst[n][k] = *(const LAS bf16x8*)(lds + PG8_SB(b, h) + boff + n * 2048 + k * 1024); } while (0)
; #define PG8_WAIT_V(n) asm volatile("s_waitcnt vmcnt(" #n ")" ::: "memory")
; #define PG8_WAIT_L(n) asm volatile("s_waitcnt lgkmcnt(" #n ")" ::: "memory")
; #define PG8_BAR __builtin_amdgcn_s_barrier()
; #define PG8_SCHED __builtin_amdgcn_sched_barrier(0)
; template <class Epi, class Sched>
; __device__ __forceinline__ void gemm_phase(LAS unsigned char* lds, const Gemm g, const Sched& S, const Epi& E) {
;     ...
;             PG8_LDB(B0, 0, 0); PG8_SCHED; PG8_LDA(At, 0, 0); PG8_STAGE(PG8_SA(1, 1), a1 + hstep, voffA);
;             PG8_WAIT_L(8); PG8_BAR; PG8_WAIT_L(0); PG8_MMA(0, 0, At, B0); PG8_BAR; PG8_SCHED;
;             PG8_LDB(B1, 0, 1); PG8_STAGE(PG8_SB(0, 0), b2, voffB);
;             PG8_BAR; PG8_WAIT_L(0); PG8_MMA(0, 1, At, B1); PG8_BAR;
;             PG8_LDA(At, 0, 1); PG8_STAGE(PG8_SA(0, 0), a2, voffA);
;             PG8_BAR; PG8_WAIT_L(0); PG8_MMA(1, 0, At, B0); PG8_BAR; PG8_SCHED;
;             PG8_STAGE(PG8_SB(0, 1), b2 + hstep, voffB);
;             PG8_WAIT_V(6); PG8_BAR; PG8_MMA(1, 1, At, B1); PG8_BAR;
;             PG8_LDB(B0, 1, 0); PG8_SCHED; PG8_LDA(At, 1, 0); PG8_STAGE(PG8_SA(0, 1), a2 + hstep, voffA);
;             PG8_WAIT_L(8); PG8_BAR; PG8_WAIT_L(0); PG8_MMA(0, 0, At, B0); PG8_BAR; PG8_SCHED;
;             PG8_LDB(B1, 1, 1); PG8_STAGE(PG8_SB(1, 0), b3, voffB);
;             PG8_BAR; PG8_WAIT_L(0); PG8_MMA(0, 1, At, B1); PG8_BAR;
;             PG8_LDA(At, 1, 1); PG8_STAGE(PG8_SA(1, 0), a3, voffA);
;             PG8_BAR; PG8_WAIT_L(0); PG8_MMA(1, 0, At, B0); PG8_BAR; PG8_SCHED;
;             PG8_STAGE(PG8_SB(1, 1), b3 + hstep, voffB);
;             PG8_WAIT_V(6); PG8_BAR; PG8_MMA(1, 1, At, B1); PG8_BAR;
	s_waitcnt lgkmcnt(0)
	s_setprio 1
	s_waitcnt lgkmcnt(0)
	v_mfma_f32_16x16x32_bf16 v[116:119], v[202:205], v[168:171], v[116:119]
	v_mfma_f32_16x16x32_bf16 v[108:111], v[210:213], v[168:171], v[108:111]
	v_mfma_f32_16x16x32_bf16 v[100:103], v[202:205], v[176:179], v[100:103]
	v_mfma_f32_16x16x32_bf16 v[92:95], v[210:213], v[176:179], v[92:95]
	v_mfma_f32_16x16x32_bf16 v[84:87], v[202:205], v[184:187], v[84:87]
	v_mfma_f32_16x16x32_bf16 v[76:79], v[210:213], v[184:187], v[76:79]
	v_mfma_f32_16x16x32_bf16 v[68:71], v[202:205], v[192:195], v[68:71]
	v_mfma_f32_16x16x32_bf16 v[64:67], v[210:213], v[192:195], v[64:67]
	v_mfma_f32_16x16x32_bf16 v[116:119], v[206:209], v[172:175], v[116:119]
	v_mfma_f32_16x16x32_bf16 v[108:111], v[214:217], v[172:175], v[108:111]
	v_mfma_f32_16x16x32_bf16 v[100:103], v[206:209], v[180:183], v[100:103]
	v_mfma_f32_16x16x32_bf16 v[92:95], v[214:217], v[180:183], v[92:95]
	v_mfma_f32_16x16x32_bf16 v[84:87], v[206:209], v[188:191], v[84:87]
	v_mfma_f32_16x16x32_bf16 v[76:79], v[214:217], v[188:191], v[76:79]
	v_mfma_f32_16x16x32_bf16 v[68:71], v[206:209], v[196:199], v[68:71]
	v_mfma_f32_16x16x32_bf16 v[64:67], v[214:217], v[196:199], v[64:67]
	s_setprio 0
	s_mov_b32 m0, s17
	v_lshl_add_u64 v[222:223], s[22:23], 0, v[128:129]
	s_barrier
	ds_read_b128 v[168:171], v150 offset:16384
	ds_read_b128 v[172:175], v150 offset:17408
	ds_read_b128 v[176:179], v150 offset:18432
	ds_read_b128 v[180:183], v150 offset:19456
	ds_read_b128 v[184:187], v150 offset:20480
	ds_read_b128 v[188:191], v150 offset:21504
	ds_read_b128 v[192:195], v150 offset:22528
	ds_read_b128 v[196:199], v150 offset:23552
	global_load_lds_dwordx4 v128, s[22:23]
	v_lshl_add_u64 v[224:225], s[22:23], 0, v[132:133]
	s_mov_b32 m0, s29
	s_nop 0
	global_load_lds_dwordx4 v132, s[22:23]
	s_barrier
	s_waitcnt lgkmcnt(0)
	s_setprio 1
	s_waitcnt lgkmcnt(0)
	v_mfma_f32_16x16x32_bf16 v[60:63], v[152:155], v[168:171], v[60:63]
	v_mfma_f32_16x16x32_bf16 v[56:59], v[160:163], v[168:171], v[56:59]
	v_mfma_f32_16x16x32_bf16 v[48:51], v[152:155], v[176:179], v[48:51]
	v_mfma_f32_16x16x32_bf16 v[40:43], v[160:163], v[176:179], v[40:43]
	v_mfma_f32_16x16x32_bf16 v[32:35], v[152:155], v[184:187], v[32:35]
	v_mfma_f32_16x16x32_bf16 v[24:27], v[160:163], v[184:187], v[24:27]
	v_mfma_f32_16x16x32_bf16 v[16:19], v[152:155], v[192:195], v[16:19]
	v_mfma_f32_16x16x32_bf16 v[8:11], v[160:163], v[192:195], v[8:11]
	v_mfma_f32_16x16x32_bf16 v[60:63], v[156:159], v[172:175], v[60:63]
	v_mfma_f32_16x16x32_bf16 v[56:59], v[164:167], v[172:175], v[56:59]
	v_mfma_f32_16x16x32_bf16 v[48:51], v[156:159], v[180:183], v[48:51]
	v_mfma_f32_16x16x32_bf16 v[40:43], v[164:167], v[180:183], v[40:43]
	v_mfma_f32_16x16x32_bf16 v[32:35], v[156:159], v[188:191], v[32:35]
	v_mfma_f32_16x16x32_bf16 v[24:27], v[164:167], v[188:191], v[24:27]
	v_mfma_f32_16x16x32_bf16 v[16:19], v[156:159], v[196:199], v[16:19]
	v_mfma_f32_16x16x32_bf16 v[8:11], v[164:167], v[196:199], v[8:11]
	s_setprio 0
	s_barrier
	s_add_u32 s52, s20, 0x40000
	s_addc_u32 s53, s21, 0
	s_add_i32 s54, s44, s28
	s_mov_b32 m0, s54
	s_nop 0
	global_load_lds_dwordx4 v130, s[52:53]
	s_add_i32 m0, s54, 0x2000
	s_nop 0
	global_load_lds_dwordx4 v134, s[52:53]
	s_waitcnt vmcnt(10)
	s_barrier
	s_setprio 1
	v_mfma_f32_16x16x32_bf16 v[52:55], v[202:205], v[168:171], v[52:55]
	v_mfma_f32_16x16x32_bf16 v[44:47], v[210:213], v[168:171], v[44:47]
	v_mfma_f32_16x16x32_bf16 v[36:39], v[202:205], v[176:179], v[36:39]
	v_mfma_f32_16x16x32_bf16 v[28:31], v[210:213], v[176:179], v[28:31]
	v_mfma_f32_16x16x32_bf16 v[20:23], v[202:205], v[184:187], v[20:23]
	v_mfma_f32_16x16x32_bf16 v[12:15], v[210:213], v[184:187], v[12:15]
	v_mfma_f32_16x16x32_bf16 v[4:7], v[202:205], v[192:195], v[4:7]
	v_mfma_f32_16x16x32_bf16 v[0:3], v[210:213], v[192:195], v[0:3]
	v_mfma_f32_16x16x32_bf16 v[52:55], v[206:209], v[172:175], v[52:55]
	v_mfma_f32_16x16x32_bf16 v[44:47], v[214:217], v[172:175], v[44:47]
	v_mfma_f32_16x16x32_bf16 v[36:39], v[206:209], v[180:183], v[36:39]
	v_mfma_f32_16x16x32_bf16 v[28:31], v[214:217], v[180:183], v[28:31]
	v_mfma_f32_16x16x32_bf16 v[20:23], v[206:209], v[188:191], v[20:23]
	v_mfma_f32_16x16x32_bf16 v[12:15], v[214:217], v[188:191], v[12:15]
	v_mfma_f32_16x16x32_bf16 v[4:7], v[206:209], v[196:199], v[4:7]
	v_mfma_f32_16x16x32_bf16 v[0:3], v[214:217], v[196:199], v[0:3]
	s_setprio 0
	s_add_i32 s52, 0, 0x18000
	v_add_u32_e32 v136, s52, v148
	s_barrier
	ds_read_b128 v[152:155], v136
	ds_read_b128 v[156:159], v136 offset:1024
	ds_read_b128 v[160:163], v136 offset:2048
	ds_read_b128 v[164:167], v136 offset:3072
	s_add_u32 s22, s22, 0x40000
	s_addc_u32 s23, s23, 0
	s_mov_b32 m0, s30
	ds_read_b128 v[168:171], v150 offset:32768
	ds_read_b128 v[172:175], v150 offset:33792
	ds_read_b128 v[176:179], v150 offset:34816
	ds_read_b128 v[180:183], v150 offset:35840
	ds_read_b128 v[184:187], v150 offset:36864
	ds_read_b128 v[188:191], v150 offset:37888
	ds_read_b128 v[192:195], v150 offset:38912
	ds_read_b128 v[196:199], v150 offset:39936
	global_load_lds_dwordx4 v128, s[22:23]
	s_mov_b32 m0, s31
	s_nop 0
	global_load_lds_dwordx4 v132, s[22:23]
	s_waitcnt lgkmcnt(8)
	s_waitcnt vmcnt(10)
	s_barrier
; #define PG8_STAGE(bufoff, gbase, voff) do { _Pragma("unroll") for (int _i = 0; _i < 2; ++_i) \
;         __builtin_amdgcn_global_load_lds((const unsigned*)((const char*)(gbase) + (voff)[_i]), (LAS unsigned*)(lds + (bufoff) + ldsw + _i * 8192), 16, 0, 0); } while (0)
; #define PG8_LDA(dst, b, h) do { _Pragma("unroll") for (int m = 0; m < 4; ++m) _Pragma("unroll") for (int k = 0; k < 2; ++k) dst[m][k] = *(const LAS bf16x8*)(lds + PG8_SA(b, h) + aoff + m * 2048 + k * 1024); } while (0)
; #define PG8_LDB(dst, b, h) do { _Pragma("unroll") for (int n = 0; n < 2; ++n) _Pragma("unroll") for (int k = 0; k < 2; ++k) dst[n][k] = *(const LAS bf16x8*)(lds + PG8_SB(b, h) + boff + n * 2048 + k * 1024); } while (0)
; #define PG8_WAIT_V(n) asm volatile("s_waitcnt vmcnt(" #n ")" ::: "memory")
; #define PG8_WAIT_L(n) asm volatile("s_waitcnt lgkmcnt(" #n ")" ::: "memory")
; #define PG8_BAR __builtin_amdgcn_s_barrier()
; #define PG8_SCHED __builtin_amdgcn_sched_barrier(0)
; template <class Epi, class Sched>
; __device__ __forceinline__ void gemm_phase(LAS unsigned char* lds, const Gemm g, const Sched& S, const Epi& E) {
;     ...
;             PG8_LDB(B0, 0, 0); PG8_SCHED; PG8_LDA(At, 0, 0); PG8_STAGE(PG8_SA(1, 1), a1 + hstep, voffA);
;             PG8_WAIT_L(8); PG8_BAR; PG8_WAIT_L(0); PG8_MMA(0, 0, At, B0); PG8_BAR; PG8_SCHED;
;             PG8_LDB(B1, 0, 1); PG8_STAGE(PG8_SB(0, 0), b2, voffB);
;             PG8_BAR; PG8_WAIT_L(0); PG8_MMA(0, 1, At, B1); PG8_BAR;
;             PG8_LDA(At, 0, 1); PG8_STAGE(PG8_SA(0, 0), a2, voffA);
;             PG8_BAR; PG8_WAIT_L(0); PG8_MMA(1, 0, At, B0); PG8_BAR; PG8_SCHED;
;             PG8_STAGE(PG8_SB(0, 1), b2 + hstep, voffB);
;             PG8_WAIT_V(6); PG8_BAR; PG8_MMA(1, 1, At, B1); PG8_BAR;
;             PG8_LDB(B0, 1, 0); PG8_SCHED; PG8_LDA(At, 1, 0); PG8_STAGE(PG8_SA(0, 1), a2 + hstep, voffA);
;             PG8_WAIT_L(8); PG8_BAR; PG8_WAIT_L(0); PG8_MMA(0, 0, At, B0); PG8_BAR; PG8_SCHED;
;             PG8_LDB(B1, 1, 1); PG8_STAGE(PG8_SB(1, 0), b3, voffB);
;             PG8_BAR; PG8_WAIT_L(0); PG8_MMA(0, 1, At, B1); PG8_BAR;
;             PG8_LDA(At, 1, 1); PG8_STAGE(PG8_SA(1, 0), a3, voffA);
;             PG8_BAR; PG8_WAIT_L(0); PG8_MMA(1, 0, At, B0); PG8_BAR; PG8_SCHED;
;             PG8_STAGE(PG8_SB(1, 1), b3 + hstep, voffB);
;             PG8_WAIT_V(6); PG8_BAR; PG8_MMA(1, 1, At, B1); PG8_BAR;
	s_waitcnt lgkmcnt(0)
	s_setprio 1
	s_waitcnt lgkmcnt(0)
	v_mfma_f32_16x16x32_bf16 v[124:127], v[152:155], v[168:171], v[124:127]
	v_mfma_f32_16x16x32_bf16 v[120:123], v[160:163], v[168:171], v[120:123]
	v_mfma_f32_16x16x32_bf16 v[112:115], v[152:155], v[176:179], v[112:115]
	v_mfma_f32_16x16x32_bf16 v[104:107], v[160:163], v[176:179], v[104:107]
	v_mfma_f32_16x16x32_bf16 v[96:99], v[152:155], v[184:187], v[96:99]
	v_mfma_f32_16x16x32_bf16 v[88:91], v[160:163], v[184:187], v[88:91]
	v_mfma_f32_16x16x32_bf16 v[80:83], v[152:155], v[192:195], v[80:83]
	v_mfma_f32_16x16x32_bf16 v[72:75], v[160:163], v[192:195], v[72:75]
	v_mfma_f32_16x16x32_bf16 v[124:127], v[156:159], v[172:175], v[124:127]
	v_mfma_f32_16x16x32_bf16 v[120:123], v[164:167], v[172:175], v[120:123]
	v_mfma_f32_16x16x32_bf16 v[112:115], v[156:159], v[180:183], v[112:115]
	v_mfma_f32_16x16x32_bf16 v[104:107], v[164:167], v[180:183], v[104:107]
	v_mfma_f32_16x16x32_bf16 v[96:99], v[156:159], v[188:191], v[96:99]
	v_mfma_f32_16x16x32_bf16 v[88:91], v[164:167], v[188:191], v[88:91]
	v_mfma_f32_16x16x32_bf16 v[80:83], v[156:159], v[196:199], v[80:83]
	v_mfma_f32_16x16x32_bf16 v[72:75], v[164:167], v[196:199], v[72:75]
	s_setprio 0
	s_barrier
	s_add_i32 s22, 0, 0x1c000
	s_add_i32 s23, s52, s28
	v_add_u32_e32 v136, s22, v148
	s_add_u32 s0, s20, 0x80
	s_addc_u32 s1, s21, 0
	s_mov_b32 m0, s23
	ds_read_b128 v[202:205], v136
	ds_read_b128 v[206:209], v136 offset:1024
	ds_read_b128 v[210:213], v136 offset:2048
	ds_read_b128 v[214:217], v136 offset:3072
	global_load_lds_dwordx4 v130, s[0:1]
	s_add_i32 m0, s23, 0x2000
	s_nop 0
	global_load_lds_dwordx4 v134, s[0:1]
	s_waitcnt vmcnt(10)
	s_barrier
	s_waitcnt lgkmcnt(0)
	s_setprio 1
	s_waitcnt lgkmcnt(0)
	v_mfma_f32_16x16x32_bf16 v[116:119], v[202:205], v[168:171], v[116:119]
	v_mfma_f32_16x16x32_bf16 v[108:111], v[210:213], v[168:171], v[108:111]
	v_mfma_f32_16x16x32_bf16 v[100:103], v[202:205], v[176:179], v[100:103]
	v_mfma_f32_16x16x32_bf16 v[92:95], v[210:213], v[176:179], v[92:95]
	v_mfma_f32_16x16x32_bf16 v[84:87], v[202:205], v[184:187], v[84:87]
	v_mfma_f32_16x16x32_bf16 v[76:79], v[210:213], v[184:187], v[76:79]
	v_mfma_f32_16x16x32_bf16 v[68:71], v[202:205], v[192:195], v[68:71]
	v_mfma_f32_16x16x32_bf16 v[64:67], v[210:213], v[192:195], v[64:67]
	v_mfma_f32_16x16x32_bf16 v[116:119], v[206:209], v[172:175], v[116:119]
	v_mfma_f32_16x16x32_bf16 v[108:111], v[214:217], v[172:175], v[108:111]
	v_mfma_f32_16x16x32_bf16 v[100:103], v[206:209], v[180:183], v[100:103]
	v_mfma_f32_16x16x32_bf16 v[92:95], v[214:217], v[180:183], v[92:95]
	v_mfma_f32_16x16x32_bf16 v[84:87], v[206:209], v[188:191], v[84:87]
	v_mfma_f32_16x16x32_bf16 v[76:79], v[214:217], v[188:191], v[76:79]
	v_mfma_f32_16x16x32_bf16 v[68:71], v[206:209], v[196:199], v[68:71]
	v_mfma_f32_16x16x32_bf16 v[64:67], v[214:217], v[196:199], v[64:67]
	s_setprio 0
	s_mov_b32 m0, s36
	s_mov_b64 s[0:1], 0x80
	v_lshl_add_u64 v[218:219], v[222:223], 0, s[0:1]
	s_barrier
	ds_read_b128 v[168:171], v150 offset:49152
	ds_read_b128 v[172:175], v150 offset:50176
	ds_read_b128 v[176:179], v150 offset:51200
	ds_read_b128 v[180:183], v150 offset:52224
	ds_read_b128 v[184:187], v150 offset:53248
	ds_read_b128 v[188:191], v150 offset:54272
	ds_read_b128 v[192:195], v150 offset:55296
	ds_read_b128 v[196:199], v150 offset:56320
	global_load_lds_dwordx4 v[218:219], off
	v_lshl_add_u64 v[218:219], v[224:225], 0, s[0:1]
	s_mov_b32 m0, s37
	s_nop 0
	global_load_lds_dwordx4 v[218:219], off
	s_barrier
	s_waitcnt lgkmcnt(0)
	s_setprio 1
	s_waitcnt lgkmcnt(0)
	v_mfma_f32_16x16x32_bf16 v[60:63], v[152:155], v[168:171], v[60:63]
	v_mfma_f32_16x16x32_bf16 v[56:59], v[160:163], v[168:171], v[56:59]
	v_mfma_f32_16x16x32_bf16 v[48:51], v[152:155], v[176:179], v[48:51]
	v_mfma_f32_16x16x32_bf16 v[40:43], v[160:163], v[176:179], v[40:43]
	v_mfma_f32_16x16x32_bf16 v[32:35], v[152:155], v[184:187], v[32:35]
	v_mfma_f32_16x16x32_bf16 v[24:27], v[160:163], v[184:187], v[24:27]
	v_mfma_f32_16x16x32_bf16 v[16:19], v[152:155], v[192:195], v[16:19]
	v_mfma_f32_16x16x32_bf16 v[8:11], v[160:163], v[192:195], v[8:11]
	v_mfma_f32_16x16x32_bf16 v[60:63], v[156:159], v[172:175], v[60:63]
	v_mfma_f32_16x16x32_bf16 v[56:59], v[164:167], v[172:175], v[56:59]
	v_mfma_f32_16x16x32_bf16 v[48:51], v[156:159], v[180:183], v[48:51]
	v_mfma_f32_16x16x32_bf16 v[40:43], v[164:167], v[180:183], v[40:43]
	v_mfma_f32_16x16x32_bf16 v[32:35], v[156:159], v[188:191], v[32:35]
	v_mfma_f32_16x16x32_bf16 v[24:27], v[164:167], v[188:191], v[24:27]
	v_mfma_f32_16x16x32_bf16 v[16:19], v[156:159], v[196:199], v[16:19]
	v_mfma_f32_16x16x32_bf16 v[8:11], v[164:167], v[196:199], v[8:11]
	s_setprio 0
	s_barrier
	s_add_u32 s20, s20, 0x40080
	s_addc_u32 s21, s21, 0
	s_add_i32 s22, s22, s28
	s_mov_b32 m0, s22
	s_nop 0
	global_load_lds_dwordx4 v130, s[20:21]
	s_add_i32 m0, s22, 0x2000
	s_nop 0
	global_load_lds_dwordx4 v134, s[20:21]
	s_waitcnt vmcnt(10)
	s_barrier
	s_setprio 1
	v_mfma_f32_16x16x32_bf16 v[52:55], v[202:205], v[168:171], v[52:55]
	v_mfma_f32_16x16x32_bf16 v[44:47], v[210:213], v[168:171], v[44:47]
	v_mfma_f32_16x16x32_bf16 v[36:39], v[202:205], v[176:179], v[36:39]
	v_mfma_f32_16x16x32_bf16 v[28:31], v[210:213], v[176:179], v[28:31]
	v_mfma_f32_16x16x32_bf16 v[20:23], v[202:205], v[184:187], v[20:23]
	v_mfma_f32_16x16x32_bf16 v[12:15], v[210:213], v[184:187], v[12:15]
	v_mfma_f32_16x16x32_bf16 v[4:7], v[202:205], v[192:195], v[4:7]
	v_mfma_f32_16x16x32_bf16 v[0:3], v[210:213], v[192:195], v[0:3]
	v_mfma_f32_16x16x32_bf16 v[52:55], v[206:209], v[172:175], v[52:55]
	v_mfma_f32_16x16x32_bf16 v[44:47], v[214:217], v[172:175], v[44:47]
	v_mfma_f32_16x16x32_bf16 v[36:39], v[206:209], v[180:183], v[36:39]
	v_mfma_f32_16x16x32_bf16 v[28:31], v[214:217], v[180:183], v[28:31]
	v_mfma_f32_16x16x32_bf16 v[20:23], v[206:209], v[188:191], v[20:23]
	v_mfma_f32_16x16x32_bf16 v[12:15], v[214:217], v[188:191], v[12:15]
	v_mfma_f32_16x16x32_bf16 v[4:7], v[206:209], v[196:199], v[4:7]
	v_mfma_f32_16x16x32_bf16 v[0:3], v[214:217], v[196:199], v[0:3]
	s_setprio 0
	s_add_i32 s51, s51, 2
	s_add_u32 s18, s18, 0x100
	s_addc_u32 s19, s19, 0
	s_add_u32 s48, s48, 0x100
	s_addc_u32 s49, s49, 0
	s_cmp_gt_u32 s51, 13
	s_barrier
; __device__ __forceinline__ unsigned cvt_pk_bf16(float lo, float hi) { unsigned r; asm volatile("v_cvt_pk_bf16_f32 %0, %1, %2" : "=v"(r) : "v"(lo), "v"(hi)); return r; }
; template <class Epi, class Sched>
; __device__ __forceinline__ void gemm_phase(LAS unsigned char* lds, const Gemm g, const Sched& S, const Epi& E) {
;     ...
;         E(acc, cur, wr, wc, fr, fq);
;         if (!has_next) break;
; #pragma unroll
;         for (int a = 0; a < 2; ++a)
; #pragma unroll
;             for (int b = 0; b < 2; ++b)
; #pragma unroll
;                 for (int m = 0; m < 4; ++m)
; #pragma unroll
;                     for (int n = 0; n < 2; ++n) acc[a][b][m][n] = (f32x4){0.f, 0.f, 0.f, 0.f};
;         cur = nxt; cA = nA; cB = nB; ++ui;
;     __device__ __forceinline__ void operator()(const AccT& acc, const Unit& u, int wr, int wc, int fr, int fq) const {
;     ...
;         for (int ai = 0; ai < 2; ++ai)
; #pragma unroll
;             for (int m = 0; m < 4; ++m) {
;                 const int gm = rbase + ai * 128 + m * 16;
; #pragma unroll
;                 for (int bj = 0; bj < 2; ++bj) {
;                     const int t0 = tb + bj * 128;
;                     const f32x4 v0 = acc[ai][bj][m][0], v1 = acc[ai][bj][m][1];
;                     u32x4 w; w.x = cvt_pk_bf16(v0[0], v0[1]); w.y = cvt_pk_bf16(v0[2], v0[3]); w.z = cvt_pk_bf16(v1[0], v1[1]); w.w = cvt_pk_bf16(v1[2], v1[3]);
;                     *(u32x4*)(YT + ((size_t)((t0 >> 10) * 512 + gm)) * 2048 + part * 1024 + (t0 & 1023)) = w;
;                 }
	s_cbranch_scc0 .LBB0_673
	v_mov_b32_e32 v136, v147
	v_mov_b32_e32 v152, v146
	s_lshl_b32 s7, s16, 8
	s_add_i32 s7, s7, s34
	v_add_u32_e32 v152, s7, v152
	s_lshl_b32 s7, s45, 8
	s_or_b32 s7, s7, s35
	v_lshl_add_u32 v153, v136, 3, s7
	v_cvt_pk_bf16_f32 v124, v124, v125
	v_cvt_pk_bf16_f32 v125, v126, v127
	v_cvt_pk_bf16_f32 v126, v120, v121
	v_ashrrev_i32_e32 v120, 1, v153
	v_cvt_pk_bf16_f32 v127, v122, v123
	v_and_b32_e32 v122, 0xfffffe00, v120
	v_add_u32_e32 v120, v122, v152
	v_ashrrev_i32_e32 v121, 31, v120
	v_lshlrev_b64 v[120:121], 12, v[120:121]
	v_and_b32_e32 v123, 0x3f8, v153
	v_lshl_add_u64 v[120:121], s[4:5], 0, v[120:121]
	v_lshlrev_b32_e32 v136, 1, v123
	v_lshl_add_u64 v[120:121], v[120:121], 0, v[136:137]
	global_store_dwordx4 v[120:121], v[124:127], off
	v_add_u32_e32 v120, 0x80, v153
	v_cvt_pk_bf16_f32 v116, v116, v117
	v_cvt_pk_bf16_f32 v117, v118, v119
	v_cvt_pk_bf16_f32 v118, v108, v109
	v_ashrrev_i32_e32 v108, 1, v120
	v_and_b32_e32 v121, 0xfffffe00, v108
	v_add_u32_e32 v108, v121, v152
	v_ashrrev_i32_e32 v109, 31, v108
	v_lshlrev_b64 v[108:109], 12, v[108:109]
	v_cvt_pk_bf16_f32 v119, v110, v111
	v_lshl_add_u64 v[110:111], s[4:5], 0, v[108:109]
	v_and_b32_e32 v108, 0x3f8, v120
	v_lshlrev_b32_e32 v108, 1, v108
	v_mov_b32_e32 v109, v137
	v_lshl_add_u64 v[110:111], v[110:111], 0, v[108:109]
	global_store_dwordx4 v[110:111], v[116:119], off
	v_cvt_pk_bf16_f32 v110, v112, v113
	v_cvt_pk_bf16_f32 v111, v114, v115
	v_cvt_pk_bf16_f32 v112, v104, v105
	v_cvt_pk_bf16_f32 v113, v106, v107
	s_and_b64 vcc, exec, s[2:3]
	s_nop 0
	v_add_u32_e32 v116, 16, v152
	v_add_u32_e32 v104, v122, v116
	v_ashrrev_i32_e32 v105, 31, v104
	v_lshlrev_b64 v[104:105], 12, v[104:105]
	v_lshl_add_u64 v[104:105], s[4:5], 0, v[104:105]
	v_lshl_add_u64 v[104:105], v[104:105], 0, v[136:137]
	global_store_dwordx4 v[104:105], v[110:113], off
	v_cvt_pk_bf16_f32 v100, v100, v101
	v_cvt_pk_bf16_f32 v101, v102, v103
	v_cvt_pk_bf16_f32 v102, v92, v93
	v_add_u32_e32 v92, v121, v116
	v_ashrrev_i32_e32 v93, 31, v92
	v_lshlrev_b64 v[92:93], 12, v[92:93]
	v_lshl_add_u64 v[92:93], s[4:5], 0, v[92:93]
	v_lshl_add_u64 v[92:93], v[92:93], 0, v[108:109]
	v_cvt_pk_bf16_f32 v103, v94, v95
	global_store_dwordx4 v[92:93], v[100:103], off
	v_cvt_pk_bf16_f32 v92, v96, v97
	v_cvt_pk_bf16_f32 v93, v98, v99
	v_cvt_pk_bf16_f32 v94, v88, v89
	v_cvt_pk_bf16_f32 v95, v90, v91
	s_mov_b32 s45, s6
	s_nop 0
	v_add_u32_e32 v100, 32, v152
	v_add_u32_e32 v88, v122, v100
	v_ashrrev_i32_e32 v89, 31, v88
	v_lshlrev_b64 v[88:89], 12, v[88:89]
	v_lshl_add_u64 v[88:89], s[4:5], 0, v[88:89]
	v_lshl_add_u64 v[88:89], v[88:89], 0, v[136:137]
	global_store_dwordx4 v[88:89], v[92:95], off
	v_cvt_pk_bf16_f32 v84, v84, v85
	v_cvt_pk_bf16_f32 v85, v86, v87
	v_cvt_pk_bf16_f32 v86, v76, v77
	v_add_u32_e32 v76, v121, v100
	v_ashrrev_i32_e32 v77, 31, v76
	v_lshlrev_b64 v[76:77], 12, v[76:77]
	v_lshl_add_u64 v[76:77], s[4:5], 0, v[76:77]
	v_lshl_add_u64 v[76:77], v[76:77], 0, v[108:109]
	v_cvt_pk_bf16_f32 v87, v78, v79
	global_store_dwordx4 v[76:77], v[84:87], off
	v_cvt_pk_bf16_f32 v76, v80, v81
	v_cvt_pk_bf16_f32 v77, v82, v83
	v_cvt_pk_bf16_f32 v78, v72, v73
	v_cvt_pk_bf16_f32 v79, v74, v75
	s_mov_b32 s16, s8
	s_nop 0
	v_add_u32_e32 v84, 48, v152
	v_add_u32_e32 v72, v122, v84
	v_ashrrev_i32_e32 v73, 31, v72
	v_lshlrev_b64 v[72:73], 12, v[72:73]
	v_lshl_add_u64 v[72:73], s[4:5], 0, v[72:73]
	v_lshl_add_u64 v[72:73], v[72:73], 0, v[136:137]
	global_store_dwordx4 v[72:73], v[76:79], off
	v_cvt_pk_bf16_f32 v68, v68, v69
	v_cvt_pk_bf16_f32 v69, v70, v71
	v_cvt_pk_bf16_f32 v70, v64, v65
	v_add_u32_e32 v64, v121, v84
	v_ashrrev_i32_e32 v65, 31, v64
	v_lshlrev_b64 v[64:65], 12, v[64:65]
	v_lshl_add_u64 v[64:65], s[4:5], 0, v[64:65]
	v_lshl_add_u64 v[64:65], v[64:65], 0, v[108:109]
	v_cvt_pk_bf16_f32 v71, v66, v67
	global_store_dwordx4 v[64:65], v[68:71], off
	v_add_u32_e32 v64, 0x80, v152
	v_cvt_pk_bf16_f32 v60, v60, v61
	v_cvt_pk_bf16_f32 v61, v62, v63
	v_cvt_pk_bf16_f32 v62, v56, v57
	v_add_u32_e32 v56, v122, v64
	v_ashrrev_i32_e32 v57, 31, v56
	v_lshlrev_b64 v[56:57], 12, v[56:57]
	v_lshl_add_u64 v[56:57], s[4:5], 0, v[56:57]
	v_lshl_add_u64 v[56:57], v[56:57], 0, v[136:137]
	v_cvt_pk_bf16_f32 v63, v58, v59
	global_store_dwordx4 v[56:57], v[60:63], off
	v_cvt_pk_bf16_f32 v52, v52, v53
	v_cvt_pk_bf16_f32 v53, v54, v55
	v_cvt_pk_bf16_f32 v54, v44, v45
	v_add_u32_e32 v44, v121, v64
	v_ashrrev_i32_e32 v45, 31, v44
	v_lshlrev_b64 v[44:45], 12, v[44:45]
	v_lshl_add_u64 v[44:45], s[4:5], 0, v[44:45]
	v_lshl_add_u64 v[44:45], v[44:45], 0, v[108:109]
	v_cvt_pk_bf16_f32 v55, v46, v47
	global_store_dwordx4 v[44:45], v[52:55], off
	v_cvt_pk_bf16_f32 v44, v48, v49
	v_cvt_pk_bf16_f32 v45, v50, v51
	v_cvt_pk_bf16_f32 v46, v40, v41
	v_cvt_pk_bf16_f32 v47, v42, v43
	s_mov_b64 s[20:21], s[14:15]
	s_nop 0
	v_add_u32_e32 v52, 0x90, v152
	v_add_u32_e32 v40, v122, v52
	v_ashrrev_i32_e32 v41, 31, v40
	v_lshlrev_b64 v[40:41], 12, v[40:41]
	v_lshl_add_u64 v[40:41], s[4:5], 0, v[40:41]
	v_lshl_add_u64 v[40:41], v[40:41], 0, v[136:137]
	global_store_dwordx4 v[40:41], v[44:47], off
	v_cvt_pk_bf16_f32 v36, v36, v37
	v_cvt_pk_bf16_f32 v37, v38, v39
	v_cvt_pk_bf16_f32 v38, v28, v29
	v_add_u32_e32 v28, v121, v52
	v_ashrrev_i32_e32 v29, 31, v28
	v_lshlrev_b64 v[28:29], 12, v[28:29]
	v_lshl_add_u64 v[28:29], s[4:5], 0, v[28:29]
	v_lshl_add_u64 v[28:29], v[28:29], 0, v[108:109]
	v_cvt_pk_bf16_f32 v39, v30, v31
	global_store_dwordx4 v[28:29], v[36:39], off
	v_cvt_pk_bf16_f32 v28, v32, v33
	v_cvt_pk_bf16_f32 v29, v34, v35
	v_cvt_pk_bf16_f32 v30, v24, v25
	v_cvt_pk_bf16_f32 v31, v26, v27
	s_mov_b64 s[18:19], s[12:13]
	s_nop 0
	v_add_u32_e32 v36, 0xa0, v152
	v_add_u32_e32 v24, v122, v36
	v_ashrrev_i32_e32 v25, 31, v24
	v_lshlrev_b64 v[24:25], 12, v[24:25]
	v_lshl_add_u64 v[24:25], s[4:5], 0, v[24:25]
	v_lshl_add_u64 v[24:25], v[24:25], 0, v[136:137]
	global_store_dwordx4 v[24:25], v[28:31], off
	v_cvt_pk_bf16_f32 v20, v20, v21
	v_cvt_pk_bf16_f32 v21, v22, v23
	v_cvt_pk_bf16_f32 v22, v12, v13
	v_add_u32_e32 v12, v121, v36
	v_ashrrev_i32_e32 v13, 31, v12
	v_lshlrev_b64 v[12:13], 12, v[12:13]
	v_lshl_add_u64 v[12:13], s[4:5], 0, v[12:13]
	v_lshl_add_u64 v[12:13], v[12:13], 0, v[108:109]
	v_cvt_pk_bf16_f32 v23, v14, v15
	global_store_dwordx4 v[12:13], v[20:23], off
	v_cvt_pk_bf16_f32 v12, v16, v17
	v_cvt_pk_bf16_f32 v13, v18, v19
	v_cvt_pk_bf16_f32 v14, v8, v9
	v_cvt_pk_bf16_f32 v15, v10, v11
	s_nop 1
	v_add_u32_e32 v20, 0xb0, v152
	v_add_u32_e32 v8, v122, v20
	v_ashrrev_i32_e32 v9, 31, v8
	v_lshlrev_b64 v[8:9], 12, v[8:9]
	v_lshl_add_u64 v[8:9], s[4:5], 0, v[8:9]
	v_lshl_add_u64 v[8:9], v[8:9], 0, v[136:137]
	global_store_dwordx4 v[8:9], v[12:15], off
	v_cvt_pk_bf16_f32 v4, v4, v5
	v_cvt_pk_bf16_f32 v5, v6, v7
	v_cvt_pk_bf16_f32 v6, v0, v1
	v_add_u32_e32 v0, v121, v20
	v_ashrrev_i32_e32 v1, 31, v0
	v_lshlrev_b64 v[0:1], 12, v[0:1]
	v_lshl_add_u64 v[0:1], s[4:5], 0, v[0:1]
	v_lshl_add_u64 v[0:1], v[0:1], 0, v[108:109]
	v_cvt_pk_bf16_f32 v7, v2, v3
	global_store_dwordx4 v[0:1], v[4:7], off
	s_cbranch_vccz .LBB0_666
; #define PG8_WAIT_V(n) asm volatile("s_waitcnt vmcnt(" #n ")" ::: "memory")
; #define PG8_BAR __builtin_amdgcn_s_barrier()
; template <class Epi, class Sched>
; __device__ __forceinline__ void gemm_phase(LAS unsigned char* lds, const Gemm g, const Sched& S, const Epi& E) {
;     ...
;     PG8_WAIT_V(0);
;     if (wr == 0) PG8_BAR;
;     PG8_BAR;
	s_waitcnt vmcnt(0)
	s_cmpk_gt_u32 s24, 0xff
	s_cbranch_scc1 .LBB0_677
	s_barrier

; #define PG8_STAGE(bufoff, gbase, voff) do { _Pragma("unroll") for (int _i = 0; _i < 2; ++_i) \
;         __builtin_amdgcn_global_load_lds((const unsigned*)((const char*)(gbase) + (voff)[_i]), (LAS unsigned*)(lds + (bufoff) + ldsw + _i * 8192), 16, 0, 0); } while (0)
; #define PG8_LDA(dst, b, h) do { _Pragma("unroll") for (int m = 0; m < 4; ++m) _Pragma("unroll") for (int k = 0; k < 2; ++k) dst[m][k] = *(const LAS bf16x8*)(lds + PG8_SA(b, h) + aoff + m * 2048 + k * 1024); } while (0)
; #define PG8_LDB(dst, b, h) do { _Pragma("unroll") for (int n = 0; n < 2; ++n) _Pragma("unroll") for (int k = 0; k < 2; ++k) dst[n][k] = *(const LAS bf16x8*)(lds + PG8_SB(b, h) + boff + n * 2048 + k * 1024); } while (0)
; #define PG8_MMA(ai, bj, At, Bt) do { __builtin_amdgcn_s_setprio(1); _Pragma("unroll") for (int m = 0; m < 4; ++m) _Pragma("unroll") for (int n = 0; n < 2; ++n) _Pragma("unroll") for (int k = 0; k < 2; ++k) \
;         acc[ai][bj][m][n] = __builtin_amdgcn_mfma_f32_16x16x32_bf16(Bt[n][k], At[m][k], acc[ai][bj][m][n], 0, 0, 0); __builtin_amdgcn_s_setprio(0); } while (0)
; #define PG8_WAIT_L(n) asm volatile("s_waitcnt lgkmcnt(" #n ")" ::: "memory")
; template <class Epi, class Sched>
; __device__ __forceinline__ void gemm_phase(LAS unsigned char* lds, const Gemm g, const Sched& S, const Epi& E) {
;     ...
;         const bool has_next = S.next(ui + 1, nxt);
;         const char* nA = has_next ? (const char*)g.A + (size_t)nxt.pm * tstep : cA; const char* nB = has_next ? (const char*)g.Bt + (size_t)nxt.pn * tstep : cB;
;         for (int t = 0; t < nt; t += 2) {
;             const bool last = (t == nt - 2);
;             const char* a1 = cA + (size_t)(t + 1) * kstep;
;             const char* a2 = last ? nA : cA + (size_t)(t + 2) * kstep; const char* b2 = last ? nB : cB + (size_t)(t + 2) * kstep;
;             const char* a3 = a2 + kstep; const char* b3 = b2 + kstep;
;             PG8_LDB(B0, 0, 0); PG8_SCHED; PG8_LDA(At, 0, 0); PG8_STAGE(PG8_SA(1, 1), a1 + hstep, voffA);
;             PG8_WAIT_L(8); PG8_BAR; PG8_WAIT_L(0); PG8_MMA(0, 0, At, B0); PG8_BAR; PG8_SCHED;
;             PG8_LDB(B1, 0, 1); PG8_STAGE(PG8_SB(0, 0), b2, voffB);
;             PG8_BAR; PG8_WAIT_L(0); PG8_MMA(0, 1, At, B1); PG8_BAR;
;             PG8_LDA(At, 0, 1); PG8_STAGE(PG8_SA(0, 0), a2, voffA);
;             PG8_BAR; PG8_WAIT_L(0); PG8_MMA(1, 0, At, B0); PG8_BAR; PG8_SCHED;
.LBB0_692:
	s_ashr_i32 s19, s18, 31
	v_cmp_lt_i64_e64 s[24:25], s[20:21], 32
	s_lshl_b64 s[20:21], s[18:19], 19
	s_add_u32 s20, s40, s20
	s_addc_u32 s21, s41, s21
	s_and_b64 s[22:23], s[24:25], exec
	s_cselect_b32 s19, s21, s3
	s_cselect_b32 s57, s20, s2
	s_ashr_i32 s17, s16, 31
	s_lshl_b64 s[22:23], s[16:17], 19
	s_add_u32 s22, s28, s22
	s_addc_u32 s23, s29, s23
	s_and_b64 s[24:25], s[24:25], exec
	s_cselect_b32 s17, s23, s5
	s_cselect_b32 s58, s22, s4
	s_add_u32 s2, s2, 0x40080
	s_addc_u32 s3, s3, 0
	s_add_u32 s59, s4, 0x100
	s_addc_u32 s60, s5, 0
	s_mov_b32 s61, -2
	s_waitcnt lgkmcnt(0)
	ds_read_b128 v[140:143], v149
	ds_read_b128 v[154:157], v149 offset:1024
	ds_read_b128 v[158:161], v149 offset:2048
	ds_read_b128 v[162:165], v149 offset:3072
	s_add_u32 s4, s2, 0xfffc0080
	s_addc_u32 s5, s3, -1
	s_cmp_eq_u32 s61, 12
	s_cselect_b32 s25, s19, s5
	s_cselect_b32 s24, s57, s4
	s_cselect_b32 s5, s17, s60
	s_cselect_b32 s4, s58, s59
	s_add_i32 m0, s33, 0xc000
	ds_read_b128 v[166:169], v150
	ds_read_b128 v[170:173], v150 offset:1024
	ds_read_b128 v[174:177], v150 offset:2048
	ds_read_b128 v[178:181], v150 offset:3072
	ds_read_b128 v[182:185], v150 offset:4096
	ds_read_b128 v[186:189], v150 offset:5120
	ds_read_b128 v[190:193], v150 offset:6144
	ds_read_b128 v[194:197], v150 offset:7168
	global_load_lds_dwordx4 v136, s[2:3]
	s_add_i32 m0, s33, 0xe000
	s_nop 0
	global_load_lds_dwordx4 v138, s[2:3]
	s_waitcnt lgkmcnt(8)
	s_waitcnt vmcnt(10)
	s_barrier
	s_waitcnt lgkmcnt(0)
	s_setprio 1
	s_waitcnt lgkmcnt(0)
	v_mfma_f32_16x16x32_bf16 v[124:127], v[140:143], v[166:169], 0
	v_mfma_f32_16x16x32_bf16 v[120:123], v[158:161], v[166:169], 0
	v_mfma_f32_16x16x32_bf16 v[108:111], v[140:143], v[174:177], 0
	v_mfma_f32_16x16x32_bf16 v[104:107], v[158:161], v[174:177], 0
	v_mfma_f32_16x16x32_bf16 v[92:95], v[140:143], v[182:185], 0
	v_mfma_f32_16x16x32_bf16 v[88:91], v[158:161], v[182:185], 0
	v_mfma_f32_16x16x32_bf16 v[76:79], v[140:143], v[190:193], 0
	v_mfma_f32_16x16x32_bf16 v[72:75], v[158:161], v[190:193], 0
	v_mfma_f32_16x16x32_bf16 v[124:127], v[154:157], v[170:173], v[124:127]
	v_mfma_f32_16x16x32_bf16 v[120:123], v[162:165], v[170:173], v[120:123]
	v_mfma_f32_16x16x32_bf16 v[108:111], v[154:157], v[178:181], v[108:111]
	v_mfma_f32_16x16x32_bf16 v[104:107], v[162:165], v[178:181], v[104:107]
	v_mfma_f32_16x16x32_bf16 v[92:95], v[154:157], v[186:189], v[92:95]
	v_mfma_f32_16x16x32_bf16 v[88:91], v[162:165], v[186:189], v[88:91]
	v_mfma_f32_16x16x32_bf16 v[76:79], v[154:157], v[194:197], v[76:79]
	v_mfma_f32_16x16x32_bf16 v[72:75], v[162:165], v[194:197], v[72:75]
	s_setprio 0
	s_barrier
	s_add_i32 s62, s47, s31
	s_mov_b32 m0, s62
	ds_read_b128 v[202:205], v151
	ds_read_b128 v[206:209], v151 offset:1024
	ds_read_b128 v[210:213], v151 offset:2048
	ds_read_b128 v[214:217], v151 offset:3072
	global_load_lds_dwordx4 v130, s[4:5]
	s_add_i32 m0, s62, 0x2000
	s_nop 0
	global_load_lds_dwordx4 v134, s[4:5]
	s_waitcnt vmcnt(10)
	s_barrier
	s_waitcnt lgkmcnt(0)
	s_setprio 1
	s_waitcnt lgkmcnt(0)
	v_mfma_f32_16x16x32_bf16 v[116:119], v[202:205], v[166:169], 0
	v_mfma_f32_16x16x32_bf16 v[112:115], v[210:213], v[166:169], 0
	v_mfma_f32_16x16x32_bf16 v[100:103], v[202:205], v[174:177], 0
	v_mfma_f32_16x16x32_bf16 v[96:99], v[210:213], v[174:177], 0
	v_mfma_f32_16x16x32_bf16 v[84:87], v[202:205], v[182:185], 0
	v_mfma_f32_16x16x32_bf16 v[80:83], v[210:213], v[182:185], 0
	v_mfma_f32_16x16x32_bf16 v[68:71], v[202:205], v[190:193], 0
	v_mfma_f32_16x16x32_bf16 v[64:67], v[210:213], v[190:193], 0
	v_mfma_f32_16x16x32_bf16 v[116:119], v[206:209], v[170:173], v[116:119]
	v_mfma_f32_16x16x32_bf16 v[112:115], v[214:217], v[170:173], v[112:115]
	v_mfma_f32_16x16x32_bf16 v[100:103], v[206:209], v[178:181], v[100:103]
	v_mfma_f32_16x16x32_bf16 v[96:99], v[214:217], v[178:181], v[96:99]
	v_mfma_f32_16x16x32_bf16 v[84:87], v[206:209], v[186:189], v[84:87]
	v_mfma_f32_16x16x32_bf16 v[80:83], v[214:217], v[186:189], v[80:83]
	v_mfma_f32_16x16x32_bf16 v[68:71], v[206:209], v[194:197], v[68:71]
	v_mfma_f32_16x16x32_bf16 v[64:67], v[214:217], v[194:197], v[64:67]
	s_setprio 0
	s_mov_b32 m0, s33
	v_lshl_add_u64 v[218:219], s[24:25], 0, v[128:129]
	s_barrier
	ds_read_b128 v[166:169], v150 offset:16384
	ds_read_b128 v[170:173], v150 offset:17408
	ds_read_b128 v[174:177], v150 offset:18432
	ds_read_b128 v[178:181], v150 offset:19456
	ds_read_b128 v[182:185], v150 offset:20480
	ds_read_b128 v[186:189], v150 offset:21504
	ds_read_b128 v[190:193], v150 offset:22528
	ds_read_b128 v[194:197], v150 offset:23552
	global_load_lds_dwordx4 v128, s[24:25]
	v_lshl_add_u64 v[220:221], s[24:25], 0, v[132:133]
	s_mov_b32 m0, s34
	s_nop 0
	global_load_lds_dwordx4 v132, s[24:25]
	s_barrier
	s_waitcnt lgkmcnt(0)
	s_setprio 1
	s_waitcnt lgkmcnt(0)
	v_mfma_f32_16x16x32_bf16 v[60:63], v[140:143], v[166:169], 0
	v_mfma_f32_16x16x32_bf16 v[56:59], v[158:161], v[166:169], 0
	v_mfma_f32_16x16x32_bf16 v[44:47], v[140:143], v[174:177], 0
	v_mfma_f32_16x16x32_bf16 v[40:43], v[158:161], v[174:177], 0
	v_mfma_f32_16x16x32_bf16 v[28:31], v[140:143], v[182:185], 0
	v_mfma_f32_16x16x32_bf16 v[24:27], v[158:161], v[182:185], 0
	v_mfma_f32_16x16x32_bf16 v[12:15], v[140:143], v[190:193], 0
	v_mfma_f32_16x16x32_bf16 v[8:11], v[158:161], v[190:193], 0
	v_mfma_f32_16x16x32_bf16 v[60:63], v[154:157], v[170:173], v[60:63]
	v_mfma_f32_16x16x32_bf16 v[56:59], v[162:165], v[170:173], v[56:59]
	v_mfma_f32_16x16x32_bf16 v[44:47], v[154:157], v[178:181], v[44:47]
	v_mfma_f32_16x16x32_bf16 v[40:43], v[162:165], v[178:181], v[40:43]
	v_mfma_f32_16x16x32_bf16 v[28:31], v[154:157], v[186:189], v[28:31]
	v_mfma_f32_16x16x32_bf16 v[24:27], v[162:165], v[186:189], v[24:27]
	v_mfma_f32_16x16x32_bf16 v[12:15], v[154:157], v[194:197], v[12:15]
	v_mfma_f32_16x16x32_bf16 v[8:11], v[162:165], v[194:197], v[8:11]
	s_setprio 0
	s_barrier
; #define PG8_STAGE(bufoff, gbase, voff) do { _Pragma("unroll") for (int _i = 0; _i < 2; ++_i) \
;         __builtin_amdgcn_global_load_lds((const unsigned*)((const char*)(gbase) + (voff)[_i]), (LAS unsigned*)(lds + (bufoff) + ldsw + _i * 8192), 16, 0, 0); } while (0)
; #define PG8_LDA(dst, b, h) do { _Pragma("unroll") for (int m = 0; m < 4; ++m) _Pragma("unroll") for (int k = 0; k < 2; ++k) dst[m][k] = *(const LAS bf16x8*)(lds + PG8_SA(b, h) + aoff + m * 2048 + k * 1024); } while (0)
; #define PG8_LDB(dst, b, h) do { _Pragma("unroll") for (int n = 0; n < 2; ++n) _Pragma("unroll") for (int k = 0; k < 2; ++k) dst[n][k] = *(const LAS bf16x8*)(lds + PG8_SB(b, h) + boff + n * 2048 + k * 1024); } while (0)
; #define PG8_MMA(ai, bj, At, Bt) do { __builtin_amdgcn_s_setprio(1); _Pragma("unroll") for (int m = 0; m < 4; ++m) _Pragma("unroll") for (int n = 0; n < 2; ++n) _Pragma("unroll") for (int k = 0; k < 2; ++k) \
;         acc[ai][bj][m][n] = __builtin_amdgcn_mfma_f32_16x16x32_bf16(Bt[n][k], At[m][k], acc[ai][bj][m][n], 0, 0, 0); __builtin_amdgcn_s_setprio(0); } while (0)
; #define PG8_WAIT_V(n) asm volatile("s_waitcnt vmcnt(" #n ")" ::: "memory")
; #define PG8_WAIT_L(n) asm volatile("s_waitcnt lgkmcnt(" #n ")" ::: "memory")
; #define PG8_BAR __builtin_amdgcn_s_barrier()
; #define PG8_SCHED __builtin_amdgcn_sched_barrier(0)
; template <class Epi, class Sched>
; __device__ __forceinline__ void gemm_phase(LAS unsigned char* lds, const Gemm g, const Sched& S, const Epi& E) {
;     ...
;             PG8_BAR; PG8_WAIT_L(0); PG8_MMA(1, 0, At, B0); PG8_BAR; PG8_SCHED;
;             PG8_STAGE(PG8_SB(0, 1), b2 + hstep, voffB);
;             PG8_WAIT_V(6); PG8_BAR; PG8_MMA(1, 1, At, B1); PG8_BAR;
;             PG8_LDB(B0, 1, 0); PG8_SCHED; PG8_LDA(At, 1, 0); PG8_STAGE(PG8_SA(0, 1), a2 + hstep, voffA);
;             PG8_WAIT_L(8); PG8_BAR; PG8_WAIT_L(0); PG8_MMA(0, 0, At, B0); PG8_BAR; PG8_SCHED;
;             PG8_LDB(B1, 1, 1); PG8_STAGE(PG8_SB(1, 0), b3, voffB);
;             PG8_BAR; PG8_WAIT_L(0); PG8_MMA(0, 1, At, B1); PG8_BAR;
;             PG8_LDA(At, 1, 1); PG8_STAGE(PG8_SA(1, 0), a3, voffA);
;             PG8_BAR; PG8_WAIT_L(0); PG8_MMA(1, 0, At, B0); PG8_BAR; PG8_SCHED;
	s_add_u32 s62, s4, 0x40000
	s_addc_u32 s63, s5, 0
	s_add_i32 s64, s48, s31
	s_mov_b32 m0, s64
	s_nop 0
	global_load_lds_dwordx4 v130, s[62:63]
	s_add_i32 m0, s64, 0x2000
	s_nop 0
	global_load_lds_dwordx4 v134, s[62:63]
	s_waitcnt vmcnt(10)
	s_barrier
	s_setprio 1
	v_mfma_f32_16x16x32_bf16 v[52:55], v[202:205], v[166:169], 0
	v_mfma_f32_16x16x32_bf16 v[48:51], v[210:213], v[166:169], 0
	v_mfma_f32_16x16x32_bf16 v[36:39], v[202:205], v[174:177], 0
	v_mfma_f32_16x16x32_bf16 v[32:35], v[210:213], v[174:177], 0
	v_mfma_f32_16x16x32_bf16 v[20:23], v[202:205], v[182:185], 0
	v_mfma_f32_16x16x32_bf16 v[16:19], v[210:213], v[182:185], 0
	v_mfma_f32_16x16x32_bf16 v[4:7], v[202:205], v[190:193], 0
	v_mfma_f32_16x16x32_bf16 v[0:3], v[210:213], v[190:193], 0
	v_mfma_f32_16x16x32_bf16 v[52:55], v[206:209], v[170:173], v[52:55]
	v_mfma_f32_16x16x32_bf16 v[48:51], v[214:217], v[170:173], v[48:51]
	v_mfma_f32_16x16x32_bf16 v[36:39], v[206:209], v[178:181], v[36:39]
	v_mfma_f32_16x16x32_bf16 v[32:35], v[214:217], v[178:181], v[32:35]
	v_mfma_f32_16x16x32_bf16 v[20:23], v[206:209], v[186:189], v[20:23]
	v_mfma_f32_16x16x32_bf16 v[16:19], v[214:217], v[186:189], v[16:19]
	v_mfma_f32_16x16x32_bf16 v[4:7], v[206:209], v[194:197], v[4:7]
	v_mfma_f32_16x16x32_bf16 v[0:3], v[214:217], v[194:197], v[0:3]
	s_setprio 0
	s_add_i32 s62, 0, 0x18000
	v_add_u32_e32 v162, s62, v148
	s_barrier
	ds_read_b128 v[140:143], v162
	ds_read_b128 v[154:157], v162 offset:1024
	ds_read_b128 v[158:161], v162 offset:2048
	ds_read_b128 v[162:165], v162 offset:3072
	s_add_u32 s24, s24, 0x40000
	s_addc_u32 s25, s25, 0
	s_mov_b32 m0, s35
	ds_read_b128 v[166:169], v150 offset:32768
	ds_read_b128 v[170:173], v150 offset:33792
	ds_read_b128 v[174:177], v150 offset:34816
	ds_read_b128 v[178:181], v150 offset:35840
	ds_read_b128 v[182:185], v150 offset:36864
	ds_read_b128 v[186:189], v150 offset:37888
	ds_read_b128 v[190:193], v150 offset:38912
	ds_read_b128 v[194:197], v150 offset:39936
	global_load_lds_dwordx4 v128, s[24:25]
	s_mov_b32 m0, s36
	s_nop 0
	global_load_lds_dwordx4 v132, s[24:25]
	s_waitcnt lgkmcnt(8)
	s_waitcnt vmcnt(10)
	s_barrier
	s_waitcnt lgkmcnt(0)
	s_setprio 1
	s_waitcnt lgkmcnt(0)
	v_mfma_f32_16x16x32_bf16 v[124:127], v[140:143], v[166:169], v[124:127]
	v_mfma_f32_16x16x32_bf16 v[120:123], v[158:161], v[166:169], v[120:123]
	v_mfma_f32_16x16x32_bf16 v[108:111], v[140:143], v[174:177], v[108:111]
	v_mfma_f32_16x16x32_bf16 v[104:107], v[158:161], v[174:177], v[104:107]
	v_mfma_f32_16x16x32_bf16 v[92:95], v[140:143], v[182:185], v[92:95]
	v_mfma_f32_16x16x32_bf16 v[88:91], v[158:161], v[182:185], v[88:91]
	v_mfma_f32_16x16x32_bf16 v[76:79], v[140:143], v[190:193], v[76:79]
	v_mfma_f32_16x16x32_bf16 v[72:75], v[158:161], v[190:193], v[72:75]
	v_mfma_f32_16x16x32_bf16 v[124:127], v[154:157], v[170:173], v[124:127]
	v_mfma_f32_16x16x32_bf16 v[120:123], v[162:165], v[170:173], v[120:123]
	v_mfma_f32_16x16x32_bf16 v[108:111], v[154:157], v[178:181], v[108:111]
	v_mfma_f32_16x16x32_bf16 v[104:107], v[162:165], v[178:181], v[104:107]
	v_mfma_f32_16x16x32_bf16 v[92:95], v[154:157], v[186:189], v[92:95]
	v_mfma_f32_16x16x32_bf16 v[88:91], v[162:165], v[186:189], v[88:91]
	v_mfma_f32_16x16x32_bf16 v[76:79], v[154:157], v[194:197], v[76:79]
	v_mfma_f32_16x16x32_bf16 v[72:75], v[162:165], v[194:197], v[72:75]
	s_setprio 0
	s_barrier
	s_add_i32 s24, 0, 0x1c000
	s_add_i32 s25, s62, s31
	v_add_u32_e32 v214, s24, v148
	s_add_u32 s0, s4, 0x80
	s_addc_u32 s1, s5, 0
	s_mov_b32 m0, s25
	ds_read_b128 v[202:205], v214
	ds_read_b128 v[206:209], v214 offset:1024
	ds_read_b128 v[210:213], v214 offset:2048
	ds_read_b128 v[214:217], v214 offset:3072
	global_load_lds_dwordx4 v130, s[0:1]
	s_add_i32 m0, s25, 0x2000
	s_nop 0
	global_load_lds_dwordx4 v134, s[0:1]
	s_waitcnt vmcnt(10)
	s_barrier
	s_waitcnt lgkmcnt(0)
	s_setprio 1
	s_waitcnt lgkmcnt(0)
	v_mfma_f32_16x16x32_bf16 v[116:119], v[202:205], v[166:169], v[116:119]
	v_mfma_f32_16x16x32_bf16 v[112:115], v[210:213], v[166:169], v[112:115]
	v_mfma_f32_16x16x32_bf16 v[100:103], v[202:205], v[174:177], v[100:103]
	v_mfma_f32_16x16x32_bf16 v[96:99], v[210:213], v[174:177], v[96:99]
	v_mfma_f32_16x16x32_bf16 v[84:87], v[202:205], v[182:185], v[84:87]
	v_mfma_f32_16x16x32_bf16 v[80:83], v[210:213], v[182:185], v[80:83]
	v_mfma_f32_16x16x32_bf16 v[68:71], v[202:205], v[190:193], v[68:71]
	v_mfma_f32_16x16x32_bf16 v[64:67], v[210:213], v[190:193], v[64:67]
	v_mfma_f32_16x16x32_bf16 v[116:119], v[206:209], v[170:173], v[116:119]
	v_mfma_f32_16x16x32_bf16 v[112:115], v[214:217], v[170:173], v[112:115]
	v_mfma_f32_16x16x32_bf16 v[100:103], v[206:209], v[178:181], v[100:103]
	v_mfma_f32_16x16x32_bf16 v[96:99], v[214:217], v[178:181], v[96:99]
	v_mfma_f32_16x16x32_bf16 v[84:87], v[206:209], v[186:189], v[84:87]
	v_mfma_f32_16x16x32_bf16 v[80:83], v[214:217], v[186:189], v[80:83]
	v_mfma_f32_16x16x32_bf16 v[68:71], v[206:209], v[194:197], v[68:71]
	v_mfma_f32_16x16x32_bf16 v[64:67], v[214:217], v[194:197], v[64:67]
	s_setprio 0
	s_mov_b32 m0, s44
	s_mov_b64 s[0:1], 0x80
	v_lshl_add_u64 v[144:145], v[218:219], 0, s[0:1]
	s_barrier
	ds_read_b128 v[166:169], v150 offset:49152
	ds_read_b128 v[170:173], v150 offset:50176
	ds_read_b128 v[174:177], v150 offset:51200
	ds_read_b128 v[178:181], v150 offset:52224
	ds_read_b128 v[182:185], v150 offset:53248
	ds_read_b128 v[186:189], v150 offset:54272
	ds_read_b128 v[190:193], v150 offset:55296
	ds_read_b128 v[194:197], v150 offset:56320
	global_load_lds_dwordx4 v[144:145], off
	v_lshl_add_u64 v[144:145], v[220:221], 0, s[0:1]
	s_mov_b32 m0, s45
	s_nop 0
	global_load_lds_dwordx4 v[144:145], off
	s_barrier
; #define PG8_STAGE(bufoff, gbase, voff) do { _Pragma("unroll") for (int _i = 0; _i < 2; ++_i) \
;         __builtin_amdgcn_global_load_lds((const unsigned*)((const char*)(gbase) + (voff)[_i]), (LAS unsigned*)(lds + (bufoff) + ldsw + _i * 8192), 16, 0, 0); } while (0)
; #define PG8_LDA(dst, b, h) do { _Pragma("unroll") for (int m = 0; m < 4; ++m) _Pragma("unroll") for (int k = 0; k < 2; ++k) dst[m][k] = *(const LAS bf16x8*)(lds + PG8_SA(b, h) + aoff + m * 2048 + k * 1024); } while (0)
; #define PG8_LDB(dst, b, h) do { _Pragma("unroll") for (int n = 0; n < 2; ++n) _Pragma("unroll") for (int k = 0; k < 2; ++k) dst[n][k] = *(const LAS bf16x8*)(lds + PG8_SB(b, h) + boff + n * 2048 + k * 1024); } while (0)
; #define PG8_WAIT_V(n) asm volatile("s_waitcnt vmcnt(" #n ")" ::: "memory")
; #define PG8_WAIT_L(n) asm volatile("s_waitcnt lgkmcnt(" #n ")" ::: "memory")
; #define PG8_BAR __builtin_amdgcn_s_barrier()
; #define PG8_SCHED __builtin_amdgcn_sched_barrier(0)
; template <class Epi, class Sched>
; __device__ __forceinline__ void gemm_phase(LAS unsigned char* lds, const Gemm g, const Sched& S, const Epi& E) {
;     ...
;             PG8_LDB(B0, 0, 0); PG8_SCHED; PG8_LDA(At, 0, 0); PG8_STAGE(PG8_SA(1, 1), a1 + hstep, voffA);
;             PG8_WAIT_L(8); PG8_BAR; PG8_WAIT_L(0); PG8_MMA(0, 0, At, B0); PG8_BAR; PG8_SCHED;
;             PG8_LDB(B1, 0, 1); PG8_STAGE(PG8_SB(0, 0), b2, voffB);
;             PG8_BAR; PG8_WAIT_L(0); PG8_MMA(0, 1, At, B1); PG8_BAR;
;             PG8_LDA(At, 0, 1); PG8_STAGE(PG8_SA(0, 0), a2, voffA);
;             PG8_BAR; PG8_WAIT_L(0); PG8_MMA(1, 0, At, B0); PG8_BAR; PG8_SCHED;
;             PG8_STAGE(PG8_SB(0, 1), b2 + hstep, voffB);
;             PG8_WAIT_V(6); PG8_BAR; PG8_MMA(1, 1, At, B1); PG8_BAR;
;             PG8_LDB(B0, 1, 0); PG8_SCHED; PG8_LDA(At, 1, 0); PG8_STAGE(PG8_SA(0, 1), a2 + hstep, voffA);
;             PG8_WAIT_L(8); PG8_BAR; PG8_WAIT_L(0); PG8_MMA(0, 0, At, B0); PG8_BAR; PG8_SCHED;
;             PG8_LDB(B1, 1, 1); PG8_STAGE(PG8_SB(1, 0), b3, voffB);
;             PG8_BAR; PG8_WAIT_L(0); PG8_MMA(0, 1, At, B1); PG8_BAR;
;             PG8_LDA(At, 1, 1); PG8_STAGE(PG8_SA(1, 0), a3, voffA);
;             PG8_BAR; PG8_WAIT_L(0); PG8_MMA(1, 0, At, B0); PG8_BAR; PG8_SCHED;
;             PG8_STAGE(PG8_SB(1, 1), b3 + hstep, voffB);
;             PG8_WAIT_V(6); PG8_BAR; PG8_MMA(1, 1, At, B1); PG8_BAR;
	s_waitcnt lgkmcnt(0)
	s_setprio 1
	s_waitcnt lgkmcnt(0)
	v_mfma_f32_16x16x32_bf16 v[60:63], v[140:143], v[166:169], v[60:63]
	v_mfma_f32_16x16x32_bf16 v[56:59], v[158:161], v[166:169], v[56:59]
	v_mfma_f32_16x16x32_bf16 v[44:47], v[140:143], v[174:177], v[44:47]
	v_mfma_f32_16x16x32_bf16 v[40:43], v[158:161], v[174:177], v[40:43]
	v_mfma_f32_16x16x32_bf16 v[28:31], v[140:143], v[182:185], v[28:31]
	v_mfma_f32_16x16x32_bf16 v[24:27], v[158:161], v[182:185], v[24:27]
	v_mfma_f32_16x16x32_bf16 v[12:15], v[140:143], v[190:193], v[12:15]
	v_mfma_f32_16x16x32_bf16 v[8:11], v[158:161], v[190:193], v[8:11]
	v_mfma_f32_16x16x32_bf16 v[60:63], v[154:157], v[170:173], v[60:63]
	v_mfma_f32_16x16x32_bf16 v[56:59], v[162:165], v[170:173], v[56:59]
	v_mfma_f32_16x16x32_bf16 v[44:47], v[154:157], v[178:181], v[44:47]
	v_mfma_f32_16x16x32_bf16 v[40:43], v[162:165], v[178:181], v[40:43]
	v_mfma_f32_16x16x32_bf16 v[28:31], v[154:157], v[186:189], v[28:31]
	v_mfma_f32_16x16x32_bf16 v[24:27], v[162:165], v[186:189], v[24:27]
	v_mfma_f32_16x16x32_bf16 v[12:15], v[154:157], v[194:197], v[12:15]
	v_mfma_f32_16x16x32_bf16 v[8:11], v[162:165], v[194:197], v[8:11]
	s_setprio 0
	s_barrier
	s_add_u32 s4, s4, 0x40080
	s_addc_u32 s5, s5, 0
	s_add_i32 s24, s24, s31
	s_mov_b32 m0, s24
	s_nop 0
	global_load_lds_dwordx4 v130, s[4:5]
	s_add_i32 m0, s24, 0x2000
	s_nop 0
	global_load_lds_dwordx4 v134, s[4:5]
	s_waitcnt vmcnt(10)
	s_barrier
	s_setprio 1
	v_mfma_f32_16x16x32_bf16 v[52:55], v[202:205], v[166:169], v[52:55]
	v_mfma_f32_16x16x32_bf16 v[48:51], v[210:213], v[166:169], v[48:51]
	v_mfma_f32_16x16x32_bf16 v[36:39], v[202:205], v[174:177], v[36:39]
	v_mfma_f32_16x16x32_bf16 v[32:35], v[210:213], v[174:177], v[32:35]
	v_mfma_f32_16x16x32_bf16 v[20:23], v[202:205], v[182:185], v[20:23]
	v_mfma_f32_16x16x32_bf16 v[16:19], v[210:213], v[182:185], v[16:19]
	v_mfma_f32_16x16x32_bf16 v[4:7], v[202:205], v[190:193], v[4:7]
	v_mfma_f32_16x16x32_bf16 v[0:3], v[210:213], v[190:193], v[0:3]
	v_mfma_f32_16x16x32_bf16 v[52:55], v[206:209], v[170:173], v[52:55]
	v_mfma_f32_16x16x32_bf16 v[48:51], v[214:217], v[170:173], v[48:51]
	v_mfma_f32_16x16x32_bf16 v[36:39], v[206:209], v[178:181], v[36:39]
	v_mfma_f32_16x16x32_bf16 v[32:35], v[214:217], v[178:181], v[32:35]
	v_mfma_f32_16x16x32_bf16 v[20:23], v[206:209], v[186:189], v[20:23]
	v_mfma_f32_16x16x32_bf16 v[16:19], v[214:217], v[186:189], v[16:19]
	v_mfma_f32_16x16x32_bf16 v[4:7], v[206:209], v[194:197], v[4:7]
	v_mfma_f32_16x16x32_bf16 v[0:3], v[214:217], v[194:197], v[0:3]
	s_setprio 0
	s_add_i32 s61, s61, 2
	s_add_u32 s2, s2, 0x100
	s_addc_u32 s3, s3, 0
	s_add_u32 s59, s59, 0x100
	s_addc_u32 s60, s60, 0
	s_cmp_gt_u32 s61, 13
	s_barrier
.LBB0_693:
	ds_read_b128 v[140:143], v149
	ds_read_b128 v[154:157], v149 offset:1024
	ds_read_b128 v[158:161], v149 offset:2048
	ds_read_b128 v[162:165], v149 offset:3072
	s_add_u32 s4, s2, 0xfffc0080
	s_addc_u32 s5, s3, -1
	s_cmp_eq_u32 s61, 12
	s_cselect_b32 s25, s19, s5
	s_cselect_b32 s24, s57, s4
	s_cselect_b32 s5, s17, s60
	s_cselect_b32 s4, s58, s59
	s_add_i32 m0, s33, 0xc000
	ds_read_b128 v[166:169], v150
	ds_read_b128 v[170:173], v150 offset:1024
	ds_read_b128 v[174:177], v150 offset:2048
	ds_read_b128 v[178:181], v150 offset:3072
	ds_read_b128 v[182:185], v150 offset:4096
	ds_read_b128 v[186:189], v150 offset:5120
	ds_read_b128 v[190:193], v150 offset:6144
	ds_read_b128 v[194:197], v150 offset:7168
	global_load_lds_dwordx4 v136, s[2:3]
	s_add_i32 m0, s33, 0xe000
	s_nop 0
	global_load_lds_dwordx4 v138, s[2:3]
	s_waitcnt lgkmcnt(8)
	s_waitcnt vmcnt(10)
	s_barrier
	s_waitcnt lgkmcnt(0)
	s_setprio 1
	s_waitcnt lgkmcnt(0)
	v_mfma_f32_16x16x32_bf16 v[124:127], v[140:143], v[166:169], v[124:127]
	v_mfma_f32_16x16x32_bf16 v[120:123], v[158:161], v[166:169], v[120:123]
	v_mfma_f32_16x16x32_bf16 v[108:111], v[140:143], v[174:177], v[108:111]
	v_mfma_f32_16x16x32_bf16 v[104:107], v[158:161], v[174:177], v[104:107]
	v_mfma_f32_16x16x32_bf16 v[92:95], v[140:143], v[182:185], v[92:95]
	v_mfma_f32_16x16x32_bf16 v[88:91], v[158:161], v[182:185], v[88:91]
	v_mfma_f32_16x16x32_bf16 v[76:79], v[140:143], v[190:193], v[76:79]
	v_mfma_f32_16x16x32_bf16 v[72:75], v[158:161], v[190:193], v[72:75]
	v_mfma_f32_16x16x32_bf16 v[124:127], v[154:157], v[170:173], v[124:127]
	v_mfma_f32_16x16x32_bf16 v[120:123], v[162:165], v[170:173], v[120:123]
	v_mfma_f32_16x16x32_bf16 v[108:111], v[154:157], v[178:181], v[108:111]
	v_mfma_f32_16x16x32_bf16 v[104:107], v[162:165], v[178:181], v[104:107]
	v_mfma_f32_16x16x32_bf16 v[92:95], v[154:157], v[186:189], v[92:95]
	v_mfma_f32_16x16x32_bf16 v[88:91], v[162:165], v[186:189], v[88:91]
	v_mfma_f32_16x16x32_bf16 v[76:79], v[154:157], v[194:197], v[76:79]
	v_mfma_f32_16x16x32_bf16 v[72:75], v[162:165], v[194:197], v[72:75]
	s_setprio 0
	s_barrier
	s_add_i32 s62, s47, s31
	s_mov_b32 m0, s62
	ds_read_b128 v[202:205], v151
	ds_read_b128 v[206:209], v151 offset:1024
	ds_read_b128 v[210:213], v151 offset:2048
	ds_read_b128 v[214:217], v151 offset:3072
	global_load_lds_dwordx4 v130, s[4:5]
	s_add_i32 m0, s62, 0x2000
	s_nop 0
	global_load_lds_dwordx4 v134, s[4:5]
	s_waitcnt vmcnt(10)
	s_barrier
; #define PG8_STAGE(bufoff, gbase, voff) do { _Pragma("unroll") for (int _i = 0; _i < 2; ++_i) \
;         __builtin_amdgcn_global_load_lds((const unsigned*)((const char*)(gbase) + (voff)[_i]), (LAS unsigned*)(lds + (bufoff) + ldsw + _i * 8192), 16, 0, 0); } while (0)
; #define PG8_LDA(dst, b, h) do { _Pragma("unroll") for (int m = 0; m < 4; ++m) _Pragma("unroll") for (int k = 0; k < 2; ++k) dst[m][k] = *(const LAS bf16x8*)(lds + PG8_SA(b, h) + aoff + m * 2048 + k * 1024); } while (0)
; #define PG8_LDB(dst, b, h) do { _Pragma("unroll") for (int n = 0; n < 2; ++n) _Pragma("unroll") for (int k = 0; k < 2; ++k) dst[n][k] = *(const LAS bf16x8*)(lds + PG8_SB(b, h) + boff + n * 2048 + k * 1024); } while (0)
; #define PG8_WAIT_V(n) asm volatile("s_waitcnt vmcnt(" #n ")" ::: "memory")
; #define PG8_WAIT_L(n) asm volatile("s_waitcnt lgkmcnt(" #n ")" ::: "memory")
; #define PG8_BAR __builtin_amdgcn_s_barrier()
; #define PG8_SCHED __builtin_amdgcn_sched_barrier(0)
; template <class Epi, class Sched>
; __device__ __forceinline__ void gemm_phase(LAS unsigned char* lds, const Gemm g, const Sched& S, const Epi& E) {
;     ...
;             PG8_LDB(B0, 0, 0); PG8_SCHED; PG8_LDA(At, 0, 0); PG8_STAGE(PG8_SA(1, 1), a1 + hstep, voffA);
;             PG8_WAIT_L(8); PG8_BAR; PG8_WAIT_L(0); PG8_MMA(0, 0, At, B0); PG8_BAR; PG8_SCHED;
;             PG8_LDB(B1, 0, 1); PG8_STAGE(PG8_SB(0, 0), b2, voffB);
;             PG8_BAR; PG8_WAIT_L(0); PG8_MMA(0, 1, At, B1); PG8_BAR;
;             PG8_LDA(At, 0, 1); PG8_STAGE(PG8_SA(0, 0), a2, voffA);
;             PG8_BAR; PG8_WAIT_L(0); PG8_MMA(1, 0, At, B0); PG8_BAR; PG8_SCHED;
;             PG8_STAGE(PG8_SB(0, 1), b2 + hstep, voffB);
;             PG8_WAIT_V(6); PG8_BAR; PG8_MMA(1, 1, At, B1); PG8_BAR;
;             PG8_LDB(B0, 1, 0); PG8_SCHED; PG8_LDA(At, 1, 0); PG8_STAGE(PG8_SA(0, 1), a2 + hstep, voffA);
;             PG8_WAIT_L(8); PG8_BAR; PG8_WAIT_L(0); PG8_MMA(0, 0, At, B0); PG8_BAR; PG8_SCHED;
;             PG8_LDB(B1, 1, 1); PG8_STAGE(PG8_SB(1, 0), b3, voffB);
;             PG8_BAR; PG8_WAIT_L(0); PG8_MMA(0, 1, At, B1); PG8_BAR;
;             PG8_LDA(At, 1, 1); PG8_STAGE(PG8_SA(1, 0), a3, voffA);
;             PG8_BAR; PG8_WAIT_L(0); PG8_MMA(1, 0, At, B0); PG8_BAR; PG8_SCHED;
;             PG8_STAGE(PG8_SB(1, 1), b3 + hstep, voffB);
;             PG8_WAIT_V(6); PG8_BAR; PG8_MMA(1, 1, At, B1); PG8_BAR;
	s_waitcnt lgkmcnt(0)
	s_setprio 1
	s_waitcnt lgkmcnt(0)
	v_mfma_f32_16x16x32_bf16 v[116:119], v[202:205], v[166:169], v[116:119]
	v_mfma_f32_16x16x32_bf16 v[112:115], v[210:213], v[166:169], v[112:115]
	v_mfma_f32_16x16x32_bf16 v[100:103], v[202:205], v[174:177], v[100:103]
	v_mfma_f32_16x16x32_bf16 v[96:99], v[210:213], v[174:177], v[96:99]
	v_mfma_f32_16x16x32_bf16 v[84:87], v[202:205], v[182:185], v[84:87]
	v_mfma_f32_16x16x32_bf16 v[80:83], v[210:213], v[182:185], v[80:83]
	v_mfma_f32_16x16x32_bf16 v[68:71], v[202:205], v[190:193], v[68:71]
	v_mfma_f32_16x16x32_bf16 v[64:67], v[210:213], v[190:193], v[64:67]
	v_mfma_f32_16x16x32_bf16 v[116:119], v[206:209], v[170:173], v[116:119]
	v_mfma_f32_16x16x32_bf16 v[112:115], v[214:217], v[170:173], v[112:115]
	v_mfma_f32_16x16x32_bf16 v[100:103], v[206:209], v[178:181], v[100:103]
	v_mfma_f32_16x16x32_bf16 v[96:99], v[214:217], v[178:181], v[96:99]
	v_mfma_f32_16x16x32_bf16 v[84:87], v[206:209], v[186:189], v[84:87]
	v_mfma_f32_16x16x32_bf16 v[80:83], v[214:217], v[186:189], v[80:83]
	v_mfma_f32_16x16x32_bf16 v[68:71], v[206:209], v[194:197], v[68:71]
	v_mfma_f32_16x16x32_bf16 v[64:67], v[214:217], v[194:197], v[64:67]
	s_setprio 0
	s_mov_b32 m0, s33
	v_lshl_add_u64 v[218:219], s[24:25], 0, v[128:129]
	s_barrier
	ds_read_b128 v[166:169], v150 offset:16384
	ds_read_b128 v[170:173], v150 offset:17408
	ds_read_b128 v[174:177], v150 offset:18432
	ds_read_b128 v[178:181], v150 offset:19456
	ds_read_b128 v[182:185], v150 offset:20480
	ds_read_b128 v[186:189], v150 offset:21504
	ds_read_b128 v[190:193], v150 offset:22528
	ds_read_b128 v[194:197], v150 offset:23552
	global_load_lds_dwordx4 v128, s[24:25]
	v_lshl_add_u64 v[220:221], s[24:25], 0, v[132:133]
	s_mov_b32 m0, s34
	s_nop 0
	global_load_lds_dwordx4 v132, s[24:25]
	s_barrier
	s_waitcnt lgkmcnt(0)
	s_setprio 1
	s_waitcnt lgkmcnt(0)
	v_mfma_f32_16x16x32_bf16 v[60:63], v[140:143], v[166:169], v[60:63]
	v_mfma_f32_16x16x32_bf16 v[56:59], v[158:161], v[166:169], v[56:59]
	v_mfma_f32_16x16x32_bf16 v[44:47], v[140:143], v[174:177], v[44:47]
	v_mfma_f32_16x16x32_bf16 v[40:43], v[158:161], v[174:177], v[40:43]
	v_mfma_f32_16x16x32_bf16 v[28:31], v[140:143], v[182:185], v[28:31]
	v_mfma_f32_16x16x32_bf16 v[24:27], v[158:161], v[182:185], v[24:27]
	v_mfma_f32_16x16x32_bf16 v[12:15], v[140:143], v[190:193], v[12:15]
	v_mfma_f32_16x16x32_bf16 v[8:11], v[158:161], v[190:193], v[8:11]
	v_mfma_f32_16x16x32_bf16 v[60:63], v[154:157], v[170:173], v[60:63]
	v_mfma_f32_16x16x32_bf16 v[56:59], v[162:165], v[170:173], v[56:59]
	v_mfma_f32_16x16x32_bf16 v[44:47], v[154:157], v[178:181], v[44:47]
	v_mfma_f32_16x16x32_bf16 v[40:43], v[162:165], v[178:181], v[40:43]
	v_mfma_f32_16x16x32_bf16 v[28:31], v[154:157], v[186:189], v[28:31]
	v_mfma_f32_16x16x32_bf16 v[24:27], v[162:165], v[186:189], v[24:27]
	v_mfma_f32_16x16x32_bf16 v[12:15], v[154:157], v[194:197], v[12:15]
	v_mfma_f32_16x16x32_bf16 v[8:11], v[162:165], v[194:197], v[8:11]
	s_setprio 0
	s_barrier
	s_add_u32 s62, s4, 0x40000
	s_addc_u32 s63, s5, 0
	s_add_i32 s64, s48, s31
	s_mov_b32 m0, s64
	s_nop 0
	global_load_lds_dwordx4 v130, s[62:63]
	s_add_i32 m0, s64, 0x2000
	s_nop 0
	global_load_lds_dwordx4 v134, s[62:63]
	s_waitcnt vmcnt(10)
	s_barrier
	s_setprio 1
	v_mfma_f32_16x16x32_bf16 v[52:55], v[202:205], v[166:169], v[52:55]
	v_mfma_f32_16x16x32_bf16 v[48:51], v[210:213], v[166:169], v[48:51]
	v_mfma_f32_16x16x32_bf16 v[36:39], v[202:205], v[174:177], v[36:39]
	v_mfma_f32_16x16x32_bf16 v[32:35], v[210:213], v[174:177], v[32:35]
	v_mfma_f32_16x16x32_bf16 v[20:23], v[202:205], v[182:185], v[20:23]
	v_mfma_f32_16x16x32_bf16 v[16:19], v[210:213], v[182:185], v[16:19]
	v_mfma_f32_16x16x32_bf16 v[4:7], v[202:205], v[190:193], v[4:7]
	v_mfma_f32_16x16x32_bf16 v[0:3], v[210:213], v[190:193], v[0:3]
	v_mfma_f32_16x16x32_bf16 v[52:55], v[206:209], v[170:173], v[52:55]
	v_mfma_f32_16x16x32_bf16 v[48:51], v[214:217], v[170:173], v[48:51]
	v_mfma_f32_16x16x32_bf16 v[36:39], v[206:209], v[178:181], v[36:39]
	v_mfma_f32_16x16x32_bf16 v[32:35], v[214:217], v[178:181], v[32:35]
	v_mfma_f32_16x16x32_bf16 v[20:23], v[206:209], v[186:189], v[20:23]
	v_mfma_f32_16x16x32_bf16 v[16:19], v[214:217], v[186:189], v[16:19]
	v_mfma_f32_16x16x32_bf16 v[4:7], v[206:209], v[194:197], v[4:7]
	v_mfma_f32_16x16x32_bf16 v[0:3], v[214:217], v[194:197], v[0:3]
	s_setprio 0
	s_add_i32 s62, 0, 0x18000
	v_add_u32_e32 v162, s62, v148
	s_barrier
	ds_read_b128 v[140:143], v162
	ds_read_b128 v[154:157], v162 offset:1024
	ds_read_b128 v[158:161], v162 offset:2048
	ds_read_b128 v[162:165], v162 offset:3072
	s_add_u32 s24, s24, 0x40000
	s_addc_u32 s25, s25, 0
	s_mov_b32 m0, s35
	ds_read_b128 v[166:169], v150 offset:32768
	ds_read_b128 v[170:173], v150 offset:33792
	ds_read_b128 v[174:177], v150 offset:34816
	ds_read_b128 v[178:181], v150 offset:35840
	ds_read_b128 v[182:185], v150 offset:36864
	ds_read_b128 v[186:189], v150 offset:37888
	ds_read_b128 v[190:193], v150 offset:38912
	ds_read_b128 v[194:197], v150 offset:39936
	global_load_lds_dwordx4 v128, s[24:25]
	s_mov_b32 m0, s36
	s_nop 0
	global_load_lds_dwordx4 v132, s[24:25]
	s_waitcnt lgkmcnt(8)
	s_waitcnt vmcnt(10)
	s_barrier
; #define PG8_STAGE(bufoff, gbase, voff) do { _Pragma("unroll") for (int _i = 0; _i < 2; ++_i) \
;         __builtin_amdgcn_global_load_lds((const unsigned*)((const char*)(gbase) + (voff)[_i]), (LAS unsigned*)(lds + (bufoff) + ldsw + _i * 8192), 16, 0, 0); } while (0)
; #define PG8_LDA(dst, b, h) do { _Pragma("unroll") for (int m = 0; m < 4; ++m) _Pragma("unroll") for (int k = 0; k < 2; ++k) dst[m][k] = *(const LAS bf16x8*)(lds + PG8_SA(b, h) + aoff + m * 2048 + k * 1024); } while (0)
; #define PG8_LDB(dst, b, h) do { _Pragma("unroll") for (int n = 0; n < 2; ++n) _Pragma("unroll") for (int k = 0; k < 2; ++k) dst[n][k] = *(const LAS bf16x8*)(lds + PG8_SB(b, h) + boff + n * 2048 + k * 1024); } while (0)
; #define PG8_WAIT_V(n) asm volatile("s_waitcnt vmcnt(" #n ")" ::: "memory")
; #define PG8_WAIT_L(n) asm volatile("s_waitcnt lgkmcnt(" #n ")" ::: "memory")
; #define PG8_BAR __builtin_amdgcn_s_barrier()
; #define PG8_SCHED __builtin_amdgcn_sched_barrier(0)
; template <class Epi, class Sched>
; __device__ __forceinline__ void gemm_phase(LAS unsigned char* lds, const Gemm g, const Sched& S, const Epi& E) {
;     ...
;             PG8_LDB(B0, 0, 0); PG8_SCHED; PG8_LDA(At, 0, 0); PG8_STAGE(PG8_SA(1, 1), a1 + hstep, voffA);
;             PG8_WAIT_L(8); PG8_BAR; PG8_WAIT_L(0); PG8_MMA(0, 0, At, B0); PG8_BAR; PG8_SCHED;
;             PG8_LDB(B1, 0, 1); PG8_STAGE(PG8_SB(0, 0), b2, voffB);
;             PG8_BAR; PG8_WAIT_L(0); PG8_MMA(0, 1, At, B1); PG8_BAR;
;             PG8_LDA(At, 0, 1); PG8_STAGE(PG8_SA(0, 0), a2, voffA);
;             PG8_BAR; PG8_WAIT_L(0); PG8_MMA(1, 0, At, B0); PG8_BAR; PG8_SCHED;
;             PG8_STAGE(PG8_SB(0, 1), b2 + hstep, voffB);
;             PG8_WAIT_V(6); PG8_BAR; PG8_MMA(1, 1, At, B1); PG8_BAR;
;             PG8_LDB(B0, 1, 0); PG8_SCHED; PG8_LDA(At, 1, 0); PG8_STAGE(PG8_SA(0, 1), a2 + hstep, voffA);
;             PG8_WAIT_L(8); PG8_BAR; PG8_WAIT_L(0); PG8_MMA(0, 0, At, B0); PG8_BAR; PG8_SCHED;
;             PG8_LDB(B1, 1, 1); PG8_STAGE(PG8_SB(1, 0), b3, voffB);
;             PG8_BAR; PG8_WAIT_L(0); PG8_MMA(0, 1, At, B1); PG8_BAR;
;             PG8_LDA(At, 1, 1); PG8_STAGE(PG8_SA(1, 0), a3, voffA);
;             PG8_BAR; PG8_WAIT_L(0); PG8_MMA(1, 0, At, B0); PG8_BAR; PG8_SCHED;
;             PG8_STAGE(PG8_SB(1, 1), b3 + hstep, voffB);
;             PG8_WAIT_V(6); PG8_BAR; PG8_MMA(1, 1, At, B1); PG8_BAR;
	s_waitcnt lgkmcnt(0)
	s_setprio 1
	s_waitcnt lgkmcnt(0)
	v_mfma_f32_16x16x32_bf16 v[124:127], v[140:143], v[166:169], v[124:127]
	v_mfma_f32_16x16x32_bf16 v[120:123], v[158:161], v[166:169], v[120:123]
	v_mfma_f32_16x16x32_bf16 v[108:111], v[140:143], v[174:177], v[108:111]
	v_mfma_f32_16x16x32_bf16 v[104:107], v[158:161], v[174:177], v[104:107]
	v_mfma_f32_16x16x32_bf16 v[92:95], v[140:143], v[182:185], v[92:95]
	v_mfma_f32_16x16x32_bf16 v[88:91], v[158:161], v[182:185], v[88:91]
	v_mfma_f32_16x16x32_bf16 v[76:79], v[140:143], v[190:193], v[76:79]
	v_mfma_f32_16x16x32_bf16 v[72:75], v[158:161], v[190:193], v[72:75]
	v_mfma_f32_16x16x32_bf16 v[124:127], v[154:157], v[170:173], v[124:127]
	v_mfma_f32_16x16x32_bf16 v[120:123], v[162:165], v[170:173], v[120:123]
	v_mfma_f32_16x16x32_bf16 v[108:111], v[154:157], v[178:181], v[108:111]
	v_mfma_f32_16x16x32_bf16 v[104:107], v[162:165], v[178:181], v[104:107]
	v_mfma_f32_16x16x32_bf16 v[92:95], v[154:157], v[186:189], v[92:95]
	v_mfma_f32_16x16x32_bf16 v[88:91], v[162:165], v[186:189], v[88:91]
	v_mfma_f32_16x16x32_bf16 v[76:79], v[154:157], v[194:197], v[76:79]
	v_mfma_f32_16x16x32_bf16 v[72:75], v[162:165], v[194:197], v[72:75]
	s_setprio 0
	s_barrier
	s_add_i32 s24, 0, 0x1c000
	s_add_i32 s25, s62, s31
	v_add_u32_e32 v214, s24, v148
	s_add_u32 s0, s4, 0x80
	s_addc_u32 s1, s5, 0
	s_mov_b32 m0, s25
	ds_read_b128 v[202:205], v214
	ds_read_b128 v[206:209], v214 offset:1024
	ds_read_b128 v[210:213], v214 offset:2048
	ds_read_b128 v[214:217], v214 offset:3072
	global_load_lds_dwordx4 v130, s[0:1]
	s_add_i32 m0, s25, 0x2000
	s_nop 0
	global_load_lds_dwordx4 v134, s[0:1]
	s_waitcnt vmcnt(10)
	s_barrier
	s_waitcnt lgkmcnt(0)
	s_setprio 1
	s_waitcnt lgkmcnt(0)
	v_mfma_f32_16x16x32_bf16 v[116:119], v[202:205], v[166:169], v[116:119]
	v_mfma_f32_16x16x32_bf16 v[112:115], v[210:213], v[166:169], v[112:115]
	v_mfma_f32_16x16x32_bf16 v[100:103], v[202:205], v[174:177], v[100:103]
	v_mfma_f32_16x16x32_bf16 v[96:99], v[210:213], v[174:177], v[96:99]
	v_mfma_f32_16x16x32_bf16 v[84:87], v[202:205], v[182:185], v[84:87]
	v_mfma_f32_16x16x32_bf16 v[80:83], v[210:213], v[182:185], v[80:83]
	v_mfma_f32_16x16x32_bf16 v[68:71], v[202:205], v[190:193], v[68:71]
	v_mfma_f32_16x16x32_bf16 v[64:67], v[210:213], v[190:193], v[64:67]
	v_mfma_f32_16x16x32_bf16 v[116:119], v[206:209], v[170:173], v[116:119]
	v_mfma_f32_16x16x32_bf16 v[112:115], v[214:217], v[170:173], v[112:115]
	v_mfma_f32_16x16x32_bf16 v[100:103], v[206:209], v[178:181], v[100:103]
	v_mfma_f32_16x16x32_bf16 v[96:99], v[214:217], v[178:181], v[96:99]
	v_mfma_f32_16x16x32_bf16 v[84:87], v[206:209], v[186:189], v[84:87]
	v_mfma_f32_16x16x32_bf16 v[80:83], v[214:217], v[186:189], v[80:83]
	v_mfma_f32_16x16x32_bf16 v[68:71], v[206:209], v[194:197], v[68:71]
	v_mfma_f32_16x16x32_bf16 v[64:67], v[214:217], v[194:197], v[64:67]
	s_setprio 0
	s_mov_b32 m0, s44
	s_mov_b64 s[0:1], 0x80
	v_lshl_add_u64 v[144:145], v[218:219], 0, s[0:1]
	s_barrier
	ds_read_b128 v[166:169], v150 offset:49152
	ds_read_b128 v[170:173], v150 offset:50176
	ds_read_b128 v[174:177], v150 offset:51200
	ds_read_b128 v[178:181], v150 offset:52224
	ds_read_b128 v[182:185], v150 offset:53248
	ds_read_b128 v[186:189], v150 offset:54272
	ds_read_b128 v[190:193], v150 offset:55296
	ds_read_b128 v[194:197], v150 offset:56320
	global_load_lds_dwordx4 v[144:145], off
	v_lshl_add_u64 v[144:145], v[220:221], 0, s[0:1]
	s_mov_b32 m0, s45
	s_nop 0
	global_load_lds_dwordx4 v[144:145], off
	s_barrier
	s_waitcnt lgkmcnt(0)
	s_setprio 1
	s_waitcnt lgkmcnt(0)
	v_mfma_f32_16x16x32_bf16 v[60:63], v[140:143], v[166:169], v[60:63]
	v_mfma_f32_16x16x32_bf16 v[56:59], v[158:161], v[166:169], v[56:59]
	v_mfma_f32_16x16x32_bf16 v[44:47], v[140:143], v[174:177], v[44:47]
	v_mfma_f32_16x16x32_bf16 v[40:43], v[158:161], v[174:177], v[40:43]
	v_mfma_f32_16x16x32_bf16 v[28:31], v[140:143], v[182:185], v[28:31]
	v_mfma_f32_16x16x32_bf16 v[24:27], v[158:161], v[182:185], v[24:27]
	v_mfma_f32_16x16x32_bf16 v[12:15], v[140:143], v[190:193], v[12:15]
	v_mfma_f32_16x16x32_bf16 v[8:11], v[158:161], v[190:193], v[8:11]
	v_mfma_f32_16x16x32_bf16 v[60:63], v[154:157], v[170:173], v[60:63]
	v_mfma_f32_16x16x32_bf16 v[56:59], v[162:165], v[170:173], v[56:59]
	v_mfma_f32_16x16x32_bf16 v[44:47], v[154:157], v[178:181], v[44:47]
	v_mfma_f32_16x16x32_bf16 v[40:43], v[162:165], v[178:181], v[40:43]
	v_mfma_f32_16x16x32_bf16 v[28:31], v[154:157], v[186:189], v[28:31]
	v_mfma_f32_16x16x32_bf16 v[24:27], v[162:165], v[186:189], v[24:27]
	v_mfma_f32_16x16x32_bf16 v[12:15], v[154:157], v[194:197], v[12:15]
	v_mfma_f32_16x16x32_bf16 v[8:11], v[162:165], v[194:197], v[8:11]
	s_setprio 0
	s_barrier
	s_add_u32 s4, s4, 0x40080
	s_addc_u32 s5, s5, 0
	s_add_i32 s24, s24, s31
	s_mov_b32 m0, s24
	s_nop 0
	global_load_lds_dwordx4 v130, s[4:5]
	s_add_i32 m0, s24, 0x2000
	s_nop 0
	global_load_lds_dwordx4 v134, s[4:5]
	s_waitcnt vmcnt(10)
	s_barrier
	s_setprio 1
	v_mfma_f32_16x16x32_bf16 v[52:55], v[202:205], v[166:169], v[52:55]
	v_mfma_f32_16x16x32_bf16 v[48:51], v[210:213], v[166:169], v[48:51]
	v_mfma_f32_16x16x32_bf16 v[36:39], v[202:205], v[174:177], v[36:39]
	v_mfma_f32_16x16x32_bf16 v[32:35], v[210:213], v[174:177], v[32:35]
	v_mfma_f32_16x16x32_bf16 v[20:23], v[202:205], v[182:185], v[20:23]
	v_mfma_f32_16x16x32_bf16 v[16:19], v[210:213], v[182:185], v[16:19]
	v_mfma_f32_16x16x32_bf16 v[4:7], v[202:205], v[190:193], v[4:7]
	v_mfma_f32_16x16x32_bf16 v[0:3], v[210:213], v[190:193], v[0:3]
	v_mfma_f32_16x16x32_bf16 v[52:55], v[206:209], v[170:173], v[52:55]
	v_mfma_f32_16x16x32_bf16 v[48:51], v[214:217], v[170:173], v[48:51]
	v_mfma_f32_16x16x32_bf16 v[36:39], v[206:209], v[178:181], v[36:39]
	v_mfma_f32_16x16x32_bf16 v[32:35], v[214:217], v[178:181], v[32:35]
	v_mfma_f32_16x16x32_bf16 v[20:23], v[206:209], v[186:189], v[20:23]
	v_mfma_f32_16x16x32_bf16 v[16:19], v[214:217], v[186:189], v[16:19]
	v_mfma_f32_16x16x32_bf16 v[4:7], v[206:209], v[194:197], v[4:7]
	v_mfma_f32_16x16x32_bf16 v[0:3], v[214:217], v[194:197], v[0:3]
	s_setprio 0
	s_add_i32 s61, s61, 2
	s_add_u32 s2, s2, 0x100
	s_addc_u32 s3, s3, 0
	s_add_u32 s59, s59, 0x100
	s_addc_u32 s60, s60, 0
	s_cmp_gt_u32 s61, 13
	s_barrier
;     __device__ __forceinline__ void operator()(const AccT& acc, const Unit& u, int wr, int wc, int fr, int fq) const {
;     ...
;         const int j = fr & 3; const float sgn = ((fr >> 2) & 1) ? 1.0f : -1.0f;
; #pragma unroll
;         for (int ai = 0; ai < 2; ++ai) {
;             const int hh = 2 * ai + wr;
;             const float l2f = lgd[hh] * 1.4426950408889634f, l2b = lgd[4 + hh] * 1.4426950408889634f;
;             const float zf0 = exp2f((float)(127 - o0) * l2f), zfs = exp2f(-l2f), zb0 = exp2f((float)o0 * l2b), zbs = exp2f(l2b);
; #pragma unroll
;             for (int m = 0; m < 4; ++m) {
;                 const int r = rbase + ai * 128 + m * 16;
;                 const int d = 4 * (2 * m + (fr >> 3)) + j;
; #pragma unroll
;                 for (int bj = 0; bj < 2; ++bj) {
;                     const int t0 = tb + bj * 128;
;                     float v[8];
; #pragma unroll
;                     for (int jj = 0; jj < 4; ++jj) { v[jj] = acc[ai][bj][m][0][jj]; v[4 + jj] = acc[ai][bj][m][1][jj]; }
;                     if constexpr (ROPE) {
;                         const int t = t0 & 2047;
; #pragma unroll
;                         for (int hf = 0; hf < 2; ++hf) {
;                             f32x4 cs, sn;
;                             if (m < 2) { const float c1 = ropeA[(t >> 6) * 16 + d], s1 = ropeA[1024 + (t >> 6) * 16 + d]; cs = (f32x4){c1, c1, c1, c1}; sn = (f32x4){s1, s1, s1, s1}; }
;                             else { const float* cb = ropeA + 2048 + (d - 16) * 64 + (t & 63) + 4 * hf; cs = *(const f32x4*)(cb); sn = *(const f32x4*)(cb + 1024); }
; #pragma unroll
;                             for (int jj = 0; jj < 4; ++jj) { const float pr = __shfl_xor(v[4 * hf + jj], 4); v[4 * hf + jj] = v[4 * hf + jj] * cs[jj] + sgn * pr * sn[jj]; }
;                             __builtin_amdgcn_sched_barrier(0);
;                         }
;                     }
;                     float zf[8], zb[8]; zf[0] = zf0; zb[0] = zb0;
; #pragma unroll
;                     for (int jj = 1; jj < 8; ++jj) { zf[jj] = zf[jj - 1] * zfs; zb[jj] = zb[jj - 1] * zbs; }
;                     u32x4 wf, wb;
;                     wf.x = cvt_pk_bf16(v[0] * zf[0], v[1] * zf[1]); wf.y = cvt_pk_bf16(v[2] * zf[2], v[3] * zf[3]); wf.z = cvt_pk_bf16(v[4] * zf[4], v[5] * zf[5]); wf.w = cvt_pk_bf16(v[6] * zf[6], v[7] * zf[7]);
	s_cbranch_scc0 .LBB0_693
	v_mov_b32_e32 v141, v147
	v_mov_b32_e32 v140, v146
	global_load_dword v156, v131, s[6:7]
	global_load_dword v157, v131, s[6:7] offset:16
	s_lshl_b32 s2, s56, 8
	s_or_b32 s2, s2, s43
	v_add_u32_e32 v140, s42, v140
	v_lshlrev_b32_e32 v141, 3, v141
	v_add_u32_e32 v142, s2, v141
	v_add_u32_e32 v143, s43, v141
	v_ashrrev_i32_e32 v141, 31, v140
	v_sub_u32_e32 v144, 0x7f, v143
	v_lshlrev_b64 v[140:141], 14, v[140:141]
	v_cvt_f32_i32_e32 v154, v143
	v_ashrrev_i32_e32 v143, 31, v142
	v_cvt_f32_i32_e32 v155, v144
	v_lshl_add_u64 v[140:141], s[70:71], 0, v[140:141]
	s_mov_b32 s3, 0x400000
	v_lshl_add_u64 v[140:141], v[142:143], 1, v[140:141]
	v_add_co_u32_e32 v144, vcc, s3, v140
	s_mov_b64 s[4:5], 0x400000
	s_nop 0
	v_addc_co_u32_e32 v145, vcc, 0, v141, vcc
	v_lshl_add_u64 v[142:143], v[140:141], 0, s[4:5]
	s_waitcnt vmcnt(0)
	v_mul_f32_e32 v158, 0x3fb8aa3b, v156
	v_mul_f32_e32 v159, 0x3fb8aa3b, v157
	v_mul_f32_e32 v160, v158, v155
	v_cmp_lt_f32_e32 vcc, s51, v158
	v_mul_f32_e32 v162, v159, v154
	v_cmp_gt_f32_e64 s[2:3], s49, v159
	v_cndmask_b32_e32 v161, 0, v153, vcc
	v_cmp_gt_f32_e64 s[4:5], s49, v160
	v_cndmask_b32_e64 v163, 0, v153, s[2:3]
	s_and_b64 s[24:25], vcc, exec
	v_cmp_gt_f32_e32 vcc, s49, v162
	v_fmac_f32_e32 v163, 0x3fb8aa3b, v157
	v_cndmask_b32_e64 v157, 0, v153, s[4:5]
	v_cndmask_b32_e32 v162, 0, v153, vcc
	v_fmac_f32_e32 v161, 0xbfb8aa3b, v156
	v_fmac_f32_e32 v157, v158, v155
	v_fmac_f32_e32 v162, v159, v154
	v_exp_f32_e32 v161, v161
	v_exp_f32_e32 v163, v163
	v_exp_f32_e32 v157, v157
	v_exp_f32_e32 v158, v162
	v_cndmask_b32_e64 v160, 0, v152, s[4:5]
	s_cselect_b32 s4, 0xffffffc0, 0
	s_and_b64 s[2:3], s[2:3], exec
	v_cndmask_b32_e32 v156, 0, v152, vcc
	s_cselect_b32 s2, 0xffffffc0, 0
	v_ldexp_f32 v161, v161, s4
	v_ldexp_f32 v162, v163, s2
	v_ldexp_f32 v163, v157, v160
	v_ldexp_f32 v156, v158, v156
	v_mul_f32_e32 v164, v161, v163
	v_mul_f32_e32 v157, v162, v156
	v_mul_f32_e32 v158, v124, v163
	v_mul_f32_e32 v165, v124, v156
	v_mul_f32_e32 v166, v161, v164
	v_mul_f32_e32 v124, v162, v157
	v_mul_f32_e32 v159, v125, v164
	v_mul_f32_e32 v167, v125, v157
	v_mul_f32_e32 v168, v161, v166
	v_mul_f32_e32 v125, v162, v124
	v_cvt_pk_bf16_f32 v158, v158, v159
	v_mul_f32_e32 v159, v126, v166
	v_mul_f32_e32 v169, v126, v124
	v_mul_f32_e32 v170, v161, v168
	v_mul_f32_e32 v126, v162, v125
	v_mul_f32_e32 v171, v161, v170
	v_mul_f32_e32 v172, v162, v126
	v_mul_f32_e32 v160, v127, v168
	v_mul_f32_e32 v174, v161, v171
	v_mul_f32_e32 v175, v162, v172
	v_cvt_pk_bf16_f32 v159, v159, v160
	v_mul_f32_e32 v160, v120, v170
	v_mul_f32_e32 v173, v120, v126
	v_mul_f32_e32 v120, v121, v171
	v_mul_f32_e32 v177, v161, v174
	v_mul_f32_e32 v162, v162, v175
	v_mul_f32_e32 v176, v121, v172
	v_cvt_pk_bf16_f32 v160, v160, v120
	v_mul_f32_e32 v120, v122, v174
	v_mul_f32_e32 v121, v123, v177
	v_mul_f32_e32 v123, v123, v162
	v_cvt_pk_bf16_f32 v161, v120, v121
	v_mul_f32_e32 v127, v127, v125
	v_mul_f32_e32 v178, v122, v175
	v_cvt_pk_bf16_f32 v120, v165, v167
	v_cvt_pk_bf16_f32 v121, v169, v127
	v_cvt_pk_bf16_f32 v122, v173, v176
	v_cvt_pk_bf16_f32 v123, v178, v123
	global_store_dwordx4 v[140:141], v[158:161], off
	global_store_dwordx4 v[144:145], v[120:123], off
	s_nop 1
	v_mul_f32_e32 v120, v116, v163
	v_mul_f32_e32 v121, v117, v164
	v_cvt_pk_bf16_f32 v120, v120, v121
	v_mul_f32_e32 v121, v118, v166
	v_mul_f32_e32 v122, v119, v168
	v_cvt_pk_bf16_f32 v121, v121, v122
	v_mul_f32_e32 v122, v112, v170
	v_mul_f32_e32 v123, v113, v171
	v_cvt_pk_bf16_f32 v122, v122, v123
	v_mul_f32_e32 v123, v114, v174
	v_mul_f32_e32 v116, v116, v156
	v_mul_f32_e32 v117, v117, v157
	v_mul_f32_e32 v127, v115, v177
	v_cvt_pk_bf16_f32 v123, v123, v127
	v_cvt_pk_bf16_f32 v116, v116, v117
	v_mul_f32_e32 v117, v118, v124
	v_mul_f32_e32 v118, v119, v125
	v_mul_f32_e32 v112, v112, v126
	v_mul_f32_e32 v113, v113, v172
	v_cvt_pk_bf16_f32 v117, v117, v118
	v_cvt_pk_bf16_f32 v118, v112, v113
	v_mul_f32_e32 v112, v114, v175
	v_mul_f32_e32 v113, v115, v162
	v_cvt_pk_bf16_f32 v119, v112, v113
	global_store_dwordx4 v[140:141], v[120:123], off offset:256
	global_store_dwordx4 v[142:143], v[116:119], off offset:256
	v_mul_f32_e32 v112, v108, v163
	v_mul_f32_e32 v113, v109, v164
	v_cvt_pk_bf16_f32 v112, v112, v113
	v_mul_f32_e32 v113, v110, v166
	v_mul_f32_e32 v114, v111, v168
	v_cvt_pk_bf16_f32 v113, v113, v114
	v_mul_f32_e32 v114, v104, v170
	v_mul_f32_e32 v115, v105, v171
	v_cvt_pk_bf16_f32 v114, v114, v115
	v_mul_f32_e32 v115, v106, v174
	v_mul_f32_e32 v108, v108, v156
	v_mul_f32_e32 v109, v109, v157
	v_mul_f32_e32 v116, v107, v177
	v_cvt_pk_bf16_f32 v115, v115, v116
	v_cvt_pk_bf16_f32 v108, v108, v109
	v_mul_f32_e32 v109, v110, v124
	v_mul_f32_e32 v110, v111, v125
	v_mul_f32_e32 v104, v104, v126
	s_mov_b64 s[2:3], 0x40000
	v_cvt_pk_bf16_f32 v109, v109, v110
	v_mul_f32_e32 v105, v105, v172
	v_cvt_pk_bf16_f32 v110, v104, v105
	v_mul_f32_e32 v104, v106, v175
	v_lshl_add_u64 v[116:117], v[140:141], 0, s[2:3]
	s_mov_b32 s2, 0x40000
	v_mul_f32_e32 v105, v107, v162
	v_cvt_pk_bf16_f32 v111, v104, v105
	v_add_co_u32_e32 v104, vcc, s2, v140
	s_mov_b64 s[2:3], 0x440000
	s_nop 0
	v_addc_co_u32_e32 v105, vcc, 0, v141, vcc
	global_store_dwordx4 v[104:105], v[112:115], off
	s_nop 1
	v_lshl_add_u64 v[112:113], v[140:141], 0, s[2:3]
	s_mov_b32 s2, 0x440000
	v_add_co_u32_e32 v104, vcc, s2, v140
	s_nop 1
	v_addc_co_u32_e32 v105, vcc, 0, v141, vcc
	global_store_dwordx4 v[104:105], v[108:111], off
	v_mul_f32_e32 v104, v100, v163
	v_mul_f32_e32 v105, v101, v164
	v_cvt_pk_bf16_f32 v104, v104, v105
	v_mul_f32_e32 v105, v102, v166
	v_mul_f32_e32 v106, v103, v168
	v_cvt_pk_bf16_f32 v105, v105, v106
; __device__ __forceinline__ unsigned cvt_pk_bf16(float lo, float hi) { unsigned r; asm volatile("v_cvt_pk_bf16_f32 %0, %1, %2" : "=v"(r) : "v"(lo), "v"(hi)); return r; }
;     __device__ __forceinline__ void operator()(const AccT& acc, const Unit& u, int wr, int wc, int fr, int fq) const {
;     ...
;                     float zf[8], zb[8]; zf[0] = zf0; zb[0] = zb0;
; #pragma unroll
;                     for (int jj = 1; jj < 8; ++jj) { zf[jj] = zf[jj - 1] * zfs; zb[jj] = zb[jj - 1] * zbs; }
;                     u32x4 wf, wb;
;                     wf.x = cvt_pk_bf16(v[0] * zf[0], v[1] * zf[1]); wf.y = cvt_pk_bf16(v[2] * zf[2], v[3] * zf[3]); wf.z = cvt_pk_bf16(v[4] * zf[4], v[5] * zf[5]); wf.w = cvt_pk_bf16(v[6] * zf[6], v[7] * zf[7]);
;                     wb.x = cvt_pk_bf16(v[0] * zb[0], v[1] * zb[1]); wb.y = cvt_pk_bf16(v[2] * zb[2], v[3] * zb[3]); wb.z = cvt_pk_bf16(v[4] * zb[4], v[5] * zb[5]); wb.w = cvt_pk_bf16(v[6] * zb[6], v[7] * zb[7]);
;                     *(u32x4*)(KTZ + (size_t)r * NT + t0) = wf;
;                     *(u32x4*)(KTZ + (size_t)(256 + r) * NT + t0) = wb;
	v_mul_f32_e32 v106, v96, v170
	v_mul_f32_e32 v107, v97, v171
	v_cvt_pk_bf16_f32 v106, v106, v107
	v_mul_f32_e32 v107, v98, v174
	v_mul_f32_e32 v100, v100, v156
	v_mul_f32_e32 v101, v101, v157
	v_mul_f32_e32 v108, v99, v177
	v_cvt_pk_bf16_f32 v107, v107, v108
	v_cvt_pk_bf16_f32 v100, v100, v101
	v_mul_f32_e32 v101, v102, v124
	v_mul_f32_e32 v102, v103, v125
	v_mul_f32_e32 v96, v96, v126
	v_mul_f32_e32 v97, v97, v172
	v_cvt_pk_bf16_f32 v101, v101, v102
	v_cvt_pk_bf16_f32 v102, v96, v97
	v_mul_f32_e32 v96, v98, v175
	v_mul_f32_e32 v97, v99, v162
	v_cvt_pk_bf16_f32 v103, v96, v97
	global_store_dwordx4 v[116:117], v[104:107], off offset:256
	global_store_dwordx4 v[112:113], v[100:103], off offset:256
	v_mul_f32_e32 v96, v92, v163
	v_mul_f32_e32 v97, v93, v164
	v_cvt_pk_bf16_f32 v96, v96, v97
	v_mul_f32_e32 v97, v94, v166
	v_mul_f32_e32 v98, v95, v168
	v_cvt_pk_bf16_f32 v97, v97, v98
	v_mul_f32_e32 v98, v88, v170
	v_mul_f32_e32 v99, v89, v171
	v_cvt_pk_bf16_f32 v98, v98, v99
	v_mul_f32_e32 v99, v90, v174
	v_mul_f32_e32 v92, v92, v156
	v_mul_f32_e32 v93, v93, v157
	v_mul_f32_e32 v100, v91, v177
	v_cvt_pk_bf16_f32 v99, v99, v100
	v_cvt_pk_bf16_f32 v92, v92, v93
	v_mul_f32_e32 v93, v94, v124
	v_mul_f32_e32 v94, v95, v125
	v_mul_f32_e32 v88, v88, v126
	s_mov_b64 s[2:3], 0x80000
	v_cvt_pk_bf16_f32 v93, v93, v94
	v_mul_f32_e32 v89, v89, v172
	v_cvt_pk_bf16_f32 v94, v88, v89
	v_mul_f32_e32 v88, v90, v175
	v_lshl_add_u64 v[100:101], v[140:141], 0, s[2:3]
	s_mov_b32 s2, 0x80000
	v_mul_f32_e32 v89, v91, v162
	v_cvt_pk_bf16_f32 v95, v88, v89
	v_add_co_u32_e32 v88, vcc, s2, v140
	s_mov_b64 s[2:3], 0x480000
	s_nop 0
	v_addc_co_u32_e32 v89, vcc, 0, v141, vcc
	global_store_dwordx4 v[88:89], v[96:99], off
	s_nop 1
	v_lshl_add_u64 v[96:97], v[140:141], 0, s[2:3]
	s_mov_b32 s2, 0x480000
	v_add_co_u32_e32 v88, vcc, s2, v140
	s_nop 1
	v_addc_co_u32_e32 v89, vcc, 0, v141, vcc
	global_store_dwordx4 v[88:89], v[92:95], off
	v_mul_f32_e32 v88, v84, v163
	v_mul_f32_e32 v89, v85, v164
	v_cvt_pk_bf16_f32 v88, v88, v89
	v_mul_f32_e32 v89, v86, v166
	v_mul_f32_e32 v90, v87, v168
	v_cvt_pk_bf16_f32 v89, v89, v90
	v_mul_f32_e32 v90, v80, v170
	v_mul_f32_e32 v91, v81, v171
	v_cvt_pk_bf16_f32 v90, v90, v91
	v_mul_f32_e32 v91, v82, v174
	v_mul_f32_e32 v84, v84, v156
	v_mul_f32_e32 v85, v85, v157
	v_mul_f32_e32 v92, v83, v177
	v_cvt_pk_bf16_f32 v91, v91, v92
	v_cvt_pk_bf16_f32 v84, v84, v85
	v_mul_f32_e32 v85, v86, v124
	v_mul_f32_e32 v86, v87, v125
	v_mul_f32_e32 v80, v80, v126
	v_mul_f32_e32 v81, v81, v172
	v_cvt_pk_bf16_f32 v85, v85, v86
	v_cvt_pk_bf16_f32 v86, v80, v81
	v_mul_f32_e32 v80, v82, v175
	v_mul_f32_e32 v81, v83, v162
	v_cvt_pk_bf16_f32 v87, v80, v81
	global_store_dwordx4 v[100:101], v[88:91], off offset:256
	global_store_dwordx4 v[96:97], v[84:87], off offset:256
	v_mul_f32_e32 v80, v76, v163
	v_mul_f32_e32 v81, v77, v164
	v_cvt_pk_bf16_f32 v80, v80, v81
	v_mul_f32_e32 v81, v78, v166
	v_mul_f32_e32 v82, v79, v168
	v_cvt_pk_bf16_f32 v81, v81, v82
	v_mul_f32_e32 v82, v72, v170
	v_mul_f32_e32 v83, v73, v171
	v_cvt_pk_bf16_f32 v82, v82, v83
	v_mul_f32_e32 v83, v74, v174
	v_mul_f32_e32 v76, v76, v156
	v_mul_f32_e32 v77, v77, v157
	v_mul_f32_e32 v84, v75, v177
	v_cvt_pk_bf16_f32 v83, v83, v84
	v_cvt_pk_bf16_f32 v76, v76, v77
	v_mul_f32_e32 v77, v78, v124
	v_mul_f32_e32 v78, v79, v125
	v_mul_f32_e32 v72, v72, v126
	s_mov_b64 s[2:3], 0xc0000
	v_cvt_pk_bf16_f32 v77, v77, v78
	v_mul_f32_e32 v73, v73, v172
	v_cvt_pk_bf16_f32 v78, v72, v73
	v_mul_f32_e32 v72, v74, v175
	v_lshl_add_u64 v[84:85], v[140:141], 0, s[2:3]
	s_mov_b32 s2, 0xc0000
	v_mul_f32_e32 v73, v75, v162
	v_cvt_pk_bf16_f32 v79, v72, v73
	v_add_co_u32_e32 v72, vcc, s2, v140
	s_mov_b64 s[2:3], 0x4c0000
	s_nop 0
	v_addc_co_u32_e32 v73, vcc, 0, v141, vcc
	global_store_dwordx4 v[72:73], v[80:83], off
	s_nop 1
	v_lshl_add_u64 v[80:81], v[140:141], 0, s[2:3]
	s_mov_b32 s2, 0x4c0000
	v_add_co_u32_e32 v72, vcc, s2, v140
	s_nop 1
	v_addc_co_u32_e32 v73, vcc, 0, v141, vcc
	global_store_dwordx4 v[72:73], v[76:79], off
	v_mul_f32_e32 v72, v68, v163
	v_mul_f32_e32 v73, v69, v164
	v_cvt_pk_bf16_f32 v72, v72, v73
	v_mul_f32_e32 v73, v70, v166
	v_mul_f32_e32 v74, v71, v168
	v_cvt_pk_bf16_f32 v73, v73, v74
	v_mul_f32_e32 v74, v64, v170
	v_mul_f32_e32 v75, v65, v171
	v_cvt_pk_bf16_f32 v74, v74, v75
	v_mul_f32_e32 v75, v66, v174
	v_mul_f32_e32 v68, v68, v156
	v_mul_f32_e32 v69, v69, v157
	v_mul_f32_e32 v76, v67, v177
	v_cvt_pk_bf16_f32 v75, v75, v76
	v_cvt_pk_bf16_f32 v68, v68, v69
	v_mul_f32_e32 v69, v70, v124
	v_mul_f32_e32 v70, v71, v125
	v_mul_f32_e32 v64, v64, v126
	v_mul_f32_e32 v65, v65, v172
	v_cvt_pk_bf16_f32 v69, v69, v70
	v_cvt_pk_bf16_f32 v70, v64, v65
	v_mul_f32_e32 v64, v66, v175
	v_mul_f32_e32 v65, v67, v162
	v_cvt_pk_bf16_f32 v71, v64, v65
	global_store_dwordx4 v[84:85], v[72:75], off offset:256
	global_store_dwordx4 v[80:81], v[68:71], off offset:256
	global_load_dword v70, v131, s[6:7] offset:8
	s_nop 0
	global_load_dword v71, v131, s[6:7] offset:24
	s_mov_b32 s17, 0x200000
	v_add_co_u32_e32 v76, vcc, s17, v140
	s_mov_b32 s19, 0x600000
	s_nop 0
	v_addc_co_u32_e32 v77, vcc, 0, v141, vcc
	v_add_co_u32_e32 v68, vcc, s19, v140
	s_mov_b64 s[2:3], 0x200000
	s_nop 0
	v_addc_co_u32_e32 v69, vcc, 0, v141, vcc
	s_mov_b64 s[4:5], 0x600000
	v_lshl_add_u64 v[64:65], v[140:141], 0, s[2:3]
	v_lshl_add_u64 v[66:67], v[140:141], 0, s[4:5]
	s_waitcnt vmcnt(0)
;     __device__ __forceinline__ void operator()(const AccT& acc, const Unit& u, int wr, int wc, int fr, int fq) const {
;     ...
;         for (int ai = 0; ai < 2; ++ai) {
;             const int hh = 2 * ai + wr;
;             const float l2f = lgd[hh] * 1.4426950408889634f, l2b = lgd[4 + hh] * 1.4426950408889634f;
;             const float zf0 = exp2f((float)(127 - o0) * l2f), zfs = exp2f(-l2f), zb0 = exp2f((float)o0 * l2b), zbs = exp2f(l2b);
; #pragma unroll
;             for (int m = 0; m < 4; ++m) {
;                 const int r = rbase + ai * 128 + m * 16;
;                 const int d = 4 * (2 * m + (fr >> 3)) + j;
; #pragma unroll
;                 for (int bj = 0; bj < 2; ++bj) {
;                     const int t0 = tb + bj * 128;
;                     float v[8];
; #pragma unroll
;                     for (int jj = 0; jj < 4; ++jj) { v[jj] = acc[ai][bj][m][0][jj]; v[4 + jj] = acc[ai][bj][m][1][jj]; }
;                     if constexpr (ROPE) {
;                         const int t = t0 & 2047;
; #pragma unroll
;                         for (int hf = 0; hf < 2; ++hf) {
;                             f32x4 cs, sn;
;                             if (m < 2) { const float c1 = ropeA[(t >> 6) * 16 + d], s1 = ropeA[1024 + (t >> 6) * 16 + d]; cs = (f32x4){c1, c1, c1, c1}; sn = (f32x4){s1, s1, s1, s1}; }
;                             else { const float* cb = ropeA + 2048 + (d - 16) * 64 + (t & 63) + 4 * hf; cs = *(const f32x4*)(cb); sn = *(const f32x4*)(cb + 1024); }
; #pragma unroll
;                             for (int jj = 0; jj < 4; ++jj) { const float pr = __shfl_xor(v[4 * hf + jj], 4); v[4 * hf + jj] = v[4 * hf + jj] * cs[jj] + sgn * pr * sn[jj]; }
;                             __builtin_amdgcn_sched_barrier(0);
;                         }
;                     }
;                     float zf[8], zb[8]; zf[0] = zf0; zb[0] = zb0;
; #pragma unroll
;                     for (int jj = 1; jj < 8; ++jj) { zf[jj] = zf[jj - 1] * zfs; zb[jj] = zb[jj - 1] * zbs; }
;                     u32x4 wf, wb;
;                     wf.x = cvt_pk_bf16(v[0] * zf[0], v[1] * zf[1]); wf.y = cvt_pk_bf16(v[2] * zf[2], v[3] * zf[3]); wf.z = cvt_pk_bf16(v[4] * zf[4], v[5] * zf[5]); wf.w = cvt_pk_bf16(v[6] * zf[6], v[7] * zf[7]);
	v_mul_f32_e32 v72, 0x3fb8aa3b, v70
	v_mul_f32_e32 v73, 0x3fb8aa3b, v71
	v_mul_f32_e32 v74, v72, v155
	v_cmp_lt_f32_e32 vcc, s51, v72
	v_mul_f32_e32 v78, v73, v154
	v_cmp_gt_f32_e64 s[2:3], s49, v73
	v_cndmask_b32_e32 v75, 0, v153, vcc
	v_cmp_gt_f32_e64 s[4:5], s49, v74
	v_cndmask_b32_e64 v79, 0, v153, s[2:3]
	s_and_b64 s[24:25], vcc, exec
	v_cmp_gt_f32_e32 vcc, s49, v78
	v_fmac_f32_e32 v79, 0x3fb8aa3b, v71
	v_cndmask_b32_e64 v71, 0, v153, s[4:5]
	v_cndmask_b32_e32 v78, 0, v153, vcc
	v_fmac_f32_e32 v75, 0xbfb8aa3b, v70
	v_fmac_f32_e32 v71, v72, v155
	v_fmac_f32_e32 v78, v73, v154
	v_exp_f32_e32 v75, v75
	v_exp_f32_e32 v79, v79
	v_exp_f32_e32 v71, v71
	v_exp_f32_e32 v72, v78
	v_cndmask_b32_e64 v74, 0, v152, s[4:5]
	s_cselect_b32 s4, 0xffffffc0, 0
	s_and_b64 s[2:3], s[2:3], exec
	v_cndmask_b32_e32 v70, 0, v152, vcc
	s_cselect_b32 s2, 0xffffffc0, 0
	v_ldexp_f32 v75, v75, s4
	v_ldexp_f32 v78, v79, s2
	v_ldexp_f32 v79, v71, v74
	v_ldexp_f32 v70, v72, v70
	v_mul_f32_e32 v80, v75, v79
	v_mul_f32_e32 v71, v78, v70
	v_mul_f32_e32 v72, v60, v79
	v_mul_f32_e32 v81, v60, v70
	v_mul_f32_e32 v82, v75, v80
	v_mul_f32_e32 v60, v78, v71
	v_mul_f32_e32 v83, v75, v82
	v_mul_f32_e32 v84, v78, v60
	v_mul_f32_e32 v85, v75, v83
	v_mul_f32_e32 v86, v78, v84
	v_mul_f32_e32 v73, v61, v80
	v_mul_f32_e32 v87, v75, v85
	v_mul_f32_e32 v88, v78, v86
	v_cvt_pk_bf16_f32 v72, v72, v73
	v_mul_f32_e32 v73, v62, v82
	v_mul_f32_e32 v74, v63, v83
	v_mul_f32_e32 v90, v75, v87
	v_mul_f32_e32 v91, v78, v88
	v_cvt_pk_bf16_f32 v73, v73, v74
	v_mul_f32_e32 v74, v56, v85
	v_mul_f32_e32 v89, v56, v86
	v_mul_f32_e32 v56, v57, v87
	v_mul_f32_e32 v93, v75, v90
	v_mul_f32_e32 v78, v78, v91
	v_mul_f32_e32 v92, v57, v88
	v_cvt_pk_bf16_f32 v74, v74, v56
	v_mul_f32_e32 v56, v58, v90
	v_mul_f32_e32 v57, v59, v93
	v_mul_f32_e32 v59, v59, v78
	v_cvt_pk_bf16_f32 v75, v56, v57
	v_mul_f32_e32 v61, v61, v71
	v_mul_f32_e32 v62, v62, v60
	v_mul_f32_e32 v63, v63, v84
	v_mul_f32_e32 v94, v58, v91
	v_cvt_pk_bf16_f32 v56, v81, v61
	v_cvt_pk_bf16_f32 v57, v62, v63
	v_cvt_pk_bf16_f32 v58, v89, v92
	v_cvt_pk_bf16_f32 v59, v94, v59
	global_store_dwordx4 v[76:77], v[72:75], off
	global_store_dwordx4 v[68:69], v[56:59], off
	s_nop 1
	v_mul_f32_e32 v56, v52, v79
	v_mul_f32_e32 v57, v53, v80
	v_cvt_pk_bf16_f32 v56, v56, v57
	v_mul_f32_e32 v57, v54, v82
	v_mul_f32_e32 v58, v55, v83
	v_cvt_pk_bf16_f32 v57, v57, v58
	v_mul_f32_e32 v58, v48, v85
	v_mul_f32_e32 v59, v49, v87
	v_cvt_pk_bf16_f32 v58, v58, v59
	v_mul_f32_e32 v59, v50, v90
	v_mul_f32_e32 v52, v52, v70
	v_mul_f32_e32 v53, v53, v71
	v_mul_f32_e32 v61, v51, v93
	v_cvt_pk_bf16_f32 v59, v59, v61
	v_cvt_pk_bf16_f32 v52, v52, v53
	v_mul_f32_e32 v53, v54, v60
	v_mul_f32_e32 v54, v55, v84
	v_mul_f32_e32 v48, v48, v86
	v_mul_f32_e32 v49, v49, v88
	v_cvt_pk_bf16_f32 v53, v53, v54
	v_cvt_pk_bf16_f32 v54, v48, v49
	v_mul_f32_e32 v48, v50, v91
	v_mul_f32_e32 v49, v51, v78
	v_cvt_pk_bf16_f32 v55, v48, v49
	global_store_dwordx4 v[64:65], v[56:59], off offset:256
	global_store_dwordx4 v[66:67], v[52:55], off offset:256
	v_mul_f32_e32 v48, v44, v79
	v_mul_f32_e32 v49, v45, v80
	v_cvt_pk_bf16_f32 v48, v48, v49
	v_mul_f32_e32 v49, v46, v82
	v_mul_f32_e32 v50, v47, v83
	v_cvt_pk_bf16_f32 v49, v49, v50
	v_mul_f32_e32 v50, v40, v85
	v_mul_f32_e32 v51, v41, v87
	v_cvt_pk_bf16_f32 v50, v50, v51
	v_mul_f32_e32 v51, v42, v90
	v_mul_f32_e32 v44, v44, v70
	v_mul_f32_e32 v45, v45, v71
	v_mul_f32_e32 v52, v43, v93
	v_cvt_pk_bf16_f32 v51, v51, v52
	v_cvt_pk_bf16_f32 v44, v44, v45
	v_mul_f32_e32 v45, v46, v60
	v_mul_f32_e32 v46, v47, v84
	v_mul_f32_e32 v40, v40, v86
	s_mov_b64 s[2:3], 0x240000
	v_cvt_pk_bf16_f32 v45, v45, v46
	v_mul_f32_e32 v41, v41, v88
	v_cvt_pk_bf16_f32 v46, v40, v41
	v_mul_f32_e32 v40, v42, v91
	v_lshl_add_u64 v[52:53], v[140:141], 0, s[2:3]
	s_mov_b32 s2, 0x240000
	v_mul_f32_e32 v41, v43, v78
	v_cvt_pk_bf16_f32 v47, v40, v41
	v_add_co_u32_e32 v40, vcc, s2, v140
	s_mov_b64 s[2:3], 0x640000
	s_nop 0
	v_addc_co_u32_e32 v41, vcc, 0, v141, vcc
	global_store_dwordx4 v[40:41], v[48:51], off
	s_nop 1
	v_lshl_add_u64 v[48:49], v[140:141], 0, s[2:3]
	s_mov_b32 s2, 0x640000
	v_add_co_u32_e32 v40, vcc, s2, v140
	s_nop 1
	v_addc_co_u32_e32 v41, vcc, 0, v141, vcc
	global_store_dwordx4 v[40:41], v[44:47], off
	v_mul_f32_e32 v40, v36, v79
	v_mul_f32_e32 v41, v37, v80
	v_cvt_pk_bf16_f32 v40, v40, v41
	v_mul_f32_e32 v41, v38, v82
	v_mul_f32_e32 v42, v39, v83
	v_cvt_pk_bf16_f32 v41, v41, v42
	v_mul_f32_e32 v42, v32, v85
	v_mul_f32_e32 v43, v33, v87
	v_cvt_pk_bf16_f32 v42, v42, v43
	v_mul_f32_e32 v43, v34, v90
	v_mul_f32_e32 v36, v36, v70
; __device__ __forceinline__ unsigned cvt_pk_bf16(float lo, float hi) { unsigned r; asm volatile("v_cvt_pk_bf16_f32 %0, %1, %2" : "=v"(r) : "v"(lo), "v"(hi)); return r; }
; #define PG8_WAIT_V(n) asm volatile("s_waitcnt vmcnt(" #n ")" ::: "memory")
; #define PG8_BAR __builtin_amdgcn_s_barrier()
; template <class Epi, class Sched>
; __device__ __forceinline__ void gemm_phase(LAS unsigned char* lds, const Gemm g, const Sched& S, const Epi& E) {
;     ...
;     PG8_WAIT_V(0);
;     if (wr == 0) PG8_BAR;
;     PG8_BAR;
;     __device__ __forceinline__ void operator()(const AccT& acc, const Unit& u, int wr, int wc, int fr, int fq) const {
;     ...
;                     float zf[8], zb[8]; zf[0] = zf0; zb[0] = zb0;
; #pragma unroll
;                     for (int jj = 1; jj < 8; ++jj) { zf[jj] = zf[jj - 1] * zfs; zb[jj] = zb[jj - 1] * zbs; }
;                     u32x4 wf, wb;
;                     wf.x = cvt_pk_bf16(v[0] * zf[0], v[1] * zf[1]); wf.y = cvt_pk_bf16(v[2] * zf[2], v[3] * zf[3]); wf.z = cvt_pk_bf16(v[4] * zf[4], v[5] * zf[5]); wf.w = cvt_pk_bf16(v[6] * zf[6], v[7] * zf[7]);
;                     wb.x = cvt_pk_bf16(v[0] * zb[0], v[1] * zb[1]); wb.y = cvt_pk_bf16(v[2] * zb[2], v[3] * zb[3]); wb.z = cvt_pk_bf16(v[4] * zb[4], v[5] * zb[5]); wb.w = cvt_pk_bf16(v[6] * zb[6], v[7] * zb[7]);
;                     *(u32x4*)(KTZ + (size_t)r * NT + t0) = wf;
;                     *(u32x4*)(KTZ + (size_t)(256 + r) * NT + t0) = wb;
	v_mul_f32_e32 v37, v37, v71
	v_mul_f32_e32 v44, v35, v93
	v_cvt_pk_bf16_f32 v43, v43, v44
	v_cvt_pk_bf16_f32 v36, v36, v37
	v_mul_f32_e32 v37, v38, v60
	v_mul_f32_e32 v38, v39, v84
	v_mul_f32_e32 v32, v32, v86
	v_mul_f32_e32 v33, v33, v88
	v_cvt_pk_bf16_f32 v37, v37, v38
	v_cvt_pk_bf16_f32 v38, v32, v33
	v_mul_f32_e32 v32, v34, v91
	v_mul_f32_e32 v33, v35, v78
	v_cvt_pk_bf16_f32 v39, v32, v33
	global_store_dwordx4 v[52:53], v[40:43], off offset:256
	global_store_dwordx4 v[48:49], v[36:39], off offset:256
	v_mul_f32_e32 v32, v28, v79
	v_mul_f32_e32 v33, v29, v80
	v_cvt_pk_bf16_f32 v32, v32, v33
	v_mul_f32_e32 v33, v30, v82
	v_mul_f32_e32 v34, v31, v83
	v_cvt_pk_bf16_f32 v33, v33, v34
	v_mul_f32_e32 v34, v24, v85
	v_mul_f32_e32 v35, v25, v87
	v_cvt_pk_bf16_f32 v34, v34, v35
	v_mul_f32_e32 v35, v26, v90
	v_mul_f32_e32 v28, v28, v70
	v_mul_f32_e32 v29, v29, v71
	v_mul_f32_e32 v36, v27, v93
	v_cvt_pk_bf16_f32 v35, v35, v36
	v_cvt_pk_bf16_f32 v28, v28, v29
	v_mul_f32_e32 v29, v30, v60
	v_mul_f32_e32 v30, v31, v84
	v_mul_f32_e32 v24, v24, v86
	v_cvt_pk_bf16_f32 v29, v29, v30
	v_mul_f32_e32 v25, v25, v88
	v_cvt_pk_bf16_f32 v30, v24, v25
	v_mul_f32_e32 v24, v26, v91
	v_mul_f32_e32 v25, v27, v78
	v_cvt_pk_bf16_f32 v31, v24, v25
	v_add_co_u32_e32 v24, vcc, s52, v140
	s_mov_b64 s[2:3], 0x280000
	s_nop 0
	v_addc_co_u32_e32 v25, vcc, 0, v141, vcc
	global_store_dwordx4 v[24:25], v[32:35], off
	v_add_co_u32_e32 v24, vcc, s53, v140
	v_lshl_add_u64 v[36:37], v[140:141], 0, s[2:3]
	s_nop 0
	v_addc_co_u32_e32 v25, vcc, 0, v141, vcc
	v_lshl_add_u64 v[32:33], v[140:141], 0, s[8:9]
	global_store_dwordx4 v[24:25], v[28:31], off
	v_mul_f32_e32 v24, v20, v79
	v_mul_f32_e32 v25, v21, v80
	v_cvt_pk_bf16_f32 v24, v24, v25
	v_mul_f32_e32 v25, v22, v82
	v_mul_f32_e32 v26, v23, v83
	v_cvt_pk_bf16_f32 v25, v25, v26
	v_mul_f32_e32 v26, v16, v85
	v_mul_f32_e32 v27, v17, v87
	v_cvt_pk_bf16_f32 v26, v26, v27
	v_mul_f32_e32 v27, v18, v90
	v_mul_f32_e32 v20, v20, v70
	v_mul_f32_e32 v21, v21, v71
	v_mul_f32_e32 v28, v19, v93
	v_cvt_pk_bf16_f32 v27, v27, v28
	v_cvt_pk_bf16_f32 v20, v20, v21
	v_mul_f32_e32 v21, v22, v60
	v_mul_f32_e32 v22, v23, v84
	v_mul_f32_e32 v16, v16, v86
	v_mul_f32_e32 v17, v17, v88
	v_cvt_pk_bf16_f32 v21, v21, v22
	v_cvt_pk_bf16_f32 v22, v16, v17
	v_mul_f32_e32 v16, v18, v91
	v_mul_f32_e32 v17, v19, v78
	v_cvt_pk_bf16_f32 v23, v16, v17
	global_store_dwordx4 v[36:37], v[24:27], off offset:256
	global_store_dwordx4 v[32:33], v[20:23], off offset:256
	v_mul_f32_e32 v16, v12, v79
	v_mul_f32_e32 v17, v13, v80
	v_cvt_pk_bf16_f32 v16, v16, v17
	v_mul_f32_e32 v17, v14, v82
	v_mul_f32_e32 v18, v15, v83
	v_cvt_pk_bf16_f32 v17, v17, v18
	v_mul_f32_e32 v18, v8, v85
	v_mul_f32_e32 v19, v9, v87
	v_cvt_pk_bf16_f32 v18, v18, v19
	v_mul_f32_e32 v19, v10, v90
	v_mul_f32_e32 v12, v12, v70
	v_mul_f32_e32 v13, v13, v71
	v_mul_f32_e32 v20, v11, v93
	v_cvt_pk_bf16_f32 v19, v19, v20
	v_cvt_pk_bf16_f32 v12, v12, v13
	v_mul_f32_e32 v13, v14, v60
	v_mul_f32_e32 v14, v15, v84
	v_mul_f32_e32 v8, v8, v86
	v_cvt_pk_bf16_f32 v13, v13, v14
	v_mul_f32_e32 v9, v9, v88
	v_cvt_pk_bf16_f32 v14, v8, v9
	v_mul_f32_e32 v8, v10, v91
	v_mul_f32_e32 v9, v11, v78
	v_cvt_pk_bf16_f32 v15, v8, v9
	v_add_co_u32_e32 v8, vcc, s54, v140
	v_lshl_add_u64 v[20:21], v[140:141], 0, s[10:11]
	s_nop 0
	v_addc_co_u32_e32 v9, vcc, 0, v141, vcc
	global_store_dwordx4 v[8:9], v[16:19], off
	v_add_co_u32_e32 v8, vcc, s55, v140
	s_nop 0
	v_lshl_add_u64 v[16:17], v[140:141], 0, s[12:13]
	v_addc_co_u32_e32 v9, vcc, 0, v141, vcc
	global_store_dwordx4 v[8:9], v[12:15], off
	v_mul_f32_e32 v8, v4, v79
	v_mul_f32_e32 v9, v5, v80
	v_cvt_pk_bf16_f32 v8, v8, v9
	v_mul_f32_e32 v9, v6, v82
	v_mul_f32_e32 v10, v7, v83
	v_cvt_pk_bf16_f32 v9, v9, v10
	v_mul_f32_e32 v10, v0, v85
	v_mul_f32_e32 v11, v1, v87
	v_cvt_pk_bf16_f32 v10, v10, v11
	v_mul_f32_e32 v11, v2, v90
	v_mul_f32_e32 v4, v4, v70
	v_mul_f32_e32 v5, v5, v71
	v_mul_f32_e32 v12, v3, v93
	v_cvt_pk_bf16_f32 v11, v11, v12
	v_cvt_pk_bf16_f32 v4, v4, v5
	v_mul_f32_e32 v5, v6, v60
	v_mul_f32_e32 v6, v7, v84
	v_mul_f32_e32 v0, v0, v86
	v_mul_f32_e32 v1, v1, v88
	v_cvt_pk_bf16_f32 v5, v5, v6
	v_cvt_pk_bf16_f32 v6, v0, v1
	v_mul_f32_e32 v0, v2, v91
	v_mul_f32_e32 v1, v3, v78
	v_cvt_pk_bf16_f32 v7, v0, v1
	global_store_dwordx4 v[20:21], v[8:11], off offset:256
	global_store_dwordx4 v[16:17], v[4:7], off offset:256
	s_and_b64 vcc, exec, s[14:15]
	s_mov_b32 s56, s16
	s_mov_b64 s[4:5], s[22:23]
	s_mov_b64 s[2:3], s[20:21]
	s_cbranch_vccz .LBB0_686
	s_waitcnt vmcnt(0)
	s_cmpk_gt_u32 s27, 0xff
	s_cbranch_scc1 .LBB0_697
	s_barrier

; #define PG8_STAGE(bufoff, gbase, voff) do { _Pragma("unroll") for (int _i = 0; _i < 2; ++_i) \
;         __builtin_amdgcn_global_load_lds((const unsigned*)((const char*)(gbase) + (voff)[_i]), (LAS unsigned*)(lds + (bufoff) + ldsw + _i * 8192), 16, 0, 0); } while (0)
; #define PG8_LDA(dst, b, h) do { _Pragma("unroll") for (int m = 0; m < 4; ++m) _Pragma("unroll") for (int k = 0; k < 2; ++k) dst[m][k] = *(const LAS bf16x8*)(lds + PG8_SA(b, h) + aoff + m * 2048 + k * 1024); } while (0)
; #define PG8_LDB(dst, b, h) do { _Pragma("unroll") for (int n = 0; n < 2; ++n) _Pragma("unroll") for (int k = 0; k < 2; ++k) dst[n][k] = *(const LAS bf16x8*)(lds + PG8_SB(b, h) + boff + n * 2048 + k * 1024); } while (0)
; #define PG8_MMA(ai, bj, At, Bt) do { __builtin_amdgcn_s_setprio(1); _Pragma("unroll") for (int m = 0; m < 4; ++m) _Pragma("unroll") for (int n = 0; n < 2; ++n) _Pragma("unroll") for (int k = 0; k < 2; ++k) \
;         acc[ai][bj][m][n] = __builtin_amdgcn_mfma_f32_16x16x32_bf16(Bt[n][k], At[m][k], acc[ai][bj][m][n], 0, 0, 0); __builtin_amdgcn_s_setprio(0); } while (0)
; #define PG8_WAIT_L(n) asm volatile("s_waitcnt lgkmcnt(" #n ")" ::: "memory")
; template <class Epi, class Sched>
; __device__ __forceinline__ void gemm_phase(LAS unsigned char* lds, const Gemm g, const Sched& S, const Epi& E) {
;     ...
;         const bool has_next = S.next(ui + 1, nxt);
;         const char* nA = has_next ? (const char*)g.A + (size_t)nxt.pm * tstep : cA; const char* nB = has_next ? (const char*)g.Bt + (size_t)nxt.pn * tstep : cB;
;         for (int t = 0; t < nt; t += 2) {
;             const bool last = (t == nt - 2);
;             const char* a1 = cA + (size_t)(t + 1) * kstep;
;             const char* a2 = last ? nA : cA + (size_t)(t + 2) * kstep; const char* b2 = last ? nB : cB + (size_t)(t + 2) * kstep;
;             const char* a3 = a2 + kstep; const char* b3 = b2 + kstep;
;             PG8_LDB(B0, 0, 0); PG8_SCHED; PG8_LDA(At, 0, 0); PG8_STAGE(PG8_SA(1, 1), a1 + hstep, voffA);
;             PG8_WAIT_L(8); PG8_BAR; PG8_WAIT_L(0); PG8_MMA(0, 0, At, B0); PG8_BAR; PG8_SCHED;
;             PG8_LDB(B1, 0, 1); PG8_STAGE(PG8_SB(0, 0), b2, voffB);
;             PG8_BAR; PG8_WAIT_L(0); PG8_MMA(0, 1, At, B1); PG8_BAR;
;             PG8_LDA(At, 0, 1); PG8_STAGE(PG8_SA(0, 0), a2, voffA);
;             PG8_BAR; PG8_WAIT_L(0); PG8_MMA(1, 0, At, B0); PG8_BAR; PG8_SCHED;
.LBB0_712:
	s_ashr_i32 s15, s14, 31
	v_cmp_lt_i64_e64 s[26:27], s[16:17], 64
	s_lshl_b64 s[16:17], s[14:15], 19
	s_add_u32 s16, s38, s16
	s_addc_u32 s17, s39, s17
	s_and_b64 s[18:19], s[26:27], exec
	s_cselect_b32 s15, s17, s23
	s_cselect_b32 s54, s16, s22
	s_ashr_i32 s13, s12, 31
	s_lshl_b64 s[18:19], s[12:13], 19
	s_add_u32 s18, s28, s18
	s_addc_u32 s19, s29, s19
	s_and_b64 s[26:27], s[26:27], exec
	s_cselect_b32 s13, s19, s25
	s_cselect_b32 s55, s18, s24
	s_add_u32 s22, s22, 0x40080
	s_addc_u32 s23, s23, 0
	s_add_u32 s56, s24, 0x100
	s_addc_u32 s57, s25, 0
	s_mov_b32 s58, -2
	s_waitcnt lgkmcnt(0)
	ds_read_b128 v[146:149], v143
	ds_read_b128 v[150:153], v143 offset:1024
	ds_read_b128 v[154:157], v143 offset:2048
	ds_read_b128 v[158:161], v143 offset:3072
	s_add_u32 s24, s22, 0xfffc0080
	s_addc_u32 s25, s23, -1
	s_cmp_eq_u32 s58, 12
	s_cselect_b32 s27, s15, s25
	s_cselect_b32 s26, s54, s24
	s_cselect_b32 s25, s13, s57
	s_cselect_b32 s24, s55, s56
	s_add_i32 m0, s21, 0xc000
	ds_read_b128 v[162:165], v144
	ds_read_b128 v[166:169], v144 offset:1024
	ds_read_b128 v[170:173], v144 offset:2048
	ds_read_b128 v[174:177], v144 offset:3072
	ds_read_b128 v[178:181], v144 offset:4096
	ds_read_b128 v[182:185], v144 offset:5120
	ds_read_b128 v[186:189], v144 offset:6144
	ds_read_b128 v[190:193], v144 offset:7168
	global_load_lds_dwordx4 v136, s[22:23]
	s_add_i32 m0, s21, 0xe000
	s_nop 0
	global_load_lds_dwordx4 v138, s[22:23]
	s_waitcnt lgkmcnt(8)
	s_waitcnt vmcnt(10)
	s_barrier
	s_waitcnt lgkmcnt(0)
	s_setprio 1
	s_waitcnt lgkmcnt(0)
	v_mfma_f32_16x16x32_bf16 v[124:127], v[146:149], v[162:165], 0
	v_mfma_f32_16x16x32_bf16 v[120:123], v[154:157], v[162:165], 0
	v_mfma_f32_16x16x32_bf16 v[116:119], v[146:149], v[170:173], 0
	v_mfma_f32_16x16x32_bf16 v[108:111], v[154:157], v[170:173], 0
	v_mfma_f32_16x16x32_bf16 v[100:103], v[146:149], v[178:181], 0
	v_mfma_f32_16x16x32_bf16 v[92:95], v[154:157], v[178:181], 0
	v_mfma_f32_16x16x32_bf16 v[84:87], v[146:149], v[186:189], 0
	v_mfma_f32_16x16x32_bf16 v[76:79], v[154:157], v[186:189], 0
	v_mfma_f32_16x16x32_bf16 v[124:127], v[150:153], v[166:169], v[124:127]
	v_mfma_f32_16x16x32_bf16 v[120:123], v[158:161], v[166:169], v[120:123]
	v_mfma_f32_16x16x32_bf16 v[116:119], v[150:153], v[174:177], v[116:119]
	v_mfma_f32_16x16x32_bf16 v[108:111], v[158:161], v[174:177], v[108:111]
	v_mfma_f32_16x16x32_bf16 v[100:103], v[150:153], v[182:185], v[100:103]
	v_mfma_f32_16x16x32_bf16 v[92:95], v[158:161], v[182:185], v[92:95]
	v_mfma_f32_16x16x32_bf16 v[84:87], v[150:153], v[190:193], v[84:87]
	v_mfma_f32_16x16x32_bf16 v[76:79], v[158:161], v[190:193], v[76:79]
	s_setprio 0
	s_barrier
	s_add_i32 s59, s46, s34
	s_mov_b32 m0, s59
	ds_read_b128 v[194:197], v145
	ds_read_b128 v[202:205], v145 offset:1024
	ds_read_b128 v[206:209], v145 offset:2048
	ds_read_b128 v[210:213], v145 offset:3072
	global_load_lds_dwordx4 v130, s[24:25]
	s_add_i32 m0, s59, 0x2000
	s_nop 0
	global_load_lds_dwordx4 v134, s[24:25]
	s_waitcnt vmcnt(10)
	s_barrier
	s_waitcnt lgkmcnt(0)
	s_setprio 1
	s_waitcnt lgkmcnt(0)
	v_mfma_f32_16x16x32_bf16 v[112:115], v[194:197], v[162:165], 0
	v_mfma_f32_16x16x32_bf16 v[104:107], v[206:209], v[162:165], 0
	v_mfma_f32_16x16x32_bf16 v[96:99], v[194:197], v[170:173], 0
	v_mfma_f32_16x16x32_bf16 v[88:91], v[206:209], v[170:173], 0
	v_mfma_f32_16x16x32_bf16 v[80:83], v[194:197], v[178:181], 0
	v_mfma_f32_16x16x32_bf16 v[72:75], v[206:209], v[178:181], 0
	v_mfma_f32_16x16x32_bf16 v[68:71], v[194:197], v[186:189], 0
	v_mfma_f32_16x16x32_bf16 v[64:67], v[206:209], v[186:189], 0
	v_mfma_f32_16x16x32_bf16 v[112:115], v[202:205], v[166:169], v[112:115]
	v_mfma_f32_16x16x32_bf16 v[104:107], v[210:213], v[166:169], v[104:107]
	v_mfma_f32_16x16x32_bf16 v[96:99], v[202:205], v[174:177], v[96:99]
	v_mfma_f32_16x16x32_bf16 v[88:91], v[210:213], v[174:177], v[88:91]
	v_mfma_f32_16x16x32_bf16 v[80:83], v[202:205], v[182:185], v[80:83]
	v_mfma_f32_16x16x32_bf16 v[72:75], v[210:213], v[182:185], v[72:75]
	v_mfma_f32_16x16x32_bf16 v[68:71], v[202:205], v[190:193], v[68:71]
	v_mfma_f32_16x16x32_bf16 v[64:67], v[210:213], v[190:193], v[64:67]
	s_setprio 0
	s_mov_b32 m0, s21
	v_lshl_add_u64 v[216:217], s[26:27], 0, v[128:129]
	s_barrier
	ds_read_b128 v[162:165], v144 offset:16384
	ds_read_b128 v[166:169], v144 offset:17408
	ds_read_b128 v[170:173], v144 offset:18432
	ds_read_b128 v[174:177], v144 offset:19456
	ds_read_b128 v[178:181], v144 offset:20480
	ds_read_b128 v[182:185], v144 offset:21504
	ds_read_b128 v[186:189], v144 offset:22528
	ds_read_b128 v[190:193], v144 offset:23552
	global_load_lds_dwordx4 v128, s[26:27]
	v_lshl_add_u64 v[218:219], s[26:27], 0, v[132:133]
	s_mov_b32 m0, s35
	s_nop 0
	global_load_lds_dwordx4 v132, s[26:27]
	s_barrier
	s_waitcnt lgkmcnt(0)
	s_setprio 1
	s_waitcnt lgkmcnt(0)
	v_mfma_f32_16x16x32_bf16 v[60:63], v[146:149], v[162:165], 0
	v_mfma_f32_16x16x32_bf16 v[56:59], v[154:157], v[162:165], 0
	v_mfma_f32_16x16x32_bf16 v[52:55], v[146:149], v[170:173], 0
	v_mfma_f32_16x16x32_bf16 v[44:47], v[154:157], v[170:173], 0
	v_mfma_f32_16x16x32_bf16 v[36:39], v[146:149], v[178:181], 0
	v_mfma_f32_16x16x32_bf16 v[28:31], v[154:157], v[178:181], 0
	v_mfma_f32_16x16x32_bf16 v[20:23], v[146:149], v[186:189], 0
	v_mfma_f32_16x16x32_bf16 v[12:15], v[154:157], v[186:189], 0
	v_mfma_f32_16x16x32_bf16 v[60:63], v[150:153], v[166:169], v[60:63]
	v_mfma_f32_16x16x32_bf16 v[56:59], v[158:161], v[166:169], v[56:59]
	v_mfma_f32_16x16x32_bf16 v[52:55], v[150:153], v[174:177], v[52:55]
	v_mfma_f32_16x16x32_bf16 v[44:47], v[158:161], v[174:177], v[44:47]
	v_mfma_f32_16x16x32_bf16 v[36:39], v[150:153], v[182:185], v[36:39]
	v_mfma_f32_16x16x32_bf16 v[28:31], v[158:161], v[182:185], v[28:31]
	v_mfma_f32_16x16x32_bf16 v[20:23], v[150:153], v[190:193], v[20:23]
	v_mfma_f32_16x16x32_bf16 v[12:15], v[158:161], v[190:193], v[12:15]
	s_setprio 0
	s_barrier
; #define PG8_STAGE(bufoff, gbase, voff) do { _Pragma("unroll") for (int _i = 0; _i < 2; ++_i) \
;         __builtin_amdgcn_global_load_lds((const unsigned*)((const char*)(gbase) + (voff)[_i]), (LAS unsigned*)(lds + (bufoff) + ldsw + _i * 8192), 16, 0, 0); } while (0)
; #define PG8_LDA(dst, b, h) do { _Pragma("unroll") for (int m = 0; m < 4; ++m) _Pragma("unroll") for (int k = 0; k < 2; ++k) dst[m][k] = *(const LAS bf16x8*)(lds + PG8_SA(b, h) + aoff + m * 2048 + k * 1024); } while (0)
; #define PG8_LDB(dst, b, h) do { _Pragma("unroll") for (int n = 0; n < 2; ++n) _Pragma("unroll") for (int k = 0; k < 2; ++k) dst[n][k] = *(const LAS bf16x8*)(lds + PG8_SB(b, h) + boff + n * 2048 + k * 1024); } while (0)
; #define PG8_MMA(ai, bj, At, Bt) do { __builtin_amdgcn_s_setprio(1); _Pragma("unroll") for (int m = 0; m < 4; ++m) _Pragma("unroll") for (int n = 0; n < 2; ++n) _Pragma("unroll") for (int k = 0; k < 2; ++k) \
;         acc[ai][bj][m][n] = __builtin_amdgcn_mfma_f32_16x16x32_bf16(Bt[n][k], At[m][k], acc[ai][bj][m][n], 0, 0, 0); __builtin_amdgcn_s_setprio(0); } while (0)
; #define PG8_WAIT_V(n) asm volatile("s_waitcnt vmcnt(" #n ")" ::: "memory")
; #define PG8_WAIT_L(n) asm volatile("s_waitcnt lgkmcnt(" #n ")" ::: "memory")
; #define PG8_BAR __builtin_amdgcn_s_barrier()
; #define PG8_SCHED __builtin_amdgcn_sched_barrier(0)
; template <class Epi, class Sched>
; __device__ __forceinline__ void gemm_phase(LAS unsigned char* lds, const Gemm g, const Sched& S, const Epi& E) {
;     ...
;             PG8_BAR; PG8_WAIT_L(0); PG8_MMA(1, 0, At, B0); PG8_BAR; PG8_SCHED;
;             PG8_STAGE(PG8_SB(0, 1), b2 + hstep, voffB);
;             PG8_WAIT_V(6); PG8_BAR; PG8_MMA(1, 1, At, B1); PG8_BAR;
;             PG8_LDB(B0, 1, 0); PG8_SCHED; PG8_LDA(At, 1, 0); PG8_STAGE(PG8_SA(0, 1), a2 + hstep, voffA);
;             PG8_WAIT_L(8); PG8_BAR; PG8_WAIT_L(0); PG8_MMA(0, 0, At, B0); PG8_BAR; PG8_SCHED;
;             PG8_LDB(B1, 1, 1); PG8_STAGE(PG8_SB(1, 0), b3, voffB);
;             PG8_BAR; PG8_WAIT_L(0); PG8_MMA(0, 1, At, B1); PG8_BAR;
;             PG8_LDA(At, 1, 1); PG8_STAGE(PG8_SA(1, 0), a3, voffA);
;             PG8_BAR; PG8_WAIT_L(0); PG8_MMA(1, 0, At, B0); PG8_BAR; PG8_SCHED;
	s_add_u32 s60, s24, 0x40000
	s_addc_u32 s61, s25, 0
	s_add_i32 s59, s47, s34
	s_mov_b32 m0, s59
	s_nop 0
	global_load_lds_dwordx4 v130, s[60:61]
	s_add_i32 m0, s59, 0x2000
	s_nop 0
	global_load_lds_dwordx4 v134, s[60:61]
	s_waitcnt vmcnt(10)
	s_barrier
	s_setprio 1
	v_mfma_f32_16x16x32_bf16 v[48:51], v[194:197], v[162:165], 0
	v_mfma_f32_16x16x32_bf16 v[40:43], v[206:209], v[162:165], 0
	v_mfma_f32_16x16x32_bf16 v[32:35], v[194:197], v[170:173], 0
	v_mfma_f32_16x16x32_bf16 v[24:27], v[206:209], v[170:173], 0
	v_mfma_f32_16x16x32_bf16 v[16:19], v[194:197], v[178:181], 0
	v_mfma_f32_16x16x32_bf16 v[8:11], v[206:209], v[178:181], 0
	v_mfma_f32_16x16x32_bf16 v[4:7], v[194:197], v[186:189], 0
	v_mfma_f32_16x16x32_bf16 v[0:3], v[206:209], v[186:189], 0
	v_mfma_f32_16x16x32_bf16 v[48:51], v[202:205], v[166:169], v[48:51]
	v_mfma_f32_16x16x32_bf16 v[40:43], v[210:213], v[166:169], v[40:43]
	v_mfma_f32_16x16x32_bf16 v[32:35], v[202:205], v[174:177], v[32:35]
	v_mfma_f32_16x16x32_bf16 v[24:27], v[210:213], v[174:177], v[24:27]
	v_mfma_f32_16x16x32_bf16 v[16:19], v[202:205], v[182:185], v[16:19]
	v_mfma_f32_16x16x32_bf16 v[8:11], v[210:213], v[182:185], v[8:11]
	v_mfma_f32_16x16x32_bf16 v[4:7], v[202:205], v[190:193], v[4:7]
	v_mfma_f32_16x16x32_bf16 v[0:3], v[210:213], v[190:193], v[0:3]
	s_setprio 0
	s_add_i32 s59, 0, 0x18000
	v_add_u32_e32 v158, s59, v142
	s_barrier
	ds_read_b128 v[146:149], v158
	ds_read_b128 v[150:153], v158 offset:1024
	ds_read_b128 v[154:157], v158 offset:2048
	ds_read_b128 v[158:161], v158 offset:3072
	s_add_u32 s26, s26, 0x40000
	s_addc_u32 s27, s27, 0
	s_mov_b32 m0, s36
	ds_read_b128 v[162:165], v144 offset:32768
	ds_read_b128 v[166:169], v144 offset:33792
	ds_read_b128 v[170:173], v144 offset:34816
	ds_read_b128 v[174:177], v144 offset:35840
	ds_read_b128 v[178:181], v144 offset:36864
	ds_read_b128 v[182:185], v144 offset:37888
	ds_read_b128 v[186:189], v144 offset:38912
	ds_read_b128 v[190:193], v144 offset:39936
	global_load_lds_dwordx4 v128, s[26:27]
	s_mov_b32 m0, s37
	s_nop 0
	global_load_lds_dwordx4 v132, s[26:27]
	s_waitcnt lgkmcnt(8)
	s_waitcnt vmcnt(10)
	s_barrier
	s_waitcnt lgkmcnt(0)
	s_setprio 1
	s_waitcnt lgkmcnt(0)
	v_mfma_f32_16x16x32_bf16 v[124:127], v[146:149], v[162:165], v[124:127]
	v_mfma_f32_16x16x32_bf16 v[120:123], v[154:157], v[162:165], v[120:123]
	v_mfma_f32_16x16x32_bf16 v[116:119], v[146:149], v[170:173], v[116:119]
	v_mfma_f32_16x16x32_bf16 v[108:111], v[154:157], v[170:173], v[108:111]
	v_mfma_f32_16x16x32_bf16 v[100:103], v[146:149], v[178:181], v[100:103]
	v_mfma_f32_16x16x32_bf16 v[92:95], v[154:157], v[178:181], v[92:95]
	v_mfma_f32_16x16x32_bf16 v[84:87], v[146:149], v[186:189], v[84:87]
	v_mfma_f32_16x16x32_bf16 v[76:79], v[154:157], v[186:189], v[76:79]
	v_mfma_f32_16x16x32_bf16 v[124:127], v[150:153], v[166:169], v[124:127]
	v_mfma_f32_16x16x32_bf16 v[120:123], v[158:161], v[166:169], v[120:123]
	v_mfma_f32_16x16x32_bf16 v[116:119], v[150:153], v[174:177], v[116:119]
	v_mfma_f32_16x16x32_bf16 v[108:111], v[158:161], v[174:177], v[108:111]
	v_mfma_f32_16x16x32_bf16 v[100:103], v[150:153], v[182:185], v[100:103]
	v_mfma_f32_16x16x32_bf16 v[92:95], v[158:161], v[182:185], v[92:95]
	v_mfma_f32_16x16x32_bf16 v[84:87], v[150:153], v[190:193], v[84:87]
	v_mfma_f32_16x16x32_bf16 v[76:79], v[158:161], v[190:193], v[76:79]
	s_setprio 0
	s_barrier
	s_add_i32 s26, 0, 0x1c000
	s_add_i32 s27, s59, s34
	v_add_u32_e32 v210, s26, v142
	s_add_u32 s0, s24, 0x80
	s_addc_u32 s1, s25, 0
	s_mov_b32 m0, s27
	ds_read_b128 v[194:197], v210
	ds_read_b128 v[202:205], v210 offset:1024
	ds_read_b128 v[206:209], v210 offset:2048
	ds_read_b128 v[210:213], v210 offset:3072
	global_load_lds_dwordx4 v130, s[0:1]
	s_add_i32 m0, s27, 0x2000
	s_nop 0
	global_load_lds_dwordx4 v134, s[0:1]
	s_waitcnt vmcnt(10)
	s_barrier
	s_waitcnt lgkmcnt(0)
	s_setprio 1
	s_waitcnt lgkmcnt(0)
	v_mfma_f32_16x16x32_bf16 v[112:115], v[194:197], v[162:165], v[112:115]
	v_mfma_f32_16x16x32_bf16 v[104:107], v[206:209], v[162:165], v[104:107]
	v_mfma_f32_16x16x32_bf16 v[96:99], v[194:197], v[170:173], v[96:99]
	v_mfma_f32_16x16x32_bf16 v[88:91], v[206:209], v[170:173], v[88:91]
	v_mfma_f32_16x16x32_bf16 v[80:83], v[194:197], v[178:181], v[80:83]
	v_mfma_f32_16x16x32_bf16 v[72:75], v[206:209], v[178:181], v[72:75]
	v_mfma_f32_16x16x32_bf16 v[68:71], v[194:197], v[186:189], v[68:71]
	v_mfma_f32_16x16x32_bf16 v[64:67], v[206:209], v[186:189], v[64:67]
	v_mfma_f32_16x16x32_bf16 v[112:115], v[202:205], v[166:169], v[112:115]
	v_mfma_f32_16x16x32_bf16 v[104:107], v[210:213], v[166:169], v[104:107]
	v_mfma_f32_16x16x32_bf16 v[96:99], v[202:205], v[174:177], v[96:99]
	v_mfma_f32_16x16x32_bf16 v[88:91], v[210:213], v[174:177], v[88:91]
	v_mfma_f32_16x16x32_bf16 v[80:83], v[202:205], v[182:185], v[80:83]
	v_mfma_f32_16x16x32_bf16 v[72:75], v[210:213], v[182:185], v[72:75]
	v_mfma_f32_16x16x32_bf16 v[68:71], v[202:205], v[190:193], v[68:71]
	v_mfma_f32_16x16x32_bf16 v[64:67], v[210:213], v[190:193], v[64:67]
	s_setprio 0
	s_mov_b32 m0, s43
	s_mov_b64 s[0:1], 0x80
	v_lshl_add_u64 v[198:199], v[216:217], 0, s[0:1]
	s_barrier
	ds_read_b128 v[162:165], v144 offset:49152
	ds_read_b128 v[166:169], v144 offset:50176
	ds_read_b128 v[170:173], v144 offset:51200
	ds_read_b128 v[174:177], v144 offset:52224
	ds_read_b128 v[178:181], v144 offset:53248
	ds_read_b128 v[182:185], v144 offset:54272
	ds_read_b128 v[186:189], v144 offset:55296
	ds_read_b128 v[190:193], v144 offset:56320
	global_load_lds_dwordx4 v[198:199], off
	v_lshl_add_u64 v[198:199], v[218:219], 0, s[0:1]
	s_mov_b32 m0, s44
	s_nop 0
	global_load_lds_dwordx4 v[198:199], off
	s_barrier
; #define PG8_STAGE(bufoff, gbase, voff) do { _Pragma("unroll") for (int _i = 0; _i < 2; ++_i) \
;         __builtin_amdgcn_global_load_lds((const unsigned*)((const char*)(gbase) + (voff)[_i]), (LAS unsigned*)(lds + (bufoff) + ldsw + _i * 8192), 16, 0, 0); } while (0)
; #define PG8_LDA(dst, b, h) do { _Pragma("unroll") for (int m = 0; m < 4; ++m) _Pragma("unroll") for (int k = 0; k < 2; ++k) dst[m][k] = *(const LAS bf16x8*)(lds + PG8_SA(b, h) + aoff + m * 2048 + k * 1024); } while (0)
; #define PG8_LDB(dst, b, h) do { _Pragma("unroll") for (int n = 0; n < 2; ++n) _Pragma("unroll") for (int k = 0; k < 2; ++k) dst[n][k] = *(const LAS bf16x8*)(lds + PG8_SB(b, h) + boff + n * 2048 + k * 1024); } while (0)
; #define PG8_WAIT_V(n) asm volatile("s_waitcnt vmcnt(" #n ")" ::: "memory")
; #define PG8_WAIT_L(n) asm volatile("s_waitcnt lgkmcnt(" #n ")" ::: "memory")
; #define PG8_BAR __builtin_amdgcn_s_barrier()
; #define PG8_SCHED __builtin_amdgcn_sched_barrier(0)
; template <class Epi, class Sched>
; __device__ __forceinline__ void gemm_phase(LAS unsigned char* lds, const Gemm g, const Sched& S, const Epi& E) {
;     ...
;             PG8_LDB(B0, 0, 0); PG8_SCHED; PG8_LDA(At, 0, 0); PG8_STAGE(PG8_SA(1, 1), a1 + hstep, voffA);
;             PG8_WAIT_L(8); PG8_BAR; PG8_WAIT_L(0); PG8_MMA(0, 0, At, B0); PG8_BAR; PG8_SCHED;
;             PG8_LDB(B1, 0, 1); PG8_STAGE(PG8_SB(0, 0), b2, voffB);
;             PG8_BAR; PG8_WAIT_L(0); PG8_MMA(0, 1, At, B1); PG8_BAR;
;             PG8_LDA(At, 0, 1); PG8_STAGE(PG8_SA(0, 0), a2, voffA);
;             PG8_BAR; PG8_WAIT_L(0); PG8_MMA(1, 0, At, B0); PG8_BAR; PG8_SCHED;
;             PG8_STAGE(PG8_SB(0, 1), b2 + hstep, voffB);
;             PG8_WAIT_V(6); PG8_BAR; PG8_MMA(1, 1, At, B1); PG8_BAR;
;             PG8_LDB(B0, 1, 0); PG8_SCHED; PG8_LDA(At, 1, 0); PG8_STAGE(PG8_SA(0, 1), a2 + hstep, voffA);
;             PG8_WAIT_L(8); PG8_BAR; PG8_WAIT_L(0); PG8_MMA(0, 0, At, B0); PG8_BAR; PG8_SCHED;
;             PG8_LDB(B1, 1, 1); PG8_STAGE(PG8_SB(1, 0), b3, voffB);
;             PG8_BAR; PG8_WAIT_L(0); PG8_MMA(0, 1, At, B1); PG8_BAR;
;             PG8_LDA(At, 1, 1); PG8_STAGE(PG8_SA(1, 0), a3, voffA);
;             PG8_BAR; PG8_WAIT_L(0); PG8_MMA(1, 0, At, B0); PG8_BAR; PG8_SCHED;
;             PG8_STAGE(PG8_SB(1, 1), b3 + hstep, voffB);
;             PG8_WAIT_V(6); PG8_BAR; PG8_MMA(1, 1, At, B1); PG8_BAR;
	s_waitcnt lgkmcnt(0)
	s_setprio 1
	s_waitcnt lgkmcnt(0)
	v_mfma_f32_16x16x32_bf16 v[60:63], v[146:149], v[162:165], v[60:63]
	v_mfma_f32_16x16x32_bf16 v[56:59], v[154:157], v[162:165], v[56:59]
	v_mfma_f32_16x16x32_bf16 v[52:55], v[146:149], v[170:173], v[52:55]
	v_mfma_f32_16x16x32_bf16 v[44:47], v[154:157], v[170:173], v[44:47]
	v_mfma_f32_16x16x32_bf16 v[36:39], v[146:149], v[178:181], v[36:39]
	v_mfma_f32_16x16x32_bf16 v[28:31], v[154:157], v[178:181], v[28:31]
	v_mfma_f32_16x16x32_bf16 v[20:23], v[146:149], v[186:189], v[20:23]
	v_mfma_f32_16x16x32_bf16 v[12:15], v[154:157], v[186:189], v[12:15]
	v_mfma_f32_16x16x32_bf16 v[60:63], v[150:153], v[166:169], v[60:63]
	v_mfma_f32_16x16x32_bf16 v[56:59], v[158:161], v[166:169], v[56:59]
	v_mfma_f32_16x16x32_bf16 v[52:55], v[150:153], v[174:177], v[52:55]
	v_mfma_f32_16x16x32_bf16 v[44:47], v[158:161], v[174:177], v[44:47]
	v_mfma_f32_16x16x32_bf16 v[36:39], v[150:153], v[182:185], v[36:39]
	v_mfma_f32_16x16x32_bf16 v[28:31], v[158:161], v[182:185], v[28:31]
	v_mfma_f32_16x16x32_bf16 v[20:23], v[150:153], v[190:193], v[20:23]
	v_mfma_f32_16x16x32_bf16 v[12:15], v[158:161], v[190:193], v[12:15]
	s_setprio 0
	s_barrier
	s_add_u32 s24, s24, 0x40080
	s_addc_u32 s25, s25, 0
	s_add_i32 s26, s26, s34
	s_mov_b32 m0, s26
	s_nop 0
	global_load_lds_dwordx4 v130, s[24:25]
	s_add_i32 m0, s26, 0x2000
	s_nop 0
	global_load_lds_dwordx4 v134, s[24:25]
	s_waitcnt vmcnt(10)
	s_barrier
	s_setprio 1
	v_mfma_f32_16x16x32_bf16 v[48:51], v[194:197], v[162:165], v[48:51]
	v_mfma_f32_16x16x32_bf16 v[40:43], v[206:209], v[162:165], v[40:43]
	v_mfma_f32_16x16x32_bf16 v[32:35], v[194:197], v[170:173], v[32:35]
	v_mfma_f32_16x16x32_bf16 v[24:27], v[206:209], v[170:173], v[24:27]
	v_mfma_f32_16x16x32_bf16 v[16:19], v[194:197], v[178:181], v[16:19]
	v_mfma_f32_16x16x32_bf16 v[8:11], v[206:209], v[178:181], v[8:11]
	v_mfma_f32_16x16x32_bf16 v[4:7], v[194:197], v[186:189], v[4:7]
	v_mfma_f32_16x16x32_bf16 v[0:3], v[206:209], v[186:189], v[0:3]
	v_mfma_f32_16x16x32_bf16 v[48:51], v[202:205], v[166:169], v[48:51]
	v_mfma_f32_16x16x32_bf16 v[40:43], v[210:213], v[166:169], v[40:43]
	v_mfma_f32_16x16x32_bf16 v[32:35], v[202:205], v[174:177], v[32:35]
	v_mfma_f32_16x16x32_bf16 v[24:27], v[210:213], v[174:177], v[24:27]
	v_mfma_f32_16x16x32_bf16 v[16:19], v[202:205], v[182:185], v[16:19]
	v_mfma_f32_16x16x32_bf16 v[8:11], v[210:213], v[182:185], v[8:11]
	v_mfma_f32_16x16x32_bf16 v[4:7], v[202:205], v[190:193], v[4:7]
	v_mfma_f32_16x16x32_bf16 v[0:3], v[210:213], v[190:193], v[0:3]
	s_setprio 0
	s_add_i32 s58, s58, 2
	s_add_u32 s22, s22, 0x100
	s_addc_u32 s23, s23, 0
	s_add_u32 s56, s56, 0x100
	s_addc_u32 s57, s57, 0
	s_cmp_gt_u32 s58, 13
	s_barrier
.LBB0_713:
	ds_read_b128 v[146:149], v143
	ds_read_b128 v[150:153], v143 offset:1024
	ds_read_b128 v[154:157], v143 offset:2048
	ds_read_b128 v[158:161], v143 offset:3072
	s_add_u32 s24, s22, 0xfffc0080
	s_addc_u32 s25, s23, -1
	s_cmp_eq_u32 s58, 12
	s_cselect_b32 s27, s15, s25
	s_cselect_b32 s26, s54, s24
	s_cselect_b32 s25, s13, s57
	s_cselect_b32 s24, s55, s56
	s_add_i32 m0, s21, 0xc000
	ds_read_b128 v[162:165], v144
	ds_read_b128 v[166:169], v144 offset:1024
	ds_read_b128 v[170:173], v144 offset:2048
	ds_read_b128 v[174:177], v144 offset:3072
	ds_read_b128 v[178:181], v144 offset:4096
	ds_read_b128 v[182:185], v144 offset:5120
	ds_read_b128 v[186:189], v144 offset:6144
	ds_read_b128 v[190:193], v144 offset:7168
	global_load_lds_dwordx4 v136, s[22:23]
	s_add_i32 m0, s21, 0xe000
	s_nop 0
	global_load_lds_dwordx4 v138, s[22:23]
	s_waitcnt lgkmcnt(8)
	s_waitcnt vmcnt(10)
	s_barrier
	s_waitcnt lgkmcnt(0)
	s_setprio 1
	s_waitcnt lgkmcnt(0)
	v_mfma_f32_16x16x32_bf16 v[124:127], v[146:149], v[162:165], v[124:127]
	v_mfma_f32_16x16x32_bf16 v[120:123], v[154:157], v[162:165], v[120:123]
	v_mfma_f32_16x16x32_bf16 v[116:119], v[146:149], v[170:173], v[116:119]
	v_mfma_f32_16x16x32_bf16 v[108:111], v[154:157], v[170:173], v[108:111]
	v_mfma_f32_16x16x32_bf16 v[100:103], v[146:149], v[178:181], v[100:103]
	v_mfma_f32_16x16x32_bf16 v[92:95], v[154:157], v[178:181], v[92:95]
	v_mfma_f32_16x16x32_bf16 v[84:87], v[146:149], v[186:189], v[84:87]
	v_mfma_f32_16x16x32_bf16 v[76:79], v[154:157], v[186:189], v[76:79]
	v_mfma_f32_16x16x32_bf16 v[124:127], v[150:153], v[166:169], v[124:127]
	v_mfma_f32_16x16x32_bf16 v[120:123], v[158:161], v[166:169], v[120:123]
	v_mfma_f32_16x16x32_bf16 v[116:119], v[150:153], v[174:177], v[116:119]
	v_mfma_f32_16x16x32_bf16 v[108:111], v[158:161], v[174:177], v[108:111]
	v_mfma_f32_16x16x32_bf16 v[100:103], v[150:153], v[182:185], v[100:103]
	v_mfma_f32_16x16x32_bf16 v[92:95], v[158:161], v[182:185], v[92:95]
	v_mfma_f32_16x16x32_bf16 v[84:87], v[150:153], v[190:193], v[84:87]
	v_mfma_f32_16x16x32_bf16 v[76:79], v[158:161], v[190:193], v[76:79]
	s_setprio 0
	s_barrier
	s_add_i32 s59, s46, s34
	s_mov_b32 m0, s59
	ds_read_b128 v[194:197], v145
	ds_read_b128 v[202:205], v145 offset:1024
	ds_read_b128 v[206:209], v145 offset:2048
	ds_read_b128 v[210:213], v145 offset:3072
	global_load_lds_dwordx4 v130, s[24:25]
	s_add_i32 m0, s59, 0x2000
	s_nop 0
	global_load_lds_dwordx4 v134, s[24:25]
	s_waitcnt vmcnt(10)
	s_barrier
; #define PG8_STAGE(bufoff, gbase, voff) do { _Pragma("unroll") for (int _i = 0; _i < 2; ++_i) \
;         __builtin_amdgcn_global_load_lds((const unsigned*)((const char*)(gbase) + (voff)[_i]), (LAS unsigned*)(lds + (bufoff) + ldsw + _i * 8192), 16, 0, 0); } while (0)
; #define PG8_LDA(dst, b, h) do { _Pragma("unroll") for (int m = 0; m < 4; ++m) _Pragma("unroll") for (int k = 0; k < 2; ++k) dst[m][k] = *(const LAS bf16x8*)(lds + PG8_SA(b, h) + aoff + m * 2048 + k * 1024); } while (0)
; #define PG8_LDB(dst, b, h) do { _Pragma("unroll") for (int n = 0; n < 2; ++n) _Pragma("unroll") for (int k = 0; k < 2; ++k) dst[n][k] = *(const LAS bf16x8*)(lds + PG8_SB(b, h) + boff + n * 2048 + k * 1024); } while (0)
; #define PG8_WAIT_V(n) asm volatile("s_waitcnt vmcnt(" #n ")" ::: "memory")
; #define PG8_WAIT_L(n) asm volatile("s_waitcnt lgkmcnt(" #n ")" ::: "memory")
; #define PG8_BAR __builtin_amdgcn_s_barrier()
; #define PG8_SCHED __builtin_amdgcn_sched_barrier(0)
; template <class Epi, class Sched>
; __device__ __forceinline__ void gemm_phase(LAS unsigned char* lds, const Gemm g, const Sched& S, const Epi& E) {
;     ...
;             PG8_LDB(B0, 0, 0); PG8_SCHED; PG8_LDA(At, 0, 0); PG8_STAGE(PG8_SA(1, 1), a1 + hstep, voffA);
;             PG8_WAIT_L(8); PG8_BAR; PG8_WAIT_L(0); PG8_MMA(0, 0, At, B0); PG8_BAR; PG8_SCHED;
;             PG8_LDB(B1, 0, 1); PG8_STAGE(PG8_SB(0, 0), b2, voffB);
;             PG8_BAR; PG8_WAIT_L(0); PG8_MMA(0, 1, At, B1); PG8_BAR;
;             PG8_LDA(At, 0, 1); PG8_STAGE(PG8_SA(0, 0), a2, voffA);
;             PG8_BAR; PG8_WAIT_L(0); PG8_MMA(1, 0, At, B0); PG8_BAR; PG8_SCHED;
;             PG8_STAGE(PG8_SB(0, 1), b2 + hstep, voffB);
;             PG8_WAIT_V(6); PG8_BAR; PG8_MMA(1, 1, At, B1); PG8_BAR;
;             PG8_LDB(B0, 1, 0); PG8_SCHED; PG8_LDA(At, 1, 0); PG8_STAGE(PG8_SA(0, 1), a2 + hstep, voffA);
;             PG8_WAIT_L(8); PG8_BAR; PG8_WAIT_L(0); PG8_MMA(0, 0, At, B0); PG8_BAR; PG8_SCHED;
;             PG8_LDB(B1, 1, 1); PG8_STAGE(PG8_SB(1, 0), b3, voffB);
;             PG8_BAR; PG8_WAIT_L(0); PG8_MMA(0, 1, At, B1); PG8_BAR;
;             PG8_LDA(At, 1, 1); PG8_STAGE(PG8_SA(1, 0), a3, voffA);
;             PG8_BAR; PG8_WAIT_L(0); PG8_MMA(1, 0, At, B0); PG8_BAR; PG8_SCHED;
;             PG8_STAGE(PG8_SB(1, 1), b3 + hstep, voffB);
;             PG8_WAIT_V(6); PG8_BAR; PG8_MMA(1, 1, At, B1); PG8_BAR;
	s_waitcnt lgkmcnt(0)
	s_setprio 1
	s_waitcnt lgkmcnt(0)
	v_mfma_f32_16x16x32_bf16 v[112:115], v[194:197], v[162:165], v[112:115]
	v_mfma_f32_16x16x32_bf16 v[104:107], v[206:209], v[162:165], v[104:107]
	v_mfma_f32_16x16x32_bf16 v[96:99], v[194:197], v[170:173], v[96:99]
	v_mfma_f32_16x16x32_bf16 v[88:91], v[206:209], v[170:173], v[88:91]
	v_mfma_f32_16x16x32_bf16 v[80:83], v[194:197], v[178:181], v[80:83]
	v_mfma_f32_16x16x32_bf16 v[72:75], v[206:209], v[178:181], v[72:75]
	v_mfma_f32_16x16x32_bf16 v[68:71], v[194:197], v[186:189], v[68:71]
	v_mfma_f32_16x16x32_bf16 v[64:67], v[206:209], v[186:189], v[64:67]
	v_mfma_f32_16x16x32_bf16 v[112:115], v[202:205], v[166:169], v[112:115]
	v_mfma_f32_16x16x32_bf16 v[104:107], v[210:213], v[166:169], v[104:107]
	v_mfma_f32_16x16x32_bf16 v[96:99], v[202:205], v[174:177], v[96:99]
	v_mfma_f32_16x16x32_bf16 v[88:91], v[210:213], v[174:177], v[88:91]
	v_mfma_f32_16x16x32_bf16 v[80:83], v[202:205], v[182:185], v[80:83]
	v_mfma_f32_16x16x32_bf16 v[72:75], v[210:213], v[182:185], v[72:75]
	v_mfma_f32_16x16x32_bf16 v[68:71], v[202:205], v[190:193], v[68:71]
	v_mfma_f32_16x16x32_bf16 v[64:67], v[210:213], v[190:193], v[64:67]
	s_setprio 0
	s_mov_b32 m0, s21
	v_lshl_add_u64 v[216:217], s[26:27], 0, v[128:129]
	s_barrier
	ds_read_b128 v[162:165], v144 offset:16384
	ds_read_b128 v[166:169], v144 offset:17408
	ds_read_b128 v[170:173], v144 offset:18432
	ds_read_b128 v[174:177], v144 offset:19456
	ds_read_b128 v[178:181], v144 offset:20480
	ds_read_b128 v[182:185], v144 offset:21504
	ds_read_b128 v[186:189], v144 offset:22528
	ds_read_b128 v[190:193], v144 offset:23552
	global_load_lds_dwordx4 v128, s[26:27]
	v_lshl_add_u64 v[218:219], s[26:27], 0, v[132:133]
	s_mov_b32 m0, s35
	s_nop 0
	global_load_lds_dwordx4 v132, s[26:27]
	s_barrier
	s_waitcnt lgkmcnt(0)
	s_setprio 1
	s_waitcnt lgkmcnt(0)
	v_mfma_f32_16x16x32_bf16 v[60:63], v[146:149], v[162:165], v[60:63]
	v_mfma_f32_16x16x32_bf16 v[56:59], v[154:157], v[162:165], v[56:59]
	v_mfma_f32_16x16x32_bf16 v[52:55], v[146:149], v[170:173], v[52:55]
	v_mfma_f32_16x16x32_bf16 v[44:47], v[154:157], v[170:173], v[44:47]
	v_mfma_f32_16x16x32_bf16 v[36:39], v[146:149], v[178:181], v[36:39]
	v_mfma_f32_16x16x32_bf16 v[28:31], v[154:157], v[178:181], v[28:31]
	v_mfma_f32_16x16x32_bf16 v[20:23], v[146:149], v[186:189], v[20:23]
	v_mfma_f32_16x16x32_bf16 v[12:15], v[154:157], v[186:189], v[12:15]
	v_mfma_f32_16x16x32_bf16 v[60:63], v[150:153], v[166:169], v[60:63]
	v_mfma_f32_16x16x32_bf16 v[56:59], v[158:161], v[166:169], v[56:59]
	v_mfma_f32_16x16x32_bf16 v[52:55], v[150:153], v[174:177], v[52:55]
	v_mfma_f32_16x16x32_bf16 v[44:47], v[158:161], v[174:177], v[44:47]
	v_mfma_f32_16x16x32_bf16 v[36:39], v[150:153], v[182:185], v[36:39]
	v_mfma_f32_16x16x32_bf16 v[28:31], v[158:161], v[182:185], v[28:31]
	v_mfma_f32_16x16x32_bf16 v[20:23], v[150:153], v[190:193], v[20:23]
	v_mfma_f32_16x16x32_bf16 v[12:15], v[158:161], v[190:193], v[12:15]
	s_setprio 0
	s_barrier
	s_add_u32 s60, s24, 0x40000
	s_addc_u32 s61, s25, 0
	s_add_i32 s59, s47, s34
	s_mov_b32 m0, s59
	s_nop 0
	global_load_lds_dwordx4 v130, s[60:61]
	s_add_i32 m0, s59, 0x2000
	s_nop 0
	global_load_lds_dwordx4 v134, s[60:61]
	s_waitcnt vmcnt(10)
	s_barrier
	s_setprio 1
	v_mfma_f32_16x16x32_bf16 v[48:51], v[194:197], v[162:165], v[48:51]
	v_mfma_f32_16x16x32_bf16 v[40:43], v[206:209], v[162:165], v[40:43]
	v_mfma_f32_16x16x32_bf16 v[32:35], v[194:197], v[170:173], v[32:35]
	v_mfma_f32_16x16x32_bf16 v[24:27], v[206:209], v[170:173], v[24:27]
	v_mfma_f32_16x16x32_bf16 v[16:19], v[194:197], v[178:181], v[16:19]
	v_mfma_f32_16x16x32_bf16 v[8:11], v[206:209], v[178:181], v[8:11]
	v_mfma_f32_16x16x32_bf16 v[4:7], v[194:197], v[186:189], v[4:7]
	v_mfma_f32_16x16x32_bf16 v[0:3], v[206:209], v[186:189], v[0:3]
	v_mfma_f32_16x16x32_bf16 v[48:51], v[202:205], v[166:169], v[48:51]
	v_mfma_f32_16x16x32_bf16 v[40:43], v[210:213], v[166:169], v[40:43]
	v_mfma_f32_16x16x32_bf16 v[32:35], v[202:205], v[174:177], v[32:35]
	v_mfma_f32_16x16x32_bf16 v[24:27], v[210:213], v[174:177], v[24:27]
	v_mfma_f32_16x16x32_bf16 v[16:19], v[202:205], v[182:185], v[16:19]
	v_mfma_f32_16x16x32_bf16 v[8:11], v[210:213], v[182:185], v[8:11]
	v_mfma_f32_16x16x32_bf16 v[4:7], v[202:205], v[190:193], v[4:7]
	v_mfma_f32_16x16x32_bf16 v[0:3], v[210:213], v[190:193], v[0:3]
	s_setprio 0
	s_add_i32 s59, 0, 0x18000
	v_add_u32_e32 v158, s59, v142
	s_barrier
	ds_read_b128 v[146:149], v158
	ds_read_b128 v[150:153], v158 offset:1024
	ds_read_b128 v[154:157], v158 offset:2048
	ds_read_b128 v[158:161], v158 offset:3072
	s_add_u32 s26, s26, 0x40000
	s_addc_u32 s27, s27, 0
	s_mov_b32 m0, s36
	ds_read_b128 v[162:165], v144 offset:32768
	ds_read_b128 v[166:169], v144 offset:33792
	ds_read_b128 v[170:173], v144 offset:34816
	ds_read_b128 v[174:177], v144 offset:35840
	ds_read_b128 v[178:181], v144 offset:36864
	ds_read_b128 v[182:185], v144 offset:37888
	ds_read_b128 v[186:189], v144 offset:38912
	ds_read_b128 v[190:193], v144 offset:39936
	global_load_lds_dwordx4 v128, s[26:27]
	s_mov_b32 m0, s37
	s_nop 0
	global_load_lds_dwordx4 v132, s[26:27]
	s_waitcnt lgkmcnt(8)
	s_waitcnt vmcnt(10)
	s_barrier
; #define PG8_STAGE(bufoff, gbase, voff) do { _Pragma("unroll") for (int _i = 0; _i < 2; ++_i) \
;         __builtin_amdgcn_global_load_lds((const unsigned*)((const char*)(gbase) + (voff)[_i]), (LAS unsigned*)(lds + (bufoff) + ldsw + _i * 8192), 16, 0, 0); } while (0)
; #define PG8_LDA(dst, b, h) do { _Pragma("unroll") for (int m = 0; m < 4; ++m) _Pragma("unroll") for (int k = 0; k < 2; ++k) dst[m][k] = *(const LAS bf16x8*)(lds + PG8_SA(b, h) + aoff + m * 2048 + k * 1024); } while (0)
; #define PG8_LDB(dst, b, h) do { _Pragma("unroll") for (int n = 0; n < 2; ++n) _Pragma("unroll") for (int k = 0; k < 2; ++k) dst[n][k] = *(const LAS bf16x8*)(lds + PG8_SB(b, h) + boff + n * 2048 + k * 1024); } while (0)
; #define PG8_WAIT_V(n) asm volatile("s_waitcnt vmcnt(" #n ")" ::: "memory")
; #define PG8_WAIT_L(n) asm volatile("s_waitcnt lgkmcnt(" #n ")" ::: "memory")
; #define PG8_BAR __builtin_amdgcn_s_barrier()
; #define PG8_SCHED __builtin_amdgcn_sched_barrier(0)
; template <class Epi, class Sched>
; __device__ __forceinline__ void gemm_phase(LAS unsigned char* lds, const Gemm g, const Sched& S, const Epi& E) {
;     ...
;             PG8_LDB(B0, 0, 0); PG8_SCHED; PG8_LDA(At, 0, 0); PG8_STAGE(PG8_SA(1, 1), a1 + hstep, voffA);
;             PG8_WAIT_L(8); PG8_BAR; PG8_WAIT_L(0); PG8_MMA(0, 0, At, B0); PG8_BAR; PG8_SCHED;
;             PG8_LDB(B1, 0, 1); PG8_STAGE(PG8_SB(0, 0), b2, voffB);
;             PG8_BAR; PG8_WAIT_L(0); PG8_MMA(0, 1, At, B1); PG8_BAR;
;             PG8_LDA(At, 0, 1); PG8_STAGE(PG8_SA(0, 0), a2, voffA);
;             PG8_BAR; PG8_WAIT_L(0); PG8_MMA(1, 0, At, B0); PG8_BAR; PG8_SCHED;
;             PG8_STAGE(PG8_SB(0, 1), b2 + hstep, voffB);
;             PG8_WAIT_V(6); PG8_BAR; PG8_MMA(1, 1, At, B1); PG8_BAR;
;             PG8_LDB(B0, 1, 0); PG8_SCHED; PG8_LDA(At, 1, 0); PG8_STAGE(PG8_SA(0, 1), a2 + hstep, voffA);
;             PG8_WAIT_L(8); PG8_BAR; PG8_WAIT_L(0); PG8_MMA(0, 0, At, B0); PG8_BAR; PG8_SCHED;
;             PG8_LDB(B1, 1, 1); PG8_STAGE(PG8_SB(1, 0), b3, voffB);
;             PG8_BAR; PG8_WAIT_L(0); PG8_MMA(0, 1, At, B1); PG8_BAR;
;             PG8_LDA(At, 1, 1); PG8_STAGE(PG8_SA(1, 0), a3, voffA);
;             PG8_BAR; PG8_WAIT_L(0); PG8_MMA(1, 0, At, B0); PG8_BAR; PG8_SCHED;
;             PG8_STAGE(PG8_SB(1, 1), b3 + hstep, voffB);
;             PG8_WAIT_V(6); PG8_BAR; PG8_MMA(1, 1, At, B1); PG8_BAR;
	s_waitcnt lgkmcnt(0)
	s_setprio 1
	s_waitcnt lgkmcnt(0)
	v_mfma_f32_16x16x32_bf16 v[124:127], v[146:149], v[162:165], v[124:127]
	v_mfma_f32_16x16x32_bf16 v[120:123], v[154:157], v[162:165], v[120:123]
	v_mfma_f32_16x16x32_bf16 v[116:119], v[146:149], v[170:173], v[116:119]
	v_mfma_f32_16x16x32_bf16 v[108:111], v[154:157], v[170:173], v[108:111]
	v_mfma_f32_16x16x32_bf16 v[100:103], v[146:149], v[178:181], v[100:103]
	v_mfma_f32_16x16x32_bf16 v[92:95], v[154:157], v[178:181], v[92:95]
	v_mfma_f32_16x16x32_bf16 v[84:87], v[146:149], v[186:189], v[84:87]
	v_mfma_f32_16x16x32_bf16 v[76:79], v[154:157], v[186:189], v[76:79]
	v_mfma_f32_16x16x32_bf16 v[124:127], v[150:153], v[166:169], v[124:127]
	v_mfma_f32_16x16x32_bf16 v[120:123], v[158:161], v[166:169], v[120:123]
	v_mfma_f32_16x16x32_bf16 v[116:119], v[150:153], v[174:177], v[116:119]
	v_mfma_f32_16x16x32_bf16 v[108:111], v[158:161], v[174:177], v[108:111]
	v_mfma_f32_16x16x32_bf16 v[100:103], v[150:153], v[182:185], v[100:103]
	v_mfma_f32_16x16x32_bf16 v[92:95], v[158:161], v[182:185], v[92:95]
	v_mfma_f32_16x16x32_bf16 v[84:87], v[150:153], v[190:193], v[84:87]
	v_mfma_f32_16x16x32_bf16 v[76:79], v[158:161], v[190:193], v[76:79]
	s_setprio 0
	s_barrier
	s_add_i32 s26, 0, 0x1c000
	s_add_i32 s27, s59, s34
	v_add_u32_e32 v210, s26, v142
	s_add_u32 s0, s24, 0x80
	s_addc_u32 s1, s25, 0
	s_mov_b32 m0, s27
	ds_read_b128 v[194:197], v210
	ds_read_b128 v[202:205], v210 offset:1024
	ds_read_b128 v[206:209], v210 offset:2048
	ds_read_b128 v[210:213], v210 offset:3072
	global_load_lds_dwordx4 v130, s[0:1]
	s_add_i32 m0, s27, 0x2000
	s_nop 0
	global_load_lds_dwordx4 v134, s[0:1]
	s_waitcnt vmcnt(10)
	s_barrier
	s_waitcnt lgkmcnt(0)
	s_setprio 1
	s_waitcnt lgkmcnt(0)
	v_mfma_f32_16x16x32_bf16 v[112:115], v[194:197], v[162:165], v[112:115]
	v_mfma_f32_16x16x32_bf16 v[104:107], v[206:209], v[162:165], v[104:107]
	v_mfma_f32_16x16x32_bf16 v[96:99], v[194:197], v[170:173], v[96:99]
	v_mfma_f32_16x16x32_bf16 v[88:91], v[206:209], v[170:173], v[88:91]
	v_mfma_f32_16x16x32_bf16 v[80:83], v[194:197], v[178:181], v[80:83]
	v_mfma_f32_16x16x32_bf16 v[72:75], v[206:209], v[178:181], v[72:75]
	v_mfma_f32_16x16x32_bf16 v[68:71], v[194:197], v[186:189], v[68:71]
	v_mfma_f32_16x16x32_bf16 v[64:67], v[206:209], v[186:189], v[64:67]
	v_mfma_f32_16x16x32_bf16 v[112:115], v[202:205], v[166:169], v[112:115]
	v_mfma_f32_16x16x32_bf16 v[104:107], v[210:213], v[166:169], v[104:107]
	v_mfma_f32_16x16x32_bf16 v[96:99], v[202:205], v[174:177], v[96:99]
	v_mfma_f32_16x16x32_bf16 v[88:91], v[210:213], v[174:177], v[88:91]
	v_mfma_f32_16x16x32_bf16 v[80:83], v[202:205], v[182:185], v[80:83]
	v_mfma_f32_16x16x32_bf16 v[72:75], v[210:213], v[182:185], v[72:75]
	v_mfma_f32_16x16x32_bf16 v[68:71], v[202:205], v[190:193], v[68:71]
	v_mfma_f32_16x16x32_bf16 v[64:67], v[210:213], v[190:193], v[64:67]
	s_setprio 0
	s_mov_b32 m0, s43
	s_mov_b64 s[0:1], 0x80
	v_lshl_add_u64 v[198:199], v[216:217], 0, s[0:1]
	s_barrier
	ds_read_b128 v[162:165], v144 offset:49152
	ds_read_b128 v[166:169], v144 offset:50176
	ds_read_b128 v[170:173], v144 offset:51200
	ds_read_b128 v[174:177], v144 offset:52224
	ds_read_b128 v[178:181], v144 offset:53248
	ds_read_b128 v[182:185], v144 offset:54272
	ds_read_b128 v[186:189], v144 offset:55296
	ds_read_b128 v[190:193], v144 offset:56320
	global_load_lds_dwordx4 v[198:199], off
	v_lshl_add_u64 v[198:199], v[218:219], 0, s[0:1]
	s_mov_b32 m0, s44
	s_nop 0
	global_load_lds_dwordx4 v[198:199], off
	s_barrier
	s_waitcnt lgkmcnt(0)
	s_setprio 1
	s_waitcnt lgkmcnt(0)
	v_mfma_f32_16x16x32_bf16 v[60:63], v[146:149], v[162:165], v[60:63]
	v_mfma_f32_16x16x32_bf16 v[56:59], v[154:157], v[162:165], v[56:59]
	v_mfma_f32_16x16x32_bf16 v[52:55], v[146:149], v[170:173], v[52:55]
	v_mfma_f32_16x16x32_bf16 v[44:47], v[154:157], v[170:173], v[44:47]
	v_mfma_f32_16x16x32_bf16 v[36:39], v[146:149], v[178:181], v[36:39]
	v_mfma_f32_16x16x32_bf16 v[28:31], v[154:157], v[178:181], v[28:31]
	v_mfma_f32_16x16x32_bf16 v[20:23], v[146:149], v[186:189], v[20:23]
	v_mfma_f32_16x16x32_bf16 v[12:15], v[154:157], v[186:189], v[12:15]
	v_mfma_f32_16x16x32_bf16 v[60:63], v[150:153], v[166:169], v[60:63]
	v_mfma_f32_16x16x32_bf16 v[56:59], v[158:161], v[166:169], v[56:59]
	v_mfma_f32_16x16x32_bf16 v[52:55], v[150:153], v[174:177], v[52:55]
	v_mfma_f32_16x16x32_bf16 v[44:47], v[158:161], v[174:177], v[44:47]
	v_mfma_f32_16x16x32_bf16 v[36:39], v[150:153], v[182:185], v[36:39]
	v_mfma_f32_16x16x32_bf16 v[28:31], v[158:161], v[182:185], v[28:31]
	v_mfma_f32_16x16x32_bf16 v[20:23], v[150:153], v[190:193], v[20:23]
	v_mfma_f32_16x16x32_bf16 v[12:15], v[158:161], v[190:193], v[12:15]
	s_setprio 0
	s_barrier
	s_add_u32 s24, s24, 0x40080
	s_addc_u32 s25, s25, 0
	s_add_i32 s26, s26, s34
	s_mov_b32 m0, s26
	s_nop 0
	global_load_lds_dwordx4 v130, s[24:25]
	s_add_i32 m0, s26, 0x2000
	s_nop 0
	global_load_lds_dwordx4 v134, s[24:25]
	s_waitcnt vmcnt(10)
	s_barrier
; __device__ __forceinline__ unsigned cvt_pk_bf16(float lo, float hi) { unsigned r; asm volatile("v_cvt_pk_bf16_f32 %0, %1, %2" : "=v"(r) : "v"(lo), "v"(hi)); return r; }
; #define PG8_WAIT_V(n) asm volatile("s_waitcnt vmcnt(" #n ")" ::: "memory")
; #define PG8_BAR __builtin_amdgcn_s_barrier()
; template <class Epi, class Sched>
; __device__ __forceinline__ void gemm_phase(LAS unsigned char* lds, const Gemm g, const Sched& S, const Epi& E) {
;     ...
;     PG8_WAIT_V(0);
;     if (wr == 0) PG8_BAR;
;     PG8_BAR;
;     __device__ __forceinline__ void operator()(const AccT& acc, const Unit& u, int wr, int wc, int fr, int fq) const {
;     ...
;         const int rbase = u.pm * 256 + wr * 64 + fr;
;         const int tb = u.pn * 256 + wc * 32 + 8 * fq;
; #pragma unroll
;         for (int ai = 0; ai < 2; ++ai)
; #pragma unroll
;             for (int m = 0; m < 4; ++m) {
;                 const int r = rbase + ai * 128 + m * 16;
; #pragma unroll
;                 for (int bj = 0; bj < 2; ++bj) {
;                     const int t0 = tb + bj * 128;
;                     const f32x4 v0 = acc[ai][bj][m][0], v1 = acc[ai][bj][m][1];
;                     u32x4 w; w.x = cvt_pk_bf16(v0[0], v0[1]); w.y = cvt_pk_bf16(v0[2], v0[3]); w.z = cvt_pk_bf16(v1[0], v1[1]); w.w = cvt_pk_bf16(v1[2], v1[3]);
;                     *(u32x4*)(VT + (size_t)r * NT + t0) = w;
;                 }
	s_setprio 1
	v_mfma_f32_16x16x32_bf16 v[48:51], v[194:197], v[162:165], v[48:51]
	v_mfma_f32_16x16x32_bf16 v[40:43], v[206:209], v[162:165], v[40:43]
	v_mfma_f32_16x16x32_bf16 v[32:35], v[194:197], v[170:173], v[32:35]
	v_mfma_f32_16x16x32_bf16 v[24:27], v[206:209], v[170:173], v[24:27]
	v_mfma_f32_16x16x32_bf16 v[16:19], v[194:197], v[178:181], v[16:19]
	v_mfma_f32_16x16x32_bf16 v[8:11], v[206:209], v[178:181], v[8:11]
	v_mfma_f32_16x16x32_bf16 v[4:7], v[194:197], v[186:189], v[4:7]
	v_mfma_f32_16x16x32_bf16 v[0:3], v[206:209], v[186:189], v[0:3]
	v_mfma_f32_16x16x32_bf16 v[48:51], v[202:205], v[166:169], v[48:51]
	v_mfma_f32_16x16x32_bf16 v[40:43], v[210:213], v[166:169], v[40:43]
	v_mfma_f32_16x16x32_bf16 v[32:35], v[202:205], v[174:177], v[32:35]
	v_mfma_f32_16x16x32_bf16 v[24:27], v[210:213], v[174:177], v[24:27]
	v_mfma_f32_16x16x32_bf16 v[16:19], v[202:205], v[182:185], v[16:19]
	v_mfma_f32_16x16x32_bf16 v[8:11], v[210:213], v[182:185], v[8:11]
	v_mfma_f32_16x16x32_bf16 v[4:7], v[202:205], v[190:193], v[4:7]
	v_mfma_f32_16x16x32_bf16 v[0:3], v[210:213], v[190:193], v[0:3]
	s_setprio 0
	s_add_i32 s58, s58, 2
	s_add_u32 s22, s22, 0x100
	s_addc_u32 s23, s23, 0
	s_add_u32 s56, s56, 0x100
	s_addc_u32 s57, s57, 0
	s_cmp_gt_u32 s58, 13
	s_barrier
	s_cbranch_scc0 .LBB0_713
	v_mov_b32_e32 v146, v140
	v_mov_b32_e32 v147, v141
	s_lshl_b32 s13, s20, 8
	s_add_i32 s13, s13, s41
	v_add_u32_e32 v146, s13, v146
	s_lshl_b32 s13, s53, 8
	s_or_b32 s13, s13, s42
	v_lshl_add_u32 v148, v147, 3, s13
	v_ashrrev_i32_e32 v147, 31, v146
	v_cvt_pk_bf16_f32 v124, v124, v125
	v_cvt_pk_bf16_f32 v125, v126, v127
	v_cvt_pk_bf16_f32 v126, v120, v121
	v_lshlrev_b64 v[120:121], 14, v[146:147]
	v_lshl_add_u64 v[120:121], s[62:63], 0, v[120:121]
	v_ashrrev_i32_e32 v149, 31, v148
	v_lshl_add_u64 v[120:121], v[148:149], 1, v[120:121]
	s_mov_b32 s13, 0x40000
	v_cvt_pk_bf16_f32 v127, v122, v123
	global_store_dwordx4 v[120:121], v[124:127], off
	v_cvt_pk_bf16_f32 v112, v112, v113
	v_cvt_pk_bf16_f32 v113, v114, v115
	v_cvt_pk_bf16_f32 v114, v104, v105
	v_cvt_pk_bf16_f32 v115, v106, v107
	global_store_dwordx4 v[120:121], v[112:115], off offset:256
	v_cvt_pk_bf16_f32 v104, v116, v117
	v_cvt_pk_bf16_f32 v105, v118, v119
	v_cvt_pk_bf16_f32 v106, v108, v109
	v_cvt_pk_bf16_f32 v107, v110, v111
	s_mov_b64 s[22:23], 0x40000
	v_add_co_u32_e32 v110, vcc, s13, v120
	v_lshl_add_u64 v[108:109], v[120:121], 0, s[22:23]
	s_nop 0
	v_addc_co_u32_e32 v111, vcc, 0, v121, vcc
	s_mov_b32 s13, 0x80000
	global_store_dwordx4 v[110:111], v[104:107], off
	v_cvt_pk_bf16_f32 v96, v96, v97
	v_cvt_pk_bf16_f32 v97, v98, v99
	v_cvt_pk_bf16_f32 v98, v88, v89
	v_cvt_pk_bf16_f32 v99, v90, v91
	global_store_dwordx4 v[108:109], v[96:99], off offset:256
	v_cvt_pk_bf16_f32 v88, v100, v101
	v_cvt_pk_bf16_f32 v89, v102, v103
	v_cvt_pk_bf16_f32 v90, v92, v93
	v_cvt_pk_bf16_f32 v91, v94, v95
	s_mov_b64 s[22:23], 0x80000
	v_add_co_u32_e32 v94, vcc, s13, v120
	v_lshl_add_u64 v[92:93], v[120:121], 0, s[22:23]
	s_nop 0
	v_addc_co_u32_e32 v95, vcc, 0, v121, vcc
	global_store_dwordx4 v[94:95], v[88:91], off
	v_cvt_pk_bf16_f32 v80, v80, v81
	v_cvt_pk_bf16_f32 v81, v82, v83
	v_cvt_pk_bf16_f32 v82, v72, v73
	v_cvt_pk_bf16_f32 v83, v74, v75
	global_store_dwordx4 v[92:93], v[80:83], off offset:256
	v_cvt_pk_bf16_f32 v72, v84, v85
	v_cvt_pk_bf16_f32 v73, v86, v87
	v_cvt_pk_bf16_f32 v74, v76, v77
	v_cvt_pk_bf16_f32 v75, v78, v79
	s_mov_b64 s[22:23], 0xc0000
	v_add_co_u32_e32 v78, vcc, s48, v120
	v_lshl_add_u64 v[76:77], v[120:121], 0, s[22:23]
	s_nop 0
	v_addc_co_u32_e32 v79, vcc, 0, v121, vcc
	global_store_dwordx4 v[78:79], v[72:75], off
	v_cvt_pk_bf16_f32 v68, v68, v69
	v_cvt_pk_bf16_f32 v69, v70, v71
	v_cvt_pk_bf16_f32 v70, v64, v65
	v_cvt_pk_bf16_f32 v71, v66, v67
	global_store_dwordx4 v[76:77], v[68:71], off offset:256
	v_cvt_pk_bf16_f32 v60, v60, v61
	v_cvt_pk_bf16_f32 v61, v62, v63
	v_cvt_pk_bf16_f32 v62, v56, v57
	v_cvt_pk_bf16_f32 v63, v58, v59
	v_add_co_u32_e32 v58, vcc, s49, v120
	v_lshl_add_u64 v[56:57], v[120:121], 0, s[2:3]
	s_nop 0
	v_addc_co_u32_e32 v59, vcc, 0, v121, vcc
	global_store_dwordx4 v[58:59], v[60:63], off
	v_cvt_pk_bf16_f32 v48, v48, v49
	v_cvt_pk_bf16_f32 v49, v50, v51
	v_cvt_pk_bf16_f32 v50, v40, v41
	v_cvt_pk_bf16_f32 v51, v42, v43
	global_store_dwordx4 v[56:57], v[48:51], off offset:256
	v_cvt_pk_bf16_f32 v40, v52, v53
	v_cvt_pk_bf16_f32 v41, v54, v55
	v_cvt_pk_bf16_f32 v42, v44, v45
	v_cvt_pk_bf16_f32 v43, v46, v47
	v_add_co_u32_e32 v46, vcc, s50, v120
	v_lshl_add_u64 v[44:45], v[120:121], 0, s[4:5]
	s_nop 0
	v_addc_co_u32_e32 v47, vcc, 0, v121, vcc
	global_store_dwordx4 v[46:47], v[40:43], off
	v_cvt_pk_bf16_f32 v32, v32, v33
	v_cvt_pk_bf16_f32 v33, v34, v35
	v_cvt_pk_bf16_f32 v34, v24, v25
	v_cvt_pk_bf16_f32 v35, v26, v27
	global_store_dwordx4 v[44:45], v[32:35], off offset:256
	v_cvt_pk_bf16_f32 v24, v36, v37
	v_cvt_pk_bf16_f32 v25, v38, v39
	v_cvt_pk_bf16_f32 v26, v28, v29
	v_cvt_pk_bf16_f32 v27, v30, v31
	v_add_co_u32_e32 v30, vcc, s51, v120
	v_lshl_add_u64 v[28:29], v[120:121], 0, s[6:7]
	s_nop 0
	v_addc_co_u32_e32 v31, vcc, 0, v121, vcc
	global_store_dwordx4 v[30:31], v[24:27], off
	v_cvt_pk_bf16_f32 v16, v16, v17
	v_cvt_pk_bf16_f32 v17, v18, v19
	v_cvt_pk_bf16_f32 v18, v8, v9
	v_cvt_pk_bf16_f32 v19, v10, v11
	global_store_dwordx4 v[28:29], v[16:19], off offset:256
	v_cvt_pk_bf16_f32 v8, v20, v21
	v_cvt_pk_bf16_f32 v9, v22, v23
	v_cvt_pk_bf16_f32 v10, v12, v13
	v_cvt_pk_bf16_f32 v11, v14, v15
	v_add_co_u32_e32 v14, vcc, s52, v120
	v_lshl_add_u64 v[12:13], v[120:121], 0, s[8:9]
	s_nop 0
	v_addc_co_u32_e32 v15, vcc, 0, v121, vcc
	s_and_b64 vcc, exec, s[10:11]
	s_mov_b32 s53, s12
	s_mov_b32 s20, s14
	s_mov_b64 s[24:25], s[18:19]
	s_mov_b64 s[22:23], s[16:17]
	global_store_dwordx4 v[14:15], v[8:11], off
	v_cvt_pk_bf16_f32 v4, v4, v5
	v_cvt_pk_bf16_f32 v5, v6, v7
	v_cvt_pk_bf16_f32 v6, v0, v1
	v_cvt_pk_bf16_f32 v7, v2, v3
	global_store_dwordx4 v[12:13], v[4:7], off offset:256
	s_cbranch_vccz .LBB0_706
	s_waitcnt vmcnt(0)
	s_cmpk_gt_u32 s31, 0xff
	s_cbranch_scc1 .LBB0_717
	s_barrier

; #define PG8_STAGE(bufoff, gbase, voff) do { _Pragma("unroll") for (int _i = 0; _i < 2; ++_i) \
;         __builtin_amdgcn_global_load_lds((const unsigned*)((const char*)(gbase) + (voff)[_i]), (LAS unsigned*)(lds + (bufoff) + ldsw + _i * 8192), 16, 0, 0); } while (0)
; #define PG8_LDA(dst, b, h) do { _Pragma("unroll") for (int m = 0; m < 4; ++m) _Pragma("unroll") for (int k = 0; k < 2; ++k) dst[m][k] = *(const LAS bf16x8*)(lds + PG8_SA(b, h) + aoff + m * 2048 + k * 1024); } while (0)
; #define PG8_LDB(dst, b, h) do { _Pragma("unroll") for (int n = 0; n < 2; ++n) _Pragma("unroll") for (int k = 0; k < 2; ++k) dst[n][k] = *(const LAS bf16x8*)(lds + PG8_SB(b, h) + boff + n * 2048 + k * 1024); } while (0)
; #define PG8_MMA(ai, bj, At, Bt) do { __builtin_amdgcn_s_setprio(1); _Pragma("unroll") for (int m = 0; m < 4; ++m) _Pragma("unroll") for (int n = 0; n < 2; ++n) _Pragma("unroll") for (int k = 0; k < 2; ++k) \
;         acc[ai][bj][m][n] = __builtin_amdgcn_mfma_f32_16x16x32_bf16(Bt[n][k], At[m][k], acc[ai][bj][m][n], 0, 0, 0); __builtin_amdgcn_s_setprio(0); } while (0)
; #define PG8_WAIT_L(n) asm volatile("s_waitcnt lgkmcnt(" #n ")" ::: "memory")
; template <class Epi, class Sched>
; __device__ __forceinline__ void gemm_phase(LAS unsigned char* lds, const Gemm g, const Sched& S, const Epi& E) {
;     ...
;         const bool has_next = S.next(ui + 1, nxt);
;         const char* nA = has_next ? (const char*)g.A + (size_t)nxt.pm * tstep : cA; const char* nB = has_next ? (const char*)g.Bt + (size_t)nxt.pn * tstep : cB;
;         for (int t = 0; t < nt; t += 2) {
;             const bool last = (t == nt - 2);
;             const char* a1 = cA + (size_t)(t + 1) * kstep;
;             const char* a2 = last ? nA : cA + (size_t)(t + 2) * kstep; const char* b2 = last ? nB : cB + (size_t)(t + 2) * kstep;
;             const char* a3 = a2 + kstep; const char* b3 = b2 + kstep;
;             PG8_LDB(B0, 0, 0); PG8_SCHED; PG8_LDA(At, 0, 0); PG8_STAGE(PG8_SA(1, 1), a1 + hstep, voffA);
;             PG8_WAIT_L(8); PG8_BAR; PG8_WAIT_L(0); PG8_MMA(0, 0, At, B0); PG8_BAR; PG8_SCHED;
;             PG8_LDB(B1, 0, 1); PG8_STAGE(PG8_SB(0, 0), b2, voffB);
;             PG8_BAR; PG8_WAIT_L(0); PG8_MMA(0, 1, At, B1); PG8_BAR;
;             PG8_LDA(At, 0, 1); PG8_STAGE(PG8_SA(0, 0), a2, voffA);
;             PG8_BAR; PG8_WAIT_L(0); PG8_MMA(1, 0, At, B0); PG8_BAR; PG8_SCHED;
.LBB0_825:
	s_ashr_i32 s7, s6, 31
	v_cmp_lt_i64_e32 vcc, s[8:9], v[156:157]
	s_lshl_b64 s[8:9], s[6:7], 20
	s_add_u32 s8, s22, s8
	s_addc_u32 s9, s23, s9
	s_and_b64 s[10:11], vcc, exec
	s_cselect_b32 s7, s9, s15
	s_cselect_b32 s39, s8, s14
	s_ashr_i32 s5, s4, 31
	s_lshl_b64 s[10:11], s[4:5], 20
	s_add_u32 s10, s50, s10
	s_addc_u32 s11, s51, s11
	s_and_b64 s[18:19], vcc, exec
	s_cselect_b32 s5, s11, s17
	s_cselect_b32 s40, s10, s16
	s_add_u32 s14, s14, 0x80080
	s_addc_u32 s15, s15, 0
	s_add_u32 s41, s16, 0x100
	s_addc_u32 s42, s17, 0
	s_mov_b32 s43, -2
	ds_read_b128 v[128:131], v168
	ds_read_b128 v[132:135], v168 offset:1024
	ds_read_b128 v[136:139], v168 offset:2048
	ds_read_b128 v[140:143], v168 offset:3072
	s_add_u32 s16, s14, 0xfff80080
	s_addc_u32 s17, s15, -1
	s_cmp_eq_u32 s43, 28
	s_cselect_b32 s19, s7, s17
	s_cselect_b32 s18, s39, s16
	s_cselect_b32 s17, s5, s42
	s_cselect_b32 s16, s40, s41
	s_add_i32 m0, s13, 0xc000
	ds_read_b128 v[162:165], v169
	ds_read_b128 v[172:175], v169 offset:1024
	ds_read_b128 v[176:179], v169 offset:2048
	ds_read_b128 v[180:183], v169 offset:3072
	ds_read_b128 v[184:187], v169 offset:4096
	ds_read_b128 v[188:191], v169 offset:5120
	ds_read_b128 v[192:195], v169 offset:6144
	ds_read_b128 v[196:199], v169 offset:7168
	global_load_lds_dwordx4 v152, s[14:15]
	s_add_i32 m0, s13, 0xe000
	s_nop 0
	global_load_lds_dwordx4 v154, s[14:15]
	s_waitcnt lgkmcnt(8)
	s_waitcnt vmcnt(10)
	s_barrier
	s_waitcnt lgkmcnt(0)
	s_setprio 1
	s_waitcnt lgkmcnt(0)
	v_mfma_f32_16x16x32_bf16 v[124:127], v[128:131], v[162:165], 0
	v_mfma_f32_16x16x32_bf16 v[120:123], v[136:139], v[162:165], 0
	v_mfma_f32_16x16x32_bf16 v[116:119], v[128:131], v[176:179], 0
	v_mfma_f32_16x16x32_bf16 v[112:115], v[136:139], v[176:179], 0
	v_mfma_f32_16x16x32_bf16 v[108:111], v[128:131], v[184:187], 0
	v_mfma_f32_16x16x32_bf16 v[100:103], v[136:139], v[184:187], 0
	v_mfma_f32_16x16x32_bf16 v[76:79], v[128:131], v[192:195], 0
	v_mfma_f32_16x16x32_bf16 v[72:75], v[136:139], v[192:195], 0
	v_mfma_f32_16x16x32_bf16 v[124:127], v[132:135], v[172:175], v[124:127]
	v_mfma_f32_16x16x32_bf16 v[120:123], v[140:143], v[172:175], v[120:123]
	v_mfma_f32_16x16x32_bf16 v[116:119], v[132:135], v[180:183], v[116:119]
	v_mfma_f32_16x16x32_bf16 v[112:115], v[140:143], v[180:183], v[112:115]
	v_mfma_f32_16x16x32_bf16 v[108:111], v[132:135], v[188:191], v[108:111]
	v_mfma_f32_16x16x32_bf16 v[100:103], v[140:143], v[188:191], v[100:103]
	v_mfma_f32_16x16x32_bf16 v[76:79], v[132:135], v[196:199], v[76:79]
	v_mfma_f32_16x16x32_bf16 v[72:75], v[140:143], v[196:199], v[72:75]
	s_setprio 0
	s_barrier
	s_add_i32 s44, s35, s24
	s_mov_b32 m0, s44
	ds_read_b128 v[202:205], v170
	ds_read_b128 v[206:209], v170 offset:1024
	ds_read_b128 v[210:213], v170 offset:2048
	ds_read_b128 v[214:217], v170 offset:3072
	global_load_lds_dwordx4 v146, s[16:17]
	s_add_i32 m0, s44, 0x2000
	s_nop 0
	global_load_lds_dwordx4 v150, s[16:17]
	s_waitcnt vmcnt(10)
	s_barrier
	s_waitcnt lgkmcnt(0)
	s_setprio 1
	s_waitcnt lgkmcnt(0)
	v_mfma_f32_16x16x32_bf16 v[104:107], v[202:205], v[162:165], 0
	v_mfma_f32_16x16x32_bf16 v[96:99], v[210:213], v[162:165], 0
	v_mfma_f32_16x16x32_bf16 v[92:95], v[202:205], v[176:179], 0
	v_mfma_f32_16x16x32_bf16 v[88:91], v[210:213], v[176:179], 0
	v_mfma_f32_16x16x32_bf16 v[84:87], v[202:205], v[184:187], 0
	v_mfma_f32_16x16x32_bf16 v[80:83], v[210:213], v[184:187], 0
	v_mfma_f32_16x16x32_bf16 v[68:71], v[202:205], v[192:195], 0
	v_mfma_f32_16x16x32_bf16 v[64:67], v[210:213], v[192:195], 0
	v_mfma_f32_16x16x32_bf16 v[104:107], v[206:209], v[172:175], v[104:107]
	v_mfma_f32_16x16x32_bf16 v[96:99], v[214:217], v[172:175], v[96:99]
	v_mfma_f32_16x16x32_bf16 v[92:95], v[206:209], v[180:183], v[92:95]
	v_mfma_f32_16x16x32_bf16 v[88:91], v[214:217], v[180:183], v[88:91]
	v_mfma_f32_16x16x32_bf16 v[84:87], v[206:209], v[188:191], v[84:87]
	v_mfma_f32_16x16x32_bf16 v[80:83], v[214:217], v[188:191], v[80:83]
	v_mfma_f32_16x16x32_bf16 v[68:71], v[206:209], v[196:199], v[68:71]
	v_mfma_f32_16x16x32_bf16 v[64:67], v[214:217], v[196:199], v[64:67]
	s_setprio 0
	s_mov_b32 m0, s13
	v_lshl_add_u64 v[222:223], s[18:19], 0, v[144:145]
	s_barrier
	ds_read_b128 v[162:165], v169 offset:16384
	ds_read_b128 v[172:175], v169 offset:17408
	ds_read_b128 v[176:179], v169 offset:18432
	ds_read_b128 v[180:183], v169 offset:19456
	ds_read_b128 v[184:187], v169 offset:20480
	ds_read_b128 v[188:191], v169 offset:21504
	ds_read_b128 v[192:195], v169 offset:22528
	ds_read_b128 v[196:199], v169 offset:23552
	global_load_lds_dwordx4 v144, s[18:19]
	v_lshl_add_u64 v[224:225], s[18:19], 0, v[148:149]
	s_mov_b32 m0, s25
	s_nop 0
	global_load_lds_dwordx4 v148, s[18:19]
	s_barrier
	s_waitcnt lgkmcnt(0)
	s_setprio 1
	s_waitcnt lgkmcnt(0)
	v_mfma_f32_16x16x32_bf16 v[60:63], v[128:131], v[162:165], 0
	v_mfma_f32_16x16x32_bf16 v[56:59], v[136:139], v[162:165], 0
	v_mfma_f32_16x16x32_bf16 v[48:51], v[128:131], v[176:179], 0
	v_mfma_f32_16x16x32_bf16 v[40:43], v[136:139], v[176:179], 0
	v_mfma_f32_16x16x32_bf16 v[32:35], v[128:131], v[184:187], 0
	v_mfma_f32_16x16x32_bf16 v[24:27], v[136:139], v[184:187], 0
	v_mfma_f32_16x16x32_bf16 v[16:19], v[128:131], v[192:195], 0
	v_mfma_f32_16x16x32_bf16 v[8:11], v[136:139], v[192:195], 0
	v_mfma_f32_16x16x32_bf16 v[60:63], v[132:135], v[172:175], v[60:63]
	v_mfma_f32_16x16x32_bf16 v[56:59], v[140:143], v[172:175], v[56:59]
	v_mfma_f32_16x16x32_bf16 v[48:51], v[132:135], v[180:183], v[48:51]
	v_mfma_f32_16x16x32_bf16 v[40:43], v[140:143], v[180:183], v[40:43]
	v_mfma_f32_16x16x32_bf16 v[32:35], v[132:135], v[188:191], v[32:35]
	v_mfma_f32_16x16x32_bf16 v[24:27], v[140:143], v[188:191], v[24:27]
	v_mfma_f32_16x16x32_bf16 v[16:19], v[132:135], v[196:199], v[16:19]
	v_mfma_f32_16x16x32_bf16 v[8:11], v[140:143], v[196:199], v[8:11]
	s_setprio 0
	s_barrier
; #define PG8_STAGE(bufoff, gbase, voff) do { _Pragma("unroll") for (int _i = 0; _i < 2; ++_i) \
;         __builtin_amdgcn_global_load_lds((const unsigned*)((const char*)(gbase) + (voff)[_i]), (LAS unsigned*)(lds + (bufoff) + ldsw + _i * 8192), 16, 0, 0); } while (0)
; #define PG8_LDA(dst, b, h) do { _Pragma("unroll") for (int m = 0; m < 4; ++m) _Pragma("unroll") for (int k = 0; k < 2; ++k) dst[m][k] = *(const LAS bf16x8*)(lds + PG8_SA(b, h) + aoff + m * 2048 + k * 1024); } while (0)
; #define PG8_LDB(dst, b, h) do { _Pragma("unroll") for (int n = 0; n < 2; ++n) _Pragma("unroll") for (int k = 0; k < 2; ++k) dst[n][k] = *(const LAS bf16x8*)(lds + PG8_SB(b, h) + boff + n * 2048 + k * 1024); } while (0)
; #define PG8_MMA(ai, bj, At, Bt) do { __builtin_amdgcn_s_setprio(1); _Pragma("unroll") for (int m = 0; m < 4; ++m) _Pragma("unroll") for (int n = 0; n < 2; ++n) _Pragma("unroll") for (int k = 0; k < 2; ++k) \
;         acc[ai][bj][m][n] = __builtin_amdgcn_mfma_f32_16x16x32_bf16(Bt[n][k], At[m][k], acc[ai][bj][m][n], 0, 0, 0); __builtin_amdgcn_s_setprio(0); } while (0)
; #define PG8_WAIT_V(n) asm volatile("s_waitcnt vmcnt(" #n ")" ::: "memory")
; #define PG8_WAIT_L(n) asm volatile("s_waitcnt lgkmcnt(" #n ")" ::: "memory")
; #define PG8_BAR __builtin_amdgcn_s_barrier()
; #define PG8_SCHED __builtin_amdgcn_sched_barrier(0)
; template <class Epi, class Sched>
; __device__ __forceinline__ void gemm_phase(LAS unsigned char* lds, const Gemm g, const Sched& S, const Epi& E) {
;     ...
;             PG8_BAR; PG8_WAIT_L(0); PG8_MMA(1, 0, At, B0); PG8_BAR; PG8_SCHED;
;             PG8_STAGE(PG8_SB(0, 1), b2 + hstep, voffB);
;             PG8_WAIT_V(6); PG8_BAR; PG8_MMA(1, 1, At, B1); PG8_BAR;
;             PG8_LDB(B0, 1, 0); PG8_SCHED; PG8_LDA(At, 1, 0); PG8_STAGE(PG8_SA(0, 1), a2 + hstep, voffA);
;             PG8_WAIT_L(8); PG8_BAR; PG8_WAIT_L(0); PG8_MMA(0, 0, At, B0); PG8_BAR; PG8_SCHED;
;             PG8_LDB(B1, 1, 1); PG8_STAGE(PG8_SB(1, 0), b3, voffB);
;             PG8_BAR; PG8_WAIT_L(0); PG8_MMA(0, 1, At, B1); PG8_BAR;
;             PG8_LDA(At, 1, 1); PG8_STAGE(PG8_SA(1, 0), a3, voffA);
;             PG8_BAR; PG8_WAIT_L(0); PG8_MMA(1, 0, At, B0); PG8_BAR; PG8_SCHED;
	s_add_u32 s44, s16, 0x80000
	s_addc_u32 s45, s17, 0
	s_add_i32 s46, s36, s24
	s_mov_b32 m0, s46
	s_nop 0
	global_load_lds_dwordx4 v146, s[44:45]
	s_add_i32 m0, s46, 0x2000
	s_nop 0
	global_load_lds_dwordx4 v150, s[44:45]
	s_waitcnt vmcnt(10)
	s_barrier
	s_setprio 1
	v_mfma_f32_16x16x32_bf16 v[52:55], v[202:205], v[162:165], 0
	v_mfma_f32_16x16x32_bf16 v[44:47], v[210:213], v[162:165], 0
	v_mfma_f32_16x16x32_bf16 v[36:39], v[202:205], v[176:179], 0
	v_mfma_f32_16x16x32_bf16 v[28:31], v[210:213], v[176:179], 0
	v_mfma_f32_16x16x32_bf16 v[20:23], v[202:205], v[184:187], 0
	v_mfma_f32_16x16x32_bf16 v[12:15], v[210:213], v[184:187], 0
	v_mfma_f32_16x16x32_bf16 v[4:7], v[202:205], v[192:195], 0
	v_mfma_f32_16x16x32_bf16 v[0:3], v[210:213], v[192:195], 0
	v_mfma_f32_16x16x32_bf16 v[52:55], v[206:209], v[172:175], v[52:55]
	v_mfma_f32_16x16x32_bf16 v[44:47], v[214:217], v[172:175], v[44:47]
	v_mfma_f32_16x16x32_bf16 v[36:39], v[206:209], v[180:183], v[36:39]
	v_mfma_f32_16x16x32_bf16 v[28:31], v[214:217], v[180:183], v[28:31]
	v_mfma_f32_16x16x32_bf16 v[20:23], v[206:209], v[188:191], v[20:23]
	v_mfma_f32_16x16x32_bf16 v[12:15], v[214:217], v[188:191], v[12:15]
	v_mfma_f32_16x16x32_bf16 v[4:7], v[206:209], v[196:199], v[4:7]
	v_mfma_f32_16x16x32_bf16 v[0:3], v[214:217], v[196:199], v[0:3]
	s_setprio 0
	s_add_i32 s44, 0, 0x18000
	v_add_u32_e32 v140, s44, v167
	s_barrier
	ds_read_b128 v[128:131], v140
	ds_read_b128 v[132:135], v140 offset:1024
	ds_read_b128 v[136:139], v140 offset:2048
	ds_read_b128 v[140:143], v140 offset:3072
	s_add_u32 s18, s18, 0x80000
	s_addc_u32 s19, s19, 0
	s_mov_b32 m0, s26
	ds_read_b128 v[162:165], v169 offset:32768
	ds_read_b128 v[172:175], v169 offset:33792
	ds_read_b128 v[176:179], v169 offset:34816
	ds_read_b128 v[180:183], v169 offset:35840
	ds_read_b128 v[184:187], v169 offset:36864
	ds_read_b128 v[188:191], v169 offset:37888
	ds_read_b128 v[192:195], v169 offset:38912
	ds_read_b128 v[196:199], v169 offset:39936
	global_load_lds_dwordx4 v144, s[18:19]
	s_mov_b32 m0, s27
	s_nop 0
	global_load_lds_dwordx4 v148, s[18:19]
	s_waitcnt lgkmcnt(8)
	s_waitcnt vmcnt(10)
	s_barrier
	s_waitcnt lgkmcnt(0)
	s_setprio 1
	s_waitcnt lgkmcnt(0)
	v_mfma_f32_16x16x32_bf16 v[124:127], v[128:131], v[162:165], v[124:127]
	v_mfma_f32_16x16x32_bf16 v[120:123], v[136:139], v[162:165], v[120:123]
	v_mfma_f32_16x16x32_bf16 v[116:119], v[128:131], v[176:179], v[116:119]
	v_mfma_f32_16x16x32_bf16 v[112:115], v[136:139], v[176:179], v[112:115]
	v_mfma_f32_16x16x32_bf16 v[108:111], v[128:131], v[184:187], v[108:111]
	v_mfma_f32_16x16x32_bf16 v[100:103], v[136:139], v[184:187], v[100:103]
	v_mfma_f32_16x16x32_bf16 v[76:79], v[128:131], v[192:195], v[76:79]
	v_mfma_f32_16x16x32_bf16 v[72:75], v[136:139], v[192:195], v[72:75]
	v_mfma_f32_16x16x32_bf16 v[124:127], v[132:135], v[172:175], v[124:127]
	v_mfma_f32_16x16x32_bf16 v[120:123], v[140:143], v[172:175], v[120:123]
	v_mfma_f32_16x16x32_bf16 v[116:119], v[132:135], v[180:183], v[116:119]
	v_mfma_f32_16x16x32_bf16 v[112:115], v[140:143], v[180:183], v[112:115]
	v_mfma_f32_16x16x32_bf16 v[108:111], v[132:135], v[188:191], v[108:111]
	v_mfma_f32_16x16x32_bf16 v[100:103], v[140:143], v[188:191], v[100:103]
	v_mfma_f32_16x16x32_bf16 v[76:79], v[132:135], v[196:199], v[76:79]
	v_mfma_f32_16x16x32_bf16 v[72:75], v[140:143], v[196:199], v[72:75]
	s_setprio 0
	s_barrier
	s_add_i32 s18, 0, 0x1c000
	s_add_i32 s19, s44, s24
	v_add_u32_e32 v160, s18, v167
	s_add_u32 s0, s16, 0x80
	s_addc_u32 s1, s17, 0
	s_mov_b32 m0, s19
	ds_read_b128 v[202:205], v160
	ds_read_b128 v[206:209], v160 offset:1024
	ds_read_b128 v[210:213], v160 offset:2048
	ds_read_b128 v[214:217], v160 offset:3072
	global_load_lds_dwordx4 v146, s[0:1]
	s_add_i32 m0, s19, 0x2000
	s_nop 0
	global_load_lds_dwordx4 v150, s[0:1]
	s_waitcnt vmcnt(10)
	s_barrier
	s_waitcnt lgkmcnt(0)
	s_setprio 1
	s_waitcnt lgkmcnt(0)
	v_mfma_f32_16x16x32_bf16 v[104:107], v[202:205], v[162:165], v[104:107]
	v_mfma_f32_16x16x32_bf16 v[96:99], v[210:213], v[162:165], v[96:99]
	v_mfma_f32_16x16x32_bf16 v[92:95], v[202:205], v[176:179], v[92:95]
	v_mfma_f32_16x16x32_bf16 v[88:91], v[210:213], v[176:179], v[88:91]
	v_mfma_f32_16x16x32_bf16 v[84:87], v[202:205], v[184:187], v[84:87]
	v_mfma_f32_16x16x32_bf16 v[80:83], v[210:213], v[184:187], v[80:83]
	v_mfma_f32_16x16x32_bf16 v[68:71], v[202:205], v[192:195], v[68:71]
	v_mfma_f32_16x16x32_bf16 v[64:67], v[210:213], v[192:195], v[64:67]
	v_mfma_f32_16x16x32_bf16 v[104:107], v[206:209], v[172:175], v[104:107]
	v_mfma_f32_16x16x32_bf16 v[96:99], v[214:217], v[172:175], v[96:99]
	v_mfma_f32_16x16x32_bf16 v[92:95], v[206:209], v[180:183], v[92:95]
	v_mfma_f32_16x16x32_bf16 v[88:91], v[214:217], v[180:183], v[88:91]
	v_mfma_f32_16x16x32_bf16 v[84:87], v[206:209], v[188:191], v[84:87]
	v_mfma_f32_16x16x32_bf16 v[80:83], v[214:217], v[188:191], v[80:83]
	v_mfma_f32_16x16x32_bf16 v[68:71], v[206:209], v[196:199], v[68:71]
	v_mfma_f32_16x16x32_bf16 v[64:67], v[214:217], v[196:199], v[64:67]
	s_setprio 0
	s_mov_b32 m0, s31
	s_mov_b64 s[0:1], 0x80
	v_lshl_add_u64 v[218:219], v[222:223], 0, s[0:1]
	s_barrier
	ds_read_b128 v[162:165], v169 offset:49152
	ds_read_b128 v[172:175], v169 offset:50176
	ds_read_b128 v[176:179], v169 offset:51200
	ds_read_b128 v[180:183], v169 offset:52224
	ds_read_b128 v[184:187], v169 offset:53248
	ds_read_b128 v[188:191], v169 offset:54272
	ds_read_b128 v[192:195], v169 offset:55296
	ds_read_b128 v[196:199], v169 offset:56320
	global_load_lds_dwordx4 v[218:219], off
	v_lshl_add_u64 v[218:219], v[224:225], 0, s[0:1]
	s_mov_b32 m0, s33
	s_nop 0
	global_load_lds_dwordx4 v[218:219], off
	s_barrier
; #define PG8_STAGE(bufoff, gbase, voff) do { _Pragma("unroll") for (int _i = 0; _i < 2; ++_i) \
;         __builtin_amdgcn_global_load_lds((const unsigned*)((const char*)(gbase) + (voff)[_i]), (LAS unsigned*)(lds + (bufoff) + ldsw + _i * 8192), 16, 0, 0); } while (0)
; #define PG8_LDA(dst, b, h) do { _Pragma("unroll") for (int m = 0; m < 4; ++m) _Pragma("unroll") for (int k = 0; k < 2; ++k) dst[m][k] = *(const LAS bf16x8*)(lds + PG8_SA(b, h) + aoff + m * 2048 + k * 1024); } while (0)
; #define PG8_LDB(dst, b, h) do { _Pragma("unroll") for (int n = 0; n < 2; ++n) _Pragma("unroll") for (int k = 0; k < 2; ++k) dst[n][k] = *(const LAS bf16x8*)(lds + PG8_SB(b, h) + boff + n * 2048 + k * 1024); } while (0)
; #define PG8_WAIT_V(n) asm volatile("s_waitcnt vmcnt(" #n ")" ::: "memory")
; #define PG8_WAIT_L(n) asm volatile("s_waitcnt lgkmcnt(" #n ")" ::: "memory")
; #define PG8_BAR __builtin_amdgcn_s_barrier()
; #define PG8_SCHED __builtin_amdgcn_sched_barrier(0)
; template <class Epi, class Sched>
; __device__ __forceinline__ void gemm_phase(LAS unsigned char* lds, const Gemm g, const Sched& S, const Epi& E) {
;     ...
;             PG8_LDB(B0, 0, 0); PG8_SCHED; PG8_LDA(At, 0, 0); PG8_STAGE(PG8_SA(1, 1), a1 + hstep, voffA);
;             PG8_WAIT_L(8); PG8_BAR; PG8_WAIT_L(0); PG8_MMA(0, 0, At, B0); PG8_BAR; PG8_SCHED;
;             PG8_LDB(B1, 0, 1); PG8_STAGE(PG8_SB(0, 0), b2, voffB);
;             PG8_BAR; PG8_WAIT_L(0); PG8_MMA(0, 1, At, B1); PG8_BAR;
;             PG8_LDA(At, 0, 1); PG8_STAGE(PG8_SA(0, 0), a2, voffA);
;             PG8_BAR; PG8_WAIT_L(0); PG8_MMA(1, 0, At, B0); PG8_BAR; PG8_SCHED;
;             PG8_STAGE(PG8_SB(0, 1), b2 + hstep, voffB);
;             PG8_WAIT_V(6); PG8_BAR; PG8_MMA(1, 1, At, B1); PG8_BAR;
;             PG8_LDB(B0, 1, 0); PG8_SCHED; PG8_LDA(At, 1, 0); PG8_STAGE(PG8_SA(0, 1), a2 + hstep, voffA);
;             PG8_WAIT_L(8); PG8_BAR; PG8_WAIT_L(0); PG8_MMA(0, 0, At, B0); PG8_BAR; PG8_SCHED;
;             PG8_LDB(B1, 1, 1); PG8_STAGE(PG8_SB(1, 0), b3, voffB);
;             PG8_BAR; PG8_WAIT_L(0); PG8_MMA(0, 1, At, B1); PG8_BAR;
;             PG8_LDA(At, 1, 1); PG8_STAGE(PG8_SA(1, 0), a3, voffA);
;             PG8_BAR; PG8_WAIT_L(0); PG8_MMA(1, 0, At, B0); PG8_BAR; PG8_SCHED;
;             PG8_STAGE(PG8_SB(1, 1), b3 + hstep, voffB);
;             PG8_WAIT_V(6); PG8_BAR; PG8_MMA(1, 1, At, B1); PG8_BAR;
	s_waitcnt lgkmcnt(0)
	s_setprio 1
	s_waitcnt lgkmcnt(0)
	v_mfma_f32_16x16x32_bf16 v[60:63], v[128:131], v[162:165], v[60:63]
	v_mfma_f32_16x16x32_bf16 v[56:59], v[136:139], v[162:165], v[56:59]
	v_mfma_f32_16x16x32_bf16 v[48:51], v[128:131], v[176:179], v[48:51]
	v_mfma_f32_16x16x32_bf16 v[40:43], v[136:139], v[176:179], v[40:43]
	v_mfma_f32_16x16x32_bf16 v[32:35], v[128:131], v[184:187], v[32:35]
	v_mfma_f32_16x16x32_bf16 v[24:27], v[136:139], v[184:187], v[24:27]
	v_mfma_f32_16x16x32_bf16 v[16:19], v[128:131], v[192:195], v[16:19]
	v_mfma_f32_16x16x32_bf16 v[8:11], v[136:139], v[192:195], v[8:11]
	v_mfma_f32_16x16x32_bf16 v[60:63], v[132:135], v[172:175], v[60:63]
	v_mfma_f32_16x16x32_bf16 v[56:59], v[140:143], v[172:175], v[56:59]
	v_mfma_f32_16x16x32_bf16 v[48:51], v[132:135], v[180:183], v[48:51]
	v_mfma_f32_16x16x32_bf16 v[40:43], v[140:143], v[180:183], v[40:43]
	v_mfma_f32_16x16x32_bf16 v[32:35], v[132:135], v[188:191], v[32:35]
	v_mfma_f32_16x16x32_bf16 v[24:27], v[140:143], v[188:191], v[24:27]
	v_mfma_f32_16x16x32_bf16 v[16:19], v[132:135], v[196:199], v[16:19]
	v_mfma_f32_16x16x32_bf16 v[8:11], v[140:143], v[196:199], v[8:11]
	s_setprio 0
	s_barrier
	s_add_u32 s16, s16, 0x80080
	s_addc_u32 s17, s17, 0
	s_add_i32 s18, s18, s24
	s_mov_b32 m0, s18
	s_nop 0
	global_load_lds_dwordx4 v146, s[16:17]
	s_add_i32 m0, s18, 0x2000
	s_nop 0
	global_load_lds_dwordx4 v150, s[16:17]
	s_waitcnt vmcnt(10)
	s_barrier
	s_setprio 1
	v_mfma_f32_16x16x32_bf16 v[52:55], v[202:205], v[162:165], v[52:55]
	v_mfma_f32_16x16x32_bf16 v[44:47], v[210:213], v[162:165], v[44:47]
	v_mfma_f32_16x16x32_bf16 v[36:39], v[202:205], v[176:179], v[36:39]
	v_mfma_f32_16x16x32_bf16 v[28:31], v[210:213], v[176:179], v[28:31]
	v_mfma_f32_16x16x32_bf16 v[20:23], v[202:205], v[184:187], v[20:23]
	v_mfma_f32_16x16x32_bf16 v[12:15], v[210:213], v[184:187], v[12:15]
	v_mfma_f32_16x16x32_bf16 v[4:7], v[202:205], v[192:195], v[4:7]
	v_mfma_f32_16x16x32_bf16 v[0:3], v[210:213], v[192:195], v[0:3]
	v_mfma_f32_16x16x32_bf16 v[52:55], v[206:209], v[172:175], v[52:55]
	v_mfma_f32_16x16x32_bf16 v[44:47], v[214:217], v[172:175], v[44:47]
	v_mfma_f32_16x16x32_bf16 v[36:39], v[206:209], v[180:183], v[36:39]
	v_mfma_f32_16x16x32_bf16 v[28:31], v[214:217], v[180:183], v[28:31]
	v_mfma_f32_16x16x32_bf16 v[20:23], v[206:209], v[188:191], v[20:23]
	v_mfma_f32_16x16x32_bf16 v[12:15], v[214:217], v[188:191], v[12:15]
	v_mfma_f32_16x16x32_bf16 v[4:7], v[206:209], v[196:199], v[4:7]
	v_mfma_f32_16x16x32_bf16 v[0:3], v[214:217], v[196:199], v[0:3]
	s_setprio 0
	s_add_i32 s43, s43, 2
	s_add_u32 s14, s14, 0x100
	s_addc_u32 s15, s15, 0
	s_add_u32 s41, s41, 0x100
	s_addc_u32 s42, s42, 0
	s_cmp_gt_u32 s43, 29
	s_barrier
.LBB0_826:
	ds_read_b128 v[128:131], v168
	ds_read_b128 v[132:135], v168 offset:1024
	ds_read_b128 v[136:139], v168 offset:2048
	ds_read_b128 v[140:143], v168 offset:3072
	s_add_u32 s16, s14, 0xfff80080
	s_addc_u32 s17, s15, -1
	s_cmp_eq_u32 s43, 28
	s_cselect_b32 s19, s7, s17
	s_cselect_b32 s18, s39, s16
	s_cselect_b32 s17, s5, s42
	s_cselect_b32 s16, s40, s41
	s_add_i32 m0, s13, 0xc000
	ds_read_b128 v[162:165], v169
	ds_read_b128 v[172:175], v169 offset:1024
	ds_read_b128 v[176:179], v169 offset:2048
	ds_read_b128 v[180:183], v169 offset:3072
	ds_read_b128 v[184:187], v169 offset:4096
	ds_read_b128 v[188:191], v169 offset:5120
	ds_read_b128 v[192:195], v169 offset:6144
	ds_read_b128 v[196:199], v169 offset:7168
	global_load_lds_dwordx4 v152, s[14:15]
	s_add_i32 m0, s13, 0xe000
	s_nop 0
	global_load_lds_dwordx4 v154, s[14:15]
	s_waitcnt lgkmcnt(8)
	s_waitcnt vmcnt(10)
	s_barrier
	s_waitcnt lgkmcnt(0)
	s_setprio 1
	s_waitcnt lgkmcnt(0)
	v_mfma_f32_16x16x32_bf16 v[124:127], v[128:131], v[162:165], v[124:127]
	v_mfma_f32_16x16x32_bf16 v[120:123], v[136:139], v[162:165], v[120:123]
	v_mfma_f32_16x16x32_bf16 v[116:119], v[128:131], v[176:179], v[116:119]
	v_mfma_f32_16x16x32_bf16 v[112:115], v[136:139], v[176:179], v[112:115]
	v_mfma_f32_16x16x32_bf16 v[108:111], v[128:131], v[184:187], v[108:111]
	v_mfma_f32_16x16x32_bf16 v[100:103], v[136:139], v[184:187], v[100:103]
	v_mfma_f32_16x16x32_bf16 v[76:79], v[128:131], v[192:195], v[76:79]
	v_mfma_f32_16x16x32_bf16 v[72:75], v[136:139], v[192:195], v[72:75]
	v_mfma_f32_16x16x32_bf16 v[124:127], v[132:135], v[172:175], v[124:127]
	v_mfma_f32_16x16x32_bf16 v[120:123], v[140:143], v[172:175], v[120:123]
	v_mfma_f32_16x16x32_bf16 v[116:119], v[132:135], v[180:183], v[116:119]
	v_mfma_f32_16x16x32_bf16 v[112:115], v[140:143], v[180:183], v[112:115]
	v_mfma_f32_16x16x32_bf16 v[108:111], v[132:135], v[188:191], v[108:111]
	v_mfma_f32_16x16x32_bf16 v[100:103], v[140:143], v[188:191], v[100:103]
	v_mfma_f32_16x16x32_bf16 v[76:79], v[132:135], v[196:199], v[76:79]
	v_mfma_f32_16x16x32_bf16 v[72:75], v[140:143], v[196:199], v[72:75]
	s_setprio 0
	s_barrier
	s_add_i32 s44, s35, s24
	s_mov_b32 m0, s44
	ds_read_b128 v[202:205], v170
	ds_read_b128 v[206:209], v170 offset:1024
	ds_read_b128 v[210:213], v170 offset:2048
	ds_read_b128 v[214:217], v170 offset:3072
	global_load_lds_dwordx4 v146, s[16:17]
	s_add_i32 m0, s44, 0x2000
	s_nop 0
	global_load_lds_dwordx4 v150, s[16:17]
	s_waitcnt vmcnt(10)
	s_barrier
; #define PG8_STAGE(bufoff, gbase, voff) do { _Pragma("unroll") for (int _i = 0; _i < 2; ++_i) \
;         __builtin_amdgcn_global_load_lds((const unsigned*)((const char*)(gbase) + (voff)[_i]), (LAS unsigned*)(lds + (bufoff) + ldsw + _i * 8192), 16, 0, 0); } while (0)
; #define PG8_LDA(dst, b, h) do { _Pragma("unroll") for (int m = 0; m < 4; ++m) _Pragma("unroll") for (int k = 0; k < 2; ++k) dst[m][k] = *(const LAS bf16x8*)(lds + PG8_SA(b, h) + aoff + m * 2048 + k * 1024); } while (0)
; #define PG8_LDB(dst, b, h) do { _Pragma("unroll") for (int n = 0; n < 2; ++n) _Pragma("unroll") for (int k = 0; k < 2; ++k) dst[n][k] = *(const LAS bf16x8*)(lds + PG8_SB(b, h) + boff + n * 2048 + k * 1024); } while (0)
; #define PG8_WAIT_V(n) asm volatile("s_waitcnt vmcnt(" #n ")" ::: "memory")
; #define PG8_WAIT_L(n) asm volatile("s_waitcnt lgkmcnt(" #n ")" ::: "memory")
; #define PG8_BAR __builtin_amdgcn_s_barrier()
; #define PG8_SCHED __builtin_amdgcn_sched_barrier(0)
; template <class Epi, class Sched>
; __device__ __forceinline__ void gemm_phase(LAS unsigned char* lds, const Gemm g, const Sched& S, const Epi& E) {
;     ...
;             PG8_LDB(B0, 0, 0); PG8_SCHED; PG8_LDA(At, 0, 0); PG8_STAGE(PG8_SA(1, 1), a1 + hstep, voffA);
;             PG8_WAIT_L(8); PG8_BAR; PG8_WAIT_L(0); PG8_MMA(0, 0, At, B0); PG8_BAR; PG8_SCHED;
;             PG8_LDB(B1, 0, 1); PG8_STAGE(PG8_SB(0, 0), b2, voffB);
;             PG8_BAR; PG8_WAIT_L(0); PG8_MMA(0, 1, At, B1); PG8_BAR;
;             PG8_LDA(At, 0, 1); PG8_STAGE(PG8_SA(0, 0), a2, voffA);
;             PG8_BAR; PG8_WAIT_L(0); PG8_MMA(1, 0, At, B0); PG8_BAR; PG8_SCHED;
;             PG8_STAGE(PG8_SB(0, 1), b2 + hstep, voffB);
;             PG8_WAIT_V(6); PG8_BAR; PG8_MMA(1, 1, At, B1); PG8_BAR;
;             PG8_LDB(B0, 1, 0); PG8_SCHED; PG8_LDA(At, 1, 0); PG8_STAGE(PG8_SA(0, 1), a2 + hstep, voffA);
;             PG8_WAIT_L(8); PG8_BAR; PG8_WAIT_L(0); PG8_MMA(0, 0, At, B0); PG8_BAR; PG8_SCHED;
;             PG8_LDB(B1, 1, 1); PG8_STAGE(PG8_SB(1, 0), b3, voffB);
;             PG8_BAR; PG8_WAIT_L(0); PG8_MMA(0, 1, At, B1); PG8_BAR;
;             PG8_LDA(At, 1, 1); PG8_STAGE(PG8_SA(1, 0), a3, voffA);
;             PG8_BAR; PG8_WAIT_L(0); PG8_MMA(1, 0, At, B0); PG8_BAR; PG8_SCHED;
;             PG8_STAGE(PG8_SB(1, 1), b3 + hstep, voffB);
;             PG8_WAIT_V(6); PG8_BAR; PG8_MMA(1, 1, At, B1); PG8_BAR;
	s_waitcnt lgkmcnt(0)
	s_setprio 1
	s_waitcnt lgkmcnt(0)
	v_mfma_f32_16x16x32_bf16 v[104:107], v[202:205], v[162:165], v[104:107]
	v_mfma_f32_16x16x32_bf16 v[96:99], v[210:213], v[162:165], v[96:99]
	v_mfma_f32_16x16x32_bf16 v[92:95], v[202:205], v[176:179], v[92:95]
	v_mfma_f32_16x16x32_bf16 v[88:91], v[210:213], v[176:179], v[88:91]
	v_mfma_f32_16x16x32_bf16 v[84:87], v[202:205], v[184:187], v[84:87]
	v_mfma_f32_16x16x32_bf16 v[80:83], v[210:213], v[184:187], v[80:83]
	v_mfma_f32_16x16x32_bf16 v[68:71], v[202:205], v[192:195], v[68:71]
	v_mfma_f32_16x16x32_bf16 v[64:67], v[210:213], v[192:195], v[64:67]
	v_mfma_f32_16x16x32_bf16 v[104:107], v[206:209], v[172:175], v[104:107]
	v_mfma_f32_16x16x32_bf16 v[96:99], v[214:217], v[172:175], v[96:99]
	v_mfma_f32_16x16x32_bf16 v[92:95], v[206:209], v[180:183], v[92:95]
	v_mfma_f32_16x16x32_bf16 v[88:91], v[214:217], v[180:183], v[88:91]
	v_mfma_f32_16x16x32_bf16 v[84:87], v[206:209], v[188:191], v[84:87]
	v_mfma_f32_16x16x32_bf16 v[80:83], v[214:217], v[188:191], v[80:83]
	v_mfma_f32_16x16x32_bf16 v[68:71], v[206:209], v[196:199], v[68:71]
	v_mfma_f32_16x16x32_bf16 v[64:67], v[214:217], v[196:199], v[64:67]
	s_setprio 0
	s_mov_b32 m0, s13
	v_lshl_add_u64 v[222:223], s[18:19], 0, v[144:145]
	s_barrier
	ds_read_b128 v[162:165], v169 offset:16384
	ds_read_b128 v[172:175], v169 offset:17408
	ds_read_b128 v[176:179], v169 offset:18432
	ds_read_b128 v[180:183], v169 offset:19456
	ds_read_b128 v[184:187], v169 offset:20480
	ds_read_b128 v[188:191], v169 offset:21504
	ds_read_b128 v[192:195], v169 offset:22528
	ds_read_b128 v[196:199], v169 offset:23552
	global_load_lds_dwordx4 v144, s[18:19]
	v_lshl_add_u64 v[224:225], s[18:19], 0, v[148:149]
	s_mov_b32 m0, s25
	s_nop 0
	global_load_lds_dwordx4 v148, s[18:19]
	s_barrier
	s_waitcnt lgkmcnt(0)
	s_setprio 1
	s_waitcnt lgkmcnt(0)
	v_mfma_f32_16x16x32_bf16 v[60:63], v[128:131], v[162:165], v[60:63]
	v_mfma_f32_16x16x32_bf16 v[56:59], v[136:139], v[162:165], v[56:59]
	v_mfma_f32_16x16x32_bf16 v[48:51], v[128:131], v[176:179], v[48:51]
	v_mfma_f32_16x16x32_bf16 v[40:43], v[136:139], v[176:179], v[40:43]
	v_mfma_f32_16x16x32_bf16 v[32:35], v[128:131], v[184:187], v[32:35]
	v_mfma_f32_16x16x32_bf16 v[24:27], v[136:139], v[184:187], v[24:27]
	v_mfma_f32_16x16x32_bf16 v[16:19], v[128:131], v[192:195], v[16:19]
	v_mfma_f32_16x16x32_bf16 v[8:11], v[136:139], v[192:195], v[8:11]
	v_mfma_f32_16x16x32_bf16 v[60:63], v[132:135], v[172:175], v[60:63]
	v_mfma_f32_16x16x32_bf16 v[56:59], v[140:143], v[172:175], v[56:59]
	v_mfma_f32_16x16x32_bf16 v[48:51], v[132:135], v[180:183], v[48:51]
	v_mfma_f32_16x16x32_bf16 v[40:43], v[140:143], v[180:183], v[40:43]
	v_mfma_f32_16x16x32_bf16 v[32:35], v[132:135], v[188:191], v[32:35]
	v_mfma_f32_16x16x32_bf16 v[24:27], v[140:143], v[188:191], v[24:27]
	v_mfma_f32_16x16x32_bf16 v[16:19], v[132:135], v[196:199], v[16:19]
	v_mfma_f32_16x16x32_bf16 v[8:11], v[140:143], v[196:199], v[8:11]
	s_setprio 0
	s_barrier
	s_add_u32 s44, s16, 0x80000
	s_addc_u32 s45, s17, 0
	s_add_i32 s46, s36, s24
	s_mov_b32 m0, s46
	s_nop 0
	global_load_lds_dwordx4 v146, s[44:45]
	s_add_i32 m0, s46, 0x2000
	s_nop 0
	global_load_lds_dwordx4 v150, s[44:45]
	s_waitcnt vmcnt(10)
	s_barrier
	s_setprio 1
	v_mfma_f32_16x16x32_bf16 v[52:55], v[202:205], v[162:165], v[52:55]
	v_mfma_f32_16x16x32_bf16 v[44:47], v[210:213], v[162:165], v[44:47]
	v_mfma_f32_16x16x32_bf16 v[36:39], v[202:205], v[176:179], v[36:39]
	v_mfma_f32_16x16x32_bf16 v[28:31], v[210:213], v[176:179], v[28:31]
	v_mfma_f32_16x16x32_bf16 v[20:23], v[202:205], v[184:187], v[20:23]
	v_mfma_f32_16x16x32_bf16 v[12:15], v[210:213], v[184:187], v[12:15]
	v_mfma_f32_16x16x32_bf16 v[4:7], v[202:205], v[192:195], v[4:7]
	v_mfma_f32_16x16x32_bf16 v[0:3], v[210:213], v[192:195], v[0:3]
	v_mfma_f32_16x16x32_bf16 v[52:55], v[206:209], v[172:175], v[52:55]
	v_mfma_f32_16x16x32_bf16 v[44:47], v[214:217], v[172:175], v[44:47]
	v_mfma_f32_16x16x32_bf16 v[36:39], v[206:209], v[180:183], v[36:39]
	v_mfma_f32_16x16x32_bf16 v[28:31], v[214:217], v[180:183], v[28:31]
	v_mfma_f32_16x16x32_bf16 v[20:23], v[206:209], v[188:191], v[20:23]
	v_mfma_f32_16x16x32_bf16 v[12:15], v[214:217], v[188:191], v[12:15]
	v_mfma_f32_16x16x32_bf16 v[4:7], v[206:209], v[196:199], v[4:7]
	v_mfma_f32_16x16x32_bf16 v[0:3], v[214:217], v[196:199], v[0:3]
	s_setprio 0
	s_add_i32 s44, 0, 0x18000
	v_add_u32_e32 v140, s44, v167
	s_barrier
	ds_read_b128 v[128:131], v140
	ds_read_b128 v[132:135], v140 offset:1024
	ds_read_b128 v[136:139], v140 offset:2048
	ds_read_b128 v[140:143], v140 offset:3072
	s_add_u32 s18, s18, 0x80000
	s_addc_u32 s19, s19, 0
	s_mov_b32 m0, s26
	ds_read_b128 v[162:165], v169 offset:32768
	ds_read_b128 v[172:175], v169 offset:33792
	ds_read_b128 v[176:179], v169 offset:34816
	ds_read_b128 v[180:183], v169 offset:35840
	ds_read_b128 v[184:187], v169 offset:36864
	ds_read_b128 v[188:191], v169 offset:37888
	ds_read_b128 v[192:195], v169 offset:38912
	ds_read_b128 v[196:199], v169 offset:39936
	global_load_lds_dwordx4 v144, s[18:19]
	s_mov_b32 m0, s27
	s_nop 0
	global_load_lds_dwordx4 v148, s[18:19]
	s_waitcnt lgkmcnt(8)
	s_waitcnt vmcnt(10)
	s_barrier
; #define PG8_STAGE(bufoff, gbase, voff) do { _Pragma("unroll") for (int _i = 0; _i < 2; ++_i) \
;         __builtin_amdgcn_global_load_lds((const unsigned*)((const char*)(gbase) + (voff)[_i]), (LAS unsigned*)(lds + (bufoff) + ldsw + _i * 8192), 16, 0, 0); } while (0)
; #define PG8_LDA(dst, b, h) do { _Pragma("unroll") for (int m = 0; m < 4; ++m) _Pragma("unroll") for (int k = 0; k < 2; ++k) dst[m][k] = *(const LAS bf16x8*)(lds + PG8_SA(b, h) + aoff + m * 2048 + k * 1024); } while (0)
; #define PG8_LDB(dst, b, h) do { _Pragma("unroll") for (int n = 0; n < 2; ++n) _Pragma("unroll") for (int k = 0; k < 2; ++k) dst[n][k] = *(const LAS bf16x8*)(lds + PG8_SB(b, h) + boff + n * 2048 + k * 1024); } while (0)
; #define PG8_MMA(ai, bj, At, Bt) do { __builtin_amdgcn_s_setprio(1); _Pragma("unroll") for (int m = 0; m < 4; ++m) _Pragma("unroll") for (int n = 0; n < 2; ++n) _Pragma("unroll") for (int k = 0; k < 2; ++k) \
;         acc[ai][bj][m][n] = __builtin_amdgcn_mfma_f32_16x16x32_bf16(Bt[n][k], At[m][k], acc[ai][bj][m][n], 0, 0, 0); __builtin_amdgcn_s_setprio(0); } while (0)
; #define PG8_WAIT_V(n) asm volatile("s_waitcnt vmcnt(" #n ")" ::: "memory")
; #define PG8_WAIT_L(n) asm volatile("s_waitcnt lgkmcnt(" #n ")" ::: "memory")
; #define PG8_BAR __builtin_amdgcn_s_barrier()
; #define PG8_SCHED __builtin_amdgcn_sched_barrier(0)
; template <class Epi, class Sched>
; __device__ __forceinline__ void gemm_phase(LAS unsigned char* lds, const Gemm g, const Sched& S, const Epi& E) {
;     ...
;             PG8_WAIT_L(8); PG8_BAR; PG8_WAIT_L(0); PG8_MMA(0, 0, At, B0); PG8_BAR; PG8_SCHED;
;             PG8_LDB(B1, 1, 1); PG8_STAGE(PG8_SB(1, 0), b3, voffB);
;             PG8_BAR; PG8_WAIT_L(0); PG8_MMA(0, 1, At, B1); PG8_BAR;
;             PG8_LDA(At, 1, 1); PG8_STAGE(PG8_SA(1, 0), a3, voffA);
;             PG8_BAR; PG8_WAIT_L(0); PG8_MMA(1, 0, At, B0); PG8_BAR; PG8_SCHED;
;             PG8_STAGE(PG8_SB(1, 1), b3 + hstep, voffB);
;             PG8_WAIT_V(6); PG8_BAR; PG8_MMA(1, 1, At, B1); PG8_BAR;
	s_waitcnt lgkmcnt(0)
	s_setprio 1
	s_waitcnt lgkmcnt(0)
	v_mfma_f32_16x16x32_bf16 v[124:127], v[128:131], v[162:165], v[124:127]
	v_mfma_f32_16x16x32_bf16 v[120:123], v[136:139], v[162:165], v[120:123]
	v_mfma_f32_16x16x32_bf16 v[116:119], v[128:131], v[176:179], v[116:119]
	v_mfma_f32_16x16x32_bf16 v[112:115], v[136:139], v[176:179], v[112:115]
	v_mfma_f32_16x16x32_bf16 v[108:111], v[128:131], v[184:187], v[108:111]
	v_mfma_f32_16x16x32_bf16 v[100:103], v[136:139], v[184:187], v[100:103]
	v_mfma_f32_16x16x32_bf16 v[76:79], v[128:131], v[192:195], v[76:79]
	v_mfma_f32_16x16x32_bf16 v[72:75], v[136:139], v[192:195], v[72:75]
	v_mfma_f32_16x16x32_bf16 v[124:127], v[132:135], v[172:175], v[124:127]
	v_mfma_f32_16x16x32_bf16 v[120:123], v[140:143], v[172:175], v[120:123]
	v_mfma_f32_16x16x32_bf16 v[116:119], v[132:135], v[180:183], v[116:119]
	v_mfma_f32_16x16x32_bf16 v[112:115], v[140:143], v[180:183], v[112:115]
	v_mfma_f32_16x16x32_bf16 v[108:111], v[132:135], v[188:191], v[108:111]
	v_mfma_f32_16x16x32_bf16 v[100:103], v[140:143], v[188:191], v[100:103]
	v_mfma_f32_16x16x32_bf16 v[76:79], v[132:135], v[196:199], v[76:79]
	v_mfma_f32_16x16x32_bf16 v[72:75], v[140:143], v[196:199], v[72:75]
	s_setprio 0
	s_barrier
	s_add_i32 s18, 0, 0x1c000
	s_add_i32 s19, s44, s24
	v_add_u32_e32 v160, s18, v167
	s_add_u32 s0, s16, 0x80
	s_addc_u32 s1, s17, 0
	s_mov_b32 m0, s19
	ds_read_b128 v[202:205], v160
	ds_read_b128 v[206:209], v160 offset:1024
	ds_read_b128 v[210:213], v160 offset:2048
	ds_read_b128 v[214:217], v160 offset:3072
	global_load_lds_dwordx4 v146, s[0:1]
	s_add_i32 m0, s19, 0x2000
	s_nop 0
	global_load_lds_dwordx4 v150, s[0:1]
	s_waitcnt vmcnt(10)
	s_barrier
	s_waitcnt lgkmcnt(0)
	s_setprio 1
	s_waitcnt lgkmcnt(0)
	v_mfma_f32_16x16x32_bf16 v[104:107], v[202:205], v[162:165], v[104:107]
	v_mfma_f32_16x16x32_bf16 v[96:99], v[210:213], v[162:165], v[96:99]
	v_mfma_f32_16x16x32_bf16 v[92:95], v[202:205], v[176:179], v[92:95]
	v_mfma_f32_16x16x32_bf16 v[88:91], v[210:213], v[176:179], v[88:91]
	v_mfma_f32_16x16x32_bf16 v[84:87], v[202:205], v[184:187], v[84:87]
	v_mfma_f32_16x16x32_bf16 v[80:83], v[210:213], v[184:187], v[80:83]
	v_mfma_f32_16x16x32_bf16 v[68:71], v[202:205], v[192:195], v[68:71]
	v_mfma_f32_16x16x32_bf16 v[64:67], v[210:213], v[192:195], v[64:67]
	v_mfma_f32_16x16x32_bf16 v[104:107], v[206:209], v[172:175], v[104:107]
	v_mfma_f32_16x16x32_bf16 v[96:99], v[214:217], v[172:175], v[96:99]
	v_mfma_f32_16x16x32_bf16 v[92:95], v[206:209], v[180:183], v[92:95]
	v_mfma_f32_16x16x32_bf16 v[88:91], v[214:217], v[180:183], v[88:91]
	v_mfma_f32_16x16x32_bf16 v[84:87], v[206:209], v[188:191], v[84:87]
	v_mfma_f32_16x16x32_bf16 v[80:83], v[214:217], v[188:191], v[80:83]
	v_mfma_f32_16x16x32_bf16 v[68:71], v[206:209], v[196:199], v[68:71]
	v_mfma_f32_16x16x32_bf16 v[64:67], v[214:217], v[196:199], v[64:67]
	s_setprio 0
	s_mov_b32 m0, s31
	s_mov_b64 s[0:1], 0x80
	v_lshl_add_u64 v[218:219], v[222:223], 0, s[0:1]
	s_barrier
	ds_read_b128 v[162:165], v169 offset:49152
	ds_read_b128 v[172:175], v169 offset:50176
	ds_read_b128 v[176:179], v169 offset:51200
	ds_read_b128 v[180:183], v169 offset:52224
	ds_read_b128 v[184:187], v169 offset:53248
	ds_read_b128 v[188:191], v169 offset:54272
	ds_read_b128 v[192:195], v169 offset:55296
	ds_read_b128 v[196:199], v169 offset:56320
	global_load_lds_dwordx4 v[218:219], off
	v_lshl_add_u64 v[218:219], v[224:225], 0, s[0:1]
	s_mov_b32 m0, s33
	s_nop 0
	global_load_lds_dwordx4 v[218:219], off
	s_barrier
	s_waitcnt lgkmcnt(0)
	s_setprio 1
	s_waitcnt lgkmcnt(0)
	v_mfma_f32_16x16x32_bf16 v[60:63], v[128:131], v[162:165], v[60:63]
	v_mfma_f32_16x16x32_bf16 v[56:59], v[136:139], v[162:165], v[56:59]
	v_mfma_f32_16x16x32_bf16 v[48:51], v[128:131], v[176:179], v[48:51]
	v_mfma_f32_16x16x32_bf16 v[40:43], v[136:139], v[176:179], v[40:43]
	v_mfma_f32_16x16x32_bf16 v[32:35], v[128:131], v[184:187], v[32:35]
	v_mfma_f32_16x16x32_bf16 v[24:27], v[136:139], v[184:187], v[24:27]
	v_mfma_f32_16x16x32_bf16 v[16:19], v[128:131], v[192:195], v[16:19]
	v_mfma_f32_16x16x32_bf16 v[8:11], v[136:139], v[192:195], v[8:11]
	v_mfma_f32_16x16x32_bf16 v[60:63], v[132:135], v[172:175], v[60:63]
	v_mfma_f32_16x16x32_bf16 v[56:59], v[140:143], v[172:175], v[56:59]
	v_mfma_f32_16x16x32_bf16 v[48:51], v[132:135], v[180:183], v[48:51]
	v_mfma_f32_16x16x32_bf16 v[40:43], v[140:143], v[180:183], v[40:43]
	v_mfma_f32_16x16x32_bf16 v[32:35], v[132:135], v[188:191], v[32:35]
	v_mfma_f32_16x16x32_bf16 v[24:27], v[140:143], v[188:191], v[24:27]
	v_mfma_f32_16x16x32_bf16 v[16:19], v[132:135], v[196:199], v[16:19]
	v_mfma_f32_16x16x32_bf16 v[8:11], v[140:143], v[196:199], v[8:11]
	s_setprio 0
	s_barrier
	s_add_u32 s16, s16, 0x80080
	s_addc_u32 s17, s17, 0
	s_add_i32 s18, s18, s24
	s_mov_b32 m0, s18
	s_nop 0
	global_load_lds_dwordx4 v146, s[16:17]
	s_add_i32 m0, s18, 0x2000
	s_nop 0
	global_load_lds_dwordx4 v150, s[16:17]
	s_waitcnt vmcnt(10)
	s_barrier
	s_setprio 1
	v_mfma_f32_16x16x32_bf16 v[52:55], v[202:205], v[162:165], v[52:55]
	v_mfma_f32_16x16x32_bf16 v[44:47], v[210:213], v[162:165], v[44:47]
	v_mfma_f32_16x16x32_bf16 v[36:39], v[202:205], v[176:179], v[36:39]
	v_mfma_f32_16x16x32_bf16 v[28:31], v[210:213], v[176:179], v[28:31]
	v_mfma_f32_16x16x32_bf16 v[20:23], v[202:205], v[184:187], v[20:23]
	v_mfma_f32_16x16x32_bf16 v[12:15], v[210:213], v[184:187], v[12:15]
	v_mfma_f32_16x16x32_bf16 v[4:7], v[202:205], v[192:195], v[4:7]
	v_mfma_f32_16x16x32_bf16 v[0:3], v[210:213], v[192:195], v[0:3]
	v_mfma_f32_16x16x32_bf16 v[52:55], v[206:209], v[172:175], v[52:55]
	v_mfma_f32_16x16x32_bf16 v[44:47], v[214:217], v[172:175], v[44:47]
	v_mfma_f32_16x16x32_bf16 v[36:39], v[206:209], v[180:183], v[36:39]
	v_mfma_f32_16x16x32_bf16 v[28:31], v[214:217], v[180:183], v[28:31]
	v_mfma_f32_16x16x32_bf16 v[20:23], v[206:209], v[188:191], v[20:23]
	v_mfma_f32_16x16x32_bf16 v[12:15], v[214:217], v[188:191], v[12:15]
	v_mfma_f32_16x16x32_bf16 v[4:7], v[206:209], v[196:199], v[4:7]
	v_mfma_f32_16x16x32_bf16 v[0:3], v[214:217], v[196:199], v[0:3]
	s_setprio 0
	s_add_i32 s43, s43, 2
	s_add_u32 s14, s14, 0x100
	s_addc_u32 s15, s15, 0
	s_add_u32 s41, s41, 0x100
	s_addc_u32 s42, s42, 0
	s_cmp_gt_u32 s43, 29
	s_barrier
; __device__ __forceinline__ unsigned cvt_pk_bf16(float lo, float hi) { unsigned r; asm volatile("v_cvt_pk_bf16_f32 %0, %1, %2" : "=v"(r) : "v"(lo), "v"(hi)); return r; }
;     __device__ __forceinline__ void operator()(const AccT& acc, const Unit& u, int wr, int wc, int fr, int fq) const {
;         asm volatile("" : "+v"(fr), "+v"(fq));
;         const int row0 = u.pm * 256 + wr * 64 + fr; const int b = u.pn >> 1, ch0 = (u.pn & 1) * 256 + wc * 32 + 8 * fq;
;         const float sg = (fr & 1) ? -1.0f : 1.0f;
;         f32x4 yh[2][2];
; #pragma unroll
;         for (int bj = 0; bj < 2; ++bj)
; #pragma unroll
;             for (int n = 0; n < 2; ++n) yh[bj][n] = *(const f32x4*)(YCH + b * 512 + ch0 + bj * 128 + 4 * n) * sg;
; #pragma unroll
;         for (int ai = 0; ai < 2; ++ai)
; #pragma unroll
;             for (int m = 0; m < 4; ++m) {
;                 const int k = row0 + ai * 128 + m * 16;
; #pragma unroll
;                 for (int bj = 0; bj < 2; ++bj) {
;                     const f32x4 v0 = acc[ai][bj][m][0] + yh[bj][0], v1 = acc[ai][bj][m][1] + yh[bj][1];
;                     u32x4 w; w.x = cvt_pk_bf16(v0[0], v0[1]); w.y = cvt_pk_bf16(v0[2], v0[3]); w.z = cvt_pk_bf16(v1[0], v1[1]); w.w = cvt_pk_bf16(v1[2], v1[3]);
;                     *(u32x4*)(CAT + (size_t)(b * 2048 + k) * CATW + 1024 + ch0 + bj * 128) = w;
;                 }
	s_cbranch_scc0 .LBB0_826
	s_ashr_i32 s5, s38, 1
	s_lshl_b32 s7, s38, 8
	s_lshl_b32 s14, s5, 9
	s_and_b32 s7, s7, 0x100
	s_ashr_i32 s15, s14, 31
	v_mov_b32_e32 v171, v161
	v_mov_b32_e32 v128, v166
	s_or_b32 s7, s7, s30
	s_lshl_b64 s[14:15], s[14:15], 2
	s_add_u32 s14, s48, s14
	v_lshl_add_u32 v164, v128, 3, s7
	s_addc_u32 s15, s49, s15
	v_ashrrev_i32_e32 v165, 31, v164
	v_lshl_add_u64 v[128:129], v[164:165], 2, s[14:15]
	global_load_dwordx4 v[140:143], v[128:129], off
	global_load_dwordx4 v[136:139], v[128:129], off offset:16
	global_load_dwordx4 v[132:135], v[128:129], off offset:512
	s_nop 0
	global_load_dwordx4 v[128:131], v[128:129], off offset:528
	s_lshl_b32 s7, s12, 8
	s_lshl_b32 s5, s5, 11
	s_add_i32 s7, s7, s29
	v_and_b32_e32 v160, 1, v171
	s_add_i32 s7, s7, s5
	v_mov_b64_e32 v[162:163], s[96:97]
	v_cmp_eq_u32_e32 vcc, 0, v160
	v_add_u32_e32 v171, s7, v171
	v_lshlrev_b64 v[164:165], 1, v[164:165]
	v_cndmask_b32_e64 v160, -1.0, 1.0, vcc
	v_mad_i64_i32 v[172:173], s[14:15], v171, s37, v[162:163]
	v_add_u32_e32 v174, 16, v171
	v_lshl_add_u64 v[172:173], v[172:173], 0, v[164:165]
	v_mad_i64_i32 v[174:175], s[14:15], v174, s37, v[162:163]
	v_add_u32_e32 v176, 32, v171
	v_lshl_add_u64 v[174:175], v[174:175], 0, v[164:165]
	v_mad_i64_i32 v[176:177], s[14:15], v176, s37, v[162:163]
	v_lshl_add_u64 v[176:177], v[176:177], 0, v[164:165]
	v_add_u32_e32 v182, 48, v171
	s_and_b64 vcc, exec, s[2:3]
	s_mov_b32 s38, s4
	s_mov_b32 s12, s6
	s_mov_b64 s[16:17], s[10:11]
	s_waitcnt vmcnt(0)
	v_pk_fma_f32 v[126:127], v[142:143], v[160:161], v[126:127] op_sel_hi:[1,0,1]
	v_pk_fma_f32 v[124:125], v[140:141], v[160:161], v[124:125] op_sel_hi:[1,0,1]
	v_pk_fma_f32 v[122:123], v[138:139], v[160:161], v[122:123] op_sel_hi:[1,0,1]
	v_pk_fma_f32 v[180:181], v[128:129], v[160:161], v[80:81] op_sel_hi:[1,0,1]
	v_cvt_pk_bf16_f32 v80, v124, v125
	v_cvt_pk_bf16_f32 v81, v126, v127
	v_pk_fma_f32 v[120:121], v[136:137], v[160:161], v[120:121] op_sel_hi:[1,0,1]
	v_pk_fma_f32 v[106:107], v[134:135], v[160:161], v[106:107] op_sel_hi:[1,0,1]
	v_pk_fma_f32 v[104:105], v[132:133], v[160:161], v[104:105] op_sel_hi:[1,0,1]
	v_pk_fma_f32 v[178:179], v[130:131], v[160:161], v[82:83] op_sel_hi:[1,0,1]
	v_cvt_pk_bf16_f32 v82, v120, v121
	v_cvt_pk_bf16_f32 v83, v122, v123
	global_store_dwordx4 v[172:173], v[80:83], off offset:2048
	v_pk_fma_f32 v[98:99], v[130:131], v[160:161], v[98:99] op_sel_hi:[1,0,1]
	v_pk_fma_f32 v[96:97], v[128:129], v[160:161], v[96:97] op_sel_hi:[1,0,1]
	v_cvt_pk_bf16_f32 v80, v104, v105
	v_cvt_pk_bf16_f32 v81, v106, v107
	v_pk_fma_f32 v[118:119], v[142:143], v[160:161], v[118:119] op_sel_hi:[1,0,1]
	v_pk_fma_f32 v[116:117], v[140:141], v[160:161], v[116:117] op_sel_hi:[1,0,1]
	v_cvt_pk_bf16_f32 v82, v96, v97
	v_cvt_pk_bf16_f32 v83, v98, v99
	global_store_dwordx4 v[172:173], v[80:83], off offset:2304
	v_pk_fma_f32 v[114:115], v[138:139], v[160:161], v[114:115] op_sel_hi:[1,0,1]
	v_pk_fma_f32 v[112:113], v[136:137], v[160:161], v[112:113] op_sel_hi:[1,0,1]
	v_cvt_pk_bf16_f32 v80, v116, v117
	v_cvt_pk_bf16_f32 v81, v118, v119
	v_pk_fma_f32 v[94:95], v[134:135], v[160:161], v[94:95] op_sel_hi:[1,0,1]
	v_pk_fma_f32 v[92:93], v[132:133], v[160:161], v[92:93] op_sel_hi:[1,0,1]
	v_cvt_pk_bf16_f32 v82, v112, v113
	v_cvt_pk_bf16_f32 v83, v114, v115
	global_store_dwordx4 v[174:175], v[80:83], off offset:2048
	v_pk_fma_f32 v[90:91], v[130:131], v[160:161], v[90:91] op_sel_hi:[1,0,1]
	v_pk_fma_f32 v[88:89], v[128:129], v[160:161], v[88:89] op_sel_hi:[1,0,1]
	v_cvt_pk_bf16_f32 v80, v92, v93
	v_cvt_pk_bf16_f32 v81, v94, v95
	v_pk_fma_f32 v[110:111], v[142:143], v[160:161], v[110:111] op_sel_hi:[1,0,1]
	v_pk_fma_f32 v[108:109], v[140:141], v[160:161], v[108:109] op_sel_hi:[1,0,1]
	v_cvt_pk_bf16_f32 v82, v88, v89
	v_cvt_pk_bf16_f32 v83, v90, v91
	global_store_dwordx4 v[174:175], v[80:83], off offset:2304
	v_pk_fma_f32 v[102:103], v[138:139], v[160:161], v[102:103] op_sel_hi:[1,0,1]
	v_pk_fma_f32 v[100:101], v[136:137], v[160:161], v[100:101] op_sel_hi:[1,0,1]
	v_cvt_pk_bf16_f32 v80, v108, v109
	v_cvt_pk_bf16_f32 v81, v110, v111
	v_pk_fma_f32 v[86:87], v[134:135], v[160:161], v[86:87] op_sel_hi:[1,0,1]
	v_pk_fma_f32 v[84:85], v[132:133], v[160:161], v[84:85] op_sel_hi:[1,0,1]
	v_cvt_pk_bf16_f32 v82, v100, v101
	v_cvt_pk_bf16_f32 v83, v102, v103
	global_store_dwordx4 v[176:177], v[80:83], off offset:2048
	v_pk_fma_f32 v[76:77], v[140:141], v[160:161], v[76:77] op_sel_hi:[1,0,1]
	v_pk_fma_f32 v[78:79], v[142:143], v[160:161], v[78:79] op_sel_hi:[1,0,1]
	v_cvt_pk_bf16_f32 v80, v84, v85
	v_cvt_pk_bf16_f32 v81, v86, v87
	v_cvt_pk_bf16_f32 v82, v180, v181
	v_cvt_pk_bf16_f32 v83, v178, v179
	global_store_dwordx4 v[176:177], v[80:83], off offset:2304
	v_pk_fma_f32 v[70:71], v[134:135], v[160:161], v[70:71] op_sel_hi:[1,0,1]
	v_pk_fma_f32 v[68:69], v[132:133], v[160:161], v[68:69] op_sel_hi:[1,0,1]
	v_pk_fma_f32 v[80:81], v[138:139], v[160:161], v[74:75] op_sel_hi:[1,0,1]
	v_pk_fma_f32 v[74:75], v[136:137], v[160:161], v[72:73] op_sel_hi:[1,0,1]
	v_cvt_pk_bf16_f32 v72, v76, v77
	v_mad_i64_i32 v[76:77], s[14:15], v182, s37, v[162:163]
	v_cvt_pk_bf16_f32 v73, v78, v79
; __device__ __forceinline__ unsigned cvt_pk_bf16(float lo, float hi) { unsigned r; asm volatile("v_cvt_pk_bf16_f32 %0, %1, %2" : "=v"(r) : "v"(lo), "v"(hi)); return r; }
; #define PG8_WAIT_V(n) asm volatile("s_waitcnt vmcnt(" #n ")" ::: "memory")
; #define PG8_BAR __builtin_amdgcn_s_barrier()
; template <class Epi, class Sched>
; __device__ __forceinline__ void gemm_phase(LAS unsigned char* lds, const Gemm g, const Sched& S, const Epi& E) {
;     ...
;         if (!has_next) break;
; #pragma unroll
;         for (int a = 0; a < 2; ++a)
; #pragma unroll
;             for (int b = 0; b < 2; ++b)
; #pragma unroll
;                 for (int m = 0; m < 4; ++m)
; #pragma unroll
;                     for (int n = 0; n < 2; ++n) acc[a][b][m][n] = (f32x4){0.f, 0.f, 0.f, 0.f};
;         cur = nxt; cA = nA; cB = nB; ++ui;
;     }
;     PG8_WAIT_V(0);
;     if (wr == 0) PG8_BAR;
;     PG8_BAR;
;     __device__ __forceinline__ void operator()(const AccT& acc, const Unit& u, int wr, int wc, int fr, int fq) const {
;     ...
;             for (int m = 0; m < 4; ++m) {
;                 const int k = row0 + ai * 128 + m * 16;
; #pragma unroll
;                 for (int bj = 0; bj < 2; ++bj) {
;                     const f32x4 v0 = acc[ai][bj][m][0] + yh[bj][0], v1 = acc[ai][bj][m][1] + yh[bj][1];
;                     u32x4 w; w.x = cvt_pk_bf16(v0[0], v0[1]); w.y = cvt_pk_bf16(v0[2], v0[3]); w.z = cvt_pk_bf16(v1[0], v1[1]); w.w = cvt_pk_bf16(v1[2], v1[3]);
;                     *(u32x4*)(CAT + (size_t)(b * 2048 + k) * CATW + 1024 + ch0 + bj * 128) = w;
;                 }
	v_lshl_add_u64 v[76:77], v[76:77], 0, v[164:165]
	v_cvt_pk_bf16_f32 v74, v74, v75
	v_cvt_pk_bf16_f32 v75, v80, v81
	global_store_dwordx4 v[76:77], v[72:75], off offset:2048
	v_pk_fma_f32 v[60:61], v[140:141], v[160:161], v[60:61] op_sel_hi:[1,0,1]
	v_pk_fma_f32 v[62:63], v[142:143], v[160:161], v[62:63] op_sel_hi:[1,0,1]
	v_pk_fma_f32 v[72:73], v[130:131], v[160:161], v[66:67] op_sel_hi:[1,0,1]
	v_pk_fma_f32 v[66:67], v[128:129], v[160:161], v[64:65] op_sel_hi:[1,0,1]
	v_cvt_pk_bf16_f32 v64, v68, v69
	v_cvt_pk_bf16_f32 v65, v70, v71
	v_pk_fma_f32 v[54:55], v[134:135], v[160:161], v[54:55] op_sel_hi:[1,0,1]
	v_cvt_pk_bf16_f32 v66, v66, v67
	v_cvt_pk_bf16_f32 v67, v72, v73
	global_store_dwordx4 v[76:77], v[64:67], off offset:2304
	v_pk_fma_f32 v[52:53], v[132:133], v[160:161], v[52:53] op_sel_hi:[1,0,1]
	v_pk_fma_f32 v[38:39], v[134:135], v[160:161], v[38:39] op_sel_hi:[1,0,1]
	v_add_u32_e32 v66, 0x80, v171
	v_pk_fma_f32 v[64:65], v[138:139], v[160:161], v[58:59] op_sel_hi:[1,0,1]
	v_pk_fma_f32 v[58:59], v[136:137], v[160:161], v[56:57] op_sel_hi:[1,0,1]
	v_cvt_pk_bf16_f32 v56, v60, v61
	v_mad_i64_i32 v[60:61], s[14:15], v66, s37, v[162:163]
	v_cvt_pk_bf16_f32 v57, v62, v63
	v_lshl_add_u64 v[60:61], v[60:61], 0, v[164:165]
	v_cvt_pk_bf16_f32 v58, v58, v59
	v_cvt_pk_bf16_f32 v59, v64, v65
	global_store_dwordx4 v[60:61], v[56:59], off offset:2048
	v_pk_fma_f32 v[36:37], v[132:133], v[160:161], v[36:37] op_sel_hi:[1,0,1]
	v_pk_fma_f32 v[22:23], v[134:135], v[160:161], v[22:23] op_sel_hi:[1,0,1]
	v_pk_fma_f32 v[56:57], v[130:131], v[160:161], v[46:47] op_sel_hi:[1,0,1]
	v_pk_fma_f32 v[46:47], v[128:129], v[160:161], v[44:45] op_sel_hi:[1,0,1]
	v_cvt_pk_bf16_f32 v44, v52, v53
	v_cvt_pk_bf16_f32 v45, v54, v55
	v_add_u32_e32 v52, 0x90, v171
	v_cvt_pk_bf16_f32 v46, v46, v47
	v_cvt_pk_bf16_f32 v47, v56, v57
	global_store_dwordx4 v[60:61], v[44:47], off offset:2304
	v_pk_fma_f32 v[20:21], v[132:133], v[160:161], v[20:21] op_sel_hi:[1,0,1]
	v_pk_fma_f32 v[6:7], v[134:135], v[160:161], v[6:7] op_sel_hi:[1,0,1]
	v_pk_fma_f32 v[44:45], v[142:143], v[160:161], v[50:51] op_sel_hi:[1,0,1]
	v_pk_fma_f32 v[46:47], v[140:141], v[160:161], v[48:49] op_sel_hi:[1,0,1]
	v_pk_fma_f32 v[48:49], v[138:139], v[160:161], v[42:43] op_sel_hi:[1,0,1]
	v_pk_fma_f32 v[42:43], v[136:137], v[160:161], v[40:41] op_sel_hi:[1,0,1]
	v_cvt_pk_bf16_f32 v40, v46, v47
	v_cvt_pk_bf16_f32 v41, v44, v45
	v_mad_i64_i32 v[44:45], s[14:15], v52, s37, v[162:163]
	v_lshl_add_u64 v[44:45], v[44:45], 0, v[164:165]
	v_cvt_pk_bf16_f32 v42, v42, v43
	v_cvt_pk_bf16_f32 v43, v48, v49
	global_store_dwordx4 v[44:45], v[40:43], off offset:2048
	v_pk_fma_f32 v[4:5], v[132:133], v[160:161], v[4:5] op_sel_hi:[1,0,1]
	s_nop 0
	v_pk_fma_f32 v[40:41], v[130:131], v[160:161], v[30:31] op_sel_hi:[1,0,1]
	v_pk_fma_f32 v[30:31], v[128:129], v[160:161], v[28:29] op_sel_hi:[1,0,1]
	v_cvt_pk_bf16_f32 v28, v36, v37
	v_cvt_pk_bf16_f32 v29, v38, v39
	v_add_u32_e32 v36, 0xa0, v171
	v_cvt_pk_bf16_f32 v30, v30, v31
	v_cvt_pk_bf16_f32 v31, v40, v41
	global_store_dwordx4 v[44:45], v[28:31], off offset:2304
	s_nop 1
	v_pk_fma_f32 v[28:29], v[142:143], v[160:161], v[34:35] op_sel_hi:[1,0,1]
	v_pk_fma_f32 v[30:31], v[140:141], v[160:161], v[32:33] op_sel_hi:[1,0,1]
	v_pk_fma_f32 v[32:33], v[138:139], v[160:161], v[26:27] op_sel_hi:[1,0,1]
	v_pk_fma_f32 v[26:27], v[136:137], v[160:161], v[24:25] op_sel_hi:[1,0,1]
	v_cvt_pk_bf16_f32 v24, v30, v31
	v_cvt_pk_bf16_f32 v25, v28, v29
	v_mad_i64_i32 v[28:29], s[14:15], v36, s37, v[162:163]
	v_lshl_add_u64 v[28:29], v[28:29], 0, v[164:165]
	v_cvt_pk_bf16_f32 v26, v26, v27
	v_cvt_pk_bf16_f32 v27, v32, v33
	global_store_dwordx4 v[28:29], v[24:27], off offset:2048
	s_nop 1
	v_pk_fma_f32 v[24:25], v[130:131], v[160:161], v[14:15] op_sel_hi:[1,0,1]
	v_pk_fma_f32 v[14:15], v[128:129], v[160:161], v[12:13] op_sel_hi:[1,0,1]
	v_cvt_pk_bf16_f32 v12, v20, v21
	v_cvt_pk_bf16_f32 v13, v22, v23
	v_add_u32_e32 v20, 0xb0, v171
	v_cvt_pk_bf16_f32 v14, v14, v15
	v_cvt_pk_bf16_f32 v15, v24, v25
	global_store_dwordx4 v[28:29], v[12:15], off offset:2304
	s_nop 1
	v_pk_fma_f32 v[12:13], v[142:143], v[160:161], v[18:19] op_sel_hi:[1,0,1]
	v_pk_fma_f32 v[14:15], v[140:141], v[160:161], v[16:17] op_sel_hi:[1,0,1]
	v_pk_fma_f32 v[16:17], v[138:139], v[160:161], v[10:11] op_sel_hi:[1,0,1]
	v_pk_fma_f32 v[10:11], v[136:137], v[160:161], v[8:9] op_sel_hi:[1,0,1]
	v_cvt_pk_bf16_f32 v8, v14, v15
	v_cvt_pk_bf16_f32 v9, v12, v13
	v_mad_i64_i32 v[12:13], s[14:15], v20, s37, v[162:163]
	v_lshl_add_u64 v[12:13], v[12:13], 0, v[164:165]
	v_cvt_pk_bf16_f32 v10, v10, v11
	v_cvt_pk_bf16_f32 v11, v16, v17
	global_store_dwordx4 v[12:13], v[8:11], off offset:2048
	s_mov_b64 s[14:15], s[8:9]
	s_nop 0
	v_pk_fma_f32 v[8:9], v[130:131], v[160:161], v[2:3] op_sel_hi:[1,0,1]
	v_pk_fma_f32 v[2:3], v[128:129], v[160:161], v[0:1] op_sel_hi:[1,0,1]
	v_cvt_pk_bf16_f32 v0, v4, v5
	v_cvt_pk_bf16_f32 v1, v6, v7
	s_nop 0
	v_cvt_pk_bf16_f32 v2, v2, v3
	v_cvt_pk_bf16_f32 v3, v8, v9
	global_store_dwordx4 v[12:13], v[0:3], off offset:2304
	s_cbranch_vccz .LBB0_819
	s_waitcnt vmcnt(0)
	s_cmpk_gt_u32 s20, 0xff
	s_cbranch_scc1 .LBB0_830
	s_barrier

; #define PG8_STAGE(bufoff, gbase, voff) do { _Pragma("unroll") for (int _i = 0; _i < 2; ++_i) \
;         __builtin_amdgcn_global_load_lds((const unsigned*)((const char*)(gbase) + (voff)[_i]), (LAS unsigned*)(lds + (bufoff) + ldsw + _i * 8192), 16, 0, 0); } while (0)
; #define PG8_LDA(dst, b, h) do { _Pragma("unroll") for (int m = 0; m < 4; ++m) _Pragma("unroll") for (int k = 0; k < 2; ++k) dst[m][k] = *(const LAS bf16x8*)(lds + PG8_SA(b, h) + aoff + m * 2048 + k * 1024); } while (0)
; #define PG8_LDB(dst, b, h) do { _Pragma("unroll") for (int n = 0; n < 2; ++n) _Pragma("unroll") for (int k = 0; k < 2; ++k) dst[n][k] = *(const LAS bf16x8*)(lds + PG8_SB(b, h) + boff + n * 2048 + k * 1024); } while (0)
; #define PG8_MMA(ai, bj, At, Bt) do { __builtin_amdgcn_s_setprio(1); _Pragma("unroll") for (int m = 0; m < 4; ++m) _Pragma("unroll") for (int n = 0; n < 2; ++n) _Pragma("unroll") for (int k = 0; k < 2; ++k) \
;         acc[ai][bj][m][n] = __builtin_amdgcn_mfma_f32_16x16x32_bf16(Bt[n][k], At[m][k], acc[ai][bj][m][n], 0, 0, 0); __builtin_amdgcn_s_setprio(0); } while (0)
; #define PG8_WAIT_V(n) asm volatile("s_waitcnt vmcnt(" #n ")" ::: "memory")
; #define PG8_WAIT_L(n) asm volatile("s_waitcnt lgkmcnt(" #n ")" ::: "memory")
; #define PG8_BAR __builtin_amdgcn_s_barrier()
; #define PG8_SCHED __builtin_amdgcn_sched_barrier(0)
; template <class Epi, class Sched>
; __device__ __forceinline__ void gemm_phase(LAS unsigned char* lds, const Gemm g, const Sched& S, const Epi& E) {
;     ...
;             PG8_LDB(B0, 0, 0); PG8_SCHED; PG8_LDA(At, 0, 0); PG8_STAGE(PG8_SA(1, 1), a1 + hstep, voffA);
;             PG8_WAIT_L(8); PG8_BAR; PG8_WAIT_L(0); PG8_MMA(0, 0, At, B0); PG8_BAR; PG8_SCHED;
;             PG8_LDB(B1, 0, 1); PG8_STAGE(PG8_SB(0, 0), b2, voffB);
;             PG8_BAR; PG8_WAIT_L(0); PG8_MMA(0, 1, At, B1); PG8_BAR;
;             PG8_LDA(At, 0, 1); PG8_STAGE(PG8_SA(0, 0), a2, voffA);
;             PG8_BAR; PG8_WAIT_L(0); PG8_MMA(1, 0, At, B0); PG8_BAR; PG8_SCHED;
;             PG8_STAGE(PG8_SB(0, 1), b2 + hstep, voffB);
;             PG8_WAIT_V(6); PG8_BAR; PG8_MMA(1, 1, At, B1); PG8_BAR;
.LBB0_901:
	s_add_u32 s56, s26, 0x100
	s_addc_u32 s57, s27, 0
	s_mov_b32 s58, -2
	s_waitcnt vmcnt(0)
	ds_read_b128 v[128:131], v237
	ds_read_b128 v[132:135], v237 offset:1024
	ds_read_b128 v[136:139], v237 offset:2048
	ds_read_b128 v[140:143], v237 offset:3072
	s_add_u32 s26, s24, 0x100
	s_addc_u32 s27, s25, 0
	s_cmp_eq_u32 s58, 20
	s_cselect_b32 s31, s5, s27
	s_cselect_b32 s30, s4, s26
	s_cselect_b32 s29, s7, s57
	s_cselect_b32 s28, s6, s56
	v_lshl_add_u64 v[176:177], s[24:25], 0, v[210:211]
	s_add_i32 m0, s38, 0xc000
	ds_read_b128 v[144:147], v238
	ds_read_b128 v[148:151], v238 offset:1024
	ds_read_b128 v[152:155], v238 offset:2048
	ds_read_b128 v[156:159], v238 offset:3072
	ds_read_b128 v[160:163], v238 offset:4096
	ds_read_b128 v[164:167], v238 offset:5120
	ds_read_b128 v[168:171], v238 offset:6144
	ds_read_b128 v[172:175], v238 offset:7168
	global_load_lds_dwordx4 v[176:177], off
	v_lshl_add_u64 v[176:177], s[24:25], 0, v[212:213]
	s_add_i32 m0, s38, 0xe000
	s_nop 0
	global_load_lds_dwordx4 v[176:177], off
	s_waitcnt lgkmcnt(8)
	s_waitcnt vmcnt(10)
	s_barrier
	s_waitcnt lgkmcnt(0)
	s_setprio 1
	s_waitcnt lgkmcnt(0)
	v_mfma_f32_16x16x32_bf16 v[124:127], v[128:131], v[144:147], 0
	v_mfma_f32_16x16x32_bf16 v[120:123], v[136:139], v[144:147], 0
	v_mfma_f32_16x16x32_bf16 v[108:111], v[128:131], v[152:155], 0
	v_mfma_f32_16x16x32_bf16 v[104:107], v[136:139], v[152:155], 0
	v_mfma_f32_16x16x32_bf16 v[92:95], v[128:131], v[160:163], 0
	v_mfma_f32_16x16x32_bf16 v[88:91], v[136:139], v[160:163], 0
	v_mfma_f32_16x16x32_bf16 v[76:79], v[128:131], v[168:171], 0
	v_mfma_f32_16x16x32_bf16 v[72:75], v[136:139], v[168:171], 0
	v_mfma_f32_16x16x32_bf16 v[124:127], v[132:135], v[148:151], v[124:127]
	v_mfma_f32_16x16x32_bf16 v[120:123], v[140:143], v[148:151], v[120:123]
	v_mfma_f32_16x16x32_bf16 v[108:111], v[132:135], v[156:159], v[108:111]
	v_mfma_f32_16x16x32_bf16 v[104:107], v[140:143], v[156:159], v[104:107]
	v_mfma_f32_16x16x32_bf16 v[92:95], v[132:135], v[164:167], v[92:95]
	v_mfma_f32_16x16x32_bf16 v[88:91], v[140:143], v[164:167], v[88:91]
	v_mfma_f32_16x16x32_bf16 v[76:79], v[132:135], v[172:175], v[76:79]
	v_mfma_f32_16x16x32_bf16 v[72:75], v[140:143], v[172:175], v[72:75]
	s_setprio 0
	s_barrier
	s_add_i32 s24, s50, s37
	s_mov_b32 m0, s24
	ds_read_b128 v[176:179], v239
	ds_read_b128 v[180:183], v239 offset:1024
	ds_read_b128 v[184:187], v239 offset:2048
	ds_read_b128 v[188:191], v239 offset:3072
	global_load_lds_dwordx4 v204, s[28:29]
	s_add_i32 m0, s24, 0x2000
	s_nop 0
	global_load_lds_dwordx4 v208, s[28:29]
	s_waitcnt vmcnt(10)
	s_barrier
	s_waitcnt lgkmcnt(0)
	s_setprio 1
	s_waitcnt lgkmcnt(0)
	v_mfma_f32_16x16x32_bf16 v[116:119], v[176:179], v[144:147], 0
	v_mfma_f32_16x16x32_bf16 v[112:115], v[184:187], v[144:147], 0
	v_mfma_f32_16x16x32_bf16 v[100:103], v[176:179], v[152:155], 0
	v_mfma_f32_16x16x32_bf16 v[96:99], v[184:187], v[152:155], 0
	v_mfma_f32_16x16x32_bf16 v[84:87], v[176:179], v[160:163], 0
	v_mfma_f32_16x16x32_bf16 v[80:83], v[184:187], v[160:163], 0
	v_mfma_f32_16x16x32_bf16 v[68:71], v[176:179], v[168:171], 0
	v_mfma_f32_16x16x32_bf16 v[64:67], v[184:187], v[168:171], 0
	v_mfma_f32_16x16x32_bf16 v[116:119], v[180:183], v[148:151], v[116:119]
	v_mfma_f32_16x16x32_bf16 v[112:115], v[188:191], v[148:151], v[112:115]
	v_mfma_f32_16x16x32_bf16 v[100:103], v[180:183], v[156:159], v[100:103]
	v_mfma_f32_16x16x32_bf16 v[96:99], v[188:191], v[156:159], v[96:99]
	v_mfma_f32_16x16x32_bf16 v[84:87], v[180:183], v[164:167], v[84:87]
	v_mfma_f32_16x16x32_bf16 v[80:83], v[188:191], v[164:167], v[80:83]
	v_mfma_f32_16x16x32_bf16 v[68:71], v[180:183], v[172:175], v[68:71]
	v_mfma_f32_16x16x32_bf16 v[64:67], v[188:191], v[172:175], v[64:67]
	s_setprio 0
	s_mov_b32 m0, s38
	v_lshl_add_u64 v[196:197], s[30:31], 0, v[202:203]
	s_barrier
	ds_read_b128 v[144:147], v238 offset:16384
	ds_read_b128 v[148:151], v238 offset:17408
	ds_read_b128 v[152:155], v238 offset:18432
	ds_read_b128 v[156:159], v238 offset:19456
	ds_read_b128 v[160:163], v238 offset:20480
	ds_read_b128 v[164:167], v238 offset:21504
	ds_read_b128 v[168:171], v238 offset:22528
	ds_read_b128 v[172:175], v238 offset:23552
	global_load_lds_dwordx4 v202, s[30:31]
	v_lshl_add_u64 v[198:199], s[30:31], 0, v[206:207]
	s_mov_b32 m0, s39
	s_nop 0
	global_load_lds_dwordx4 v206, s[30:31]
	s_barrier
	s_waitcnt lgkmcnt(0)
	s_setprio 1
	s_waitcnt lgkmcnt(0)
	v_mfma_f32_16x16x32_bf16 v[60:63], v[128:131], v[144:147], 0
	v_mfma_f32_16x16x32_bf16 v[56:59], v[136:139], v[144:147], 0
	v_mfma_f32_16x16x32_bf16 v[44:47], v[128:131], v[152:155], 0
	v_mfma_f32_16x16x32_bf16 v[40:43], v[136:139], v[152:155], 0
	v_mfma_f32_16x16x32_bf16 v[28:31], v[128:131], v[160:163], 0
	v_mfma_f32_16x16x32_bf16 v[24:27], v[136:139], v[160:163], 0
	v_mfma_f32_16x16x32_bf16 v[12:15], v[128:131], v[168:171], 0
	v_mfma_f32_16x16x32_bf16 v[8:11], v[136:139], v[168:171], 0
	v_mfma_f32_16x16x32_bf16 v[60:63], v[132:135], v[148:151], v[60:63]
	v_mfma_f32_16x16x32_bf16 v[56:59], v[140:143], v[148:151], v[56:59]
	v_mfma_f32_16x16x32_bf16 v[44:47], v[132:135], v[156:159], v[44:47]
	v_mfma_f32_16x16x32_bf16 v[40:43], v[140:143], v[156:159], v[40:43]
	v_mfma_f32_16x16x32_bf16 v[28:31], v[132:135], v[164:167], v[28:31]
	v_mfma_f32_16x16x32_bf16 v[24:27], v[140:143], v[164:167], v[24:27]
	v_mfma_f32_16x16x32_bf16 v[12:15], v[132:135], v[172:175], v[12:15]
	v_mfma_f32_16x16x32_bf16 v[8:11], v[140:143], v[172:175], v[8:11]
	s_setprio 0
	s_barrier
	s_add_u32 s24, s28, 0x60000
	s_addc_u32 s25, s29, 0
	s_add_i32 s59, s51, s37
	s_mov_b32 m0, s59
	s_nop 0
	global_load_lds_dwordx4 v204, s[24:25]
	s_add_i32 m0, s59, 0x2000
	s_nop 0
	global_load_lds_dwordx4 v208, s[24:25]
	s_waitcnt vmcnt(10)
	s_barrier
; #define PG8_STAGE(bufoff, gbase, voff) do { _Pragma("unroll") for (int _i = 0; _i < 2; ++_i) \
;         __builtin_amdgcn_global_load_lds((const unsigned*)((const char*)(gbase) + (voff)[_i]), (LAS unsigned*)(lds + (bufoff) + ldsw + _i * 8192), 16, 0, 0); } while (0)
; #define PG8_LDA(dst, b, h) do { _Pragma("unroll") for (int m = 0; m < 4; ++m) _Pragma("unroll") for (int k = 0; k < 2; ++k) dst[m][k] = *(const LAS bf16x8*)(lds + PG8_SA(b, h) + aoff + m * 2048 + k * 1024); } while (0)
; #define PG8_LDB(dst, b, h) do { _Pragma("unroll") for (int n = 0; n < 2; ++n) _Pragma("unroll") for (int k = 0; k < 2; ++k) dst[n][k] = *(const LAS bf16x8*)(lds + PG8_SB(b, h) + boff + n * 2048 + k * 1024); } while (0)
; #define PG8_MMA(ai, bj, At, Bt) do { __builtin_amdgcn_s_setprio(1); _Pragma("unroll") for (int m = 0; m < 4; ++m) _Pragma("unroll") for (int n = 0; n < 2; ++n) _Pragma("unroll") for (int k = 0; k < 2; ++k) \
;         acc[ai][bj][m][n] = __builtin_amdgcn_mfma_f32_16x16x32_bf16(Bt[n][k], At[m][k], acc[ai][bj][m][n], 0, 0, 0); __builtin_amdgcn_s_setprio(0); } while (0)
; #define PG8_WAIT_V(n) asm volatile("s_waitcnt vmcnt(" #n ")" ::: "memory")
; #define PG8_WAIT_L(n) asm volatile("s_waitcnt lgkmcnt(" #n ")" ::: "memory")
; #define PG8_BAR __builtin_amdgcn_s_barrier()
; #define PG8_SCHED __builtin_amdgcn_sched_barrier(0)
; template <class Epi, class Sched>
; __device__ __forceinline__ void gemm_phase(LAS unsigned char* lds, const Gemm g, const Sched& S, const Epi& E) {
;     ...
;             PG8_WAIT_V(6); PG8_BAR; PG8_MMA(1, 1, At, B1); PG8_BAR;
;             PG8_LDB(B0, 1, 0); PG8_SCHED; PG8_LDA(At, 1, 0); PG8_STAGE(PG8_SA(0, 1), a2 + hstep, voffA);
;             PG8_WAIT_L(8); PG8_BAR; PG8_WAIT_L(0); PG8_MMA(0, 0, At, B0); PG8_BAR; PG8_SCHED;
;             PG8_LDB(B1, 1, 1); PG8_STAGE(PG8_SB(1, 0), b3, voffB);
;             PG8_BAR; PG8_WAIT_L(0); PG8_MMA(0, 1, At, B1); PG8_BAR;
;             PG8_LDA(At, 1, 1); PG8_STAGE(PG8_SA(1, 0), a3, voffA);
;             PG8_BAR; PG8_WAIT_L(0); PG8_MMA(1, 0, At, B0); PG8_BAR; PG8_SCHED;
	s_setprio 1
	v_mfma_f32_16x16x32_bf16 v[52:55], v[176:179], v[144:147], 0
	v_mfma_f32_16x16x32_bf16 v[48:51], v[184:187], v[144:147], 0
	v_mfma_f32_16x16x32_bf16 v[36:39], v[176:179], v[152:155], 0
	v_mfma_f32_16x16x32_bf16 v[32:35], v[184:187], v[152:155], 0
	v_mfma_f32_16x16x32_bf16 v[20:23], v[176:179], v[160:163], 0
	v_mfma_f32_16x16x32_bf16 v[16:19], v[184:187], v[160:163], 0
	v_mfma_f32_16x16x32_bf16 v[4:7], v[176:179], v[168:171], 0
	v_mfma_f32_16x16x32_bf16 v[0:3], v[184:187], v[168:171], 0
	v_mfma_f32_16x16x32_bf16 v[52:55], v[180:183], v[148:151], v[52:55]
	v_mfma_f32_16x16x32_bf16 v[48:51], v[188:191], v[148:151], v[48:51]
	v_mfma_f32_16x16x32_bf16 v[36:39], v[180:183], v[156:159], v[36:39]
	v_mfma_f32_16x16x32_bf16 v[32:35], v[188:191], v[156:159], v[32:35]
	v_mfma_f32_16x16x32_bf16 v[20:23], v[180:183], v[164:167], v[20:23]
	v_mfma_f32_16x16x32_bf16 v[16:19], v[188:191], v[164:167], v[16:19]
	v_mfma_f32_16x16x32_bf16 v[4:7], v[180:183], v[172:175], v[4:7]
	v_mfma_f32_16x16x32_bf16 v[0:3], v[188:191], v[172:175], v[0:3]
	s_setprio 0
	s_add_i32 s59, 0, 0x18000
	v_add_u32_e32 v140, s59, v236
	s_barrier
	ds_read_b128 v[128:131], v140
	ds_read_b128 v[132:135], v140 offset:1024
	ds_read_b128 v[136:139], v140 offset:2048
	ds_read_b128 v[140:143], v140 offset:3072
	s_add_u32 s24, s30, 0x60000
	s_addc_u32 s25, s31, 0
	s_mov_b32 m0, s40
	ds_read_b128 v[144:147], v238 offset:32768
	ds_read_b128 v[148:151], v238 offset:33792
	ds_read_b128 v[152:155], v238 offset:34816
	ds_read_b128 v[156:159], v238 offset:35840
	ds_read_b128 v[160:163], v238 offset:36864
	ds_read_b128 v[164:167], v238 offset:37888
	ds_read_b128 v[168:171], v238 offset:38912
	ds_read_b128 v[172:175], v238 offset:39936
	global_load_lds_dwordx4 v202, s[24:25]
	s_mov_b32 m0, s41
	s_nop 0
	global_load_lds_dwordx4 v206, s[24:25]
	s_waitcnt lgkmcnt(8)
	s_waitcnt vmcnt(10)
	s_barrier
	s_waitcnt lgkmcnt(0)
	s_setprio 1
	s_waitcnt lgkmcnt(0)
	v_mfma_f32_16x16x32_bf16 v[124:127], v[128:131], v[144:147], v[124:127]
	v_mfma_f32_16x16x32_bf16 v[120:123], v[136:139], v[144:147], v[120:123]
	v_mfma_f32_16x16x32_bf16 v[108:111], v[128:131], v[152:155], v[108:111]
	v_mfma_f32_16x16x32_bf16 v[104:107], v[136:139], v[152:155], v[104:107]
	v_mfma_f32_16x16x32_bf16 v[92:95], v[128:131], v[160:163], v[92:95]
	v_mfma_f32_16x16x32_bf16 v[88:91], v[136:139], v[160:163], v[88:91]
	v_mfma_f32_16x16x32_bf16 v[76:79], v[128:131], v[168:171], v[76:79]
	v_mfma_f32_16x16x32_bf16 v[72:75], v[136:139], v[168:171], v[72:75]
	v_mfma_f32_16x16x32_bf16 v[124:127], v[132:135], v[148:151], v[124:127]
	v_mfma_f32_16x16x32_bf16 v[120:123], v[140:143], v[148:151], v[120:123]
	v_mfma_f32_16x16x32_bf16 v[108:111], v[132:135], v[156:159], v[108:111]
	v_mfma_f32_16x16x32_bf16 v[104:107], v[140:143], v[156:159], v[104:107]
	v_mfma_f32_16x16x32_bf16 v[92:95], v[132:135], v[164:167], v[92:95]
	v_mfma_f32_16x16x32_bf16 v[88:91], v[140:143], v[164:167], v[88:91]
	v_mfma_f32_16x16x32_bf16 v[76:79], v[132:135], v[172:175], v[76:79]
	v_mfma_f32_16x16x32_bf16 v[72:75], v[140:143], v[172:175], v[72:75]
	s_setprio 0
	s_barrier
	s_add_i32 s30, 0, 0x1c000
	s_add_i32 s24, s59, s37
	v_add_u32_e32 v188, s30, v236
	s_add_u32 s0, s28, 0x80
	s_addc_u32 s1, s29, 0
	s_mov_b32 m0, s24
	ds_read_b128 v[176:179], v188
	ds_read_b128 v[180:183], v188 offset:1024
	ds_read_b128 v[184:187], v188 offset:2048
	ds_read_b128 v[188:191], v188 offset:3072
	global_load_lds_dwordx4 v204, s[0:1]
	s_add_i32 m0, s24, 0x2000
	s_nop 0
	global_load_lds_dwordx4 v208, s[0:1]
	s_waitcnt vmcnt(10)
	s_barrier
	s_waitcnt lgkmcnt(0)
	s_setprio 1
	s_waitcnt lgkmcnt(0)
	v_mfma_f32_16x16x32_bf16 v[116:119], v[176:179], v[144:147], v[116:119]
	v_mfma_f32_16x16x32_bf16 v[112:115], v[184:187], v[144:147], v[112:115]
	v_mfma_f32_16x16x32_bf16 v[100:103], v[176:179], v[152:155], v[100:103]
	v_mfma_f32_16x16x32_bf16 v[96:99], v[184:187], v[152:155], v[96:99]
	v_mfma_f32_16x16x32_bf16 v[84:87], v[176:179], v[160:163], v[84:87]
	v_mfma_f32_16x16x32_bf16 v[80:83], v[184:187], v[160:163], v[80:83]
	v_mfma_f32_16x16x32_bf16 v[68:71], v[176:179], v[168:171], v[68:71]
	v_mfma_f32_16x16x32_bf16 v[64:67], v[184:187], v[168:171], v[64:67]
	v_mfma_f32_16x16x32_bf16 v[116:119], v[180:183], v[148:151], v[116:119]
	v_mfma_f32_16x16x32_bf16 v[112:115], v[188:191], v[148:151], v[112:115]
	v_mfma_f32_16x16x32_bf16 v[100:103], v[180:183], v[156:159], v[100:103]
	v_mfma_f32_16x16x32_bf16 v[96:99], v[188:191], v[156:159], v[96:99]
	v_mfma_f32_16x16x32_bf16 v[84:87], v[180:183], v[164:167], v[84:87]
	v_mfma_f32_16x16x32_bf16 v[80:83], v[188:191], v[164:167], v[80:83]
	v_mfma_f32_16x16x32_bf16 v[68:71], v[180:183], v[172:175], v[68:71]
	v_mfma_f32_16x16x32_bf16 v[64:67], v[188:191], v[172:175], v[64:67]
	s_setprio 0
	s_mov_b32 m0, s47
	s_mov_b64 s[0:1], 0x80
	v_lshl_add_u64 v[192:193], v[196:197], 0, s[0:1]
	s_barrier
	ds_read_b128 v[144:147], v238 offset:49152
	ds_read_b128 v[148:151], v238 offset:50176
	ds_read_b128 v[152:155], v238 offset:51200
	ds_read_b128 v[156:159], v238 offset:52224
	ds_read_b128 v[160:163], v238 offset:53248
	ds_read_b128 v[164:167], v238 offset:54272
	ds_read_b128 v[168:171], v238 offset:55296
	ds_read_b128 v[172:175], v238 offset:56320
	global_load_lds_dwordx4 v[192:193], off
	v_lshl_add_u64 v[192:193], v[198:199], 0, s[0:1]
	s_mov_b32 m0, s48
	s_nop 0
	global_load_lds_dwordx4 v[192:193], off
	s_barrier
; #define PG8_STAGE(bufoff, gbase, voff) do { _Pragma("unroll") for (int _i = 0; _i < 2; ++_i) \
;         __builtin_amdgcn_global_load_lds((const unsigned*)((const char*)(gbase) + (voff)[_i]), (LAS unsigned*)(lds + (bufoff) + ldsw + _i * 8192), 16, 0, 0); } while (0)
; #define PG8_LDA(dst, b, h) do { _Pragma("unroll") for (int m = 0; m < 4; ++m) _Pragma("unroll") for (int k = 0; k < 2; ++k) dst[m][k] = *(const LAS bf16x8*)(lds + PG8_SA(b, h) + aoff + m * 2048 + k * 1024); } while (0)
; #define PG8_LDB(dst, b, h) do { _Pragma("unroll") for (int n = 0; n < 2; ++n) _Pragma("unroll") for (int k = 0; k < 2; ++k) dst[n][k] = *(const LAS bf16x8*)(lds + PG8_SB(b, h) + boff + n * 2048 + k * 1024); } while (0)
; #define PG8_MMA(ai, bj, At, Bt) do { __builtin_amdgcn_s_setprio(1); _Pragma("unroll") for (int m = 0; m < 4; ++m) _Pragma("unroll") for (int n = 0; n < 2; ++n) _Pragma("unroll") for (int k = 0; k < 2; ++k) \
;         acc[ai][bj][m][n] = __builtin_amdgcn_mfma_f32_16x16x32_bf16(Bt[n][k], At[m][k], acc[ai][bj][m][n], 0, 0, 0); __builtin_amdgcn_s_setprio(0); } while (0)
; #define PG8_WAIT_V(n) asm volatile("s_waitcnt vmcnt(" #n ")" ::: "memory")
; #define PG8_WAIT_L(n) asm volatile("s_waitcnt lgkmcnt(" #n ")" ::: "memory")
; #define PG8_BAR __builtin_amdgcn_s_barrier()
; #define PG8_SCHED __builtin_amdgcn_sched_barrier(0)
; template <class Epi, class Sched>
; __device__ __forceinline__ void gemm_phase(LAS unsigned char* lds, const Gemm g, const Sched& S, const Epi& E) {
;     ...
;             PG8_LDB(B0, 0, 0); PG8_SCHED; PG8_LDA(At, 0, 0); PG8_STAGE(PG8_SA(1, 1), a1 + hstep, voffA);
;             PG8_WAIT_L(8); PG8_BAR; PG8_WAIT_L(0); PG8_MMA(0, 0, At, B0); PG8_BAR; PG8_SCHED;
;             PG8_LDB(B1, 0, 1); PG8_STAGE(PG8_SB(0, 0), b2, voffB);
;             PG8_BAR; PG8_WAIT_L(0); PG8_MMA(0, 1, At, B1); PG8_BAR;
;     ...
;             PG8_BAR; PG8_WAIT_L(0); PG8_MMA(1, 0, At, B0); PG8_BAR; PG8_SCHED;
;             PG8_STAGE(PG8_SB(1, 1), b3 + hstep, voffB);
;             PG8_WAIT_V(6); PG8_BAR; PG8_MMA(1, 1, At, B1); PG8_BAR;
	s_waitcnt lgkmcnt(0)
	s_setprio 1
	s_waitcnt lgkmcnt(0)
	v_mfma_f32_16x16x32_bf16 v[60:63], v[128:131], v[144:147], v[60:63]
	v_mfma_f32_16x16x32_bf16 v[56:59], v[136:139], v[144:147], v[56:59]
	v_mfma_f32_16x16x32_bf16 v[44:47], v[128:131], v[152:155], v[44:47]
	v_mfma_f32_16x16x32_bf16 v[40:43], v[136:139], v[152:155], v[40:43]
	v_mfma_f32_16x16x32_bf16 v[28:31], v[128:131], v[160:163], v[28:31]
	v_mfma_f32_16x16x32_bf16 v[24:27], v[136:139], v[160:163], v[24:27]
	v_mfma_f32_16x16x32_bf16 v[12:15], v[128:131], v[168:171], v[12:15]
	v_mfma_f32_16x16x32_bf16 v[8:11], v[136:139], v[168:171], v[8:11]
	v_mfma_f32_16x16x32_bf16 v[60:63], v[132:135], v[148:151], v[60:63]
	v_mfma_f32_16x16x32_bf16 v[56:59], v[140:143], v[148:151], v[56:59]
	v_mfma_f32_16x16x32_bf16 v[44:47], v[132:135], v[156:159], v[44:47]
	v_mfma_f32_16x16x32_bf16 v[40:43], v[140:143], v[156:159], v[40:43]
	v_mfma_f32_16x16x32_bf16 v[28:31], v[132:135], v[164:167], v[28:31]
	v_mfma_f32_16x16x32_bf16 v[24:27], v[140:143], v[164:167], v[24:27]
	v_mfma_f32_16x16x32_bf16 v[12:15], v[132:135], v[172:175], v[12:15]
	v_mfma_f32_16x16x32_bf16 v[8:11], v[140:143], v[172:175], v[8:11]
	s_setprio 0
	s_barrier
	s_add_u32 s24, s28, 0x60080
	s_addc_u32 s25, s29, 0
	s_add_i32 s28, s30, s37
	s_mov_b32 m0, s28
	s_nop 0
	global_load_lds_dwordx4 v204, s[24:25]
	s_add_i32 m0, s28, 0x2000
	s_nop 0
	global_load_lds_dwordx4 v208, s[24:25]
	s_waitcnt vmcnt(10)
	s_barrier
	s_setprio 1
	v_mfma_f32_16x16x32_bf16 v[52:55], v[176:179], v[144:147], v[52:55]
	v_mfma_f32_16x16x32_bf16 v[48:51], v[184:187], v[144:147], v[48:51]
	v_mfma_f32_16x16x32_bf16 v[36:39], v[176:179], v[152:155], v[36:39]
	v_mfma_f32_16x16x32_bf16 v[32:35], v[184:187], v[152:155], v[32:35]
	v_mfma_f32_16x16x32_bf16 v[20:23], v[176:179], v[160:163], v[20:23]
	v_mfma_f32_16x16x32_bf16 v[16:19], v[184:187], v[160:163], v[16:19]
	v_mfma_f32_16x16x32_bf16 v[4:7], v[176:179], v[168:171], v[4:7]
	v_mfma_f32_16x16x32_bf16 v[0:3], v[184:187], v[168:171], v[0:3]
	v_mfma_f32_16x16x32_bf16 v[52:55], v[180:183], v[148:151], v[52:55]
	v_mfma_f32_16x16x32_bf16 v[48:51], v[188:191], v[148:151], v[48:51]
	v_mfma_f32_16x16x32_bf16 v[36:39], v[180:183], v[156:159], v[36:39]
	v_mfma_f32_16x16x32_bf16 v[32:35], v[188:191], v[156:159], v[32:35]
	v_mfma_f32_16x16x32_bf16 v[20:23], v[180:183], v[164:167], v[20:23]
	v_mfma_f32_16x16x32_bf16 v[16:19], v[188:191], v[164:167], v[16:19]
	v_mfma_f32_16x16x32_bf16 v[4:7], v[180:183], v[172:175], v[4:7]
	v_mfma_f32_16x16x32_bf16 v[0:3], v[188:191], v[172:175], v[0:3]
	s_setprio 0
	s_add_i32 s58, s58, 2
	s_add_u32 s56, s56, 0x100
	s_addc_u32 s57, s57, 0
	s_cmp_gt_u32 s58, 21
	s_mov_b64 s[24:25], s[26:27]
	s_barrier
.LBB0_902:
	ds_read_b128 v[128:131], v237
	ds_read_b128 v[132:135], v237 offset:1024
	ds_read_b128 v[136:139], v237 offset:2048
	ds_read_b128 v[140:143], v237 offset:3072
	s_add_u32 s26, s24, 0x100
	s_addc_u32 s27, s25, 0
	s_cmp_eq_u32 s58, 20
	s_cselect_b32 s31, s5, s27
	s_cselect_b32 s30, s4, s26
	s_cselect_b32 s29, s7, s57
	s_cselect_b32 s28, s6, s56
	v_lshl_add_u64 v[176:177], s[24:25], 0, v[210:211]
	s_add_i32 m0, s38, 0xc000
	ds_read_b128 v[144:147], v238
	ds_read_b128 v[148:151], v238 offset:1024
	ds_read_b128 v[152:155], v238 offset:2048
	ds_read_b128 v[156:159], v238 offset:3072
	ds_read_b128 v[160:163], v238 offset:4096
	ds_read_b128 v[164:167], v238 offset:5120
	ds_read_b128 v[168:171], v238 offset:6144
	ds_read_b128 v[172:175], v238 offset:7168
	global_load_lds_dwordx4 v[176:177], off
	v_lshl_add_u64 v[176:177], s[24:25], 0, v[212:213]
	s_add_i32 m0, s38, 0xe000
	s_nop 0
	global_load_lds_dwordx4 v[176:177], off
	s_waitcnt lgkmcnt(8)
	s_waitcnt vmcnt(10)
	s_barrier
	s_waitcnt lgkmcnt(0)
	s_setprio 1
	s_waitcnt lgkmcnt(0)
	v_mfma_f32_16x16x32_bf16 v[124:127], v[128:131], v[144:147], v[124:127]
	v_mfma_f32_16x16x32_bf16 v[120:123], v[136:139], v[144:147], v[120:123]
	v_mfma_f32_16x16x32_bf16 v[108:111], v[128:131], v[152:155], v[108:111]
	v_mfma_f32_16x16x32_bf16 v[104:107], v[136:139], v[152:155], v[104:107]
	v_mfma_f32_16x16x32_bf16 v[92:95], v[128:131], v[160:163], v[92:95]
	v_mfma_f32_16x16x32_bf16 v[88:91], v[136:139], v[160:163], v[88:91]
	v_mfma_f32_16x16x32_bf16 v[76:79], v[128:131], v[168:171], v[76:79]
	v_mfma_f32_16x16x32_bf16 v[72:75], v[136:139], v[168:171], v[72:75]
	v_mfma_f32_16x16x32_bf16 v[124:127], v[132:135], v[148:151], v[124:127]
	v_mfma_f32_16x16x32_bf16 v[120:123], v[140:143], v[148:151], v[120:123]
	v_mfma_f32_16x16x32_bf16 v[108:111], v[132:135], v[156:159], v[108:111]
	v_mfma_f32_16x16x32_bf16 v[104:107], v[140:143], v[156:159], v[104:107]
	v_mfma_f32_16x16x32_bf16 v[92:95], v[132:135], v[164:167], v[92:95]
	v_mfma_f32_16x16x32_bf16 v[88:91], v[140:143], v[164:167], v[88:91]
	v_mfma_f32_16x16x32_bf16 v[76:79], v[132:135], v[172:175], v[76:79]
	v_mfma_f32_16x16x32_bf16 v[72:75], v[140:143], v[172:175], v[72:75]
	s_setprio 0
	s_barrier
	s_add_i32 s24, s50, s37
	s_mov_b32 m0, s24
	ds_read_b128 v[176:179], v239
	ds_read_b128 v[180:183], v239 offset:1024
	ds_read_b128 v[184:187], v239 offset:2048
	ds_read_b128 v[188:191], v239 offset:3072
	global_load_lds_dwordx4 v204, s[28:29]
	s_add_i32 m0, s24, 0x2000
	s_nop 0
	global_load_lds_dwordx4 v208, s[28:29]
	s_waitcnt vmcnt(10)
	s_barrier
; #define PG8_STAGE(bufoff, gbase, voff) do { _Pragma("unroll") for (int _i = 0; _i < 2; ++_i) \
;         __builtin_amdgcn_global_load_lds((const unsigned*)((const char*)(gbase) + (voff)[_i]), (LAS unsigned*)(lds + (bufoff) + ldsw + _i * 8192), 16, 0, 0); } while (0)
; #define PG8_LDA(dst, b, h) do { _Pragma("unroll") for (int m = 0; m < 4; ++m) _Pragma("unroll") for (int k = 0; k < 2; ++k) dst[m][k] = *(const LAS bf16x8*)(lds + PG8_SA(b, h) + aoff + m * 2048 + k * 1024); } while (0)
; #define PG8_LDB(dst, b, h) do { _Pragma("unroll") for (int n = 0; n < 2; ++n) _Pragma("unroll") for (int k = 0; k < 2; ++k) dst[n][k] = *(const LAS bf16x8*)(lds + PG8_SB(b, h) + boff + n * 2048 + k * 1024); } while (0)
; #define PG8_MMA(ai, bj, At, Bt) do { __builtin_amdgcn_s_setprio(1); _Pragma("unroll") for (int m = 0; m < 4; ++m) _Pragma("unroll") for (int n = 0; n < 2; ++n) _Pragma("unroll") for (int k = 0; k < 2; ++k) \
;         acc[ai][bj][m][n] = __builtin_amdgcn_mfma_f32_16x16x32_bf16(Bt[n][k], At[m][k], acc[ai][bj][m][n], 0, 0, 0); __builtin_amdgcn_s_setprio(0); } while (0)
; #define PG8_WAIT_V(n) asm volatile("s_waitcnt vmcnt(" #n ")" ::: "memory")
; #define PG8_WAIT_L(n) asm volatile("s_waitcnt lgkmcnt(" #n ")" ::: "memory")
; #define PG8_BAR __builtin_amdgcn_s_barrier()
; #define PG8_SCHED __builtin_amdgcn_sched_barrier(0)
; template <class Epi, class Sched>
; __device__ __forceinline__ void gemm_phase(LAS unsigned char* lds, const Gemm g, const Sched& S, const Epi& E) {
;     ...
;             PG8_BAR; PG8_WAIT_L(0); PG8_MMA(0, 1, At, B1); PG8_BAR;
;             PG8_LDA(At, 0, 1); PG8_STAGE(PG8_SA(0, 0), a2, voffA);
;             PG8_BAR; PG8_WAIT_L(0); PG8_MMA(1, 0, At, B0); PG8_BAR; PG8_SCHED;
;             PG8_STAGE(PG8_SB(0, 1), b2 + hstep, voffB);
;             PG8_WAIT_V(6); PG8_BAR; PG8_MMA(1, 1, At, B1); PG8_BAR;
;             PG8_LDB(B0, 1, 0); PG8_SCHED; PG8_LDA(At, 1, 0); PG8_STAGE(PG8_SA(0, 1), a2 + hstep, voffA);
	s_waitcnt lgkmcnt(0)
	s_setprio 1
	s_waitcnt lgkmcnt(0)
	v_mfma_f32_16x16x32_bf16 v[116:119], v[176:179], v[144:147], v[116:119]
	v_mfma_f32_16x16x32_bf16 v[112:115], v[184:187], v[144:147], v[112:115]
	v_mfma_f32_16x16x32_bf16 v[100:103], v[176:179], v[152:155], v[100:103]
	v_mfma_f32_16x16x32_bf16 v[96:99], v[184:187], v[152:155], v[96:99]
	v_mfma_f32_16x16x32_bf16 v[84:87], v[176:179], v[160:163], v[84:87]
	v_mfma_f32_16x16x32_bf16 v[80:83], v[184:187], v[160:163], v[80:83]
	v_mfma_f32_16x16x32_bf16 v[68:71], v[176:179], v[168:171], v[68:71]
	v_mfma_f32_16x16x32_bf16 v[64:67], v[184:187], v[168:171], v[64:67]
	v_mfma_f32_16x16x32_bf16 v[116:119], v[180:183], v[148:151], v[116:119]
	v_mfma_f32_16x16x32_bf16 v[112:115], v[188:191], v[148:151], v[112:115]
	v_mfma_f32_16x16x32_bf16 v[100:103], v[180:183], v[156:159], v[100:103]
	v_mfma_f32_16x16x32_bf16 v[96:99], v[188:191], v[156:159], v[96:99]
	v_mfma_f32_16x16x32_bf16 v[84:87], v[180:183], v[164:167], v[84:87]
	v_mfma_f32_16x16x32_bf16 v[80:83], v[188:191], v[164:167], v[80:83]
	v_mfma_f32_16x16x32_bf16 v[68:71], v[180:183], v[172:175], v[68:71]
	v_mfma_f32_16x16x32_bf16 v[64:67], v[188:191], v[172:175], v[64:67]
	s_setprio 0
	s_mov_b32 m0, s38
	v_lshl_add_u64 v[196:197], s[30:31], 0, v[202:203]
	s_barrier
	ds_read_b128 v[144:147], v238 offset:16384
	ds_read_b128 v[148:151], v238 offset:17408
	ds_read_b128 v[152:155], v238 offset:18432
	ds_read_b128 v[156:159], v238 offset:19456
	ds_read_b128 v[160:163], v238 offset:20480
	ds_read_b128 v[164:167], v238 offset:21504
	ds_read_b128 v[168:171], v238 offset:22528
	ds_read_b128 v[172:175], v238 offset:23552
	global_load_lds_dwordx4 v202, s[30:31]
	v_lshl_add_u64 v[198:199], s[30:31], 0, v[206:207]
	s_mov_b32 m0, s39
	s_nop 0
	global_load_lds_dwordx4 v206, s[30:31]
	s_barrier
	s_waitcnt lgkmcnt(0)
	s_setprio 1
	s_waitcnt lgkmcnt(0)
	v_mfma_f32_16x16x32_bf16 v[60:63], v[128:131], v[144:147], v[60:63]
	v_mfma_f32_16x16x32_bf16 v[56:59], v[136:139], v[144:147], v[56:59]
	v_mfma_f32_16x16x32_bf16 v[44:47], v[128:131], v[152:155], v[44:47]
	v_mfma_f32_16x16x32_bf16 v[40:43], v[136:139], v[152:155], v[40:43]
	v_mfma_f32_16x16x32_bf16 v[28:31], v[128:131], v[160:163], v[28:31]
	v_mfma_f32_16x16x32_bf16 v[24:27], v[136:139], v[160:163], v[24:27]
	v_mfma_f32_16x16x32_bf16 v[12:15], v[128:131], v[168:171], v[12:15]
	v_mfma_f32_16x16x32_bf16 v[8:11], v[136:139], v[168:171], v[8:11]
	v_mfma_f32_16x16x32_bf16 v[60:63], v[132:135], v[148:151], v[60:63]
	v_mfma_f32_16x16x32_bf16 v[56:59], v[140:143], v[148:151], v[56:59]
	v_mfma_f32_16x16x32_bf16 v[44:47], v[132:135], v[156:159], v[44:47]
	v_mfma_f32_16x16x32_bf16 v[40:43], v[140:143], v[156:159], v[40:43]
	v_mfma_f32_16x16x32_bf16 v[28:31], v[132:135], v[164:167], v[28:31]
	v_mfma_f32_16x16x32_bf16 v[24:27], v[140:143], v[164:167], v[24:27]
	v_mfma_f32_16x16x32_bf16 v[12:15], v[132:135], v[172:175], v[12:15]
	v_mfma_f32_16x16x32_bf16 v[8:11], v[140:143], v[172:175], v[8:11]
	s_setprio 0
	s_barrier
	s_add_u32 s24, s28, 0x60000
	s_addc_u32 s25, s29, 0
	s_add_i32 s59, s51, s37
	s_mov_b32 m0, s59
	s_nop 0
	global_load_lds_dwordx4 v204, s[24:25]
	s_add_i32 m0, s59, 0x2000
	s_nop 0
	global_load_lds_dwordx4 v208, s[24:25]
	s_waitcnt vmcnt(10)
	s_barrier
	s_setprio 1
	v_mfma_f32_16x16x32_bf16 v[52:55], v[176:179], v[144:147], v[52:55]
	v_mfma_f32_16x16x32_bf16 v[48:51], v[184:187], v[144:147], v[48:51]
	v_mfma_f32_16x16x32_bf16 v[36:39], v[176:179], v[152:155], v[36:39]
	v_mfma_f32_16x16x32_bf16 v[32:35], v[184:187], v[152:155], v[32:35]
	v_mfma_f32_16x16x32_bf16 v[20:23], v[176:179], v[160:163], v[20:23]
	v_mfma_f32_16x16x32_bf16 v[16:19], v[184:187], v[160:163], v[16:19]
	v_mfma_f32_16x16x32_bf16 v[4:7], v[176:179], v[168:171], v[4:7]
	v_mfma_f32_16x16x32_bf16 v[0:3], v[184:187], v[168:171], v[0:3]
	v_mfma_f32_16x16x32_bf16 v[52:55], v[180:183], v[148:151], v[52:55]
	v_mfma_f32_16x16x32_bf16 v[48:51], v[188:191], v[148:151], v[48:51]
	v_mfma_f32_16x16x32_bf16 v[36:39], v[180:183], v[156:159], v[36:39]
	v_mfma_f32_16x16x32_bf16 v[32:35], v[188:191], v[156:159], v[32:35]
	v_mfma_f32_16x16x32_bf16 v[20:23], v[180:183], v[164:167], v[20:23]
	v_mfma_f32_16x16x32_bf16 v[16:19], v[188:191], v[164:167], v[16:19]
	v_mfma_f32_16x16x32_bf16 v[4:7], v[180:183], v[172:175], v[4:7]
	v_mfma_f32_16x16x32_bf16 v[0:3], v[188:191], v[172:175], v[0:3]
	s_setprio 0
	s_add_i32 s59, 0, 0x18000
	v_add_u32_e32 v140, s59, v236
	s_barrier
	ds_read_b128 v[128:131], v140
	ds_read_b128 v[132:135], v140 offset:1024
	ds_read_b128 v[136:139], v140 offset:2048
	ds_read_b128 v[140:143], v140 offset:3072
	s_add_u32 s24, s30, 0x60000
	s_addc_u32 s25, s31, 0
	s_mov_b32 m0, s40
	ds_read_b128 v[144:147], v238 offset:32768
	ds_read_b128 v[148:151], v238 offset:33792
	ds_read_b128 v[152:155], v238 offset:34816
	ds_read_b128 v[156:159], v238 offset:35840
	ds_read_b128 v[160:163], v238 offset:36864
	ds_read_b128 v[164:167], v238 offset:37888
	ds_read_b128 v[168:171], v238 offset:38912
	ds_read_b128 v[172:175], v238 offset:39936
	global_load_lds_dwordx4 v202, s[24:25]
	s_mov_b32 m0, s41
	s_nop 0
	global_load_lds_dwordx4 v206, s[24:25]
	s_waitcnt lgkmcnt(8)
	s_waitcnt vmcnt(10)
	s_barrier
; #define PG8_STAGE(bufoff, gbase, voff) do { _Pragma("unroll") for (int _i = 0; _i < 2; ++_i) \
;         __builtin_amdgcn_global_load_lds((const unsigned*)((const char*)(gbase) + (voff)[_i]), (LAS unsigned*)(lds + (bufoff) + ldsw + _i * 8192), 16, 0, 0); } while (0)
; #define PG8_LDA(dst, b, h) do { _Pragma("unroll") for (int m = 0; m < 4; ++m) _Pragma("unroll") for (int k = 0; k < 2; ++k) dst[m][k] = *(const LAS bf16x8*)(lds + PG8_SA(b, h) + aoff + m * 2048 + k * 1024); } while (0)
; #define PG8_LDB(dst, b, h) do { _Pragma("unroll") for (int n = 0; n < 2; ++n) _Pragma("unroll") for (int k = 0; k < 2; ++k) dst[n][k] = *(const LAS bf16x8*)(lds + PG8_SB(b, h) + boff + n * 2048 + k * 1024); } while (0)
; #define PG8_MMA(ai, bj, At, Bt) do { __builtin_amdgcn_s_setprio(1); _Pragma("unroll") for (int m = 0; m < 4; ++m) _Pragma("unroll") for (int n = 0; n < 2; ++n) _Pragma("unroll") for (int k = 0; k < 2; ++k) \
;         acc[ai][bj][m][n] = __builtin_amdgcn_mfma_f32_16x16x32_bf16(Bt[n][k], At[m][k], acc[ai][bj][m][n], 0, 0, 0); __builtin_amdgcn_s_setprio(0); } while (0)
; #define PG8_WAIT_V(n) asm volatile("s_waitcnt vmcnt(" #n ")" ::: "memory")
; #define PG8_WAIT_L(n) asm volatile("s_waitcnt lgkmcnt(" #n ")" ::: "memory")
; #define PG8_BAR __builtin_amdgcn_s_barrier()
; #define PG8_SCHED __builtin_amdgcn_sched_barrier(0)
; template <class Epi, class Sched>
; __device__ __forceinline__ void gemm_phase(LAS unsigned char* lds, const Gemm g, const Sched& S, const Epi& E) {
;     ...
;             PG8_WAIT_L(8); PG8_BAR; PG8_WAIT_L(0); PG8_MMA(0, 0, At, B0); PG8_BAR; PG8_SCHED;
;             PG8_LDB(B1, 1, 1); PG8_STAGE(PG8_SB(1, 0), b3, voffB);
;             PG8_BAR; PG8_WAIT_L(0); PG8_MMA(0, 1, At, B1); PG8_BAR;
;             PG8_LDA(At, 1, 1); PG8_STAGE(PG8_SA(1, 0), a3, voffA);
;             PG8_BAR; PG8_WAIT_L(0); PG8_MMA(1, 0, At, B0); PG8_BAR; PG8_SCHED;
;             PG8_STAGE(PG8_SB(1, 1), b3 + hstep, voffB);
;             PG8_WAIT_V(6); PG8_BAR; PG8_MMA(1, 1, At, B1); PG8_BAR;
	s_waitcnt lgkmcnt(0)
	s_setprio 1
	s_waitcnt lgkmcnt(0)
	v_mfma_f32_16x16x32_bf16 v[124:127], v[128:131], v[144:147], v[124:127]
	v_mfma_f32_16x16x32_bf16 v[120:123], v[136:139], v[144:147], v[120:123]
	v_mfma_f32_16x16x32_bf16 v[108:111], v[128:131], v[152:155], v[108:111]
	v_mfma_f32_16x16x32_bf16 v[104:107], v[136:139], v[152:155], v[104:107]
	v_mfma_f32_16x16x32_bf16 v[92:95], v[128:131], v[160:163], v[92:95]
	v_mfma_f32_16x16x32_bf16 v[88:91], v[136:139], v[160:163], v[88:91]
	v_mfma_f32_16x16x32_bf16 v[76:79], v[128:131], v[168:171], v[76:79]
	v_mfma_f32_16x16x32_bf16 v[72:75], v[136:139], v[168:171], v[72:75]
	v_mfma_f32_16x16x32_bf16 v[124:127], v[132:135], v[148:151], v[124:127]
	v_mfma_f32_16x16x32_bf16 v[120:123], v[140:143], v[148:151], v[120:123]
	v_mfma_f32_16x16x32_bf16 v[108:111], v[132:135], v[156:159], v[108:111]
	v_mfma_f32_16x16x32_bf16 v[104:107], v[140:143], v[156:159], v[104:107]
	v_mfma_f32_16x16x32_bf16 v[92:95], v[132:135], v[164:167], v[92:95]
	v_mfma_f32_16x16x32_bf16 v[88:91], v[140:143], v[164:167], v[88:91]
	v_mfma_f32_16x16x32_bf16 v[76:79], v[132:135], v[172:175], v[76:79]
	v_mfma_f32_16x16x32_bf16 v[72:75], v[140:143], v[172:175], v[72:75]
	s_setprio 0
	s_barrier
	s_add_i32 s30, 0, 0x1c000
	s_add_i32 s24, s59, s37
	v_add_u32_e32 v188, s30, v236
	s_add_u32 s0, s28, 0x80
	s_addc_u32 s1, s29, 0
	s_mov_b32 m0, s24
	ds_read_b128 v[176:179], v188
	ds_read_b128 v[180:183], v188 offset:1024
	ds_read_b128 v[184:187], v188 offset:2048
	ds_read_b128 v[188:191], v188 offset:3072
	global_load_lds_dwordx4 v204, s[0:1]
	s_add_i32 m0, s24, 0x2000
	s_nop 0
	global_load_lds_dwordx4 v208, s[0:1]
	s_waitcnt vmcnt(10)
	s_barrier
	s_waitcnt lgkmcnt(0)
	s_setprio 1
	s_waitcnt lgkmcnt(0)
	v_mfma_f32_16x16x32_bf16 v[116:119], v[176:179], v[144:147], v[116:119]
	v_mfma_f32_16x16x32_bf16 v[112:115], v[184:187], v[144:147], v[112:115]
	v_mfma_f32_16x16x32_bf16 v[100:103], v[176:179], v[152:155], v[100:103]
	v_mfma_f32_16x16x32_bf16 v[96:99], v[184:187], v[152:155], v[96:99]
	v_mfma_f32_16x16x32_bf16 v[84:87], v[176:179], v[160:163], v[84:87]
	v_mfma_f32_16x16x32_bf16 v[80:83], v[184:187], v[160:163], v[80:83]
	v_mfma_f32_16x16x32_bf16 v[68:71], v[176:179], v[168:171], v[68:71]
	v_mfma_f32_16x16x32_bf16 v[64:67], v[184:187], v[168:171], v[64:67]
	v_mfma_f32_16x16x32_bf16 v[116:119], v[180:183], v[148:151], v[116:119]
	v_mfma_f32_16x16x32_bf16 v[112:115], v[188:191], v[148:151], v[112:115]
	v_mfma_f32_16x16x32_bf16 v[100:103], v[180:183], v[156:159], v[100:103]
	v_mfma_f32_16x16x32_bf16 v[96:99], v[188:191], v[156:159], v[96:99]
	v_mfma_f32_16x16x32_bf16 v[84:87], v[180:183], v[164:167], v[84:87]
	v_mfma_f32_16x16x32_bf16 v[80:83], v[188:191], v[164:167], v[80:83]
	v_mfma_f32_16x16x32_bf16 v[68:71], v[180:183], v[172:175], v[68:71]
	v_mfma_f32_16x16x32_bf16 v[64:67], v[188:191], v[172:175], v[64:67]
	s_setprio 0
	s_mov_b32 m0, s47
	s_mov_b64 s[0:1], 0x80
	v_lshl_add_u64 v[192:193], v[196:197], 0, s[0:1]
	s_barrier
	ds_read_b128 v[144:147], v238 offset:49152
	ds_read_b128 v[148:151], v238 offset:50176
	ds_read_b128 v[152:155], v238 offset:51200
	ds_read_b128 v[156:159], v238 offset:52224
	ds_read_b128 v[160:163], v238 offset:53248
	ds_read_b128 v[164:167], v238 offset:54272
	ds_read_b128 v[168:171], v238 offset:55296
	ds_read_b128 v[172:175], v238 offset:56320
	global_load_lds_dwordx4 v[192:193], off
	v_lshl_add_u64 v[192:193], v[198:199], 0, s[0:1]
	s_mov_b32 m0, s48
	s_nop 0
	global_load_lds_dwordx4 v[192:193], off
	s_barrier
	s_waitcnt lgkmcnt(0)
	s_setprio 1
	s_waitcnt lgkmcnt(0)
	v_mfma_f32_16x16x32_bf16 v[60:63], v[128:131], v[144:147], v[60:63]
	v_mfma_f32_16x16x32_bf16 v[56:59], v[136:139], v[144:147], v[56:59]
	v_mfma_f32_16x16x32_bf16 v[44:47], v[128:131], v[152:155], v[44:47]
	v_mfma_f32_16x16x32_bf16 v[40:43], v[136:139], v[152:155], v[40:43]
	v_mfma_f32_16x16x32_bf16 v[28:31], v[128:131], v[160:163], v[28:31]
	v_mfma_f32_16x16x32_bf16 v[24:27], v[136:139], v[160:163], v[24:27]
	v_mfma_f32_16x16x32_bf16 v[12:15], v[128:131], v[168:171], v[12:15]
	v_mfma_f32_16x16x32_bf16 v[8:11], v[136:139], v[168:171], v[8:11]
	v_mfma_f32_16x16x32_bf16 v[60:63], v[132:135], v[148:151], v[60:63]
	v_mfma_f32_16x16x32_bf16 v[56:59], v[140:143], v[148:151], v[56:59]
	v_mfma_f32_16x16x32_bf16 v[44:47], v[132:135], v[156:159], v[44:47]
	v_mfma_f32_16x16x32_bf16 v[40:43], v[140:143], v[156:159], v[40:43]
	v_mfma_f32_16x16x32_bf16 v[28:31], v[132:135], v[164:167], v[28:31]
	v_mfma_f32_16x16x32_bf16 v[24:27], v[140:143], v[164:167], v[24:27]
	v_mfma_f32_16x16x32_bf16 v[12:15], v[132:135], v[172:175], v[12:15]
	v_mfma_f32_16x16x32_bf16 v[8:11], v[140:143], v[172:175], v[8:11]
	s_setprio 0
	s_barrier
	s_add_u32 s24, s28, 0x60080
	s_addc_u32 s25, s29, 0
	s_add_i32 s28, s30, s37
	s_mov_b32 m0, s28
	s_nop 0
	global_load_lds_dwordx4 v204, s[24:25]
	s_add_i32 m0, s28, 0x2000
	s_nop 0
	global_load_lds_dwordx4 v208, s[24:25]
	s_waitcnt vmcnt(10)
	s_barrier
	s_setprio 1
	v_mfma_f32_16x16x32_bf16 v[52:55], v[176:179], v[144:147], v[52:55]
	v_mfma_f32_16x16x32_bf16 v[48:51], v[184:187], v[144:147], v[48:51]
	v_mfma_f32_16x16x32_bf16 v[36:39], v[176:179], v[152:155], v[36:39]
	v_mfma_f32_16x16x32_bf16 v[32:35], v[184:187], v[152:155], v[32:35]
	v_mfma_f32_16x16x32_bf16 v[20:23], v[176:179], v[160:163], v[20:23]
	v_mfma_f32_16x16x32_bf16 v[16:19], v[184:187], v[160:163], v[16:19]
	v_mfma_f32_16x16x32_bf16 v[4:7], v[176:179], v[168:171], v[4:7]
	v_mfma_f32_16x16x32_bf16 v[0:3], v[184:187], v[168:171], v[0:3]
	v_mfma_f32_16x16x32_bf16 v[52:55], v[180:183], v[148:151], v[52:55]
	v_mfma_f32_16x16x32_bf16 v[48:51], v[188:191], v[148:151], v[48:51]
	v_mfma_f32_16x16x32_bf16 v[36:39], v[180:183], v[156:159], v[36:39]
	v_mfma_f32_16x16x32_bf16 v[32:35], v[188:191], v[156:159], v[32:35]
	v_mfma_f32_16x16x32_bf16 v[20:23], v[180:183], v[164:167], v[20:23]
	v_mfma_f32_16x16x32_bf16 v[16:19], v[188:191], v[164:167], v[16:19]
	v_mfma_f32_16x16x32_bf16 v[4:7], v[180:183], v[172:175], v[4:7]
	v_mfma_f32_16x16x32_bf16 v[0:3], v[188:191], v[172:175], v[0:3]
	s_setprio 0
	s_add_i32 s58, s58, 2
	s_add_u32 s56, s56, 0x100
	s_addc_u32 s57, s57, 0
	s_cmp_gt_u32 s58, 21
	s_mov_b64 s[24:25], s[26:27]
	s_barrier
; __device__ __forceinline__ unsigned cvt_pk_bf16(float lo, float hi) { unsigned r; asm volatile("v_cvt_pk_bf16_f32 %0, %1, %2" : "=v"(r) : "v"(lo), "v"(hi)); return r; }
; __device__ __forceinline__ float bf_lo(unsigned u) { return __uint_as_float(u << 16); }
; __device__ __forceinline__ float bf_hi(unsigned u) { return __uint_as_float(u & 0xffff0000u); }
;     __device__ __forceinline__ void operator()(const AccT& acc, const Unit& u, int wr, int wc, int fr, int fq) const {
;         asm volatile("" : "+v"(fr), "+v"(fq));
;         const int rowt = u.pm * 256; const int b = rowt >> 11;
;         const bf16_t* res = res_b + (size_t)rowt * DM; bf16_t* out = hb + (size_t)rowt * DM;
;         const int col0 = u.pn * 256 + wc * 32 + 8 * fq;
;         f32x4 gv[2][2];
; #pragma unroll
;         for (int bj = 0; bj < 2; ++bj)
; #pragma unroll
;             for (int n = 0; n < 2; ++n) gv[bj][n] = *(const f32x4*)(gate + (size_t)b * NMOD + col0 + bj * 128 + n * 4) * gs;
;         u32x4 r[2][4][2];
; #pragma unroll
;         for (int ai = 0; ai < 2; ++ai)
; #pragma unroll
;             for (int m = 0; m < 4; ++m)
; #pragma unroll
;                 for (int bj = 0; bj < 2; ++bj) r[ai][m][bj] = *(const u32x4*)(res + (size_t)(wr * 64 + fr + ai * 128 + m * 16) * DM + col0 + bj * 128);
; #pragma unroll
;         for (int ai = 0; ai < 2; ++ai)
; #pragma unroll
;             for (int m = 0; m < 4; ++m)
; #pragma unroll
;                 for (int bj = 0; bj < 2; ++bj) {
;                     const u32x4 q = r[ai][m][bj];
;                     const f32x4 r0 = {bf_lo(q.x), bf_hi(q.x), bf_lo(q.y), bf_hi(q.y)}, r1 = {bf_lo(q.z), bf_hi(q.z), bf_lo(q.w), bf_hi(q.w)};
;                     const f32x4 h0 = r0 + gv[bj][0] * acc[ai][bj][m][0], h1 = r1 + gv[bj][1] * acc[ai][bj][m][1];
;                     u32x4 w; w.x = cvt_pk_bf16(h0[0], h0[1]); w.y = cvt_pk_bf16(h0[2], h0[3]); w.z = cvt_pk_bf16(h1[0], h1[1]); w.w = cvt_pk_bf16(h1[2], h1[3]);
;                     *(u32x4*)(out + (size_t)(wr * 64 + fr + ai * 128 + m * 16) * DM + col0 + bj * 128) = w;
	s_cbranch_scc0 .LBB0_902
	s_lshl_b32 s27, s55, 8
	v_mov_b32_e32 v146, v235
	v_mov_b32_e32 v128, v234
	s_lshl_b32 s24, s54, 8
	s_ashr_i32 s26, s54, 3
	s_or_b32 s27, s27, s46
	s_ashr_i32 s25, s24, 31
	v_lshl_add_u32 v144, v128, 3, s27
	s_mul_hi_i32 s27, s26, 0x9000
	s_mul_i32 s26, s26, 0x9000
	s_add_u32 s26, s43, s26
	s_addc_u32 s27, s44, s27
	v_ashrrev_i32_e32 v145, 31, v144
	s_lshl_b64 s[24:25], s[24:25], 11
	v_lshl_add_u64 v[132:133], v[144:145], 2, s[26:27]
	s_add_u32 s26, s62, s24
	v_add_u32_e32 v146, s45, v146
	s_addc_u32 s27, s63, s25
	v_lshlrev_b64 v[222:223], 1, v[144:145]
	v_ashrrev_i32_e32 v147, 31, v146
	v_lshl_add_u64 v[144:145], s[26:27], 0, v[222:223]
	v_lshlrev_b64 v[248:249], 11, v[146:147]
	v_lshl_add_u64 v[146:147], v[144:145], 0, v[248:249]
	global_load_dwordx4 v[136:139], v[132:133], off offset:16
	global_load_dwordx4 v[140:143], v[132:133], off
	global_load_dwordx4 v[128:131], v[132:133], off offset:528
	s_nop 0
	global_load_dwordx4 v[132:135], v[132:133], off offset:512
	s_nop 0
	global_load_dwordx4 v[240:243], v[146:147], off
	global_load_dwordx4 v[244:247], v[146:147], off offset:256
	v_lshl_add_u64 v[232:233], v[248:249], 0, s[10:11]
	v_lshl_add_u64 v[146:147], v[144:145], 0, v[232:233]
	global_load_dwordx4 v[196:199], v[146:147], off
	global_load_dwordx4 v[192:195], v[146:147], off offset:256
	v_lshl_add_u64 v[230:231], v[248:249], 0, s[12:13]
	v_lshl_add_u64 v[146:147], v[144:145], 0, v[230:231]
	global_load_dwordx4 v[188:191], v[146:147], off
	global_load_dwordx4 v[184:187], v[146:147], off offset:256
	v_lshl_add_u64 v[228:229], v[248:249], 0, s[14:15]
	v_lshl_add_u64 v[146:147], v[144:145], 0, v[228:229]
	global_load_dwordx4 v[180:183], v[146:147], off
	global_load_dwordx4 v[176:179], v[146:147], off offset:256
	v_lshl_add_u64 v[226:227], v[248:249], 0, s[16:17]
	v_lshl_add_u64 v[146:147], v[144:145], 0, v[226:227]
	global_load_dwordx4 v[172:175], v[146:147], off
	global_load_dwordx4 v[168:171], v[146:147], off offset:256
	v_lshl_add_u64 v[224:225], v[248:249], 0, s[18:19]
	v_lshl_add_u64 v[146:147], v[144:145], 0, v[224:225]
	global_load_dwordx4 v[164:167], v[146:147], off
	global_load_dwordx4 v[160:163], v[146:147], off offset:256
	v_lshl_add_u64 v[220:221], v[248:249], 0, s[20:21]
	v_lshl_add_u64 v[146:147], v[144:145], 0, v[220:221]
	global_load_dwordx4 v[156:159], v[146:147], off
	global_load_dwordx4 v[152:155], v[146:147], off offset:256
	v_lshl_add_u64 v[218:219], v[248:249], 0, s[22:23]
	v_lshl_add_u64 v[144:145], v[144:145], 0, v[218:219]
	global_load_dwordx4 v[148:151], v[144:145], off
	s_nop 0
	global_load_dwordx4 v[144:147], v[144:145], off offset:256
	s_add_u32 s24, s80, s24
	s_addc_u32 s25, s81, s25
	v_lshl_add_u64 v[222:223], s[24:25], 0, v[222:223]
	v_lshl_add_u64 v[248:249], v[222:223], 0, v[248:249]
	s_and_b64 vcc, exec, s[2:3]
	s_mov_b32 s55, s52
	s_mov_b32 s54, s53
	s_mov_b64 s[26:27], s[6:7]
	s_mov_b64 s[24:25], s[4:5]
	s_waitcnt vmcnt(0)
	v_lshlrev_b32_e32 v250, 16, v240
	v_and_b32_e32 v251, 0xffff0000, v240
	v_lshlrev_b32_e32 v240, 16, v241
	v_and_b32_e32 v241, 0xffff0000, v241
	v_lshlrev_b32_e32 v252, 16, v242
	v_and_b32_e32 v253, 0xffff0000, v242
	v_lshlrev_b32_e32 v242, 16, v243
	v_and_b32_e32 v243, 0xffff0000, v243
	v_pk_fma_f32 v[126:127], v[126:127], v[142:143], v[240:241]
	v_pk_fma_f32 v[124:125], v[124:125], v[140:141], v[250:251]
	v_pk_fma_f32 v[240:241], v[122:123], v[138:139], v[242:243]
	v_pk_fma_f32 v[122:123], v[120:121], v[136:137], v[252:253]
	v_cvt_pk_bf16_f32 v120, v124, v125
	v_cvt_pk_bf16_f32 v121, v126, v127
	v_lshlrev_b32_e32 v124, 16, v246
	v_cvt_pk_bf16_f32 v122, v122, v123
	v_cvt_pk_bf16_f32 v123, v240, v241
	global_store_dwordx4 v[248:249], v[120:123], off
	v_and_b32_e32 v125, 0xffff0000, v246
	v_lshlrev_b32_e32 v126, 16, v247
	v_lshlrev_b32_e32 v120, 16, v244
	v_and_b32_e32 v121, 0xffff0000, v244
	v_and_b32_e32 v127, 0xffff0000, v247
	v_lshlrev_b32_e32 v122, 16, v245
	v_and_b32_e32 v123, 0xffff0000, v245
	v_pk_fma_f32 v[116:117], v[116:117], v[132:133], v[120:121]
	v_pk_fma_f32 v[120:121], v[114:115], v[130:131], v[126:127]
	v_pk_fma_f32 v[114:115], v[112:113], v[128:129], v[124:125]
	v_pk_fma_f32 v[118:119], v[118:119], v[134:135], v[122:123]
	v_cvt_pk_bf16_f32 v112, v116, v117
	v_lshlrev_b32_e32 v116, 16, v197
	v_cvt_pk_bf16_f32 v113, v118, v119
	v_cvt_pk_bf16_f32 v114, v114, v115
	v_cvt_pk_bf16_f32 v115, v120, v121
	global_store_dwordx4 v[248:249], v[112:115], off offset:256
	v_and_b32_e32 v117, 0xffff0000, v197
	v_lshlrev_b32_e32 v118, 16, v198
	v_lshlrev_b32_e32 v114, 16, v196
	v_and_b32_e32 v115, 0xffff0000, v196
	v_and_b32_e32 v119, 0xffff0000, v198
	v_lshlrev_b32_e32 v120, 16, v199
	v_and_b32_e32 v121, 0xffff0000, v199
	v_lshl_add_u64 v[112:113], v[222:223], 0, v[232:233]
	v_pk_fma_f32 v[110:111], v[110:111], v[142:143], v[116:117]
	v_pk_fma_f32 v[108:109], v[108:109], v[140:141], v[114:115]
	v_pk_fma_f32 v[114:115], v[106:107], v[138:139], v[120:121]
	v_pk_fma_f32 v[106:107], v[104:105], v[136:137], v[118:119]
	v_cvt_pk_bf16_f32 v104, v108, v109
	v_cvt_pk_bf16_f32 v105, v110, v111
	v_lshlrev_b32_e32 v108, 16, v194
	v_cvt_pk_bf16_f32 v106, v106, v107
	v_cvt_pk_bf16_f32 v107, v114, v115
	global_store_dwordx4 v[112:113], v[104:107], off
	v_and_b32_e32 v109, 0xffff0000, v194
	v_lshlrev_b32_e32 v110, 16, v195
	v_lshlrev_b32_e32 v104, 16, v192
	v_and_b32_e32 v105, 0xffff0000, v192
	v_and_b32_e32 v111, 0xffff0000, v195
	v_lshlrev_b32_e32 v106, 16, v193
	v_and_b32_e32 v107, 0xffff0000, v193
	v_pk_fma_f32 v[100:101], v[100:101], v[132:133], v[104:105]
	v_pk_fma_f32 v[104:105], v[98:99], v[130:131], v[110:111]
	v_pk_fma_f32 v[98:99], v[96:97], v[128:129], v[108:109]
; __device__ __forceinline__ unsigned cvt_pk_bf16(float lo, float hi) { unsigned r; asm volatile("v_cvt_pk_bf16_f32 %0, %1, %2" : "=v"(r) : "v"(lo), "v"(hi)); return r; }
; __device__ __forceinline__ float bf_lo(unsigned u) { return __uint_as_float(u << 16); }
; __device__ __forceinline__ float bf_hi(unsigned u) { return __uint_as_float(u & 0xffff0000u); }
;     __device__ __forceinline__ void operator()(const AccT& acc, const Unit& u, int wr, int wc, int fr, int fq) const {
;     ...
;         for (int ai = 0; ai < 2; ++ai)
; #pragma unroll
;             for (int m = 0; m < 4; ++m)
; #pragma unroll
;                 for (int bj = 0; bj < 2; ++bj) {
;                     const u32x4 q = r[ai][m][bj];
;                     const f32x4 r0 = {bf_lo(q.x), bf_hi(q.x), bf_lo(q.y), bf_hi(q.y)}, r1 = {bf_lo(q.z), bf_hi(q.z), bf_lo(q.w), bf_hi(q.w)};
;                     const f32x4 h0 = r0 + gv[bj][0] * acc[ai][bj][m][0], h1 = r1 + gv[bj][1] * acc[ai][bj][m][1];
;                     u32x4 w; w.x = cvt_pk_bf16(h0[0], h0[1]); w.y = cvt_pk_bf16(h0[2], h0[3]); w.z = cvt_pk_bf16(h1[0], h1[1]); w.w = cvt_pk_bf16(h1[2], h1[3]);
;                     *(u32x4*)(out + (size_t)(wr * 64 + fr + ai * 128 + m * 16) * DM + col0 + bj * 128) = w;
	v_pk_fma_f32 v[102:103], v[102:103], v[134:135], v[106:107]
	v_cvt_pk_bf16_f32 v96, v100, v101
	v_lshlrev_b32_e32 v100, 16, v189
	v_cvt_pk_bf16_f32 v97, v102, v103
	v_cvt_pk_bf16_f32 v98, v98, v99
	v_cvt_pk_bf16_f32 v99, v104, v105
	global_store_dwordx4 v[112:113], v[96:99], off offset:256
	v_and_b32_e32 v101, 0xffff0000, v189
	v_lshlrev_b32_e32 v102, 16, v190
	v_lshlrev_b32_e32 v98, 16, v188
	v_and_b32_e32 v99, 0xffff0000, v188
	v_and_b32_e32 v103, 0xffff0000, v190
	v_lshlrev_b32_e32 v104, 16, v191
	v_and_b32_e32 v105, 0xffff0000, v191
	v_lshl_add_u64 v[96:97], v[222:223], 0, v[230:231]
	v_pk_fma_f32 v[94:95], v[94:95], v[142:143], v[100:101]
	v_pk_fma_f32 v[92:93], v[92:93], v[140:141], v[98:99]
	v_pk_fma_f32 v[98:99], v[90:91], v[138:139], v[104:105]
	v_pk_fma_f32 v[90:91], v[88:89], v[136:137], v[102:103]
	v_cvt_pk_bf16_f32 v88, v92, v93
	v_cvt_pk_bf16_f32 v89, v94, v95
	v_lshlrev_b32_e32 v92, 16, v186
	v_cvt_pk_bf16_f32 v90, v90, v91
	v_cvt_pk_bf16_f32 v91, v98, v99
	global_store_dwordx4 v[96:97], v[88:91], off
	v_and_b32_e32 v93, 0xffff0000, v186
	v_lshlrev_b32_e32 v94, 16, v187
	v_lshlrev_b32_e32 v88, 16, v184
	v_and_b32_e32 v89, 0xffff0000, v184
	v_and_b32_e32 v95, 0xffff0000, v187
	v_lshlrev_b32_e32 v90, 16, v185
	v_and_b32_e32 v91, 0xffff0000, v185
	v_pk_fma_f32 v[84:85], v[84:85], v[132:133], v[88:89]
	v_pk_fma_f32 v[88:89], v[82:83], v[130:131], v[94:95]
	v_pk_fma_f32 v[82:83], v[80:81], v[128:129], v[92:93]
	v_pk_fma_f32 v[86:87], v[86:87], v[134:135], v[90:91]
	v_cvt_pk_bf16_f32 v80, v84, v85
	v_lshlrev_b32_e32 v84, 16, v181
	v_cvt_pk_bf16_f32 v81, v86, v87
	v_cvt_pk_bf16_f32 v82, v82, v83
	v_cvt_pk_bf16_f32 v83, v88, v89
	global_store_dwordx4 v[96:97], v[80:83], off offset:256
	v_and_b32_e32 v85, 0xffff0000, v181
	v_lshlrev_b32_e32 v86, 16, v182
	v_lshlrev_b32_e32 v82, 16, v180
	v_and_b32_e32 v83, 0xffff0000, v180
	v_and_b32_e32 v87, 0xffff0000, v182
	v_lshlrev_b32_e32 v88, 16, v183
	v_and_b32_e32 v89, 0xffff0000, v183
	v_lshl_add_u64 v[80:81], v[222:223], 0, v[228:229]
	v_pk_fma_f32 v[78:79], v[78:79], v[142:143], v[84:85]
	v_pk_fma_f32 v[76:77], v[76:77], v[140:141], v[82:83]
	v_pk_fma_f32 v[82:83], v[74:75], v[138:139], v[88:89]
	v_pk_fma_f32 v[74:75], v[72:73], v[136:137], v[86:87]
	v_cvt_pk_bf16_f32 v72, v76, v77
	v_cvt_pk_bf16_f32 v73, v78, v79
	v_lshlrev_b32_e32 v76, 16, v178
	v_cvt_pk_bf16_f32 v74, v74, v75
	v_cvt_pk_bf16_f32 v75, v82, v83
	global_store_dwordx4 v[80:81], v[72:75], off
	v_and_b32_e32 v77, 0xffff0000, v178
	v_lshlrev_b32_e32 v78, 16, v179
	v_lshlrev_b32_e32 v72, 16, v176
	v_and_b32_e32 v73, 0xffff0000, v176
	v_and_b32_e32 v79, 0xffff0000, v179
	v_lshlrev_b32_e32 v74, 16, v177
	v_and_b32_e32 v75, 0xffff0000, v177
	v_pk_fma_f32 v[68:69], v[68:69], v[132:133], v[72:73]
	v_pk_fma_f32 v[72:73], v[66:67], v[130:131], v[78:79]
	v_pk_fma_f32 v[66:67], v[64:65], v[128:129], v[76:77]
	v_pk_fma_f32 v[70:71], v[70:71], v[134:135], v[74:75]
	v_cvt_pk_bf16_f32 v64, v68, v69
	v_lshlrev_b32_e32 v68, 16, v173
	v_cvt_pk_bf16_f32 v65, v70, v71
	v_cvt_pk_bf16_f32 v66, v66, v67
	v_cvt_pk_bf16_f32 v67, v72, v73
	global_store_dwordx4 v[80:81], v[64:67], off offset:256
	v_and_b32_e32 v69, 0xffff0000, v173
	v_lshlrev_b32_e32 v70, 16, v174
	v_lshlrev_b32_e32 v66, 16, v172
	v_and_b32_e32 v67, 0xffff0000, v172
	v_and_b32_e32 v71, 0xffff0000, v174
	v_lshlrev_b32_e32 v72, 16, v175
	v_and_b32_e32 v73, 0xffff0000, v175
	v_lshl_add_u64 v[64:65], v[222:223], 0, v[226:227]
	v_pk_fma_f32 v[62:63], v[62:63], v[142:143], v[68:69]
	v_pk_fma_f32 v[60:61], v[60:61], v[140:141], v[66:67]
	v_pk_fma_f32 v[66:67], v[58:59], v[138:139], v[72:73]
	v_pk_fma_f32 v[58:59], v[56:57], v[136:137], v[70:71]
	v_cvt_pk_bf16_f32 v56, v60, v61
	v_cvt_pk_bf16_f32 v57, v62, v63
	v_lshlrev_b32_e32 v60, 16, v170
	v_cvt_pk_bf16_f32 v58, v58, v59
	v_cvt_pk_bf16_f32 v59, v66, v67
	global_store_dwordx4 v[64:65], v[56:59], off
	v_and_b32_e32 v61, 0xffff0000, v170
	v_lshlrev_b32_e32 v62, 16, v171
	v_lshlrev_b32_e32 v56, 16, v168
	v_and_b32_e32 v57, 0xffff0000, v168
	v_and_b32_e32 v63, 0xffff0000, v171
	v_lshlrev_b32_e32 v58, 16, v169
	v_and_b32_e32 v59, 0xffff0000, v169
	v_pk_fma_f32 v[52:53], v[52:53], v[132:133], v[56:57]
	v_pk_fma_f32 v[56:57], v[50:51], v[130:131], v[62:63]
	v_pk_fma_f32 v[50:51], v[48:49], v[128:129], v[60:61]
	v_pk_fma_f32 v[54:55], v[54:55], v[134:135], v[58:59]
	v_cvt_pk_bf16_f32 v48, v52, v53
	v_lshlrev_b32_e32 v52, 16, v165
	v_cvt_pk_bf16_f32 v49, v54, v55
; __device__ __forceinline__ unsigned cvt_pk_bf16(float lo, float hi) { unsigned r; asm volatile("v_cvt_pk_bf16_f32 %0, %1, %2" : "=v"(r) : "v"(lo), "v"(hi)); return r; }
; __device__ __forceinline__ float bf_lo(unsigned u) { return __uint_as_float(u << 16); }
; __device__ __forceinline__ float bf_hi(unsigned u) { return __uint_as_float(u & 0xffff0000u); }
; #define PG8_WAIT_V(n) asm volatile("s_waitcnt vmcnt(" #n ")" ::: "memory")
; #define PG8_BAR __builtin_amdgcn_s_barrier()
; template <class Epi, class Sched>
; __device__ __forceinline__ void gemm_phase(LAS unsigned char* lds, const Gemm g, const Sched& S, const Epi& E) {
;     ...
;         if (!has_next) break;
; #pragma unroll
;         for (int a = 0; a < 2; ++a)
; #pragma unroll
;             for (int b = 0; b < 2; ++b)
; #pragma unroll
;                 for (int m = 0; m < 4; ++m)
; #pragma unroll
;                     for (int n = 0; n < 2; ++n) acc[a][b][m][n] = (f32x4){0.f, 0.f, 0.f, 0.f};
;         cur = nxt; cA = nA; cB = nB; ++ui;
;     }
;     PG8_WAIT_V(0);
;     if (wr == 0) PG8_BAR;
;     PG8_BAR;
;     __device__ __forceinline__ void operator()(const AccT& acc, const Unit& u, int wr, int wc, int fr, int fq) const {
;     ...
;                 for (int bj = 0; bj < 2; ++bj) {
;                     const u32x4 q = r[ai][m][bj];
;                     const f32x4 r0 = {bf_lo(q.x), bf_hi(q.x), bf_lo(q.y), bf_hi(q.y)}, r1 = {bf_lo(q.z), bf_hi(q.z), bf_lo(q.w), bf_hi(q.w)};
;                     const f32x4 h0 = r0 + gv[bj][0] * acc[ai][bj][m][0], h1 = r1 + gv[bj][1] * acc[ai][bj][m][1];
;                     u32x4 w; w.x = cvt_pk_bf16(h0[0], h0[1]); w.y = cvt_pk_bf16(h0[2], h0[3]); w.z = cvt_pk_bf16(h1[0], h1[1]); w.w = cvt_pk_bf16(h1[2], h1[3]);
;                     *(u32x4*)(out + (size_t)(wr * 64 + fr + ai * 128 + m * 16) * DM + col0 + bj * 128) = w;
	v_cvt_pk_bf16_f32 v50, v50, v51
	v_cvt_pk_bf16_f32 v51, v56, v57
	global_store_dwordx4 v[64:65], v[48:51], off offset:256
	v_and_b32_e32 v53, 0xffff0000, v165
	v_lshlrev_b32_e32 v54, 16, v166
	v_lshlrev_b32_e32 v50, 16, v164
	v_and_b32_e32 v51, 0xffff0000, v164
	v_and_b32_e32 v55, 0xffff0000, v166
	v_lshlrev_b32_e32 v56, 16, v167
	v_and_b32_e32 v57, 0xffff0000, v167
	v_lshl_add_u64 v[48:49], v[222:223], 0, v[224:225]
	v_pk_fma_f32 v[46:47], v[46:47], v[142:143], v[52:53]
	v_pk_fma_f32 v[44:45], v[44:45], v[140:141], v[50:51]
	v_pk_fma_f32 v[50:51], v[42:43], v[138:139], v[56:57]
	v_pk_fma_f32 v[42:43], v[40:41], v[136:137], v[54:55]
	v_cvt_pk_bf16_f32 v40, v44, v45
	v_cvt_pk_bf16_f32 v41, v46, v47
	v_lshlrev_b32_e32 v44, 16, v162
	v_cvt_pk_bf16_f32 v42, v42, v43
	v_cvt_pk_bf16_f32 v43, v50, v51
	global_store_dwordx4 v[48:49], v[40:43], off
	v_and_b32_e32 v45, 0xffff0000, v162
	v_lshlrev_b32_e32 v46, 16, v163
	v_lshlrev_b32_e32 v40, 16, v160
	v_and_b32_e32 v41, 0xffff0000, v160
	v_and_b32_e32 v47, 0xffff0000, v163
	v_lshlrev_b32_e32 v42, 16, v161
	v_and_b32_e32 v43, 0xffff0000, v161
	v_pk_fma_f32 v[36:37], v[36:37], v[132:133], v[40:41]
	v_pk_fma_f32 v[40:41], v[34:35], v[130:131], v[46:47]
	v_pk_fma_f32 v[34:35], v[32:33], v[128:129], v[44:45]
	v_pk_fma_f32 v[38:39], v[38:39], v[134:135], v[42:43]
	v_cvt_pk_bf16_f32 v32, v36, v37
	v_lshlrev_b32_e32 v36, 16, v157
	v_cvt_pk_bf16_f32 v33, v38, v39
	v_cvt_pk_bf16_f32 v34, v34, v35
	v_cvt_pk_bf16_f32 v35, v40, v41
	global_store_dwordx4 v[48:49], v[32:35], off offset:256
	v_and_b32_e32 v37, 0xffff0000, v157
	v_lshlrev_b32_e32 v38, 16, v158
	v_lshlrev_b32_e32 v34, 16, v156
	v_and_b32_e32 v35, 0xffff0000, v156
	v_and_b32_e32 v39, 0xffff0000, v158
	v_lshlrev_b32_e32 v40, 16, v159
	v_and_b32_e32 v41, 0xffff0000, v159
	v_lshl_add_u64 v[32:33], v[222:223], 0, v[220:221]
	v_pk_fma_f32 v[30:31], v[30:31], v[142:143], v[36:37]
	v_pk_fma_f32 v[28:29], v[28:29], v[140:141], v[34:35]
	v_pk_fma_f32 v[34:35], v[26:27], v[138:139], v[40:41]
	v_pk_fma_f32 v[26:27], v[24:25], v[136:137], v[38:39]
	v_cvt_pk_bf16_f32 v24, v28, v29
	v_cvt_pk_bf16_f32 v25, v30, v31
	v_lshlrev_b32_e32 v28, 16, v154
	v_cvt_pk_bf16_f32 v26, v26, v27
	v_cvt_pk_bf16_f32 v27, v34, v35
	global_store_dwordx4 v[32:33], v[24:27], off
	v_and_b32_e32 v29, 0xffff0000, v154
	v_lshlrev_b32_e32 v30, 16, v155
	v_lshlrev_b32_e32 v24, 16, v152
	v_and_b32_e32 v25, 0xffff0000, v152
	v_and_b32_e32 v31, 0xffff0000, v155
	v_lshlrev_b32_e32 v26, 16, v153
	v_and_b32_e32 v27, 0xffff0000, v153
	v_pk_fma_f32 v[20:21], v[20:21], v[132:133], v[24:25]
	v_pk_fma_f32 v[24:25], v[18:19], v[130:131], v[30:31]
	v_pk_fma_f32 v[18:19], v[16:17], v[128:129], v[28:29]
	v_pk_fma_f32 v[22:23], v[22:23], v[134:135], v[26:27]
	v_cvt_pk_bf16_f32 v16, v20, v21
	v_lshlrev_b32_e32 v20, 16, v149
	v_cvt_pk_bf16_f32 v17, v22, v23
	v_cvt_pk_bf16_f32 v18, v18, v19
	v_cvt_pk_bf16_f32 v19, v24, v25
	global_store_dwordx4 v[32:33], v[16:19], off offset:256
	v_and_b32_e32 v21, 0xffff0000, v149
	v_lshlrev_b32_e32 v22, 16, v150
	v_lshlrev_b32_e32 v18, 16, v148
	v_and_b32_e32 v19, 0xffff0000, v148
	v_and_b32_e32 v23, 0xffff0000, v150
	v_lshlrev_b32_e32 v24, 16, v151
	v_and_b32_e32 v25, 0xffff0000, v151
	v_lshl_add_u64 v[16:17], v[222:223], 0, v[218:219]
	v_pk_fma_f32 v[14:15], v[14:15], v[142:143], v[20:21]
	v_pk_fma_f32 v[12:13], v[12:13], v[140:141], v[18:19]
	v_pk_fma_f32 v[18:19], v[10:11], v[138:139], v[24:25]
	v_pk_fma_f32 v[10:11], v[8:9], v[136:137], v[22:23]
	v_cvt_pk_bf16_f32 v8, v12, v13
	v_cvt_pk_bf16_f32 v9, v14, v15
	v_lshlrev_b32_e32 v12, 16, v146
	v_cvt_pk_bf16_f32 v10, v10, v11
	v_cvt_pk_bf16_f32 v11, v18, v19
	global_store_dwordx4 v[16:17], v[8:11], off
	v_and_b32_e32 v13, 0xffff0000, v146
	v_lshlrev_b32_e32 v14, 16, v147
	v_lshlrev_b32_e32 v8, 16, v144
	v_and_b32_e32 v9, 0xffff0000, v144
	v_and_b32_e32 v15, 0xffff0000, v147
	v_lshlrev_b32_e32 v10, 16, v145
	v_and_b32_e32 v11, 0xffff0000, v145
	v_pk_fma_f32 v[4:5], v[4:5], v[132:133], v[8:9]
	v_pk_fma_f32 v[8:9], v[2:3], v[130:131], v[14:15]
	v_pk_fma_f32 v[2:3], v[0:1], v[128:129], v[12:13]
	v_pk_fma_f32 v[6:7], v[6:7], v[134:135], v[10:11]
	v_cvt_pk_bf16_f32 v0, v4, v5
	s_nop 0
	v_cvt_pk_bf16_f32 v1, v6, v7
	v_cvt_pk_bf16_f32 v2, v2, v3
	v_cvt_pk_bf16_f32 v3, v8, v9
	global_store_dwordx4 v[16:17], v[0:3], off offset:256
	s_cbranch_vccz .LBB0_891
	s_waitcnt vmcnt(0)
	s_cmpk_gt_u32 s33, 0xff
	s_cbranch_scc1 .LBB0_906
	s_barrier

; #define PG8_STAGE(bufoff, gbase, voff) do { _Pragma("unroll") for (int _i = 0; _i < 2; ++_i) \
;         __builtin_amdgcn_global_load_lds((const unsigned*)((const char*)(gbase) + (voff)[_i]), (LAS unsigned*)(lds + (bufoff) + ldsw + _i * 8192), 16, 0, 0); } while (0)
; #define PG8_LDA(dst, b, h) do { _Pragma("unroll") for (int m = 0; m < 4; ++m) _Pragma("unroll") for (int k = 0; k < 2; ++k) dst[m][k] = *(const LAS bf16x8*)(lds + PG8_SA(b, h) + aoff + m * 2048 + k * 1024); } while (0)
; #define PG8_LDB(dst, b, h) do { _Pragma("unroll") for (int n = 0; n < 2; ++n) _Pragma("unroll") for (int k = 0; k < 2; ++k) dst[n][k] = *(const LAS bf16x8*)(lds + PG8_SB(b, h) + boff + n * 2048 + k * 1024); } while (0)
; #define PG8_MMA(ai, bj, At, Bt) do { __builtin_amdgcn_s_setprio(1); _Pragma("unroll") for (int m = 0; m < 4; ++m) _Pragma("unroll") for (int n = 0; n < 2; ++n) _Pragma("unroll") for (int k = 0; k < 2; ++k) \
;         acc[ai][bj][m][n] = __builtin_amdgcn_mfma_f32_16x16x32_bf16(Bt[n][k], At[m][k], acc[ai][bj][m][n], 0, 0, 0); __builtin_amdgcn_s_setprio(0); } while (0)
; #define PG8_WAIT_L(n) asm volatile("s_waitcnt lgkmcnt(" #n ")" ::: "memory")
; template <class Epi, class Sched>
; __device__ __forceinline__ void gemm_phase(LAS unsigned char* lds, const Gemm g, const Sched& S, const Epi& E) {
;     ...
;         const bool has_next = S.next(ui + 1, nxt);
;         const char* nA = has_next ? (const char*)g.A + (size_t)nxt.pm * tstep : cA; const char* nB = has_next ? (const char*)g.Bt + (size_t)nxt.pn * tstep : cB;
;         for (int t = 0; t < nt; t += 2) {
;             const bool last = (t == nt - 2);
;             const char* a1 = cA + (size_t)(t + 1) * kstep;
;             const char* a2 = last ? nA : cA + (size_t)(t + 2) * kstep; const char* b2 = last ? nB : cB + (size_t)(t + 2) * kstep;
;             const char* a3 = a2 + kstep; const char* b3 = b2 + kstep;
;             PG8_LDB(B0, 0, 0); PG8_SCHED; PG8_LDA(At, 0, 0); PG8_STAGE(PG8_SA(1, 1), a1 + hstep, voffA);
;             PG8_WAIT_L(8); PG8_BAR; PG8_WAIT_L(0); PG8_MMA(0, 0, At, B0); PG8_BAR; PG8_SCHED;
;             PG8_LDB(B1, 0, 1); PG8_STAGE(PG8_SB(0, 0), b2, voffB);
;             PG8_BAR; PG8_WAIT_L(0); PG8_MMA(0, 1, At, B1); PG8_BAR;
;             PG8_LDA(At, 0, 1); PG8_STAGE(PG8_SA(0, 0), a2, voffA);
;             PG8_BAR; PG8_WAIT_L(0); PG8_MMA(1, 0, At, B0); PG8_BAR; PG8_SCHED;
.LBB0_1020:
	s_ashr_i32 s7, s6, 31
	v_cmp_lt_i64_e32 vcc, s[10:11], v[140:141]
	s_lshl_b64 s[10:11], s[6:7], 19
	s_add_u32 s10, s96, s10
	s_addc_u32 s11, s97, s11
	s_and_b64 s[12:13], vcc, exec
	s_cselect_b32 s7, s11, s17
	s_cselect_b32 s42, s10, s16
	s_ashr_i32 s5, s4, 31
	s_lshl_b64 s[12:13], s[4:5], 19
	s_add_u32 s12, s23, s12
	s_addc_u32 s13, s24, s13
	s_and_b64 s[20:21], vcc, exec
	s_cselect_b32 s5, s13, s19
	s_cselect_b32 s43, s12, s18
	s_add_u32 s16, s16, 0x40080
	s_addc_u32 s17, s17, 0
	s_add_u32 s44, s18, 0x100
	s_addc_u32 s45, s19, 0
	s_mov_b32 s46, -2
	ds_read_b128 v[150:153], v147
	ds_read_b128 v[154:157], v147 offset:1024
	ds_read_b128 v[158:161], v147 offset:2048
	ds_read_b128 v[162:165], v147 offset:3072
	s_add_u32 s18, s16, 0xfffc0080
	s_addc_u32 s19, s17, -1
	s_cmp_eq_u32 s46, 12
	s_cselect_b32 s21, s7, s19
	s_cselect_b32 s20, s42, s18
	s_cselect_b32 s19, s5, s45
	s_cselect_b32 s18, s43, s44
	s_add_i32 m0, s15, 0xc000
	ds_read_b128 v[166:169], v148
	ds_read_b128 v[170:173], v148 offset:1024
	ds_read_b128 v[174:177], v148 offset:2048
	ds_read_b128 v[178:181], v148 offset:3072
	ds_read_b128 v[182:185], v148 offset:4096
	ds_read_b128 v[186:189], v148 offset:5120
	ds_read_b128 v[190:193], v148 offset:6144
	ds_read_b128 v[194:197], v148 offset:7168
	global_load_lds_dwordx4 v136, s[16:17]
	s_add_i32 m0, s15, 0xe000
	s_nop 0
	global_load_lds_dwordx4 v138, s[16:17]
	s_waitcnt lgkmcnt(8)
	s_waitcnt vmcnt(10)
	s_barrier
	s_waitcnt lgkmcnt(0)
	s_setprio 1
	s_waitcnt lgkmcnt(0)
	v_mfma_f32_16x16x32_bf16 v[124:127], v[150:153], v[166:169], 0
	v_mfma_f32_16x16x32_bf16 v[116:119], v[158:161], v[166:169], 0
	v_mfma_f32_16x16x32_bf16 v[108:111], v[150:153], v[174:177], 0
	v_mfma_f32_16x16x32_bf16 v[100:103], v[158:161], v[174:177], 0
	v_mfma_f32_16x16x32_bf16 v[92:95], v[150:153], v[182:185], 0
	v_mfma_f32_16x16x32_bf16 v[84:87], v[158:161], v[182:185], 0
	v_mfma_f32_16x16x32_bf16 v[76:79], v[150:153], v[190:193], 0
	v_mfma_f32_16x16x32_bf16 v[68:71], v[158:161], v[190:193], 0
	v_mfma_f32_16x16x32_bf16 v[124:127], v[154:157], v[170:173], v[124:127]
	v_mfma_f32_16x16x32_bf16 v[116:119], v[162:165], v[170:173], v[116:119]
	v_mfma_f32_16x16x32_bf16 v[108:111], v[154:157], v[178:181], v[108:111]
	v_mfma_f32_16x16x32_bf16 v[100:103], v[162:165], v[178:181], v[100:103]
	v_mfma_f32_16x16x32_bf16 v[92:95], v[154:157], v[186:189], v[92:95]
	v_mfma_f32_16x16x32_bf16 v[84:87], v[162:165], v[186:189], v[84:87]
	v_mfma_f32_16x16x32_bf16 v[76:79], v[154:157], v[194:197], v[76:79]
	v_mfma_f32_16x16x32_bf16 v[68:71], v[162:165], v[194:197], v[68:71]
	s_setprio 0
	s_barrier
	s_add_i32 s47, s38, s25
	s_mov_b32 m0, s47
	ds_read_b128 v[202:205], v149
	ds_read_b128 v[206:209], v149 offset:1024
	ds_read_b128 v[210:213], v149 offset:2048
	ds_read_b128 v[214:217], v149 offset:3072
	global_load_lds_dwordx4 v132, s[18:19]
	s_add_i32 m0, s47, 0x2000
	s_nop 0
	global_load_lds_dwordx4 v128, s[18:19]
	s_waitcnt vmcnt(10)
	s_barrier
	s_waitcnt lgkmcnt(0)
	s_setprio 1
	s_waitcnt lgkmcnt(0)
	v_mfma_f32_16x16x32_bf16 v[120:123], v[202:205], v[166:169], 0
	v_mfma_f32_16x16x32_bf16 v[112:115], v[210:213], v[166:169], 0
	v_mfma_f32_16x16x32_bf16 v[104:107], v[202:205], v[174:177], 0
	v_mfma_f32_16x16x32_bf16 v[96:99], v[210:213], v[174:177], 0
	v_mfma_f32_16x16x32_bf16 v[88:91], v[202:205], v[182:185], 0
	v_mfma_f32_16x16x32_bf16 v[80:83], v[210:213], v[182:185], 0
	v_mfma_f32_16x16x32_bf16 v[72:75], v[202:205], v[190:193], 0
	v_mfma_f32_16x16x32_bf16 v[64:67], v[210:213], v[190:193], 0
	v_mfma_f32_16x16x32_bf16 v[120:123], v[206:209], v[170:173], v[120:123]
	v_mfma_f32_16x16x32_bf16 v[112:115], v[214:217], v[170:173], v[112:115]
	v_mfma_f32_16x16x32_bf16 v[104:107], v[206:209], v[178:181], v[104:107]
	v_mfma_f32_16x16x32_bf16 v[96:99], v[214:217], v[178:181], v[96:99]
	v_mfma_f32_16x16x32_bf16 v[88:91], v[206:209], v[186:189], v[88:91]
	v_mfma_f32_16x16x32_bf16 v[80:83], v[214:217], v[186:189], v[80:83]
	v_mfma_f32_16x16x32_bf16 v[72:75], v[206:209], v[194:197], v[72:75]
	v_mfma_f32_16x16x32_bf16 v[64:67], v[214:217], v[194:197], v[64:67]
	s_setprio 0
	s_mov_b32 m0, s15
	v_lshl_add_u64 v[220:221], s[20:21], 0, v[134:135]
	s_barrier
	ds_read_b128 v[166:169], v148 offset:16384
	ds_read_b128 v[170:173], v148 offset:17408
	ds_read_b128 v[174:177], v148 offset:18432
	ds_read_b128 v[178:181], v148 offset:19456
	ds_read_b128 v[182:185], v148 offset:20480
	ds_read_b128 v[186:189], v148 offset:21504
	ds_read_b128 v[190:193], v148 offset:22528
	ds_read_b128 v[194:197], v148 offset:23552
	global_load_lds_dwordx4 v134, s[20:21]
	v_lshl_add_u64 v[222:223], s[20:21], 0, v[130:131]
	s_mov_b32 m0, s28
	s_nop 0
	global_load_lds_dwordx4 v130, s[20:21]
	s_barrier
	s_waitcnt lgkmcnt(0)
	s_setprio 1
	s_waitcnt lgkmcnt(0)
	v_mfma_f32_16x16x32_bf16 v[60:63], v[150:153], v[166:169], 0
	v_mfma_f32_16x16x32_bf16 v[56:59], v[158:161], v[166:169], 0
	v_mfma_f32_16x16x32_bf16 v[44:47], v[150:153], v[174:177], 0
	v_mfma_f32_16x16x32_bf16 v[40:43], v[158:161], v[174:177], 0
	v_mfma_f32_16x16x32_bf16 v[28:31], v[150:153], v[182:185], 0
	v_mfma_f32_16x16x32_bf16 v[24:27], v[158:161], v[182:185], 0
	v_mfma_f32_16x16x32_bf16 v[12:15], v[150:153], v[190:193], 0
	v_mfma_f32_16x16x32_bf16 v[8:11], v[158:161], v[190:193], 0
	v_mfma_f32_16x16x32_bf16 v[60:63], v[154:157], v[170:173], v[60:63]
	v_mfma_f32_16x16x32_bf16 v[56:59], v[162:165], v[170:173], v[56:59]
	v_mfma_f32_16x16x32_bf16 v[44:47], v[154:157], v[178:181], v[44:47]
	v_mfma_f32_16x16x32_bf16 v[40:43], v[162:165], v[178:181], v[40:43]
	v_mfma_f32_16x16x32_bf16 v[28:31], v[154:157], v[186:189], v[28:31]
	v_mfma_f32_16x16x32_bf16 v[24:27], v[162:165], v[186:189], v[24:27]
	v_mfma_f32_16x16x32_bf16 v[12:15], v[154:157], v[194:197], v[12:15]
	v_mfma_f32_16x16x32_bf16 v[8:11], v[162:165], v[194:197], v[8:11]
	s_setprio 0
	s_barrier
; #define PG8_STAGE(bufoff, gbase, voff) do { _Pragma("unroll") for (int _i = 0; _i < 2; ++_i) \
;         __builtin_amdgcn_global_load_lds((const unsigned*)((const char*)(gbase) + (voff)[_i]), (LAS unsigned*)(lds + (bufoff) + ldsw + _i * 8192), 16, 0, 0); } while (0)
; #define PG8_LDA(dst, b, h) do { _Pragma("unroll") for (int m = 0; m < 4; ++m) _Pragma("unroll") for (int k = 0; k < 2; ++k) dst[m][k] = *(const LAS bf16x8*)(lds + PG8_SA(b, h) + aoff + m * 2048 + k * 1024); } while (0)
; #define PG8_LDB(dst, b, h) do { _Pragma("unroll") for (int n = 0; n < 2; ++n) _Pragma("unroll") for (int k = 0; k < 2; ++k) dst[n][k] = *(const LAS bf16x8*)(lds + PG8_SB(b, h) + boff + n * 2048 + k * 1024); } while (0)
; #define PG8_MMA(ai, bj, At, Bt) do { __builtin_amdgcn_s_setprio(1); _Pragma("unroll") for (int m = 0; m < 4; ++m) _Pragma("unroll") for (int n = 0; n < 2; ++n) _Pragma("unroll") for (int k = 0; k < 2; ++k) \
;         acc[ai][bj][m][n] = __builtin_amdgcn_mfma_f32_16x16x32_bf16(Bt[n][k], At[m][k], acc[ai][bj][m][n], 0, 0, 0); __builtin_amdgcn_s_setprio(0); } while (0)
; #define PG8_WAIT_V(n) asm volatile("s_waitcnt vmcnt(" #n ")" ::: "memory")
; #define PG8_WAIT_L(n) asm volatile("s_waitcnt lgkmcnt(" #n ")" ::: "memory")
; #define PG8_BAR __builtin_amdgcn_s_barrier()
; #define PG8_SCHED __builtin_amdgcn_sched_barrier(0)
; template <class Epi, class Sched>
; __device__ __forceinline__ void gemm_phase(LAS unsigned char* lds, const Gemm g, const Sched& S, const Epi& E) {
;     ...
;             PG8_STAGE(PG8_SB(0, 1), b2 + hstep, voffB);
;             PG8_WAIT_V(6); PG8_BAR; PG8_MMA(1, 1, At, B1); PG8_BAR;
;             PG8_LDB(B0, 1, 0); PG8_SCHED; PG8_LDA(At, 1, 0); PG8_STAGE(PG8_SA(0, 1), a2 + hstep, voffA);
;             PG8_WAIT_L(8); PG8_BAR; PG8_WAIT_L(0); PG8_MMA(0, 0, At, B0); PG8_BAR; PG8_SCHED;
;             PG8_LDB(B1, 1, 1); PG8_STAGE(PG8_SB(1, 0), b3, voffB);
;             PG8_BAR; PG8_WAIT_L(0); PG8_MMA(0, 1, At, B1); PG8_BAR;
;             PG8_LDA(At, 1, 1); PG8_STAGE(PG8_SA(1, 0), a3, voffA);
	s_add_u32 s48, s18, 0x40000
	s_addc_u32 s49, s19, 0
	s_add_i32 s47, s39, s25
	s_mov_b32 m0, s47
	s_nop 0
	global_load_lds_dwordx4 v132, s[48:49]
	s_add_i32 m0, s47, 0x2000
	s_nop 0
	global_load_lds_dwordx4 v128, s[48:49]
	s_waitcnt vmcnt(10)
	s_barrier
	s_setprio 1
	v_mfma_f32_16x16x32_bf16 v[52:55], v[202:205], v[166:169], 0
	v_mfma_f32_16x16x32_bf16 v[48:51], v[210:213], v[166:169], 0
	v_mfma_f32_16x16x32_bf16 v[36:39], v[202:205], v[174:177], 0
	v_mfma_f32_16x16x32_bf16 v[32:35], v[210:213], v[174:177], 0
	v_mfma_f32_16x16x32_bf16 v[20:23], v[202:205], v[182:185], 0
	v_mfma_f32_16x16x32_bf16 v[16:19], v[210:213], v[182:185], 0
	v_mfma_f32_16x16x32_bf16 v[4:7], v[202:205], v[190:193], 0
	v_mfma_f32_16x16x32_bf16 v[0:3], v[210:213], v[190:193], 0
	v_mfma_f32_16x16x32_bf16 v[52:55], v[206:209], v[170:173], v[52:55]
	v_mfma_f32_16x16x32_bf16 v[48:51], v[214:217], v[170:173], v[48:51]
	v_mfma_f32_16x16x32_bf16 v[36:39], v[206:209], v[178:181], v[36:39]
	v_mfma_f32_16x16x32_bf16 v[32:35], v[214:217], v[178:181], v[32:35]
	v_mfma_f32_16x16x32_bf16 v[20:23], v[206:209], v[186:189], v[20:23]
	v_mfma_f32_16x16x32_bf16 v[16:19], v[214:217], v[186:189], v[16:19]
	v_mfma_f32_16x16x32_bf16 v[4:7], v[206:209], v[194:197], v[4:7]
	v_mfma_f32_16x16x32_bf16 v[0:3], v[214:217], v[194:197], v[0:3]
	s_setprio 0
	s_add_i32 s47, 0, 0x18000
	v_add_u32_e32 v162, s47, v146
	s_barrier
	ds_read_b128 v[150:153], v162
	ds_read_b128 v[154:157], v162 offset:1024
	ds_read_b128 v[158:161], v162 offset:2048
	ds_read_b128 v[162:165], v162 offset:3072
	s_add_u32 s20, s20, 0x40000
	s_addc_u32 s21, s21, 0
	s_mov_b32 m0, s29
	ds_read_b128 v[166:169], v148 offset:32768
	ds_read_b128 v[170:173], v148 offset:33792
	ds_read_b128 v[174:177], v148 offset:34816
	ds_read_b128 v[178:181], v148 offset:35840
	ds_read_b128 v[182:185], v148 offset:36864
	ds_read_b128 v[186:189], v148 offset:37888
	ds_read_b128 v[190:193], v148 offset:38912
	ds_read_b128 v[194:197], v148 offset:39936
	global_load_lds_dwordx4 v134, s[20:21]
	s_mov_b32 m0, s30
	s_nop 0
	global_load_lds_dwordx4 v130, s[20:21]
	s_waitcnt lgkmcnt(8)
	s_waitcnt vmcnt(10)
	s_barrier
	s_waitcnt lgkmcnt(0)
	s_setprio 1
	s_waitcnt lgkmcnt(0)
	v_mfma_f32_16x16x32_bf16 v[124:127], v[150:153], v[166:169], v[124:127]
	v_mfma_f32_16x16x32_bf16 v[116:119], v[158:161], v[166:169], v[116:119]
	v_mfma_f32_16x16x32_bf16 v[108:111], v[150:153], v[174:177], v[108:111]
	v_mfma_f32_16x16x32_bf16 v[100:103], v[158:161], v[174:177], v[100:103]
	v_mfma_f32_16x16x32_bf16 v[92:95], v[150:153], v[182:185], v[92:95]
	v_mfma_f32_16x16x32_bf16 v[84:87], v[158:161], v[182:185], v[84:87]
	v_mfma_f32_16x16x32_bf16 v[76:79], v[150:153], v[190:193], v[76:79]
	v_mfma_f32_16x16x32_bf16 v[68:71], v[158:161], v[190:193], v[68:71]
	v_mfma_f32_16x16x32_bf16 v[124:127], v[154:157], v[170:173], v[124:127]
	v_mfma_f32_16x16x32_bf16 v[116:119], v[162:165], v[170:173], v[116:119]
	v_mfma_f32_16x16x32_bf16 v[108:111], v[154:157], v[178:181], v[108:111]
	v_mfma_f32_16x16x32_bf16 v[100:103], v[162:165], v[178:181], v[100:103]
	v_mfma_f32_16x16x32_bf16 v[92:95], v[154:157], v[186:189], v[92:95]
	v_mfma_f32_16x16x32_bf16 v[84:87], v[162:165], v[186:189], v[84:87]
	v_mfma_f32_16x16x32_bf16 v[76:79], v[154:157], v[194:197], v[76:79]
	v_mfma_f32_16x16x32_bf16 v[68:71], v[162:165], v[194:197], v[68:71]
	s_setprio 0
	s_barrier
	s_add_i32 s20, 0, 0x1c000
	s_add_i32 s21, s47, s25
	v_add_u32_e32 v214, s20, v146
	s_add_u32 s0, s18, 0x80
	s_addc_u32 s1, s19, 0
	s_mov_b32 m0, s21
	ds_read_b128 v[202:205], v214
	ds_read_b128 v[206:209], v214 offset:1024
	ds_read_b128 v[210:213], v214 offset:2048
	ds_read_b128 v[214:217], v214 offset:3072
	global_load_lds_dwordx4 v132, s[0:1]
	s_add_i32 m0, s21, 0x2000
	s_nop 0
	global_load_lds_dwordx4 v128, s[0:1]
	s_waitcnt vmcnt(10)
	s_barrier
	s_waitcnt lgkmcnt(0)
	s_setprio 1
	s_waitcnt lgkmcnt(0)
	v_mfma_f32_16x16x32_bf16 v[120:123], v[202:205], v[166:169], v[120:123]
	v_mfma_f32_16x16x32_bf16 v[112:115], v[210:213], v[166:169], v[112:115]
	v_mfma_f32_16x16x32_bf16 v[104:107], v[202:205], v[174:177], v[104:107]
	v_mfma_f32_16x16x32_bf16 v[96:99], v[210:213], v[174:177], v[96:99]
	v_mfma_f32_16x16x32_bf16 v[88:91], v[202:205], v[182:185], v[88:91]
	v_mfma_f32_16x16x32_bf16 v[80:83], v[210:213], v[182:185], v[80:83]
	v_mfma_f32_16x16x32_bf16 v[72:75], v[202:205], v[190:193], v[72:75]
	v_mfma_f32_16x16x32_bf16 v[64:67], v[210:213], v[190:193], v[64:67]
	v_mfma_f32_16x16x32_bf16 v[120:123], v[206:209], v[170:173], v[120:123]
	v_mfma_f32_16x16x32_bf16 v[112:115], v[214:217], v[170:173], v[112:115]
	v_mfma_f32_16x16x32_bf16 v[104:107], v[206:209], v[178:181], v[104:107]
	v_mfma_f32_16x16x32_bf16 v[96:99], v[214:217], v[178:181], v[96:99]
	v_mfma_f32_16x16x32_bf16 v[88:91], v[206:209], v[186:189], v[88:91]
	v_mfma_f32_16x16x32_bf16 v[80:83], v[214:217], v[186:189], v[80:83]
	v_mfma_f32_16x16x32_bf16 v[72:75], v[206:209], v[194:197], v[72:75]
	v_mfma_f32_16x16x32_bf16 v[64:67], v[214:217], v[194:197], v[64:67]
	s_setprio 0
	s_mov_b32 m0, s35
	s_mov_b64 s[0:1], 0x80
	v_lshl_add_u64 v[198:199], v[220:221], 0, s[0:1]
	s_barrier
	ds_read_b128 v[166:169], v148 offset:49152
	ds_read_b128 v[170:173], v148 offset:50176
	ds_read_b128 v[174:177], v148 offset:51200
	ds_read_b128 v[178:181], v148 offset:52224
	ds_read_b128 v[182:185], v148 offset:53248
	ds_read_b128 v[186:189], v148 offset:54272
	ds_read_b128 v[190:193], v148 offset:55296
	ds_read_b128 v[194:197], v148 offset:56320
	global_load_lds_dwordx4 v[198:199], off
	v_lshl_add_u64 v[198:199], v[222:223], 0, s[0:1]
	s_mov_b32 m0, s36
	s_nop 0
	global_load_lds_dwordx4 v[198:199], off
	s_barrier
; #define PG8_STAGE(bufoff, gbase, voff) do { _Pragma("unroll") for (int _i = 0; _i < 2; ++_i) \
;         __builtin_amdgcn_global_load_lds((const unsigned*)((const char*)(gbase) + (voff)[_i]), (LAS unsigned*)(lds + (bufoff) + ldsw + _i * 8192), 16, 0, 0); } while (0)
; #define PG8_LDA(dst, b, h) do { _Pragma("unroll") for (int m = 0; m < 4; ++m) _Pragma("unroll") for (int k = 0; k < 2; ++k) dst[m][k] = *(const LAS bf16x8*)(lds + PG8_SA(b, h) + aoff + m * 2048 + k * 1024); } while (0)
; #define PG8_LDB(dst, b, h) do { _Pragma("unroll") for (int n = 0; n < 2; ++n) _Pragma("unroll") for (int k = 0; k < 2; ++k) dst[n][k] = *(const LAS bf16x8*)(lds + PG8_SB(b, h) + boff + n * 2048 + k * 1024); } while (0)
; #define PG8_MMA(ai, bj, At, Bt) do { __builtin_amdgcn_s_setprio(1); _Pragma("unroll") for (int m = 0; m < 4; ++m) _Pragma("unroll") for (int n = 0; n < 2; ++n) _Pragma("unroll") for (int k = 0; k < 2; ++k) \
;         acc[ai][bj][m][n] = __builtin_amdgcn_mfma_f32_16x16x32_bf16(Bt[n][k], At[m][k], acc[ai][bj][m][n], 0, 0, 0); __builtin_amdgcn_s_setprio(0); } while (0)
; #define PG8_WAIT_V(n) asm volatile("s_waitcnt vmcnt(" #n ")" ::: "memory")
; #define PG8_WAIT_L(n) asm volatile("s_waitcnt lgkmcnt(" #n ")" ::: "memory")
; #define PG8_BAR __builtin_amdgcn_s_barrier()
; #define PG8_SCHED __builtin_amdgcn_sched_barrier(0)
; template <class Epi, class Sched>
; __device__ __forceinline__ void gemm_phase(LAS unsigned char* lds, const Gemm g, const Sched& S, const Epi& E) {
;     ...
;             PG8_LDB(B0, 0, 0); PG8_SCHED; PG8_LDA(At, 0, 0); PG8_STAGE(PG8_SA(1, 1), a1 + hstep, voffA);
;             PG8_WAIT_L(8); PG8_BAR; PG8_WAIT_L(0); PG8_MMA(0, 0, At, B0); PG8_BAR; PG8_SCHED;
;             PG8_LDB(B1, 0, 1); PG8_STAGE(PG8_SB(0, 0), b2, voffB);
;             PG8_BAR; PG8_WAIT_L(0); PG8_MMA(0, 1, At, B1); PG8_BAR;
;     ...
;             PG8_BAR; PG8_WAIT_L(0); PG8_MMA(1, 0, At, B0); PG8_BAR; PG8_SCHED;
;             PG8_STAGE(PG8_SB(1, 1), b3 + hstep, voffB);
;             PG8_WAIT_V(6); PG8_BAR; PG8_MMA(1, 1, At, B1); PG8_BAR;
	s_waitcnt lgkmcnt(0)
	s_setprio 1
	s_waitcnt lgkmcnt(0)
	v_mfma_f32_16x16x32_bf16 v[60:63], v[150:153], v[166:169], v[60:63]
	v_mfma_f32_16x16x32_bf16 v[56:59], v[158:161], v[166:169], v[56:59]
	v_mfma_f32_16x16x32_bf16 v[44:47], v[150:153], v[174:177], v[44:47]
	v_mfma_f32_16x16x32_bf16 v[40:43], v[158:161], v[174:177], v[40:43]
	v_mfma_f32_16x16x32_bf16 v[28:31], v[150:153], v[182:185], v[28:31]
	v_mfma_f32_16x16x32_bf16 v[24:27], v[158:161], v[182:185], v[24:27]
	v_mfma_f32_16x16x32_bf16 v[12:15], v[150:153], v[190:193], v[12:15]
	v_mfma_f32_16x16x32_bf16 v[8:11], v[158:161], v[190:193], v[8:11]
	v_mfma_f32_16x16x32_bf16 v[60:63], v[154:157], v[170:173], v[60:63]
	v_mfma_f32_16x16x32_bf16 v[56:59], v[162:165], v[170:173], v[56:59]
	v_mfma_f32_16x16x32_bf16 v[44:47], v[154:157], v[178:181], v[44:47]
	v_mfma_f32_16x16x32_bf16 v[40:43], v[162:165], v[178:181], v[40:43]
	v_mfma_f32_16x16x32_bf16 v[28:31], v[154:157], v[186:189], v[28:31]
	v_mfma_f32_16x16x32_bf16 v[24:27], v[162:165], v[186:189], v[24:27]
	v_mfma_f32_16x16x32_bf16 v[12:15], v[154:157], v[194:197], v[12:15]
	v_mfma_f32_16x16x32_bf16 v[8:11], v[162:165], v[194:197], v[8:11]
	s_setprio 0
	s_barrier
	s_add_u32 s18, s18, 0x40080
	s_addc_u32 s19, s19, 0
	s_add_i32 s20, s20, s25
	s_mov_b32 m0, s20
	s_nop 0
	global_load_lds_dwordx4 v132, s[18:19]
	s_add_i32 m0, s20, 0x2000
	s_nop 0
	global_load_lds_dwordx4 v128, s[18:19]
	s_waitcnt vmcnt(10)
	s_barrier
	s_setprio 1
	v_mfma_f32_16x16x32_bf16 v[52:55], v[202:205], v[166:169], v[52:55]
	v_mfma_f32_16x16x32_bf16 v[48:51], v[210:213], v[166:169], v[48:51]
	v_mfma_f32_16x16x32_bf16 v[36:39], v[202:205], v[174:177], v[36:39]
	v_mfma_f32_16x16x32_bf16 v[32:35], v[210:213], v[174:177], v[32:35]
	v_mfma_f32_16x16x32_bf16 v[20:23], v[202:205], v[182:185], v[20:23]
	v_mfma_f32_16x16x32_bf16 v[16:19], v[210:213], v[182:185], v[16:19]
	v_mfma_f32_16x16x32_bf16 v[4:7], v[202:205], v[190:193], v[4:7]
	v_mfma_f32_16x16x32_bf16 v[0:3], v[210:213], v[190:193], v[0:3]
	v_mfma_f32_16x16x32_bf16 v[52:55], v[206:209], v[170:173], v[52:55]
	v_mfma_f32_16x16x32_bf16 v[48:51], v[214:217], v[170:173], v[48:51]
	v_mfma_f32_16x16x32_bf16 v[36:39], v[206:209], v[178:181], v[36:39]
	v_mfma_f32_16x16x32_bf16 v[32:35], v[214:217], v[178:181], v[32:35]
	v_mfma_f32_16x16x32_bf16 v[20:23], v[206:209], v[186:189], v[20:23]
	v_mfma_f32_16x16x32_bf16 v[16:19], v[214:217], v[186:189], v[16:19]
	v_mfma_f32_16x16x32_bf16 v[4:7], v[206:209], v[194:197], v[4:7]
	v_mfma_f32_16x16x32_bf16 v[0:3], v[214:217], v[194:197], v[0:3]
	s_setprio 0
	s_add_i32 s46, s46, 2
	s_add_u32 s16, s16, 0x100
	s_addc_u32 s17, s17, 0
	s_add_u32 s44, s44, 0x100
	s_addc_u32 s45, s45, 0
	s_cmp_gt_u32 s46, 13
	s_barrier
.LBB0_1021:
	ds_read_b128 v[150:153], v147
	ds_read_b128 v[154:157], v147 offset:1024
	ds_read_b128 v[158:161], v147 offset:2048
	ds_read_b128 v[162:165], v147 offset:3072
	s_add_u32 s18, s16, 0xfffc0080
	s_addc_u32 s19, s17, -1
	s_cmp_eq_u32 s46, 12
	s_cselect_b32 s21, s7, s19
	s_cselect_b32 s20, s42, s18
	s_cselect_b32 s19, s5, s45
	s_cselect_b32 s18, s43, s44
	s_add_i32 m0, s15, 0xc000
	ds_read_b128 v[166:169], v148
	ds_read_b128 v[170:173], v148 offset:1024
	ds_read_b128 v[174:177], v148 offset:2048
	ds_read_b128 v[178:181], v148 offset:3072
	ds_read_b128 v[182:185], v148 offset:4096
	ds_read_b128 v[186:189], v148 offset:5120
	ds_read_b128 v[190:193], v148 offset:6144
	ds_read_b128 v[194:197], v148 offset:7168
	global_load_lds_dwordx4 v136, s[16:17]
	s_add_i32 m0, s15, 0xe000
	s_nop 0
	global_load_lds_dwordx4 v138, s[16:17]
	s_waitcnt lgkmcnt(8)
	s_waitcnt vmcnt(10)
	s_barrier
	s_waitcnt lgkmcnt(0)
	s_setprio 1
	s_waitcnt lgkmcnt(0)
	v_mfma_f32_16x16x32_bf16 v[124:127], v[150:153], v[166:169], v[124:127]
	v_mfma_f32_16x16x32_bf16 v[116:119], v[158:161], v[166:169], v[116:119]
	v_mfma_f32_16x16x32_bf16 v[108:111], v[150:153], v[174:177], v[108:111]
	v_mfma_f32_16x16x32_bf16 v[100:103], v[158:161], v[174:177], v[100:103]
	v_mfma_f32_16x16x32_bf16 v[92:95], v[150:153], v[182:185], v[92:95]
	v_mfma_f32_16x16x32_bf16 v[84:87], v[158:161], v[182:185], v[84:87]
	v_mfma_f32_16x16x32_bf16 v[76:79], v[150:153], v[190:193], v[76:79]
	v_mfma_f32_16x16x32_bf16 v[68:71], v[158:161], v[190:193], v[68:71]
	v_mfma_f32_16x16x32_bf16 v[124:127], v[154:157], v[170:173], v[124:127]
	v_mfma_f32_16x16x32_bf16 v[116:119], v[162:165], v[170:173], v[116:119]
	v_mfma_f32_16x16x32_bf16 v[108:111], v[154:157], v[178:181], v[108:111]
	v_mfma_f32_16x16x32_bf16 v[100:103], v[162:165], v[178:181], v[100:103]
	v_mfma_f32_16x16x32_bf16 v[92:95], v[154:157], v[186:189], v[92:95]
	v_mfma_f32_16x16x32_bf16 v[84:87], v[162:165], v[186:189], v[84:87]
	v_mfma_f32_16x16x32_bf16 v[76:79], v[154:157], v[194:197], v[76:79]
	v_mfma_f32_16x16x32_bf16 v[68:71], v[162:165], v[194:197], v[68:71]
	s_setprio 0
	s_barrier
	s_add_i32 s47, s38, s25
	s_mov_b32 m0, s47
	ds_read_b128 v[202:205], v149
	ds_read_b128 v[206:209], v149 offset:1024
	ds_read_b128 v[210:213], v149 offset:2048
	ds_read_b128 v[214:217], v149 offset:3072
	global_load_lds_dwordx4 v132, s[18:19]
	s_add_i32 m0, s47, 0x2000
	s_nop 0
	global_load_lds_dwordx4 v128, s[18:19]
	s_waitcnt vmcnt(10)
	s_barrier
; #define PG8_STAGE(bufoff, gbase, voff) do { _Pragma("unroll") for (int _i = 0; _i < 2; ++_i) \
;         __builtin_amdgcn_global_load_lds((const unsigned*)((const char*)(gbase) + (voff)[_i]), (LAS unsigned*)(lds + (bufoff) + ldsw + _i * 8192), 16, 0, 0); } while (0)
; #define PG8_LDA(dst, b, h) do { _Pragma("unroll") for (int m = 0; m < 4; ++m) _Pragma("unroll") for (int k = 0; k < 2; ++k) dst[m][k] = *(const LAS bf16x8*)(lds + PG8_SA(b, h) + aoff + m * 2048 + k * 1024); } while (0)
; #define PG8_LDB(dst, b, h) do { _Pragma("unroll") for (int n = 0; n < 2; ++n) _Pragma("unroll") for (int k = 0; k < 2; ++k) dst[n][k] = *(const LAS bf16x8*)(lds + PG8_SB(b, h) + boff + n * 2048 + k * 1024); } while (0)
; #define PG8_MMA(ai, bj, At, Bt) do { __builtin_amdgcn_s_setprio(1); _Pragma("unroll") for (int m = 0; m < 4; ++m) _Pragma("unroll") for (int n = 0; n < 2; ++n) _Pragma("unroll") for (int k = 0; k < 2; ++k) \
;         acc[ai][bj][m][n] = __builtin_amdgcn_mfma_f32_16x16x32_bf16(Bt[n][k], At[m][k], acc[ai][bj][m][n], 0, 0, 0); __builtin_amdgcn_s_setprio(0); } while (0)
; #define PG8_WAIT_V(n) asm volatile("s_waitcnt vmcnt(" #n ")" ::: "memory")
; #define PG8_WAIT_L(n) asm volatile("s_waitcnt lgkmcnt(" #n ")" ::: "memory")
; #define PG8_BAR __builtin_amdgcn_s_barrier()
; #define PG8_SCHED __builtin_amdgcn_sched_barrier(0)
; template <class Epi, class Sched>
; __device__ __forceinline__ void gemm_phase(LAS unsigned char* lds, const Gemm g, const Sched& S, const Epi& E) {
;     ...
;             PG8_LDA(At, 0, 1); PG8_STAGE(PG8_SA(0, 0), a2, voffA);
;             PG8_BAR; PG8_WAIT_L(0); PG8_MMA(1, 0, At, B0); PG8_BAR; PG8_SCHED;
;             PG8_STAGE(PG8_SB(0, 1), b2 + hstep, voffB);
;             PG8_WAIT_V(6); PG8_BAR; PG8_MMA(1, 1, At, B1); PG8_BAR;
;             PG8_LDB(B0, 1, 0); PG8_SCHED; PG8_LDA(At, 1, 0); PG8_STAGE(PG8_SA(0, 1), a2 + hstep, voffA);
;             PG8_WAIT_L(8); PG8_BAR; PG8_WAIT_L(0); PG8_MMA(0, 0, At, B0); PG8_BAR; PG8_SCHED;
	s_waitcnt lgkmcnt(0)
	s_setprio 1
	s_waitcnt lgkmcnt(0)
	v_mfma_f32_16x16x32_bf16 v[120:123], v[202:205], v[166:169], v[120:123]
	v_mfma_f32_16x16x32_bf16 v[112:115], v[210:213], v[166:169], v[112:115]
	v_mfma_f32_16x16x32_bf16 v[104:107], v[202:205], v[174:177], v[104:107]
	v_mfma_f32_16x16x32_bf16 v[96:99], v[210:213], v[174:177], v[96:99]
	v_mfma_f32_16x16x32_bf16 v[88:91], v[202:205], v[182:185], v[88:91]
	v_mfma_f32_16x16x32_bf16 v[80:83], v[210:213], v[182:185], v[80:83]
	v_mfma_f32_16x16x32_bf16 v[72:75], v[202:205], v[190:193], v[72:75]
	v_mfma_f32_16x16x32_bf16 v[64:67], v[210:213], v[190:193], v[64:67]
	v_mfma_f32_16x16x32_bf16 v[120:123], v[206:209], v[170:173], v[120:123]
	v_mfma_f32_16x16x32_bf16 v[112:115], v[214:217], v[170:173], v[112:115]
	v_mfma_f32_16x16x32_bf16 v[104:107], v[206:209], v[178:181], v[104:107]
	v_mfma_f32_16x16x32_bf16 v[96:99], v[214:217], v[178:181], v[96:99]
	v_mfma_f32_16x16x32_bf16 v[88:91], v[206:209], v[186:189], v[88:91]
	v_mfma_f32_16x16x32_bf16 v[80:83], v[214:217], v[186:189], v[80:83]
	v_mfma_f32_16x16x32_bf16 v[72:75], v[206:209], v[194:197], v[72:75]
	v_mfma_f32_16x16x32_bf16 v[64:67], v[214:217], v[194:197], v[64:67]
	s_setprio 0
	s_mov_b32 m0, s15
	v_lshl_add_u64 v[220:221], s[20:21], 0, v[134:135]
	s_barrier
	ds_read_b128 v[166:169], v148 offset:16384
	ds_read_b128 v[170:173], v148 offset:17408
	ds_read_b128 v[174:177], v148 offset:18432
	ds_read_b128 v[178:181], v148 offset:19456
	ds_read_b128 v[182:185], v148 offset:20480
	ds_read_b128 v[186:189], v148 offset:21504
	ds_read_b128 v[190:193], v148 offset:22528
	ds_read_b128 v[194:197], v148 offset:23552
	global_load_lds_dwordx4 v134, s[20:21]
	v_lshl_add_u64 v[222:223], s[20:21], 0, v[130:131]
	s_mov_b32 m0, s28
	s_nop 0
	global_load_lds_dwordx4 v130, s[20:21]
	s_barrier
	s_waitcnt lgkmcnt(0)
	s_setprio 1
	s_waitcnt lgkmcnt(0)
	v_mfma_f32_16x16x32_bf16 v[60:63], v[150:153], v[166:169], v[60:63]
	v_mfma_f32_16x16x32_bf16 v[56:59], v[158:161], v[166:169], v[56:59]
	v_mfma_f32_16x16x32_bf16 v[44:47], v[150:153], v[174:177], v[44:47]
	v_mfma_f32_16x16x32_bf16 v[40:43], v[158:161], v[174:177], v[40:43]
	v_mfma_f32_16x16x32_bf16 v[28:31], v[150:153], v[182:185], v[28:31]
	v_mfma_f32_16x16x32_bf16 v[24:27], v[158:161], v[182:185], v[24:27]
	v_mfma_f32_16x16x32_bf16 v[12:15], v[150:153], v[190:193], v[12:15]
	v_mfma_f32_16x16x32_bf16 v[8:11], v[158:161], v[190:193], v[8:11]
	v_mfma_f32_16x16x32_bf16 v[60:63], v[154:157], v[170:173], v[60:63]
	v_mfma_f32_16x16x32_bf16 v[56:59], v[162:165], v[170:173], v[56:59]
	v_mfma_f32_16x16x32_bf16 v[44:47], v[154:157], v[178:181], v[44:47]
	v_mfma_f32_16x16x32_bf16 v[40:43], v[162:165], v[178:181], v[40:43]
	v_mfma_f32_16x16x32_bf16 v[28:31], v[154:157], v[186:189], v[28:31]
	v_mfma_f32_16x16x32_bf16 v[24:27], v[162:165], v[186:189], v[24:27]
	v_mfma_f32_16x16x32_bf16 v[12:15], v[154:157], v[194:197], v[12:15]
	v_mfma_f32_16x16x32_bf16 v[8:11], v[162:165], v[194:197], v[8:11]
	s_setprio 0
	s_barrier
	s_add_u32 s48, s18, 0x40000
	s_addc_u32 s49, s19, 0
	s_add_i32 s47, s39, s25
	s_mov_b32 m0, s47
	s_nop 0
	global_load_lds_dwordx4 v132, s[48:49]
	s_add_i32 m0, s47, 0x2000
	s_nop 0
	global_load_lds_dwordx4 v128, s[48:49]
	s_waitcnt vmcnt(10)
	s_barrier
	s_setprio 1
	v_mfma_f32_16x16x32_bf16 v[52:55], v[202:205], v[166:169], v[52:55]
	v_mfma_f32_16x16x32_bf16 v[48:51], v[210:213], v[166:169], v[48:51]
	v_mfma_f32_16x16x32_bf16 v[36:39], v[202:205], v[174:177], v[36:39]
	v_mfma_f32_16x16x32_bf16 v[32:35], v[210:213], v[174:177], v[32:35]
	v_mfma_f32_16x16x32_bf16 v[20:23], v[202:205], v[182:185], v[20:23]
	v_mfma_f32_16x16x32_bf16 v[16:19], v[210:213], v[182:185], v[16:19]
	v_mfma_f32_16x16x32_bf16 v[4:7], v[202:205], v[190:193], v[4:7]
	v_mfma_f32_16x16x32_bf16 v[0:3], v[210:213], v[190:193], v[0:3]
	v_mfma_f32_16x16x32_bf16 v[52:55], v[206:209], v[170:173], v[52:55]
	v_mfma_f32_16x16x32_bf16 v[48:51], v[214:217], v[170:173], v[48:51]
	v_mfma_f32_16x16x32_bf16 v[36:39], v[206:209], v[178:181], v[36:39]
	v_mfma_f32_16x16x32_bf16 v[32:35], v[214:217], v[178:181], v[32:35]
	v_mfma_f32_16x16x32_bf16 v[20:23], v[206:209], v[186:189], v[20:23]
	v_mfma_f32_16x16x32_bf16 v[16:19], v[214:217], v[186:189], v[16:19]
	v_mfma_f32_16x16x32_bf16 v[4:7], v[206:209], v[194:197], v[4:7]
	v_mfma_f32_16x16x32_bf16 v[0:3], v[214:217], v[194:197], v[0:3]
	s_setprio 0
	s_add_i32 s47, 0, 0x18000
	v_add_u32_e32 v162, s47, v146
	s_barrier
	ds_read_b128 v[150:153], v162
	ds_read_b128 v[154:157], v162 offset:1024
	ds_read_b128 v[158:161], v162 offset:2048
	ds_read_b128 v[162:165], v162 offset:3072
	s_add_u32 s20, s20, 0x40000
	s_addc_u32 s21, s21, 0
	s_mov_b32 m0, s29
	ds_read_b128 v[166:169], v148 offset:32768
	ds_read_b128 v[170:173], v148 offset:33792
	ds_read_b128 v[174:177], v148 offset:34816
	ds_read_b128 v[178:181], v148 offset:35840
	ds_read_b128 v[182:185], v148 offset:36864
	ds_read_b128 v[186:189], v148 offset:37888
	ds_read_b128 v[190:193], v148 offset:38912
	ds_read_b128 v[194:197], v148 offset:39936
	global_load_lds_dwordx4 v134, s[20:21]
	s_mov_b32 m0, s30
	s_nop 0
	global_load_lds_dwordx4 v130, s[20:21]
	s_waitcnt lgkmcnt(8)
	s_waitcnt vmcnt(10)
	s_barrier
; #define PG8_STAGE(bufoff, gbase, voff) do { _Pragma("unroll") for (int _i = 0; _i < 2; ++_i) \
;         __builtin_amdgcn_global_load_lds((const unsigned*)((const char*)(gbase) + (voff)[_i]), (LAS unsigned*)(lds + (bufoff) + ldsw + _i * 8192), 16, 0, 0); } while (0)
; #define PG8_LDA(dst, b, h) do { _Pragma("unroll") for (int m = 0; m < 4; ++m) _Pragma("unroll") for (int k = 0; k < 2; ++k) dst[m][k] = *(const LAS bf16x8*)(lds + PG8_SA(b, h) + aoff + m * 2048 + k * 1024); } while (0)
; #define PG8_LDB(dst, b, h) do { _Pragma("unroll") for (int n = 0; n < 2; ++n) _Pragma("unroll") for (int k = 0; k < 2; ++k) dst[n][k] = *(const LAS bf16x8*)(lds + PG8_SB(b, h) + boff + n * 2048 + k * 1024); } while (0)
; #define PG8_MMA(ai, bj, At, Bt) do { __builtin_amdgcn_s_setprio(1); _Pragma("unroll") for (int m = 0; m < 4; ++m) _Pragma("unroll") for (int n = 0; n < 2; ++n) _Pragma("unroll") for (int k = 0; k < 2; ++k) \
;         acc[ai][bj][m][n] = __builtin_amdgcn_mfma_f32_16x16x32_bf16(Bt[n][k], At[m][k], acc[ai][bj][m][n], 0, 0, 0); __builtin_amdgcn_s_setprio(0); } while (0)
; #define PG8_WAIT_V(n) asm volatile("s_waitcnt vmcnt(" #n ")" ::: "memory")
; #define PG8_WAIT_L(n) asm volatile("s_waitcnt lgkmcnt(" #n ")" ::: "memory")
; #define PG8_BAR __builtin_amdgcn_s_barrier()
; #define PG8_SCHED __builtin_amdgcn_sched_barrier(0)
; template <class Epi, class Sched>
; __device__ __forceinline__ void gemm_phase(LAS unsigned char* lds, const Gemm g, const Sched& S, const Epi& E) {
;     ...
;             PG8_LDB(B1, 1, 1); PG8_STAGE(PG8_SB(1, 0), b3, voffB);
;             PG8_BAR; PG8_WAIT_L(0); PG8_MMA(0, 1, At, B1); PG8_BAR;
;             PG8_LDA(At, 1, 1); PG8_STAGE(PG8_SA(1, 0), a3, voffA);
;             PG8_BAR; PG8_WAIT_L(0); PG8_MMA(1, 0, At, B0); PG8_BAR; PG8_SCHED;
;             PG8_STAGE(PG8_SB(1, 1), b3 + hstep, voffB);
;             PG8_WAIT_V(6); PG8_BAR; PG8_MMA(1, 1, At, B1); PG8_BAR;
	s_waitcnt lgkmcnt(0)
	s_setprio 1
	s_waitcnt lgkmcnt(0)
	v_mfma_f32_16x16x32_bf16 v[124:127], v[150:153], v[166:169], v[124:127]
	v_mfma_f32_16x16x32_bf16 v[116:119], v[158:161], v[166:169], v[116:119]
	v_mfma_f32_16x16x32_bf16 v[108:111], v[150:153], v[174:177], v[108:111]
	v_mfma_f32_16x16x32_bf16 v[100:103], v[158:161], v[174:177], v[100:103]
	v_mfma_f32_16x16x32_bf16 v[92:95], v[150:153], v[182:185], v[92:95]
	v_mfma_f32_16x16x32_bf16 v[84:87], v[158:161], v[182:185], v[84:87]
	v_mfma_f32_16x16x32_bf16 v[76:79], v[150:153], v[190:193], v[76:79]
	v_mfma_f32_16x16x32_bf16 v[68:71], v[158:161], v[190:193], v[68:71]
	v_mfma_f32_16x16x32_bf16 v[124:127], v[154:157], v[170:173], v[124:127]
	v_mfma_f32_16x16x32_bf16 v[116:119], v[162:165], v[170:173], v[116:119]
	v_mfma_f32_16x16x32_bf16 v[108:111], v[154:157], v[178:181], v[108:111]
	v_mfma_f32_16x16x32_bf16 v[100:103], v[162:165], v[178:181], v[100:103]
	v_mfma_f32_16x16x32_bf16 v[92:95], v[154:157], v[186:189], v[92:95]
	v_mfma_f32_16x16x32_bf16 v[84:87], v[162:165], v[186:189], v[84:87]
	v_mfma_f32_16x16x32_bf16 v[76:79], v[154:157], v[194:197], v[76:79]
	v_mfma_f32_16x16x32_bf16 v[68:71], v[162:165], v[194:197], v[68:71]
	s_setprio 0
	s_barrier
	s_add_i32 s20, 0, 0x1c000
	s_add_i32 s21, s47, s25
	v_add_u32_e32 v214, s20, v146
	s_add_u32 s0, s18, 0x80
	s_addc_u32 s1, s19, 0
	s_mov_b32 m0, s21
	ds_read_b128 v[202:205], v214
	ds_read_b128 v[206:209], v214 offset:1024
	ds_read_b128 v[210:213], v214 offset:2048
	ds_read_b128 v[214:217], v214 offset:3072
	global_load_lds_dwordx4 v132, s[0:1]
	s_add_i32 m0, s21, 0x2000
	s_nop 0
	global_load_lds_dwordx4 v128, s[0:1]
	s_waitcnt vmcnt(10)
	s_barrier
	s_waitcnt lgkmcnt(0)
	s_setprio 1
	s_waitcnt lgkmcnt(0)
	v_mfma_f32_16x16x32_bf16 v[120:123], v[202:205], v[166:169], v[120:123]
	v_mfma_f32_16x16x32_bf16 v[112:115], v[210:213], v[166:169], v[112:115]
	v_mfma_f32_16x16x32_bf16 v[104:107], v[202:205], v[174:177], v[104:107]
	v_mfma_f32_16x16x32_bf16 v[96:99], v[210:213], v[174:177], v[96:99]
	v_mfma_f32_16x16x32_bf16 v[88:91], v[202:205], v[182:185], v[88:91]
	v_mfma_f32_16x16x32_bf16 v[80:83], v[210:213], v[182:185], v[80:83]
	v_mfma_f32_16x16x32_bf16 v[72:75], v[202:205], v[190:193], v[72:75]
	v_mfma_f32_16x16x32_bf16 v[64:67], v[210:213], v[190:193], v[64:67]
	v_mfma_f32_16x16x32_bf16 v[120:123], v[206:209], v[170:173], v[120:123]
	v_mfma_f32_16x16x32_bf16 v[112:115], v[214:217], v[170:173], v[112:115]
	v_mfma_f32_16x16x32_bf16 v[104:107], v[206:209], v[178:181], v[104:107]
	v_mfma_f32_16x16x32_bf16 v[96:99], v[214:217], v[178:181], v[96:99]
	v_mfma_f32_16x16x32_bf16 v[88:91], v[206:209], v[186:189], v[88:91]
	v_mfma_f32_16x16x32_bf16 v[80:83], v[214:217], v[186:189], v[80:83]
	v_mfma_f32_16x16x32_bf16 v[72:75], v[206:209], v[194:197], v[72:75]
	v_mfma_f32_16x16x32_bf16 v[64:67], v[214:217], v[194:197], v[64:67]
	s_setprio 0
	s_mov_b32 m0, s35
	s_mov_b64 s[0:1], 0x80
	v_lshl_add_u64 v[198:199], v[220:221], 0, s[0:1]
	s_barrier
	ds_read_b128 v[166:169], v148 offset:49152
	ds_read_b128 v[170:173], v148 offset:50176
	ds_read_b128 v[174:177], v148 offset:51200
	ds_read_b128 v[178:181], v148 offset:52224
	ds_read_b128 v[182:185], v148 offset:53248
	ds_read_b128 v[186:189], v148 offset:54272
	ds_read_b128 v[190:193], v148 offset:55296
	ds_read_b128 v[194:197], v148 offset:56320
	global_load_lds_dwordx4 v[198:199], off
	v_lshl_add_u64 v[198:199], v[222:223], 0, s[0:1]
	s_mov_b32 m0, s36
	s_nop 0
	global_load_lds_dwordx4 v[198:199], off
	s_barrier
	s_waitcnt lgkmcnt(0)
	s_setprio 1
	s_waitcnt lgkmcnt(0)
	v_mfma_f32_16x16x32_bf16 v[60:63], v[150:153], v[166:169], v[60:63]
	v_mfma_f32_16x16x32_bf16 v[56:59], v[158:161], v[166:169], v[56:59]
	v_mfma_f32_16x16x32_bf16 v[44:47], v[150:153], v[174:177], v[44:47]
	v_mfma_f32_16x16x32_bf16 v[40:43], v[158:161], v[174:177], v[40:43]
	v_mfma_f32_16x16x32_bf16 v[28:31], v[150:153], v[182:185], v[28:31]
	v_mfma_f32_16x16x32_bf16 v[24:27], v[158:161], v[182:185], v[24:27]
	v_mfma_f32_16x16x32_bf16 v[12:15], v[150:153], v[190:193], v[12:15]
	v_mfma_f32_16x16x32_bf16 v[8:11], v[158:161], v[190:193], v[8:11]
	v_mfma_f32_16x16x32_bf16 v[60:63], v[154:157], v[170:173], v[60:63]
	v_mfma_f32_16x16x32_bf16 v[56:59], v[162:165], v[170:173], v[56:59]
	v_mfma_f32_16x16x32_bf16 v[44:47], v[154:157], v[178:181], v[44:47]
	v_mfma_f32_16x16x32_bf16 v[40:43], v[162:165], v[178:181], v[40:43]
	v_mfma_f32_16x16x32_bf16 v[28:31], v[154:157], v[186:189], v[28:31]
	v_mfma_f32_16x16x32_bf16 v[24:27], v[162:165], v[186:189], v[24:27]
	v_mfma_f32_16x16x32_bf16 v[12:15], v[154:157], v[194:197], v[12:15]
	v_mfma_f32_16x16x32_bf16 v[8:11], v[162:165], v[194:197], v[8:11]
	s_setprio 0
	s_barrier
	s_add_u32 s18, s18, 0x40080
	s_addc_u32 s19, s19, 0
	s_add_i32 s20, s20, s25
	s_mov_b32 m0, s20
	s_nop 0
	global_load_lds_dwordx4 v132, s[18:19]
	s_add_i32 m0, s20, 0x2000
	s_nop 0
	global_load_lds_dwordx4 v128, s[18:19]
	s_waitcnt vmcnt(10)
	s_barrier
	s_setprio 1
	v_mfma_f32_16x16x32_bf16 v[52:55], v[202:205], v[166:169], v[52:55]
	v_mfma_f32_16x16x32_bf16 v[48:51], v[210:213], v[166:169], v[48:51]
	v_mfma_f32_16x16x32_bf16 v[36:39], v[202:205], v[174:177], v[36:39]
	v_mfma_f32_16x16x32_bf16 v[32:35], v[210:213], v[174:177], v[32:35]
	v_mfma_f32_16x16x32_bf16 v[20:23], v[202:205], v[182:185], v[20:23]
	v_mfma_f32_16x16x32_bf16 v[16:19], v[210:213], v[182:185], v[16:19]
	v_mfma_f32_16x16x32_bf16 v[4:7], v[202:205], v[190:193], v[4:7]
	v_mfma_f32_16x16x32_bf16 v[0:3], v[210:213], v[190:193], v[0:3]
	v_mfma_f32_16x16x32_bf16 v[52:55], v[206:209], v[170:173], v[52:55]
	v_mfma_f32_16x16x32_bf16 v[48:51], v[214:217], v[170:173], v[48:51]
	v_mfma_f32_16x16x32_bf16 v[36:39], v[206:209], v[178:181], v[36:39]
	v_mfma_f32_16x16x32_bf16 v[32:35], v[214:217], v[178:181], v[32:35]
	v_mfma_f32_16x16x32_bf16 v[20:23], v[206:209], v[186:189], v[20:23]
	v_mfma_f32_16x16x32_bf16 v[16:19], v[214:217], v[186:189], v[16:19]
	v_mfma_f32_16x16x32_bf16 v[4:7], v[206:209], v[194:197], v[4:7]
	v_mfma_f32_16x16x32_bf16 v[0:3], v[214:217], v[194:197], v[0:3]
	s_setprio 0
	s_add_i32 s46, s46, 2
	s_add_u32 s16, s16, 0x100
	s_addc_u32 s17, s17, 0
	s_add_u32 s44, s44, 0x100
	s_addc_u32 s45, s45, 0
	s_cmp_gt_u32 s46, 13
	s_barrier
; __device__ __forceinline__ unsigned cvt_pk_bf16(float lo, float hi) { unsigned r; asm volatile("v_cvt_pk_bf16_f32 %0, %1, %2" : "=v"(r) : "v"(lo), "v"(hi)); return r; }
; __device__ __forceinline__ float silu_f(float a) { return a * __builtin_amdgcn_rcpf(1.0f + __expf(-a)); }
;     __device__ __forceinline__ void operator()(const AccT& acc, const Unit& u, int wr, int wc, int fr, int fq) const {
;         asm volatile("" : "+v"(fr), "+v"(fq));
;         const int row0 = u.pm * 256 + wr * 64 + fr, hc0 = u.pn * 128 + wc * 32 + 8 * fq;
; #pragma unroll
;         for (int ai = 0; ai < 2; ++ai)
; #pragma unroll
;             for (int m = 0; m < 4; ++m) {
;                 const f32x4 a0 = acc[ai][0][m][0], a1 = acc[ai][0][m][1], b0 = acc[ai][1][m][0], b1 = acc[ai][1][m][1];
;                 u32x4 w;
;                 w.x = cvt_pk_bf16(silu_f(a0[0]) * b0[0], silu_f(a0[1]) * b0[1]); w.y = cvt_pk_bf16(silu_f(a0[2]) * b0[2], silu_f(a0[3]) * b0[3]);
;                 w.z = cvt_pk_bf16(silu_f(a1[0]) * b1[0], silu_f(a1[1]) * b1[1]); w.w = cvt_pk_bf16(silu_f(a1[2]) * b1[2], silu_f(a1[3]) * b1[3]);
;                 *(u32x4*)(H + (size_t)(row0 + ai * 128 + m * 16) * DFF + hc0) = w;
;             }
	s_cbranch_scc0 .LBB0_1021
	v_mul_f32_e32 v152, 0xbfb8aa3b, v124
	v_mov_b32_e32 v150, v144
	v_mov_b32_e32 v151, v145
	s_lshl_b32 s5, s14, 8
	v_exp_f32_e32 v153, v152
	v_mul_f32_e32 v152, 0xbfb8aa3b, v125
	s_add_i32 s5, s5, s33
	v_exp_f32_e32 v154, v152
	v_add_u32_e32 v150, s5, v150
	s_lshl_b32 s5, s41, 7
	s_or_b32 s5, s5, s34
	v_lshl_add_u32 v152, v151, 3, s5
	v_add_f32_e32 v151, 1.0, v153
	v_rcp_f32_e32 v151, v151
	v_add_f32_e32 v153, 1.0, v154
	v_rcp_f32_e32 v154, v153
	v_ashrrev_i32_e32 v153, 31, v152
	v_mul_f32_e32 v124, v124, v151
	v_mul_f32_e32 v120, v124, v120
	v_mul_f32_e32 v124, v125, v154
	v_mul_f32_e32 v125, 0xbfb8aa3b, v126
	v_exp_f32_e32 v125, v125
	v_mul_f32_e32 v151, 0xbfb8aa3b, v127
	v_exp_f32_e32 v151, v151
	v_mul_f32_e32 v121, v124, v121
	v_add_f32_e32 v124, 1.0, v125
	v_rcp_f32_e32 v124, v124
	v_add_f32_e32 v125, 1.0, v151
	v_rcp_f32_e32 v125, v125
	v_cvt_pk_bf16_f32 v120, v120, v121
	v_mul_f32_e32 v121, v126, v124
	v_mul_f32_e32 v124, 0xbfb8aa3b, v116
	v_mul_f32_e32 v121, v121, v122
	v_mul_f32_e32 v122, v127, v125
	v_exp_f32_e32 v124, v124
	v_mul_f32_e32 v125, 0xbfb8aa3b, v117
	v_exp_f32_e32 v125, v125
	v_mul_f32_e32 v122, v122, v123
	v_add_f32_e32 v123, 1.0, v124
	v_rcp_f32_e32 v123, v123
	v_add_f32_e32 v124, 1.0, v125
	v_rcp_f32_e32 v124, v124
	v_cvt_pk_bf16_f32 v121, v121, v122
	v_mul_f32_e32 v116, v116, v123
	v_mul_f32_e32 v112, v116, v112
	v_mul_f32_e32 v116, v117, v124
	v_mul_f32_e32 v117, 0xbfb8aa3b, v118
	v_exp_f32_e32 v117, v117
	v_mul_f32_e32 v122, 0xbfb8aa3b, v119
	v_exp_f32_e32 v122, v122
	v_mul_f32_e32 v113, v116, v113
	v_add_f32_e32 v116, 1.0, v117
	v_rcp_f32_e32 v116, v116
	v_add_f32_e32 v117, 1.0, v122
	v_rcp_f32_e32 v117, v117
	v_cvt_pk_bf16_f32 v122, v112, v113
	v_mul_f32_e32 v112, v118, v116
	v_mul_f32_e32 v118, 0xbfb8aa3b, v108
	v_mul_f32_e32 v113, v119, v117
	v_exp_f32_e32 v118, v118
	v_mul_f32_e32 v119, 0xbfb8aa3b, v109
	v_exp_f32_e32 v119, v119
	v_mul_f32_e32 v112, v112, v114
	v_add_f32_e32 v118, 1.0, v118
	v_rcp_f32_e32 v118, v118
	v_add_f32_e32 v119, 1.0, v119
	v_rcp_f32_e32 v119, v119
	v_mul_f32_e32 v113, v113, v115
	v_cvt_pk_bf16_f32 v123, v112, v113
	v_mov_b64_e32 v[112:113], s[82:83]
	v_mad_i64_i32 v[116:117], s[16:17], v150, s40, v[112:113]
	v_lshlrev_b64 v[114:115], 1, v[152:153]
	v_mul_f32_e32 v108, v108, v118
	v_lshl_add_u64 v[116:117], v[116:117], 0, v[114:115]
	v_mul_f32_e32 v104, v108, v104
	v_mul_f32_e32 v108, v109, v119
	v_mul_f32_e32 v109, 0xbfb8aa3b, v110
	global_store_dwordx4 v[116:117], v[120:123], off
	v_exp_f32_e32 v109, v109
	v_mul_f32_e32 v116, 0xbfb8aa3b, v111
	v_exp_f32_e32 v116, v116
	v_mul_f32_e32 v105, v108, v105
	v_add_f32_e32 v108, 1.0, v109
	v_rcp_f32_e32 v108, v108
	v_add_f32_e32 v109, 1.0, v116
	v_rcp_f32_e32 v109, v109
	v_cvt_pk_bf16_f32 v104, v104, v105
	v_mul_f32_e32 v105, v110, v108
	v_mul_f32_e32 v108, 0xbfb8aa3b, v100
	v_mul_f32_e32 v105, v105, v106
	v_mul_f32_e32 v106, v111, v109
	v_exp_f32_e32 v108, v108
	v_mul_f32_e32 v109, 0xbfb8aa3b, v101
	v_exp_f32_e32 v109, v109
	v_mul_f32_e32 v106, v106, v107
	v_add_f32_e32 v107, 1.0, v108
	v_rcp_f32_e32 v107, v107
	v_add_f32_e32 v108, 1.0, v109
	v_rcp_f32_e32 v108, v108
	v_cvt_pk_bf16_f32 v105, v105, v106
	v_mul_f32_e32 v100, v100, v107
	v_mul_f32_e32 v96, v100, v96
	v_mul_f32_e32 v100, v101, v108
	v_mul_f32_e32 v101, 0xbfb8aa3b, v102
	v_exp_f32_e32 v101, v101
	v_mul_f32_e32 v106, 0xbfb8aa3b, v103
	v_exp_f32_e32 v106, v106
	v_mul_f32_e32 v97, v100, v97
	v_add_f32_e32 v100, 1.0, v101
	v_rcp_f32_e32 v100, v100
	v_add_f32_e32 v101, 1.0, v106
	v_rcp_f32_e32 v101, v101
	v_cvt_pk_bf16_f32 v106, v96, v97
	v_mul_f32_e32 v96, v102, v100
	v_mul_f32_e32 v96, v96, v98
	v_mul_f32_e32 v97, v103, v101
	v_mul_f32_e32 v98, 0xbfb8aa3b, v92
	v_mul_f32_e32 v97, v97, v99
	v_exp_f32_e32 v98, v98
	v_mul_f32_e32 v99, 0xbfb8aa3b, v93
	v_exp_f32_e32 v99, v99
	v_cvt_pk_bf16_f32 v107, v96, v97
	v_add_f32_e32 v98, 1.0, v98
	v_rcp_f32_e32 v98, v98
	v_add_f32_e32 v99, 1.0, v99
	v_rcp_f32_e32 v99, v99
	v_add_u32_e32 v96, 16, v150
	v_mad_i64_i32 v[96:97], s[16:17], v96, s40, v[112:113]
	v_mul_f32_e32 v92, v92, v98
	v_lshl_add_u64 v[96:97], v[96:97], 0, v[114:115]
	v_mul_f32_e32 v88, v92, v88
	v_mul_f32_e32 v92, v93, v99
	v_mul_f32_e32 v93, 0xbfb8aa3b, v94
	global_store_dwordx4 v[96:97], v[104:107], off
	v_exp_f32_e32 v93, v93
	v_mul_f32_e32 v96, 0xbfb8aa3b, v95
	v_exp_f32_e32 v96, v96
	v_mul_f32_e32 v89, v92, v89
	v_add_f32_e32 v92, 1.0, v93
	v_rcp_f32_e32 v92, v92
	v_add_f32_e32 v93, 1.0, v96
	v_rcp_f32_e32 v93, v93
	v_cvt_pk_bf16_f32 v88, v88, v89
	v_mul_f32_e32 v89, v94, v92
	v_mul_f32_e32 v92, 0xbfb8aa3b, v84
	v_mul_f32_e32 v89, v89, v90
	v_mul_f32_e32 v90, v95, v93
	v_exp_f32_e32 v92, v92
	v_mul_f32_e32 v93, 0xbfb8aa3b, v85
	v_exp_f32_e32 v93, v93
	v_mul_f32_e32 v90, v90, v91
	v_add_f32_e32 v91, 1.0, v92
	v_rcp_f32_e32 v91, v91
	v_add_f32_e32 v92, 1.0, v93
	v_rcp_f32_e32 v92, v92
	v_cvt_pk_bf16_f32 v89, v89, v90
	v_mul_f32_e32 v84, v84, v91
	v_mul_f32_e32 v80, v84, v80
	v_mul_f32_e32 v84, v85, v92
	v_mul_f32_e32 v85, 0xbfb8aa3b, v86
	v_exp_f32_e32 v85, v85
	v_mul_f32_e32 v90, 0xbfb8aa3b, v87
	v_exp_f32_e32 v90, v90
	v_mul_f32_e32 v81, v84, v81
	v_add_f32_e32 v84, 1.0, v85
	v_rcp_f32_e32 v84, v84
	v_add_f32_e32 v85, 1.0, v90
	v_rcp_f32_e32 v85, v85
	v_cvt_pk_bf16_f32 v90, v80, v81
	v_mul_f32_e32 v80, v86, v84
	v_mul_f32_e32 v80, v80, v82
	v_mul_f32_e32 v81, v87, v85
	v_mul_f32_e32 v82, 0xbfb8aa3b, v76
	v_mul_f32_e32 v81, v81, v83
	v_exp_f32_e32 v82, v82
	v_mul_f32_e32 v83, 0xbfb8aa3b, v77
	v_exp_f32_e32 v83, v83
	v_cvt_pk_bf16_f32 v91, v80, v81
	v_add_f32_e32 v82, 1.0, v82
	v_rcp_f32_e32 v82, v82
	v_add_f32_e32 v83, 1.0, v83
	v_rcp_f32_e32 v83, v83
; __device__ __forceinline__ unsigned cvt_pk_bf16(float lo, float hi) { unsigned r; asm volatile("v_cvt_pk_bf16_f32 %0, %1, %2" : "=v"(r) : "v"(lo), "v"(hi)); return r; }
; __device__ __forceinline__ float silu_f(float a) { return a * __builtin_amdgcn_rcpf(1.0f + __expf(-a)); }
;     __device__ __forceinline__ void operator()(const AccT& acc, const Unit& u, int wr, int wc, int fr, int fq) const {
;     ...
;         for (int ai = 0; ai < 2; ++ai)
; #pragma unroll
;             for (int m = 0; m < 4; ++m) {
;                 const f32x4 a0 = acc[ai][0][m][0], a1 = acc[ai][0][m][1], b0 = acc[ai][1][m][0], b1 = acc[ai][1][m][1];
;                 u32x4 w;
;                 w.x = cvt_pk_bf16(silu_f(a0[0]) * b0[0], silu_f(a0[1]) * b0[1]); w.y = cvt_pk_bf16(silu_f(a0[2]) * b0[2], silu_f(a0[3]) * b0[3]);
;                 w.z = cvt_pk_bf16(silu_f(a1[0]) * b1[0], silu_f(a1[1]) * b1[1]); w.w = cvt_pk_bf16(silu_f(a1[2]) * b1[2], silu_f(a1[3]) * b1[3]);
;                 *(u32x4*)(H + (size_t)(row0 + ai * 128 + m * 16) * DFF + hc0) = w;
;             }
	v_add_u32_e32 v80, 32, v150
	v_mad_i64_i32 v[80:81], s[16:17], v80, s40, v[112:113]
	v_mul_f32_e32 v76, v76, v82
	v_lshl_add_u64 v[80:81], v[80:81], 0, v[114:115]
	v_mul_f32_e32 v72, v76, v72
	v_mul_f32_e32 v76, v77, v83
	v_mul_f32_e32 v77, 0xbfb8aa3b, v78
	global_store_dwordx4 v[80:81], v[88:91], off
	v_exp_f32_e32 v77, v77
	v_mul_f32_e32 v80, 0xbfb8aa3b, v79
	v_exp_f32_e32 v80, v80
	v_mul_f32_e32 v73, v76, v73
	v_add_f32_e32 v76, 1.0, v77
	v_rcp_f32_e32 v76, v76
	v_add_f32_e32 v77, 1.0, v80
	v_rcp_f32_e32 v77, v77
	v_cvt_pk_bf16_f32 v72, v72, v73
	v_mul_f32_e32 v73, v78, v76
	v_mul_f32_e32 v76, 0xbfb8aa3b, v68
	v_mul_f32_e32 v73, v73, v74
	v_mul_f32_e32 v74, v79, v77
	v_exp_f32_e32 v76, v76
	v_mul_f32_e32 v77, 0xbfb8aa3b, v69
	v_exp_f32_e32 v77, v77
	v_mul_f32_e32 v74, v74, v75
	v_add_f32_e32 v75, 1.0, v76
	v_rcp_f32_e32 v75, v75
	v_add_f32_e32 v76, 1.0, v77
	v_rcp_f32_e32 v76, v76
	v_cvt_pk_bf16_f32 v73, v73, v74
	v_mul_f32_e32 v68, v68, v75
	v_mul_f32_e32 v64, v68, v64
	v_mul_f32_e32 v68, v69, v76
	v_mul_f32_e32 v69, 0xbfb8aa3b, v70
	v_exp_f32_e32 v69, v69
	v_mul_f32_e32 v74, 0xbfb8aa3b, v71
	v_exp_f32_e32 v74, v74
	v_mul_f32_e32 v65, v68, v65
	v_add_f32_e32 v68, 1.0, v69
	v_rcp_f32_e32 v68, v68
	v_add_f32_e32 v69, 1.0, v74
	v_rcp_f32_e32 v69, v69
	v_cvt_pk_bf16_f32 v74, v64, v65
	v_mul_f32_e32 v64, v70, v68
	v_mul_f32_e32 v64, v64, v66
	v_mul_f32_e32 v65, v71, v69
	v_mul_f32_e32 v66, 0xbfb8aa3b, v60
	v_mul_f32_e32 v65, v65, v67
	v_exp_f32_e32 v66, v66
	v_mul_f32_e32 v67, 0xbfb8aa3b, v61
	v_cvt_pk_bf16_f32 v75, v64, v65
	v_add_u32_e32 v64, 48, v150
	v_exp_f32_e32 v67, v67
	v_mad_i64_i32 v[64:65], s[16:17], v64, s40, v[112:113]
	v_lshl_add_u64 v[64:65], v[64:65], 0, v[114:115]
	global_store_dwordx4 v[64:65], v[72:75], off
	v_add_f32_e32 v64, 1.0, v66
	v_rcp_f32_e32 v64, v64
	v_add_f32_e32 v65, 1.0, v67
	v_rcp_f32_e32 v65, v65
	v_add_u32_e32 v66, 0x80, v150
	v_mul_f32_e32 v60, v60, v64
	v_mul_f32_e32 v52, v60, v52
	v_mul_f32_e32 v60, v61, v65
	v_mul_f32_e32 v61, 0xbfb8aa3b, v62
	v_exp_f32_e32 v61, v61
	v_mul_f32_e32 v64, 0xbfb8aa3b, v63
	v_exp_f32_e32 v64, v64
	v_mul_f32_e32 v53, v60, v53
	v_add_f32_e32 v60, 1.0, v61
	v_rcp_f32_e32 v60, v60
	v_add_f32_e32 v61, 1.0, v64
	v_rcp_f32_e32 v61, v61
	v_cvt_pk_bf16_f32 v52, v52, v53
	v_mul_f32_e32 v53, v62, v60
	v_mul_f32_e32 v60, 0xbfb8aa3b, v56
	v_exp_f32_e32 v60, v60
	v_mul_f32_e32 v53, v53, v54
	v_mul_f32_e32 v54, v63, v61
	v_mul_f32_e32 v61, 0xbfb8aa3b, v57
	v_exp_f32_e32 v61, v61
	v_mul_f32_e32 v54, v54, v55
	v_add_f32_e32 v55, 1.0, v60
	v_rcp_f32_e32 v55, v55
	v_add_f32_e32 v60, 1.0, v61
	v_rcp_f32_e32 v60, v60
	v_cvt_pk_bf16_f32 v53, v53, v54
	v_mul_f32_e32 v54, v56, v55
	v_mul_f32_e32 v55, 0xbfb8aa3b, v58
	v_exp_f32_e32 v55, v55
	v_mul_f32_e32 v56, 0xbfb8aa3b, v59
	v_exp_f32_e32 v56, v56
	v_mul_f32_e32 v48, v54, v48
	v_mul_f32_e32 v54, v57, v60
	v_mul_f32_e32 v49, v54, v49
	v_add_f32_e32 v54, 1.0, v55
	v_rcp_f32_e32 v55, v54
	v_add_f32_e32 v54, 1.0, v56
	v_rcp_f32_e32 v56, v54
	v_cvt_pk_bf16_f32 v54, v48, v49
	v_mul_f32_e32 v48, v58, v55
	v_mul_f32_e32 v48, v48, v50
	v_mul_f32_e32 v49, v59, v56
	v_mul_f32_e32 v50, 0xbfb8aa3b, v44
	v_mul_f32_e32 v49, v49, v51
	v_exp_f32_e32 v50, v50
	v_mul_f32_e32 v51, 0xbfb8aa3b, v45
	v_exp_f32_e32 v51, v51
	v_cvt_pk_bf16_f32 v55, v48, v49
	v_add_f32_e32 v50, 1.0, v50
	v_rcp_f32_e32 v50, v50
	v_add_f32_e32 v51, 1.0, v51
	v_rcp_f32_e32 v51, v51
	v_mad_i64_i32 v[48:49], s[16:17], v66, s40, v[112:113]
	v_mul_f32_e32 v44, v44, v50
	v_mul_f32_e32 v36, v44, v36
	v_mul_f32_e32 v44, v45, v51
	v_mul_f32_e32 v45, 0xbfb8aa3b, v46
	v_exp_f32_e32 v45, v45
	v_lshl_add_u64 v[48:49], v[48:49], 0, v[114:115]
	global_store_dwordx4 v[48:49], v[52:55], off
	v_mul_f32_e32 v48, 0xbfb8aa3b, v47
	v_exp_f32_e32 v48, v48
	v_mul_f32_e32 v37, v44, v37
	v_add_f32_e32 v44, 1.0, v45
	v_rcp_f32_e32 v44, v44
	v_add_f32_e32 v45, 1.0, v48
	v_rcp_f32_e32 v45, v45
	v_cvt_pk_bf16_f32 v36, v36, v37
	v_mul_f32_e32 v37, v46, v44
	v_mul_f32_e32 v44, 0xbfb8aa3b, v40
	v_exp_f32_e32 v44, v44
	v_mul_f32_e32 v37, v37, v38
	v_mul_f32_e32 v38, v47, v45
	v_mul_f32_e32 v45, 0xbfb8aa3b, v41
	v_exp_f32_e32 v45, v45
	v_mul_f32_e32 v38, v38, v39
	v_add_f32_e32 v39, 1.0, v44
	v_rcp_f32_e32 v39, v39
	v_add_f32_e32 v44, 1.0, v45
	v_rcp_f32_e32 v44, v44
; __device__ __forceinline__ unsigned cvt_pk_bf16(float lo, float hi) { unsigned r; asm volatile("v_cvt_pk_bf16_f32 %0, %1, %2" : "=v"(r) : "v"(lo), "v"(hi)); return r; }
; __device__ __forceinline__ float silu_f(float a) { return a * __builtin_amdgcn_rcpf(1.0f + __expf(-a)); }
; #define PG8_WAIT_V(n) asm volatile("s_waitcnt vmcnt(" #n ")" ::: "memory")
; #define PG8_BAR __builtin_amdgcn_s_barrier()
; template <class Epi, class Sched>
; __device__ __forceinline__ void gemm_phase(LAS unsigned char* lds, const Gemm g, const Sched& S, const Epi& E) {
;     ...
;         if (!has_next) break;
; #pragma unroll
;         for (int a = 0; a < 2; ++a)
; #pragma unroll
;             for (int b = 0; b < 2; ++b)
; #pragma unroll
;                 for (int m = 0; m < 4; ++m)
; #pragma unroll
;                     for (int n = 0; n < 2; ++n) acc[a][b][m][n] = (f32x4){0.f, 0.f, 0.f, 0.f};
;         cur = nxt; cA = nA; cB = nB; ++ui;
;     }
;     PG8_WAIT_V(0);
;     if (wr == 0) PG8_BAR;
;     PG8_BAR;
;     __device__ __forceinline__ void operator()(const AccT& acc, const Unit& u, int wr, int wc, int fr, int fq) const {
;     ...
;         for (int ai = 0; ai < 2; ++ai)
; #pragma unroll
;             for (int m = 0; m < 4; ++m) {
;                 const f32x4 a0 = acc[ai][0][m][0], a1 = acc[ai][0][m][1], b0 = acc[ai][1][m][0], b1 = acc[ai][1][m][1];
;                 u32x4 w;
;                 w.x = cvt_pk_bf16(silu_f(a0[0]) * b0[0], silu_f(a0[1]) * b0[1]); w.y = cvt_pk_bf16(silu_f(a0[2]) * b0[2], silu_f(a0[3]) * b0[3]);
;                 w.z = cvt_pk_bf16(silu_f(a1[0]) * b1[0], silu_f(a1[1]) * b1[1]); w.w = cvt_pk_bf16(silu_f(a1[2]) * b1[2], silu_f(a1[3]) * b1[3]);
;                 *(u32x4*)(H + (size_t)(row0 + ai * 128 + m * 16) * DFF + hc0) = w;
;             }
	v_cvt_pk_bf16_f32 v37, v37, v38
	v_mul_f32_e32 v38, v40, v39
	v_mul_f32_e32 v39, 0xbfb8aa3b, v42
	v_exp_f32_e32 v39, v39
	v_mul_f32_e32 v40, 0xbfb8aa3b, v43
	v_exp_f32_e32 v40, v40
	v_mul_f32_e32 v32, v38, v32
	v_mul_f32_e32 v38, v41, v44
	v_mul_f32_e32 v33, v38, v33
	v_add_f32_e32 v38, 1.0, v39
	v_rcp_f32_e32 v39, v38
	v_add_f32_e32 v38, 1.0, v40
	v_rcp_f32_e32 v40, v38
	v_cvt_pk_bf16_f32 v38, v32, v33
	v_mul_f32_e32 v32, v42, v39
	v_mul_f32_e32 v32, v32, v34
	v_mul_f32_e32 v33, v43, v40
	v_mul_f32_e32 v34, 0xbfb8aa3b, v28
	v_mul_f32_e32 v33, v33, v35
	v_exp_f32_e32 v34, v34
	v_mul_f32_e32 v35, 0xbfb8aa3b, v29
	v_exp_f32_e32 v35, v35
	v_cvt_pk_bf16_f32 v39, v32, v33
	v_add_f32_e32 v34, 1.0, v34
	v_rcp_f32_e32 v34, v34
	v_add_f32_e32 v35, 1.0, v35
	v_rcp_f32_e32 v35, v35
	v_add_u32_e32 v32, 0x90, v150
	v_mul_f32_e32 v28, v28, v34
	v_mul_f32_e32 v20, v28, v20
	v_mul_f32_e32 v28, v29, v35
	v_mul_f32_e32 v29, 0xbfb8aa3b, v30
	v_exp_f32_e32 v29, v29
	v_mad_i64_i32 v[32:33], s[16:17], v32, s40, v[112:113]
	v_lshl_add_u64 v[32:33], v[32:33], 0, v[114:115]
	global_store_dwordx4 v[32:33], v[36:39], off
	v_mul_f32_e32 v32, 0xbfb8aa3b, v31
	v_exp_f32_e32 v32, v32
	v_mul_f32_e32 v21, v28, v21
	v_add_f32_e32 v28, 1.0, v29
	v_rcp_f32_e32 v28, v28
	v_add_f32_e32 v29, 1.0, v32
	v_rcp_f32_e32 v29, v29
	v_cvt_pk_bf16_f32 v20, v20, v21
	v_mul_f32_e32 v21, v30, v28
	v_mul_f32_e32 v28, 0xbfb8aa3b, v24
	v_exp_f32_e32 v28, v28
	v_mul_f32_e32 v21, v21, v22
	v_mul_f32_e32 v22, v31, v29
	v_mul_f32_e32 v29, 0xbfb8aa3b, v25
	v_exp_f32_e32 v29, v29
	v_mul_f32_e32 v22, v22, v23
	v_add_f32_e32 v23, 1.0, v28
	v_rcp_f32_e32 v23, v23
	v_add_f32_e32 v28, 1.0, v29
	v_rcp_f32_e32 v28, v28
	v_cvt_pk_bf16_f32 v21, v21, v22
	v_mul_f32_e32 v22, v24, v23
	v_mul_f32_e32 v23, 0xbfb8aa3b, v26
	v_exp_f32_e32 v23, v23
	v_mul_f32_e32 v24, 0xbfb8aa3b, v27
	v_exp_f32_e32 v24, v24
	v_mul_f32_e32 v16, v22, v16
	v_mul_f32_e32 v22, v25, v28
	v_mul_f32_e32 v17, v22, v17
	v_add_f32_e32 v22, 1.0, v23
	v_rcp_f32_e32 v23, v22
	v_add_f32_e32 v22, 1.0, v24
	v_rcp_f32_e32 v24, v22
	v_cvt_pk_bf16_f32 v22, v16, v17
	v_mul_f32_e32 v16, v26, v23
	v_mul_f32_e32 v16, v16, v18
	v_mul_f32_e32 v17, v27, v24
	v_mul_f32_e32 v18, 0xbfb8aa3b, v12
	v_mul_f32_e32 v17, v17, v19
	v_exp_f32_e32 v18, v18
	v_mul_f32_e32 v19, 0xbfb8aa3b, v13
	v_exp_f32_e32 v19, v19
	v_cvt_pk_bf16_f32 v23, v16, v17
	v_add_f32_e32 v18, 1.0, v18
	v_rcp_f32_e32 v18, v18
	v_add_f32_e32 v19, 1.0, v19
	v_rcp_f32_e32 v19, v19
	v_add_u32_e32 v16, 0xa0, v150
	v_mul_f32_e32 v12, v12, v18
	v_mul_f32_e32 v4, v12, v4
	v_mul_f32_e32 v12, v13, v19
	v_mul_f32_e32 v13, 0xbfb8aa3b, v14
	v_exp_f32_e32 v13, v13
	v_mad_i64_i32 v[16:17], s[16:17], v16, s40, v[112:113]
	v_lshl_add_u64 v[16:17], v[16:17], 0, v[114:115]
	global_store_dwordx4 v[16:17], v[20:23], off
	v_mul_f32_e32 v16, 0xbfb8aa3b, v15
	v_exp_f32_e32 v16, v16
	v_mul_f32_e32 v5, v12, v5
	v_add_f32_e32 v12, 1.0, v13
	v_rcp_f32_e32 v12, v12
	v_add_f32_e32 v13, 1.0, v16
	v_rcp_f32_e32 v13, v13
	v_cvt_pk_bf16_f32 v4, v4, v5
	v_mul_f32_e32 v5, v14, v12
	v_mul_f32_e32 v12, 0xbfb8aa3b, v8
	v_exp_f32_e32 v12, v12
	v_mul_f32_e32 v5, v5, v6
	v_mul_f32_e32 v6, v15, v13
	v_mul_f32_e32 v13, 0xbfb8aa3b, v9
	v_exp_f32_e32 v13, v13
	v_mul_f32_e32 v6, v6, v7
	v_add_f32_e32 v7, 1.0, v12
	v_rcp_f32_e32 v7, v7
	v_add_f32_e32 v12, 1.0, v13
	v_rcp_f32_e32 v12, v12
	v_cvt_pk_bf16_f32 v5, v5, v6
	v_mul_f32_e32 v6, v8, v7
	v_mul_f32_e32 v7, 0xbfb8aa3b, v10
	v_exp_f32_e32 v7, v7
	v_mul_f32_e32 v8, 0xbfb8aa3b, v11
	v_exp_f32_e32 v8, v8
	v_mul_f32_e32 v0, v6, v0
	v_mul_f32_e32 v6, v9, v12
	v_mul_f32_e32 v1, v6, v1
	v_add_f32_e32 v6, 1.0, v7
	v_rcp_f32_e32 v7, v6
	v_add_f32_e32 v6, 1.0, v8
	v_rcp_f32_e32 v8, v6
	v_cvt_pk_bf16_f32 v6, v0, v1
	v_mul_f32_e32 v0, v10, v7
	v_mul_f32_e32 v0, v0, v2
	v_mul_f32_e32 v1, v11, v8
	v_mul_f32_e32 v1, v1, v3
	v_cvt_pk_bf16_f32 v7, v0, v1
	v_add_u32_e32 v0, 0xb0, v150
	v_mad_i64_i32 v[0:1], s[16:17], v0, s40, v[112:113]
	v_lshl_add_u64 v[0:1], v[0:1], 0, v[114:115]
	s_and_b64 vcc, exec, s[2:3]
	s_mov_b32 s41, s4
	s_mov_b32 s14, s6
	s_mov_b64 s[18:19], s[12:13]
	s_mov_b64 s[16:17], s[10:11]
	global_store_dwordx4 v[0:1], v[4:7], off
	s_cbranch_vccz .LBB0_1018
	s_waitcnt vmcnt(0)
	s_cmpk_gt_u32 s22, 0xff
	s_cbranch_scc1 .LBB0_1025
	s_barrier

; #define PG8_STAGE(bufoff, gbase, voff) do { _Pragma("unroll") for (int _i = 0; _i < 2; ++_i) \
;         __builtin_amdgcn_global_load_lds((const unsigned*)((const char*)(gbase) + (voff)[_i]), (LAS unsigned*)(lds + (bufoff) + ldsw + _i * 8192), 16, 0, 0); } while (0)
; #define PG8_LDA(dst, b, h) do { _Pragma("unroll") for (int m = 0; m < 4; ++m) _Pragma("unroll") for (int k = 0; k < 2; ++k) dst[m][k] = *(const LAS bf16x8*)(lds + PG8_SA(b, h) + aoff + m * 2048 + k * 1024); } while (0)
; #define PG8_LDB(dst, b, h) do { _Pragma("unroll") for (int n = 0; n < 2; ++n) _Pragma("unroll") for (int k = 0; k < 2; ++k) dst[n][k] = *(const LAS bf16x8*)(lds + PG8_SB(b, h) + boff + n * 2048 + k * 1024); } while (0)
; #define PG8_MMA(ai, bj, At, Bt) do { __builtin_amdgcn_s_setprio(1); _Pragma("unroll") for (int m = 0; m < 4; ++m) _Pragma("unroll") for (int n = 0; n < 2; ++n) _Pragma("unroll") for (int k = 0; k < 2; ++k) \
;         acc[ai][bj][m][n] = __builtin_amdgcn_mfma_f32_16x16x32_bf16(Bt[n][k], At[m][k], acc[ai][bj][m][n], 0, 0, 0); __builtin_amdgcn_s_setprio(0); } while (0)
; #define PG8_WAIT_V(n) asm volatile("s_waitcnt vmcnt(" #n ")" ::: "memory")
; #define PG8_WAIT_L(n) asm volatile("s_waitcnt lgkmcnt(" #n ")" ::: "memory")
; #define PG8_BAR __builtin_amdgcn_s_barrier()
; #define PG8_SCHED __builtin_amdgcn_sched_barrier(0)
; template <class Epi, class Sched>
; __device__ __forceinline__ void gemm_phase(LAS unsigned char* lds, const Gemm g, const Sched& S, const Epi& E) {
;     ...
;             PG8_LDB(B0, 0, 0); PG8_SCHED; PG8_LDA(At, 0, 0); PG8_STAGE(PG8_SA(1, 1), a1 + hstep, voffA);
;             PG8_WAIT_L(8); PG8_BAR; PG8_WAIT_L(0); PG8_MMA(0, 0, At, B0); PG8_BAR; PG8_SCHED;
;             PG8_LDB(B1, 0, 1); PG8_STAGE(PG8_SB(0, 0), b2, voffB);
;             PG8_BAR; PG8_WAIT_L(0); PG8_MMA(0, 1, At, B1); PG8_BAR;
;             PG8_LDA(At, 0, 1); PG8_STAGE(PG8_SA(0, 0), a2, voffA);
;             PG8_BAR; PG8_WAIT_L(0); PG8_MMA(1, 0, At, B0); PG8_BAR; PG8_SCHED;
;             PG8_STAGE(PG8_SB(0, 1), b2 + hstep, voffB);
;             PG8_WAIT_V(6); PG8_BAR; PG8_MMA(1, 1, At, B1); PG8_BAR;
.LBB0_1096:
	s_add_u32 s54, s24, 0x100
	s_addc_u32 s55, s25, 0
	s_mov_b32 s56, -2
	ds_read_b128 v[128:131], v241
	ds_read_b128 v[132:135], v241 offset:1024
	ds_read_b128 v[136:139], v241 offset:2048
	ds_read_b128 v[140:143], v241 offset:3072
	s_add_u32 s24, s22, 0x100
	s_addc_u32 s25, s23, 0
	s_cmp_eq_u32 s56, 40
	s_cselect_b32 s29, s5, s25
	s_cselect_b32 s28, s4, s24
	s_cselect_b32 s27, s7, s55
	s_cselect_b32 s26, s6, s54
	v_lshl_add_u64 v[176:177], s[22:23], 0, v[196:197]
	s_add_i32 m0, s35, 0xc000
	ds_read_b128 v[144:147], v242
	ds_read_b128 v[148:151], v242 offset:1024
	ds_read_b128 v[152:155], v242 offset:2048
	ds_read_b128 v[156:159], v242 offset:3072
	ds_read_b128 v[160:163], v242 offset:4096
	ds_read_b128 v[164:167], v242 offset:5120
	ds_read_b128 v[168:171], v242 offset:6144
	ds_read_b128 v[172:175], v242 offset:7168
	global_load_lds_dwordx4 v[176:177], off
	v_lshl_add_u64 v[176:177], s[22:23], 0, v[198:199]
	s_add_i32 m0, s35, 0xe000
	s_nop 0
	global_load_lds_dwordx4 v[176:177], off
	s_waitcnt lgkmcnt(8)
	s_waitcnt vmcnt(10)
	s_barrier
	s_waitcnt lgkmcnt(0)
	s_setprio 1
	s_waitcnt lgkmcnt(0)
	v_mfma_f32_16x16x32_bf16 v[124:127], v[128:131], v[144:147], 0
	v_mfma_f32_16x16x32_bf16 v[120:123], v[136:139], v[144:147], 0
	v_mfma_f32_16x16x32_bf16 v[108:111], v[128:131], v[152:155], 0
	v_mfma_f32_16x16x32_bf16 v[104:107], v[136:139], v[152:155], 0
	v_mfma_f32_16x16x32_bf16 v[92:95], v[128:131], v[160:163], 0
	v_mfma_f32_16x16x32_bf16 v[88:91], v[136:139], v[160:163], 0
	v_mfma_f32_16x16x32_bf16 v[76:79], v[128:131], v[168:171], 0
	v_mfma_f32_16x16x32_bf16 v[72:75], v[136:139], v[168:171], 0
	v_mfma_f32_16x16x32_bf16 v[124:127], v[132:135], v[148:151], v[124:127]
	v_mfma_f32_16x16x32_bf16 v[120:123], v[140:143], v[148:151], v[120:123]
	v_mfma_f32_16x16x32_bf16 v[108:111], v[132:135], v[156:159], v[108:111]
	v_mfma_f32_16x16x32_bf16 v[104:107], v[140:143], v[156:159], v[104:107]
	v_mfma_f32_16x16x32_bf16 v[92:95], v[132:135], v[164:167], v[92:95]
	v_mfma_f32_16x16x32_bf16 v[88:91], v[140:143], v[164:167], v[88:91]
	v_mfma_f32_16x16x32_bf16 v[76:79], v[132:135], v[172:175], v[76:79]
	v_mfma_f32_16x16x32_bf16 v[72:75], v[140:143], v[172:175], v[72:75]
	s_setprio 0
	s_barrier
	s_add_i32 s22, s48, s34
	s_mov_b32 m0, s22
	ds_read_b128 v[176:179], v243
	ds_read_b128 v[180:183], v243 offset:1024
	ds_read_b128 v[184:187], v243 offset:2048
	ds_read_b128 v[206:209], v243 offset:3072
	global_load_lds_dwordx4 v190, s[26:27]
	s_add_i32 m0, s22, 0x2000
	s_nop 0
	global_load_lds_dwordx4 v194, s[26:27]
	s_waitcnt vmcnt(10)
	s_barrier
	s_waitcnt lgkmcnt(0)
	s_setprio 1
	s_waitcnt lgkmcnt(0)
	v_mfma_f32_16x16x32_bf16 v[116:119], v[176:179], v[144:147], 0
	v_mfma_f32_16x16x32_bf16 v[112:115], v[184:187], v[144:147], 0
	v_mfma_f32_16x16x32_bf16 v[100:103], v[176:179], v[152:155], 0
	v_mfma_f32_16x16x32_bf16 v[96:99], v[184:187], v[152:155], 0
	v_mfma_f32_16x16x32_bf16 v[84:87], v[176:179], v[160:163], 0
	v_mfma_f32_16x16x32_bf16 v[80:83], v[184:187], v[160:163], 0
	v_mfma_f32_16x16x32_bf16 v[68:71], v[176:179], v[168:171], 0
	v_mfma_f32_16x16x32_bf16 v[64:67], v[184:187], v[168:171], 0
	v_mfma_f32_16x16x32_bf16 v[116:119], v[180:183], v[148:151], v[116:119]
	v_mfma_f32_16x16x32_bf16 v[112:115], v[206:209], v[148:151], v[112:115]
	v_mfma_f32_16x16x32_bf16 v[100:103], v[180:183], v[156:159], v[100:103]
	v_mfma_f32_16x16x32_bf16 v[96:99], v[206:209], v[156:159], v[96:99]
	v_mfma_f32_16x16x32_bf16 v[84:87], v[180:183], v[164:167], v[84:87]
	v_mfma_f32_16x16x32_bf16 v[80:83], v[206:209], v[164:167], v[80:83]
	v_mfma_f32_16x16x32_bf16 v[68:71], v[180:183], v[172:175], v[68:71]
	v_mfma_f32_16x16x32_bf16 v[64:67], v[206:209], v[172:175], v[64:67]
	s_setprio 0
	s_mov_b32 m0, s35
	v_lshl_add_u64 v[214:215], s[28:29], 0, v[188:189]
	s_barrier
	ds_read_b128 v[144:147], v242 offset:16384
	ds_read_b128 v[148:151], v242 offset:17408
	ds_read_b128 v[152:155], v242 offset:18432
	ds_read_b128 v[156:159], v242 offset:19456
	ds_read_b128 v[160:163], v242 offset:20480
	ds_read_b128 v[164:167], v242 offset:21504
	ds_read_b128 v[168:171], v242 offset:22528
	ds_read_b128 v[172:175], v242 offset:23552
	global_load_lds_dwordx4 v188, s[28:29]
	v_lshl_add_u64 v[216:217], s[28:29], 0, v[192:193]
	s_mov_b32 m0, s36
	s_nop 0
	global_load_lds_dwordx4 v192, s[28:29]
	s_barrier
	s_waitcnt lgkmcnt(0)
	s_setprio 1
	s_waitcnt lgkmcnt(0)
	v_mfma_f32_16x16x32_bf16 v[60:63], v[128:131], v[144:147], 0
	v_mfma_f32_16x16x32_bf16 v[56:59], v[136:139], v[144:147], 0
	v_mfma_f32_16x16x32_bf16 v[44:47], v[128:131], v[152:155], 0
	v_mfma_f32_16x16x32_bf16 v[40:43], v[136:139], v[152:155], 0
	v_mfma_f32_16x16x32_bf16 v[28:31], v[128:131], v[160:163], 0
	v_mfma_f32_16x16x32_bf16 v[24:27], v[136:139], v[160:163], 0
	v_mfma_f32_16x16x32_bf16 v[12:15], v[128:131], v[168:171], 0
	v_mfma_f32_16x16x32_bf16 v[8:11], v[136:139], v[168:171], 0
	v_mfma_f32_16x16x32_bf16 v[60:63], v[132:135], v[148:151], v[60:63]
	v_mfma_f32_16x16x32_bf16 v[56:59], v[140:143], v[148:151], v[56:59]
	v_mfma_f32_16x16x32_bf16 v[44:47], v[132:135], v[156:159], v[44:47]
	v_mfma_f32_16x16x32_bf16 v[40:43], v[140:143], v[156:159], v[40:43]
	v_mfma_f32_16x16x32_bf16 v[28:31], v[132:135], v[164:167], v[28:31]
	v_mfma_f32_16x16x32_bf16 v[24:27], v[140:143], v[164:167], v[24:27]
	v_mfma_f32_16x16x32_bf16 v[12:15], v[132:135], v[172:175], v[12:15]
	v_mfma_f32_16x16x32_bf16 v[8:11], v[140:143], v[172:175], v[8:11]
	s_setprio 0
	s_barrier
	s_add_u32 s22, s26, 0xb0000
	s_addc_u32 s23, s27, 0
	s_add_i32 s57, s49, s34
	s_mov_b32 m0, s57
	s_nop 0
	global_load_lds_dwordx4 v190, s[22:23]
	s_add_i32 m0, s57, 0x2000
	s_nop 0
	global_load_lds_dwordx4 v194, s[22:23]
	s_waitcnt vmcnt(10)
	s_barrier
; #define PG8_STAGE(bufoff, gbase, voff) do { _Pragma("unroll") for (int _i = 0; _i < 2; ++_i) \
;         __builtin_amdgcn_global_load_lds((const unsigned*)((const char*)(gbase) + (voff)[_i]), (LAS unsigned*)(lds + (bufoff) + ldsw + _i * 8192), 16, 0, 0); } while (0)
; #define PG8_LDA(dst, b, h) do { _Pragma("unroll") for (int m = 0; m < 4; ++m) _Pragma("unroll") for (int k = 0; k < 2; ++k) dst[m][k] = *(const LAS bf16x8*)(lds + PG8_SA(b, h) + aoff + m * 2048 + k * 1024); } while (0)
; #define PG8_LDB(dst, b, h) do { _Pragma("unroll") for (int n = 0; n < 2; ++n) _Pragma("unroll") for (int k = 0; k < 2; ++k) dst[n][k] = *(const LAS bf16x8*)(lds + PG8_SB(b, h) + boff + n * 2048 + k * 1024); } while (0)
; #define PG8_MMA(ai, bj, At, Bt) do { __builtin_amdgcn_s_setprio(1); _Pragma("unroll") for (int m = 0; m < 4; ++m) _Pragma("unroll") for (int n = 0; n < 2; ++n) _Pragma("unroll") for (int k = 0; k < 2; ++k) \
;         acc[ai][bj][m][n] = __builtin_amdgcn_mfma_f32_16x16x32_bf16(Bt[n][k], At[m][k], acc[ai][bj][m][n], 0, 0, 0); __builtin_amdgcn_s_setprio(0); } while (0)
; #define PG8_WAIT_V(n) asm volatile("s_waitcnt vmcnt(" #n ")" ::: "memory")
; #define PG8_WAIT_L(n) asm volatile("s_waitcnt lgkmcnt(" #n ")" ::: "memory")
; #define PG8_BAR __builtin_amdgcn_s_barrier()
; #define PG8_SCHED __builtin_amdgcn_sched_barrier(0)
; template <class Epi, class Sched>
; __device__ __forceinline__ void gemm_phase(LAS unsigned char* lds, const Gemm g, const Sched& S, const Epi& E) {
;     ...
;             PG8_WAIT_V(6); PG8_BAR; PG8_MMA(1, 1, At, B1); PG8_BAR;
;             PG8_LDB(B0, 1, 0); PG8_SCHED; PG8_LDA(At, 1, 0); PG8_STAGE(PG8_SA(0, 1), a2 + hstep, voffA);
;             PG8_WAIT_L(8); PG8_BAR; PG8_WAIT_L(0); PG8_MMA(0, 0, At, B0); PG8_BAR; PG8_SCHED;
;             PG8_LDB(B1, 1, 1); PG8_STAGE(PG8_SB(1, 0), b3, voffB);
;             PG8_BAR; PG8_WAIT_L(0); PG8_MMA(0, 1, At, B1); PG8_BAR;
;             PG8_LDA(At, 1, 1); PG8_STAGE(PG8_SA(1, 0), a3, voffA);
;             PG8_BAR; PG8_WAIT_L(0); PG8_MMA(1, 0, At, B0); PG8_BAR; PG8_SCHED;
	s_setprio 1
	v_mfma_f32_16x16x32_bf16 v[52:55], v[176:179], v[144:147], 0
	v_mfma_f32_16x16x32_bf16 v[48:51], v[184:187], v[144:147], 0
	v_mfma_f32_16x16x32_bf16 v[36:39], v[176:179], v[152:155], 0
	v_mfma_f32_16x16x32_bf16 v[32:35], v[184:187], v[152:155], 0
	v_mfma_f32_16x16x32_bf16 v[20:23], v[176:179], v[160:163], 0
	v_mfma_f32_16x16x32_bf16 v[16:19], v[184:187], v[160:163], 0
	v_mfma_f32_16x16x32_bf16 v[4:7], v[176:179], v[168:171], 0
	v_mfma_f32_16x16x32_bf16 v[0:3], v[184:187], v[168:171], 0
	v_mfma_f32_16x16x32_bf16 v[52:55], v[180:183], v[148:151], v[52:55]
	v_mfma_f32_16x16x32_bf16 v[48:51], v[206:209], v[148:151], v[48:51]
	v_mfma_f32_16x16x32_bf16 v[36:39], v[180:183], v[156:159], v[36:39]
	v_mfma_f32_16x16x32_bf16 v[32:35], v[206:209], v[156:159], v[32:35]
	v_mfma_f32_16x16x32_bf16 v[20:23], v[180:183], v[164:167], v[20:23]
	v_mfma_f32_16x16x32_bf16 v[16:19], v[206:209], v[164:167], v[16:19]
	v_mfma_f32_16x16x32_bf16 v[4:7], v[180:183], v[172:175], v[4:7]
	v_mfma_f32_16x16x32_bf16 v[0:3], v[206:209], v[172:175], v[0:3]
	s_setprio 0
	s_add_i32 s57, 0, 0x18000
	v_add_u32_e32 v140, s57, v240
	s_barrier
	ds_read_b128 v[128:131], v140
	ds_read_b128 v[132:135], v140 offset:1024
	ds_read_b128 v[136:139], v140 offset:2048
	ds_read_b128 v[140:143], v140 offset:3072
	s_add_u32 s22, s28, 0xb0000
	s_addc_u32 s23, s29, 0
	s_mov_b32 m0, s37
	ds_read_b128 v[144:147], v242 offset:32768
	ds_read_b128 v[148:151], v242 offset:33792
	ds_read_b128 v[152:155], v242 offset:34816
	ds_read_b128 v[156:159], v242 offset:35840
	ds_read_b128 v[160:163], v242 offset:36864
	ds_read_b128 v[164:167], v242 offset:37888
	ds_read_b128 v[168:171], v242 offset:38912
	ds_read_b128 v[172:175], v242 offset:39936
	global_load_lds_dwordx4 v188, s[22:23]
	s_mov_b32 m0, s38
	s_nop 0
	global_load_lds_dwordx4 v192, s[22:23]
	s_waitcnt lgkmcnt(8)
	s_waitcnt vmcnt(10)
	s_barrier
	s_waitcnt lgkmcnt(0)
	s_setprio 1
	s_waitcnt lgkmcnt(0)
	v_mfma_f32_16x16x32_bf16 v[124:127], v[128:131], v[144:147], v[124:127]
	v_mfma_f32_16x16x32_bf16 v[120:123], v[136:139], v[144:147], v[120:123]
	v_mfma_f32_16x16x32_bf16 v[108:111], v[128:131], v[152:155], v[108:111]
	v_mfma_f32_16x16x32_bf16 v[104:107], v[136:139], v[152:155], v[104:107]
	v_mfma_f32_16x16x32_bf16 v[92:95], v[128:131], v[160:163], v[92:95]
	v_mfma_f32_16x16x32_bf16 v[88:91], v[136:139], v[160:163], v[88:91]
	v_mfma_f32_16x16x32_bf16 v[76:79], v[128:131], v[168:171], v[76:79]
	v_mfma_f32_16x16x32_bf16 v[72:75], v[136:139], v[168:171], v[72:75]
	v_mfma_f32_16x16x32_bf16 v[124:127], v[132:135], v[148:151], v[124:127]
	v_mfma_f32_16x16x32_bf16 v[120:123], v[140:143], v[148:151], v[120:123]
	v_mfma_f32_16x16x32_bf16 v[108:111], v[132:135], v[156:159], v[108:111]
	v_mfma_f32_16x16x32_bf16 v[104:107], v[140:143], v[156:159], v[104:107]
	v_mfma_f32_16x16x32_bf16 v[92:95], v[132:135], v[164:167], v[92:95]
	v_mfma_f32_16x16x32_bf16 v[88:91], v[140:143], v[164:167], v[88:91]
	v_mfma_f32_16x16x32_bf16 v[76:79], v[132:135], v[172:175], v[76:79]
	v_mfma_f32_16x16x32_bf16 v[72:75], v[140:143], v[172:175], v[72:75]
	s_setprio 0
	s_barrier
	s_add_i32 s28, 0, 0x1c000
	s_add_i32 s22, s57, s34
	v_add_u32_e32 v206, s28, v240
	s_add_u32 s0, s26, 0x80
	s_addc_u32 s1, s27, 0
	s_mov_b32 m0, s22
	ds_read_b128 v[176:179], v206
	ds_read_b128 v[180:183], v206 offset:1024
	ds_read_b128 v[184:187], v206 offset:2048
	ds_read_b128 v[206:209], v206 offset:3072
	global_load_lds_dwordx4 v190, s[0:1]
	s_add_i32 m0, s22, 0x2000
	s_nop 0
	global_load_lds_dwordx4 v194, s[0:1]
	s_waitcnt vmcnt(10)
	s_barrier
	s_waitcnt lgkmcnt(0)
	s_setprio 1
	s_waitcnt lgkmcnt(0)
	v_mfma_f32_16x16x32_bf16 v[116:119], v[176:179], v[144:147], v[116:119]
	v_mfma_f32_16x16x32_bf16 v[112:115], v[184:187], v[144:147], v[112:115]
	v_mfma_f32_16x16x32_bf16 v[100:103], v[176:179], v[152:155], v[100:103]
	v_mfma_f32_16x16x32_bf16 v[96:99], v[184:187], v[152:155], v[96:99]
	v_mfma_f32_16x16x32_bf16 v[84:87], v[176:179], v[160:163], v[84:87]
	v_mfma_f32_16x16x32_bf16 v[80:83], v[184:187], v[160:163], v[80:83]
	v_mfma_f32_16x16x32_bf16 v[68:71], v[176:179], v[168:171], v[68:71]
	v_mfma_f32_16x16x32_bf16 v[64:67], v[184:187], v[168:171], v[64:67]
	v_mfma_f32_16x16x32_bf16 v[116:119], v[180:183], v[148:151], v[116:119]
	v_mfma_f32_16x16x32_bf16 v[112:115], v[206:209], v[148:151], v[112:115]
	v_mfma_f32_16x16x32_bf16 v[100:103], v[180:183], v[156:159], v[100:103]
	v_mfma_f32_16x16x32_bf16 v[96:99], v[206:209], v[156:159], v[96:99]
	v_mfma_f32_16x16x32_bf16 v[84:87], v[180:183], v[164:167], v[84:87]
	v_mfma_f32_16x16x32_bf16 v[80:83], v[206:209], v[164:167], v[80:83]
	v_mfma_f32_16x16x32_bf16 v[68:71], v[180:183], v[172:175], v[68:71]
	v_mfma_f32_16x16x32_bf16 v[64:67], v[206:209], v[172:175], v[64:67]
	s_setprio 0
	s_mov_b32 m0, s44
	s_mov_b64 s[0:1], 0x80
	v_lshl_add_u64 v[210:211], v[214:215], 0, s[0:1]
	s_barrier
	ds_read_b128 v[144:147], v242 offset:49152
	ds_read_b128 v[148:151], v242 offset:50176
	ds_read_b128 v[152:155], v242 offset:51200
	ds_read_b128 v[156:159], v242 offset:52224
	ds_read_b128 v[160:163], v242 offset:53248
	ds_read_b128 v[164:167], v242 offset:54272
	ds_read_b128 v[168:171], v242 offset:55296
	ds_read_b128 v[172:175], v242 offset:56320
	global_load_lds_dwordx4 v[210:211], off
	v_lshl_add_u64 v[210:211], v[216:217], 0, s[0:1]
	s_mov_b32 m0, s45
	s_nop 0
	global_load_lds_dwordx4 v[210:211], off
	s_barrier
; #define PG8_STAGE(bufoff, gbase, voff) do { _Pragma("unroll") for (int _i = 0; _i < 2; ++_i) \
;         __builtin_amdgcn_global_load_lds((const unsigned*)((const char*)(gbase) + (voff)[_i]), (LAS unsigned*)(lds + (bufoff) + ldsw + _i * 8192), 16, 0, 0); } while (0)
; #define PG8_LDA(dst, b, h) do { _Pragma("unroll") for (int m = 0; m < 4; ++m) _Pragma("unroll") for (int k = 0; k < 2; ++k) dst[m][k] = *(const LAS bf16x8*)(lds + PG8_SA(b, h) + aoff + m * 2048 + k * 1024); } while (0)
; #define PG8_LDB(dst, b, h) do { _Pragma("unroll") for (int n = 0; n < 2; ++n) _Pragma("unroll") for (int k = 0; k < 2; ++k) dst[n][k] = *(const LAS bf16x8*)(lds + PG8_SB(b, h) + boff + n * 2048 + k * 1024); } while (0)
; #define PG8_MMA(ai, bj, At, Bt) do { __builtin_amdgcn_s_setprio(1); _Pragma("unroll") for (int m = 0; m < 4; ++m) _Pragma("unroll") for (int n = 0; n < 2; ++n) _Pragma("unroll") for (int k = 0; k < 2; ++k) \
;         acc[ai][bj][m][n] = __builtin_amdgcn_mfma_f32_16x16x32_bf16(Bt[n][k], At[m][k], acc[ai][bj][m][n], 0, 0, 0); __builtin_amdgcn_s_setprio(0); } while (0)
; #define PG8_WAIT_V(n) asm volatile("s_waitcnt vmcnt(" #n ")" ::: "memory")
; #define PG8_WAIT_L(n) asm volatile("s_waitcnt lgkmcnt(" #n ")" ::: "memory")
; #define PG8_BAR __builtin_amdgcn_s_barrier()
; #define PG8_SCHED __builtin_amdgcn_sched_barrier(0)
; template <class Epi, class Sched>
; __device__ __forceinline__ void gemm_phase(LAS unsigned char* lds, const Gemm g, const Sched& S, const Epi& E) {
;     ...
;             PG8_LDB(B0, 0, 0); PG8_SCHED; PG8_LDA(At, 0, 0); PG8_STAGE(PG8_SA(1, 1), a1 + hstep, voffA);
;             PG8_WAIT_L(8); PG8_BAR; PG8_WAIT_L(0); PG8_MMA(0, 0, At, B0); PG8_BAR; PG8_SCHED;
;             PG8_LDB(B1, 0, 1); PG8_STAGE(PG8_SB(0, 0), b2, voffB);
;             PG8_BAR; PG8_WAIT_L(0); PG8_MMA(0, 1, At, B1); PG8_BAR;
;     ...
;             PG8_BAR; PG8_WAIT_L(0); PG8_MMA(1, 0, At, B0); PG8_BAR; PG8_SCHED;
;             PG8_STAGE(PG8_SB(1, 1), b3 + hstep, voffB);
;             PG8_WAIT_V(6); PG8_BAR; PG8_MMA(1, 1, At, B1); PG8_BAR;
	s_waitcnt lgkmcnt(0)
	s_setprio 1
	s_waitcnt lgkmcnt(0)
	v_mfma_f32_16x16x32_bf16 v[60:63], v[128:131], v[144:147], v[60:63]
	v_mfma_f32_16x16x32_bf16 v[56:59], v[136:139], v[144:147], v[56:59]
	v_mfma_f32_16x16x32_bf16 v[44:47], v[128:131], v[152:155], v[44:47]
	v_mfma_f32_16x16x32_bf16 v[40:43], v[136:139], v[152:155], v[40:43]
	v_mfma_f32_16x16x32_bf16 v[28:31], v[128:131], v[160:163], v[28:31]
	v_mfma_f32_16x16x32_bf16 v[24:27], v[136:139], v[160:163], v[24:27]
	v_mfma_f32_16x16x32_bf16 v[12:15], v[128:131], v[168:171], v[12:15]
	v_mfma_f32_16x16x32_bf16 v[8:11], v[136:139], v[168:171], v[8:11]
	v_mfma_f32_16x16x32_bf16 v[60:63], v[132:135], v[148:151], v[60:63]
	v_mfma_f32_16x16x32_bf16 v[56:59], v[140:143], v[148:151], v[56:59]
	v_mfma_f32_16x16x32_bf16 v[44:47], v[132:135], v[156:159], v[44:47]
	v_mfma_f32_16x16x32_bf16 v[40:43], v[140:143], v[156:159], v[40:43]
	v_mfma_f32_16x16x32_bf16 v[28:31], v[132:135], v[164:167], v[28:31]
	v_mfma_f32_16x16x32_bf16 v[24:27], v[140:143], v[164:167], v[24:27]
	v_mfma_f32_16x16x32_bf16 v[12:15], v[132:135], v[172:175], v[12:15]
	v_mfma_f32_16x16x32_bf16 v[8:11], v[140:143], v[172:175], v[8:11]
	s_setprio 0
	s_barrier
	s_add_u32 s22, s26, 0xb0080
	s_addc_u32 s23, s27, 0
	s_add_i32 s26, s28, s34
	s_mov_b32 m0, s26
	s_nop 0
	global_load_lds_dwordx4 v190, s[22:23]
	s_add_i32 m0, s26, 0x2000
	s_nop 0
	global_load_lds_dwordx4 v194, s[22:23]
	s_waitcnt vmcnt(10)
	s_barrier
	s_setprio 1
	v_mfma_f32_16x16x32_bf16 v[52:55], v[176:179], v[144:147], v[52:55]
	v_mfma_f32_16x16x32_bf16 v[48:51], v[184:187], v[144:147], v[48:51]
	v_mfma_f32_16x16x32_bf16 v[36:39], v[176:179], v[152:155], v[36:39]
	v_mfma_f32_16x16x32_bf16 v[32:35], v[184:187], v[152:155], v[32:35]
	v_mfma_f32_16x16x32_bf16 v[20:23], v[176:179], v[160:163], v[20:23]
	v_mfma_f32_16x16x32_bf16 v[16:19], v[184:187], v[160:163], v[16:19]
	v_mfma_f32_16x16x32_bf16 v[4:7], v[176:179], v[168:171], v[4:7]
	v_mfma_f32_16x16x32_bf16 v[0:3], v[184:187], v[168:171], v[0:3]
	v_mfma_f32_16x16x32_bf16 v[52:55], v[180:183], v[148:151], v[52:55]
	v_mfma_f32_16x16x32_bf16 v[48:51], v[206:209], v[148:151], v[48:51]
	v_mfma_f32_16x16x32_bf16 v[36:39], v[180:183], v[156:159], v[36:39]
	v_mfma_f32_16x16x32_bf16 v[32:35], v[206:209], v[156:159], v[32:35]
	v_mfma_f32_16x16x32_bf16 v[20:23], v[180:183], v[164:167], v[20:23]
	v_mfma_f32_16x16x32_bf16 v[16:19], v[206:209], v[164:167], v[16:19]
	v_mfma_f32_16x16x32_bf16 v[4:7], v[180:183], v[172:175], v[4:7]
	v_mfma_f32_16x16x32_bf16 v[0:3], v[206:209], v[172:175], v[0:3]
	s_setprio 0
	s_add_i32 s56, s56, 2
	s_add_u32 s54, s54, 0x100
	s_addc_u32 s55, s55, 0
	s_cmp_gt_u32 s56, 41
	s_mov_b64 s[22:23], s[24:25]
	s_barrier
.LBB0_1097:
	ds_read_b128 v[128:131], v241
	ds_read_b128 v[132:135], v241 offset:1024
	ds_read_b128 v[136:139], v241 offset:2048
	ds_read_b128 v[140:143], v241 offset:3072
	s_add_u32 s24, s22, 0x100
	s_addc_u32 s25, s23, 0
	s_cmp_eq_u32 s56, 40
	s_cselect_b32 s29, s5, s25
	s_cselect_b32 s28, s4, s24
	s_cselect_b32 s27, s7, s55
	s_cselect_b32 s26, s6, s54
	v_lshl_add_u64 v[176:177], s[22:23], 0, v[196:197]
	s_add_i32 m0, s35, 0xc000
	ds_read_b128 v[144:147], v242
	ds_read_b128 v[148:151], v242 offset:1024
	ds_read_b128 v[152:155], v242 offset:2048
	ds_read_b128 v[156:159], v242 offset:3072
	ds_read_b128 v[160:163], v242 offset:4096
	ds_read_b128 v[164:167], v242 offset:5120
	ds_read_b128 v[168:171], v242 offset:6144
	ds_read_b128 v[172:175], v242 offset:7168
	global_load_lds_dwordx4 v[176:177], off
	v_lshl_add_u64 v[176:177], s[22:23], 0, v[198:199]
	s_add_i32 m0, s35, 0xe000
	s_nop 0
	global_load_lds_dwordx4 v[176:177], off
	s_waitcnt lgkmcnt(8)
	s_waitcnt vmcnt(10)
	s_barrier
	s_waitcnt lgkmcnt(0)
	s_setprio 1
	s_waitcnt lgkmcnt(0)
	v_mfma_f32_16x16x32_bf16 v[124:127], v[128:131], v[144:147], v[124:127]
	v_mfma_f32_16x16x32_bf16 v[120:123], v[136:139], v[144:147], v[120:123]
	v_mfma_f32_16x16x32_bf16 v[108:111], v[128:131], v[152:155], v[108:111]
	v_mfma_f32_16x16x32_bf16 v[104:107], v[136:139], v[152:155], v[104:107]
	v_mfma_f32_16x16x32_bf16 v[92:95], v[128:131], v[160:163], v[92:95]
	v_mfma_f32_16x16x32_bf16 v[88:91], v[136:139], v[160:163], v[88:91]
	v_mfma_f32_16x16x32_bf16 v[76:79], v[128:131], v[168:171], v[76:79]
	v_mfma_f32_16x16x32_bf16 v[72:75], v[136:139], v[168:171], v[72:75]
	v_mfma_f32_16x16x32_bf16 v[124:127], v[132:135], v[148:151], v[124:127]
	v_mfma_f32_16x16x32_bf16 v[120:123], v[140:143], v[148:151], v[120:123]
	v_mfma_f32_16x16x32_bf16 v[108:111], v[132:135], v[156:159], v[108:111]
	v_mfma_f32_16x16x32_bf16 v[104:107], v[140:143], v[156:159], v[104:107]
	v_mfma_f32_16x16x32_bf16 v[92:95], v[132:135], v[164:167], v[92:95]
	v_mfma_f32_16x16x32_bf16 v[88:91], v[140:143], v[164:167], v[88:91]
	v_mfma_f32_16x16x32_bf16 v[76:79], v[132:135], v[172:175], v[76:79]
	v_mfma_f32_16x16x32_bf16 v[72:75], v[140:143], v[172:175], v[72:75]
	s_setprio 0
	s_barrier
	s_add_i32 s22, s48, s34
	s_mov_b32 m0, s22
	ds_read_b128 v[176:179], v243
	ds_read_b128 v[180:183], v243 offset:1024
	ds_read_b128 v[184:187], v243 offset:2048
	ds_read_b128 v[206:209], v243 offset:3072
	global_load_lds_dwordx4 v190, s[26:27]
	s_add_i32 m0, s22, 0x2000
	s_nop 0
	global_load_lds_dwordx4 v194, s[26:27]
	s_waitcnt vmcnt(10)
	s_barrier
; #define PG8_STAGE(bufoff, gbase, voff) do { _Pragma("unroll") for (int _i = 0; _i < 2; ++_i) \
;         __builtin_amdgcn_global_load_lds((const unsigned*)((const char*)(gbase) + (voff)[_i]), (LAS unsigned*)(lds + (bufoff) + ldsw + _i * 8192), 16, 0, 0); } while (0)
; #define PG8_LDA(dst, b, h) do { _Pragma("unroll") for (int m = 0; m < 4; ++m) _Pragma("unroll") for (int k = 0; k < 2; ++k) dst[m][k] = *(const LAS bf16x8*)(lds + PG8_SA(b, h) + aoff + m * 2048 + k * 1024); } while (0)
; #define PG8_LDB(dst, b, h) do { _Pragma("unroll") for (int n = 0; n < 2; ++n) _Pragma("unroll") for (int k = 0; k < 2; ++k) dst[n][k] = *(const LAS bf16x8*)(lds + PG8_SB(b, h) + boff + n * 2048 + k * 1024); } while (0)
; #define PG8_MMA(ai, bj, At, Bt) do { __builtin_amdgcn_s_setprio(1); _Pragma("unroll") for (int m = 0; m < 4; ++m) _Pragma("unroll") for (int n = 0; n < 2; ++n) _Pragma("unroll") for (int k = 0; k < 2; ++k) \
;         acc[ai][bj][m][n] = __builtin_amdgcn_mfma_f32_16x16x32_bf16(Bt[n][k], At[m][k], acc[ai][bj][m][n], 0, 0, 0); __builtin_amdgcn_s_setprio(0); } while (0)
; #define PG8_WAIT_V(n) asm volatile("s_waitcnt vmcnt(" #n ")" ::: "memory")
; #define PG8_WAIT_L(n) asm volatile("s_waitcnt lgkmcnt(" #n ")" ::: "memory")
; #define PG8_BAR __builtin_amdgcn_s_barrier()
; #define PG8_SCHED __builtin_amdgcn_sched_barrier(0)
; template <class Epi, class Sched>
; __device__ __forceinline__ void gemm_phase(LAS unsigned char* lds, const Gemm g, const Sched& S, const Epi& E) {
;     ...
;             PG8_LDA(At, 0, 1); PG8_STAGE(PG8_SA(0, 0), a2, voffA);
;             PG8_BAR; PG8_WAIT_L(0); PG8_MMA(1, 0, At, B0); PG8_BAR; PG8_SCHED;
;             PG8_STAGE(PG8_SB(0, 1), b2 + hstep, voffB);
;             PG8_WAIT_V(6); PG8_BAR; PG8_MMA(1, 1, At, B1); PG8_BAR;
;             PG8_LDB(B0, 1, 0); PG8_SCHED; PG8_LDA(At, 1, 0); PG8_STAGE(PG8_SA(0, 1), a2 + hstep, voffA);
;             PG8_WAIT_L(8); PG8_BAR; PG8_WAIT_L(0); PG8_MMA(0, 0, At, B0); PG8_BAR; PG8_SCHED;
	s_waitcnt lgkmcnt(0)
	s_setprio 1
	s_waitcnt lgkmcnt(0)
	v_mfma_f32_16x16x32_bf16 v[116:119], v[176:179], v[144:147], v[116:119]
	v_mfma_f32_16x16x32_bf16 v[112:115], v[184:187], v[144:147], v[112:115]
	v_mfma_f32_16x16x32_bf16 v[100:103], v[176:179], v[152:155], v[100:103]
	v_mfma_f32_16x16x32_bf16 v[96:99], v[184:187], v[152:155], v[96:99]
	v_mfma_f32_16x16x32_bf16 v[84:87], v[176:179], v[160:163], v[84:87]
	v_mfma_f32_16x16x32_bf16 v[80:83], v[184:187], v[160:163], v[80:83]
	v_mfma_f32_16x16x32_bf16 v[68:71], v[176:179], v[168:171], v[68:71]
	v_mfma_f32_16x16x32_bf16 v[64:67], v[184:187], v[168:171], v[64:67]
	v_mfma_f32_16x16x32_bf16 v[116:119], v[180:183], v[148:151], v[116:119]
	v_mfma_f32_16x16x32_bf16 v[112:115], v[206:209], v[148:151], v[112:115]
	v_mfma_f32_16x16x32_bf16 v[100:103], v[180:183], v[156:159], v[100:103]
	v_mfma_f32_16x16x32_bf16 v[96:99], v[206:209], v[156:159], v[96:99]
	v_mfma_f32_16x16x32_bf16 v[84:87], v[180:183], v[164:167], v[84:87]
	v_mfma_f32_16x16x32_bf16 v[80:83], v[206:209], v[164:167], v[80:83]
	v_mfma_f32_16x16x32_bf16 v[68:71], v[180:183], v[172:175], v[68:71]
	v_mfma_f32_16x16x32_bf16 v[64:67], v[206:209], v[172:175], v[64:67]
	s_setprio 0
	s_mov_b32 m0, s35
	v_lshl_add_u64 v[214:215], s[28:29], 0, v[188:189]
	s_barrier
	ds_read_b128 v[144:147], v242 offset:16384
	ds_read_b128 v[148:151], v242 offset:17408
	ds_read_b128 v[152:155], v242 offset:18432
	ds_read_b128 v[156:159], v242 offset:19456
	ds_read_b128 v[160:163], v242 offset:20480
	ds_read_b128 v[164:167], v242 offset:21504
	ds_read_b128 v[168:171], v242 offset:22528
	ds_read_b128 v[172:175], v242 offset:23552
	global_load_lds_dwordx4 v188, s[28:29]
	v_lshl_add_u64 v[216:217], s[28:29], 0, v[192:193]
	s_mov_b32 m0, s36
	s_nop 0
	global_load_lds_dwordx4 v192, s[28:29]
	s_barrier
	s_waitcnt lgkmcnt(0)
	s_setprio 1
	s_waitcnt lgkmcnt(0)
	v_mfma_f32_16x16x32_bf16 v[60:63], v[128:131], v[144:147], v[60:63]
	v_mfma_f32_16x16x32_bf16 v[56:59], v[136:139], v[144:147], v[56:59]
	v_mfma_f32_16x16x32_bf16 v[44:47], v[128:131], v[152:155], v[44:47]
	v_mfma_f32_16x16x32_bf16 v[40:43], v[136:139], v[152:155], v[40:43]
	v_mfma_f32_16x16x32_bf16 v[28:31], v[128:131], v[160:163], v[28:31]
	v_mfma_f32_16x16x32_bf16 v[24:27], v[136:139], v[160:163], v[24:27]
	v_mfma_f32_16x16x32_bf16 v[12:15], v[128:131], v[168:171], v[12:15]
	v_mfma_f32_16x16x32_bf16 v[8:11], v[136:139], v[168:171], v[8:11]
	v_mfma_f32_16x16x32_bf16 v[60:63], v[132:135], v[148:151], v[60:63]
	v_mfma_f32_16x16x32_bf16 v[56:59], v[140:143], v[148:151], v[56:59]
	v_mfma_f32_16x16x32_bf16 v[44:47], v[132:135], v[156:159], v[44:47]
	v_mfma_f32_16x16x32_bf16 v[40:43], v[140:143], v[156:159], v[40:43]
	v_mfma_f32_16x16x32_bf16 v[28:31], v[132:135], v[164:167], v[28:31]
	v_mfma_f32_16x16x32_bf16 v[24:27], v[140:143], v[164:167], v[24:27]
	v_mfma_f32_16x16x32_bf16 v[12:15], v[132:135], v[172:175], v[12:15]
	v_mfma_f32_16x16x32_bf16 v[8:11], v[140:143], v[172:175], v[8:11]
	s_setprio 0
	s_barrier
	s_add_u32 s22, s26, 0xb0000
	s_addc_u32 s23, s27, 0
	s_add_i32 s57, s49, s34
	s_mov_b32 m0, s57
	s_nop 0
	global_load_lds_dwordx4 v190, s[22:23]
	s_add_i32 m0, s57, 0x2000
	s_nop 0
	global_load_lds_dwordx4 v194, s[22:23]
	s_waitcnt vmcnt(10)
	s_barrier
	s_setprio 1
	v_mfma_f32_16x16x32_bf16 v[52:55], v[176:179], v[144:147], v[52:55]
	v_mfma_f32_16x16x32_bf16 v[48:51], v[184:187], v[144:147], v[48:51]
	v_mfma_f32_16x16x32_bf16 v[36:39], v[176:179], v[152:155], v[36:39]
	v_mfma_f32_16x16x32_bf16 v[32:35], v[184:187], v[152:155], v[32:35]
	v_mfma_f32_16x16x32_bf16 v[20:23], v[176:179], v[160:163], v[20:23]
	v_mfma_f32_16x16x32_bf16 v[16:19], v[184:187], v[160:163], v[16:19]
	v_mfma_f32_16x16x32_bf16 v[4:7], v[176:179], v[168:171], v[4:7]
	v_mfma_f32_16x16x32_bf16 v[0:3], v[184:187], v[168:171], v[0:3]
	v_mfma_f32_16x16x32_bf16 v[52:55], v[180:183], v[148:151], v[52:55]
	v_mfma_f32_16x16x32_bf16 v[48:51], v[206:209], v[148:151], v[48:51]
	v_mfma_f32_16x16x32_bf16 v[36:39], v[180:183], v[156:159], v[36:39]
	v_mfma_f32_16x16x32_bf16 v[32:35], v[206:209], v[156:159], v[32:35]
	v_mfma_f32_16x16x32_bf16 v[20:23], v[180:183], v[164:167], v[20:23]
	v_mfma_f32_16x16x32_bf16 v[16:19], v[206:209], v[164:167], v[16:19]
	v_mfma_f32_16x16x32_bf16 v[4:7], v[180:183], v[172:175], v[4:7]
	v_mfma_f32_16x16x32_bf16 v[0:3], v[206:209], v[172:175], v[0:3]
	s_setprio 0
	s_add_i32 s57, 0, 0x18000
	v_add_u32_e32 v140, s57, v240
	s_barrier
	ds_read_b128 v[128:131], v140
	ds_read_b128 v[132:135], v140 offset:1024
	ds_read_b128 v[136:139], v140 offset:2048
	ds_read_b128 v[140:143], v140 offset:3072
	s_add_u32 s22, s28, 0xb0000
	s_addc_u32 s23, s29, 0
	s_mov_b32 m0, s37
	ds_read_b128 v[144:147], v242 offset:32768
	ds_read_b128 v[148:151], v242 offset:33792
	ds_read_b128 v[152:155], v242 offset:34816
	ds_read_b128 v[156:159], v242 offset:35840
	ds_read_b128 v[160:163], v242 offset:36864
	ds_read_b128 v[164:167], v242 offset:37888
	ds_read_b128 v[168:171], v242 offset:38912
	ds_read_b128 v[172:175], v242 offset:39936
	global_load_lds_dwordx4 v188, s[22:23]
	s_mov_b32 m0, s38
	s_nop 0
	global_load_lds_dwordx4 v192, s[22:23]
	s_waitcnt lgkmcnt(8)
	s_waitcnt vmcnt(10)
	s_barrier
; #define PG8_STAGE(bufoff, gbase, voff) do { _Pragma("unroll") for (int _i = 0; _i < 2; ++_i) \
;         __builtin_amdgcn_global_load_lds((const unsigned*)((const char*)(gbase) + (voff)[_i]), (LAS unsigned*)(lds + (bufoff) + ldsw + _i * 8192), 16, 0, 0); } while (0)
; #define PG8_LDA(dst, b, h) do { _Pragma("unroll") for (int m = 0; m < 4; ++m) _Pragma("unroll") for (int k = 0; k < 2; ++k) dst[m][k] = *(const LAS bf16x8*)(lds + PG8_SA(b, h) + aoff + m * 2048 + k * 1024); } while (0)
; #define PG8_LDB(dst, b, h) do { _Pragma("unroll") for (int n = 0; n < 2; ++n) _Pragma("unroll") for (int k = 0; k < 2; ++k) dst[n][k] = *(const LAS bf16x8*)(lds + PG8_SB(b, h) + boff + n * 2048 + k * 1024); } while (0)
; #define PG8_MMA(ai, bj, At, Bt) do { __builtin_amdgcn_s_setprio(1); _Pragma("unroll") for (int m = 0; m < 4; ++m) _Pragma("unroll") for (int n = 0; n < 2; ++n) _Pragma("unroll") for (int k = 0; k < 2; ++k) \
;         acc[ai][bj][m][n] = __builtin_amdgcn_mfma_f32_16x16x32_bf16(Bt[n][k], At[m][k], acc[ai][bj][m][n], 0, 0, 0); __builtin_amdgcn_s_setprio(0); } while (0)
; #define PG8_WAIT_V(n) asm volatile("s_waitcnt vmcnt(" #n ")" ::: "memory")
; #define PG8_WAIT_L(n) asm volatile("s_waitcnt lgkmcnt(" #n ")" ::: "memory")
; #define PG8_BAR __builtin_amdgcn_s_barrier()
; #define PG8_SCHED __builtin_amdgcn_sched_barrier(0)
; template <class Epi, class Sched>
; __device__ __forceinline__ void gemm_phase(LAS unsigned char* lds, const Gemm g, const Sched& S, const Epi& E) {
;     ...
;             PG8_LDB(B0, 1, 0); PG8_SCHED; PG8_LDA(At, 1, 0); PG8_STAGE(PG8_SA(0, 1), a2 + hstep, voffA);
;             PG8_WAIT_L(8); PG8_BAR; PG8_WAIT_L(0); PG8_MMA(0, 0, At, B0); PG8_BAR; PG8_SCHED;
;             PG8_LDB(B1, 1, 1); PG8_STAGE(PG8_SB(1, 0), b3, voffB);
;             PG8_BAR; PG8_WAIT_L(0); PG8_MMA(0, 1, At, B1); PG8_BAR;
;             PG8_LDA(At, 1, 1); PG8_STAGE(PG8_SA(1, 0), a3, voffA);
;             PG8_BAR; PG8_WAIT_L(0); PG8_MMA(1, 0, At, B0); PG8_BAR; PG8_SCHED;
;             PG8_STAGE(PG8_SB(1, 1), b3 + hstep, voffB);
;             PG8_WAIT_V(6); PG8_BAR; PG8_MMA(1, 1, At, B1); PG8_BAR;
	s_waitcnt lgkmcnt(0)
	s_setprio 1
	s_waitcnt lgkmcnt(0)
	v_mfma_f32_16x16x32_bf16 v[124:127], v[128:131], v[144:147], v[124:127]
	v_mfma_f32_16x16x32_bf16 v[120:123], v[136:139], v[144:147], v[120:123]
	v_mfma_f32_16x16x32_bf16 v[108:111], v[128:131], v[152:155], v[108:111]
	v_mfma_f32_16x16x32_bf16 v[104:107], v[136:139], v[152:155], v[104:107]
	v_mfma_f32_16x16x32_bf16 v[92:95], v[128:131], v[160:163], v[92:95]
	v_mfma_f32_16x16x32_bf16 v[88:91], v[136:139], v[160:163], v[88:91]
	v_mfma_f32_16x16x32_bf16 v[76:79], v[128:131], v[168:171], v[76:79]
	v_mfma_f32_16x16x32_bf16 v[72:75], v[136:139], v[168:171], v[72:75]
	v_mfma_f32_16x16x32_bf16 v[124:127], v[132:135], v[148:151], v[124:127]
	v_mfma_f32_16x16x32_bf16 v[120:123], v[140:143], v[148:151], v[120:123]
	v_mfma_f32_16x16x32_bf16 v[108:111], v[132:135], v[156:159], v[108:111]
	v_mfma_f32_16x16x32_bf16 v[104:107], v[140:143], v[156:159], v[104:107]
	v_mfma_f32_16x16x32_bf16 v[92:95], v[132:135], v[164:167], v[92:95]
	v_mfma_f32_16x16x32_bf16 v[88:91], v[140:143], v[164:167], v[88:91]
	v_mfma_f32_16x16x32_bf16 v[76:79], v[132:135], v[172:175], v[76:79]
	v_mfma_f32_16x16x32_bf16 v[72:75], v[140:143], v[172:175], v[72:75]
	s_setprio 0
	s_barrier
	s_add_i32 s28, 0, 0x1c000
	s_add_i32 s22, s57, s34
	v_add_u32_e32 v206, s28, v240
	s_add_u32 s0, s26, 0x80
	s_addc_u32 s1, s27, 0
	s_mov_b32 m0, s22
	ds_read_b128 v[176:179], v206
	ds_read_b128 v[180:183], v206 offset:1024
	ds_read_b128 v[184:187], v206 offset:2048
	ds_read_b128 v[206:209], v206 offset:3072
	global_load_lds_dwordx4 v190, s[0:1]
	s_add_i32 m0, s22, 0x2000
	s_nop 0
	global_load_lds_dwordx4 v194, s[0:1]
	s_waitcnt vmcnt(10)
	s_barrier
	s_waitcnt lgkmcnt(0)
	s_setprio 1
	s_waitcnt lgkmcnt(0)
	v_mfma_f32_16x16x32_bf16 v[116:119], v[176:179], v[144:147], v[116:119]
	v_mfma_f32_16x16x32_bf16 v[112:115], v[184:187], v[144:147], v[112:115]
	v_mfma_f32_16x16x32_bf16 v[100:103], v[176:179], v[152:155], v[100:103]
	v_mfma_f32_16x16x32_bf16 v[96:99], v[184:187], v[152:155], v[96:99]
	v_mfma_f32_16x16x32_bf16 v[84:87], v[176:179], v[160:163], v[84:87]
	v_mfma_f32_16x16x32_bf16 v[80:83], v[184:187], v[160:163], v[80:83]
	v_mfma_f32_16x16x32_bf16 v[68:71], v[176:179], v[168:171], v[68:71]
	v_mfma_f32_16x16x32_bf16 v[64:67], v[184:187], v[168:171], v[64:67]
	v_mfma_f32_16x16x32_bf16 v[116:119], v[180:183], v[148:151], v[116:119]
	v_mfma_f32_16x16x32_bf16 v[112:115], v[206:209], v[148:151], v[112:115]
	v_mfma_f32_16x16x32_bf16 v[100:103], v[180:183], v[156:159], v[100:103]
	v_mfma_f32_16x16x32_bf16 v[96:99], v[206:209], v[156:159], v[96:99]
	v_mfma_f32_16x16x32_bf16 v[84:87], v[180:183], v[164:167], v[84:87]
	v_mfma_f32_16x16x32_bf16 v[80:83], v[206:209], v[164:167], v[80:83]
	v_mfma_f32_16x16x32_bf16 v[68:71], v[180:183], v[172:175], v[68:71]
	v_mfma_f32_16x16x32_bf16 v[64:67], v[206:209], v[172:175], v[64:67]
	s_setprio 0
	s_mov_b32 m0, s44
	s_mov_b64 s[0:1], 0x80
	v_lshl_add_u64 v[210:211], v[214:215], 0, s[0:1]
	s_barrier
	ds_read_b128 v[144:147], v242 offset:49152
	ds_read_b128 v[148:151], v242 offset:50176
	ds_read_b128 v[152:155], v242 offset:51200
	ds_read_b128 v[156:159], v242 offset:52224
	ds_read_b128 v[160:163], v242 offset:53248
	ds_read_b128 v[164:167], v242 offset:54272
	ds_read_b128 v[168:171], v242 offset:55296
	ds_read_b128 v[172:175], v242 offset:56320
	global_load_lds_dwordx4 v[210:211], off
	v_lshl_add_u64 v[210:211], v[216:217], 0, s[0:1]
	s_mov_b32 m0, s45
	s_nop 0
	global_load_lds_dwordx4 v[210:211], off
	s_barrier
	s_waitcnt lgkmcnt(0)
	s_setprio 1
	s_waitcnt lgkmcnt(0)
	v_mfma_f32_16x16x32_bf16 v[60:63], v[128:131], v[144:147], v[60:63]
	v_mfma_f32_16x16x32_bf16 v[56:59], v[136:139], v[144:147], v[56:59]
	v_mfma_f32_16x16x32_bf16 v[44:47], v[128:131], v[152:155], v[44:47]
	v_mfma_f32_16x16x32_bf16 v[40:43], v[136:139], v[152:155], v[40:43]
	v_mfma_f32_16x16x32_bf16 v[28:31], v[128:131], v[160:163], v[28:31]
	v_mfma_f32_16x16x32_bf16 v[24:27], v[136:139], v[160:163], v[24:27]
	v_mfma_f32_16x16x32_bf16 v[12:15], v[128:131], v[168:171], v[12:15]
	v_mfma_f32_16x16x32_bf16 v[8:11], v[136:139], v[168:171], v[8:11]
	v_mfma_f32_16x16x32_bf16 v[60:63], v[132:135], v[148:151], v[60:63]
	v_mfma_f32_16x16x32_bf16 v[56:59], v[140:143], v[148:151], v[56:59]
	v_mfma_f32_16x16x32_bf16 v[44:47], v[132:135], v[156:159], v[44:47]
	v_mfma_f32_16x16x32_bf16 v[40:43], v[140:143], v[156:159], v[40:43]
	v_mfma_f32_16x16x32_bf16 v[28:31], v[132:135], v[164:167], v[28:31]
	v_mfma_f32_16x16x32_bf16 v[24:27], v[140:143], v[164:167], v[24:27]
	v_mfma_f32_16x16x32_bf16 v[12:15], v[132:135], v[172:175], v[12:15]
	v_mfma_f32_16x16x32_bf16 v[8:11], v[140:143], v[172:175], v[8:11]
	s_setprio 0
	s_barrier
	s_add_u32 s22, s26, 0xb0080
	s_addc_u32 s23, s27, 0
	s_add_i32 s26, s28, s34
	s_mov_b32 m0, s26
	s_nop 0
	global_load_lds_dwordx4 v190, s[22:23]
	s_add_i32 m0, s26, 0x2000
	s_nop 0
	global_load_lds_dwordx4 v194, s[22:23]
	s_waitcnt vmcnt(10)
	s_barrier
	s_setprio 1
	v_mfma_f32_16x16x32_bf16 v[52:55], v[176:179], v[144:147], v[52:55]
	v_mfma_f32_16x16x32_bf16 v[48:51], v[184:187], v[144:147], v[48:51]
	v_mfma_f32_16x16x32_bf16 v[36:39], v[176:179], v[152:155], v[36:39]
	v_mfma_f32_16x16x32_bf16 v[32:35], v[184:187], v[152:155], v[32:35]
	v_mfma_f32_16x16x32_bf16 v[20:23], v[176:179], v[160:163], v[20:23]
	v_mfma_f32_16x16x32_bf16 v[16:19], v[184:187], v[160:163], v[16:19]
	v_mfma_f32_16x16x32_bf16 v[4:7], v[176:179], v[168:171], v[4:7]
	v_mfma_f32_16x16x32_bf16 v[0:3], v[184:187], v[168:171], v[0:3]
	v_mfma_f32_16x16x32_bf16 v[52:55], v[180:183], v[148:151], v[52:55]
	v_mfma_f32_16x16x32_bf16 v[48:51], v[206:209], v[148:151], v[48:51]
	v_mfma_f32_16x16x32_bf16 v[36:39], v[180:183], v[156:159], v[36:39]
	v_mfma_f32_16x16x32_bf16 v[32:35], v[206:209], v[156:159], v[32:35]
	v_mfma_f32_16x16x32_bf16 v[20:23], v[180:183], v[164:167], v[20:23]
	v_mfma_f32_16x16x32_bf16 v[16:19], v[206:209], v[164:167], v[16:19]
	v_mfma_f32_16x16x32_bf16 v[4:7], v[180:183], v[172:175], v[4:7]
	v_mfma_f32_16x16x32_bf16 v[0:3], v[206:209], v[172:175], v[0:3]
	s_setprio 0
	s_add_i32 s56, s56, 2
	s_add_u32 s54, s54, 0x100
	s_addc_u32 s55, s55, 0
	s_cmp_gt_u32 s56, 41
	s_mov_b64 s[22:23], s[24:25]
	s_barrier
; __device__ __forceinline__ float bf_lo(unsigned u) { return __uint_as_float(u << 16); }
; __device__ __forceinline__ float bf_hi(unsigned u) { return __uint_as_float(u & 0xffff0000u); }
;     __device__ __forceinline__ void operator()(const AccT& acc, const Unit& u, int wr, int wc, int fr, int fq) const {
;         asm volatile("" : "+v"(fr), "+v"(fq));
;         const int rowt = u.pm * 256; const int b = rowt >> 11;
;         const bf16_t* res = res_b + (size_t)rowt * DM; bf16_t* out = hb + (size_t)rowt * DM;
;         const int col0 = u.pn * 256 + wc * 32 + 8 * fq;
;         f32x4 gv[2][2];
; #pragma unroll
;         for (int bj = 0; bj < 2; ++bj)
; #pragma unroll
;             for (int n = 0; n < 2; ++n) gv[bj][n] = *(const f32x4*)(gate + (size_t)b * NMOD + col0 + bj * 128 + n * 4) * gs;
;         u32x4 r[2][4][2];
; #pragma unroll
;         for (int ai = 0; ai < 2; ++ai)
; #pragma unroll
;             for (int m = 0; m < 4; ++m)
; #pragma unroll
;                 for (int bj = 0; bj < 2; ++bj) r[ai][m][bj] = *(const u32x4*)(res + (size_t)(wr * 64 + fr + ai * 128 + m * 16) * DM + col0 + bj * 128);
; #pragma unroll
;         for (int ai = 0; ai < 2; ++ai)
; #pragma unroll
;             for (int m = 0; m < 4; ++m)
; #pragma unroll
;                 for (int bj = 0; bj < 2; ++bj) {
;                     const u32x4 q = r[ai][m][bj];
;                     const f32x4 r0 = {bf_lo(q.x), bf_hi(q.x), bf_lo(q.y), bf_hi(q.y)}, r1 = {bf_lo(q.z), bf_hi(q.z), bf_lo(q.w), bf_hi(q.w)};
;                     const f32x4 h0 = r0 + gv[bj][0] * acc[ai][bj][m][0], h1 = r1 + gv[bj][1] * acc[ai][bj][m][1];
	s_cbranch_scc0 .LBB0_1097
	s_lshl_b32 s25, s52, 8
	v_mov_b32_e32 v140, v239
	v_mov_b32_e32 v128, v238
	s_lshl_b32 s22, s53, 8
	s_ashr_i32 s24, s53, 3
	s_or_b32 s25, s25, s43
	s_ashr_i32 s23, s22, 31
	v_lshl_add_u32 v136, v128, 3, s25
	s_mul_hi_i32 s25, s24, 0x9000
	s_mul_i32 s24, s24, 0x9000
	s_add_u32 s24, s40, s24
	s_addc_u32 s25, s41, s25
	v_ashrrev_i32_e32 v137, 31, v136
	v_lshl_add_u64 v[138:139], v[136:137], 2, s[24:25]
	global_load_dwordx4 v[128:131], v[138:139], off offset:16
	global_load_dwordx4 v[132:135], v[138:139], off
	s_lshl_b64 s[22:23], s[22:23], 11
	s_add_u32 s24, s80, s22
	s_addc_u32 s25, s81, s23
	v_lshlrev_b64 v[226:227], 1, v[136:137]
	s_add_u32 s22, s96, s22
	s_addc_u32 s23, s97, s23
	s_and_b64 vcc, exec, s[2:3]
	s_mov_b32 s52, s50
	s_mov_b32 s53, s51
	s_waitcnt vmcnt(0)
	v_pk_mul_f32 v[216:217], v[130:131], 0.5 op_sel_hi:[1,0]
	v_pk_mul_f32 v[220:221], v[134:135], 0.5 op_sel_hi:[1,0]
	v_pk_mul_f32 v[218:219], v[132:133], 0.5 op_sel_hi:[1,0]
	v_pk_mul_f32 v[214:215], v[128:129], 0.5 op_sel_hi:[1,0]
	global_load_dwordx4 v[128:131], v[138:139], off offset:528
	global_load_dwordx4 v[132:135], v[138:139], off offset:512
	s_waitcnt vmcnt(0)
	v_pk_mul_f32 v[206:207], v[128:129], 0.5 op_sel_hi:[1,0]
	v_add_u32_e32 v128, s42, v140
	v_ashrrev_i32_e32 v129, 31, v128
	v_pk_mul_f32 v[208:209], v[130:131], 0.5 op_sel_hi:[1,0]
	v_lshl_add_u64 v[130:131], s[24:25], 0, v[226:227]
	v_lshlrev_b64 v[248:249], 11, v[128:129]
	v_lshl_add_u64 v[128:129], v[130:131], 0, v[248:249]
	global_load_dwordx4 v[244:247], v[128:129], off
	global_load_dwordx4 v[184:187], v[128:129], off offset:256
	v_lshl_add_u64 v[236:237], v[248:249], 0, s[8:9]
	v_lshl_add_u64 v[128:129], v[130:131], 0, v[236:237]
	global_load_dwordx4 v[180:183], v[128:129], off
	global_load_dwordx4 v[176:179], v[128:129], off offset:256
	v_lshl_add_u64 v[234:235], v[248:249], 0, s[10:11]
	v_lshl_add_u64 v[128:129], v[130:131], 0, v[234:235]
	global_load_dwordx4 v[172:175], v[128:129], off
	global_load_dwordx4 v[168:171], v[128:129], off offset:256
	v_lshl_add_u64 v[232:233], v[248:249], 0, s[12:13]
	v_lshl_add_u64 v[128:129], v[130:131], 0, v[232:233]
	global_load_dwordx4 v[164:167], v[128:129], off
	global_load_dwordx4 v[160:163], v[128:129], off offset:256
	v_lshl_add_u64 v[230:231], v[248:249], 0, s[14:15]
	v_lshl_add_u64 v[128:129], v[130:131], 0, v[230:231]
	global_load_dwordx4 v[156:159], v[128:129], off
	global_load_dwordx4 v[152:155], v[128:129], off offset:256
	v_lshl_add_u64 v[228:229], v[248:249], 0, s[16:17]
	v_lshl_add_u64 v[128:129], v[130:131], 0, v[228:229]
	global_load_dwordx4 v[148:151], v[128:129], off
	global_load_dwordx4 v[144:147], v[128:129], off offset:256
	v_lshl_add_u64 v[224:225], v[248:249], 0, s[18:19]
	v_lshl_add_u64 v[128:129], v[130:131], 0, v[224:225]
	global_load_dwordx4 v[140:143], v[128:129], off
	global_load_dwordx4 v[136:139], v[128:129], off offset:256
	v_lshl_add_u64 v[222:223], v[248:249], 0, s[20:21]
	v_lshl_add_u64 v[128:129], v[130:131], 0, v[222:223]
	v_pk_mul_f32 v[212:213], v[134:135], 0.5 op_sel_hi:[1,0]
	v_pk_mul_f32 v[210:211], v[132:133], 0.5 op_sel_hi:[1,0]
	global_load_dwordx4 v[132:135], v[128:129], off
	s_nop 0
	global_load_dwordx4 v[128:131], v[128:129], off offset:256
	v_lshl_add_u64 v[226:227], s[22:23], 0, v[226:227]
	v_lshl_add_u64 v[248:249], v[226:227], 0, v[248:249]
	s_mov_b64 s[24:25], s[6:7]
	s_mov_b64 s[22:23], s[4:5]
	s_waitcnt vmcnt(0)
	v_lshlrev_b32_e32 v250, 16, v244
	v_and_b32_e32 v251, 0xffff0000, v244
	v_lshlrev_b32_e32 v244, 16, v245
	v_and_b32_e32 v245, 0xffff0000, v245
	v_lshlrev_b32_e32 v252, 16, v246
	v_and_b32_e32 v253, 0xffff0000, v246
	v_lshlrev_b32_e32 v246, 16, v247
	v_and_b32_e32 v247, 0xffff0000, v247
	v_pk_fma_f32 v[126:127], v[126:127], v[220:221], v[244:245]
	v_pk_fma_f32 v[124:125], v[124:125], v[218:219], v[250:251]
	v_pk_fma_f32 v[244:245], v[122:123], v[216:217], v[246:247]
	v_pk_fma_f32 v[122:123], v[120:121], v[214:215], v[252:253]
	v_cvt_pk_bf16_f32 v120, v124, v125
	v_cvt_pk_bf16_f32 v121, v126, v127
	v_lshlrev_b32_e32 v124, 16, v186
	v_cvt_pk_bf16_f32 v122, v122, v123
	v_cvt_pk_bf16_f32 v123, v244, v245
	global_store_dwordx4 v[248:249], v[120:123], off
	v_and_b32_e32 v125, 0xffff0000, v186
	v_lshlrev_b32_e32 v126, 16, v187
	v_lshlrev_b32_e32 v120, 16, v184
	v_and_b32_e32 v121, 0xffff0000, v184
	v_and_b32_e32 v127, 0xffff0000, v187
	v_lshlrev_b32_e32 v122, 16, v185
	v_and_b32_e32 v123, 0xffff0000, v185
	v_pk_fma_f32 v[116:117], v[116:117], v[210:211], v[120:121]
	v_pk_fma_f32 v[120:121], v[114:115], v[208:209], v[126:127]
	v_pk_fma_f32 v[114:115], v[112:113], v[206:207], v[124:125]
	v_pk_fma_f32 v[118:119], v[118:119], v[212:213], v[122:123]
	v_cvt_pk_bf16_f32 v112, v116, v117
	v_lshlrev_b32_e32 v116, 16, v181
	v_cvt_pk_bf16_f32 v113, v118, v119
	v_cvt_pk_bf16_f32 v114, v114, v115
	v_cvt_pk_bf16_f32 v115, v120, v121
	global_store_dwordx4 v[248:249], v[112:115], off offset:256
	v_and_b32_e32 v117, 0xffff0000, v181
	v_lshlrev_b32_e32 v118, 16, v182
	v_lshlrev_b32_e32 v114, 16, v180
	v_and_b32_e32 v115, 0xffff0000, v180
	v_and_b32_e32 v119, 0xffff0000, v182
	v_lshlrev_b32_e32 v120, 16, v183
	v_and_b32_e32 v121, 0xffff0000, v183
	v_lshl_add_u64 v[112:113], v[226:227], 0, v[236:237]
	v_pk_fma_f32 v[110:111], v[110:111], v[220:221], v[116:117]
	v_pk_fma_f32 v[108:109], v[108:109], v[218:219], v[114:115]
	v_pk_fma_f32 v[114:115], v[106:107], v[216:217], v[120:121]
	v_pk_fma_f32 v[106:107], v[104:105], v[214:215], v[118:119]
	v_cvt_pk_bf16_f32 v104, v108, v109
	v_cvt_pk_bf16_f32 v105, v110, v111
	v_lshlrev_b32_e32 v108, 16, v178
	v_cvt_pk_bf16_f32 v106, v106, v107
	v_cvt_pk_bf16_f32 v107, v114, v115
; __device__ __forceinline__ unsigned cvt_pk_bf16(float lo, float hi) { unsigned r; asm volatile("v_cvt_pk_bf16_f32 %0, %1, %2" : "=v"(r) : "v"(lo), "v"(hi)); return r; }
; __device__ __forceinline__ float bf_lo(unsigned u) { return __uint_as_float(u << 16); }
; __device__ __forceinline__ float bf_hi(unsigned u) { return __uint_as_float(u & 0xffff0000u); }
;     __device__ __forceinline__ void operator()(const AccT& acc, const Unit& u, int wr, int wc, int fr, int fq) const {
;     ...
;         for (int ai = 0; ai < 2; ++ai)
; #pragma unroll
;             for (int m = 0; m < 4; ++m)
; #pragma unroll
;                 for (int bj = 0; bj < 2; ++bj) {
;                     const u32x4 q = r[ai][m][bj];
;                     const f32x4 r0 = {bf_lo(q.x), bf_hi(q.x), bf_lo(q.y), bf_hi(q.y)}, r1 = {bf_lo(q.z), bf_hi(q.z), bf_lo(q.w), bf_hi(q.w)};
;                     const f32x4 h0 = r0 + gv[bj][0] * acc[ai][bj][m][0], h1 = r1 + gv[bj][1] * acc[ai][bj][m][1];
;                     u32x4 w; w.x = cvt_pk_bf16(h0[0], h0[1]); w.y = cvt_pk_bf16(h0[2], h0[3]); w.z = cvt_pk_bf16(h1[0], h1[1]); w.w = cvt_pk_bf16(h1[2], h1[3]);
;                     *(u32x4*)(out + (size_t)(wr * 64 + fr + ai * 128 + m * 16) * DM + col0 + bj * 128) = w;
	global_store_dwordx4 v[112:113], v[104:107], off
	v_and_b32_e32 v109, 0xffff0000, v178
	v_lshlrev_b32_e32 v110, 16, v179
	v_lshlrev_b32_e32 v104, 16, v176
	v_and_b32_e32 v105, 0xffff0000, v176
	v_and_b32_e32 v111, 0xffff0000, v179
	v_lshlrev_b32_e32 v106, 16, v177
	v_and_b32_e32 v107, 0xffff0000, v177
	v_pk_fma_f32 v[100:101], v[100:101], v[210:211], v[104:105]
	v_pk_fma_f32 v[104:105], v[98:99], v[208:209], v[110:111]
	v_pk_fma_f32 v[98:99], v[96:97], v[206:207], v[108:109]
	v_pk_fma_f32 v[102:103], v[102:103], v[212:213], v[106:107]
	v_cvt_pk_bf16_f32 v96, v100, v101
	v_lshlrev_b32_e32 v100, 16, v173
	v_cvt_pk_bf16_f32 v97, v102, v103
	v_cvt_pk_bf16_f32 v98, v98, v99
	v_cvt_pk_bf16_f32 v99, v104, v105
	global_store_dwordx4 v[112:113], v[96:99], off offset:256
	v_and_b32_e32 v101, 0xffff0000, v173
	v_lshlrev_b32_e32 v102, 16, v174
	v_lshlrev_b32_e32 v98, 16, v172
	v_and_b32_e32 v99, 0xffff0000, v172
	v_and_b32_e32 v103, 0xffff0000, v174
	v_lshlrev_b32_e32 v104, 16, v175
	v_and_b32_e32 v105, 0xffff0000, v175
	v_lshl_add_u64 v[96:97], v[226:227], 0, v[234:235]
	v_pk_fma_f32 v[94:95], v[94:95], v[220:221], v[100:101]
	v_pk_fma_f32 v[92:93], v[92:93], v[218:219], v[98:99]
	v_pk_fma_f32 v[98:99], v[90:91], v[216:217], v[104:105]
	v_pk_fma_f32 v[90:91], v[88:89], v[214:215], v[102:103]
	v_cvt_pk_bf16_f32 v88, v92, v93
	v_cvt_pk_bf16_f32 v89, v94, v95
	v_lshlrev_b32_e32 v92, 16, v170
	v_cvt_pk_bf16_f32 v90, v90, v91
	v_cvt_pk_bf16_f32 v91, v98, v99
	global_store_dwordx4 v[96:97], v[88:91], off
	v_and_b32_e32 v93, 0xffff0000, v170
	v_lshlrev_b32_e32 v94, 16, v171
	v_lshlrev_b32_e32 v88, 16, v168
	v_and_b32_e32 v89, 0xffff0000, v168
	v_and_b32_e32 v95, 0xffff0000, v171
	v_lshlrev_b32_e32 v90, 16, v169
	v_and_b32_e32 v91, 0xffff0000, v169
	v_pk_fma_f32 v[84:85], v[84:85], v[210:211], v[88:89]
	v_pk_fma_f32 v[88:89], v[82:83], v[208:209], v[94:95]
	v_pk_fma_f32 v[82:83], v[80:81], v[206:207], v[92:93]
	v_pk_fma_f32 v[86:87], v[86:87], v[212:213], v[90:91]
	v_cvt_pk_bf16_f32 v80, v84, v85
	v_lshlrev_b32_e32 v84, 16, v165
	v_cvt_pk_bf16_f32 v81, v86, v87
	v_cvt_pk_bf16_f32 v82, v82, v83
	v_cvt_pk_bf16_f32 v83, v88, v89
	global_store_dwordx4 v[96:97], v[80:83], off offset:256
	v_and_b32_e32 v85, 0xffff0000, v165
	v_lshlrev_b32_e32 v86, 16, v166
	v_lshlrev_b32_e32 v82, 16, v164
	v_and_b32_e32 v83, 0xffff0000, v164
	v_and_b32_e32 v87, 0xffff0000, v166
	v_lshlrev_b32_e32 v88, 16, v167
	v_and_b32_e32 v89, 0xffff0000, v167
	v_lshl_add_u64 v[80:81], v[226:227], 0, v[232:233]
	v_pk_fma_f32 v[78:79], v[78:79], v[220:221], v[84:85]
	v_pk_fma_f32 v[76:77], v[76:77], v[218:219], v[82:83]
	v_pk_fma_f32 v[82:83], v[74:75], v[216:217], v[88:89]
	v_pk_fma_f32 v[74:75], v[72:73], v[214:215], v[86:87]
	v_cvt_pk_bf16_f32 v72, v76, v77
	v_cvt_pk_bf16_f32 v73, v78, v79
	v_lshlrev_b32_e32 v76, 16, v162
	v_cvt_pk_bf16_f32 v74, v74, v75
	v_cvt_pk_bf16_f32 v75, v82, v83
	global_store_dwordx4 v[80:81], v[72:75], off
	v_and_b32_e32 v77, 0xffff0000, v162
	v_lshlrev_b32_e32 v78, 16, v163
	v_lshlrev_b32_e32 v72, 16, v160
	v_and_b32_e32 v73, 0xffff0000, v160
	v_and_b32_e32 v79, 0xffff0000, v163
	v_lshlrev_b32_e32 v74, 16, v161
	v_and_b32_e32 v75, 0xffff0000, v161
	v_pk_fma_f32 v[68:69], v[68:69], v[210:211], v[72:73]
	v_pk_fma_f32 v[72:73], v[66:67], v[208:209], v[78:79]
	v_pk_fma_f32 v[66:67], v[64:65], v[206:207], v[76:77]
	v_pk_fma_f32 v[70:71], v[70:71], v[212:213], v[74:75]
	v_cvt_pk_bf16_f32 v64, v68, v69
	v_lshlrev_b32_e32 v68, 16, v157
	v_cvt_pk_bf16_f32 v65, v70, v71
	v_cvt_pk_bf16_f32 v66, v66, v67
	v_cvt_pk_bf16_f32 v67, v72, v73
	global_store_dwordx4 v[80:81], v[64:67], off offset:256
	v_and_b32_e32 v69, 0xffff0000, v157
	v_lshlrev_b32_e32 v70, 16, v158
	v_lshlrev_b32_e32 v66, 16, v156
	v_and_b32_e32 v67, 0xffff0000, v156
	v_and_b32_e32 v71, 0xffff0000, v158
	v_lshlrev_b32_e32 v72, 16, v159
	v_and_b32_e32 v73, 0xffff0000, v159
	v_lshl_add_u64 v[64:65], v[226:227], 0, v[230:231]
	v_pk_fma_f32 v[62:63], v[62:63], v[220:221], v[68:69]
	v_pk_fma_f32 v[60:61], v[60:61], v[218:219], v[66:67]
	v_pk_fma_f32 v[66:67], v[58:59], v[216:217], v[72:73]
	v_pk_fma_f32 v[58:59], v[56:57], v[214:215], v[70:71]
	v_cvt_pk_bf16_f32 v56, v60, v61
	v_cvt_pk_bf16_f32 v57, v62, v63
	v_lshlrev_b32_e32 v60, 16, v154
	v_cvt_pk_bf16_f32 v58, v58, v59
	v_cvt_pk_bf16_f32 v59, v66, v67
	global_store_dwordx4 v[64:65], v[56:59], off
	v_and_b32_e32 v61, 0xffff0000, v154
	v_lshlrev_b32_e32 v62, 16, v155
	v_lshlrev_b32_e32 v56, 16, v152
	v_and_b32_e32 v57, 0xffff0000, v152
	v_and_b32_e32 v63, 0xffff0000, v155
	v_lshlrev_b32_e32 v58, 16, v153
	v_and_b32_e32 v59, 0xffff0000, v153
	v_pk_fma_f32 v[52:53], v[52:53], v[210:211], v[56:57]
; __device__ __forceinline__ unsigned cvt_pk_bf16(float lo, float hi) { unsigned r; asm volatile("v_cvt_pk_bf16_f32 %0, %1, %2" : "=v"(r) : "v"(lo), "v"(hi)); return r; }
; __device__ __forceinline__ float bf_lo(unsigned u) { return __uint_as_float(u << 16); }
; __device__ __forceinline__ float bf_hi(unsigned u) { return __uint_as_float(u & 0xffff0000u); }
; #define PG8_WAIT_V(n) asm volatile("s_waitcnt vmcnt(" #n ")" ::: "memory")
; #define PG8_BAR __builtin_amdgcn_s_barrier()
; template <class Epi, class Sched>
; __device__ __forceinline__ void gemm_phase(LAS unsigned char* lds, const Gemm g, const Sched& S, const Epi& E) {
;     ...
;         if (!has_next) break;
; #pragma unroll
;         for (int a = 0; a < 2; ++a)
; #pragma unroll
;             for (int b = 0; b < 2; ++b)
; #pragma unroll
;                 for (int m = 0; m < 4; ++m)
; #pragma unroll
;                     for (int n = 0; n < 2; ++n) acc[a][b][m][n] = (f32x4){0.f, 0.f, 0.f, 0.f};
;         cur = nxt; cA = nA; cB = nB; ++ui;
;     }
;     PG8_WAIT_V(0);
;     if (wr == 0) PG8_BAR;
;     PG8_BAR;
;     __device__ __forceinline__ void operator()(const AccT& acc, const Unit& u, int wr, int wc, int fr, int fq) const {
;     ...
;                 for (int bj = 0; bj < 2; ++bj) {
;                     const u32x4 q = r[ai][m][bj];
;                     const f32x4 r0 = {bf_lo(q.x), bf_hi(q.x), bf_lo(q.y), bf_hi(q.y)}, r1 = {bf_lo(q.z), bf_hi(q.z), bf_lo(q.w), bf_hi(q.w)};
;                     const f32x4 h0 = r0 + gv[bj][0] * acc[ai][bj][m][0], h1 = r1 + gv[bj][1] * acc[ai][bj][m][1];
;                     u32x4 w; w.x = cvt_pk_bf16(h0[0], h0[1]); w.y = cvt_pk_bf16(h0[2], h0[3]); w.z = cvt_pk_bf16(h1[0], h1[1]); w.w = cvt_pk_bf16(h1[2], h1[3]);
;                     *(u32x4*)(out + (size_t)(wr * 64 + fr + ai * 128 + m * 16) * DM + col0 + bj * 128) = w;
	v_pk_fma_f32 v[56:57], v[50:51], v[208:209], v[62:63]
	v_pk_fma_f32 v[50:51], v[48:49], v[206:207], v[60:61]
	v_pk_fma_f32 v[54:55], v[54:55], v[212:213], v[58:59]
	v_cvt_pk_bf16_f32 v48, v52, v53
	v_lshlrev_b32_e32 v52, 16, v149
	v_cvt_pk_bf16_f32 v49, v54, v55
	v_cvt_pk_bf16_f32 v50, v50, v51
	v_cvt_pk_bf16_f32 v51, v56, v57
	global_store_dwordx4 v[64:65], v[48:51], off offset:256
	v_and_b32_e32 v53, 0xffff0000, v149
	v_lshlrev_b32_e32 v54, 16, v150
	v_lshlrev_b32_e32 v50, 16, v148
	v_and_b32_e32 v51, 0xffff0000, v148
	v_and_b32_e32 v55, 0xffff0000, v150
	v_lshlrev_b32_e32 v56, 16, v151
	v_and_b32_e32 v57, 0xffff0000, v151
	v_lshl_add_u64 v[48:49], v[226:227], 0, v[228:229]
	v_pk_fma_f32 v[46:47], v[46:47], v[220:221], v[52:53]
	v_pk_fma_f32 v[44:45], v[44:45], v[218:219], v[50:51]
	v_pk_fma_f32 v[50:51], v[42:43], v[216:217], v[56:57]
	v_pk_fma_f32 v[42:43], v[40:41], v[214:215], v[54:55]
	v_cvt_pk_bf16_f32 v40, v44, v45
	v_cvt_pk_bf16_f32 v41, v46, v47
	v_lshlrev_b32_e32 v44, 16, v146
	v_cvt_pk_bf16_f32 v42, v42, v43
	v_cvt_pk_bf16_f32 v43, v50, v51
	global_store_dwordx4 v[48:49], v[40:43], off
	v_and_b32_e32 v45, 0xffff0000, v146
	v_lshlrev_b32_e32 v46, 16, v147
	v_lshlrev_b32_e32 v40, 16, v144
	v_and_b32_e32 v41, 0xffff0000, v144
	v_and_b32_e32 v47, 0xffff0000, v147
	v_lshlrev_b32_e32 v42, 16, v145
	v_and_b32_e32 v43, 0xffff0000, v145
	v_pk_fma_f32 v[36:37], v[36:37], v[210:211], v[40:41]
	v_pk_fma_f32 v[40:41], v[34:35], v[208:209], v[46:47]
	v_pk_fma_f32 v[34:35], v[32:33], v[206:207], v[44:45]
	v_pk_fma_f32 v[38:39], v[38:39], v[212:213], v[42:43]
	v_cvt_pk_bf16_f32 v32, v36, v37
	v_lshlrev_b32_e32 v36, 16, v141
	v_cvt_pk_bf16_f32 v33, v38, v39
	v_cvt_pk_bf16_f32 v34, v34, v35
	v_cvt_pk_bf16_f32 v35, v40, v41
	global_store_dwordx4 v[48:49], v[32:35], off offset:256
	v_and_b32_e32 v37, 0xffff0000, v141
	v_lshlrev_b32_e32 v38, 16, v142
	v_lshlrev_b32_e32 v34, 16, v140
	v_and_b32_e32 v35, 0xffff0000, v140
	v_and_b32_e32 v39, 0xffff0000, v142
	v_lshlrev_b32_e32 v40, 16, v143
	v_and_b32_e32 v41, 0xffff0000, v143
	v_lshl_add_u64 v[32:33], v[226:227], 0, v[224:225]
	v_pk_fma_f32 v[30:31], v[30:31], v[220:221], v[36:37]
	v_pk_fma_f32 v[28:29], v[28:29], v[218:219], v[34:35]
	v_pk_fma_f32 v[34:35], v[26:27], v[216:217], v[40:41]
	v_pk_fma_f32 v[26:27], v[24:25], v[214:215], v[38:39]
	v_cvt_pk_bf16_f32 v24, v28, v29
	v_cvt_pk_bf16_f32 v25, v30, v31
	v_lshlrev_b32_e32 v28, 16, v138
	v_cvt_pk_bf16_f32 v26, v26, v27
	v_cvt_pk_bf16_f32 v27, v34, v35
	global_store_dwordx4 v[32:33], v[24:27], off
	v_and_b32_e32 v29, 0xffff0000, v138
	v_lshlrev_b32_e32 v30, 16, v139
	v_lshlrev_b32_e32 v24, 16, v136
	v_and_b32_e32 v25, 0xffff0000, v136
	v_and_b32_e32 v31, 0xffff0000, v139
	v_lshlrev_b32_e32 v26, 16, v137
	v_and_b32_e32 v27, 0xffff0000, v137
	v_pk_fma_f32 v[20:21], v[20:21], v[210:211], v[24:25]
	v_pk_fma_f32 v[24:25], v[18:19], v[208:209], v[30:31]
	v_pk_fma_f32 v[18:19], v[16:17], v[206:207], v[28:29]
	v_pk_fma_f32 v[22:23], v[22:23], v[212:213], v[26:27]
	v_cvt_pk_bf16_f32 v16, v20, v21
	v_lshlrev_b32_e32 v20, 16, v133
	v_cvt_pk_bf16_f32 v17, v22, v23
	v_cvt_pk_bf16_f32 v18, v18, v19
	v_cvt_pk_bf16_f32 v19, v24, v25
	global_store_dwordx4 v[32:33], v[16:19], off offset:256
	v_and_b32_e32 v21, 0xffff0000, v133
	v_lshlrev_b32_e32 v22, 16, v134
	v_lshlrev_b32_e32 v18, 16, v132
	v_and_b32_e32 v19, 0xffff0000, v132
	v_and_b32_e32 v23, 0xffff0000, v134
	v_lshlrev_b32_e32 v24, 16, v135
	v_and_b32_e32 v25, 0xffff0000, v135
	v_lshl_add_u64 v[16:17], v[226:227], 0, v[222:223]
	v_pk_fma_f32 v[14:15], v[14:15], v[220:221], v[20:21]
	v_pk_fma_f32 v[12:13], v[12:13], v[218:219], v[18:19]
	v_pk_fma_f32 v[18:19], v[10:11], v[216:217], v[24:25]
	v_pk_fma_f32 v[10:11], v[8:9], v[214:215], v[22:23]
	v_cvt_pk_bf16_f32 v8, v12, v13
	v_cvt_pk_bf16_f32 v9, v14, v15
	v_lshlrev_b32_e32 v12, 16, v130
	v_cvt_pk_bf16_f32 v10, v10, v11
	v_cvt_pk_bf16_f32 v11, v18, v19
	global_store_dwordx4 v[16:17], v[8:11], off
	v_and_b32_e32 v13, 0xffff0000, v130
	v_lshlrev_b32_e32 v14, 16, v131
	v_lshlrev_b32_e32 v8, 16, v128
	v_and_b32_e32 v9, 0xffff0000, v128
	v_and_b32_e32 v15, 0xffff0000, v131
	v_lshlrev_b32_e32 v10, 16, v129
	v_and_b32_e32 v11, 0xffff0000, v129
	v_pk_fma_f32 v[4:5], v[4:5], v[210:211], v[8:9]
	v_pk_fma_f32 v[8:9], v[2:3], v[208:209], v[14:15]
	v_pk_fma_f32 v[2:3], v[0:1], v[206:207], v[12:13]
	v_pk_fma_f32 v[6:7], v[6:7], v[212:213], v[10:11]
	v_cvt_pk_bf16_f32 v0, v4, v5
	s_nop 0
	v_cvt_pk_bf16_f32 v1, v6, v7
	v_cvt_pk_bf16_f32 v2, v2, v3
	v_cvt_pk_bf16_f32 v3, v8, v9
	global_store_dwordx4 v[16:17], v[0:3], off offset:256
	s_cbranch_vccz .LBB0_1086
	s_waitcnt vmcnt(0)
	s_cmpk_gt_u32 s30, 0xff
	s_cbranch_scc1 .LBB0_1101
	s_barrier
